# UV sweep: structured buffer loads (index = expert, offset = lane*16) remove address VALU; padding entries are out-of-range indices; header loads pipelined
# speedup vs baseline: 1.1485x; 1.0093x over previous
; __device__ __forceinline__ unsigned f2key(float f) { const unsigned u = __float_as_uint(f); return (u & 0x80000000u) ? ~u : (u | 0x80000000u); }
; __device__ __forceinline__ void peer_tile(const Args& A, LAS unsigned char* lds, int tile) {
;     ...
;         const int tg = w & 3, hg = w >> 2, tl = 16 * tg + l15;
;         const size_t m = (size_t)tile * 64 + tl;
;         unsigned LA[4][2][16];
; #pragma unroll
;         for (int hh = 0; hh < 4; ++hh) {
;             const int h = 4 * hg + hh;
; #pragma unroll
;             for (int p = 0; p < 2; ++p) {
;                 const int hp = 2 * h + p;
;                 unsigned k0[16], k1[16];
;                 { const bf16_t* sp = QRY + m * 2048 + hp * 128 + 32 * g;
;                   const u32x4 s0 = *(const u32x4*)sp, s1 = *(const u32x4*)(sp + 8), s2 = *(const u32x4*)(sp + 16), s3 = *(const u32x4*)(sp + 24);
;                   const unsigned sw[16] = {s0.x, s0.y, s0.z, s0.w, s1.x, s1.y, s1.z, s1.w, s2.x, s2.y, s2.z, s2.w, s3.x, s3.y, s3.z, s3.w};
; #pragma unroll
;                   for (int i = 0; i < 16; ++i) {
;                       const float lo = (float)__builtin_bit_cast(_Float16, (unsigned short)(sw[i] & 0xffffu)), hi = (float)__builtin_bit_cast(_Float16, (unsigned short)(sw[i] >> 16));
;                       const unsigned klo = (f2key(lo) & ~127u) | (unsigned)(127 - (32 * g + 2 * i)), khi = (f2key(hi) & ~127u) | (unsigned)(127 - (32 * g + 2 * i + 1));
;                       if (i < 8) { k0[2 * i] = klo; k0[2 * i + 1] = khi; } else { k1[2 * (i - 8)] = klo; k1[2 * (i - 8) + 1] = khi; } } }
.LBB0_699:
	v_mov_b32_e32 v19, v214
	s_ashr_i32 s3, s2, 31
	v_ashrrev_i32_e32 v7, 6, v19
	v_and_b32_e32 v0, 15, v19
	v_lshlrev_b32_e32 v1, 4, v7
	v_and_or_b32 v13, v1, 48, v0
	s_lshl_b64 s[28:29], s[2:3], 6
	v_or_b32_e32 v0, s28, v13
	v_mov_b32_e32 v1, s29
	v_bfe_u32 v221, v19, 4, 2
	v_ashrrev_i32_e32 v11, 8, v19
	v_lshlrev_b64 v[0:1], 12, v[0:1]
	v_lshlrev_b32_e32 v2, 10, v11
	v_lshl_add_u64 v[0:1], s[54:55], 0, v[0:1]
	v_lshlrev_b32_e32 v112, 6, v221
	v_lshl_add_u64 v[0:1], v[0:1], 0, v[112:113]
	v_ashrrev_i32_e32 v3, 31, v2
	v_lshl_add_u64 v[4:5], v[2:3], 1, v[0:1]
	global_load_dwordx4 v[20:23], v[4:5], off
	global_load_dwordx4 v[24:27], v[4:5], off offset:16
	global_load_dwordx4 v[0:3], v[4:5], off offset:48
	global_load_dwordx4 v[28:31], v[4:5], off offset:32
	v_lshlrev_b32_e32 v15, 5, v221
	v_or_b32_e32 v8, 8, v15
	v_or_b32_e32 v14, 2, v15
	v_or_b32_e32 v12, 4, v15
	v_or_b32_e32 v10, 6, v15
	v_and_b32_e32 v9, 63, v19
	v_cmp_gt_u32_e64 s[0:1], 16, v9
	v_cmp_gt_u32_e64 s[4:5], 32, v9
	v_mul_lo_u32 v6, v19, s17
	s_mov_b32 s3, 8
	s_waitcnt vmcnt(3)
	v_cvt_f32_f16_sdwa v17, v20 dst_sel:DWORD dst_unused:UNUSED_PAD src0_sel:WORD_1
	v_cvt_f32_f16_e32 v16, v20
	v_cvt_f32_f16_sdwa v20, v21 dst_sel:DWORD dst_unused:UNUSED_PAD src0_sel:WORD_1
	v_cvt_f32_f16_e32 v18, v21
	v_cvt_f32_f16_e32 v21, v22
	v_cvt_f32_f16_sdwa v22, v22 dst_sel:DWORD dst_unused:UNUSED_PAD src0_sel:WORD_1
	v_not_b32_e32 v34, v17
	v_or_b32_e32 v35, 0x80000000, v17
	v_cmp_gt_i32_e32 vcc, 0, v17
	v_not_b32_e32 v36, v16
	v_or_b32_e32 v37, 0x80000000, v16
	v_cndmask_b32_e32 v17, v35, v34, vcc
	v_cmp_gt_i32_e32 vcc, 0, v16
	v_cvt_f32_f16_e32 v32, v23
	v_cvt_f32_f16_sdwa v23, v23 dst_sel:DWORD dst_unused:UNUSED_PAD src0_sel:WORD_1
	v_not_b32_e32 v38, v20
	v_or_b32_e32 v39, 0x80000000, v20
	v_cndmask_b32_e32 v16, v37, v36, vcc
	v_cmp_gt_i32_e32 vcc, 0, v20
	v_not_b32_e32 v40, v18
	v_or_b32_e32 v41, 0x80000000, v18
	v_cndmask_b32_e32 v20, v39, v38, vcc
	v_cmp_gt_i32_e32 vcc, 0, v18
	s_waitcnt vmcnt(2)
	v_cvt_f32_f16_e32 v33, v24
	v_cvt_f32_f16_sdwa v24, v24 dst_sel:DWORD dst_unused:UNUSED_PAD src0_sel:WORD_1
	v_not_b32_e32 v42, v22
	v_or_b32_e32 v43, 0x80000000, v22
	v_cndmask_b32_e32 v18, v41, v40, vcc
	v_cmp_gt_i32_e32 vcc, 0, v22
	v_not_b32_e32 v44, v21
	v_or_b32_e32 v45, 0x80000000, v21
	v_cndmask_b32_e32 v22, v43, v42, vcc
	v_cmp_gt_i32_e32 vcc, 0, v21
	v_not_b32_e32 v46, v23
	v_or_b32_e32 v47, 0x80000000, v23
	v_cndmask_b32_e32 v21, v45, v44, vcc
	v_cmp_gt_i32_e32 vcc, 0, v23
	v_not_b32_e32 v48, v32
	v_or_b32_e32 v49, 0x80000000, v32
	v_cndmask_b32_e32 v23, v47, v46, vcc
	v_cmp_gt_i32_e32 vcc, 0, v32
	v_and_b32_e32 v16, 0xffffff80, v16
	v_not_b32_e32 v50, v24
	v_or_b32_e32 v51, 0x80000000, v24
	v_cndmask_b32_e32 v32, v49, v48, vcc
	v_sub_u32_e32 v16, v16, v15
	v_cmp_gt_i32_e32 vcc, 0, v24
	v_add_u32_e32 v35, 0x7f, v16
	v_and_b32_e32 v17, 0xffffff80, v17
	v_cndmask_b32_e32 v16, v51, v50, vcc
	v_and_b32_e32 v16, 0xffffff80, v16
	v_sub_u32_e32 v17, v17, v15
	v_sub_u32_e32 v16, v16, v8
	v_add_u32_e32 v34, 0x7e, v17
	v_add_u32_e32 v41, 0x7e, v16
	v_not_b32_e32 v16, v33
	v_or_b32_e32 v17, 0x80000000, v33
	v_cmp_gt_i32_e32 vcc, 0, v33
	v_and_b32_e32 v20, 0xffffff80, v20
	v_and_b32_e32 v18, 0xffffff80, v18
	v_cndmask_b32_e32 v16, v17, v16, vcc
	v_cvt_f32_f16_sdwa v17, v25 dst_sel:DWORD dst_unused:UNUSED_PAD src0_sel:WORD_1
	v_and_b32_e32 v21, 0xffffff80, v21
	v_sub_u32_e32 v20, v20, v14
	v_sub_u32_e32 v18, v18, v14
	v_sub_u32_e32 v21, v21, v12
	v_add_u32_e32 v36, 0x7e, v20
	v_add_u32_e32 v37, 0x7f, v18
	v_add_u32_e32 v39, 0x7f, v21
	v_and_b32_e32 v16, 0xffffff80, v16
	v_cvt_f32_f16_e32 v18, v25
	v_not_b32_e32 v20, v17
	v_or_b32_e32 v21, 0x80000000, v17
	v_cmp_gt_i32_e32 vcc, 0, v17
	v_sub_u32_e32 v16, v16, v8
	v_add_u32_e32 v33, 0x7f, v16
	v_cndmask_b32_e32 v17, v21, v20, vcc
	v_or_b32_e32 v16, 10, v15
	v_and_b32_e32 v17, 0xffffff80, v17
	v_sub_u32_e32 v17, v17, v16
	v_add_u32_e32 v42, 0x7e, v17
	v_not_b32_e32 v17, v18
	v_or_b32_e32 v20, 0x80000000, v18
	v_cmp_gt_i32_e32 vcc, 0, v18
	v_cvt_f32_f16_sdwa v18, v26 dst_sel:DWORD dst_unused:UNUSED_PAD src0_sel:WORD_1
	v_and_b32_e32 v22, 0xffffff80, v22
	v_sub_u32_e32 v22, v22, v12
	v_cndmask_b32_e32 v17, v20, v17, vcc
	v_add_u32_e32 v38, 0x7e, v22
	v_and_b32_e32 v17, 0xffffff80, v17
	v_cvt_f32_f16_e32 v20, v26
	v_not_b32_e32 v21, v18
	v_or_b32_e32 v22, 0x80000000, v18
	v_cmp_gt_i32_e32 vcc, 0, v18
	v_sub_u32_e32 v17, v17, v16
	v_add_u32_e32 v43, 0x7f, v17
	v_cndmask_b32_e32 v18, v22, v21, vcc
	v_or_b32_e32 v17, 12, v15
	v_and_b32_e32 v18, 0xffffff80, v18
	v_sub_u32_e32 v18, v18, v17
	v_add_u32_e32 v44, 0x7e, v18
	v_not_b32_e32 v18, v20
	v_or_b32_e32 v21, 0x80000000, v20
	v_cmp_gt_i32_e32 vcc, 0, v20
	v_cvt_f32_f16_sdwa v20, v27 dst_sel:DWORD dst_unused:UNUSED_PAD src0_sel:WORD_1
	v_and_b32_e32 v23, 0xffffff80, v23
	v_sub_u32_e32 v23, v23, v10
	v_cndmask_b32_e32 v18, v21, v18, vcc
	v_add_u32_e32 v40, 0x7e, v23
	v_and_b32_e32 v18, 0xffffff80, v18
	v_cvt_f32_f16_e32 v21, v27
	v_not_b32_e32 v22, v20
	v_or_b32_e32 v23, 0x80000000, v20
	v_cmp_gt_i32_e32 vcc, 0, v20
	v_sub_u32_e32 v18, v18, v17
	v_add_u32_e32 v45, 0x7f, v18
	v_cndmask_b32_e32 v20, v23, v22, vcc
	v_or_b32_e32 v18, 14, v15
	v_and_b32_e32 v20, 0xffffff80, v20
	v_sub_u32_e32 v20, v20, v18
	v_add_u32_e32 v27, 0x7e, v20
	v_not_b32_e32 v20, v21
	v_or_b32_e32 v22, 0x80000000, v21
	v_cmp_gt_i32_e32 vcc, 0, v21
	s_waitcnt vmcnt(0)
; __device__ __forceinline__ unsigned f2key(float f) { const unsigned u = __float_as_uint(f); return (u & 0x80000000u) ? ~u : (u | 0x80000000u); }
; __device__ __forceinline__ void peer_tile(const Args& A, LAS unsigned char* lds, int tile) {
;     ...
;                   for (int i = 0; i < 16; ++i) {
;                       const float lo = (float)__builtin_bit_cast(_Float16, (unsigned short)(sw[i] & 0xffffu)), hi = (float)__builtin_bit_cast(_Float16, (unsigned short)(sw[i] >> 16));
;                       const unsigned klo = (f2key(lo) & ~127u) | (unsigned)(127 - (32 * g + 2 * i)), khi = (f2key(hi) & ~127u) | (unsigned)(127 - (32 * g + 2 * i + 1));
;                       if (i < 8) { k0[2 * i] = klo; k0[2 * i + 1] = khi; } else { k1[2 * (i - 8)] = klo; k1[2 * (i - 8) + 1] = khi; } } }
;                 sort16_desc(k0); sort16_desc(k1); merge16(k0, k1);
	v_cvt_f32_f16_sdwa v21, v28 dst_sel:DWORD dst_unused:UNUSED_PAD src0_sel:WORD_1
	v_and_b32_e32 v32, 0xffffff80, v32
	v_cndmask_b32_e32 v20, v22, v20, vcc
	v_and_b32_e32 v20, 0xffffff80, v20
	v_cvt_f32_f16_e32 v22, v28
	v_not_b32_e32 v23, v21
	v_or_b32_e32 v24, 0x80000000, v21
	v_cmp_gt_i32_e32 vcc, 0, v21
	v_sub_u32_e32 v20, v20, v18
	v_add_u32_e32 v46, 0x7f, v20
	v_cndmask_b32_e32 v21, v24, v23, vcc
	v_or_b32_e32 v20, 16, v15
	v_and_b32_e32 v21, 0xffffff80, v21
	v_sub_u32_e32 v21, v21, v20
	v_add_u32_e32 v47, 0x7e, v21
	v_not_b32_e32 v21, v22
	v_or_b32_e32 v23, 0x80000000, v22
	v_cmp_gt_i32_e32 vcc, 0, v22
	v_cvt_f32_f16_sdwa v22, v29 dst_sel:DWORD dst_unused:UNUSED_PAD src0_sel:WORD_1
	v_sub_u32_e32 v32, v32, v10
	v_cndmask_b32_e32 v21, v23, v21, vcc
	v_and_b32_e32 v21, 0xffffff80, v21
	v_cvt_f32_f16_e32 v23, v29
	v_not_b32_e32 v24, v22
	v_or_b32_e32 v25, 0x80000000, v22
	v_cmp_gt_i32_e32 vcc, 0, v22
	v_sub_u32_e32 v21, v21, v20
	v_add_u32_e32 v48, 0x7f, v21
	v_cndmask_b32_e32 v22, v25, v24, vcc
	v_or_b32_e32 v21, 18, v15
	v_and_b32_e32 v22, 0xffffff80, v22
	v_sub_u32_e32 v22, v22, v21
	v_add_u32_e32 v29, 0x7e, v22
	v_not_b32_e32 v22, v23
	v_or_b32_e32 v24, 0x80000000, v23
	v_cmp_gt_i32_e32 vcc, 0, v23
	v_cvt_f32_f16_sdwa v23, v30 dst_sel:DWORD dst_unused:UNUSED_PAD src0_sel:WORD_1
	v_add_u32_e32 v32, 0x7f, v32
	v_cndmask_b32_e32 v22, v24, v22, vcc
	v_and_b32_e32 v22, 0xffffff80, v22
	v_cvt_f32_f16_e32 v24, v30
	v_not_b32_e32 v25, v23
	v_or_b32_e32 v26, 0x80000000, v23
	v_cmp_gt_i32_e32 vcc, 0, v23
	v_sub_u32_e32 v22, v22, v21
	v_add_u32_e32 v49, 0x7f, v22
	v_cndmask_b32_e32 v23, v26, v25, vcc
	v_or_b32_e32 v22, 20, v15
	v_and_b32_e32 v23, 0xffffff80, v23
	v_sub_u32_e32 v23, v23, v22
	v_add_u32_e32 v30, 0x7e, v23
	v_not_b32_e32 v23, v24
	v_or_b32_e32 v25, 0x80000000, v24
	v_cmp_gt_i32_e32 vcc, 0, v24
	v_cvt_f32_f16_sdwa v24, v31 dst_sel:DWORD dst_unused:UNUSED_PAD src0_sel:WORD_1
	v_max_u32_e32 v64, v48, v47
	v_cndmask_b32_e32 v23, v25, v23, vcc
	v_and_b32_e32 v23, 0xffffff80, v23
	v_cvt_f32_f16_e32 v25, v31
	v_not_b32_e32 v26, v24
	v_or_b32_e32 v28, 0x80000000, v24
	v_cmp_gt_i32_e32 vcc, 0, v24
	v_sub_u32_e32 v23, v23, v22
	v_add_u32_e32 v50, 0x7f, v23
	v_cndmask_b32_e32 v24, v28, v26, vcc
	v_or_b32_e32 v23, 22, v15
	v_and_b32_e32 v24, 0xffffff80, v24
	v_sub_u32_e32 v24, v24, v23
	v_add_u32_e32 v31, 0x7e, v24
	v_not_b32_e32 v24, v25
	v_or_b32_e32 v26, 0x80000000, v25
	v_cmp_gt_i32_e32 vcc, 0, v25
	v_cvt_f32_f16_sdwa v25, v0 dst_sel:DWORD dst_unused:UNUSED_PAD src0_sel:WORD_1
	v_cvt_f32_f16_e32 v0, v0
	v_cndmask_b32_e32 v24, v26, v24, vcc
	v_and_b32_e32 v24, 0xffffff80, v24
	v_not_b32_e32 v26, v25
	v_or_b32_e32 v28, 0x80000000, v25
	v_cmp_gt_i32_e32 vcc, 0, v25
	v_sub_u32_e32 v24, v24, v23
	v_add_u32_e32 v51, 0x7f, v24
	v_cndmask_b32_e32 v25, v28, v26, vcc
	v_or_b32_e32 v24, 24, v15
	v_and_b32_e32 v25, 0xffffff80, v25
	v_sub_u32_e32 v25, v25, v24
	v_add_u32_e32 v52, 0x7e, v25
	v_not_b32_e32 v25, v0
	v_or_b32_e32 v26, 0x80000000, v0
	v_cmp_gt_i32_e32 vcc, 0, v0
	v_min_u32_e32 v47, v48, v47
	v_max_u32_e32 v48, v29, v49
	v_cndmask_b32_e32 v0, v26, v25, vcc
	v_cvt_f32_f16_sdwa v26, v1 dst_sel:DWORD dst_unused:UNUSED_PAD src0_sel:WORD_1
	v_cvt_f32_f16_e32 v1, v1
	v_or_b32_e32 v25, 26, v15
	v_and_b32_e32 v0, 0xffffff80, v0
	v_not_b32_e32 v28, v26
	v_or_b32_e32 v53, 0x80000000, v26
	v_cmp_gt_i32_e32 vcc, 0, v26
	v_sub_u32_e32 v0, v0, v24
	v_add_u32_e32 v0, 0x7f, v0
	v_cndmask_b32_e32 v26, v53, v28, vcc
	v_and_b32_e32 v26, 0xffffff80, v26
	v_sub_u32_e32 v26, v26, v25
	v_add_u32_e32 v53, 0x7e, v26
	v_not_b32_e32 v26, v1
	v_or_b32_e32 v28, 0x80000000, v1
	v_cmp_gt_i32_e32 vcc, 0, v1
	v_min_u32_e32 v29, v29, v49
	v_max_u32_e32 v49, v50, v30
	v_cndmask_b32_e32 v1, v28, v26, vcc
	v_cvt_f32_f16_sdwa v28, v2 dst_sel:DWORD dst_unused:UNUSED_PAD src0_sel:WORD_1
	v_cvt_f32_f16_e32 v2, v2
	v_or_b32_e32 v26, 28, v15
	v_and_b32_e32 v1, 0xffffff80, v1
	v_not_b32_e32 v54, v28
	v_or_b32_e32 v55, 0x80000000, v28
	v_cmp_gt_i32_e32 vcc, 0, v28
	v_sub_u32_e32 v1, v1, v25
	v_add_u32_e32 v1, 0x7f, v1
	v_cndmask_b32_e32 v28, v55, v54, vcc
	v_and_b32_e32 v28, 0xffffff80, v28
	v_sub_u32_e32 v28, v28, v26
	v_add_u32_e32 v54, 0x7e, v28
	v_not_b32_e32 v28, v2
	v_or_b32_e32 v55, 0x80000000, v2
	v_cmp_gt_i32_e32 vcc, 0, v2
	v_min_u32_e32 v30, v50, v30
	v_max_u32_e32 v50, v31, v51
	v_cndmask_b32_e32 v2, v55, v28, vcc
	v_cvt_f32_f16_e32 v55, v3
	v_cvt_f32_f16_sdwa v3, v3 dst_sel:DWORD dst_unused:UNUSED_PAD src0_sel:WORD_1
	v_and_b32_e32 v2, 0xffffff80, v2
	v_or_b32_e32 v28, 30, v15
	v_not_b32_e32 v56, v55
	v_or_b32_e32 v57, 0x80000000, v55
	v_cmp_gt_i32_e32 vcc, 0, v55
	v_sub_u32_e32 v2, v2, v26
	v_add_u32_e32 v2, 0x7f, v2
	v_cndmask_b32_e32 v55, v57, v56, vcc
	v_not_b32_e32 v56, v3
	v_or_b32_e32 v57, 0x80000000, v3
	v_cmp_gt_i32_e32 vcc, 0, v3
	v_and_b32_e32 v55, 0xffffff80, v55
	v_sub_u32_e32 v55, v55, v28
	v_cndmask_b32_e32 v3, v57, v56, vcc
	v_and_b32_e32 v3, 0xffffff80, v3
	v_sub_u32_e32 v3, v3, v28
	v_add_u32_e32 v55, 0x7f, v55
	v_add_u32_e32 v3, 0x7e, v3
	v_max_u32_e32 v56, v35, v34
	v_min_u32_e32 v34, v35, v34
	v_max_u32_e32 v35, v36, v37
	v_min_u32_e32 v36, v36, v37
	v_max_u32_e32 v37, v39, v38
	v_min_u32_e32 v38, v39, v38
	v_max_u32_e32 v39, v40, v32
	v_min_u32_e32 v32, v40, v32
	v_max_u32_e32 v40, v33, v41
	v_min_u32_e32 v33, v33, v41
	v_max_u32_e32 v41, v42, v43
	v_min_u32_e32 v42, v42, v43
	v_max_u32_e32 v43, v45, v44
	v_min_u32_e32 v44, v45, v44
	v_max_u32_e32 v45, v27, v46
	v_min_u32_e32 v27, v27, v46
	v_min_u32_e32 v31, v31, v51
	v_max_u32_e32 v51, v0, v52
	v_min_u32_e32 v0, v0, v52
	v_max_u32_e32 v52, v53, v1
	v_min_u32_e32 v1, v53, v1
	v_max_u32_e32 v53, v2, v54
; #define CE_DESC(a, b) do { const unsigned _mx = (a) > (b) ? (a) : (b), _mn = (a) > (b) ? (b) : (a); (a) = _mx; (b) = _mn; } while (0)
; __device__ __forceinline__ void sort16_desc(unsigned (&k)[16]) {
; #pragma unroll
;     for (int size = 2; size <= 16; size <<= 1)
; #pragma unroll
;         for (int stride = size >> 1; stride > 0; stride >>= 1)
; #pragma unroll
;             for (int i = 0; i < 16; ++i) { const int j = i ^ stride;
;                 if (j > i) { if ((i & size) == 0) CE_DESC(k[i], k[j]); else CE_DESC(k[j], k[i]); } }
; }
	v_min_u32_e32 v2, v2, v54
	v_max_u32_e32 v54, v3, v55
	v_min_u32_e32 v3, v3, v55
	v_max_u32_e32 v46, v56, v36
	v_min_u32_e32 v36, v56, v36
	v_max_u32_e32 v56, v34, v35
	v_min_u32_e32 v34, v34, v35
	v_max_u32_e32 v35, v32, v37
	v_min_u32_e32 v32, v32, v37
	v_max_u32_e32 v37, v39, v38
	v_min_u32_e32 v38, v39, v38
	v_max_u32_e32 v39, v40, v42
	v_min_u32_e32 v40, v40, v42
	v_max_u32_e32 v42, v33, v41
	v_min_u32_e32 v33, v33, v41
	v_max_u32_e32 v41, v27, v43
	v_min_u32_e32 v27, v27, v43
	v_max_u32_e32 v43, v45, v44
	v_min_u32_e32 v44, v45, v44
	v_max_u32_e32 v55, v64, v29
	v_min_u32_e32 v29, v64, v29
	v_max_u32_e32 v64, v47, v48
	v_min_u32_e32 v47, v47, v48
	v_max_u32_e32 v48, v31, v49
	v_min_u32_e32 v31, v31, v49
	v_max_u32_e32 v49, v50, v30
	v_min_u32_e32 v30, v50, v30
	v_max_u32_e32 v50, v51, v1
	v_min_u32_e32 v1, v51, v1
	v_max_u32_e32 v51, v0, v52
	v_min_u32_e32 v0, v0, v52
	v_max_u32_e32 v52, v3, v53
	v_min_u32_e32 v3, v3, v53
	v_max_u32_e32 v53, v54, v2
	v_min_u32_e32 v2, v54, v2
	v_max_u32_e32 v45, v46, v56
	v_min_u32_e32 v46, v46, v56
	v_max_u32_e32 v56, v36, v34
	v_min_u32_e32 v34, v36, v34
	v_max_u32_e32 v36, v38, v32
	v_min_u32_e32 v32, v38, v32
	v_max_u32_e32 v38, v37, v35
	v_min_u32_e32 v35, v37, v35
	v_max_u32_e32 v37, v39, v42
	v_min_u32_e32 v39, v39, v42
	v_max_u32_e32 v42, v40, v33
	v_min_u32_e32 v33, v40, v33
	v_max_u32_e32 v40, v44, v27
	v_min_u32_e32 v27, v44, v27
	v_max_u32_e32 v44, v43, v41
	v_min_u32_e32 v41, v43, v41
	v_max_u32_e32 v54, v55, v64
	v_min_u32_e32 v55, v55, v64
	v_max_u32_e32 v64, v29, v47
	v_min_u32_e32 v29, v29, v47
	v_max_u32_e32 v47, v30, v31
	v_min_u32_e32 v30, v30, v31
	v_max_u32_e32 v31, v49, v48
	v_min_u32_e32 v48, v49, v48
	v_max_u32_e32 v49, v50, v51
	v_min_u32_e32 v50, v50, v51
	v_max_u32_e32 v51, v1, v0
	v_min_u32_e32 v0, v1, v0
	v_max_u32_e32 v1, v2, v3
	v_min_u32_e32 v2, v2, v3
	v_max_u32_e32 v3, v53, v52
	v_min_u32_e32 v52, v53, v52
	v_max_u32_e32 v43, v45, v32
	v_min_u32_e32 v32, v45, v32
	v_max_u32_e32 v45, v46, v36
	v_min_u32_e32 v36, v46, v36
	v_max_u32_e32 v46, v56, v35
	v_min_u32_e32 v35, v56, v35
	v_max_u32_e32 v56, v34, v38
	v_min_u32_e32 v34, v34, v38
	v_max_u32_e32 v38, v27, v37
	v_min_u32_e32 v27, v27, v37
	v_max_u32_e32 v37, v40, v39
	v_min_u32_e32 v39, v40, v39
	v_max_u32_e32 v40, v41, v42
	v_min_u32_e32 v41, v41, v42
	v_max_u32_e32 v42, v44, v33
	v_min_u32_e32 v33, v44, v33
	v_max_u32_e32 v53, v54, v30
	v_min_u32_e32 v30, v54, v30
	v_max_u32_e32 v54, v55, v47
	v_min_u32_e32 v47, v55, v47
	v_max_u32_e32 v55, v64, v48
	v_min_u32_e32 v48, v64, v48
	v_max_u32_e32 v64, v29, v31
	v_min_u32_e32 v29, v29, v31
	v_max_u32_e32 v31, v2, v49
	v_min_u32_e32 v2, v2, v49
	v_max_u32_e32 v49, v1, v50
	v_min_u32_e32 v1, v1, v50
	v_max_u32_e32 v50, v52, v51
	v_min_u32_e32 v51, v52, v51
	v_max_u32_e32 v52, v3, v0
	v_min_u32_e32 v0, v3, v0
	v_max_u32_e32 v44, v43, v46
	v_min_u32_e32 v43, v43, v46
	v_max_u32_e32 v46, v45, v56
	v_min_u32_e32 v45, v45, v56
	v_max_u32_e32 v56, v32, v35
	v_min_u32_e32 v32, v32, v35
	v_max_u32_e32 v35, v36, v34
	v_min_u32_e32 v34, v36, v34
	v_max_u32_e32 v36, v41, v27
	v_min_u32_e32 v27, v41, v27
	v_max_u32_e32 v41, v33, v39
	v_min_u32_e32 v33, v33, v39
	v_max_u32_e32 v39, v40, v38
	v_min_u32_e32 v38, v40, v38
	v_max_u32_e32 v40, v42, v37
	v_min_u32_e32 v37, v42, v37
	v_max_u32_e32 v3, v53, v55
	v_min_u32_e32 v53, v53, v55
	v_max_u32_e32 v55, v54, v64
	v_min_u32_e32 v54, v54, v64
	v_max_u32_e32 v64, v30, v48
	v_min_u32_e32 v30, v30, v48
	v_max_u32_e32 v48, v47, v29
	v_min_u32_e32 v29, v47, v29
	v_max_u32_e32 v47, v51, v2
	v_min_u32_e32 v2, v51, v2
	v_max_u32_e32 v51, v0, v1
	v_min_u32_e32 v0, v0, v1
	v_max_u32_e32 v1, v50, v31
	v_min_u32_e32 v31, v50, v31
	v_max_u32_e32 v50, v52, v49
	v_min_u32_e32 v49, v52, v49
	v_max_u32_e32 v42, v44, v46
	v_min_u32_e32 v44, v44, v46
	v_max_u32_e32 v46, v43, v45
	v_min_u32_e32 v43, v43, v45
	v_max_u32_e32 v45, v56, v35
	v_min_u32_e32 v35, v56, v35
	v_max_u32_e32 v56, v32, v34
	v_min_u32_e32 v32, v32, v34
	v_max_u32_e32 v34, v33, v27
	v_min_u32_e32 v27, v33, v27
	v_max_u32_e32 v33, v41, v36
	v_min_u32_e32 v36, v41, v36
	v_max_u32_e32 v41, v37, v38
	v_min_u32_e32 v37, v37, v38
	v_max_u32_e32 v38, v40, v39
	v_min_u32_e32 v39, v40, v39
	v_max_u32_e32 v52, v3, v55
	v_min_u32_e32 v3, v3, v55
	v_max_u32_e32 v55, v53, v54
	v_min_u32_e32 v53, v53, v54
	v_max_u32_e32 v54, v64, v48
	v_min_u32_e32 v48, v64, v48
	v_max_u32_e32 v64, v30, v29
	v_min_u32_e32 v29, v30, v29
	v_max_u32_e32 v30, v0, v2
	v_min_u32_e32 v0, v0, v2
	v_max_u32_e32 v2, v51, v47
	v_min_u32_e32 v47, v51, v47
	v_max_u32_e32 v51, v49, v31
	v_min_u32_e32 v31, v49, v31
	v_max_u32_e32 v49, v50, v1
	v_min_u32_e32 v1, v50, v1
	v_max_u32_e32 v40, v42, v27
	v_min_u32_e32 v27, v42, v27
	v_max_u32_e32 v42, v44, v34
	v_min_u32_e32 v34, v44, v34
	v_max_u32_e32 v44, v46, v36
	v_min_u32_e32 v36, v46, v36
	v_max_u32_e32 v46, v43, v33
	v_min_u32_e32 v33, v43, v33
	v_max_u32_e32 v43, v45, v37
	v_min_u32_e32 v37, v45, v37
	v_max_u32_e32 v45, v35, v41
	v_min_u32_e32 v35, v35, v41
	v_max_u32_e32 v41, v56, v39
	v_min_u32_e32 v39, v56, v39
	v_max_u32_e32 v56, v32, v38
	v_min_u32_e32 v32, v32, v38
	v_max_u32_e32 v50, v52, v0
	v_min_u32_e32 v0, v52, v0
	v_max_u32_e32 v52, v3, v30
	v_min_u32_e32 v3, v3, v30
	v_max_u32_e32 v30, v55, v47
	v_min_u32_e32 v47, v55, v47
	v_max_u32_e32 v55, v53, v2
	v_min_u32_e32 v2, v53, v2
	v_max_u32_e32 v53, v54, v31
	v_min_u32_e32 v31, v54, v31
	v_max_u32_e32 v54, v48, v51
	v_min_u32_e32 v48, v48, v51
	v_max_u32_e32 v51, v64, v1
	v_min_u32_e32 v1, v64, v1
	v_max_u32_e32 v64, v29, v49
	v_min_u32_e32 v29, v29, v49
	v_max_u32_e32 v38, v40, v43
	v_min_u32_e32 v40, v40, v43
; #define CE_DESC(a, b) do { const unsigned _mx = (a) > (b) ? (a) : (b), _mn = (a) > (b) ? (b) : (a); (a) = _mx; (b) = _mn; } while (0)
; __device__ __forceinline__ void merge16(unsigned (&a)[16], const unsigned (&b)[16]) {
; #pragma unroll
;     for (int i = 0; i < 16; ++i) a[i] = a[i] > b[15 - i] ? a[i] : b[15 - i];
; #pragma unroll
;     for (int stride = 8; stride > 0; stride >>= 1)
; #pragma unroll
;         for (int i = 0; i < 16; ++i) { const int j = i ^ stride; if (j > i) CE_DESC(a[i], a[j]); }
; __device__ __forceinline__ void peer_tile(const Args& A, LAS unsigned char* lds, int tile) {
;     ...
;                 sort16_desc(k0); sort16_desc(k1); merge16(k0, k1);
; #pragma unroll
;                 for (int msk = 16; msk <= 32; msk <<= 1) {
; #pragma unroll
;                     for (int i = 0; i < 16; ++i) k1[i] = (unsigned)__shfl_xor((int)k0[i], msk);
;                     merge16(k0, k1); }
	v_max_u32_e32 v43, v42, v45
	v_min_u32_e32 v42, v42, v45
	v_max_u32_e32 v45, v44, v41
	v_min_u32_e32 v41, v44, v41
	v_max_u32_e32 v44, v46, v56
	v_min_u32_e32 v46, v46, v56
	v_max_u32_e32 v56, v27, v37
	v_min_u32_e32 v27, v27, v37
	v_max_u32_e32 v37, v34, v35
	v_min_u32_e32 v34, v34, v35
	v_max_u32_e32 v35, v36, v39
	v_min_u32_e32 v36, v36, v39
	v_max_u32_e32 v39, v33, v32
	v_min_u32_e32 v32, v33, v32
	v_max_u32_e32 v49, v50, v53
	v_min_u32_e32 v50, v50, v53
	v_max_u32_e32 v53, v52, v54
	v_min_u32_e32 v52, v52, v54
	v_max_u32_e32 v54, v30, v51
	v_min_u32_e32 v30, v30, v51
	v_max_u32_e32 v51, v55, v64
	v_min_u32_e32 v55, v55, v64
	v_max_u32_e32 v64, v0, v31
	v_min_u32_e32 v0, v0, v31
	v_max_u32_e32 v31, v3, v48
	v_min_u32_e32 v3, v3, v48
	v_max_u32_e32 v48, v47, v1
	v_min_u32_e32 v1, v47, v1
	v_max_u32_e32 v47, v2, v29
	v_min_u32_e32 v2, v2, v29
	v_max_u32_e32 v33, v38, v45
	v_min_u32_e32 v38, v38, v45
	v_max_u32_e32 v45, v43, v44
	v_min_u32_e32 v43, v43, v44
	v_max_u32_e32 v44, v40, v41
	v_min_u32_e32 v40, v40, v41
	v_max_u32_e32 v41, v42, v46
	v_min_u32_e32 v42, v42, v46
	v_max_u32_e32 v46, v56, v35
	v_min_u32_e32 v35, v56, v35
	v_max_u32_e32 v56, v37, v39
	v_min_u32_e32 v37, v37, v39
	v_max_u32_e32 v39, v27, v36
	v_min_u32_e32 v27, v27, v36
	v_max_u32_e32 v36, v34, v32
	v_min_u32_e32 v32, v34, v32
	v_max_u32_e32 v29, v49, v54
	v_min_u32_e32 v49, v49, v54
	v_max_u32_e32 v54, v53, v51
	v_min_u32_e32 v51, v53, v51
	v_max_u32_e32 v53, v50, v30
	v_min_u32_e32 v30, v50, v30
	v_max_u32_e32 v50, v52, v55
	v_min_u32_e32 v52, v52, v55
	v_max_u32_e32 v55, v64, v48
	v_min_u32_e32 v48, v64, v48
	v_max_u32_e32 v64, v31, v47
	v_min_u32_e32 v31, v31, v47
	v_max_u32_e32 v47, v0, v1
	v_min_u32_e32 v0, v0, v1
	v_max_u32_e32 v1, v3, v2
	v_min_u32_e32 v2, v3, v2
	v_min_u32_e32 v34, v33, v45
	v_min_u32_e32 v57, v38, v43
	v_min_u32_e32 v58, v44, v41
	v_min_u32_e32 v59, v40, v42
	v_min_u32_e32 v60, v46, v56
	v_min_u32_e32 v61, v35, v37
	v_min_u32_e32 v62, v39, v36
	v_min_u32_e32 v63, v27, v32
	v_min_u32_e32 v3, v29, v54
	v_min_u32_e32 v65, v49, v51
	v_min_u32_e32 v66, v53, v50
	v_min_u32_e32 v67, v30, v52
	v_min_u32_e32 v68, v55, v64
	v_min_u32_e32 v69, v48, v31
	v_min_u32_e32 v70, v47, v1
	v_min_u32_e32 v71, v0, v2
	v_max3_u32 v33, v33, v45, v71
	v_max3_u32 v0, v34, v0, v2
	v_max3_u32 v2, v38, v43, v70
	v_max3_u32 v1, v57, v47, v1
	v_max3_u32 v34, v44, v41, v69
	v_max3_u32 v31, v58, v48, v31
	v_max3_u32 v38, v40, v42, v68
	v_max3_u32 v40, v59, v55, v64
	v_max3_u32 v41, v46, v56, v67
	v_max3_u32 v30, v60, v30, v52
	v_max3_u32 v35, v35, v37, v66
	v_max3_u32 v37, v61, v53, v50
	v_max3_u32 v36, v39, v36, v65
	v_max3_u32 v39, v62, v49, v51
	v_max3_u32 v3, v27, v32, v3
	v_max3_u32 v27, v63, v29, v54
	v_max_u32_e32 v29, v33, v41
	v_min_u32_e32 v32, v33, v41
	v_max_u32_e32 v33, v0, v30
	v_min_u32_e32 v0, v0, v30
	v_max_u32_e32 v30, v2, v35
	v_min_u32_e32 v2, v2, v35
	v_max_u32_e32 v35, v1, v37
	v_min_u32_e32 v1, v1, v37
	v_max_u32_e32 v37, v34, v36
	v_min_u32_e32 v34, v34, v36
	v_max_u32_e32 v36, v31, v39
	v_min_u32_e32 v31, v31, v39
	v_max_u32_e32 v39, v38, v3
	v_min_u32_e32 v3, v38, v3
	v_max_u32_e32 v38, v40, v27
	v_min_u32_e32 v27, v40, v27
	v_max_u32_e32 v40, v29, v37
	v_min_u32_e32 v29, v29, v37
	v_max_u32_e32 v37, v33, v36
	v_min_u32_e32 v33, v33, v36
	v_max_u32_e32 v36, v30, v39
	v_min_u32_e32 v30, v30, v39
	v_max_u32_e32 v39, v35, v38
	v_min_u32_e32 v35, v35, v38
	v_max_u32_e32 v38, v32, v34
	v_min_u32_e32 v32, v32, v34
	v_max_u32_e32 v34, v0, v31
	v_min_u32_e32 v0, v0, v31
	v_max_u32_e32 v31, v2, v3
	v_min_u32_e32 v2, v2, v3
	v_max_u32_e32 v3, v1, v27
	v_min_u32_e32 v1, v1, v27
	v_max_u32_e32 v27, v40, v36
	v_min_u32_e32 v36, v40, v36
	v_max_u32_e32 v40, v37, v39
	v_min_u32_e32 v37, v37, v39
	v_max_u32_e32 v39, v29, v30
	v_min_u32_e32 v29, v29, v30
	v_max_u32_e32 v30, v33, v35
	v_min_u32_e32 v33, v33, v35
	v_max_u32_e32 v35, v38, v31
	v_min_u32_e32 v31, v38, v31
	v_max_u32_e32 v38, v34, v3
	v_min_u32_e32 v3, v34, v3
	v_max_u32_e32 v34, v32, v2
	v_min_u32_e32 v2, v32, v2
	v_max_u32_e32 v32, v0, v1
	v_min_u32_e32 v0, v0, v1
	v_cmp_lt_i32_e32 vcc, v217, v216
	v_max_u32_e32 v41, v36, v37
	v_min_u32_e32 v36, v36, v37
	v_max_u32_e32 v37, v39, v30
	v_min_u32_e32 v30, v39, v30
	v_max_u32_e32 v39, v29, v33
	v_min_u32_e32 v29, v29, v33
	v_max_u32_e32 v33, v35, v38
	v_min_u32_e32 v35, v35, v38
	v_max_u32_e32 v38, v31, v3
	v_min_u32_e32 v3, v31, v3
	v_max_u32_e32 v31, v34, v32
	v_min_u32_e32 v32, v34, v32
	v_max_u32_e32 v34, v2, v0
	v_min_u32_e32 v0, v2, v0
	v_cndmask_b32_e32 v2, v215, v217, vcc
	v_max_u32_e32 v1, v27, v40
	v_min_u32_e32 v40, v27, v40
	v_lshlrev_b32_e32 v27, 2, v2
	ds_bpermute_b32 v2, v27, v1
	ds_bpermute_b32 v42, v27, v40
	ds_bpermute_b32 v43, v27, v41
	ds_bpermute_b32 v44, v27, v36
	ds_bpermute_b32 v45, v27, v37
	ds_bpermute_b32 v46, v27, v30
	ds_bpermute_b32 v47, v27, v39
	ds_bpermute_b32 v48, v27, v29
	ds_bpermute_b32 v49, v27, v33
	ds_bpermute_b32 v50, v27, v35
	ds_bpermute_b32 v51, v27, v38
	ds_bpermute_b32 v52, v27, v0
	ds_bpermute_b32 v53, v27, v34
	ds_bpermute_b32 v54, v27, v32
	ds_bpermute_b32 v55, v27, v31
	ds_bpermute_b32 v56, v27, v3
	s_waitcnt lgkmcnt(4)
	v_max_u32_e32 v1, v1, v52
	s_waitcnt lgkmcnt(3)
	v_max_u32_e32 v40, v40, v53
	s_waitcnt lgkmcnt(2)
	v_max_u32_e32 v41, v41, v54
	s_waitcnt lgkmcnt(1)
	v_max_u32_e32 v36, v36, v55
	s_waitcnt lgkmcnt(0)
; __device__ __forceinline__ unsigned f2key(float f) { const unsigned u = __float_as_uint(f); return (u & 0x80000000u) ? ~u : (u | 0x80000000u); }
; #define CE_DESC(a, b) do { const unsigned _mx = (a) > (b) ? (a) : (b), _mn = (a) > (b) ? (b) : (a); (a) = _mx; (b) = _mn; } while (0)
; __device__ __forceinline__ void merge16(unsigned (&a)[16], const unsigned (&b)[16]) {
; #pragma unroll
;     for (int i = 0; i < 16; ++i) a[i] = a[i] > b[15 - i] ? a[i] : b[15 - i];
; #pragma unroll
;     for (int stride = 8; stride > 0; stride >>= 1)
; #pragma unroll
;         for (int i = 0; i < 16; ++i) { const int j = i ^ stride; if (j > i) CE_DESC(a[i], a[j]); }
; __device__ __forceinline__ void peer_tile(const Args& A, LAS unsigned char* lds, int tile) {
;     ...
;                 { const bf16_t* sp = QRY + m * 2048 + hp * 128 + 32 * g;
;                   const u32x4 s0 = *(const u32x4*)sp, s1 = *(const u32x4*)(sp + 8), s2 = *(const u32x4*)(sp + 16), s3 = *(const u32x4*)(sp + 24);
;                   const unsigned sw[16] = {s0.x, s0.y, s0.z, s0.w, s1.x, s1.y, s1.z, s1.w, s2.x, s2.y, s2.z, s2.w, s3.x, s3.y, s3.z, s3.w};
; #pragma unroll
;                   for (int i = 0; i < 16; ++i) {
;                       const float lo = (float)__builtin_bit_cast(_Float16, (unsigned short)(sw[i] & 0xffffu)), hi = (float)__builtin_bit_cast(_Float16, (unsigned short)(sw[i] >> 16));
;                       const unsigned klo = (f2key(lo) & ~127u) | (unsigned)(127 - (32 * g + 2 * i)), khi = (f2key(hi) & ~127u) | (unsigned)(127 - (32 * g + 2 * i + 1));
;                       if (i < 8) { k0[2 * i] = klo; k0[2 * i + 1] = khi; } else { k1[2 * (i - 8)] = klo; k1[2 * (i - 8) + 1] = khi; } } }
;                 sort16_desc(k0); sort16_desc(k1); merge16(k0, k1);
; #pragma unroll
;                 for (int msk = 16; msk <= 32; msk <<= 1) {
; #pragma unroll
;                     for (int i = 0; i < 16; ++i) k1[i] = (unsigned)__shfl_xor((int)k0[i], msk);
;                     merge16(k0, k1); }
	v_max_u32_e32 v37, v37, v56
	v_max_u32_e32 v30, v30, v51
	v_max_u32_e32 v39, v39, v50
	v_max_u32_e32 v29, v29, v49
	v_max_u32_e32 v33, v33, v48
	v_max_u32_e32 v35, v35, v47
	v_max_u32_e32 v38, v38, v46
	v_max_u32_e32 v3, v3, v45
	v_max_u32_e32 v31, v31, v44
	v_max_u32_e32 v32, v32, v43
	v_max_u32_e32 v34, v34, v42
	v_max_u32_e32 v0, v0, v2
	v_max_u32_e32 v2, v1, v33
	v_min_u32_e32 v1, v1, v33
	v_max_u32_e32 v33, v40, v35
	v_min_u32_e32 v35, v40, v35
	v_max_u32_e32 v40, v41, v38
	v_min_u32_e32 v38, v41, v38
	v_max_u32_e32 v41, v36, v3
	v_min_u32_e32 v3, v36, v3
	v_max_u32_e32 v36, v37, v31
	v_min_u32_e32 v31, v37, v31
	v_max_u32_e32 v37, v30, v32
	v_min_u32_e32 v30, v30, v32
	v_max_u32_e32 v32, v39, v34
	v_min_u32_e32 v34, v39, v34
	v_max_u32_e32 v39, v29, v0
	v_min_u32_e32 v0, v29, v0
	v_max_u32_e32 v29, v2, v36
	v_min_u32_e32 v2, v2, v36
	v_max_u32_e32 v36, v33, v37
	v_min_u32_e32 v33, v33, v37
	v_max_u32_e32 v37, v40, v32
	v_min_u32_e32 v32, v40, v32
	v_max_u32_e32 v40, v41, v39
	v_min_u32_e32 v39, v41, v39
	v_max_u32_e32 v41, v1, v31
	v_min_u32_e32 v1, v1, v31
	v_max_u32_e32 v31, v35, v30
	v_min_u32_e32 v30, v35, v30
	v_max_u32_e32 v35, v38, v34
	v_min_u32_e32 v34, v38, v34
	v_max_u32_e32 v38, v3, v0
	v_min_u32_e32 v0, v3, v0
	v_max_u32_e32 v3, v29, v37
	v_min_u32_e32 v29, v29, v37
	v_max_u32_e32 v37, v36, v40
	v_min_u32_e32 v36, v36, v40
	v_max_u32_e32 v40, v2, v32
	v_min_u32_e32 v2, v2, v32
	v_max_u32_e32 v32, v33, v39
	v_min_u32_e32 v33, v33, v39
	v_max_u32_e32 v39, v41, v35
	v_min_u32_e32 v35, v41, v35
	v_max_u32_e32 v41, v31, v38
	v_min_u32_e32 v31, v31, v38
	v_max_u32_e32 v38, v1, v34
	v_min_u32_e32 v1, v1, v34
	v_max_u32_e32 v34, v30, v0
	v_min_u32_e32 v0, v30, v0
	v_cmp_lt_i32_e32 vcc, v218, v216
	v_max_u32_e32 v42, v40, v32
	v_min_u32_e32 v32, v40, v32
	v_max_u32_e32 v40, v2, v33
	v_min_u32_e32 v2, v2, v33
	v_max_u32_e32 v33, v39, v41
	v_min_u32_e32 v39, v39, v41
	v_max_u32_e32 v41, v35, v31
	v_min_u32_e32 v31, v35, v31
	v_max_u32_e32 v35, v38, v34
	v_min_u32_e32 v34, v38, v34
	v_max_u32_e32 v38, v1, v0
	v_min_u32_e32 v0, v1, v0
	v_cndmask_b32_e32 v1, v215, v218, vcc
	v_max_u32_e32 v30, v3, v37
	v_min_u32_e32 v3, v3, v37
	v_max_u32_e32 v37, v29, v36
	v_min_u32_e32 v36, v29, v36
	v_lshlrev_b32_e32 v29, 2, v1
	ds_bpermute_b32 v46, v29, v0
	ds_bpermute_b32 v1, v29, v30
	ds_bpermute_b32 v43, v29, v3
	ds_bpermute_b32 v44, v29, v37
	ds_bpermute_b32 v45, v29, v36
	s_waitcnt lgkmcnt(4)
	v_max_u32_e32 v30, v30, v46
	global_load_dwordx4 v[46:49], v[4:5], off offset:272
	global_load_dwordx4 v[50:53], v[4:5], off offset:256
	ds_bpermute_b32 v54, v29, v42
	ds_bpermute_b32 v55, v29, v32
	ds_bpermute_b32 v56, v29, v40
	ds_bpermute_b32 v57, v29, v2
	ds_bpermute_b32 v58, v29, v33
	ds_bpermute_b32 v59, v29, v39
	ds_bpermute_b32 v60, v29, v41
	ds_bpermute_b32 v61, v29, v31
	ds_bpermute_b32 v62, v29, v35
	ds_bpermute_b32 v63, v29, v38
	ds_bpermute_b32 v64, v29, v34
	s_waitcnt lgkmcnt(4)
	v_max_u32_e32 v32, v32, v60
	s_waitcnt lgkmcnt(3)
	v_max_u32_e32 v42, v42, v61
	s_waitcnt lgkmcnt(2)
	v_max_u32_e32 v36, v36, v62
	s_waitcnt lgkmcnt(1)
	v_max_u32_e32 v3, v3, v63
	s_waitcnt lgkmcnt(0)
	v_max_u32_e32 v37, v37, v64
	v_max_u32_e32 v40, v40, v59
	v_max_u32_e32 v2, v2, v58
	v_max_u32_e32 v33, v33, v57
	v_max_u32_e32 v39, v39, v56
	v_max_u32_e32 v41, v41, v55
	v_max_u32_e32 v31, v31, v54
	v_max_u32_e32 v35, v35, v45
	v_max_u32_e32 v34, v34, v44
	v_max_u32_e32 v38, v38, v43
	v_max_u32_e32 v0, v0, v1
	v_max_u32_e32 v1, v30, v33
	v_min_u32_e32 v30, v30, v33
	v_max_u32_e32 v33, v3, v39
	v_min_u32_e32 v3, v3, v39
	v_max_u32_e32 v39, v37, v41
	v_min_u32_e32 v37, v37, v41
	v_max_u32_e32 v41, v36, v31
	v_min_u32_e32 v31, v36, v31
	v_max_u32_e32 v36, v42, v35
	v_min_u32_e32 v35, v42, v35
	v_max_u32_e32 v42, v32, v34
	v_min_u32_e32 v32, v32, v34
	v_max_u32_e32 v34, v40, v38
	v_min_u32_e32 v38, v40, v38
	v_max_u32_e32 v40, v2, v0
	v_min_u32_e32 v0, v2, v0
	v_max_u32_e32 v2, v1, v36
	v_min_u32_e32 v1, v1, v36
	v_max_u32_e32 v36, v33, v42
	v_min_u32_e32 v33, v33, v42
	v_max_u32_e32 v42, v39, v34
	v_min_u32_e32 v34, v39, v34
	v_max_u32_e32 v39, v41, v40
	v_min_u32_e32 v40, v41, v40
	v_max_u32_e32 v41, v30, v35
	v_min_u32_e32 v30, v30, v35
	v_max_u32_e32 v35, v3, v32
	v_min_u32_e32 v3, v3, v32
	v_max_u32_e32 v32, v37, v38
	v_min_u32_e32 v37, v37, v38
	v_max_u32_e32 v38, v31, v0
	v_min_u32_e32 v0, v31, v0
	v_max_u32_e32 v31, v2, v42
	v_min_u32_e32 v2, v2, v42
	v_max_u32_e32 v42, v36, v39
	v_min_u32_e32 v36, v36, v39
	v_max_u32_e32 v39, v1, v34
	v_min_u32_e32 v1, v1, v34
	v_max_u32_e32 v34, v33, v40
	v_min_u32_e32 v33, v33, v40
	v_max_u32_e32 v54, v41, v32
	v_min_u32_e32 v32, v41, v32
	v_max_u32_e32 v55, v35, v38
	v_min_u32_e32 v56, v35, v38
	v_max_u32_e32 v57, v30, v37
	v_min_u32_e32 v30, v30, v37
	v_max_u32_e32 v58, v3, v0
	v_min_u32_e32 v0, v3, v0
	v_max_u32_e32 v45, v31, v42
	v_min_u32_e32 v44, v31, v42
	v_max_u32_e32 v43, v2, v36
	v_min_u32_e32 v42, v2, v36
	v_max_u32_e32 v41, v39, v34
	v_min_u32_e32 v40, v39, v34
	v_max_u32_e32 v39, v1, v33
	v_min_u32_e32 v38, v1, v33
	v_max_u32_e32 v37, v54, v55
	v_min_u32_e32 v36, v54, v55
	v_max_u32_e32 v35, v32, v56
	v_min_u32_e32 v34, v32, v56
	v_max_u32_e32 v33, v57, v58
	v_min_u32_e32 v32, v57, v58
	v_max_u32_e32 v31, v30, v0
	v_min_u32_e32 v30, v30, v0
	global_load_dwordx4 v[0:3], v[4:5], off offset:304
	global_load_dwordx4 v[54:57], v[4:5], off offset:288
	s_waitcnt vmcnt(2)
; __device__ __forceinline__ unsigned f2key(float f) { const unsigned u = __float_as_uint(f); return (u & 0x80000000u) ? ~u : (u | 0x80000000u); }
; __device__ __forceinline__ void peer_tile(const Args& A, LAS unsigned char* lds, int tile) {
;     ...
;                 { const bf16_t* sp = QRY + m * 2048 + hp * 128 + 32 * g;
;                   const u32x4 s0 = *(const u32x4*)sp, s1 = *(const u32x4*)(sp + 8), s2 = *(const u32x4*)(sp + 16), s3 = *(const u32x4*)(sp + 24);
;                   const unsigned sw[16] = {s0.x, s0.y, s0.z, s0.w, s1.x, s1.y, s1.z, s1.w, s2.x, s2.y, s2.z, s2.w, s3.x, s3.y, s3.z, s3.w};
; #pragma unroll
;                   for (int i = 0; i < 16; ++i) {
;                       const float lo = (float)__builtin_bit_cast(_Float16, (unsigned short)(sw[i] & 0xffffu)), hi = (float)__builtin_bit_cast(_Float16, (unsigned short)(sw[i] >> 16));
;                       const unsigned klo = (f2key(lo) & ~127u) | (unsigned)(127 - (32 * g + 2 * i)), khi = (f2key(hi) & ~127u) | (unsigned)(127 - (32 * g + 2 * i + 1));
;                       if (i < 8) { k0[2 * i] = klo; k0[2 * i + 1] = khi; } else { k1[2 * (i - 8)] = klo; k1[2 * (i - 8) + 1] = khi; } } }
	v_cvt_f32_f16_sdwa v58, v50 dst_sel:DWORD dst_unused:UNUSED_PAD src0_sel:WORD_1
	v_cvt_f32_f16_e32 v50, v50
	v_not_b32_e32 v59, v58
	v_or_b32_e32 v60, 0x80000000, v58
	v_cmp_gt_i32_e32 vcc, 0, v58
	s_nop 1
	v_cndmask_b32_e32 v58, v60, v59, vcc
	v_not_b32_e32 v59, v50
	v_or_b32_e32 v60, 0x80000000, v50
	v_cmp_gt_i32_e32 vcc, 0, v50
	v_and_b32_e32 v58, 0xffffff80, v58
	v_sub_u32_e32 v58, v58, v15
	v_cndmask_b32_e32 v50, v60, v59, vcc
	v_cvt_f32_f16_sdwa v59, v51 dst_sel:DWORD dst_unused:UNUSED_PAD src0_sel:WORD_1
	v_cvt_f32_f16_e32 v51, v51
	v_and_b32_e32 v50, 0xffffff80, v50
	v_sub_u32_e32 v50, v50, v15
	v_not_b32_e32 v60, v59
	v_or_b32_e32 v61, 0x80000000, v59
	v_cmp_gt_i32_e32 vcc, 0, v59
	v_add_u32_e32 v58, 0x7e, v58
	v_add_u32_e32 v50, 0x7f, v50
	v_cndmask_b32_e32 v59, v61, v60, vcc
	v_not_b32_e32 v60, v51
	v_or_b32_e32 v61, 0x80000000, v51
	v_cmp_gt_i32_e32 vcc, 0, v51
	v_and_b32_e32 v59, 0xffffff80, v59
	v_sub_u32_e32 v59, v59, v14
	v_cndmask_b32_e32 v51, v61, v60, vcc
	v_cvt_f32_f16_sdwa v60, v52 dst_sel:DWORD dst_unused:UNUSED_PAD src0_sel:WORD_1
	v_cvt_f32_f16_e32 v52, v52
	v_and_b32_e32 v51, 0xffffff80, v51
	v_sub_u32_e32 v51, v51, v14
	v_not_b32_e32 v61, v60
	v_or_b32_e32 v62, 0x80000000, v60
	v_cmp_gt_i32_e32 vcc, 0, v60
	v_add_u32_e32 v59, 0x7e, v59
	v_add_u32_e32 v51, 0x7f, v51
	v_cndmask_b32_e32 v60, v62, v61, vcc
	v_not_b32_e32 v61, v52
	v_or_b32_e32 v62, 0x80000000, v52
	v_cmp_gt_i32_e32 vcc, 0, v52
	v_and_b32_e32 v60, 0xffffff80, v60
	v_sub_u32_e32 v60, v60, v12
	v_cndmask_b32_e32 v52, v62, v61, vcc
	v_cvt_f32_f16_sdwa v61, v53 dst_sel:DWORD dst_unused:UNUSED_PAD src0_sel:WORD_1
	v_cvt_f32_f16_e32 v53, v53
	v_and_b32_e32 v52, 0xffffff80, v52
	v_sub_u32_e32 v52, v52, v12
	v_not_b32_e32 v62, v61
	v_or_b32_e32 v63, 0x80000000, v61
	v_cmp_gt_i32_e32 vcc, 0, v61
	v_add_u32_e32 v60, 0x7e, v60
	v_add_u32_e32 v52, 0x7f, v52
	v_cndmask_b32_e32 v61, v63, v62, vcc
	v_not_b32_e32 v62, v53
	v_or_b32_e32 v63, 0x80000000, v53
	v_cmp_gt_i32_e32 vcc, 0, v53
	v_and_b32_e32 v61, 0xffffff80, v61
	v_sub_u32_e32 v61, v61, v10
	v_cndmask_b32_e32 v53, v63, v62, vcc
	v_cvt_f32_f16_sdwa v62, v46 dst_sel:DWORD dst_unused:UNUSED_PAD src0_sel:WORD_1
	v_cvt_f32_f16_e32 v46, v46
	v_and_b32_e32 v53, 0xffffff80, v53
	v_sub_u32_e32 v53, v53, v10
	v_not_b32_e32 v63, v62
	v_or_b32_e32 v64, 0x80000000, v62
	v_cmp_gt_i32_e32 vcc, 0, v62
	v_add_u32_e32 v61, 0x7e, v61
	v_add_u32_e32 v53, 0x7f, v53
	v_cndmask_b32_e32 v62, v64, v63, vcc
	v_not_b32_e32 v63, v46
	v_or_b32_e32 v64, 0x80000000, v46
	v_cmp_gt_i32_e32 vcc, 0, v46
	v_and_b32_e32 v62, 0xffffff80, v62
	v_sub_u32_e32 v62, v62, v8
	v_cndmask_b32_e32 v46, v64, v63, vcc
	v_cvt_f32_f16_sdwa v63, v47 dst_sel:DWORD dst_unused:UNUSED_PAD src0_sel:WORD_1
	v_cvt_f32_f16_e32 v47, v47
	v_and_b32_e32 v46, 0xffffff80, v46
	v_sub_u32_e32 v46, v46, v8
	v_not_b32_e32 v64, v63
	v_or_b32_e32 v65, 0x80000000, v63
	v_cmp_gt_i32_e32 vcc, 0, v63
	v_add_u32_e32 v62, 0x7e, v62
	v_add_u32_e32 v46, 0x7f, v46
	v_cndmask_b32_e32 v63, v65, v64, vcc
	v_not_b32_e32 v64, v47
	v_or_b32_e32 v65, 0x80000000, v47
	v_cmp_gt_i32_e32 vcc, 0, v47
	v_and_b32_e32 v63, 0xffffff80, v63
	v_sub_u32_e32 v63, v63, v16
	v_cndmask_b32_e32 v47, v65, v64, vcc
	v_cvt_f32_f16_sdwa v64, v48 dst_sel:DWORD dst_unused:UNUSED_PAD src0_sel:WORD_1
	v_cvt_f32_f16_e32 v48, v48
	v_and_b32_e32 v47, 0xffffff80, v47
	v_sub_u32_e32 v47, v47, v16
	v_not_b32_e32 v65, v64
	v_or_b32_e32 v66, 0x80000000, v64
	v_cmp_gt_i32_e32 vcc, 0, v64
	v_add_u32_e32 v63, 0x7e, v63
	v_add_u32_e32 v47, 0x7f, v47
	v_cndmask_b32_e32 v64, v66, v65, vcc
	v_not_b32_e32 v65, v48
	v_or_b32_e32 v66, 0x80000000, v48
	v_cmp_gt_i32_e32 vcc, 0, v48
	v_and_b32_e32 v64, 0xffffff80, v64
	v_sub_u32_e32 v64, v64, v17
	v_cndmask_b32_e32 v48, v66, v65, vcc
	v_cvt_f32_f16_sdwa v65, v49 dst_sel:DWORD dst_unused:UNUSED_PAD src0_sel:WORD_1
	v_cvt_f32_f16_e32 v49, v49
	v_and_b32_e32 v48, 0xffffff80, v48
	v_sub_u32_e32 v48, v48, v17
	v_not_b32_e32 v66, v65
	v_or_b32_e32 v67, 0x80000000, v65
	v_cmp_gt_i32_e32 vcc, 0, v65
	v_add_u32_e32 v64, 0x7e, v64
	v_add_u32_e32 v48, 0x7f, v48
	v_cndmask_b32_e32 v65, v67, v66, vcc
	v_not_b32_e32 v66, v49
	v_or_b32_e32 v67, 0x80000000, v49
	v_cmp_gt_i32_e32 vcc, 0, v49
	v_and_b32_e32 v65, 0xffffff80, v65
	v_sub_u32_e32 v65, v65, v18
	v_cndmask_b32_e32 v49, v67, v66, vcc
	s_waitcnt vmcnt(0)
; __device__ __forceinline__ unsigned f2key(float f) { const unsigned u = __float_as_uint(f); return (u & 0x80000000u) ? ~u : (u | 0x80000000u); }
; #define CE_DESC(a, b) do { const unsigned _mx = (a) > (b) ? (a) : (b), _mn = (a) > (b) ? (b) : (a); (a) = _mx; (b) = _mn; } while (0)
; __device__ __forceinline__ void sort16_desc(unsigned (&k)[16]) {
; #pragma unroll
;     for (int size = 2; size <= 16; size <<= 1)
; #pragma unroll
;         for (int stride = size >> 1; stride > 0; stride >>= 1)
; #pragma unroll
;             for (int i = 0; i < 16; ++i) { const int j = i ^ stride;
;                 if (j > i) { if ((i & size) == 0) CE_DESC(k[i], k[j]); else CE_DESC(k[j], k[i]); } }
; }
; __device__ __forceinline__ void peer_tile(const Args& A, LAS unsigned char* lds, int tile) {
;     ...
;                   for (int i = 0; i < 16; ++i) {
;                       const float lo = (float)__builtin_bit_cast(_Float16, (unsigned short)(sw[i] & 0xffffu)), hi = (float)__builtin_bit_cast(_Float16, (unsigned short)(sw[i] >> 16));
;                       const unsigned klo = (f2key(lo) & ~127u) | (unsigned)(127 - (32 * g + 2 * i)), khi = (f2key(hi) & ~127u) | (unsigned)(127 - (32 * g + 2 * i + 1));
;                       if (i < 8) { k0[2 * i] = klo; k0[2 * i + 1] = khi; } else { k1[2 * (i - 8)] = klo; k1[2 * (i - 8) + 1] = khi; } } }
;                 sort16_desc(k0); sort16_desc(k1); merge16(k0, k1);
	v_cvt_f32_f16_sdwa v66, v54 dst_sel:DWORD dst_unused:UNUSED_PAD src0_sel:WORD_1
	v_cvt_f32_f16_e32 v54, v54
	v_and_b32_e32 v49, 0xffffff80, v49
	v_sub_u32_e32 v49, v49, v18
	v_not_b32_e32 v67, v66
	v_or_b32_e32 v68, 0x80000000, v66
	v_cmp_gt_i32_e32 vcc, 0, v66
	v_add_u32_e32 v65, 0x7e, v65
	v_add_u32_e32 v49, 0x7f, v49
	v_cndmask_b32_e32 v66, v68, v67, vcc
	v_not_b32_e32 v67, v54
	v_or_b32_e32 v68, 0x80000000, v54
	v_cmp_gt_i32_e32 vcc, 0, v54
	v_and_b32_e32 v66, 0xffffff80, v66
	v_sub_u32_e32 v66, v66, v20
	v_cndmask_b32_e32 v54, v68, v67, vcc
	v_cvt_f32_f16_sdwa v67, v55 dst_sel:DWORD dst_unused:UNUSED_PAD src0_sel:WORD_1
	v_cvt_f32_f16_e32 v55, v55
	v_and_b32_e32 v54, 0xffffff80, v54
	v_sub_u32_e32 v54, v54, v20
	v_not_b32_e32 v68, v67
	v_or_b32_e32 v69, 0x80000000, v67
	v_cmp_gt_i32_e32 vcc, 0, v67
	v_add_u32_e32 v66, 0x7e, v66
	v_add_u32_e32 v54, 0x7f, v54
	v_cndmask_b32_e32 v67, v69, v68, vcc
	v_not_b32_e32 v68, v55
	v_or_b32_e32 v69, 0x80000000, v55
	v_cmp_gt_i32_e32 vcc, 0, v55
	v_and_b32_e32 v67, 0xffffff80, v67
	v_sub_u32_e32 v67, v67, v21
	v_cndmask_b32_e32 v55, v69, v68, vcc
	v_cvt_f32_f16_sdwa v68, v56 dst_sel:DWORD dst_unused:UNUSED_PAD src0_sel:WORD_1
	v_cvt_f32_f16_e32 v56, v56
	v_and_b32_e32 v55, 0xffffff80, v55
	v_sub_u32_e32 v55, v55, v21
	v_not_b32_e32 v69, v68
	v_or_b32_e32 v70, 0x80000000, v68
	v_cmp_gt_i32_e32 vcc, 0, v68
	v_add_u32_e32 v67, 0x7e, v67
	v_add_u32_e32 v55, 0x7f, v55
	v_cndmask_b32_e32 v68, v70, v69, vcc
	v_not_b32_e32 v69, v56
	v_or_b32_e32 v70, 0x80000000, v56
	v_cmp_gt_i32_e32 vcc, 0, v56
	v_and_b32_e32 v68, 0xffffff80, v68
	v_sub_u32_e32 v68, v68, v22
	v_cndmask_b32_e32 v56, v70, v69, vcc
	v_cvt_f32_f16_sdwa v69, v57 dst_sel:DWORD dst_unused:UNUSED_PAD src0_sel:WORD_1
	v_cvt_f32_f16_e32 v57, v57
	v_and_b32_e32 v56, 0xffffff80, v56
	v_sub_u32_e32 v56, v56, v22
	v_not_b32_e32 v70, v69
	v_or_b32_e32 v71, 0x80000000, v69
	v_cmp_gt_i32_e32 vcc, 0, v69
	v_add_u32_e32 v68, 0x7e, v68
	v_add_u32_e32 v56, 0x7f, v56
	v_cndmask_b32_e32 v69, v71, v70, vcc
	v_not_b32_e32 v70, v57
	v_or_b32_e32 v71, 0x80000000, v57
	v_cmp_gt_i32_e32 vcc, 0, v57
	v_and_b32_e32 v69, 0xffffff80, v69
	v_sub_u32_e32 v69, v69, v23
	v_cndmask_b32_e32 v57, v71, v70, vcc
	v_cvt_f32_f16_sdwa v70, v0 dst_sel:DWORD dst_unused:UNUSED_PAD src0_sel:WORD_1
	v_cvt_f32_f16_e32 v0, v0
	v_and_b32_e32 v57, 0xffffff80, v57
	v_sub_u32_e32 v57, v57, v23
	v_not_b32_e32 v71, v70
	v_or_b32_e32 v72, 0x80000000, v70
	v_cmp_gt_i32_e32 vcc, 0, v70
	v_add_u32_e32 v69, 0x7e, v69
	v_add_u32_e32 v57, 0x7f, v57
	v_cndmask_b32_e32 v70, v72, v71, vcc
	v_not_b32_e32 v71, v0
	v_or_b32_e32 v72, 0x80000000, v0
	v_cmp_gt_i32_e32 vcc, 0, v0
	v_and_b32_e32 v70, 0xffffff80, v70
	v_sub_u32_e32 v70, v70, v24
	v_cndmask_b32_e32 v0, v72, v71, vcc
	v_cvt_f32_f16_sdwa v71, v1 dst_sel:DWORD dst_unused:UNUSED_PAD src0_sel:WORD_1
	v_cvt_f32_f16_e32 v1, v1
	v_and_b32_e32 v0, 0xffffff80, v0
	v_sub_u32_e32 v0, v0, v24
	v_not_b32_e32 v72, v71
	v_or_b32_e32 v73, 0x80000000, v71
	v_cmp_gt_i32_e32 vcc, 0, v71
	v_add_u32_e32 v70, 0x7e, v70
	v_add_u32_e32 v0, 0x7f, v0
	v_cndmask_b32_e32 v71, v73, v72, vcc
	v_not_b32_e32 v72, v1
	v_or_b32_e32 v73, 0x80000000, v1
	v_cmp_gt_i32_e32 vcc, 0, v1
	v_and_b32_e32 v71, 0xffffff80, v71
	v_sub_u32_e32 v71, v71, v25
	v_cndmask_b32_e32 v1, v73, v72, vcc
	v_cvt_f32_f16_sdwa v72, v2 dst_sel:DWORD dst_unused:UNUSED_PAD src0_sel:WORD_1
	v_cvt_f32_f16_e32 v2, v2
	v_and_b32_e32 v1, 0xffffff80, v1
	v_sub_u32_e32 v1, v1, v25
	v_not_b32_e32 v73, v72
	v_or_b32_e32 v74, 0x80000000, v72
	v_cmp_gt_i32_e32 vcc, 0, v72
	v_add_u32_e32 v71, 0x7e, v71
	v_add_u32_e32 v1, 0x7f, v1
	v_cndmask_b32_e32 v72, v74, v73, vcc
	v_not_b32_e32 v73, v2
	v_or_b32_e32 v74, 0x80000000, v2
	v_cmp_gt_i32_e32 vcc, 0, v2
	v_and_b32_e32 v72, 0xffffff80, v72
	v_sub_u32_e32 v72, v72, v26
	v_cndmask_b32_e32 v2, v74, v73, vcc
	v_cvt_f32_f16_sdwa v73, v3 dst_sel:DWORD dst_unused:UNUSED_PAD src0_sel:WORD_1
	v_cvt_f32_f16_e32 v3, v3
	v_and_b32_e32 v2, 0xffffff80, v2
	v_sub_u32_e32 v2, v2, v26
	v_not_b32_e32 v74, v73
	v_or_b32_e32 v75, 0x80000000, v73
	v_cmp_gt_i32_e32 vcc, 0, v73
	v_add_u32_e32 v72, 0x7e, v72
	v_add_u32_e32 v2, 0x7f, v2
	v_cndmask_b32_e32 v73, v75, v74, vcc
	v_not_b32_e32 v74, v3
	v_or_b32_e32 v75, 0x80000000, v3
	v_cmp_gt_i32_e32 vcc, 0, v3
	v_and_b32_e32 v73, 0xffffff80, v73
	v_sub_u32_e32 v73, v73, v28
	v_cndmask_b32_e32 v3, v75, v74, vcc
	v_and_b32_e32 v3, 0xffffff80, v3
	v_sub_u32_e32 v3, v3, v28
	v_add_u32_e32 v73, 0x7e, v73
	v_add_u32_e32 v3, 0x7f, v3
	v_max_u32_e32 v74, v50, v58
	v_min_u32_e32 v50, v50, v58
	v_max_u32_e32 v58, v59, v51
	v_min_u32_e32 v51, v59, v51
	v_max_u32_e32 v59, v52, v60
	v_min_u32_e32 v52, v52, v60
	v_max_u32_e32 v60, v61, v53
	v_min_u32_e32 v53, v61, v53
	v_max_u32_e32 v61, v46, v62
	v_min_u32_e32 v46, v46, v62
	v_max_u32_e32 v62, v63, v47
	v_min_u32_e32 v47, v63, v47
	v_max_u32_e32 v63, v48, v64
	v_min_u32_e32 v48, v48, v64
	v_max_u32_e32 v64, v65, v49
	v_min_u32_e32 v49, v65, v49
	v_max_u32_e32 v82, v54, v66
	v_min_u32_e32 v54, v54, v66
	v_max_u32_e32 v66, v67, v55
	v_min_u32_e32 v55, v67, v55
	v_max_u32_e32 v67, v56, v68
	v_min_u32_e32 v56, v56, v68
	v_max_u32_e32 v68, v69, v57
	v_min_u32_e32 v57, v69, v57
	v_max_u32_e32 v69, v0, v70
	v_min_u32_e32 v0, v0, v70
	v_max_u32_e32 v70, v71, v1
	v_min_u32_e32 v1, v71, v1
	v_max_u32_e32 v71, v2, v72
	v_min_u32_e32 v2, v2, v72
	v_max_u32_e32 v72, v73, v3
	v_min_u32_e32 v3, v73, v3
	v_max_u32_e32 v65, v74, v51
	v_min_u32_e32 v51, v74, v51
	v_max_u32_e32 v74, v50, v58
	v_min_u32_e32 v50, v50, v58
	v_max_u32_e32 v58, v53, v59
	v_min_u32_e32 v53, v53, v59
	v_max_u32_e32 v59, v60, v52
	v_min_u32_e32 v52, v60, v52
; #define CE_DESC(a, b) do { const unsigned _mx = (a) > (b) ? (a) : (b), _mn = (a) > (b) ? (b) : (a); (a) = _mx; (b) = _mn; } while (0)
; __device__ __forceinline__ void sort16_desc(unsigned (&k)[16]) {
; #pragma unroll
;     for (int size = 2; size <= 16; size <<= 1)
; #pragma unroll
;         for (int stride = size >> 1; stride > 0; stride >>= 1)
; #pragma unroll
;             for (int i = 0; i < 16; ++i) { const int j = i ^ stride;
;                 if (j > i) { if ((i & size) == 0) CE_DESC(k[i], k[j]); else CE_DESC(k[j], k[i]); } }
; }
	v_max_u32_e32 v60, v61, v47
	v_min_u32_e32 v47, v61, v47
	v_max_u32_e32 v61, v46, v62
	v_min_u32_e32 v46, v46, v62
	v_max_u32_e32 v62, v49, v63
	v_min_u32_e32 v49, v49, v63
	v_max_u32_e32 v63, v64, v48
	v_min_u32_e32 v48, v64, v48
	v_max_u32_e32 v73, v82, v55
	v_min_u32_e32 v55, v82, v55
	v_max_u32_e32 v82, v54, v66
	v_min_u32_e32 v54, v54, v66
	v_max_u32_e32 v66, v57, v67
	v_min_u32_e32 v57, v57, v67
	v_max_u32_e32 v67, v68, v56
	v_min_u32_e32 v56, v68, v56
	v_max_u32_e32 v68, v69, v1
	v_min_u32_e32 v1, v69, v1
	v_max_u32_e32 v69, v0, v70
	v_min_u32_e32 v0, v0, v70
	v_max_u32_e32 v70, v3, v71
	v_min_u32_e32 v3, v3, v71
	v_max_u32_e32 v71, v72, v2
	v_min_u32_e32 v2, v72, v2
	v_max_u32_e32 v64, v65, v74
	v_min_u32_e32 v65, v65, v74
	v_max_u32_e32 v74, v51, v50
	v_min_u32_e32 v50, v51, v50
	v_max_u32_e32 v51, v52, v53
	v_min_u32_e32 v52, v52, v53
	v_max_u32_e32 v53, v59, v58
	v_min_u32_e32 v58, v59, v58
	v_max_u32_e32 v59, v60, v61
	v_min_u32_e32 v60, v60, v61
	v_max_u32_e32 v61, v47, v46
	v_min_u32_e32 v46, v47, v46
	v_max_u32_e32 v47, v48, v49
	v_min_u32_e32 v48, v48, v49
	v_max_u32_e32 v49, v63, v62
	v_min_u32_e32 v62, v63, v62
	v_max_u32_e32 v72, v73, v82
	v_min_u32_e32 v73, v73, v82
	v_max_u32_e32 v82, v55, v54
	v_min_u32_e32 v54, v55, v54
	v_max_u32_e32 v55, v56, v57
	v_min_u32_e32 v56, v56, v57
	v_max_u32_e32 v57, v67, v66
	v_min_u32_e32 v66, v67, v66
	v_max_u32_e32 v67, v68, v69
	v_min_u32_e32 v68, v68, v69
	v_max_u32_e32 v69, v1, v0
	v_min_u32_e32 v0, v1, v0
	v_max_u32_e32 v1, v2, v3
	v_min_u32_e32 v2, v2, v3
	v_max_u32_e32 v3, v71, v70
	v_min_u32_e32 v70, v71, v70
	v_max_u32_e32 v63, v64, v52
	v_min_u32_e32 v52, v64, v52
	v_max_u32_e32 v64, v65, v51
	v_min_u32_e32 v51, v65, v51
	v_max_u32_e32 v65, v74, v58
	v_min_u32_e32 v58, v74, v58
	v_max_u32_e32 v74, v50, v53
	v_min_u32_e32 v50, v50, v53
	v_max_u32_e32 v53, v48, v59
	v_min_u32_e32 v48, v48, v59
	v_max_u32_e32 v59, v47, v60
	v_min_u32_e32 v47, v47, v60
	v_max_u32_e32 v60, v62, v61
	v_min_u32_e32 v61, v62, v61
	v_max_u32_e32 v62, v49, v46
	v_min_u32_e32 v46, v49, v46
	v_max_u32_e32 v71, v72, v56
	v_min_u32_e32 v56, v72, v56
	v_max_u32_e32 v72, v73, v55
	v_min_u32_e32 v55, v73, v55
	v_max_u32_e32 v73, v82, v66
	v_min_u32_e32 v66, v82, v66
	v_max_u32_e32 v82, v54, v57
	v_min_u32_e32 v54, v54, v57
	v_max_u32_e32 v57, v2, v67
	v_min_u32_e32 v2, v2, v67
	v_max_u32_e32 v67, v1, v68
	v_min_u32_e32 v1, v1, v68
	v_max_u32_e32 v68, v70, v69
	v_min_u32_e32 v69, v70, v69
	v_max_u32_e32 v70, v3, v0
	v_min_u32_e32 v0, v3, v0
	v_max_u32_e32 v49, v63, v65
	v_min_u32_e32 v63, v63, v65
	v_max_u32_e32 v65, v64, v74
	v_min_u32_e32 v64, v64, v74
	v_max_u32_e32 v74, v52, v58
	v_min_u32_e32 v52, v52, v58
	v_max_u32_e32 v58, v51, v50
	v_min_u32_e32 v50, v51, v50
	v_max_u32_e32 v51, v61, v48
	v_min_u32_e32 v48, v61, v48
	v_max_u32_e32 v61, v46, v47
	v_min_u32_e32 v46, v46, v47
	v_max_u32_e32 v47, v60, v53
	v_min_u32_e32 v53, v60, v53
	v_max_u32_e32 v60, v62, v59
	v_min_u32_e32 v59, v62, v59
	v_max_u32_e32 v3, v71, v73
	v_min_u32_e32 v71, v71, v73
	v_max_u32_e32 v73, v72, v82
	v_min_u32_e32 v72, v72, v82
	v_max_u32_e32 v82, v56, v66
	v_min_u32_e32 v56, v56, v66
	v_max_u32_e32 v66, v55, v54
	v_min_u32_e32 v54, v55, v54
	v_max_u32_e32 v55, v69, v2
	v_min_u32_e32 v2, v69, v2
	v_max_u32_e32 v69, v0, v1
	v_min_u32_e32 v0, v0, v1
	v_max_u32_e32 v1, v68, v57
	v_min_u32_e32 v57, v68, v57
	v_max_u32_e32 v68, v70, v67
	v_min_u32_e32 v67, v70, v67
	v_max_u32_e32 v62, v49, v65
	v_min_u32_e32 v49, v49, v65
	v_max_u32_e32 v65, v63, v64
	v_min_u32_e32 v63, v63, v64
	v_max_u32_e32 v64, v74, v58
	v_min_u32_e32 v58, v74, v58
	v_max_u32_e32 v74, v52, v50
	v_min_u32_e32 v50, v52, v50
	v_max_u32_e32 v52, v46, v48
	v_min_u32_e32 v46, v46, v48
	v_max_u32_e32 v48, v61, v51
	v_min_u32_e32 v51, v61, v51
	v_max_u32_e32 v61, v59, v53
	v_min_u32_e32 v53, v59, v53
	v_max_u32_e32 v59, v60, v47
	v_min_u32_e32 v47, v60, v47
	v_max_u32_e32 v70, v3, v73
	v_min_u32_e32 v3, v3, v73
	v_max_u32_e32 v73, v71, v72
	v_min_u32_e32 v71, v71, v72
	v_max_u32_e32 v72, v82, v66
	v_min_u32_e32 v66, v82, v66
	v_max_u32_e32 v82, v56, v54
	v_min_u32_e32 v54, v56, v54
	v_max_u32_e32 v56, v0, v2
	v_min_u32_e32 v0, v0, v2
	v_max_u32_e32 v2, v69, v55
	v_min_u32_e32 v55, v69, v55
	v_max_u32_e32 v69, v67, v57
	v_min_u32_e32 v57, v67, v57
	v_max_u32_e32 v67, v68, v1
	v_min_u32_e32 v1, v68, v1
	v_max_u32_e32 v60, v62, v46
	v_min_u32_e32 v46, v62, v46
	v_max_u32_e32 v62, v49, v52
	v_min_u32_e32 v49, v49, v52
	v_max_u32_e32 v52, v65, v51
	v_min_u32_e32 v51, v65, v51
	v_max_u32_e32 v65, v63, v48
	v_min_u32_e32 v48, v63, v48
	v_max_u32_e32 v63, v64, v53
	v_min_u32_e32 v53, v64, v53
	v_max_u32_e32 v64, v58, v61
	v_min_u32_e32 v58, v58, v61
	v_max_u32_e32 v61, v74, v47
	v_min_u32_e32 v47, v74, v47
	v_max_u32_e32 v74, v50, v59
	v_min_u32_e32 v50, v50, v59
	v_max_u32_e32 v68, v70, v0
	v_min_u32_e32 v0, v70, v0
	v_max_u32_e32 v70, v3, v56
	v_min_u32_e32 v3, v3, v56
	v_max_u32_e32 v56, v73, v55
	v_min_u32_e32 v55, v73, v55
	v_max_u32_e32 v73, v71, v2
	v_min_u32_e32 v2, v71, v2
	v_max_u32_e32 v71, v72, v57
	v_min_u32_e32 v57, v72, v57
	v_max_u32_e32 v72, v66, v69
	v_min_u32_e32 v66, v66, v69
	v_max_u32_e32 v69, v82, v1
	v_min_u32_e32 v1, v82, v1
	v_max_u32_e32 v82, v54, v67
	v_min_u32_e32 v54, v54, v67
	v_max_u32_e32 v59, v60, v63
	v_min_u32_e32 v60, v60, v63
	v_max_u32_e32 v63, v62, v64
	v_min_u32_e32 v62, v62, v64
	v_max_u32_e32 v64, v52, v61
	v_min_u32_e32 v52, v52, v61
	v_max_u32_e32 v61, v65, v74
	v_min_u32_e32 v65, v65, v74
	v_max_u32_e32 v74, v46, v53
	v_min_u32_e32 v46, v46, v53
	v_max_u32_e32 v53, v49, v58
	v_min_u32_e32 v49, v49, v58
	v_max_u32_e32 v58, v51, v47
; #define CE_DESC(a, b) do { const unsigned _mx = (a) > (b) ? (a) : (b), _mn = (a) > (b) ? (b) : (a); (a) = _mx; (b) = _mn; } while (0)
; __device__ __forceinline__ void merge16(unsigned (&a)[16], const unsigned (&b)[16]) {
; #pragma unroll
;     for (int i = 0; i < 16; ++i) a[i] = a[i] > b[15 - i] ? a[i] : b[15 - i];
; #pragma unroll
;     for (int stride = 8; stride > 0; stride >>= 1)
; #pragma unroll
;         for (int i = 0; i < 16; ++i) { const int j = i ^ stride; if (j > i) CE_DESC(a[i], a[j]); }
; }
; __device__ __forceinline__ void peer_tile(const Args& A, LAS unsigned char* lds, int tile) {
;     ...
;                 for (int msk = 16; msk <= 32; msk <<= 1) {
; #pragma unroll
;                     for (int i = 0; i < 16; ++i) k1[i] = (unsigned)__shfl_xor((int)k0[i], msk);
;                     merge16(k0, k1); }
	v_min_u32_e32 v47, v51, v47
	v_max_u32_e32 v51, v48, v50
	v_min_u32_e32 v48, v48, v50
	v_max_u32_e32 v67, v68, v71
	v_min_u32_e32 v68, v68, v71
	v_max_u32_e32 v71, v70, v72
	v_min_u32_e32 v70, v70, v72
	v_max_u32_e32 v72, v56, v69
	v_min_u32_e32 v56, v56, v69
	v_max_u32_e32 v69, v73, v82
	v_min_u32_e32 v73, v73, v82
	v_max_u32_e32 v82, v0, v57
	v_min_u32_e32 v0, v0, v57
	v_max_u32_e32 v57, v3, v66
	v_min_u32_e32 v3, v3, v66
	v_max_u32_e32 v66, v55, v1
	v_min_u32_e32 v1, v55, v1
	v_max_u32_e32 v55, v2, v54
	v_min_u32_e32 v2, v2, v54
	v_max_u32_e32 v50, v59, v64
	v_min_u32_e32 v59, v59, v64
	v_max_u32_e32 v64, v63, v61
	v_min_u32_e32 v61, v63, v61
	v_max_u32_e32 v63, v60, v52
	v_min_u32_e32 v52, v60, v52
	v_max_u32_e32 v60, v62, v65
	v_min_u32_e32 v62, v62, v65
	v_max_u32_e32 v65, v74, v58
	v_min_u32_e32 v58, v74, v58
	v_max_u32_e32 v74, v53, v51
	v_min_u32_e32 v51, v53, v51
	v_max_u32_e32 v53, v46, v47
	v_min_u32_e32 v46, v46, v47
	v_max_u32_e32 v47, v49, v48
	v_min_u32_e32 v48, v49, v48
	v_max_u32_e32 v54, v67, v72
	v_min_u32_e32 v67, v67, v72
	v_max_u32_e32 v72, v71, v69
	v_min_u32_e32 v69, v71, v69
	v_max_u32_e32 v71, v68, v56
	v_min_u32_e32 v56, v68, v56
	v_max_u32_e32 v68, v70, v73
	v_min_u32_e32 v70, v70, v73
	v_max_u32_e32 v73, v82, v66
	v_min_u32_e32 v66, v82, v66
	v_max_u32_e32 v82, v57, v55
	v_min_u32_e32 v55, v57, v55
	v_max_u32_e32 v57, v0, v1
	v_min_u32_e32 v0, v0, v1
	v_max_u32_e32 v1, v3, v2
	v_min_u32_e32 v2, v3, v2
	v_min_u32_e32 v49, v50, v64
	v_min_u32_e32 v75, v59, v61
	v_min_u32_e32 v76, v63, v60
	v_min_u32_e32 v77, v52, v62
	v_min_u32_e32 v78, v65, v74
	v_min_u32_e32 v79, v58, v51
	v_min_u32_e32 v80, v53, v47
	v_min_u32_e32 v81, v46, v48
	v_min_u32_e32 v3, v54, v72
	v_min_u32_e32 v83, v67, v69
	v_min_u32_e32 v84, v71, v68
	v_min_u32_e32 v85, v56, v70
	v_min_u32_e32 v86, v73, v82
	v_min_u32_e32 v87, v66, v55
	v_min_u32_e32 v88, v57, v1
	v_min_u32_e32 v89, v0, v2
	v_max3_u32 v50, v50, v64, v89
	v_max3_u32 v0, v49, v0, v2
	v_max3_u32 v2, v59, v61, v88
	v_max3_u32 v1, v75, v57, v1
	v_max3_u32 v49, v63, v60, v87
	v_max3_u32 v55, v76, v66, v55
	v_max3_u32 v52, v52, v62, v86
	v_max3_u32 v57, v77, v73, v82
	v_max3_u32 v59, v65, v74, v85
	v_max3_u32 v56, v78, v56, v70
	v_max3_u32 v51, v58, v51, v84
	v_max3_u32 v58, v79, v71, v68
	v_max3_u32 v47, v53, v47, v83
	v_max3_u32 v53, v80, v67, v69
	v_max3_u32 v3, v46, v48, v3
	v_max3_u32 v46, v81, v54, v72
	v_max_u32_e32 v48, v50, v59
	v_min_u32_e32 v50, v50, v59
	v_max_u32_e32 v54, v0, v56
	v_min_u32_e32 v0, v0, v56
	v_max_u32_e32 v56, v2, v51
	v_min_u32_e32 v2, v2, v51
	v_max_u32_e32 v51, v1, v58
	v_min_u32_e32 v1, v1, v58
	v_max_u32_e32 v58, v49, v47
	v_min_u32_e32 v47, v49, v47
	v_max_u32_e32 v49, v55, v53
	v_min_u32_e32 v53, v55, v53
	v_max_u32_e32 v55, v52, v3
	v_min_u32_e32 v3, v52, v3
	v_max_u32_e32 v52, v57, v46
	v_min_u32_e32 v46, v57, v46
	v_max_u32_e32 v57, v48, v58
	v_min_u32_e32 v48, v48, v58
	v_max_u32_e32 v58, v54, v49
	v_min_u32_e32 v49, v54, v49
	v_max_u32_e32 v54, v56, v55
	v_min_u32_e32 v55, v56, v55
	v_max_u32_e32 v56, v51, v52
	v_min_u32_e32 v51, v51, v52
	v_max_u32_e32 v52, v50, v47
	v_min_u32_e32 v47, v50, v47
	v_max_u32_e32 v50, v0, v53
	v_min_u32_e32 v0, v0, v53
	v_max_u32_e32 v53, v2, v3
	v_min_u32_e32 v2, v2, v3
	v_max_u32_e32 v3, v1, v46
	v_min_u32_e32 v1, v1, v46
	v_max_u32_e32 v46, v57, v54
	v_min_u32_e32 v54, v57, v54
	v_max_u32_e32 v57, v58, v56
	v_min_u32_e32 v56, v58, v56
	v_max_u32_e32 v58, v48, v55
	v_min_u32_e32 v48, v48, v55
	v_max_u32_e32 v55, v49, v51
	v_min_u32_e32 v49, v49, v51
	v_max_u32_e32 v51, v52, v53
	v_min_u32_e32 v52, v52, v53
	v_max_u32_e32 v53, v50, v3
	v_min_u32_e32 v3, v50, v3
	v_max_u32_e32 v50, v47, v2
	v_min_u32_e32 v2, v47, v2
	v_max_u32_e32 v47, v0, v1
	v_min_u32_e32 v0, v0, v1
	v_max_u32_e32 v1, v46, v57
	v_min_u32_e32 v46, v46, v57
	v_max_u32_e32 v57, v54, v56
	v_min_u32_e32 v54, v54, v56
	v_max_u32_e32 v56, v58, v55
	v_min_u32_e32 v55, v58, v55
	v_max_u32_e32 v58, v48, v49
	v_min_u32_e32 v48, v48, v49
	v_max_u32_e32 v49, v51, v53
	v_min_u32_e32 v51, v51, v53
	v_max_u32_e32 v53, v52, v3
	v_min_u32_e32 v3, v52, v3
	v_max_u32_e32 v52, v50, v47
	v_min_u32_e32 v47, v50, v47
	v_max_u32_e32 v50, v2, v0
	v_min_u32_e32 v0, v2, v0
	ds_bpermute_b32 v2, v27, v1
	ds_bpermute_b32 v59, v27, v46
	ds_bpermute_b32 v60, v27, v57
	ds_bpermute_b32 v61, v27, v54
	ds_bpermute_b32 v62, v27, v56
	ds_bpermute_b32 v63, v27, v55
	ds_bpermute_b32 v64, v27, v58
	ds_bpermute_b32 v65, v27, v48
	ds_bpermute_b32 v66, v27, v49
	ds_bpermute_b32 v67, v27, v51
	ds_bpermute_b32 v68, v27, v53
	ds_bpermute_b32 v69, v27, v0
	ds_bpermute_b32 v70, v27, v50
	ds_bpermute_b32 v71, v27, v47
	ds_bpermute_b32 v72, v27, v52
	ds_bpermute_b32 v73, v27, v3
	s_waitcnt lgkmcnt(4)
	v_max_u32_e32 v1, v1, v69
	s_waitcnt lgkmcnt(3)
	v_max_u32_e32 v46, v46, v70
	s_waitcnt lgkmcnt(2)
	v_max_u32_e32 v57, v57, v71
	s_waitcnt lgkmcnt(1)
	v_max_u32_e32 v54, v54, v72
	s_waitcnt lgkmcnt(0)
; #define CE_DESC(a, b) do { const unsigned _mx = (a) > (b) ? (a) : (b), _mn = (a) > (b) ? (b) : (a); (a) = _mx; (b) = _mn; } while (0)
; __device__ __forceinline__ void merge16(unsigned (&a)[16], const unsigned (&b)[16]) {
; #pragma unroll
;     for (int i = 0; i < 16; ++i) a[i] = a[i] > b[15 - i] ? a[i] : b[15 - i];
; #pragma unroll
;     for (int stride = 8; stride > 0; stride >>= 1)
; #pragma unroll
;         for (int i = 0; i < 16; ++i) { const int j = i ^ stride; if (j > i) CE_DESC(a[i], a[j]); }
; }
; __device__ __forceinline__ void peer_tile(const Args& A, LAS unsigned char* lds, int tile) {
;     ...
;                 for (int msk = 16; msk <= 32; msk <<= 1) {
; #pragma unroll
;                     for (int i = 0; i < 16; ++i) k1[i] = (unsigned)__shfl_xor((int)k0[i], msk);
;                     merge16(k0, k1); }
	v_max_u32_e32 v56, v56, v73
	v_max_u32_e32 v55, v55, v68
	v_max_u32_e32 v58, v58, v67
	v_max_u32_e32 v48, v48, v66
	v_max_u32_e32 v49, v49, v65
	v_max_u32_e32 v51, v51, v64
	v_max_u32_e32 v53, v53, v63
	v_max_u32_e32 v3, v3, v62
	v_max_u32_e32 v52, v52, v61
	v_max_u32_e32 v47, v47, v60
	v_max_u32_e32 v50, v50, v59
	v_max_u32_e32 v0, v0, v2
	v_max_u32_e32 v2, v1, v49
	v_min_u32_e32 v1, v1, v49
	v_max_u32_e32 v49, v46, v51
	v_min_u32_e32 v46, v46, v51
	v_max_u32_e32 v51, v57, v53
	v_min_u32_e32 v53, v57, v53
	v_max_u32_e32 v57, v54, v3
	v_min_u32_e32 v3, v54, v3
	v_max_u32_e32 v54, v56, v52
	v_min_u32_e32 v52, v56, v52
	v_max_u32_e32 v56, v55, v47
	v_min_u32_e32 v47, v55, v47
	v_max_u32_e32 v55, v58, v50
	v_min_u32_e32 v50, v58, v50
	v_max_u32_e32 v58, v48, v0
	v_min_u32_e32 v0, v48, v0
	v_max_u32_e32 v48, v2, v54
	v_min_u32_e32 v2, v2, v54
	v_max_u32_e32 v54, v49, v56
	v_min_u32_e32 v49, v49, v56
	v_max_u32_e32 v56, v51, v55
	v_min_u32_e32 v51, v51, v55
	v_max_u32_e32 v55, v57, v58
	v_min_u32_e32 v57, v57, v58
	v_max_u32_e32 v58, v1, v52
	v_min_u32_e32 v1, v1, v52
	v_max_u32_e32 v52, v46, v47
	v_min_u32_e32 v46, v46, v47
	v_max_u32_e32 v47, v53, v50
	v_min_u32_e32 v50, v53, v50
	v_max_u32_e32 v53, v3, v0
	v_min_u32_e32 v0, v3, v0
	v_max_u32_e32 v3, v48, v56
	v_min_u32_e32 v48, v48, v56
	v_max_u32_e32 v56, v54, v55
	v_min_u32_e32 v54, v54, v55
	v_max_u32_e32 v55, v2, v51
	v_min_u32_e32 v2, v2, v51
	v_max_u32_e32 v51, v49, v57
	v_min_u32_e32 v49, v49, v57
	v_max_u32_e32 v57, v58, v47
	v_min_u32_e32 v47, v58, v47
	v_max_u32_e32 v58, v52, v53
	v_min_u32_e32 v52, v52, v53
	v_max_u32_e32 v53, v1, v50
	v_min_u32_e32 v1, v1, v50
	v_max_u32_e32 v50, v46, v0
	v_min_u32_e32 v0, v46, v0
	v_max_u32_e32 v46, v3, v56
	v_min_u32_e32 v3, v3, v56
	v_max_u32_e32 v56, v48, v54
	v_min_u32_e32 v48, v48, v54
	v_max_u32_e32 v54, v55, v51
	v_min_u32_e32 v51, v55, v51
	v_max_u32_e32 v55, v2, v49
	v_min_u32_e32 v2, v2, v49
	v_max_u32_e32 v49, v57, v58
	v_min_u32_e32 v57, v57, v58
	v_max_u32_e32 v58, v47, v52
	v_min_u32_e32 v47, v47, v52
	v_max_u32_e32 v52, v53, v50
	v_min_u32_e32 v50, v53, v50
	v_max_u32_e32 v53, v1, v0
	v_min_u32_e32 v0, v1, v0
	ds_bpermute_b32 v62, v29, v0
	ds_bpermute_b32 v1, v29, v46
	ds_bpermute_b32 v59, v29, v3
	ds_bpermute_b32 v60, v29, v56
	ds_bpermute_b32 v61, v29, v48
	s_waitcnt lgkmcnt(4)
	v_max_u32_e32 v46, v46, v62
	global_load_dwordx4 v[62:65], v[4:5], off offset:528
	global_load_dwordx4 v[66:69], v[4:5], off offset:512
	ds_bpermute_b32 v70, v29, v54
	ds_bpermute_b32 v71, v29, v51
	ds_bpermute_b32 v72, v29, v55
	ds_bpermute_b32 v73, v29, v2
	ds_bpermute_b32 v74, v29, v49
	ds_bpermute_b32 v75, v29, v57
	ds_bpermute_b32 v76, v29, v58
	ds_bpermute_b32 v77, v29, v47
	ds_bpermute_b32 v78, v29, v52
	ds_bpermute_b32 v79, v29, v53
	ds_bpermute_b32 v80, v29, v50
	s_waitcnt lgkmcnt(4)
	v_max_u32_e32 v51, v51, v76
	s_waitcnt lgkmcnt(3)
	v_max_u32_e32 v54, v54, v77
	s_waitcnt lgkmcnt(2)
	v_max_u32_e32 v48, v48, v78
	s_waitcnt lgkmcnt(1)
	v_max_u32_e32 v3, v3, v79
	s_waitcnt lgkmcnt(0)
	v_max_u32_e32 v56, v56, v80
	v_max_u32_e32 v55, v55, v75
	v_max_u32_e32 v2, v2, v74
	v_max_u32_e32 v49, v49, v73
	v_max_u32_e32 v57, v57, v72
	v_max_u32_e32 v58, v58, v71
	v_max_u32_e32 v47, v47, v70
	v_max_u32_e32 v52, v52, v61
	v_max_u32_e32 v50, v50, v60
	v_max_u32_e32 v53, v53, v59
	v_max_u32_e32 v0, v0, v1
	v_max_u32_e32 v1, v46, v49
	v_min_u32_e32 v46, v46, v49
	v_max_u32_e32 v49, v3, v57
	v_min_u32_e32 v3, v3, v57
	v_max_u32_e32 v57, v56, v58
	v_min_u32_e32 v56, v56, v58
	v_max_u32_e32 v58, v48, v47
	v_min_u32_e32 v47, v48, v47
	v_max_u32_e32 v48, v54, v52
	v_min_u32_e32 v52, v54, v52
	v_max_u32_e32 v54, v51, v50
	v_min_u32_e32 v50, v51, v50
	v_max_u32_e32 v51, v55, v53
	v_min_u32_e32 v53, v55, v53
	v_max_u32_e32 v55, v2, v0
	v_min_u32_e32 v0, v2, v0
	v_max_u32_e32 v2, v1, v48
	v_min_u32_e32 v1, v1, v48
	v_max_u32_e32 v48, v49, v54
	v_min_u32_e32 v49, v49, v54
	v_max_u32_e32 v54, v57, v51
	v_min_u32_e32 v51, v57, v51
	v_max_u32_e32 v57, v58, v55
	v_min_u32_e32 v55, v58, v55
	v_max_u32_e32 v58, v46, v52
	v_min_u32_e32 v46, v46, v52
	v_max_u32_e32 v52, v3, v50
	v_min_u32_e32 v3, v3, v50
	v_max_u32_e32 v50, v56, v53
	v_min_u32_e32 v53, v56, v53
	v_max_u32_e32 v56, v47, v0
	v_min_u32_e32 v0, v47, v0
	v_max_u32_e32 v47, v2, v54
	v_min_u32_e32 v2, v2, v54
	v_max_u32_e32 v54, v48, v57
	v_min_u32_e32 v48, v48, v57
	v_max_u32_e32 v70, v1, v51
	v_min_u32_e32 v1, v1, v51
	v_max_u32_e32 v51, v49, v55
	v_min_u32_e32 v49, v49, v55
	v_max_u32_e32 v71, v58, v50
	v_min_u32_e32 v50, v58, v50
	v_max_u32_e32 v72, v52, v56
	v_min_u32_e32 v73, v52, v56
	v_max_u32_e32 v74, v46, v53
	v_min_u32_e32 v46, v46, v53
	v_max_u32_e32 v75, v3, v0
	v_min_u32_e32 v0, v3, v0
	v_max_u32_e32 v61, v47, v54
	v_min_u32_e32 v60, v47, v54
	v_max_u32_e32 v59, v2, v48
	v_min_u32_e32 v58, v2, v48
	v_max_u32_e32 v57, v70, v51
	v_min_u32_e32 v56, v70, v51
	v_max_u32_e32 v55, v1, v49
	v_min_u32_e32 v54, v1, v49
	v_max_u32_e32 v53, v71, v72
	v_min_u32_e32 v52, v71, v72
	v_max_u32_e32 v51, v50, v73
	v_min_u32_e32 v50, v50, v73
	v_max_u32_e32 v47, v46, v0
	v_min_u32_e32 v46, v46, v0
	global_load_dwordx4 v[0:3], v[4:5], off offset:560
	global_load_dwordx4 v[70:73], v[4:5], off offset:544
	v_max_u32_e32 v49, v74, v75
	v_min_u32_e32 v48, v74, v75
	s_waitcnt vmcnt(2)
; __device__ __forceinline__ unsigned f2key(float f) { const unsigned u = __float_as_uint(f); return (u & 0x80000000u) ? ~u : (u | 0x80000000u); }
; __device__ __forceinline__ void peer_tile(const Args& A, LAS unsigned char* lds, int tile) {
;     ...
;                 { const bf16_t* sp = QRY + m * 2048 + hp * 128 + 32 * g;
;                   const u32x4 s0 = *(const u32x4*)sp, s1 = *(const u32x4*)(sp + 8), s2 = *(const u32x4*)(sp + 16), s3 = *(const u32x4*)(sp + 24);
;                   const unsigned sw[16] = {s0.x, s0.y, s0.z, s0.w, s1.x, s1.y, s1.z, s1.w, s2.x, s2.y, s2.z, s2.w, s3.x, s3.y, s3.z, s3.w};
; #pragma unroll
;                   for (int i = 0; i < 16; ++i) {
;                       const float lo = (float)__builtin_bit_cast(_Float16, (unsigned short)(sw[i] & 0xffffu)), hi = (float)__builtin_bit_cast(_Float16, (unsigned short)(sw[i] >> 16));
;                       const unsigned klo = (f2key(lo) & ~127u) | (unsigned)(127 - (32 * g + 2 * i)), khi = (f2key(hi) & ~127u) | (unsigned)(127 - (32 * g + 2 * i + 1));
;                       if (i < 8) { k0[2 * i] = klo; k0[2 * i + 1] = khi; } else { k1[2 * (i - 8)] = klo; k1[2 * (i - 8) + 1] = khi; } } }
	v_cvt_f32_f16_sdwa v74, v66 dst_sel:DWORD dst_unused:UNUSED_PAD src0_sel:WORD_1
	v_cvt_f32_f16_e32 v66, v66
	v_not_b32_e32 v75, v74
	v_or_b32_e32 v76, 0x80000000, v74
	v_cmp_gt_i32_e32 vcc, 0, v74
	s_nop 1
	v_cndmask_b32_e32 v74, v76, v75, vcc
	v_not_b32_e32 v75, v66
	v_or_b32_e32 v76, 0x80000000, v66
	v_cmp_gt_i32_e32 vcc, 0, v66
	v_and_b32_e32 v74, 0xffffff80, v74
	v_sub_u32_e32 v74, v74, v15
	v_cndmask_b32_e32 v66, v76, v75, vcc
	v_cvt_f32_f16_sdwa v75, v67 dst_sel:DWORD dst_unused:UNUSED_PAD src0_sel:WORD_1
	v_cvt_f32_f16_e32 v67, v67
	v_and_b32_e32 v66, 0xffffff80, v66
	v_sub_u32_e32 v66, v66, v15
	v_not_b32_e32 v76, v75
	v_or_b32_e32 v77, 0x80000000, v75
	v_cmp_gt_i32_e32 vcc, 0, v75
	v_add_u32_e32 v74, 0x7e, v74
	v_add_u32_e32 v66, 0x7f, v66
	v_cndmask_b32_e32 v75, v77, v76, vcc
	v_not_b32_e32 v76, v67
	v_or_b32_e32 v77, 0x80000000, v67
	v_cmp_gt_i32_e32 vcc, 0, v67
	v_and_b32_e32 v75, 0xffffff80, v75
	v_sub_u32_e32 v75, v75, v14
	v_cndmask_b32_e32 v67, v77, v76, vcc
	v_cvt_f32_f16_sdwa v76, v68 dst_sel:DWORD dst_unused:UNUSED_PAD src0_sel:WORD_1
	v_cvt_f32_f16_e32 v68, v68
	v_and_b32_e32 v67, 0xffffff80, v67
	v_sub_u32_e32 v67, v67, v14
	v_not_b32_e32 v77, v76
	v_or_b32_e32 v78, 0x80000000, v76
	v_cmp_gt_i32_e32 vcc, 0, v76
	v_add_u32_e32 v75, 0x7e, v75
	v_add_u32_e32 v67, 0x7f, v67
	v_cndmask_b32_e32 v76, v78, v77, vcc
	v_not_b32_e32 v77, v68
	v_or_b32_e32 v78, 0x80000000, v68
	v_cmp_gt_i32_e32 vcc, 0, v68
	v_and_b32_e32 v76, 0xffffff80, v76
	v_sub_u32_e32 v76, v76, v12
	v_cndmask_b32_e32 v68, v78, v77, vcc
	v_cvt_f32_f16_sdwa v77, v69 dst_sel:DWORD dst_unused:UNUSED_PAD src0_sel:WORD_1
	v_cvt_f32_f16_e32 v69, v69
	v_and_b32_e32 v68, 0xffffff80, v68
	v_sub_u32_e32 v68, v68, v12
	v_not_b32_e32 v78, v77
	v_or_b32_e32 v79, 0x80000000, v77
	v_cmp_gt_i32_e32 vcc, 0, v77
	v_add_u32_e32 v76, 0x7e, v76
	v_add_u32_e32 v68, 0x7f, v68
	v_cndmask_b32_e32 v77, v79, v78, vcc
	v_not_b32_e32 v78, v69
	v_or_b32_e32 v79, 0x80000000, v69
	v_cmp_gt_i32_e32 vcc, 0, v69
	v_and_b32_e32 v77, 0xffffff80, v77
	v_sub_u32_e32 v77, v77, v10
	v_cndmask_b32_e32 v69, v79, v78, vcc
	v_cvt_f32_f16_sdwa v78, v62 dst_sel:DWORD dst_unused:UNUSED_PAD src0_sel:WORD_1
	v_cvt_f32_f16_e32 v62, v62
	v_and_b32_e32 v69, 0xffffff80, v69
	v_sub_u32_e32 v69, v69, v10
	v_not_b32_e32 v79, v78
	v_or_b32_e32 v80, 0x80000000, v78
	v_cmp_gt_i32_e32 vcc, 0, v78
	v_add_u32_e32 v77, 0x7e, v77
	v_add_u32_e32 v69, 0x7f, v69
	v_cndmask_b32_e32 v78, v80, v79, vcc
	v_not_b32_e32 v79, v62
	v_or_b32_e32 v80, 0x80000000, v62
	v_cmp_gt_i32_e32 vcc, 0, v62
	v_and_b32_e32 v78, 0xffffff80, v78
	v_sub_u32_e32 v78, v78, v8
	v_cndmask_b32_e32 v62, v80, v79, vcc
	v_cvt_f32_f16_sdwa v79, v63 dst_sel:DWORD dst_unused:UNUSED_PAD src0_sel:WORD_1
	v_cvt_f32_f16_e32 v63, v63
	v_and_b32_e32 v62, 0xffffff80, v62
	v_sub_u32_e32 v62, v62, v8
	v_not_b32_e32 v80, v79
	v_or_b32_e32 v81, 0x80000000, v79
	v_cmp_gt_i32_e32 vcc, 0, v79
	v_add_u32_e32 v78, 0x7e, v78
	v_add_u32_e32 v62, 0x7f, v62
	v_cndmask_b32_e32 v79, v81, v80, vcc
	v_not_b32_e32 v80, v63
	v_or_b32_e32 v81, 0x80000000, v63
	v_cmp_gt_i32_e32 vcc, 0, v63
	v_and_b32_e32 v79, 0xffffff80, v79
	v_sub_u32_e32 v79, v79, v16
	v_cndmask_b32_e32 v63, v81, v80, vcc
	v_cvt_f32_f16_sdwa v80, v64 dst_sel:DWORD dst_unused:UNUSED_PAD src0_sel:WORD_1
	v_cvt_f32_f16_e32 v64, v64
	v_and_b32_e32 v63, 0xffffff80, v63
	v_sub_u32_e32 v63, v63, v16
	v_not_b32_e32 v81, v80
	v_or_b32_e32 v82, 0x80000000, v80
	v_cmp_gt_i32_e32 vcc, 0, v80
	v_add_u32_e32 v79, 0x7e, v79
	v_add_u32_e32 v63, 0x7f, v63
	v_cndmask_b32_e32 v80, v82, v81, vcc
	v_not_b32_e32 v81, v64
	v_or_b32_e32 v82, 0x80000000, v64
	v_cmp_gt_i32_e32 vcc, 0, v64
	v_and_b32_e32 v80, 0xffffff80, v80
	v_sub_u32_e32 v80, v80, v17
	v_cndmask_b32_e32 v64, v82, v81, vcc
	v_cvt_f32_f16_sdwa v81, v65 dst_sel:DWORD dst_unused:UNUSED_PAD src0_sel:WORD_1
	v_cvt_f32_f16_e32 v65, v65
	v_and_b32_e32 v64, 0xffffff80, v64
	v_sub_u32_e32 v64, v64, v17
	v_not_b32_e32 v82, v81
	v_or_b32_e32 v83, 0x80000000, v81
	v_cmp_gt_i32_e32 vcc, 0, v81
	v_add_u32_e32 v80, 0x7e, v80
	v_add_u32_e32 v64, 0x7f, v64
	v_cndmask_b32_e32 v81, v83, v82, vcc
	v_not_b32_e32 v82, v65
	v_or_b32_e32 v83, 0x80000000, v65
	v_cmp_gt_i32_e32 vcc, 0, v65
	v_and_b32_e32 v81, 0xffffff80, v81
	v_sub_u32_e32 v81, v81, v18
	v_cndmask_b32_e32 v65, v83, v82, vcc
	s_waitcnt vmcnt(0)
; __device__ __forceinline__ unsigned f2key(float f) { const unsigned u = __float_as_uint(f); return (u & 0x80000000u) ? ~u : (u | 0x80000000u); }
; #define CE_DESC(a, b) do { const unsigned _mx = (a) > (b) ? (a) : (b), _mn = (a) > (b) ? (b) : (a); (a) = _mx; (b) = _mn; } while (0)
; __device__ __forceinline__ void sort16_desc(unsigned (&k)[16]) {
; #pragma unroll
;     for (int size = 2; size <= 16; size <<= 1)
; #pragma unroll
;         for (int stride = size >> 1; stride > 0; stride >>= 1)
; #pragma unroll
;             for (int i = 0; i < 16; ++i) { const int j = i ^ stride;
;                 if (j > i) { if ((i & size) == 0) CE_DESC(k[i], k[j]); else CE_DESC(k[j], k[i]); } }
; }
; __device__ __forceinline__ void peer_tile(const Args& A, LAS unsigned char* lds, int tile) {
;     ...
;                   for (int i = 0; i < 16; ++i) {
;                       const float lo = (float)__builtin_bit_cast(_Float16, (unsigned short)(sw[i] & 0xffffu)), hi = (float)__builtin_bit_cast(_Float16, (unsigned short)(sw[i] >> 16));
;                       const unsigned klo = (f2key(lo) & ~127u) | (unsigned)(127 - (32 * g + 2 * i)), khi = (f2key(hi) & ~127u) | (unsigned)(127 - (32 * g + 2 * i + 1));
;                       if (i < 8) { k0[2 * i] = klo; k0[2 * i + 1] = khi; } else { k1[2 * (i - 8)] = klo; k1[2 * (i - 8) + 1] = khi; } } }
;                 sort16_desc(k0); sort16_desc(k1); merge16(k0, k1);
	v_cvt_f32_f16_sdwa v82, v70 dst_sel:DWORD dst_unused:UNUSED_PAD src0_sel:WORD_1
	v_cvt_f32_f16_e32 v70, v70
	v_and_b32_e32 v65, 0xffffff80, v65
	v_sub_u32_e32 v65, v65, v18
	v_not_b32_e32 v83, v82
	v_or_b32_e32 v84, 0x80000000, v82
	v_cmp_gt_i32_e32 vcc, 0, v82
	v_add_u32_e32 v81, 0x7e, v81
	v_add_u32_e32 v65, 0x7f, v65
	v_cndmask_b32_e32 v82, v84, v83, vcc
	v_not_b32_e32 v83, v70
	v_or_b32_e32 v84, 0x80000000, v70
	v_cmp_gt_i32_e32 vcc, 0, v70
	v_and_b32_e32 v82, 0xffffff80, v82
	v_sub_u32_e32 v82, v82, v20
	v_cndmask_b32_e32 v70, v84, v83, vcc
	v_cvt_f32_f16_sdwa v83, v71 dst_sel:DWORD dst_unused:UNUSED_PAD src0_sel:WORD_1
	v_cvt_f32_f16_e32 v71, v71
	v_and_b32_e32 v70, 0xffffff80, v70
	v_sub_u32_e32 v70, v70, v20
	v_not_b32_e32 v84, v83
	v_or_b32_e32 v85, 0x80000000, v83
	v_cmp_gt_i32_e32 vcc, 0, v83
	v_add_u32_e32 v82, 0x7e, v82
	v_add_u32_e32 v70, 0x7f, v70
	v_cndmask_b32_e32 v83, v85, v84, vcc
	v_not_b32_e32 v84, v71
	v_or_b32_e32 v85, 0x80000000, v71
	v_cmp_gt_i32_e32 vcc, 0, v71
	v_and_b32_e32 v83, 0xffffff80, v83
	v_sub_u32_e32 v83, v83, v21
	v_cndmask_b32_e32 v71, v85, v84, vcc
	v_cvt_f32_f16_sdwa v84, v72 dst_sel:DWORD dst_unused:UNUSED_PAD src0_sel:WORD_1
	v_cvt_f32_f16_e32 v72, v72
	v_and_b32_e32 v71, 0xffffff80, v71
	v_sub_u32_e32 v71, v71, v21
	v_not_b32_e32 v85, v84
	v_or_b32_e32 v86, 0x80000000, v84
	v_cmp_gt_i32_e32 vcc, 0, v84
	v_add_u32_e32 v83, 0x7e, v83
	v_add_u32_e32 v71, 0x7f, v71
	v_cndmask_b32_e32 v84, v86, v85, vcc
	v_not_b32_e32 v85, v72
	v_or_b32_e32 v86, 0x80000000, v72
	v_cmp_gt_i32_e32 vcc, 0, v72
	v_and_b32_e32 v84, 0xffffff80, v84
	v_sub_u32_e32 v84, v84, v22
	v_cndmask_b32_e32 v72, v86, v85, vcc
	v_cvt_f32_f16_sdwa v85, v73 dst_sel:DWORD dst_unused:UNUSED_PAD src0_sel:WORD_1
	v_cvt_f32_f16_e32 v73, v73
	v_and_b32_e32 v72, 0xffffff80, v72
	v_sub_u32_e32 v72, v72, v22
	v_not_b32_e32 v86, v85
	v_or_b32_e32 v87, 0x80000000, v85
	v_cmp_gt_i32_e32 vcc, 0, v85
	v_add_u32_e32 v84, 0x7e, v84
	v_add_u32_e32 v72, 0x7f, v72
	v_cndmask_b32_e32 v85, v87, v86, vcc
	v_not_b32_e32 v86, v73
	v_or_b32_e32 v87, 0x80000000, v73
	v_cmp_gt_i32_e32 vcc, 0, v73
	v_and_b32_e32 v85, 0xffffff80, v85
	v_sub_u32_e32 v85, v85, v23
	v_cndmask_b32_e32 v73, v87, v86, vcc
	v_cvt_f32_f16_sdwa v86, v0 dst_sel:DWORD dst_unused:UNUSED_PAD src0_sel:WORD_1
	v_cvt_f32_f16_e32 v0, v0
	v_and_b32_e32 v73, 0xffffff80, v73
	v_sub_u32_e32 v73, v73, v23
	v_not_b32_e32 v87, v86
	v_or_b32_e32 v88, 0x80000000, v86
	v_cmp_gt_i32_e32 vcc, 0, v86
	v_add_u32_e32 v85, 0x7e, v85
	v_add_u32_e32 v73, 0x7f, v73
	v_cndmask_b32_e32 v86, v88, v87, vcc
	v_not_b32_e32 v87, v0
	v_or_b32_e32 v88, 0x80000000, v0
	v_cmp_gt_i32_e32 vcc, 0, v0
	v_and_b32_e32 v86, 0xffffff80, v86
	v_sub_u32_e32 v86, v86, v24
	v_cndmask_b32_e32 v0, v88, v87, vcc
	v_cvt_f32_f16_sdwa v87, v1 dst_sel:DWORD dst_unused:UNUSED_PAD src0_sel:WORD_1
	v_cvt_f32_f16_e32 v1, v1
	v_and_b32_e32 v0, 0xffffff80, v0
	v_sub_u32_e32 v0, v0, v24
	v_not_b32_e32 v88, v87
	v_or_b32_e32 v89, 0x80000000, v87
	v_cmp_gt_i32_e32 vcc, 0, v87
	v_add_u32_e32 v86, 0x7e, v86
	v_add_u32_e32 v0, 0x7f, v0
	v_cndmask_b32_e32 v87, v89, v88, vcc
	v_not_b32_e32 v88, v1
	v_or_b32_e32 v89, 0x80000000, v1
	v_cmp_gt_i32_e32 vcc, 0, v1
	v_and_b32_e32 v87, 0xffffff80, v87
	v_sub_u32_e32 v87, v87, v25
	v_cndmask_b32_e32 v1, v89, v88, vcc
	v_cvt_f32_f16_sdwa v88, v2 dst_sel:DWORD dst_unused:UNUSED_PAD src0_sel:WORD_1
	v_cvt_f32_f16_e32 v2, v2
	v_and_b32_e32 v1, 0xffffff80, v1
	v_sub_u32_e32 v1, v1, v25
	v_not_b32_e32 v89, v88
	v_or_b32_e32 v90, 0x80000000, v88
	v_cmp_gt_i32_e32 vcc, 0, v88
	v_add_u32_e32 v87, 0x7e, v87
	v_add_u32_e32 v1, 0x7f, v1
	v_cndmask_b32_e32 v88, v90, v89, vcc
	v_not_b32_e32 v89, v2
	v_or_b32_e32 v90, 0x80000000, v2
	v_cmp_gt_i32_e32 vcc, 0, v2
	v_and_b32_e32 v88, 0xffffff80, v88
	v_sub_u32_e32 v88, v88, v26
	v_cndmask_b32_e32 v2, v90, v89, vcc
	v_cvt_f32_f16_sdwa v89, v3 dst_sel:DWORD dst_unused:UNUSED_PAD src0_sel:WORD_1
	v_cvt_f32_f16_e32 v3, v3
	v_and_b32_e32 v2, 0xffffff80, v2
	v_sub_u32_e32 v2, v2, v26
	v_not_b32_e32 v90, v89
	v_or_b32_e32 v91, 0x80000000, v89
	v_cmp_gt_i32_e32 vcc, 0, v89
	v_add_u32_e32 v88, 0x7e, v88
	v_add_u32_e32 v2, 0x7f, v2
	v_cndmask_b32_e32 v89, v91, v90, vcc
	v_not_b32_e32 v90, v3
	v_or_b32_e32 v91, 0x80000000, v3
	v_cmp_gt_i32_e32 vcc, 0, v3
	v_and_b32_e32 v89, 0xffffff80, v89
	v_sub_u32_e32 v89, v89, v28
	v_cndmask_b32_e32 v3, v91, v90, vcc
	v_and_b32_e32 v3, 0xffffff80, v3
	v_sub_u32_e32 v3, v3, v28
	v_add_u32_e32 v89, 0x7e, v89
	v_add_u32_e32 v3, 0x7f, v3
	v_max_u32_e32 v90, v66, v74
	v_min_u32_e32 v66, v66, v74
	v_max_u32_e32 v74, v75, v67
	v_min_u32_e32 v67, v75, v67
	v_max_u32_e32 v75, v68, v76
	v_min_u32_e32 v68, v68, v76
	v_max_u32_e32 v76, v77, v69
	v_min_u32_e32 v69, v77, v69
	v_max_u32_e32 v77, v62, v78
	v_min_u32_e32 v62, v62, v78
	v_max_u32_e32 v78, v79, v63
	v_min_u32_e32 v63, v79, v63
	v_max_u32_e32 v79, v64, v80
	v_min_u32_e32 v64, v64, v80
	v_max_u32_e32 v80, v81, v65
	v_min_u32_e32 v65, v81, v65
	v_max_u32_e32 v98, v70, v82
	v_min_u32_e32 v70, v70, v82
	v_max_u32_e32 v82, v83, v71
	v_min_u32_e32 v71, v83, v71
	v_max_u32_e32 v83, v72, v84
	v_min_u32_e32 v72, v72, v84
	v_max_u32_e32 v84, v85, v73
	v_min_u32_e32 v73, v85, v73
	v_max_u32_e32 v85, v0, v86
	v_min_u32_e32 v0, v0, v86
	v_max_u32_e32 v86, v87, v1
	v_min_u32_e32 v1, v87, v1
	v_max_u32_e32 v87, v2, v88
	v_min_u32_e32 v2, v2, v88
	v_max_u32_e32 v88, v89, v3
	v_min_u32_e32 v3, v89, v3
	v_max_u32_e32 v81, v90, v67
	v_min_u32_e32 v67, v90, v67
	v_max_u32_e32 v90, v66, v74
	v_min_u32_e32 v66, v66, v74
	v_max_u32_e32 v74, v69, v75
	v_min_u32_e32 v69, v69, v75
	v_max_u32_e32 v75, v76, v68
	v_min_u32_e32 v68, v76, v68
; #define CE_DESC(a, b) do { const unsigned _mx = (a) > (b) ? (a) : (b), _mn = (a) > (b) ? (b) : (a); (a) = _mx; (b) = _mn; } while (0)
; __device__ __forceinline__ void sort16_desc(unsigned (&k)[16]) {
; #pragma unroll
;     for (int size = 2; size <= 16; size <<= 1)
; #pragma unroll
;         for (int stride = size >> 1; stride > 0; stride >>= 1)
; #pragma unroll
;             for (int i = 0; i < 16; ++i) { const int j = i ^ stride;
;                 if (j > i) { if ((i & size) == 0) CE_DESC(k[i], k[j]); else CE_DESC(k[j], k[i]); } }
; }
	v_max_u32_e32 v76, v77, v63
	v_min_u32_e32 v63, v77, v63
	v_max_u32_e32 v77, v62, v78
	v_min_u32_e32 v62, v62, v78
	v_max_u32_e32 v78, v65, v79
	v_min_u32_e32 v65, v65, v79
	v_max_u32_e32 v79, v80, v64
	v_min_u32_e32 v64, v80, v64
	v_max_u32_e32 v89, v98, v71
	v_min_u32_e32 v71, v98, v71
	v_max_u32_e32 v98, v70, v82
	v_min_u32_e32 v70, v70, v82
	v_max_u32_e32 v82, v73, v83
	v_min_u32_e32 v73, v73, v83
	v_max_u32_e32 v83, v84, v72
	v_min_u32_e32 v72, v84, v72
	v_max_u32_e32 v84, v85, v1
	v_min_u32_e32 v1, v85, v1
	v_max_u32_e32 v85, v0, v86
	v_min_u32_e32 v0, v0, v86
	v_max_u32_e32 v86, v3, v87
	v_min_u32_e32 v3, v3, v87
	v_max_u32_e32 v87, v88, v2
	v_min_u32_e32 v2, v88, v2
	v_max_u32_e32 v80, v81, v90
	v_min_u32_e32 v81, v81, v90
	v_max_u32_e32 v90, v67, v66
	v_min_u32_e32 v66, v67, v66
	v_max_u32_e32 v67, v68, v69
	v_min_u32_e32 v68, v68, v69
	v_max_u32_e32 v69, v75, v74
	v_min_u32_e32 v74, v75, v74
	v_max_u32_e32 v75, v76, v77
	v_min_u32_e32 v76, v76, v77
	v_max_u32_e32 v77, v63, v62
	v_min_u32_e32 v62, v63, v62
	v_max_u32_e32 v63, v64, v65
	v_min_u32_e32 v64, v64, v65
	v_max_u32_e32 v65, v79, v78
	v_min_u32_e32 v78, v79, v78
	v_max_u32_e32 v88, v89, v98
	v_min_u32_e32 v89, v89, v98
	v_max_u32_e32 v98, v71, v70
	v_min_u32_e32 v70, v71, v70
	v_max_u32_e32 v71, v72, v73
	v_min_u32_e32 v72, v72, v73
	v_max_u32_e32 v73, v83, v82
	v_min_u32_e32 v82, v83, v82
	v_max_u32_e32 v83, v84, v85
	v_min_u32_e32 v84, v84, v85
	v_max_u32_e32 v85, v1, v0
	v_min_u32_e32 v0, v1, v0
	v_max_u32_e32 v1, v2, v3
	v_min_u32_e32 v2, v2, v3
	v_max_u32_e32 v3, v87, v86
	v_min_u32_e32 v86, v87, v86
	v_max_u32_e32 v79, v80, v68
	v_min_u32_e32 v68, v80, v68
	v_max_u32_e32 v80, v81, v67
	v_min_u32_e32 v67, v81, v67
	v_max_u32_e32 v81, v90, v74
	v_min_u32_e32 v74, v90, v74
	v_max_u32_e32 v90, v66, v69
	v_min_u32_e32 v66, v66, v69
	v_max_u32_e32 v69, v64, v75
	v_min_u32_e32 v64, v64, v75
	v_max_u32_e32 v75, v63, v76
	v_min_u32_e32 v63, v63, v76
	v_max_u32_e32 v76, v78, v77
	v_min_u32_e32 v77, v78, v77
	v_max_u32_e32 v78, v65, v62
	v_min_u32_e32 v62, v65, v62
	v_max_u32_e32 v87, v88, v72
	v_min_u32_e32 v72, v88, v72
	v_max_u32_e32 v88, v89, v71
	v_min_u32_e32 v71, v89, v71
	v_max_u32_e32 v89, v98, v82
	v_min_u32_e32 v82, v98, v82
	v_max_u32_e32 v98, v70, v73
	v_min_u32_e32 v70, v70, v73
	v_max_u32_e32 v73, v2, v83
	v_min_u32_e32 v2, v2, v83
	v_max_u32_e32 v83, v1, v84
	v_min_u32_e32 v1, v1, v84
	v_max_u32_e32 v84, v86, v85
	v_min_u32_e32 v85, v86, v85
	v_max_u32_e32 v86, v3, v0
	v_min_u32_e32 v0, v3, v0
	v_max_u32_e32 v65, v79, v81
	v_min_u32_e32 v79, v79, v81
	v_max_u32_e32 v81, v80, v90
	v_min_u32_e32 v80, v80, v90
	v_max_u32_e32 v90, v68, v74
	v_min_u32_e32 v68, v68, v74
	v_max_u32_e32 v74, v67, v66
	v_min_u32_e32 v66, v67, v66
	v_max_u32_e32 v67, v77, v64
	v_min_u32_e32 v64, v77, v64
	v_max_u32_e32 v77, v62, v63
	v_min_u32_e32 v62, v62, v63
	v_max_u32_e32 v63, v76, v69
	v_min_u32_e32 v69, v76, v69
	v_max_u32_e32 v76, v78, v75
	v_min_u32_e32 v75, v78, v75
	v_max_u32_e32 v3, v87, v89
	v_min_u32_e32 v87, v87, v89
	v_max_u32_e32 v89, v88, v98
	v_min_u32_e32 v88, v88, v98
	v_max_u32_e32 v98, v72, v82
	v_min_u32_e32 v72, v72, v82
	v_max_u32_e32 v82, v71, v70
	v_min_u32_e32 v70, v71, v70
	v_max_u32_e32 v71, v85, v2
	v_min_u32_e32 v2, v85, v2
	v_max_u32_e32 v85, v0, v1
	v_min_u32_e32 v0, v0, v1
	v_max_u32_e32 v1, v84, v73
	v_min_u32_e32 v73, v84, v73
	v_max_u32_e32 v84, v86, v83
	v_min_u32_e32 v83, v86, v83
	v_max_u32_e32 v78, v65, v81
	v_min_u32_e32 v65, v65, v81
	v_max_u32_e32 v81, v79, v80
	v_min_u32_e32 v79, v79, v80
	v_max_u32_e32 v80, v90, v74
	v_min_u32_e32 v74, v90, v74
	v_max_u32_e32 v90, v68, v66
	v_min_u32_e32 v66, v68, v66
	v_max_u32_e32 v68, v62, v64
	v_min_u32_e32 v62, v62, v64
	v_max_u32_e32 v64, v77, v67
	v_min_u32_e32 v67, v77, v67
	v_max_u32_e32 v77, v75, v69
	v_min_u32_e32 v69, v75, v69
	v_max_u32_e32 v75, v76, v63
	v_min_u32_e32 v63, v76, v63
	v_max_u32_e32 v86, v3, v89
	v_min_u32_e32 v3, v3, v89
	v_max_u32_e32 v89, v87, v88
	v_min_u32_e32 v87, v87, v88
	v_max_u32_e32 v88, v98, v82
	v_min_u32_e32 v82, v98, v82
	v_max_u32_e32 v98, v72, v70
	v_min_u32_e32 v70, v72, v70
	v_max_u32_e32 v72, v0, v2
	v_min_u32_e32 v0, v0, v2
	v_max_u32_e32 v2, v85, v71
	v_min_u32_e32 v71, v85, v71
	v_max_u32_e32 v85, v83, v73
	v_min_u32_e32 v73, v83, v73
	v_max_u32_e32 v83, v84, v1
	v_min_u32_e32 v1, v84, v1
	v_max_u32_e32 v76, v78, v62
	v_min_u32_e32 v62, v78, v62
	v_max_u32_e32 v78, v65, v68
	v_min_u32_e32 v65, v65, v68
	v_max_u32_e32 v68, v81, v67
	v_min_u32_e32 v67, v81, v67
	v_max_u32_e32 v81, v79, v64
	v_min_u32_e32 v64, v79, v64
	v_max_u32_e32 v79, v80, v69
	v_min_u32_e32 v69, v80, v69
	v_max_u32_e32 v80, v74, v77
	v_min_u32_e32 v74, v74, v77
	v_max_u32_e32 v77, v90, v63
	v_min_u32_e32 v63, v90, v63
	v_max_u32_e32 v90, v66, v75
	v_min_u32_e32 v66, v66, v75
	v_max_u32_e32 v84, v86, v0
	v_min_u32_e32 v0, v86, v0
	v_max_u32_e32 v86, v3, v72
	v_min_u32_e32 v3, v3, v72
	v_max_u32_e32 v72, v89, v71
	v_min_u32_e32 v71, v89, v71
	v_max_u32_e32 v89, v87, v2
	v_min_u32_e32 v2, v87, v2
	v_max_u32_e32 v87, v88, v73
	v_min_u32_e32 v73, v88, v73
	v_max_u32_e32 v88, v82, v85
	v_min_u32_e32 v82, v82, v85
	v_max_u32_e32 v85, v98, v1
	v_min_u32_e32 v1, v98, v1
	v_max_u32_e32 v98, v70, v83
	v_min_u32_e32 v70, v70, v83
	v_max_u32_e32 v75, v76, v79
	v_min_u32_e32 v76, v76, v79
	v_max_u32_e32 v79, v78, v80
	v_min_u32_e32 v78, v78, v80
	v_max_u32_e32 v80, v68, v77
	v_min_u32_e32 v68, v68, v77
	v_max_u32_e32 v77, v81, v90
	v_min_u32_e32 v81, v81, v90
	v_max_u32_e32 v90, v62, v69
	v_min_u32_e32 v62, v62, v69
	v_max_u32_e32 v69, v65, v74
	v_min_u32_e32 v65, v65, v74
	v_max_u32_e32 v74, v67, v63
; #define CE_DESC(a, b) do { const unsigned _mx = (a) > (b) ? (a) : (b), _mn = (a) > (b) ? (b) : (a); (a) = _mx; (b) = _mn; } while (0)
; __device__ __forceinline__ void merge16(unsigned (&a)[16], const unsigned (&b)[16]) {
; #pragma unroll
;     for (int i = 0; i < 16; ++i) a[i] = a[i] > b[15 - i] ? a[i] : b[15 - i];
; #pragma unroll
;     for (int stride = 8; stride > 0; stride >>= 1)
; #pragma unroll
;         for (int i = 0; i < 16; ++i) { const int j = i ^ stride; if (j > i) CE_DESC(a[i], a[j]); }
; }
; __device__ __forceinline__ void peer_tile(const Args& A, LAS unsigned char* lds, int tile) {
;     ...
;                 for (int msk = 16; msk <= 32; msk <<= 1) {
; #pragma unroll
;                     for (int i = 0; i < 16; ++i) k1[i] = (unsigned)__shfl_xor((int)k0[i], msk);
;                     merge16(k0, k1); }
	v_min_u32_e32 v63, v67, v63
	v_max_u32_e32 v67, v64, v66
	v_min_u32_e32 v64, v64, v66
	v_max_u32_e32 v83, v84, v87
	v_min_u32_e32 v84, v84, v87
	v_max_u32_e32 v87, v86, v88
	v_min_u32_e32 v86, v86, v88
	v_max_u32_e32 v88, v72, v85
	v_min_u32_e32 v72, v72, v85
	v_max_u32_e32 v85, v89, v98
	v_min_u32_e32 v89, v89, v98
	v_max_u32_e32 v98, v0, v73
	v_min_u32_e32 v0, v0, v73
	v_max_u32_e32 v73, v3, v82
	v_min_u32_e32 v3, v3, v82
	v_max_u32_e32 v82, v71, v1
	v_min_u32_e32 v1, v71, v1
	v_max_u32_e32 v71, v2, v70
	v_min_u32_e32 v2, v2, v70
	v_max_u32_e32 v66, v75, v80
	v_min_u32_e32 v75, v75, v80
	v_max_u32_e32 v80, v79, v77
	v_min_u32_e32 v77, v79, v77
	v_max_u32_e32 v79, v76, v68
	v_min_u32_e32 v68, v76, v68
	v_max_u32_e32 v76, v78, v81
	v_min_u32_e32 v78, v78, v81
	v_max_u32_e32 v81, v90, v74
	v_min_u32_e32 v74, v90, v74
	v_max_u32_e32 v90, v69, v67
	v_min_u32_e32 v67, v69, v67
	v_max_u32_e32 v69, v62, v63
	v_min_u32_e32 v62, v62, v63
	v_max_u32_e32 v63, v65, v64
	v_min_u32_e32 v64, v65, v64
	v_max_u32_e32 v70, v83, v88
	v_min_u32_e32 v83, v83, v88
	v_max_u32_e32 v88, v87, v85
	v_min_u32_e32 v85, v87, v85
	v_max_u32_e32 v87, v84, v72
	v_min_u32_e32 v72, v84, v72
	v_max_u32_e32 v84, v86, v89
	v_min_u32_e32 v86, v86, v89
	v_max_u32_e32 v89, v98, v82
	v_min_u32_e32 v82, v98, v82
	v_max_u32_e32 v98, v73, v71
	v_min_u32_e32 v71, v73, v71
	v_max_u32_e32 v73, v0, v1
	v_min_u32_e32 v0, v0, v1
	v_max_u32_e32 v1, v3, v2
	v_min_u32_e32 v2, v3, v2
	v_min_u32_e32 v65, v66, v80
	v_min_u32_e32 v91, v75, v77
	v_min_u32_e32 v92, v79, v76
	v_min_u32_e32 v93, v68, v78
	v_min_u32_e32 v94, v81, v90
	v_min_u32_e32 v95, v74, v67
	v_min_u32_e32 v96, v69, v63
	v_min_u32_e32 v97, v62, v64
	v_min_u32_e32 v3, v70, v88
	v_min_u32_e32 v99, v83, v85
	v_min_u32_e32 v100, v87, v84
	v_min_u32_e32 v101, v72, v86
	v_min_u32_e32 v102, v89, v98
	v_min_u32_e32 v103, v82, v71
	v_min_u32_e32 v104, v73, v1
	v_min_u32_e32 v105, v0, v2
	v_max3_u32 v66, v66, v80, v105
	v_max3_u32 v0, v65, v0, v2
	v_max3_u32 v2, v75, v77, v104
	v_max3_u32 v1, v91, v73, v1
	v_max3_u32 v65, v79, v76, v103
	v_max3_u32 v71, v92, v82, v71
	v_max3_u32 v68, v68, v78, v102
	v_max3_u32 v73, v93, v89, v98
	v_max3_u32 v75, v81, v90, v101
	v_max3_u32 v72, v94, v72, v86
	v_max3_u32 v67, v74, v67, v100
	v_max3_u32 v74, v95, v87, v84
	v_max3_u32 v63, v69, v63, v99
	v_max3_u32 v69, v96, v83, v85
	v_max3_u32 v3, v62, v64, v3
	v_max3_u32 v62, v97, v70, v88
	v_max_u32_e32 v64, v66, v75
	v_min_u32_e32 v66, v66, v75
	v_max_u32_e32 v70, v0, v72
	v_min_u32_e32 v0, v0, v72
	v_max_u32_e32 v72, v2, v67
	v_min_u32_e32 v2, v2, v67
	v_max_u32_e32 v67, v1, v74
	v_min_u32_e32 v1, v1, v74
	v_max_u32_e32 v74, v65, v63
	v_min_u32_e32 v63, v65, v63
	v_max_u32_e32 v65, v71, v69
	v_min_u32_e32 v69, v71, v69
	v_max_u32_e32 v71, v68, v3
	v_min_u32_e32 v3, v68, v3
	v_max_u32_e32 v68, v73, v62
	v_min_u32_e32 v62, v73, v62
	v_max_u32_e32 v73, v64, v74
	v_min_u32_e32 v64, v64, v74
	v_max_u32_e32 v74, v70, v65
	v_min_u32_e32 v65, v70, v65
	v_max_u32_e32 v70, v72, v71
	v_min_u32_e32 v71, v72, v71
	v_max_u32_e32 v72, v67, v68
	v_min_u32_e32 v67, v67, v68
	v_max_u32_e32 v68, v66, v63
	v_min_u32_e32 v63, v66, v63
	v_max_u32_e32 v66, v0, v69
	v_min_u32_e32 v0, v0, v69
	v_max_u32_e32 v69, v2, v3
	v_min_u32_e32 v2, v2, v3
	v_max_u32_e32 v3, v1, v62
	v_min_u32_e32 v1, v1, v62
	v_max_u32_e32 v62, v73, v70
	v_min_u32_e32 v70, v73, v70
	v_max_u32_e32 v73, v74, v72
	v_min_u32_e32 v72, v74, v72
	v_max_u32_e32 v74, v64, v71
	v_min_u32_e32 v64, v64, v71
	v_max_u32_e32 v71, v65, v67
	v_min_u32_e32 v65, v65, v67
	v_max_u32_e32 v67, v68, v69
	v_min_u32_e32 v68, v68, v69
	v_max_u32_e32 v69, v66, v3
	v_min_u32_e32 v3, v66, v3
	v_max_u32_e32 v66, v63, v2
	v_min_u32_e32 v2, v63, v2
	v_max_u32_e32 v63, v0, v1
	v_min_u32_e32 v0, v0, v1
	v_max_u32_e32 v1, v62, v73
	v_min_u32_e32 v62, v62, v73
	v_max_u32_e32 v73, v70, v72
	v_min_u32_e32 v70, v70, v72
	v_max_u32_e32 v72, v74, v71
	v_min_u32_e32 v71, v74, v71
	v_max_u32_e32 v74, v64, v65
	v_min_u32_e32 v64, v64, v65
	v_max_u32_e32 v65, v67, v69
	v_min_u32_e32 v67, v67, v69
	v_max_u32_e32 v69, v68, v3
	v_min_u32_e32 v3, v68, v3
	v_max_u32_e32 v68, v66, v63
	v_min_u32_e32 v63, v66, v63
	v_max_u32_e32 v66, v2, v0
	v_min_u32_e32 v0, v2, v0
	ds_bpermute_b32 v2, v27, v1
	ds_bpermute_b32 v75, v27, v62
	ds_bpermute_b32 v76, v27, v73
	ds_bpermute_b32 v77, v27, v70
	ds_bpermute_b32 v78, v27, v72
	ds_bpermute_b32 v79, v27, v71
	ds_bpermute_b32 v80, v27, v74
	ds_bpermute_b32 v81, v27, v64
	ds_bpermute_b32 v82, v27, v65
	ds_bpermute_b32 v83, v27, v67
	ds_bpermute_b32 v84, v27, v69
	ds_bpermute_b32 v85, v27, v0
	ds_bpermute_b32 v86, v27, v66
	ds_bpermute_b32 v87, v27, v63
	ds_bpermute_b32 v88, v27, v68
	ds_bpermute_b32 v89, v27, v3
	s_waitcnt lgkmcnt(4)
	v_max_u32_e32 v1, v1, v85
	s_waitcnt lgkmcnt(3)
	v_max_u32_e32 v62, v62, v86
	s_waitcnt lgkmcnt(2)
	v_max_u32_e32 v73, v73, v87
	s_waitcnt lgkmcnt(1)
	v_max_u32_e32 v70, v70, v88
	s_waitcnt lgkmcnt(0)
; #define CE_DESC(a, b) do { const unsigned _mx = (a) > (b) ? (a) : (b), _mn = (a) > (b) ? (b) : (a); (a) = _mx; (b) = _mn; } while (0)
; __device__ __forceinline__ void merge16(unsigned (&a)[16], const unsigned (&b)[16]) {
; #pragma unroll
;     for (int i = 0; i < 16; ++i) a[i] = a[i] > b[15 - i] ? a[i] : b[15 - i];
; #pragma unroll
;     for (int stride = 8; stride > 0; stride >>= 1)
; #pragma unroll
;         for (int i = 0; i < 16; ++i) { const int j = i ^ stride; if (j > i) CE_DESC(a[i], a[j]); }
; }
; __device__ __forceinline__ void peer_tile(const Args& A, LAS unsigned char* lds, int tile) {
;     ...
;                 for (int msk = 16; msk <= 32; msk <<= 1) {
; #pragma unroll
;                     for (int i = 0; i < 16; ++i) k1[i] = (unsigned)__shfl_xor((int)k0[i], msk);
;                     merge16(k0, k1); }
	v_max_u32_e32 v72, v72, v89
	v_max_u32_e32 v71, v71, v84
	v_max_u32_e32 v74, v74, v83
	v_max_u32_e32 v64, v64, v82
	v_max_u32_e32 v65, v65, v81
	v_max_u32_e32 v67, v67, v80
	v_max_u32_e32 v69, v69, v79
	v_max_u32_e32 v3, v3, v78
	v_max_u32_e32 v68, v68, v77
	v_max_u32_e32 v63, v63, v76
	v_max_u32_e32 v66, v66, v75
	v_max_u32_e32 v0, v0, v2
	v_max_u32_e32 v2, v1, v65
	v_min_u32_e32 v1, v1, v65
	v_max_u32_e32 v65, v62, v67
	v_min_u32_e32 v62, v62, v67
	v_max_u32_e32 v67, v73, v69
	v_min_u32_e32 v69, v73, v69
	v_max_u32_e32 v73, v70, v3
	v_min_u32_e32 v3, v70, v3
	v_max_u32_e32 v70, v72, v68
	v_min_u32_e32 v68, v72, v68
	v_max_u32_e32 v72, v71, v63
	v_min_u32_e32 v63, v71, v63
	v_max_u32_e32 v71, v74, v66
	v_min_u32_e32 v66, v74, v66
	v_max_u32_e32 v74, v64, v0
	v_min_u32_e32 v0, v64, v0
	v_max_u32_e32 v64, v2, v70
	v_min_u32_e32 v2, v2, v70
	v_max_u32_e32 v70, v65, v72
	v_min_u32_e32 v65, v65, v72
	v_max_u32_e32 v72, v67, v71
	v_min_u32_e32 v67, v67, v71
	v_max_u32_e32 v71, v73, v74
	v_min_u32_e32 v73, v73, v74
	v_max_u32_e32 v74, v1, v68
	v_min_u32_e32 v1, v1, v68
	v_max_u32_e32 v68, v62, v63
	v_min_u32_e32 v62, v62, v63
	v_max_u32_e32 v63, v69, v66
	v_min_u32_e32 v66, v69, v66
	v_max_u32_e32 v69, v3, v0
	v_min_u32_e32 v0, v3, v0
	v_max_u32_e32 v3, v64, v72
	v_min_u32_e32 v64, v64, v72
	v_max_u32_e32 v72, v70, v71
	v_min_u32_e32 v70, v70, v71
	v_max_u32_e32 v71, v2, v67
	v_min_u32_e32 v2, v2, v67
	v_max_u32_e32 v67, v65, v73
	v_min_u32_e32 v65, v65, v73
	v_max_u32_e32 v73, v74, v63
	v_min_u32_e32 v63, v74, v63
	v_max_u32_e32 v74, v68, v69
	v_min_u32_e32 v68, v68, v69
	v_max_u32_e32 v69, v1, v66
	v_min_u32_e32 v1, v1, v66
	v_max_u32_e32 v66, v62, v0
	v_min_u32_e32 v0, v62, v0
	v_max_u32_e32 v62, v3, v72
	v_min_u32_e32 v3, v3, v72
	v_max_u32_e32 v72, v64, v70
	v_min_u32_e32 v64, v64, v70
	v_max_u32_e32 v70, v71, v67
	v_min_u32_e32 v67, v71, v67
	v_max_u32_e32 v71, v2, v65
	v_min_u32_e32 v2, v2, v65
	v_max_u32_e32 v65, v73, v74
	v_min_u32_e32 v73, v73, v74
	v_max_u32_e32 v74, v63, v68
	v_min_u32_e32 v63, v63, v68
	v_max_u32_e32 v68, v69, v66
	v_min_u32_e32 v66, v69, v66
	v_max_u32_e32 v69, v1, v0
	v_min_u32_e32 v0, v1, v0
	ds_bpermute_b32 v78, v29, v0
	ds_bpermute_b32 v1, v29, v62
	ds_bpermute_b32 v75, v29, v3
	ds_bpermute_b32 v76, v29, v72
	ds_bpermute_b32 v77, v29, v64
	s_waitcnt lgkmcnt(4)
	v_max_u32_e32 v62, v62, v78
	global_load_dwordx4 v[78:81], v[4:5], off offset:784
	global_load_dwordx4 v[82:85], v[4:5], off offset:768
	ds_bpermute_b32 v86, v29, v70
	ds_bpermute_b32 v87, v29, v67
	ds_bpermute_b32 v88, v29, v71
	ds_bpermute_b32 v89, v29, v2
	ds_bpermute_b32 v90, v29, v65
	ds_bpermute_b32 v91, v29, v73
	ds_bpermute_b32 v92, v29, v74
	ds_bpermute_b32 v93, v29, v63
	ds_bpermute_b32 v94, v29, v68
	ds_bpermute_b32 v95, v29, v69
	ds_bpermute_b32 v96, v29, v66
	s_waitcnt lgkmcnt(4)
	v_max_u32_e32 v67, v67, v92
	s_waitcnt lgkmcnt(3)
	v_max_u32_e32 v70, v70, v93
	s_waitcnt lgkmcnt(2)
	v_max_u32_e32 v64, v64, v94
	s_waitcnt lgkmcnt(1)
	v_max_u32_e32 v3, v3, v95
	s_waitcnt lgkmcnt(0)
	v_max_u32_e32 v72, v72, v96
	v_max_u32_e32 v71, v71, v91
	v_max_u32_e32 v2, v2, v90
	v_max_u32_e32 v65, v65, v89
	v_max_u32_e32 v73, v73, v88
	v_max_u32_e32 v74, v74, v87
	v_max_u32_e32 v63, v63, v86
	v_max_u32_e32 v68, v68, v77
	v_max_u32_e32 v66, v66, v76
	v_max_u32_e32 v69, v69, v75
	v_max_u32_e32 v0, v0, v1
	v_max_u32_e32 v1, v62, v65
	v_min_u32_e32 v62, v62, v65
	v_max_u32_e32 v65, v3, v73
	v_min_u32_e32 v3, v3, v73
	v_max_u32_e32 v73, v72, v74
	v_min_u32_e32 v72, v72, v74
	v_max_u32_e32 v74, v64, v63
	v_min_u32_e32 v63, v64, v63
	v_max_u32_e32 v64, v70, v68
	v_min_u32_e32 v68, v70, v68
	v_max_u32_e32 v70, v67, v66
	v_min_u32_e32 v66, v67, v66
	v_max_u32_e32 v67, v71, v69
	v_min_u32_e32 v69, v71, v69
	v_max_u32_e32 v71, v2, v0
	v_min_u32_e32 v0, v2, v0
	v_max_u32_e32 v2, v1, v64
	v_min_u32_e32 v1, v1, v64
	v_max_u32_e32 v64, v65, v70
	v_min_u32_e32 v65, v65, v70
	v_max_u32_e32 v70, v73, v67
	v_min_u32_e32 v67, v73, v67
	v_max_u32_e32 v73, v74, v71
	v_min_u32_e32 v71, v74, v71
	v_max_u32_e32 v74, v62, v68
	v_min_u32_e32 v62, v62, v68
	v_max_u32_e32 v68, v3, v66
	v_min_u32_e32 v3, v3, v66
	v_max_u32_e32 v66, v72, v69
	v_min_u32_e32 v69, v72, v69
	v_max_u32_e32 v72, v63, v0
	v_min_u32_e32 v0, v63, v0
	v_max_u32_e32 v63, v2, v70
	v_min_u32_e32 v2, v2, v70
	v_max_u32_e32 v70, v64, v73
	v_min_u32_e32 v64, v64, v73
	v_max_u32_e32 v86, v1, v67
	v_min_u32_e32 v1, v1, v67
	v_max_u32_e32 v67, v65, v71
	v_min_u32_e32 v65, v65, v71
	v_max_u32_e32 v87, v74, v66
	v_min_u32_e32 v66, v74, v66
	v_max_u32_e32 v88, v68, v72
	v_min_u32_e32 v89, v68, v72
	v_max_u32_e32 v90, v62, v69
	v_min_u32_e32 v62, v62, v69
	v_max_u32_e32 v91, v3, v0
	v_min_u32_e32 v0, v3, v0
	v_max_u32_e32 v77, v63, v70
	v_min_u32_e32 v76, v63, v70
	v_max_u32_e32 v75, v2, v64
	v_min_u32_e32 v74, v2, v64
	v_max_u32_e32 v73, v86, v67
	v_min_u32_e32 v72, v86, v67
	v_max_u32_e32 v71, v1, v65
	v_min_u32_e32 v70, v1, v65
	v_max_u32_e32 v69, v87, v88
	v_min_u32_e32 v68, v87, v88
	v_max_u32_e32 v67, v66, v89
	v_min_u32_e32 v66, v66, v89
	v_max_u32_e32 v63, v62, v0
	v_min_u32_e32 v62, v62, v0
	global_load_dwordx4 v[0:3], v[4:5], off offset:816
	global_load_dwordx4 v[86:89], v[4:5], off offset:800
	v_max_u32_e32 v65, v90, v91
	v_min_u32_e32 v64, v90, v91
	s_waitcnt vmcnt(2)
; __device__ __forceinline__ unsigned f2key(float f) { const unsigned u = __float_as_uint(f); return (u & 0x80000000u) ? ~u : (u | 0x80000000u); }
; __device__ __forceinline__ void peer_tile(const Args& A, LAS unsigned char* lds, int tile) {
;     ...
;                 { const bf16_t* sp = QRY + m * 2048 + hp * 128 + 32 * g;
;                   const u32x4 s0 = *(const u32x4*)sp, s1 = *(const u32x4*)(sp + 8), s2 = *(const u32x4*)(sp + 16), s3 = *(const u32x4*)(sp + 24);
;                   const unsigned sw[16] = {s0.x, s0.y, s0.z, s0.w, s1.x, s1.y, s1.z, s1.w, s2.x, s2.y, s2.z, s2.w, s3.x, s3.y, s3.z, s3.w};
; #pragma unroll
;                   for (int i = 0; i < 16; ++i) {
;                       const float lo = (float)__builtin_bit_cast(_Float16, (unsigned short)(sw[i] & 0xffffu)), hi = (float)__builtin_bit_cast(_Float16, (unsigned short)(sw[i] >> 16));
;                       const unsigned klo = (f2key(lo) & ~127u) | (unsigned)(127 - (32 * g + 2 * i)), khi = (f2key(hi) & ~127u) | (unsigned)(127 - (32 * g + 2 * i + 1));
;                       if (i < 8) { k0[2 * i] = klo; k0[2 * i + 1] = khi; } else { k1[2 * (i - 8)] = klo; k1[2 * (i - 8) + 1] = khi; } } }
;     ...
;                 for (int i = 0; i < 16; ++i) L2[p][i] = (g & 2) ? ((g & 1) ? LA[3][p][i] : LA[2][p][i]) : ((g & 1) ? LA[1][p][i] : LA[0][p][i]);
	v_cvt_f32_f16_sdwa v90, v82 dst_sel:DWORD dst_unused:UNUSED_PAD src0_sel:WORD_1
	v_cvt_f32_f16_e32 v82, v82
	v_cndmask_b32_e64 v38, v70, v38, s[0:1]
	v_cndmask_b32_e64 v37, v69, v37, s[0:1]
	v_not_b32_e32 v91, v90
	v_or_b32_e32 v92, 0x80000000, v90
	v_cmp_gt_i32_e32 vcc, 0, v90
	v_cndmask_b32_e64 v36, v68, v36, s[0:1]
	v_cndmask_b32_e64 v35, v67, v35, s[0:1]
	v_cndmask_b32_e32 v90, v92, v91, vcc
	v_not_b32_e32 v91, v82
	v_or_b32_e32 v92, 0x80000000, v82
	v_cmp_gt_i32_e32 vcc, 0, v82
	v_and_b32_e32 v90, 0xffffff80, v90
	v_sub_u32_e32 v90, v90, v15
	v_cndmask_b32_e32 v82, v92, v91, vcc
	v_cvt_f32_f16_sdwa v91, v83 dst_sel:DWORD dst_unused:UNUSED_PAD src0_sel:WORD_1
	v_cvt_f32_f16_e32 v83, v83
	v_and_b32_e32 v82, 0xffffff80, v82
	v_sub_u32_e32 v82, v82, v15
	v_not_b32_e32 v92, v91
	v_or_b32_e32 v93, 0x80000000, v91
	v_cmp_gt_i32_e32 vcc, 0, v91
	v_add_u32_e32 v90, 0x7e, v90
	v_add_u32_e32 v82, 0x7f, v82
	v_cndmask_b32_e32 v91, v93, v92, vcc
	v_not_b32_e32 v92, v83
	v_or_b32_e32 v93, 0x80000000, v83
	v_cmp_gt_i32_e32 vcc, 0, v83
	v_and_b32_e32 v91, 0xffffff80, v91
	v_sub_u32_e32 v91, v91, v14
	v_cndmask_b32_e32 v83, v93, v92, vcc
	v_cvt_f32_f16_sdwa v92, v84 dst_sel:DWORD dst_unused:UNUSED_PAD src0_sel:WORD_1
	v_cvt_f32_f16_e32 v84, v84
	v_and_b32_e32 v83, 0xffffff80, v83
	v_sub_u32_e32 v83, v83, v14
	v_not_b32_e32 v93, v92
	v_or_b32_e32 v94, 0x80000000, v92
	v_cmp_gt_i32_e32 vcc, 0, v92
	v_add_u32_e32 v91, 0x7e, v91
	v_add_u32_e32 v83, 0x7f, v83
	v_cndmask_b32_e32 v92, v94, v93, vcc
	v_not_b32_e32 v93, v84
	v_or_b32_e32 v94, 0x80000000, v84
	v_cmp_gt_i32_e32 vcc, 0, v84
	v_and_b32_e32 v92, 0xffffff80, v92
	v_sub_u32_e32 v92, v92, v12
	v_cndmask_b32_e32 v84, v94, v93, vcc
	v_cvt_f32_f16_sdwa v93, v85 dst_sel:DWORD dst_unused:UNUSED_PAD src0_sel:WORD_1
	v_cvt_f32_f16_e32 v85, v85
	v_and_b32_e32 v84, 0xffffff80, v84
	v_sub_u32_e32 v84, v84, v12
	v_not_b32_e32 v94, v93
	v_or_b32_e32 v95, 0x80000000, v93
	v_cmp_gt_i32_e32 vcc, 0, v93
	v_add_u32_e32 v92, 0x7e, v92
	v_add_u32_e32 v84, 0x7f, v84
	v_cndmask_b32_e32 v93, v95, v94, vcc
	v_not_b32_e32 v94, v85
	v_or_b32_e32 v95, 0x80000000, v85
	v_cmp_gt_i32_e32 vcc, 0, v85
	v_and_b32_e32 v93, 0xffffff80, v93
	v_sub_u32_e32 v93, v93, v10
	v_cndmask_b32_e32 v85, v95, v94, vcc
	v_cvt_f32_f16_sdwa v94, v78 dst_sel:DWORD dst_unused:UNUSED_PAD src0_sel:WORD_1
	v_cvt_f32_f16_e32 v78, v78
	v_and_b32_e32 v85, 0xffffff80, v85
	v_sub_u32_e32 v85, v85, v10
	v_not_b32_e32 v95, v94
	v_or_b32_e32 v96, 0x80000000, v94
	v_cmp_gt_i32_e32 vcc, 0, v94
	v_add_u32_e32 v93, 0x7e, v93
	v_add_u32_e32 v85, 0x7f, v85
	v_cndmask_b32_e32 v94, v96, v95, vcc
	v_not_b32_e32 v95, v78
	v_or_b32_e32 v96, 0x80000000, v78
	v_cmp_gt_i32_e32 vcc, 0, v78
	v_and_b32_e32 v94, 0xffffff80, v94
	v_sub_u32_e32 v94, v94, v8
	v_cndmask_b32_e32 v78, v96, v95, vcc
	v_cvt_f32_f16_sdwa v95, v79 dst_sel:DWORD dst_unused:UNUSED_PAD src0_sel:WORD_1
	v_cvt_f32_f16_e32 v79, v79
	v_and_b32_e32 v78, 0xffffff80, v78
	v_sub_u32_e32 v78, v78, v8
	v_not_b32_e32 v96, v95
	v_or_b32_e32 v97, 0x80000000, v95
	v_cmp_gt_i32_e32 vcc, 0, v95
	v_add_u32_e32 v94, 0x7e, v94
	v_add_u32_e32 v78, 0x7f, v78
	v_cndmask_b32_e32 v95, v97, v96, vcc
	v_not_b32_e32 v96, v79
	v_or_b32_e32 v97, 0x80000000, v79
	v_cmp_gt_i32_e32 vcc, 0, v79
	v_and_b32_e32 v95, 0xffffff80, v95
	v_sub_u32_e32 v95, v95, v16
	v_cndmask_b32_e32 v79, v97, v96, vcc
	v_cvt_f32_f16_sdwa v96, v80 dst_sel:DWORD dst_unused:UNUSED_PAD src0_sel:WORD_1
	v_cvt_f32_f16_e32 v80, v80
	v_and_b32_e32 v79, 0xffffff80, v79
	v_sub_u32_e32 v79, v79, v16
	v_not_b32_e32 v97, v96
	v_or_b32_e32 v98, 0x80000000, v96
	v_cmp_gt_i32_e32 vcc, 0, v96
	v_add_u32_e32 v95, 0x7e, v95
	v_add_u32_e32 v79, 0x7f, v79
	v_cndmask_b32_e32 v96, v98, v97, vcc
	v_not_b32_e32 v97, v80
	v_or_b32_e32 v98, 0x80000000, v80
	v_cmp_gt_i32_e32 vcc, 0, v80
	v_and_b32_e32 v96, 0xffffff80, v96
	v_sub_u32_e32 v96, v96, v17
	v_cndmask_b32_e32 v80, v98, v97, vcc
	v_cvt_f32_f16_sdwa v97, v81 dst_sel:DWORD dst_unused:UNUSED_PAD src0_sel:WORD_1
	v_cvt_f32_f16_e32 v81, v81
	v_and_b32_e32 v80, 0xffffff80, v80
	v_sub_u32_e32 v80, v80, v17
	v_not_b32_e32 v98, v97
	v_or_b32_e32 v99, 0x80000000, v97
	v_cmp_gt_i32_e32 vcc, 0, v97
	v_add_u32_e32 v96, 0x7e, v96
	v_add_u32_e32 v80, 0x7f, v80
	v_cndmask_b32_e32 v97, v99, v98, vcc
	v_not_b32_e32 v98, v81
	v_or_b32_e32 v99, 0x80000000, v81
	v_cmp_gt_i32_e32 vcc, 0, v81
	v_and_b32_e32 v97, 0xffffff80, v97
	v_sub_u32_e32 v97, v97, v18
	v_cndmask_b32_e32 v81, v99, v98, vcc
	s_waitcnt vmcnt(0)
; __device__ __forceinline__ unsigned f2key(float f) { const unsigned u = __float_as_uint(f); return (u & 0x80000000u) ? ~u : (u | 0x80000000u); }
; #define CE_DESC(a, b) do { const unsigned _mx = (a) > (b) ? (a) : (b), _mn = (a) > (b) ? (b) : (a); (a) = _mx; (b) = _mn; } while (0)
; __device__ __forceinline__ void sort16_desc(unsigned (&k)[16]) {
; #pragma unroll
;     for (int size = 2; size <= 16; size <<= 1)
; #pragma unroll
;         for (int stride = size >> 1; stride > 0; stride >>= 1)
; #pragma unroll
;             for (int i = 0; i < 16; ++i) { const int j = i ^ stride;
;                 if (j > i) { if ((i & size) == 0) CE_DESC(k[i], k[j]); else CE_DESC(k[j], k[i]); } }
; }
; __device__ __forceinline__ void peer_tile(const Args& A, LAS unsigned char* lds, int tile) {
;     ...
;                   for (int i = 0; i < 16; ++i) {
;                       const float lo = (float)__builtin_bit_cast(_Float16, (unsigned short)(sw[i] & 0xffffu)), hi = (float)__builtin_bit_cast(_Float16, (unsigned short)(sw[i] >> 16));
;                       const unsigned klo = (f2key(lo) & ~127u) | (unsigned)(127 - (32 * g + 2 * i)), khi = (f2key(hi) & ~127u) | (unsigned)(127 - (32 * g + 2 * i + 1));
;                       if (i < 8) { k0[2 * i] = klo; k0[2 * i + 1] = khi; } else { k1[2 * (i - 8)] = klo; k1[2 * (i - 8) + 1] = khi; } } }
;                 sort16_desc(k0); sort16_desc(k1); merge16(k0, k1);
	v_cvt_f32_f16_sdwa v98, v86 dst_sel:DWORD dst_unused:UNUSED_PAD src0_sel:WORD_1
	v_cvt_f32_f16_e32 v86, v86
	v_and_b32_e32 v81, 0xffffff80, v81
	v_sub_u32_e32 v81, v81, v18
	v_not_b32_e32 v99, v98
	v_or_b32_e32 v100, 0x80000000, v98
	v_cmp_gt_i32_e32 vcc, 0, v98
	v_add_u32_e32 v97, 0x7e, v97
	v_add_u32_e32 v81, 0x7f, v81
	v_cndmask_b32_e32 v98, v100, v99, vcc
	v_not_b32_e32 v99, v86
	v_or_b32_e32 v100, 0x80000000, v86
	v_cmp_gt_i32_e32 vcc, 0, v86
	v_and_b32_e32 v98, 0xffffff80, v98
	v_sub_u32_e32 v98, v98, v20
	v_cndmask_b32_e32 v86, v100, v99, vcc
	v_cvt_f32_f16_sdwa v99, v87 dst_sel:DWORD dst_unused:UNUSED_PAD src0_sel:WORD_1
	v_cvt_f32_f16_e32 v87, v87
	v_and_b32_e32 v86, 0xffffff80, v86
	v_sub_u32_e32 v86, v86, v20
	v_not_b32_e32 v100, v99
	v_or_b32_e32 v101, 0x80000000, v99
	v_cmp_gt_i32_e32 vcc, 0, v99
	v_add_u32_e32 v98, 0x7e, v98
	v_add_u32_e32 v86, 0x7f, v86
	v_cndmask_b32_e32 v99, v101, v100, vcc
	v_not_b32_e32 v100, v87
	v_or_b32_e32 v101, 0x80000000, v87
	v_cmp_gt_i32_e32 vcc, 0, v87
	v_and_b32_e32 v99, 0xffffff80, v99
	v_sub_u32_e32 v99, v99, v21
	v_cndmask_b32_e32 v87, v101, v100, vcc
	v_cvt_f32_f16_sdwa v100, v88 dst_sel:DWORD dst_unused:UNUSED_PAD src0_sel:WORD_1
	v_cvt_f32_f16_e32 v88, v88
	v_and_b32_e32 v87, 0xffffff80, v87
	v_sub_u32_e32 v87, v87, v21
	v_not_b32_e32 v101, v100
	v_or_b32_e32 v102, 0x80000000, v100
	v_cmp_gt_i32_e32 vcc, 0, v100
	v_add_u32_e32 v99, 0x7e, v99
	v_add_u32_e32 v87, 0x7f, v87
	v_cndmask_b32_e32 v100, v102, v101, vcc
	v_not_b32_e32 v101, v88
	v_or_b32_e32 v102, 0x80000000, v88
	v_cmp_gt_i32_e32 vcc, 0, v88
	v_and_b32_e32 v100, 0xffffff80, v100
	v_sub_u32_e32 v100, v100, v22
	v_cndmask_b32_e32 v88, v102, v101, vcc
	v_cvt_f32_f16_sdwa v101, v89 dst_sel:DWORD dst_unused:UNUSED_PAD src0_sel:WORD_1
	v_cvt_f32_f16_e32 v89, v89
	v_and_b32_e32 v88, 0xffffff80, v88
	v_sub_u32_e32 v88, v88, v22
	v_not_b32_e32 v102, v101
	v_or_b32_e32 v103, 0x80000000, v101
	v_cmp_gt_i32_e32 vcc, 0, v101
	v_add_u32_e32 v100, 0x7e, v100
	v_add_u32_e32 v88, 0x7f, v88
	v_cndmask_b32_e32 v101, v103, v102, vcc
	v_not_b32_e32 v102, v89
	v_or_b32_e32 v103, 0x80000000, v89
	v_cmp_gt_i32_e32 vcc, 0, v89
	v_and_b32_e32 v101, 0xffffff80, v101
	v_sub_u32_e32 v101, v101, v23
	v_cndmask_b32_e32 v89, v103, v102, vcc
	v_cvt_f32_f16_sdwa v102, v0 dst_sel:DWORD dst_unused:UNUSED_PAD src0_sel:WORD_1
	v_cvt_f32_f16_e32 v0, v0
	v_and_b32_e32 v89, 0xffffff80, v89
	v_sub_u32_e32 v89, v89, v23
	v_not_b32_e32 v103, v102
	v_or_b32_e32 v104, 0x80000000, v102
	v_cmp_gt_i32_e32 vcc, 0, v102
	v_add_u32_e32 v101, 0x7e, v101
	v_add_u32_e32 v89, 0x7f, v89
	v_cndmask_b32_e32 v102, v104, v103, vcc
	v_not_b32_e32 v103, v0
	v_or_b32_e32 v104, 0x80000000, v0
	v_cmp_gt_i32_e32 vcc, 0, v0
	v_and_b32_e32 v102, 0xffffff80, v102
	v_sub_u32_e32 v102, v102, v24
	v_cndmask_b32_e32 v0, v104, v103, vcc
	v_cvt_f32_f16_sdwa v103, v1 dst_sel:DWORD dst_unused:UNUSED_PAD src0_sel:WORD_1
	v_cvt_f32_f16_e32 v1, v1
	v_and_b32_e32 v0, 0xffffff80, v0
	v_sub_u32_e32 v0, v0, v24
	v_not_b32_e32 v104, v103
	v_or_b32_e32 v105, 0x80000000, v103
	v_cmp_gt_i32_e32 vcc, 0, v103
	v_add_u32_e32 v102, 0x7e, v102
	v_add_u32_e32 v0, 0x7f, v0
	v_cndmask_b32_e32 v103, v105, v104, vcc
	v_not_b32_e32 v104, v1
	v_or_b32_e32 v105, 0x80000000, v1
	v_cmp_gt_i32_e32 vcc, 0, v1
	v_and_b32_e32 v103, 0xffffff80, v103
	v_sub_u32_e32 v103, v103, v25
	v_cndmask_b32_e32 v1, v105, v104, vcc
	v_cvt_f32_f16_sdwa v104, v2 dst_sel:DWORD dst_unused:UNUSED_PAD src0_sel:WORD_1
	v_cvt_f32_f16_e32 v2, v2
	v_and_b32_e32 v1, 0xffffff80, v1
	v_sub_u32_e32 v1, v1, v25
	v_not_b32_e32 v105, v104
	v_or_b32_e32 v106, 0x80000000, v104
	v_cmp_gt_i32_e32 vcc, 0, v104
	v_add_u32_e32 v103, 0x7e, v103
	v_add_u32_e32 v1, 0x7f, v1
	v_cndmask_b32_e32 v104, v106, v105, vcc
	v_not_b32_e32 v105, v2
	v_or_b32_e32 v106, 0x80000000, v2
	v_cmp_gt_i32_e32 vcc, 0, v2
	v_and_b32_e32 v104, 0xffffff80, v104
	v_sub_u32_e32 v104, v104, v26
	v_cndmask_b32_e32 v2, v106, v105, vcc
	v_cvt_f32_f16_sdwa v105, v3 dst_sel:DWORD dst_unused:UNUSED_PAD src0_sel:WORD_1
	v_cvt_f32_f16_e32 v3, v3
	v_and_b32_e32 v2, 0xffffff80, v2
	v_sub_u32_e32 v2, v2, v26
	v_not_b32_e32 v106, v105
	v_or_b32_e32 v107, 0x80000000, v105
	v_cmp_gt_i32_e32 vcc, 0, v105
	v_add_u32_e32 v104, 0x7e, v104
	v_add_u32_e32 v2, 0x7f, v2
	v_cndmask_b32_e32 v105, v107, v106, vcc
	v_not_b32_e32 v106, v3
	v_or_b32_e32 v107, 0x80000000, v3
	v_cmp_gt_i32_e32 vcc, 0, v3
	v_and_b32_e32 v105, 0xffffff80, v105
	v_sub_u32_e32 v105, v105, v28
	v_cndmask_b32_e32 v3, v107, v106, vcc
	v_and_b32_e32 v3, 0xffffff80, v3
	v_sub_u32_e32 v3, v3, v28
	v_add_u32_e32 v105, 0x7e, v105
	v_add_u32_e32 v3, 0x7f, v3
	v_max_u32_e32 v106, v82, v90
	v_min_u32_e32 v82, v82, v90
	v_max_u32_e32 v90, v91, v83
	v_min_u32_e32 v83, v91, v83
	v_max_u32_e32 v91, v84, v92
	v_min_u32_e32 v84, v84, v92
	v_max_u32_e32 v92, v93, v85
	v_min_u32_e32 v85, v93, v85
	v_max_u32_e32 v93, v78, v94
	v_min_u32_e32 v78, v78, v94
	v_max_u32_e32 v94, v95, v79
	v_min_u32_e32 v79, v95, v79
	v_max_u32_e32 v95, v80, v96
	v_min_u32_e32 v80, v80, v96
	v_max_u32_e32 v96, v97, v81
	v_min_u32_e32 v81, v97, v81
	v_max_u32_e32 v115, v86, v98
	v_min_u32_e32 v86, v86, v98
	v_max_u32_e32 v98, v99, v87
	v_min_u32_e32 v87, v99, v87
	v_max_u32_e32 v99, v88, v100
	v_min_u32_e32 v88, v88, v100
	v_max_u32_e32 v100, v101, v89
	v_min_u32_e32 v89, v101, v89
	v_max_u32_e32 v101, v0, v102
	v_min_u32_e32 v0, v0, v102
	v_max_u32_e32 v102, v103, v1
	v_min_u32_e32 v1, v103, v1
	v_max_u32_e32 v103, v2, v104
	v_min_u32_e32 v2, v2, v104
	v_max_u32_e32 v104, v105, v3
	v_min_u32_e32 v3, v105, v3
	v_max_u32_e32 v97, v106, v83
	v_min_u32_e32 v83, v106, v83
	v_max_u32_e32 v106, v82, v90
; #define CE_DESC(a, b) do { const unsigned _mx = (a) > (b) ? (a) : (b), _mn = (a) > (b) ? (b) : (a); (a) = _mx; (b) = _mn; } while (0)
; __device__ __forceinline__ void sort16_desc(unsigned (&k)[16]) {
; #pragma unroll
;     for (int size = 2; size <= 16; size <<= 1)
; #pragma unroll
;         for (int stride = size >> 1; stride > 0; stride >>= 1)
; #pragma unroll
;             for (int i = 0; i < 16; ++i) { const int j = i ^ stride;
;                 if (j > i) { if ((i & size) == 0) CE_DESC(k[i], k[j]); else CE_DESC(k[j], k[i]); } }
; }
	v_min_u32_e32 v82, v82, v90
	v_max_u32_e32 v90, v85, v91
	v_min_u32_e32 v85, v85, v91
	v_max_u32_e32 v91, v92, v84
	v_min_u32_e32 v84, v92, v84
	v_max_u32_e32 v92, v93, v79
	v_min_u32_e32 v79, v93, v79
	v_max_u32_e32 v93, v78, v94
	v_min_u32_e32 v78, v78, v94
	v_max_u32_e32 v94, v81, v95
	v_min_u32_e32 v81, v81, v95
	v_max_u32_e32 v95, v96, v80
	v_min_u32_e32 v80, v96, v80
	v_max_u32_e32 v105, v115, v87
	v_min_u32_e32 v87, v115, v87
	v_max_u32_e32 v115, v86, v98
	v_min_u32_e32 v86, v86, v98
	v_max_u32_e32 v98, v89, v99
	v_min_u32_e32 v89, v89, v99
	v_max_u32_e32 v99, v100, v88
	v_min_u32_e32 v88, v100, v88
	v_max_u32_e32 v100, v101, v1
	v_min_u32_e32 v1, v101, v1
	v_max_u32_e32 v101, v0, v102
	v_min_u32_e32 v0, v0, v102
	v_max_u32_e32 v102, v3, v103
	v_min_u32_e32 v3, v3, v103
	v_max_u32_e32 v103, v104, v2
	v_min_u32_e32 v2, v104, v2
	v_max_u32_e32 v96, v97, v106
	v_min_u32_e32 v97, v97, v106
	v_max_u32_e32 v106, v83, v82
	v_min_u32_e32 v82, v83, v82
	v_max_u32_e32 v83, v84, v85
	v_min_u32_e32 v84, v84, v85
	v_max_u32_e32 v85, v91, v90
	v_min_u32_e32 v90, v91, v90
	v_max_u32_e32 v91, v92, v93
	v_min_u32_e32 v92, v92, v93
	v_max_u32_e32 v93, v79, v78
	v_min_u32_e32 v78, v79, v78
	v_max_u32_e32 v79, v80, v81
	v_min_u32_e32 v80, v80, v81
	v_max_u32_e32 v81, v95, v94
	v_min_u32_e32 v94, v95, v94
	v_max_u32_e32 v104, v105, v115
	v_min_u32_e32 v105, v105, v115
	v_max_u32_e32 v115, v87, v86
	v_min_u32_e32 v86, v87, v86
	v_max_u32_e32 v87, v88, v89
	v_min_u32_e32 v88, v88, v89
	v_max_u32_e32 v89, v99, v98
	v_min_u32_e32 v98, v99, v98
	v_max_u32_e32 v99, v100, v101
	v_min_u32_e32 v100, v100, v101
	v_max_u32_e32 v101, v1, v0
	v_min_u32_e32 v0, v1, v0
	v_max_u32_e32 v1, v2, v3
	v_min_u32_e32 v2, v2, v3
	v_max_u32_e32 v3, v103, v102
	v_min_u32_e32 v102, v103, v102
	v_max_u32_e32 v95, v96, v84
	v_min_u32_e32 v84, v96, v84
	v_max_u32_e32 v96, v97, v83
	v_min_u32_e32 v83, v97, v83
	v_max_u32_e32 v97, v106, v90
	v_min_u32_e32 v90, v106, v90
	v_max_u32_e32 v106, v82, v85
	v_min_u32_e32 v82, v82, v85
	v_max_u32_e32 v85, v80, v91
	v_min_u32_e32 v80, v80, v91
	v_max_u32_e32 v91, v79, v92
	v_min_u32_e32 v79, v79, v92
	v_max_u32_e32 v92, v94, v93
	v_min_u32_e32 v93, v94, v93
	v_max_u32_e32 v94, v81, v78
	v_min_u32_e32 v78, v81, v78
	v_max_u32_e32 v103, v104, v88
	v_min_u32_e32 v88, v104, v88
	v_max_u32_e32 v104, v105, v87
	v_min_u32_e32 v87, v105, v87
	v_max_u32_e32 v105, v115, v98
	v_min_u32_e32 v98, v115, v98
	v_max_u32_e32 v115, v86, v89
	v_min_u32_e32 v86, v86, v89
	v_max_u32_e32 v89, v2, v99
	v_min_u32_e32 v2, v2, v99
	v_max_u32_e32 v99, v1, v100
	v_min_u32_e32 v1, v1, v100
	v_max_u32_e32 v100, v102, v101
	v_min_u32_e32 v101, v102, v101
	v_max_u32_e32 v102, v3, v0
	v_min_u32_e32 v0, v3, v0
	v_max_u32_e32 v81, v95, v97
	v_min_u32_e32 v95, v95, v97
	v_max_u32_e32 v97, v96, v106
	v_min_u32_e32 v96, v96, v106
	v_max_u32_e32 v106, v84, v90
	v_min_u32_e32 v84, v84, v90
	v_max_u32_e32 v90, v83, v82
	v_min_u32_e32 v82, v83, v82
	v_max_u32_e32 v83, v93, v80
	v_min_u32_e32 v80, v93, v80
	v_max_u32_e32 v93, v78, v79
	v_min_u32_e32 v78, v78, v79
	v_max_u32_e32 v79, v92, v85
	v_min_u32_e32 v85, v92, v85
	v_max_u32_e32 v92, v94, v91
	v_min_u32_e32 v91, v94, v91
	v_max_u32_e32 v3, v103, v105
	v_min_u32_e32 v103, v103, v105
	v_max_u32_e32 v105, v104, v115
	v_min_u32_e32 v104, v104, v115
	v_max_u32_e32 v115, v88, v98
	v_min_u32_e32 v88, v88, v98
	v_max_u32_e32 v98, v87, v86
	v_min_u32_e32 v86, v87, v86
	v_max_u32_e32 v87, v101, v2
	v_min_u32_e32 v2, v101, v2
	v_max_u32_e32 v101, v0, v1
	v_min_u32_e32 v0, v0, v1
	v_max_u32_e32 v1, v100, v89
	v_min_u32_e32 v89, v100, v89
	v_max_u32_e32 v100, v102, v99
	v_min_u32_e32 v99, v102, v99
	v_max_u32_e32 v94, v81, v97
	v_min_u32_e32 v81, v81, v97
	v_max_u32_e32 v97, v95, v96
	v_min_u32_e32 v95, v95, v96
	v_max_u32_e32 v96, v106, v90
	v_min_u32_e32 v90, v106, v90
	v_max_u32_e32 v106, v84, v82
	v_min_u32_e32 v82, v84, v82
	v_max_u32_e32 v84, v78, v80
	v_min_u32_e32 v78, v78, v80
	v_max_u32_e32 v80, v93, v83
	v_min_u32_e32 v83, v93, v83
	v_max_u32_e32 v93, v91, v85
	v_min_u32_e32 v85, v91, v85
	v_max_u32_e32 v91, v92, v79
	v_min_u32_e32 v79, v92, v79
	v_max_u32_e32 v102, v3, v105
	v_min_u32_e32 v3, v3, v105
	v_max_u32_e32 v105, v103, v104
	v_min_u32_e32 v103, v103, v104
	v_max_u32_e32 v104, v115, v98
	v_min_u32_e32 v98, v115, v98
	v_max_u32_e32 v115, v88, v86
	v_min_u32_e32 v86, v88, v86
	v_max_u32_e32 v88, v0, v2
	v_min_u32_e32 v0, v0, v2
	v_max_u32_e32 v2, v101, v87
	v_min_u32_e32 v87, v101, v87
	v_max_u32_e32 v101, v99, v89
	v_min_u32_e32 v89, v99, v89
	v_max_u32_e32 v99, v100, v1
	v_min_u32_e32 v1, v100, v1
	v_max_u32_e32 v92, v94, v78
	v_min_u32_e32 v78, v94, v78
	v_max_u32_e32 v94, v81, v84
	v_min_u32_e32 v81, v81, v84
	v_max_u32_e32 v84, v97, v83
	v_min_u32_e32 v83, v97, v83
	v_max_u32_e32 v97, v95, v80
	v_min_u32_e32 v80, v95, v80
	v_max_u32_e32 v95, v96, v85
	v_min_u32_e32 v85, v96, v85
	v_max_u32_e32 v96, v90, v93
	v_min_u32_e32 v90, v90, v93
	v_max_u32_e32 v93, v106, v79
	v_min_u32_e32 v79, v106, v79
	v_max_u32_e32 v106, v82, v91
	v_min_u32_e32 v82, v82, v91
	v_max_u32_e32 v100, v102, v0
	v_min_u32_e32 v0, v102, v0
	v_max_u32_e32 v102, v3, v88
	v_min_u32_e32 v3, v3, v88
	v_max_u32_e32 v88, v105, v87
	v_min_u32_e32 v87, v105, v87
	v_max_u32_e32 v105, v103, v2
	v_min_u32_e32 v2, v103, v2
	v_max_u32_e32 v103, v104, v89
	v_min_u32_e32 v89, v104, v89
	v_max_u32_e32 v104, v98, v101
	v_min_u32_e32 v98, v98, v101
	v_max_u32_e32 v101, v115, v1
	v_min_u32_e32 v1, v115, v1
	v_max_u32_e32 v115, v86, v99
	v_min_u32_e32 v86, v86, v99
	v_max_u32_e32 v91, v92, v95
	v_min_u32_e32 v92, v92, v95
	v_max_u32_e32 v95, v94, v96
; #define CE_DESC(a, b) do { const unsigned _mx = (a) > (b) ? (a) : (b), _mn = (a) > (b) ? (b) : (a); (a) = _mx; (b) = _mn; } while (0)
; __device__ __forceinline__ void merge16(unsigned (&a)[16], const unsigned (&b)[16]) {
; #pragma unroll
;     for (int i = 0; i < 16; ++i) a[i] = a[i] > b[15 - i] ? a[i] : b[15 - i];
; #pragma unroll
;     for (int stride = 8; stride > 0; stride >>= 1)
; #pragma unroll
;         for (int i = 0; i < 16; ++i) { const int j = i ^ stride; if (j > i) CE_DESC(a[i], a[j]); }
; }
; __device__ __forceinline__ void peer_tile(const Args& A, LAS unsigned char* lds, int tile) {
;     ...
;                 for (int msk = 16; msk <= 32; msk <<= 1) {
; #pragma unroll
;                     for (int i = 0; i < 16; ++i) k1[i] = (unsigned)__shfl_xor((int)k0[i], msk);
;                     merge16(k0, k1); }
	v_min_u32_e32 v94, v94, v96
	v_max_u32_e32 v96, v84, v93
	v_min_u32_e32 v84, v84, v93
	v_max_u32_e32 v93, v97, v106
	v_min_u32_e32 v97, v97, v106
	v_max_u32_e32 v106, v78, v85
	v_min_u32_e32 v78, v78, v85
	v_max_u32_e32 v85, v81, v90
	v_min_u32_e32 v81, v81, v90
	v_max_u32_e32 v90, v83, v79
	v_min_u32_e32 v79, v83, v79
	v_max_u32_e32 v83, v80, v82
	v_min_u32_e32 v80, v80, v82
	v_max_u32_e32 v99, v100, v103
	v_min_u32_e32 v100, v100, v103
	v_max_u32_e32 v103, v102, v104
	v_min_u32_e32 v102, v102, v104
	v_max_u32_e32 v104, v88, v101
	v_min_u32_e32 v88, v88, v101
	v_max_u32_e32 v101, v105, v115
	v_min_u32_e32 v105, v105, v115
	v_max_u32_e32 v115, v0, v89
	v_min_u32_e32 v0, v0, v89
	v_max_u32_e32 v89, v3, v98
	v_min_u32_e32 v3, v3, v98
	v_max_u32_e32 v98, v87, v1
	v_min_u32_e32 v1, v87, v1
	v_max_u32_e32 v87, v2, v86
	v_min_u32_e32 v2, v2, v86
	v_max_u32_e32 v82, v91, v96
	v_min_u32_e32 v91, v91, v96
	v_max_u32_e32 v96, v95, v93
	v_min_u32_e32 v93, v95, v93
	v_max_u32_e32 v95, v92, v84
	v_min_u32_e32 v84, v92, v84
	v_max_u32_e32 v92, v94, v97
	v_min_u32_e32 v94, v94, v97
	v_max_u32_e32 v97, v106, v90
	v_min_u32_e32 v90, v106, v90
	v_max_u32_e32 v106, v85, v83
	v_min_u32_e32 v83, v85, v83
	v_max_u32_e32 v85, v78, v79
	v_min_u32_e32 v78, v78, v79
	v_max_u32_e32 v79, v81, v80
	v_min_u32_e32 v80, v81, v80
	v_max_u32_e32 v86, v99, v104
	v_min_u32_e32 v99, v99, v104
	v_max_u32_e32 v104, v103, v101
	v_min_u32_e32 v101, v103, v101
	v_max_u32_e32 v103, v100, v88
	v_min_u32_e32 v88, v100, v88
	v_max_u32_e32 v100, v102, v105
	v_min_u32_e32 v102, v102, v105
	v_max_u32_e32 v105, v115, v98
	v_min_u32_e32 v98, v115, v98
	v_max_u32_e32 v115, v89, v87
	v_min_u32_e32 v87, v89, v87
	v_max_u32_e32 v89, v0, v1
	v_min_u32_e32 v0, v0, v1
	v_max_u32_e32 v1, v3, v2
	v_min_u32_e32 v2, v3, v2
	v_min_u32_e32 v81, v82, v96
	v_min_u32_e32 v107, v91, v93
	v_min_u32_e32 v108, v95, v92
	v_min_u32_e32 v109, v84, v94
	v_min_u32_e32 v110, v97, v106
	v_min_u32_e32 v111, v90, v83
	v_min_u32_e32 v112, v85, v79
	v_min_u32_e32 v114, v78, v80
	v_min_u32_e32 v3, v86, v104
	v_min_u32_e32 v116, v99, v101
	v_min_u32_e32 v117, v103, v100
	v_min_u32_e32 v118, v88, v102
	v_min_u32_e32 v119, v105, v115
	v_min_u32_e32 v120, v98, v87
	v_min_u32_e32 v121, v89, v1
	v_min_u32_e32 v122, v0, v2
	v_max3_u32 v82, v82, v96, v122
	v_max3_u32 v0, v81, v0, v2
	v_max3_u32 v2, v91, v93, v121
	v_max3_u32 v1, v107, v89, v1
	v_max3_u32 v81, v95, v92, v120
	v_max3_u32 v87, v108, v98, v87
	v_max3_u32 v84, v84, v94, v119
	v_max3_u32 v89, v109, v105, v115
	v_max3_u32 v91, v97, v106, v118
	v_max3_u32 v88, v110, v88, v102
	v_max3_u32 v83, v90, v83, v117
	v_max3_u32 v90, v111, v103, v100
	v_max3_u32 v79, v85, v79, v116
	v_max3_u32 v85, v112, v99, v101
	v_max3_u32 v3, v78, v80, v3
	v_max3_u32 v78, v114, v86, v104
	v_max_u32_e32 v80, v82, v91
	v_min_u32_e32 v82, v82, v91
	v_max_u32_e32 v86, v0, v88
	v_min_u32_e32 v0, v0, v88
	v_max_u32_e32 v88, v2, v83
	v_min_u32_e32 v2, v2, v83
	v_max_u32_e32 v83, v1, v90
	v_min_u32_e32 v1, v1, v90
	v_max_u32_e32 v90, v81, v79
	v_min_u32_e32 v79, v81, v79
	v_max_u32_e32 v81, v87, v85
	v_min_u32_e32 v85, v87, v85
	v_max_u32_e32 v87, v84, v3
	v_min_u32_e32 v3, v84, v3
	v_max_u32_e32 v84, v89, v78
	v_min_u32_e32 v78, v89, v78
	v_max_u32_e32 v89, v80, v90
	v_min_u32_e32 v80, v80, v90
	v_max_u32_e32 v90, v86, v81
	v_min_u32_e32 v81, v86, v81
	v_max_u32_e32 v86, v88, v87
	v_min_u32_e32 v87, v88, v87
	v_max_u32_e32 v88, v83, v84
	v_min_u32_e32 v83, v83, v84
	v_max_u32_e32 v84, v82, v79
	v_min_u32_e32 v79, v82, v79
	v_max_u32_e32 v82, v0, v85
	v_min_u32_e32 v0, v0, v85
	v_max_u32_e32 v85, v2, v3
	v_min_u32_e32 v2, v2, v3
	v_max_u32_e32 v3, v1, v78
	v_min_u32_e32 v1, v1, v78
	v_max_u32_e32 v78, v89, v86
	v_min_u32_e32 v86, v89, v86
	v_max_u32_e32 v89, v90, v88
	v_min_u32_e32 v88, v90, v88
	v_max_u32_e32 v90, v80, v87
	v_min_u32_e32 v80, v80, v87
	v_max_u32_e32 v87, v81, v83
	v_min_u32_e32 v81, v81, v83
	v_max_u32_e32 v83, v84, v85
	v_min_u32_e32 v84, v84, v85
	v_max_u32_e32 v85, v82, v3
	v_min_u32_e32 v3, v82, v3
	v_max_u32_e32 v82, v79, v2
	v_min_u32_e32 v2, v79, v2
	v_max_u32_e32 v79, v0, v1
	v_min_u32_e32 v0, v0, v1
	v_max_u32_e32 v1, v78, v89
	v_min_u32_e32 v78, v78, v89
	v_max_u32_e32 v89, v86, v88
	v_min_u32_e32 v86, v86, v88
	v_max_u32_e32 v88, v90, v87
	v_min_u32_e32 v87, v90, v87
	v_max_u32_e32 v90, v80, v81
	v_min_u32_e32 v80, v80, v81
	v_max_u32_e32 v81, v83, v85
	v_min_u32_e32 v83, v83, v85
	v_max_u32_e32 v85, v84, v3
	v_min_u32_e32 v3, v84, v3
	v_max_u32_e32 v84, v82, v79
	v_min_u32_e32 v79, v82, v79
	v_max_u32_e32 v82, v2, v0
	v_min_u32_e32 v0, v2, v0
	ds_bpermute_b32 v2, v27, v1
	ds_bpermute_b32 v91, v27, v78
	ds_bpermute_b32 v92, v27, v89
	ds_bpermute_b32 v93, v27, v86
	ds_bpermute_b32 v94, v27, v88
	ds_bpermute_b32 v95, v27, v87
	ds_bpermute_b32 v96, v27, v90
	ds_bpermute_b32 v97, v27, v80
	ds_bpermute_b32 v98, v27, v81
	ds_bpermute_b32 v99, v27, v83
	ds_bpermute_b32 v100, v27, v85
	ds_bpermute_b32 v101, v27, v0
	ds_bpermute_b32 v102, v27, v82
	ds_bpermute_b32 v103, v27, v79
	ds_bpermute_b32 v104, v27, v84
	ds_bpermute_b32 v105, v27, v3
	s_waitcnt lgkmcnt(4)
	v_max_u32_e32 v1, v1, v101
	s_waitcnt lgkmcnt(3)
	v_max_u32_e32 v78, v78, v102
	s_waitcnt lgkmcnt(2)
	v_max_u32_e32 v89, v89, v103
	s_waitcnt lgkmcnt(1)
	v_max_u32_e32 v86, v86, v104
	s_waitcnt lgkmcnt(0)
; #define CE_DESC(a, b) do { const unsigned _mx = (a) > (b) ? (a) : (b), _mn = (a) > (b) ? (b) : (a); (a) = _mx; (b) = _mn; } while (0)
; __device__ __forceinline__ void merge16(unsigned (&a)[16], const unsigned (&b)[16]) {
; #pragma unroll
;     for (int i = 0; i < 16; ++i) a[i] = a[i] > b[15 - i] ? a[i] : b[15 - i];
; #pragma unroll
;     for (int stride = 8; stride > 0; stride >>= 1)
; #pragma unroll
;         for (int i = 0; i < 16; ++i) { const int j = i ^ stride; if (j > i) CE_DESC(a[i], a[j]); }
; }
; __device__ __forceinline__ void peer_tile(const Args& A, LAS unsigned char* lds, int tile) {
;     ...
;                 for (int msk = 16; msk <= 32; msk <<= 1) {
; #pragma unroll
;                     for (int i = 0; i < 16; ++i) k1[i] = (unsigned)__shfl_xor((int)k0[i], msk);
;                     merge16(k0, k1); }
	v_max_u32_e32 v88, v88, v105
	v_max_u32_e32 v87, v87, v100
	v_max_u32_e32 v90, v90, v99
	v_max_u32_e32 v80, v80, v98
	v_max_u32_e32 v81, v81, v97
	v_max_u32_e32 v83, v83, v96
	v_max_u32_e32 v85, v85, v95
	v_max_u32_e32 v3, v3, v94
	v_max_u32_e32 v84, v84, v93
	v_max_u32_e32 v79, v79, v92
	v_max_u32_e32 v82, v82, v91
	v_max_u32_e32 v0, v0, v2
	v_max_u32_e32 v2, v1, v81
	v_min_u32_e32 v1, v1, v81
	v_max_u32_e32 v81, v78, v83
	v_min_u32_e32 v78, v78, v83
	v_max_u32_e32 v83, v89, v85
	v_min_u32_e32 v85, v89, v85
	v_max_u32_e32 v89, v86, v3
	v_min_u32_e32 v3, v86, v3
	v_max_u32_e32 v86, v88, v84
	v_min_u32_e32 v84, v88, v84
	v_max_u32_e32 v88, v87, v79
	v_min_u32_e32 v79, v87, v79
	v_max_u32_e32 v87, v90, v82
	v_min_u32_e32 v82, v90, v82
	v_max_u32_e32 v90, v80, v0
	v_min_u32_e32 v0, v80, v0
	v_max_u32_e32 v80, v2, v86
	v_min_u32_e32 v2, v2, v86
	v_max_u32_e32 v86, v81, v88
	v_min_u32_e32 v81, v81, v88
	v_max_u32_e32 v88, v83, v87
	v_min_u32_e32 v83, v83, v87
	v_max_u32_e32 v87, v89, v90
	v_min_u32_e32 v89, v89, v90
	v_max_u32_e32 v90, v1, v84
	v_min_u32_e32 v1, v1, v84
	v_max_u32_e32 v84, v78, v79
	v_min_u32_e32 v78, v78, v79
	v_max_u32_e32 v79, v85, v82
	v_min_u32_e32 v82, v85, v82
	v_max_u32_e32 v85, v3, v0
	v_min_u32_e32 v0, v3, v0
	v_max_u32_e32 v3, v80, v88
	v_min_u32_e32 v80, v80, v88
	v_max_u32_e32 v88, v86, v87
	v_min_u32_e32 v86, v86, v87
	v_max_u32_e32 v87, v2, v83
	v_min_u32_e32 v2, v2, v83
	v_max_u32_e32 v83, v81, v89
	v_min_u32_e32 v81, v81, v89
	v_max_u32_e32 v89, v90, v79
	v_min_u32_e32 v79, v90, v79
	v_max_u32_e32 v90, v84, v85
	v_min_u32_e32 v84, v84, v85
	v_max_u32_e32 v85, v1, v82
	v_min_u32_e32 v1, v1, v82
	v_max_u32_e32 v82, v78, v0
	v_min_u32_e32 v0, v78, v0
	v_max_u32_e32 v78, v3, v88
	v_min_u32_e32 v3, v3, v88
	v_max_u32_e32 v88, v80, v86
	v_min_u32_e32 v80, v80, v86
	v_max_u32_e32 v86, v87, v83
	v_min_u32_e32 v83, v87, v83
	v_max_u32_e32 v87, v2, v81
	v_min_u32_e32 v2, v2, v81
	v_max_u32_e32 v81, v89, v90
	v_min_u32_e32 v89, v89, v90
	v_max_u32_e32 v90, v79, v84
	v_min_u32_e32 v79, v79, v84
	v_max_u32_e32 v84, v85, v82
	v_min_u32_e32 v82, v85, v82
	v_max_u32_e32 v85, v1, v0
	v_min_u32_e32 v0, v1, v0
	ds_bpermute_b32 v94, v29, v0
	ds_bpermute_b32 v1, v29, v78
	ds_bpermute_b32 v91, v29, v3
	ds_bpermute_b32 v92, v29, v88
	ds_bpermute_b32 v93, v29, v80
	s_waitcnt lgkmcnt(4)
	v_max_u32_e32 v78, v78, v94
	global_load_dwordx4 v[94:97], v[4:5], off offset:1040
	global_load_dwordx4 v[98:101], v[4:5], off offset:1024
	ds_bpermute_b32 v102, v29, v86
	ds_bpermute_b32 v103, v29, v83
	ds_bpermute_b32 v104, v29, v87
	ds_bpermute_b32 v105, v29, v2
	ds_bpermute_b32 v106, v29, v81
	ds_bpermute_b32 v107, v29, v89
	ds_bpermute_b32 v108, v29, v90
	ds_bpermute_b32 v109, v29, v79
	ds_bpermute_b32 v110, v29, v84
	ds_bpermute_b32 v111, v29, v85
	ds_bpermute_b32 v112, v29, v82
	s_waitcnt lgkmcnt(4)
	v_max_u32_e32 v83, v83, v108
	s_waitcnt lgkmcnt(3)
	v_max_u32_e32 v86, v86, v109
	s_waitcnt lgkmcnt(2)
	v_max_u32_e32 v80, v80, v110
	s_waitcnt lgkmcnt(1)
	v_max_u32_e32 v3, v3, v111
	s_waitcnt lgkmcnt(0)
	v_max_u32_e32 v88, v88, v112
	v_max_u32_e32 v87, v87, v107
	v_max_u32_e32 v2, v2, v106
	v_max_u32_e32 v81, v81, v105
	v_max_u32_e32 v89, v89, v104
	v_max_u32_e32 v90, v90, v103
	v_max_u32_e32 v79, v79, v102
	v_max_u32_e32 v84, v84, v93
	v_max_u32_e32 v82, v82, v92
	v_max_u32_e32 v85, v85, v91
	v_max_u32_e32 v0, v0, v1
	v_max_u32_e32 v1, v78, v81
	v_min_u32_e32 v78, v78, v81
	v_max_u32_e32 v81, v3, v89
	v_min_u32_e32 v3, v3, v89
	v_max_u32_e32 v89, v88, v90
	v_min_u32_e32 v88, v88, v90
	v_max_u32_e32 v90, v80, v79
	v_min_u32_e32 v79, v80, v79
	v_max_u32_e32 v80, v86, v84
	v_min_u32_e32 v84, v86, v84
	v_max_u32_e32 v86, v83, v82
	v_min_u32_e32 v82, v83, v82
	v_max_u32_e32 v83, v87, v85
	v_min_u32_e32 v85, v87, v85
	v_max_u32_e32 v87, v2, v0
	v_min_u32_e32 v0, v2, v0
	v_max_u32_e32 v2, v1, v80
	v_min_u32_e32 v1, v1, v80
	v_max_u32_e32 v80, v81, v86
	v_min_u32_e32 v81, v81, v86
	v_max_u32_e32 v86, v89, v83
	v_min_u32_e32 v83, v89, v83
	v_max_u32_e32 v89, v90, v87
	v_min_u32_e32 v87, v90, v87
	v_max_u32_e32 v90, v78, v84
	v_min_u32_e32 v78, v78, v84
	v_max_u32_e32 v84, v3, v82
	v_min_u32_e32 v3, v3, v82
	v_max_u32_e32 v82, v88, v85
	v_min_u32_e32 v85, v88, v85
	v_max_u32_e32 v88, v79, v0
	v_min_u32_e32 v0, v79, v0
	v_max_u32_e32 v79, v2, v86
	v_min_u32_e32 v2, v2, v86
	v_max_u32_e32 v86, v80, v89
	v_min_u32_e32 v80, v80, v89
	v_max_u32_e32 v102, v1, v83
	v_min_u32_e32 v1, v1, v83
	v_max_u32_e32 v83, v81, v87
	v_min_u32_e32 v81, v81, v87
	v_max_u32_e32 v103, v90, v82
	v_min_u32_e32 v82, v90, v82
	v_max_u32_e32 v104, v84, v88
	v_min_u32_e32 v105, v84, v88
	v_max_u32_e32 v106, v78, v85
	v_min_u32_e32 v78, v78, v85
	v_max_u32_e32 v107, v3, v0
	v_min_u32_e32 v0, v3, v0
	v_max_u32_e32 v93, v79, v86
	v_min_u32_e32 v92, v79, v86
	v_max_u32_e32 v91, v2, v80
	v_min_u32_e32 v90, v2, v80
	v_max_u32_e32 v89, v102, v83
	v_min_u32_e32 v88, v102, v83
	v_max_u32_e32 v87, v1, v81
	v_min_u32_e32 v86, v1, v81
	v_max_u32_e32 v85, v103, v104
	v_min_u32_e32 v84, v103, v104
	v_max_u32_e32 v83, v82, v105
	v_min_u32_e32 v82, v82, v105
	v_max_u32_e32 v79, v78, v0
	v_min_u32_e32 v78, v78, v0
	global_load_dwordx4 v[0:3], v[4:5], off offset:1072
	global_load_dwordx4 v[102:105], v[4:5], off offset:1056
	v_max_u32_e32 v81, v106, v107
	v_min_u32_e32 v80, v106, v107
	s_waitcnt vmcnt(2)
; __device__ __forceinline__ unsigned f2key(float f) { const unsigned u = __float_as_uint(f); return (u & 0x80000000u) ? ~u : (u | 0x80000000u); }
; __device__ __forceinline__ void peer_tile(const Args& A, LAS unsigned char* lds, int tile) {
;     ...
;                 { const bf16_t* sp = QRY + m * 2048 + hp * 128 + 32 * g;
;                   const u32x4 s0 = *(const u32x4*)sp, s1 = *(const u32x4*)(sp + 8), s2 = *(const u32x4*)(sp + 16), s3 = *(const u32x4*)(sp + 24);
;                   const unsigned sw[16] = {s0.x, s0.y, s0.z, s0.w, s1.x, s1.y, s1.z, s1.w, s2.x, s2.y, s2.z, s2.w, s3.x, s3.y, s3.z, s3.w};
; #pragma unroll
;                   for (int i = 0; i < 16; ++i) {
;                       const float lo = (float)__builtin_bit_cast(_Float16, (unsigned short)(sw[i] & 0xffffu)), hi = (float)__builtin_bit_cast(_Float16, (unsigned short)(sw[i] >> 16));
;                       const unsigned klo = (f2key(lo) & ~127u) | (unsigned)(127 - (32 * g + 2 * i)), khi = (f2key(hi) & ~127u) | (unsigned)(127 - (32 * g + 2 * i + 1));
;                       if (i < 8) { k0[2 * i] = klo; k0[2 * i + 1] = khi; } else { k1[2 * (i - 8)] = klo; k1[2 * (i - 8) + 1] = khi; } } }
;     ...
;                 for (int i = 0; i < 16; ++i) L2[p][i] = (g & 2) ? ((g & 1) ? LA[3][p][i] : LA[2][p][i]) : ((g & 1) ? LA[1][p][i] : LA[0][p][i]);
	v_cvt_f32_f16_sdwa v106, v98 dst_sel:DWORD dst_unused:UNUSED_PAD src0_sel:WORD_1
	v_cvt_f32_f16_e32 v98, v98
	v_cndmask_b32_e64 v34, v66, v34, s[0:1]
	v_cndmask_b32_e64 v33, v65, v33, s[0:1]
	v_not_b32_e32 v107, v106
	v_or_b32_e32 v108, 0x80000000, v106
	v_cmp_gt_i32_e32 vcc, 0, v106
	v_cndmask_b32_e64 v32, v64, v32, s[0:1]
	v_cndmask_b32_e64 v31, v63, v31, s[0:1]
	v_cndmask_b32_e32 v106, v108, v107, vcc
	v_not_b32_e32 v107, v98
	v_or_b32_e32 v108, 0x80000000, v98
	v_cmp_gt_i32_e32 vcc, 0, v98
	v_and_b32_e32 v106, 0xffffff80, v106
	v_sub_u32_e32 v106, v106, v15
	v_cndmask_b32_e32 v98, v108, v107, vcc
	v_cvt_f32_f16_sdwa v107, v99 dst_sel:DWORD dst_unused:UNUSED_PAD src0_sel:WORD_1
	v_cvt_f32_f16_e32 v99, v99
	v_and_b32_e32 v98, 0xffffff80, v98
	v_sub_u32_e32 v98, v98, v15
	v_not_b32_e32 v108, v107
	v_or_b32_e32 v109, 0x80000000, v107
	v_cmp_gt_i32_e32 vcc, 0, v107
	v_add_u32_e32 v106, 0x7e, v106
	v_add_u32_e32 v98, 0x7f, v98
	v_cndmask_b32_e32 v107, v109, v108, vcc
	v_not_b32_e32 v108, v99
	v_or_b32_e32 v109, 0x80000000, v99
	v_cmp_gt_i32_e32 vcc, 0, v99
	v_and_b32_e32 v107, 0xffffff80, v107
	v_sub_u32_e32 v107, v107, v14
	v_cndmask_b32_e32 v99, v109, v108, vcc
	v_cvt_f32_f16_sdwa v108, v100 dst_sel:DWORD dst_unused:UNUSED_PAD src0_sel:WORD_1
	v_cvt_f32_f16_e32 v100, v100
	v_and_b32_e32 v99, 0xffffff80, v99
	v_sub_u32_e32 v99, v99, v14
	v_not_b32_e32 v109, v108
	v_or_b32_e32 v110, 0x80000000, v108
	v_cmp_gt_i32_e32 vcc, 0, v108
	v_add_u32_e32 v107, 0x7e, v107
	v_add_u32_e32 v99, 0x7f, v99
	v_cndmask_b32_e32 v108, v110, v109, vcc
	v_not_b32_e32 v109, v100
	v_or_b32_e32 v110, 0x80000000, v100
	v_cmp_gt_i32_e32 vcc, 0, v100
	v_and_b32_e32 v108, 0xffffff80, v108
	v_sub_u32_e32 v108, v108, v12
	v_cndmask_b32_e32 v100, v110, v109, vcc
	v_cvt_f32_f16_sdwa v109, v101 dst_sel:DWORD dst_unused:UNUSED_PAD src0_sel:WORD_1
	v_cvt_f32_f16_e32 v101, v101
	v_and_b32_e32 v100, 0xffffff80, v100
	v_sub_u32_e32 v100, v100, v12
	v_not_b32_e32 v110, v109
	v_or_b32_e32 v111, 0x80000000, v109
	v_cmp_gt_i32_e32 vcc, 0, v109
	v_add_u32_e32 v108, 0x7e, v108
	v_add_u32_e32 v100, 0x7f, v100
	v_cndmask_b32_e32 v109, v111, v110, vcc
	v_not_b32_e32 v110, v101
	v_or_b32_e32 v111, 0x80000000, v101
	v_cmp_gt_i32_e32 vcc, 0, v101
	v_and_b32_e32 v109, 0xffffff80, v109
	v_sub_u32_e32 v109, v109, v10
	v_cndmask_b32_e32 v101, v111, v110, vcc
	v_cvt_f32_f16_sdwa v110, v94 dst_sel:DWORD dst_unused:UNUSED_PAD src0_sel:WORD_1
	v_cvt_f32_f16_e32 v94, v94
	v_and_b32_e32 v101, 0xffffff80, v101
	v_sub_u32_e32 v101, v101, v10
	v_not_b32_e32 v111, v110
	v_or_b32_e32 v112, 0x80000000, v110
	v_cmp_gt_i32_e32 vcc, 0, v110
	v_add_u32_e32 v109, 0x7e, v109
	v_add_u32_e32 v101, 0x7f, v101
	v_cndmask_b32_e32 v110, v112, v111, vcc
	v_not_b32_e32 v111, v94
	v_or_b32_e32 v112, 0x80000000, v94
	v_cmp_gt_i32_e32 vcc, 0, v94
	v_and_b32_e32 v110, 0xffffff80, v110
	v_sub_u32_e32 v110, v110, v8
	v_cndmask_b32_e32 v94, v112, v111, vcc
	v_cvt_f32_f16_sdwa v111, v95 dst_sel:DWORD dst_unused:UNUSED_PAD src0_sel:WORD_1
	v_cvt_f32_f16_e32 v95, v95
	v_and_b32_e32 v94, 0xffffff80, v94
	v_sub_u32_e32 v94, v94, v8
	v_not_b32_e32 v112, v111
	v_or_b32_e32 v114, 0x80000000, v111
	v_cmp_gt_i32_e32 vcc, 0, v111
	v_add_u32_e32 v110, 0x7e, v110
	v_add_u32_e32 v94, 0x7f, v94
	v_cndmask_b32_e32 v111, v114, v112, vcc
	v_not_b32_e32 v112, v95
	v_or_b32_e32 v114, 0x80000000, v95
	v_cmp_gt_i32_e32 vcc, 0, v95
	v_and_b32_e32 v111, 0xffffff80, v111
	v_sub_u32_e32 v111, v111, v16
	v_cndmask_b32_e32 v95, v114, v112, vcc
	v_cvt_f32_f16_sdwa v112, v96 dst_sel:DWORD dst_unused:UNUSED_PAD src0_sel:WORD_1
	v_cvt_f32_f16_e32 v96, v96
	v_and_b32_e32 v95, 0xffffff80, v95
	v_sub_u32_e32 v95, v95, v16
	v_not_b32_e32 v114, v112
	v_or_b32_e32 v115, 0x80000000, v112
	v_cmp_gt_i32_e32 vcc, 0, v112
	v_add_u32_e32 v111, 0x7e, v111
	v_add_u32_e32 v95, 0x7f, v95
	v_cndmask_b32_e32 v112, v115, v114, vcc
	v_not_b32_e32 v114, v96
	v_or_b32_e32 v115, 0x80000000, v96
	v_cmp_gt_i32_e32 vcc, 0, v96
	v_and_b32_e32 v112, 0xffffff80, v112
	v_sub_u32_e32 v112, v112, v17
	v_cndmask_b32_e32 v96, v115, v114, vcc
	v_cvt_f32_f16_sdwa v114, v97 dst_sel:DWORD dst_unused:UNUSED_PAD src0_sel:WORD_1
	v_cvt_f32_f16_e32 v97, v97
	v_and_b32_e32 v96, 0xffffff80, v96
	v_sub_u32_e32 v96, v96, v17
	v_not_b32_e32 v115, v114
	v_or_b32_e32 v116, 0x80000000, v114
	v_cmp_gt_i32_e32 vcc, 0, v114
	v_add_u32_e32 v112, 0x7e, v112
	v_add_u32_e32 v96, 0x7f, v96
	v_cndmask_b32_e32 v114, v116, v115, vcc
	v_not_b32_e32 v115, v97
	v_or_b32_e32 v116, 0x80000000, v97
	v_cmp_gt_i32_e32 vcc, 0, v97
	v_and_b32_e32 v114, 0xffffff80, v114
	v_sub_u32_e32 v114, v114, v18
	v_cndmask_b32_e32 v97, v116, v115, vcc
	s_waitcnt vmcnt(0)
; __device__ __forceinline__ unsigned f2key(float f) { const unsigned u = __float_as_uint(f); return (u & 0x80000000u) ? ~u : (u | 0x80000000u); }
; #define CE_DESC(a, b) do { const unsigned _mx = (a) > (b) ? (a) : (b), _mn = (a) > (b) ? (b) : (a); (a) = _mx; (b) = _mn; } while (0)
; __device__ __forceinline__ void sort16_desc(unsigned (&k)[16]) {
; #pragma unroll
;     for (int size = 2; size <= 16; size <<= 1)
; #pragma unroll
;         for (int stride = size >> 1; stride > 0; stride >>= 1)
; #pragma unroll
;             for (int i = 0; i < 16; ++i) { const int j = i ^ stride;
;                 if (j > i) { if ((i & size) == 0) CE_DESC(k[i], k[j]); else CE_DESC(k[j], k[i]); } }
; }
; __device__ __forceinline__ void peer_tile(const Args& A, LAS unsigned char* lds, int tile) {
;     ...
;                   for (int i = 0; i < 16; ++i) {
;                       const float lo = (float)__builtin_bit_cast(_Float16, (unsigned short)(sw[i] & 0xffffu)), hi = (float)__builtin_bit_cast(_Float16, (unsigned short)(sw[i] >> 16));
;                       const unsigned klo = (f2key(lo) & ~127u) | (unsigned)(127 - (32 * g + 2 * i)), khi = (f2key(hi) & ~127u) | (unsigned)(127 - (32 * g + 2 * i + 1));
;                       if (i < 8) { k0[2 * i] = klo; k0[2 * i + 1] = khi; } else { k1[2 * (i - 8)] = klo; k1[2 * (i - 8) + 1] = khi; } } }
;                 sort16_desc(k0); sort16_desc(k1); merge16(k0, k1);
	v_cvt_f32_f16_sdwa v115, v102 dst_sel:DWORD dst_unused:UNUSED_PAD src0_sel:WORD_1
	v_cvt_f32_f16_e32 v102, v102
	v_and_b32_e32 v97, 0xffffff80, v97
	v_sub_u32_e32 v97, v97, v18
	v_not_b32_e32 v116, v115
	v_or_b32_e32 v117, 0x80000000, v115
	v_cmp_gt_i32_e32 vcc, 0, v115
	v_add_u32_e32 v114, 0x7e, v114
	v_add_u32_e32 v97, 0x7f, v97
	v_cndmask_b32_e32 v115, v117, v116, vcc
	v_not_b32_e32 v116, v102
	v_or_b32_e32 v117, 0x80000000, v102
	v_cmp_gt_i32_e32 vcc, 0, v102
	v_and_b32_e32 v115, 0xffffff80, v115
	v_sub_u32_e32 v115, v115, v20
	v_cndmask_b32_e32 v102, v117, v116, vcc
	v_cvt_f32_f16_sdwa v116, v103 dst_sel:DWORD dst_unused:UNUSED_PAD src0_sel:WORD_1
	v_cvt_f32_f16_e32 v103, v103
	v_and_b32_e32 v102, 0xffffff80, v102
	v_sub_u32_e32 v102, v102, v20
	v_not_b32_e32 v117, v116
	v_or_b32_e32 v118, 0x80000000, v116
	v_cmp_gt_i32_e32 vcc, 0, v116
	v_add_u32_e32 v115, 0x7e, v115
	v_add_u32_e32 v102, 0x7f, v102
	v_cndmask_b32_e32 v116, v118, v117, vcc
	v_not_b32_e32 v117, v103
	v_or_b32_e32 v118, 0x80000000, v103
	v_cmp_gt_i32_e32 vcc, 0, v103
	v_and_b32_e32 v116, 0xffffff80, v116
	v_sub_u32_e32 v116, v116, v21
	v_cndmask_b32_e32 v103, v118, v117, vcc
	v_cvt_f32_f16_sdwa v117, v104 dst_sel:DWORD dst_unused:UNUSED_PAD src0_sel:WORD_1
	v_cvt_f32_f16_e32 v104, v104
	v_and_b32_e32 v103, 0xffffff80, v103
	v_sub_u32_e32 v103, v103, v21
	v_not_b32_e32 v118, v117
	v_or_b32_e32 v119, 0x80000000, v117
	v_cmp_gt_i32_e32 vcc, 0, v117
	v_add_u32_e32 v116, 0x7e, v116
	v_add_u32_e32 v103, 0x7f, v103
	v_cndmask_b32_e32 v117, v119, v118, vcc
	v_not_b32_e32 v118, v104
	v_or_b32_e32 v119, 0x80000000, v104
	v_cmp_gt_i32_e32 vcc, 0, v104
	v_and_b32_e32 v117, 0xffffff80, v117
	v_sub_u32_e32 v117, v117, v22
	v_cndmask_b32_e32 v104, v119, v118, vcc
	v_cvt_f32_f16_sdwa v118, v105 dst_sel:DWORD dst_unused:UNUSED_PAD src0_sel:WORD_1
	v_cvt_f32_f16_e32 v105, v105
	v_and_b32_e32 v104, 0xffffff80, v104
	v_sub_u32_e32 v104, v104, v22
	v_not_b32_e32 v119, v118
	v_or_b32_e32 v120, 0x80000000, v118
	v_cmp_gt_i32_e32 vcc, 0, v118
	v_add_u32_e32 v117, 0x7e, v117
	v_add_u32_e32 v104, 0x7f, v104
	v_cndmask_b32_e32 v118, v120, v119, vcc
	v_not_b32_e32 v119, v105
	v_or_b32_e32 v120, 0x80000000, v105
	v_cmp_gt_i32_e32 vcc, 0, v105
	v_and_b32_e32 v118, 0xffffff80, v118
	v_sub_u32_e32 v118, v118, v23
	v_cndmask_b32_e32 v105, v120, v119, vcc
	v_cvt_f32_f16_sdwa v119, v0 dst_sel:DWORD dst_unused:UNUSED_PAD src0_sel:WORD_1
	v_cvt_f32_f16_e32 v0, v0
	v_and_b32_e32 v105, 0xffffff80, v105
	v_sub_u32_e32 v105, v105, v23
	v_not_b32_e32 v120, v119
	v_or_b32_e32 v121, 0x80000000, v119
	v_cmp_gt_i32_e32 vcc, 0, v119
	v_add_u32_e32 v118, 0x7e, v118
	v_add_u32_e32 v105, 0x7f, v105
	v_cndmask_b32_e32 v119, v121, v120, vcc
	v_not_b32_e32 v120, v0
	v_or_b32_e32 v121, 0x80000000, v0
	v_cmp_gt_i32_e32 vcc, 0, v0
	v_and_b32_e32 v119, 0xffffff80, v119
	v_sub_u32_e32 v119, v119, v24
	v_cndmask_b32_e32 v0, v121, v120, vcc
	v_cvt_f32_f16_sdwa v120, v1 dst_sel:DWORD dst_unused:UNUSED_PAD src0_sel:WORD_1
	v_cvt_f32_f16_e32 v1, v1
	v_and_b32_e32 v0, 0xffffff80, v0
	v_sub_u32_e32 v0, v0, v24
	v_not_b32_e32 v121, v120
	v_or_b32_e32 v122, 0x80000000, v120
	v_cmp_gt_i32_e32 vcc, 0, v120
	v_add_u32_e32 v119, 0x7e, v119
	v_add_u32_e32 v0, 0x7f, v0
	v_cndmask_b32_e32 v120, v122, v121, vcc
	v_not_b32_e32 v121, v1
	v_or_b32_e32 v122, 0x80000000, v1
	v_cmp_gt_i32_e32 vcc, 0, v1
	v_and_b32_e32 v120, 0xffffff80, v120
	v_sub_u32_e32 v120, v120, v25
	v_cndmask_b32_e32 v1, v122, v121, vcc
	v_cvt_f32_f16_sdwa v121, v2 dst_sel:DWORD dst_unused:UNUSED_PAD src0_sel:WORD_1
	v_cvt_f32_f16_e32 v2, v2
	v_and_b32_e32 v1, 0xffffff80, v1
	v_sub_u32_e32 v1, v1, v25
	v_not_b32_e32 v122, v121
	v_or_b32_e32 v123, 0x80000000, v121
	v_cmp_gt_i32_e32 vcc, 0, v121
	v_add_u32_e32 v120, 0x7e, v120
	v_add_u32_e32 v1, 0x7f, v1
	v_cndmask_b32_e32 v121, v123, v122, vcc
	v_not_b32_e32 v122, v2
	v_or_b32_e32 v123, 0x80000000, v2
	v_cmp_gt_i32_e32 vcc, 0, v2
	v_and_b32_e32 v121, 0xffffff80, v121
	v_sub_u32_e32 v121, v121, v26
	v_cndmask_b32_e32 v2, v123, v122, vcc
	v_cvt_f32_f16_sdwa v122, v3 dst_sel:DWORD dst_unused:UNUSED_PAD src0_sel:WORD_1
	v_cvt_f32_f16_e32 v3, v3
	v_and_b32_e32 v2, 0xffffff80, v2
	v_sub_u32_e32 v2, v2, v26
	v_not_b32_e32 v123, v122
	v_or_b32_e32 v124, 0x80000000, v122
	v_cmp_gt_i32_e32 vcc, 0, v122
	v_add_u32_e32 v121, 0x7e, v121
	v_add_u32_e32 v2, 0x7f, v2
	v_cndmask_b32_e32 v122, v124, v123, vcc
	v_not_b32_e32 v123, v3
	v_or_b32_e32 v124, 0x80000000, v3
	v_cmp_gt_i32_e32 vcc, 0, v3
	v_and_b32_e32 v122, 0xffffff80, v122
	v_sub_u32_e32 v122, v122, v28
	v_cndmask_b32_e32 v3, v124, v123, vcc
	v_and_b32_e32 v3, 0xffffff80, v3
	v_sub_u32_e32 v3, v3, v28
	v_add_u32_e32 v122, 0x7e, v122
	v_add_u32_e32 v3, 0x7f, v3
	v_max_u32_e32 v123, v98, v106
	v_min_u32_e32 v98, v98, v106
	v_max_u32_e32 v106, v107, v99
	v_min_u32_e32 v99, v107, v99
	v_max_u32_e32 v107, v100, v108
	v_min_u32_e32 v100, v100, v108
	v_max_u32_e32 v108, v109, v101
	v_min_u32_e32 v101, v109, v101
	v_max_u32_e32 v109, v94, v110
	v_min_u32_e32 v94, v94, v110
	v_max_u32_e32 v110, v111, v95
	v_min_u32_e32 v95, v111, v95
	v_max_u32_e32 v111, v96, v112
	v_min_u32_e32 v96, v96, v112
	v_max_u32_e32 v112, v114, v97
	v_min_u32_e32 v97, v114, v97
	v_max_u32_e32 v131, v102, v115
	v_min_u32_e32 v102, v102, v115
	v_max_u32_e32 v115, v116, v103
	v_min_u32_e32 v103, v116, v103
	v_max_u32_e32 v116, v104, v117
	v_min_u32_e32 v104, v104, v117
	v_max_u32_e32 v117, v118, v105
	v_min_u32_e32 v105, v118, v105
	v_max_u32_e32 v118, v0, v119
	v_min_u32_e32 v0, v0, v119
	v_max_u32_e32 v119, v120, v1
	v_min_u32_e32 v1, v120, v1
	v_max_u32_e32 v120, v2, v121
	v_min_u32_e32 v2, v2, v121
; #define CE_DESC(a, b) do { const unsigned _mx = (a) > (b) ? (a) : (b), _mn = (a) > (b) ? (b) : (a); (a) = _mx; (b) = _mn; } while (0)
; __device__ __forceinline__ void sort16_desc(unsigned (&k)[16]) {
; #pragma unroll
;     for (int size = 2; size <= 16; size <<= 1)
; #pragma unroll
;         for (int stride = size >> 1; stride > 0; stride >>= 1)
; #pragma unroll
;             for (int i = 0; i < 16; ++i) { const int j = i ^ stride;
;                 if (j > i) { if ((i & size) == 0) CE_DESC(k[i], k[j]); else CE_DESC(k[j], k[i]); } }
; }
	v_max_u32_e32 v121, v122, v3
	v_min_u32_e32 v3, v122, v3
	v_max_u32_e32 v114, v123, v99
	v_min_u32_e32 v99, v123, v99
	v_max_u32_e32 v123, v98, v106
	v_min_u32_e32 v98, v98, v106
	v_max_u32_e32 v106, v101, v107
	v_min_u32_e32 v101, v101, v107
	v_max_u32_e32 v107, v108, v100
	v_min_u32_e32 v100, v108, v100
	v_max_u32_e32 v108, v109, v95
	v_min_u32_e32 v95, v109, v95
	v_max_u32_e32 v109, v94, v110
	v_min_u32_e32 v94, v94, v110
	v_max_u32_e32 v110, v97, v111
	v_min_u32_e32 v97, v97, v111
	v_max_u32_e32 v111, v112, v96
	v_min_u32_e32 v96, v112, v96
	v_max_u32_e32 v122, v131, v103
	v_min_u32_e32 v103, v131, v103
	v_max_u32_e32 v131, v102, v115
	v_min_u32_e32 v102, v102, v115
	v_max_u32_e32 v115, v105, v116
	v_min_u32_e32 v105, v105, v116
	v_max_u32_e32 v116, v117, v104
	v_min_u32_e32 v104, v117, v104
	v_max_u32_e32 v117, v118, v1
	v_min_u32_e32 v1, v118, v1
	v_max_u32_e32 v118, v0, v119
	v_min_u32_e32 v0, v0, v119
	v_max_u32_e32 v119, v3, v120
	v_min_u32_e32 v3, v3, v120
	v_max_u32_e32 v120, v121, v2
	v_min_u32_e32 v2, v121, v2
	v_max_u32_e32 v112, v114, v123
	v_min_u32_e32 v114, v114, v123
	v_max_u32_e32 v123, v99, v98
	v_min_u32_e32 v98, v99, v98
	v_max_u32_e32 v99, v100, v101
	v_min_u32_e32 v100, v100, v101
	v_max_u32_e32 v101, v107, v106
	v_min_u32_e32 v106, v107, v106
	v_max_u32_e32 v107, v108, v109
	v_min_u32_e32 v108, v108, v109
	v_max_u32_e32 v109, v95, v94
	v_min_u32_e32 v94, v95, v94
	v_max_u32_e32 v95, v96, v97
	v_min_u32_e32 v96, v96, v97
	v_max_u32_e32 v97, v111, v110
	v_min_u32_e32 v110, v111, v110
	v_max_u32_e32 v121, v122, v131
	v_min_u32_e32 v122, v122, v131
	v_max_u32_e32 v131, v103, v102
	v_min_u32_e32 v102, v103, v102
	v_max_u32_e32 v103, v104, v105
	v_min_u32_e32 v104, v104, v105
	v_max_u32_e32 v105, v116, v115
	v_min_u32_e32 v115, v116, v115
	v_max_u32_e32 v116, v117, v118
	v_min_u32_e32 v117, v117, v118
	v_max_u32_e32 v118, v1, v0
	v_min_u32_e32 v0, v1, v0
	v_max_u32_e32 v1, v2, v3
	v_min_u32_e32 v2, v2, v3
	v_max_u32_e32 v3, v120, v119
	v_min_u32_e32 v119, v120, v119
	v_max_u32_e32 v111, v112, v100
	v_min_u32_e32 v100, v112, v100
	v_max_u32_e32 v112, v114, v99
	v_min_u32_e32 v99, v114, v99
	v_max_u32_e32 v114, v123, v106
	v_min_u32_e32 v106, v123, v106
	v_max_u32_e32 v123, v98, v101
	v_min_u32_e32 v98, v98, v101
	v_max_u32_e32 v101, v96, v107
	v_min_u32_e32 v96, v96, v107
	v_max_u32_e32 v107, v95, v108
	v_min_u32_e32 v95, v95, v108
	v_max_u32_e32 v108, v110, v109
	v_min_u32_e32 v109, v110, v109
	v_max_u32_e32 v110, v97, v94
	v_min_u32_e32 v94, v97, v94
	v_max_u32_e32 v120, v121, v104
	v_min_u32_e32 v104, v121, v104
	v_max_u32_e32 v121, v122, v103
	v_min_u32_e32 v103, v122, v103
	v_max_u32_e32 v122, v131, v115
	v_min_u32_e32 v115, v131, v115
	v_max_u32_e32 v131, v102, v105
	v_min_u32_e32 v102, v102, v105
	v_max_u32_e32 v105, v2, v116
	v_min_u32_e32 v2, v2, v116
	v_max_u32_e32 v116, v1, v117
	v_min_u32_e32 v1, v1, v117
	v_max_u32_e32 v117, v119, v118
	v_min_u32_e32 v118, v119, v118
	v_max_u32_e32 v119, v3, v0
	v_min_u32_e32 v0, v3, v0
	v_max_u32_e32 v97, v111, v114
	v_min_u32_e32 v111, v111, v114
	v_max_u32_e32 v114, v112, v123
	v_min_u32_e32 v112, v112, v123
	v_max_u32_e32 v123, v100, v106
	v_min_u32_e32 v100, v100, v106
	v_max_u32_e32 v106, v99, v98
	v_min_u32_e32 v98, v99, v98
	v_max_u32_e32 v99, v109, v96
	v_min_u32_e32 v96, v109, v96
	v_max_u32_e32 v109, v94, v95
	v_min_u32_e32 v94, v94, v95
	v_max_u32_e32 v95, v108, v101
	v_min_u32_e32 v101, v108, v101
	v_max_u32_e32 v108, v110, v107
	v_min_u32_e32 v107, v110, v107
	v_max_u32_e32 v3, v120, v122
	v_min_u32_e32 v120, v120, v122
	v_max_u32_e32 v122, v121, v131
	v_min_u32_e32 v121, v121, v131
	v_max_u32_e32 v131, v104, v115
	v_min_u32_e32 v104, v104, v115
	v_max_u32_e32 v115, v103, v102
	v_min_u32_e32 v102, v103, v102
	v_max_u32_e32 v103, v118, v2
	v_min_u32_e32 v2, v118, v2
	v_max_u32_e32 v118, v0, v1
	v_min_u32_e32 v0, v0, v1
	v_max_u32_e32 v1, v117, v105
	v_min_u32_e32 v105, v117, v105
	v_max_u32_e32 v117, v119, v116
	v_min_u32_e32 v116, v119, v116
	v_max_u32_e32 v110, v97, v114
	v_min_u32_e32 v97, v97, v114
	v_max_u32_e32 v114, v111, v112
	v_min_u32_e32 v111, v111, v112
	v_max_u32_e32 v112, v123, v106
	v_min_u32_e32 v106, v123, v106
	v_max_u32_e32 v123, v100, v98
	v_min_u32_e32 v98, v100, v98
	v_max_u32_e32 v100, v94, v96
	v_min_u32_e32 v94, v94, v96
	v_max_u32_e32 v96, v109, v99
	v_min_u32_e32 v99, v109, v99
	v_max_u32_e32 v109, v107, v101
	v_min_u32_e32 v101, v107, v101
	v_max_u32_e32 v107, v108, v95
	v_min_u32_e32 v95, v108, v95
	v_max_u32_e32 v119, v3, v122
	v_min_u32_e32 v3, v3, v122
	v_max_u32_e32 v122, v120, v121
	v_min_u32_e32 v120, v120, v121
	v_max_u32_e32 v121, v131, v115
	v_min_u32_e32 v115, v131, v115
	v_max_u32_e32 v131, v104, v102
	v_min_u32_e32 v102, v104, v102
	v_max_u32_e32 v104, v0, v2
	v_min_u32_e32 v0, v0, v2
	v_max_u32_e32 v2, v118, v103
	v_min_u32_e32 v103, v118, v103
	v_max_u32_e32 v118, v116, v105
	v_min_u32_e32 v105, v116, v105
	v_max_u32_e32 v116, v117, v1
	v_min_u32_e32 v1, v117, v1
	v_max_u32_e32 v108, v110, v94
	v_min_u32_e32 v94, v110, v94
	v_max_u32_e32 v110, v97, v100
	v_min_u32_e32 v97, v97, v100
	v_max_u32_e32 v100, v114, v99
	v_min_u32_e32 v99, v114, v99
	v_max_u32_e32 v114, v111, v96
	v_min_u32_e32 v96, v111, v96
	v_max_u32_e32 v111, v112, v101
	v_min_u32_e32 v101, v112, v101
	v_max_u32_e32 v112, v106, v109
	v_min_u32_e32 v106, v106, v109
	v_max_u32_e32 v109, v123, v95
	v_min_u32_e32 v95, v123, v95
	v_max_u32_e32 v123, v98, v107
	v_min_u32_e32 v98, v98, v107
	v_max_u32_e32 v117, v119, v0
	v_min_u32_e32 v0, v119, v0
	v_max_u32_e32 v119, v3, v104
	v_min_u32_e32 v3, v3, v104
	v_max_u32_e32 v104, v122, v103
	v_min_u32_e32 v103, v122, v103
; #define CE_DESC(a, b) do { const unsigned _mx = (a) > (b) ? (a) : (b), _mn = (a) > (b) ? (b) : (a); (a) = _mx; (b) = _mn; } while (0)
; __device__ __forceinline__ void merge16(unsigned (&a)[16], const unsigned (&b)[16]) {
; #pragma unroll
;     for (int i = 0; i < 16; ++i) a[i] = a[i] > b[15 - i] ? a[i] : b[15 - i];
; #pragma unroll
;     for (int stride = 8; stride > 0; stride >>= 1)
; #pragma unroll
;         for (int i = 0; i < 16; ++i) { const int j = i ^ stride; if (j > i) CE_DESC(a[i], a[j]); }
; }
; __device__ __forceinline__ void peer_tile(const Args& A, LAS unsigned char* lds, int tile) {
;     ...
;                 for (int msk = 16; msk <= 32; msk <<= 1) {
; #pragma unroll
;                     for (int i = 0; i < 16; ++i) k1[i] = (unsigned)__shfl_xor((int)k0[i], msk);
;                     merge16(k0, k1); }
	v_max_u32_e32 v122, v120, v2
	v_min_u32_e32 v2, v120, v2
	v_max_u32_e32 v120, v121, v105
	v_min_u32_e32 v105, v121, v105
	v_max_u32_e32 v121, v115, v118
	v_min_u32_e32 v115, v115, v118
	v_max_u32_e32 v118, v131, v1
	v_min_u32_e32 v1, v131, v1
	v_max_u32_e32 v131, v102, v116
	v_min_u32_e32 v102, v102, v116
	v_max_u32_e32 v107, v108, v111
	v_min_u32_e32 v108, v108, v111
	v_max_u32_e32 v111, v110, v112
	v_min_u32_e32 v110, v110, v112
	v_max_u32_e32 v112, v100, v109
	v_min_u32_e32 v100, v100, v109
	v_max_u32_e32 v109, v114, v123
	v_min_u32_e32 v114, v114, v123
	v_max_u32_e32 v123, v94, v101
	v_min_u32_e32 v94, v94, v101
	v_max_u32_e32 v101, v97, v106
	v_min_u32_e32 v97, v97, v106
	v_max_u32_e32 v106, v99, v95
	v_min_u32_e32 v95, v99, v95
	v_max_u32_e32 v99, v96, v98
	v_min_u32_e32 v96, v96, v98
	v_max_u32_e32 v116, v117, v120
	v_min_u32_e32 v117, v117, v120
	v_max_u32_e32 v120, v119, v121
	v_min_u32_e32 v119, v119, v121
	v_max_u32_e32 v121, v104, v118
	v_min_u32_e32 v104, v104, v118
	v_max_u32_e32 v118, v122, v131
	v_min_u32_e32 v122, v122, v131
	v_max_u32_e32 v131, v0, v105
	v_min_u32_e32 v0, v0, v105
	v_max_u32_e32 v105, v3, v115
	v_min_u32_e32 v3, v3, v115
	v_max_u32_e32 v115, v103, v1
	v_min_u32_e32 v1, v103, v1
	v_max_u32_e32 v103, v2, v102
	v_min_u32_e32 v2, v2, v102
	v_max_u32_e32 v98, v107, v112
	v_min_u32_e32 v107, v107, v112
	v_max_u32_e32 v112, v111, v109
	v_min_u32_e32 v109, v111, v109
	v_max_u32_e32 v111, v108, v100
	v_min_u32_e32 v100, v108, v100
	v_max_u32_e32 v108, v110, v114
	v_min_u32_e32 v110, v110, v114
	v_max_u32_e32 v114, v123, v106
	v_min_u32_e32 v106, v123, v106
	v_max_u32_e32 v123, v101, v99
	v_min_u32_e32 v99, v101, v99
	v_max_u32_e32 v101, v94, v95
	v_min_u32_e32 v94, v94, v95
	v_max_u32_e32 v95, v97, v96
	v_min_u32_e32 v96, v97, v96
	v_max_u32_e32 v102, v116, v121
	v_min_u32_e32 v116, v116, v121
	v_max_u32_e32 v121, v120, v118
	v_min_u32_e32 v118, v120, v118
	v_max_u32_e32 v120, v117, v104
	v_min_u32_e32 v104, v117, v104
	v_max_u32_e32 v117, v119, v122
	v_min_u32_e32 v119, v119, v122
	v_max_u32_e32 v122, v131, v115
	v_min_u32_e32 v115, v131, v115
	v_max_u32_e32 v131, v105, v103
	v_min_u32_e32 v103, v105, v103
	v_max_u32_e32 v105, v0, v1
	v_min_u32_e32 v0, v0, v1
	v_max_u32_e32 v1, v3, v2
	v_min_u32_e32 v2, v3, v2
	v_min_u32_e32 v97, v98, v112
	v_min_u32_e32 v124, v107, v109
	v_min_u32_e32 v125, v111, v108
	v_min_u32_e32 v126, v100, v110
	v_min_u32_e32 v127, v114, v123
	v_min_u32_e32 v128, v106, v99
	v_min_u32_e32 v129, v101, v95
	v_min_u32_e32 v130, v94, v96
	v_min_u32_e32 v3, v102, v121
	v_min_u32_e32 v132, v116, v118
	v_min_u32_e32 v133, v120, v117
	v_min_u32_e32 v134, v104, v119
	v_min_u32_e32 v135, v122, v131
	v_min_u32_e32 v136, v115, v103
	v_min_u32_e32 v137, v105, v1
	v_min_u32_e32 v138, v0, v2
	v_max3_u32 v98, v98, v112, v138
	v_max3_u32 v0, v97, v0, v2
	v_max3_u32 v2, v107, v109, v137
	v_max3_u32 v1, v124, v105, v1
	v_max3_u32 v97, v111, v108, v136
	v_max3_u32 v103, v125, v115, v103
	v_max3_u32 v100, v100, v110, v135
	v_max3_u32 v105, v126, v122, v131
	v_max3_u32 v107, v114, v123, v134
	v_max3_u32 v104, v127, v104, v119
	v_max3_u32 v99, v106, v99, v133
	v_max3_u32 v106, v128, v120, v117
	v_max3_u32 v95, v101, v95, v132
	v_max3_u32 v101, v129, v116, v118
	v_max3_u32 v3, v94, v96, v3
	v_max3_u32 v94, v130, v102, v121
	v_max_u32_e32 v96, v98, v107
	v_min_u32_e32 v98, v98, v107
	v_max_u32_e32 v102, v0, v104
	v_min_u32_e32 v0, v0, v104
	v_max_u32_e32 v104, v2, v99
	v_min_u32_e32 v2, v2, v99
	v_max_u32_e32 v99, v1, v106
	v_min_u32_e32 v1, v1, v106
	v_max_u32_e32 v106, v97, v95
	v_min_u32_e32 v95, v97, v95
	v_max_u32_e32 v97, v103, v101
	v_min_u32_e32 v101, v103, v101
	v_max_u32_e32 v103, v100, v3
	v_min_u32_e32 v3, v100, v3
	v_max_u32_e32 v100, v105, v94
	v_min_u32_e32 v94, v105, v94
	v_max_u32_e32 v105, v96, v106
	v_min_u32_e32 v96, v96, v106
	v_max_u32_e32 v106, v102, v97
	v_min_u32_e32 v97, v102, v97
	v_max_u32_e32 v102, v104, v103
	v_min_u32_e32 v103, v104, v103
	v_max_u32_e32 v104, v99, v100
	v_min_u32_e32 v99, v99, v100
	v_max_u32_e32 v100, v98, v95
	v_min_u32_e32 v95, v98, v95
	v_max_u32_e32 v98, v0, v101
	v_min_u32_e32 v0, v0, v101
	v_max_u32_e32 v101, v2, v3
	v_min_u32_e32 v2, v2, v3
	v_max_u32_e32 v3, v1, v94
	v_min_u32_e32 v1, v1, v94
	v_max_u32_e32 v94, v105, v102
	v_min_u32_e32 v102, v105, v102
	v_max_u32_e32 v105, v106, v104
	v_min_u32_e32 v104, v106, v104
	v_max_u32_e32 v106, v96, v103
	v_min_u32_e32 v96, v96, v103
	v_max_u32_e32 v103, v97, v99
	v_min_u32_e32 v97, v97, v99
	v_max_u32_e32 v99, v100, v101
	v_min_u32_e32 v100, v100, v101
	v_max_u32_e32 v101, v98, v3
	v_min_u32_e32 v3, v98, v3
	v_max_u32_e32 v98, v95, v2
	v_min_u32_e32 v2, v95, v2
	v_max_u32_e32 v95, v0, v1
	v_min_u32_e32 v0, v0, v1
	v_max_u32_e32 v1, v94, v105
	v_min_u32_e32 v94, v94, v105
	v_max_u32_e32 v105, v102, v104
	v_min_u32_e32 v102, v102, v104
	v_max_u32_e32 v104, v106, v103
	v_min_u32_e32 v103, v106, v103
	v_max_u32_e32 v106, v96, v97
	v_min_u32_e32 v96, v96, v97
	v_max_u32_e32 v97, v99, v101
	v_min_u32_e32 v99, v99, v101
	v_max_u32_e32 v101, v100, v3
	v_min_u32_e32 v3, v100, v3
	v_max_u32_e32 v100, v98, v95
	v_min_u32_e32 v95, v98, v95
	v_max_u32_e32 v98, v2, v0
	v_min_u32_e32 v0, v2, v0
	ds_bpermute_b32 v2, v27, v1
	ds_bpermute_b32 v107, v27, v94
	ds_bpermute_b32 v108, v27, v105
	ds_bpermute_b32 v109, v27, v102
	ds_bpermute_b32 v110, v27, v104
	ds_bpermute_b32 v111, v27, v103
	ds_bpermute_b32 v112, v27, v106
	ds_bpermute_b32 v114, v27, v96
	ds_bpermute_b32 v115, v27, v97
	ds_bpermute_b32 v116, v27, v99
	ds_bpermute_b32 v117, v27, v101
	ds_bpermute_b32 v118, v27, v0
	ds_bpermute_b32 v119, v27, v98
	ds_bpermute_b32 v120, v27, v95
	ds_bpermute_b32 v121, v27, v100
	ds_bpermute_b32 v122, v27, v3
	s_waitcnt lgkmcnt(4)
; #define CE_DESC(a, b) do { const unsigned _mx = (a) > (b) ? (a) : (b), _mn = (a) > (b) ? (b) : (a); (a) = _mx; (b) = _mn; } while (0)
; __device__ __forceinline__ void merge16(unsigned (&a)[16], const unsigned (&b)[16]) {
; #pragma unroll
;     for (int i = 0; i < 16; ++i) a[i] = a[i] > b[15 - i] ? a[i] : b[15 - i];
; #pragma unroll
;     for (int stride = 8; stride > 0; stride >>= 1)
; #pragma unroll
;         for (int i = 0; i < 16; ++i) { const int j = i ^ stride; if (j > i) CE_DESC(a[i], a[j]); }
; }
; __device__ __forceinline__ void peer_tile(const Args& A, LAS unsigned char* lds, int tile) {
;     ...
;                 for (int msk = 16; msk <= 32; msk <<= 1) {
; #pragma unroll
;                     for (int i = 0; i < 16; ++i) k1[i] = (unsigned)__shfl_xor((int)k0[i], msk);
;                     merge16(k0, k1); }
	v_max_u32_e32 v1, v1, v118
	s_waitcnt lgkmcnt(3)
	v_max_u32_e32 v94, v94, v119
	s_waitcnt lgkmcnt(2)
	v_max_u32_e32 v105, v105, v120
	s_waitcnt lgkmcnt(1)
	v_max_u32_e32 v102, v102, v121
	s_waitcnt lgkmcnt(0)
	v_max_u32_e32 v104, v104, v122
	v_max_u32_e32 v103, v103, v117
	v_max_u32_e32 v106, v106, v116
	v_max_u32_e32 v96, v96, v115
	v_max_u32_e32 v97, v97, v114
	v_max_u32_e32 v99, v99, v112
	v_max_u32_e32 v101, v101, v111
	v_max_u32_e32 v3, v3, v110
	v_max_u32_e32 v100, v100, v109
	v_max_u32_e32 v95, v95, v108
	v_max_u32_e32 v98, v98, v107
	v_max_u32_e32 v0, v0, v2
	v_max_u32_e32 v2, v1, v97
	v_min_u32_e32 v1, v1, v97
	v_max_u32_e32 v97, v94, v99
	v_min_u32_e32 v94, v94, v99
	v_max_u32_e32 v99, v105, v101
	v_min_u32_e32 v101, v105, v101
	v_max_u32_e32 v105, v102, v3
	v_min_u32_e32 v3, v102, v3
	v_max_u32_e32 v102, v104, v100
	v_min_u32_e32 v100, v104, v100
	v_max_u32_e32 v104, v103, v95
	v_min_u32_e32 v95, v103, v95
	v_max_u32_e32 v103, v106, v98
	v_min_u32_e32 v98, v106, v98
	v_max_u32_e32 v106, v96, v0
	v_min_u32_e32 v0, v96, v0
	v_max_u32_e32 v96, v2, v102
	v_min_u32_e32 v2, v2, v102
	v_max_u32_e32 v102, v97, v104
	v_min_u32_e32 v97, v97, v104
	v_max_u32_e32 v104, v99, v103
	v_min_u32_e32 v99, v99, v103
	v_max_u32_e32 v103, v105, v106
	v_min_u32_e32 v105, v105, v106
	v_max_u32_e32 v106, v1, v100
	v_min_u32_e32 v1, v1, v100
	v_max_u32_e32 v100, v94, v95
	v_min_u32_e32 v94, v94, v95
	v_max_u32_e32 v95, v101, v98
	v_min_u32_e32 v98, v101, v98
	v_max_u32_e32 v101, v3, v0
	v_min_u32_e32 v0, v3, v0
	v_max_u32_e32 v3, v96, v104
	v_min_u32_e32 v96, v96, v104
	v_max_u32_e32 v104, v102, v103
	v_min_u32_e32 v102, v102, v103
	v_max_u32_e32 v103, v2, v99
	v_min_u32_e32 v2, v2, v99
	v_max_u32_e32 v99, v97, v105
	v_min_u32_e32 v97, v97, v105
	v_max_u32_e32 v105, v106, v95
	v_min_u32_e32 v95, v106, v95
	v_max_u32_e32 v106, v100, v101
	v_min_u32_e32 v100, v100, v101
	v_max_u32_e32 v101, v1, v98
	v_min_u32_e32 v1, v1, v98
	v_max_u32_e32 v98, v94, v0
	v_min_u32_e32 v0, v94, v0
	v_max_u32_e32 v94, v3, v104
	v_min_u32_e32 v3, v3, v104
	v_max_u32_e32 v104, v96, v102
	v_min_u32_e32 v96, v96, v102
	v_max_u32_e32 v102, v103, v99
	v_min_u32_e32 v99, v103, v99
	v_max_u32_e32 v103, v2, v97
	v_min_u32_e32 v2, v2, v97
	v_max_u32_e32 v97, v105, v106
	v_min_u32_e32 v105, v105, v106
	v_max_u32_e32 v106, v95, v100
	v_min_u32_e32 v95, v95, v100
	v_max_u32_e32 v100, v101, v98
	v_min_u32_e32 v98, v101, v98
	v_max_u32_e32 v101, v1, v0
	v_min_u32_e32 v0, v1, v0
	ds_bpermute_b32 v114, v29, v0
	ds_bpermute_b32 v1, v29, v94
	ds_bpermute_b32 v107, v29, v3
	ds_bpermute_b32 v108, v29, v104
	ds_bpermute_b32 v109, v29, v96
	s_waitcnt lgkmcnt(4)
	v_max_u32_e32 v94, v94, v114
	global_load_dwordx4 v[114:117], v[4:5], off offset:1296
	global_load_dwordx4 v[118:121], v[4:5], off offset:1280
	ds_bpermute_b32 v110, v29, v102
	ds_bpermute_b32 v111, v29, v99
	ds_bpermute_b32 v112, v29, v103
	ds_bpermute_b32 v122, v29, v2
	ds_bpermute_b32 v123, v29, v97
	ds_bpermute_b32 v124, v29, v105
	ds_bpermute_b32 v125, v29, v106
	ds_bpermute_b32 v126, v29, v95
	ds_bpermute_b32 v127, v29, v100
	ds_bpermute_b32 v128, v29, v101
	ds_bpermute_b32 v129, v29, v98
	s_waitcnt lgkmcnt(4)
	v_max_u32_e32 v99, v99, v125
	s_waitcnt lgkmcnt(3)
	v_max_u32_e32 v102, v102, v126
	s_waitcnt lgkmcnt(2)
	v_max_u32_e32 v96, v96, v127
	s_waitcnt lgkmcnt(1)
	v_max_u32_e32 v3, v3, v128
	s_waitcnt lgkmcnt(0)
	v_max_u32_e32 v104, v104, v129
	v_max_u32_e32 v103, v103, v124
	v_max_u32_e32 v2, v2, v123
	v_max_u32_e32 v97, v97, v122
	v_max_u32_e32 v105, v105, v112
	v_max_u32_e32 v106, v106, v111
	v_max_u32_e32 v95, v95, v110
	v_max_u32_e32 v100, v100, v109
	v_max_u32_e32 v98, v98, v108
	v_max_u32_e32 v101, v101, v107
	v_max_u32_e32 v0, v0, v1
	v_max_u32_e32 v1, v94, v97
	v_min_u32_e32 v94, v94, v97
	v_max_u32_e32 v97, v3, v105
	v_min_u32_e32 v3, v3, v105
	v_max_u32_e32 v105, v104, v106
	v_min_u32_e32 v104, v104, v106
	v_max_u32_e32 v106, v96, v95
	v_min_u32_e32 v95, v96, v95
	v_max_u32_e32 v96, v102, v100
	v_min_u32_e32 v100, v102, v100
	v_max_u32_e32 v102, v99, v98
	v_min_u32_e32 v98, v99, v98
	v_max_u32_e32 v99, v103, v101
	v_min_u32_e32 v101, v103, v101
	v_max_u32_e32 v103, v2, v0
	v_min_u32_e32 v0, v2, v0
	v_max_u32_e32 v2, v1, v96
	v_min_u32_e32 v1, v1, v96
	v_max_u32_e32 v96, v97, v102
	v_min_u32_e32 v97, v97, v102
	v_max_u32_e32 v102, v105, v99
	v_min_u32_e32 v99, v105, v99
	v_max_u32_e32 v105, v106, v103
	v_min_u32_e32 v103, v106, v103
	v_max_u32_e32 v106, v94, v100
	v_min_u32_e32 v94, v94, v100
	v_max_u32_e32 v100, v3, v98
	v_min_u32_e32 v3, v3, v98
	v_max_u32_e32 v98, v104, v101
	v_min_u32_e32 v101, v104, v101
	v_max_u32_e32 v104, v95, v0
	v_min_u32_e32 v0, v95, v0
	v_max_u32_e32 v95, v2, v102
	v_min_u32_e32 v2, v2, v102
	v_max_u32_e32 v102, v96, v105
	v_min_u32_e32 v96, v96, v105
	v_max_u32_e32 v110, v1, v99
	v_min_u32_e32 v1, v1, v99
	v_max_u32_e32 v99, v97, v103
	v_min_u32_e32 v97, v97, v103
	v_max_u32_e32 v111, v106, v98
	v_min_u32_e32 v98, v106, v98
	v_min_u32_e32 v122, v100, v104
	v_max_u32_e32 v123, v94, v101
	v_min_u32_e32 v94, v94, v101
	v_max_u32_e32 v124, v3, v0
	v_min_u32_e32 v0, v3, v0
	v_max_u32_e32 v112, v100, v104
	v_max_u32_e32 v109, v95, v102
	v_min_u32_e32 v108, v95, v102
	v_max_u32_e32 v107, v2, v96
	v_min_u32_e32 v106, v2, v96
	v_max_u32_e32 v105, v110, v99
	v_min_u32_e32 v104, v110, v99
	v_max_u32_e32 v103, v1, v97
	v_min_u32_e32 v102, v1, v97
	v_max_u32_e32 v99, v98, v122
	v_min_u32_e32 v98, v98, v122
	v_max_u32_e32 v97, v123, v124
	v_min_u32_e32 v96, v123, v124
	v_max_u32_e32 v95, v94, v0
	v_min_u32_e32 v94, v94, v0
	global_load_dwordx4 v[0:3], v[4:5], off offset:1328
	global_load_dwordx4 v[122:125], v[4:5], off offset:1312
	s_waitcnt vmcnt(2)
; __device__ __forceinline__ unsigned f2key(float f) { const unsigned u = __float_as_uint(f); return (u & 0x80000000u) ? ~u : (u | 0x80000000u); }
; __device__ __forceinline__ void peer_tile(const Args& A, LAS unsigned char* lds, int tile) {
;     ...
;                 { const bf16_t* sp = QRY + m * 2048 + hp * 128 + 32 * g;
;                   const u32x4 s0 = *(const u32x4*)sp, s1 = *(const u32x4*)(sp + 8), s2 = *(const u32x4*)(sp + 16), s3 = *(const u32x4*)(sp + 24);
;                   const unsigned sw[16] = {s0.x, s0.y, s0.z, s0.w, s1.x, s1.y, s1.z, s1.w, s2.x, s2.y, s2.z, s2.w, s3.x, s3.y, s3.z, s3.w};
; #pragma unroll
;                   for (int i = 0; i < 16; ++i) {
;                       const float lo = (float)__builtin_bit_cast(_Float16, (unsigned short)(sw[i] & 0xffffu)), hi = (float)__builtin_bit_cast(_Float16, (unsigned short)(sw[i] >> 16));
;                       const unsigned klo = (f2key(lo) & ~127u) | (unsigned)(127 - (32 * g + 2 * i)), khi = (f2key(hi) & ~127u) | (unsigned)(127 - (32 * g + 2 * i + 1));
;                       if (i < 8) { k0[2 * i] = klo; k0[2 * i + 1] = khi; } else { k1[2 * (i - 8)] = klo; k1[2 * (i - 8) + 1] = khi; } } }
;     ...
;                 for (int i = 0; i < 16; ++i) L2[p][i] = (g & 2) ? ((g & 1) ? LA[3][p][i] : LA[2][p][i]) : ((g & 1) ? LA[1][p][i] : LA[0][p][i]);
	v_cvt_f32_f16_sdwa v110, v118 dst_sel:DWORD dst_unused:UNUSED_PAD src0_sel:WORD_1
	v_max_u32_e32 v101, v111, v112
	v_min_u32_e32 v100, v111, v112
	v_cvt_f32_f16_e32 v111, v118
	v_not_b32_e32 v112, v110
	v_or_b32_e32 v118, 0x80000000, v110
	v_cmp_gt_i32_e32 vcc, 0, v110
	v_cndmask_b32_e64 v30, v62, v30, s[0:1]
	s_nop 0
	v_cndmask_b32_e32 v110, v118, v112, vcc
	v_not_b32_e32 v112, v111
	v_or_b32_e32 v118, 0x80000000, v111
	v_cmp_gt_i32_e32 vcc, 0, v111
	v_and_b32_e32 v110, 0xffffff80, v110
	v_sub_u32_e32 v110, v110, v15
	v_cndmask_b32_e32 v111, v118, v112, vcc
	v_cvt_f32_f16_sdwa v112, v119 dst_sel:DWORD dst_unused:UNUSED_PAD src0_sel:WORD_1
	v_cvt_f32_f16_e32 v118, v119
	v_and_b32_e32 v111, 0xffffff80, v111
	v_sub_u32_e32 v111, v111, v15
	v_not_b32_e32 v119, v112
	v_or_b32_e32 v126, 0x80000000, v112
	v_cmp_gt_i32_e32 vcc, 0, v112
	v_add_u32_e32 v110, 0x7e, v110
	v_add_u32_e32 v111, 0x7f, v111
	v_cndmask_b32_e32 v112, v126, v119, vcc
	v_not_b32_e32 v119, v118
	v_or_b32_e32 v126, 0x80000000, v118
	v_cmp_gt_i32_e32 vcc, 0, v118
	v_and_b32_e32 v112, 0xffffff80, v112
	v_sub_u32_e32 v112, v112, v14
	v_cndmask_b32_e32 v118, v126, v119, vcc
	v_cvt_f32_f16_sdwa v119, v120 dst_sel:DWORD dst_unused:UNUSED_PAD src0_sel:WORD_1
	v_cvt_f32_f16_e32 v120, v120
	v_and_b32_e32 v118, 0xffffff80, v118
	v_sub_u32_e32 v118, v118, v14
	v_not_b32_e32 v126, v119
	v_or_b32_e32 v127, 0x80000000, v119
	v_cmp_gt_i32_e32 vcc, 0, v119
	v_add_u32_e32 v112, 0x7e, v112
	v_add_u32_e32 v118, 0x7f, v118
	v_cndmask_b32_e32 v119, v127, v126, vcc
	v_not_b32_e32 v126, v120
	v_or_b32_e32 v127, 0x80000000, v120
	v_cmp_gt_i32_e32 vcc, 0, v120
	v_and_b32_e32 v119, 0xffffff80, v119
	v_sub_u32_e32 v119, v119, v12
	v_cndmask_b32_e32 v120, v127, v126, vcc
	v_cvt_f32_f16_sdwa v126, v121 dst_sel:DWORD dst_unused:UNUSED_PAD src0_sel:WORD_1
	v_cvt_f32_f16_e32 v121, v121
	v_and_b32_e32 v120, 0xffffff80, v120
	v_sub_u32_e32 v120, v120, v12
	v_not_b32_e32 v127, v126
	v_or_b32_e32 v128, 0x80000000, v126
	v_cmp_gt_i32_e32 vcc, 0, v126
	v_add_u32_e32 v119, 0x7e, v119
	v_add_u32_e32 v120, 0x7f, v120
	v_cndmask_b32_e32 v126, v128, v127, vcc
	v_not_b32_e32 v127, v121
	v_or_b32_e32 v128, 0x80000000, v121
	v_cmp_gt_i32_e32 vcc, 0, v121
	v_and_b32_e32 v126, 0xffffff80, v126
	v_sub_u32_e32 v126, v126, v10
	v_cndmask_b32_e32 v121, v128, v127, vcc
	v_cvt_f32_f16_sdwa v127, v114 dst_sel:DWORD dst_unused:UNUSED_PAD src0_sel:WORD_1
	v_cvt_f32_f16_e32 v114, v114
	v_and_b32_e32 v121, 0xffffff80, v121
	v_sub_u32_e32 v121, v121, v10
	v_not_b32_e32 v128, v127
	v_or_b32_e32 v129, 0x80000000, v127
	v_cmp_gt_i32_e32 vcc, 0, v127
	v_add_u32_e32 v126, 0x7e, v126
	v_add_u32_e32 v121, 0x7f, v121
	v_cndmask_b32_e32 v127, v129, v128, vcc
	v_not_b32_e32 v128, v114
	v_or_b32_e32 v129, 0x80000000, v114
	v_cmp_gt_i32_e32 vcc, 0, v114
	v_and_b32_e32 v127, 0xffffff80, v127
	v_sub_u32_e32 v127, v127, v8
	v_cndmask_b32_e32 v114, v129, v128, vcc
	v_cvt_f32_f16_sdwa v128, v115 dst_sel:DWORD dst_unused:UNUSED_PAD src0_sel:WORD_1
	v_cvt_f32_f16_e32 v115, v115
	v_and_b32_e32 v114, 0xffffff80, v114
	v_sub_u32_e32 v114, v114, v8
	v_not_b32_e32 v129, v128
	v_or_b32_e32 v130, 0x80000000, v128
	v_cmp_gt_i32_e32 vcc, 0, v128
	v_add_u32_e32 v127, 0x7e, v127
	v_add_u32_e32 v114, 0x7f, v114
	v_cndmask_b32_e32 v128, v130, v129, vcc
	v_not_b32_e32 v129, v115
	v_or_b32_e32 v130, 0x80000000, v115
	v_cmp_gt_i32_e32 vcc, 0, v115
	v_and_b32_e32 v128, 0xffffff80, v128
	v_sub_u32_e32 v128, v128, v16
	v_cndmask_b32_e32 v115, v130, v129, vcc
	v_cvt_f32_f16_sdwa v129, v116 dst_sel:DWORD dst_unused:UNUSED_PAD src0_sel:WORD_1
	v_cvt_f32_f16_e32 v116, v116
	v_and_b32_e32 v115, 0xffffff80, v115
	v_sub_u32_e32 v115, v115, v16
	v_not_b32_e32 v130, v129
	v_or_b32_e32 v131, 0x80000000, v129
	v_cmp_gt_i32_e32 vcc, 0, v129
	v_add_u32_e32 v128, 0x7e, v128
	v_add_u32_e32 v115, 0x7f, v115
	v_cndmask_b32_e32 v129, v131, v130, vcc
	v_not_b32_e32 v130, v116
	v_or_b32_e32 v131, 0x80000000, v116
	v_cmp_gt_i32_e32 vcc, 0, v116
	v_and_b32_e32 v129, 0xffffff80, v129
	v_sub_u32_e32 v129, v129, v17
	v_cndmask_b32_e32 v116, v131, v130, vcc
	v_cvt_f32_f16_sdwa v130, v117 dst_sel:DWORD dst_unused:UNUSED_PAD src0_sel:WORD_1
	v_cvt_f32_f16_e32 v117, v117
	v_and_b32_e32 v116, 0xffffff80, v116
	v_sub_u32_e32 v116, v116, v17
	v_not_b32_e32 v131, v130
	v_or_b32_e32 v132, 0x80000000, v130
	v_cmp_gt_i32_e32 vcc, 0, v130
	v_add_u32_e32 v129, 0x7e, v129
	v_add_u32_e32 v116, 0x7f, v116
	v_cndmask_b32_e32 v130, v132, v131, vcc
	v_not_b32_e32 v131, v117
	v_or_b32_e32 v132, 0x80000000, v117
	v_cmp_gt_i32_e32 vcc, 0, v117
	v_and_b32_e32 v130, 0xffffff80, v130
	v_sub_u32_e32 v130, v130, v18
	v_cndmask_b32_e32 v117, v132, v131, vcc
	s_waitcnt vmcnt(0)
; __device__ __forceinline__ unsigned f2key(float f) { const unsigned u = __float_as_uint(f); return (u & 0x80000000u) ? ~u : (u | 0x80000000u); }
; #define CE_DESC(a, b) do { const unsigned _mx = (a) > (b) ? (a) : (b), _mn = (a) > (b) ? (b) : (a); (a) = _mx; (b) = _mn; } while (0)
; __device__ __forceinline__ void sort16_desc(unsigned (&k)[16]) {
; #pragma unroll
;     for (int size = 2; size <= 16; size <<= 1)
; #pragma unroll
;         for (int stride = size >> 1; stride > 0; stride >>= 1)
; #pragma unroll
;             for (int i = 0; i < 16; ++i) { const int j = i ^ stride;
;                 if (j > i) { if ((i & size) == 0) CE_DESC(k[i], k[j]); else CE_DESC(k[j], k[i]); } }
; }
; __device__ __forceinline__ void peer_tile(const Args& A, LAS unsigned char* lds, int tile) {
;     ...
;                   for (int i = 0; i < 16; ++i) {
;                       const float lo = (float)__builtin_bit_cast(_Float16, (unsigned short)(sw[i] & 0xffffu)), hi = (float)__builtin_bit_cast(_Float16, (unsigned short)(sw[i] >> 16));
;                       const unsigned klo = (f2key(lo) & ~127u) | (unsigned)(127 - (32 * g + 2 * i)), khi = (f2key(hi) & ~127u) | (unsigned)(127 - (32 * g + 2 * i + 1));
;                       if (i < 8) { k0[2 * i] = klo; k0[2 * i + 1] = khi; } else { k1[2 * (i - 8)] = klo; k1[2 * (i - 8) + 1] = khi; } } }
;                 sort16_desc(k0); sort16_desc(k1); merge16(k0, k1);
	v_cvt_f32_f16_sdwa v131, v122 dst_sel:DWORD dst_unused:UNUSED_PAD src0_sel:WORD_1
	v_cvt_f32_f16_e32 v122, v122
	v_and_b32_e32 v117, 0xffffff80, v117
	v_sub_u32_e32 v117, v117, v18
	v_not_b32_e32 v132, v131
	v_or_b32_e32 v133, 0x80000000, v131
	v_cmp_gt_i32_e32 vcc, 0, v131
	v_add_u32_e32 v130, 0x7e, v130
	v_add_u32_e32 v117, 0x7f, v117
	v_cndmask_b32_e32 v131, v133, v132, vcc
	v_not_b32_e32 v132, v122
	v_or_b32_e32 v133, 0x80000000, v122
	v_cmp_gt_i32_e32 vcc, 0, v122
	v_and_b32_e32 v131, 0xffffff80, v131
	v_sub_u32_e32 v131, v131, v20
	v_cndmask_b32_e32 v122, v133, v132, vcc
	v_cvt_f32_f16_sdwa v132, v123 dst_sel:DWORD dst_unused:UNUSED_PAD src0_sel:WORD_1
	v_cvt_f32_f16_e32 v123, v123
	v_and_b32_e32 v122, 0xffffff80, v122
	v_sub_u32_e32 v122, v122, v20
	v_not_b32_e32 v133, v132
	v_or_b32_e32 v134, 0x80000000, v132
	v_cmp_gt_i32_e32 vcc, 0, v132
	v_add_u32_e32 v131, 0x7e, v131
	v_add_u32_e32 v122, 0x7f, v122
	v_cndmask_b32_e32 v132, v134, v133, vcc
	v_not_b32_e32 v133, v123
	v_or_b32_e32 v134, 0x80000000, v123
	v_cmp_gt_i32_e32 vcc, 0, v123
	v_and_b32_e32 v132, 0xffffff80, v132
	v_sub_u32_e32 v132, v132, v21
	v_cndmask_b32_e32 v123, v134, v133, vcc
	v_cvt_f32_f16_sdwa v133, v124 dst_sel:DWORD dst_unused:UNUSED_PAD src0_sel:WORD_1
	v_cvt_f32_f16_e32 v124, v124
	v_and_b32_e32 v123, 0xffffff80, v123
	v_sub_u32_e32 v123, v123, v21
	v_not_b32_e32 v134, v133
	v_or_b32_e32 v135, 0x80000000, v133
	v_cmp_gt_i32_e32 vcc, 0, v133
	v_add_u32_e32 v132, 0x7e, v132
	v_add_u32_e32 v123, 0x7f, v123
	v_cndmask_b32_e32 v133, v135, v134, vcc
	v_not_b32_e32 v134, v124
	v_or_b32_e32 v135, 0x80000000, v124
	v_cmp_gt_i32_e32 vcc, 0, v124
	v_and_b32_e32 v133, 0xffffff80, v133
	v_sub_u32_e32 v133, v133, v22
	v_cndmask_b32_e32 v124, v135, v134, vcc
	v_cvt_f32_f16_sdwa v134, v125 dst_sel:DWORD dst_unused:UNUSED_PAD src0_sel:WORD_1
	v_cvt_f32_f16_e32 v125, v125
	v_and_b32_e32 v124, 0xffffff80, v124
	v_sub_u32_e32 v124, v124, v22
	v_not_b32_e32 v135, v134
	v_or_b32_e32 v136, 0x80000000, v134
	v_cmp_gt_i32_e32 vcc, 0, v134
	v_add_u32_e32 v133, 0x7e, v133
	v_add_u32_e32 v124, 0x7f, v124
	v_cndmask_b32_e32 v134, v136, v135, vcc
	v_not_b32_e32 v135, v125
	v_or_b32_e32 v136, 0x80000000, v125
	v_cmp_gt_i32_e32 vcc, 0, v125
	v_and_b32_e32 v134, 0xffffff80, v134
	v_sub_u32_e32 v134, v134, v23
	v_cndmask_b32_e32 v125, v136, v135, vcc
	v_cvt_f32_f16_sdwa v135, v0 dst_sel:DWORD dst_unused:UNUSED_PAD src0_sel:WORD_1
	v_cvt_f32_f16_e32 v0, v0
	v_and_b32_e32 v125, 0xffffff80, v125
	v_sub_u32_e32 v125, v125, v23
	v_not_b32_e32 v136, v135
	v_or_b32_e32 v137, 0x80000000, v135
	v_cmp_gt_i32_e32 vcc, 0, v135
	v_add_u32_e32 v134, 0x7e, v134
	v_add_u32_e32 v125, 0x7f, v125
	v_cndmask_b32_e32 v135, v137, v136, vcc
	v_not_b32_e32 v136, v0
	v_or_b32_e32 v137, 0x80000000, v0
	v_cmp_gt_i32_e32 vcc, 0, v0
	v_and_b32_e32 v135, 0xffffff80, v135
	v_sub_u32_e32 v135, v135, v24
	v_cndmask_b32_e32 v0, v137, v136, vcc
	v_cvt_f32_f16_sdwa v136, v1 dst_sel:DWORD dst_unused:UNUSED_PAD src0_sel:WORD_1
	v_cvt_f32_f16_e32 v1, v1
	v_and_b32_e32 v0, 0xffffff80, v0
	v_sub_u32_e32 v0, v0, v24
	v_not_b32_e32 v137, v136
	v_or_b32_e32 v138, 0x80000000, v136
	v_cmp_gt_i32_e32 vcc, 0, v136
	v_add_u32_e32 v135, 0x7e, v135
	v_add_u32_e32 v0, 0x7f, v0
	v_cndmask_b32_e32 v136, v138, v137, vcc
	v_not_b32_e32 v137, v1
	v_or_b32_e32 v138, 0x80000000, v1
	v_cmp_gt_i32_e32 vcc, 0, v1
	v_and_b32_e32 v136, 0xffffff80, v136
	v_sub_u32_e32 v136, v136, v25
	v_cndmask_b32_e32 v1, v138, v137, vcc
	v_cvt_f32_f16_sdwa v137, v2 dst_sel:DWORD dst_unused:UNUSED_PAD src0_sel:WORD_1
	v_cvt_f32_f16_e32 v2, v2
	v_and_b32_e32 v1, 0xffffff80, v1
	v_sub_u32_e32 v1, v1, v25
	v_not_b32_e32 v138, v137
	v_or_b32_e32 v139, 0x80000000, v137
	v_cmp_gt_i32_e32 vcc, 0, v137
	v_add_u32_e32 v136, 0x7e, v136
	v_add_u32_e32 v1, 0x7f, v1
	v_cndmask_b32_e32 v137, v139, v138, vcc
	v_not_b32_e32 v138, v2
	v_or_b32_e32 v139, 0x80000000, v2
	v_cmp_gt_i32_e32 vcc, 0, v2
	v_and_b32_e32 v137, 0xffffff80, v137
	v_sub_u32_e32 v137, v137, v26
	v_cndmask_b32_e32 v2, v139, v138, vcc
	v_cvt_f32_f16_sdwa v138, v3 dst_sel:DWORD dst_unused:UNUSED_PAD src0_sel:WORD_1
	v_cvt_f32_f16_e32 v3, v3
	v_and_b32_e32 v2, 0xffffff80, v2
	v_sub_u32_e32 v2, v2, v26
	v_not_b32_e32 v139, v138
	v_or_b32_e32 v140, 0x80000000, v138
	v_cmp_gt_i32_e32 vcc, 0, v138
	v_add_u32_e32 v137, 0x7e, v137
	v_add_u32_e32 v2, 0x7f, v2
	v_cndmask_b32_e32 v138, v140, v139, vcc
	v_not_b32_e32 v139, v3
	v_or_b32_e32 v140, 0x80000000, v3
	v_cmp_gt_i32_e32 vcc, 0, v3
	v_and_b32_e32 v138, 0xffffff80, v138
	v_sub_u32_e32 v138, v138, v28
	v_cndmask_b32_e32 v3, v140, v139, vcc
	v_and_b32_e32 v3, 0xffffff80, v3
	v_sub_u32_e32 v3, v3, v28
	v_add_u32_e32 v138, 0x7e, v138
	v_add_u32_e32 v3, 0x7f, v3
	v_max_u32_e32 v139, v111, v110
	v_min_u32_e32 v110, v111, v110
	v_max_u32_e32 v111, v112, v118
	v_min_u32_e32 v112, v112, v118
	v_max_u32_e32 v118, v120, v119
	v_min_u32_e32 v119, v120, v119
	v_max_u32_e32 v120, v126, v121
	v_min_u32_e32 v121, v126, v121
	v_max_u32_e32 v126, v114, v127
	v_min_u32_e32 v114, v114, v127
	v_max_u32_e32 v127, v128, v115
	v_min_u32_e32 v115, v128, v115
	v_max_u32_e32 v128, v116, v129
	v_min_u32_e32 v116, v116, v129
	v_max_u32_e32 v129, v130, v117
	v_min_u32_e32 v117, v130, v117
	v_max_u32_e32 v147, v122, v131
	v_min_u32_e32 v122, v122, v131
	v_max_u32_e32 v131, v132, v123
	v_min_u32_e32 v123, v132, v123
	v_max_u32_e32 v132, v124, v133
	v_min_u32_e32 v124, v124, v133
	v_max_u32_e32 v133, v134, v125
	v_min_u32_e32 v125, v134, v125
	v_max_u32_e32 v134, v0, v135
	v_min_u32_e32 v0, v0, v135
	v_max_u32_e32 v135, v136, v1
	v_min_u32_e32 v1, v136, v1
	v_max_u32_e32 v136, v2, v137
	v_min_u32_e32 v2, v2, v137
; #define CE_DESC(a, b) do { const unsigned _mx = (a) > (b) ? (a) : (b), _mn = (a) > (b) ? (b) : (a); (a) = _mx; (b) = _mn; } while (0)
; __device__ __forceinline__ void sort16_desc(unsigned (&k)[16]) {
; #pragma unroll
;     for (int size = 2; size <= 16; size <<= 1)
; #pragma unroll
;         for (int stride = size >> 1; stride > 0; stride >>= 1)
; #pragma unroll
;             for (int i = 0; i < 16; ++i) { const int j = i ^ stride;
;                 if (j > i) { if ((i & size) == 0) CE_DESC(k[i], k[j]); else CE_DESC(k[j], k[i]); } }
; }
	v_max_u32_e32 v137, v138, v3
	v_min_u32_e32 v3, v138, v3
	v_max_u32_e32 v130, v139, v112
	v_min_u32_e32 v112, v139, v112
	v_max_u32_e32 v139, v110, v111
	v_min_u32_e32 v110, v110, v111
	v_max_u32_e32 v111, v121, v118
	v_min_u32_e32 v118, v121, v118
	v_max_u32_e32 v121, v120, v119
	v_min_u32_e32 v119, v120, v119
	v_max_u32_e32 v120, v126, v115
	v_min_u32_e32 v115, v126, v115
	v_max_u32_e32 v126, v114, v127
	v_min_u32_e32 v114, v114, v127
	v_max_u32_e32 v127, v117, v128
	v_min_u32_e32 v117, v117, v128
	v_max_u32_e32 v128, v129, v116
	v_min_u32_e32 v116, v129, v116
	v_max_u32_e32 v138, v147, v123
	v_min_u32_e32 v123, v147, v123
	v_max_u32_e32 v147, v122, v131
	v_min_u32_e32 v122, v122, v131
	v_max_u32_e32 v131, v125, v132
	v_min_u32_e32 v125, v125, v132
	v_max_u32_e32 v132, v133, v124
	v_min_u32_e32 v124, v133, v124
	v_max_u32_e32 v133, v134, v1
	v_min_u32_e32 v1, v134, v1
	v_max_u32_e32 v134, v0, v135
	v_min_u32_e32 v0, v0, v135
	v_max_u32_e32 v135, v3, v136
	v_min_u32_e32 v3, v3, v136
	v_max_u32_e32 v136, v137, v2
	v_min_u32_e32 v2, v137, v2
	v_max_u32_e32 v129, v130, v139
	v_min_u32_e32 v130, v130, v139
	v_max_u32_e32 v139, v112, v110
	v_min_u32_e32 v110, v112, v110
	v_max_u32_e32 v112, v119, v118
	v_min_u32_e32 v118, v119, v118
	v_max_u32_e32 v119, v121, v111
	v_min_u32_e32 v111, v121, v111
	v_max_u32_e32 v121, v120, v126
	v_min_u32_e32 v120, v120, v126
	v_max_u32_e32 v126, v115, v114
	v_min_u32_e32 v114, v115, v114
	v_max_u32_e32 v115, v116, v117
	v_min_u32_e32 v116, v116, v117
	v_max_u32_e32 v117, v128, v127
	v_min_u32_e32 v127, v128, v127
	v_max_u32_e32 v137, v138, v147
	v_min_u32_e32 v138, v138, v147
	v_max_u32_e32 v147, v123, v122
	v_min_u32_e32 v122, v123, v122
	v_max_u32_e32 v123, v124, v125
	v_min_u32_e32 v124, v124, v125
	v_max_u32_e32 v125, v132, v131
	v_min_u32_e32 v131, v132, v131
	v_max_u32_e32 v132, v133, v134
	v_min_u32_e32 v133, v133, v134
	v_max_u32_e32 v134, v1, v0
	v_min_u32_e32 v0, v1, v0
	v_max_u32_e32 v1, v2, v3
	v_min_u32_e32 v2, v2, v3
	v_max_u32_e32 v3, v136, v135
	v_min_u32_e32 v135, v136, v135
	v_max_u32_e32 v128, v129, v118
	v_min_u32_e32 v118, v129, v118
	v_max_u32_e32 v129, v130, v112
	v_min_u32_e32 v112, v130, v112
	v_max_u32_e32 v130, v139, v111
	v_min_u32_e32 v111, v139, v111
	v_max_u32_e32 v139, v110, v119
	v_min_u32_e32 v110, v110, v119
	v_max_u32_e32 v119, v116, v121
	v_min_u32_e32 v116, v116, v121
	v_max_u32_e32 v121, v115, v120
	v_min_u32_e32 v115, v115, v120
	v_max_u32_e32 v120, v127, v126
	v_min_u32_e32 v126, v127, v126
	v_max_u32_e32 v127, v117, v114
	v_min_u32_e32 v114, v117, v114
	v_max_u32_e32 v136, v137, v124
	v_min_u32_e32 v124, v137, v124
	v_max_u32_e32 v137, v138, v123
	v_min_u32_e32 v123, v138, v123
	v_max_u32_e32 v138, v147, v131
	v_min_u32_e32 v131, v147, v131
	v_max_u32_e32 v147, v122, v125
	v_min_u32_e32 v122, v122, v125
	v_max_u32_e32 v125, v2, v132
	v_min_u32_e32 v2, v2, v132
	v_max_u32_e32 v132, v1, v133
	v_min_u32_e32 v1, v1, v133
	v_max_u32_e32 v133, v135, v134
	v_min_u32_e32 v134, v135, v134
	v_max_u32_e32 v135, v3, v0
	v_min_u32_e32 v0, v3, v0
	v_max_u32_e32 v117, v128, v130
	v_min_u32_e32 v128, v128, v130
	v_max_u32_e32 v130, v129, v139
	v_min_u32_e32 v129, v129, v139
	v_max_u32_e32 v139, v118, v111
	v_min_u32_e32 v111, v118, v111
	v_max_u32_e32 v118, v112, v110
	v_min_u32_e32 v110, v112, v110
	v_max_u32_e32 v112, v126, v116
	v_min_u32_e32 v116, v126, v116
	v_max_u32_e32 v126, v114, v115
	v_min_u32_e32 v114, v114, v115
	v_max_u32_e32 v115, v120, v119
	v_min_u32_e32 v119, v120, v119
	v_max_u32_e32 v120, v127, v121
	v_min_u32_e32 v121, v127, v121
	v_max_u32_e32 v3, v136, v138
	v_min_u32_e32 v136, v136, v138
	v_max_u32_e32 v138, v137, v147
	v_min_u32_e32 v137, v137, v147
	v_max_u32_e32 v147, v124, v131
	v_min_u32_e32 v124, v124, v131
	v_max_u32_e32 v131, v123, v122
	v_min_u32_e32 v122, v123, v122
	v_max_u32_e32 v123, v134, v2
	v_min_u32_e32 v2, v134, v2
	v_max_u32_e32 v134, v0, v1
	v_min_u32_e32 v0, v0, v1
	v_max_u32_e32 v1, v133, v125
	v_min_u32_e32 v125, v133, v125
	v_max_u32_e32 v133, v135, v132
	v_min_u32_e32 v132, v135, v132
	v_max_u32_e32 v127, v117, v130
	v_min_u32_e32 v117, v117, v130
	v_max_u32_e32 v130, v128, v129
	v_min_u32_e32 v128, v128, v129
	v_max_u32_e32 v129, v139, v118
	v_min_u32_e32 v118, v139, v118
	v_max_u32_e32 v139, v111, v110
	v_min_u32_e32 v110, v111, v110
	v_max_u32_e32 v111, v114, v116
	v_min_u32_e32 v114, v114, v116
	v_max_u32_e32 v116, v126, v112
	v_min_u32_e32 v112, v126, v112
	v_max_u32_e32 v126, v121, v119
	v_min_u32_e32 v119, v121, v119
	v_max_u32_e32 v121, v120, v115
	v_min_u32_e32 v115, v120, v115
	v_max_u32_e32 v135, v3, v138
	v_min_u32_e32 v3, v3, v138
	v_max_u32_e32 v138, v136, v137
	v_min_u32_e32 v136, v136, v137
	v_max_u32_e32 v137, v147, v131
	v_min_u32_e32 v131, v147, v131
	v_max_u32_e32 v147, v124, v122
	v_min_u32_e32 v122, v124, v122
	v_max_u32_e32 v124, v0, v2
	v_min_u32_e32 v0, v0, v2
	v_max_u32_e32 v2, v134, v123
	v_min_u32_e32 v123, v134, v123
	v_max_u32_e32 v134, v132, v125
	v_min_u32_e32 v125, v132, v125
	v_max_u32_e32 v132, v133, v1
	v_min_u32_e32 v1, v133, v1
	v_max_u32_e32 v120, v127, v114
	v_min_u32_e32 v114, v127, v114
	v_max_u32_e32 v127, v117, v111
	v_min_u32_e32 v111, v117, v111
	v_max_u32_e32 v117, v130, v112
	v_min_u32_e32 v112, v130, v112
	v_max_u32_e32 v130, v128, v116
	v_min_u32_e32 v116, v128, v116
	v_max_u32_e32 v128, v129, v119
	v_min_u32_e32 v119, v129, v119
	v_max_u32_e32 v129, v118, v126
	v_min_u32_e32 v118, v118, v126
	v_max_u32_e32 v126, v139, v115
	v_min_u32_e32 v115, v139, v115
	v_max_u32_e32 v139, v110, v121
	v_min_u32_e32 v110, v110, v121
	v_max_u32_e32 v133, v135, v0
	v_min_u32_e32 v0, v135, v0
; #define CE_DESC(a, b) do { const unsigned _mx = (a) > (b) ? (a) : (b), _mn = (a) > (b) ? (b) : (a); (a) = _mx; (b) = _mn; } while (0)
; __device__ __forceinline__ void merge16(unsigned (&a)[16], const unsigned (&b)[16]) {
; #pragma unroll
;     for (int i = 0; i < 16; ++i) a[i] = a[i] > b[15 - i] ? a[i] : b[15 - i];
; #pragma unroll
;     for (int stride = 8; stride > 0; stride >>= 1)
; #pragma unroll
;         for (int i = 0; i < 16; ++i) { const int j = i ^ stride; if (j > i) CE_DESC(a[i], a[j]); }
; }
; __device__ __forceinline__ void peer_tile(const Args& A, LAS unsigned char* lds, int tile) {
;     ...
;                 sort16_desc(k0); sort16_desc(k1); merge16(k0, k1);
; #pragma unroll
;                 for (int msk = 16; msk <= 32; msk <<= 1) {
; #pragma unroll
;                     for (int i = 0; i < 16; ++i) k1[i] = (unsigned)__shfl_xor((int)k0[i], msk);
;                     merge16(k0, k1); }
	v_max_u32_e32 v135, v3, v124
	v_min_u32_e32 v3, v3, v124
	v_max_u32_e32 v124, v138, v123
	v_min_u32_e32 v123, v138, v123
	v_max_u32_e32 v138, v136, v2
	v_min_u32_e32 v2, v136, v2
	v_max_u32_e32 v136, v137, v125
	v_min_u32_e32 v125, v137, v125
	v_max_u32_e32 v137, v131, v134
	v_min_u32_e32 v131, v131, v134
	v_max_u32_e32 v134, v147, v1
	v_min_u32_e32 v1, v147, v1
	v_max_u32_e32 v147, v122, v132
	v_min_u32_e32 v122, v122, v132
	v_max_u32_e32 v121, v120, v128
	v_min_u32_e32 v120, v120, v128
	v_max_u32_e32 v128, v127, v129
	v_min_u32_e32 v127, v127, v129
	v_max_u32_e32 v129, v117, v126
	v_min_u32_e32 v117, v117, v126
	v_max_u32_e32 v126, v130, v139
	v_min_u32_e32 v130, v130, v139
	v_max_u32_e32 v139, v114, v119
	v_min_u32_e32 v114, v114, v119
	v_max_u32_e32 v119, v111, v118
	v_min_u32_e32 v111, v111, v118
	v_max_u32_e32 v118, v112, v115
	v_min_u32_e32 v112, v112, v115
	v_max_u32_e32 v115, v116, v110
	v_min_u32_e32 v110, v116, v110
	v_max_u32_e32 v132, v133, v136
	v_min_u32_e32 v133, v133, v136
	v_max_u32_e32 v136, v135, v137
	v_min_u32_e32 v135, v135, v137
	v_max_u32_e32 v137, v124, v134
	v_min_u32_e32 v124, v124, v134
	v_max_u32_e32 v134, v138, v147
	v_min_u32_e32 v138, v138, v147
	v_max_u32_e32 v147, v0, v125
	v_min_u32_e32 v0, v0, v125
	v_max_u32_e32 v125, v3, v131
	v_min_u32_e32 v3, v3, v131
	v_max_u32_e32 v131, v123, v1
	v_min_u32_e32 v1, v123, v1
	v_max_u32_e32 v123, v2, v122
	v_min_u32_e32 v2, v2, v122
	v_max_u32_e32 v116, v121, v129
	v_min_u32_e32 v121, v121, v129
	v_max_u32_e32 v129, v128, v126
	v_min_u32_e32 v126, v128, v126
	v_max_u32_e32 v128, v120, v117
	v_min_u32_e32 v117, v120, v117
	v_max_u32_e32 v120, v127, v130
	v_min_u32_e32 v127, v127, v130
	v_max_u32_e32 v130, v139, v118
	v_min_u32_e32 v118, v139, v118
	v_max_u32_e32 v139, v119, v115
	v_min_u32_e32 v115, v119, v115
	v_max_u32_e32 v119, v114, v112
	v_min_u32_e32 v112, v114, v112
	v_max_u32_e32 v114, v111, v110
	v_min_u32_e32 v110, v111, v110
	v_max_u32_e32 v122, v132, v137
	v_min_u32_e32 v132, v132, v137
	v_max_u32_e32 v137, v136, v134
	v_min_u32_e32 v134, v136, v134
	v_max_u32_e32 v136, v133, v124
	v_min_u32_e32 v124, v133, v124
	v_max_u32_e32 v133, v135, v138
	v_min_u32_e32 v135, v135, v138
	v_max_u32_e32 v138, v147, v131
	v_min_u32_e32 v131, v147, v131
	v_max_u32_e32 v147, v125, v123
	v_min_u32_e32 v123, v125, v123
	v_max_u32_e32 v125, v0, v1
	v_min_u32_e32 v0, v0, v1
	v_max_u32_e32 v1, v3, v2
	v_min_u32_e32 v2, v3, v2
	v_min_u32_e32 v111, v116, v129
	v_min_u32_e32 v140, v121, v126
	v_min_u32_e32 v141, v128, v120
	v_min_u32_e32 v142, v117, v127
	v_min_u32_e32 v143, v130, v139
	v_min_u32_e32 v144, v118, v115
	v_min_u32_e32 v145, v119, v114
	v_min_u32_e32 v146, v112, v110
	v_min_u32_e32 v3, v122, v137
	v_min_u32_e32 v148, v132, v134
	v_min_u32_e32 v149, v136, v133
	v_min_u32_e32 v150, v124, v135
	v_min_u32_e32 v151, v138, v147
	v_min_u32_e32 v152, v131, v123
	v_min_u32_e32 v153, v125, v1
	v_min_u32_e32 v154, v0, v2
	v_max3_u32 v116, v116, v129, v154
	v_max3_u32 v0, v111, v0, v2
	v_max3_u32 v2, v121, v126, v153
	v_max3_u32 v1, v140, v125, v1
	v_max3_u32 v111, v128, v120, v152
	v_max3_u32 v120, v141, v131, v123
	v_max3_u32 v117, v117, v127, v151
	v_max3_u32 v121, v142, v138, v147
	v_max3_u32 v123, v130, v139, v150
	v_max3_u32 v124, v143, v124, v135
	v_max3_u32 v115, v118, v115, v149
	v_max3_u32 v118, v144, v136, v133
	v_max3_u32 v114, v119, v114, v148
	v_max3_u32 v119, v145, v132, v134
	v_max3_u32 v3, v112, v110, v3
	v_max3_u32 v110, v146, v122, v137
	v_max_u32_e32 v112, v116, v123
	v_min_u32_e32 v116, v116, v123
	v_max_u32_e32 v122, v0, v124
	v_min_u32_e32 v0, v0, v124
	v_max_u32_e32 v123, v2, v115
	v_min_u32_e32 v2, v2, v115
	v_max_u32_e32 v115, v1, v118
	v_min_u32_e32 v1, v1, v118
	v_max_u32_e32 v118, v111, v114
	v_min_u32_e32 v111, v111, v114
	v_max_u32_e32 v114, v120, v119
	v_min_u32_e32 v119, v120, v119
	v_max_u32_e32 v120, v117, v3
	v_min_u32_e32 v3, v117, v3
	v_max_u32_e32 v117, v121, v110
	v_min_u32_e32 v110, v121, v110
	v_max_u32_e32 v121, v112, v118
	v_min_u32_e32 v112, v112, v118
	v_max_u32_e32 v118, v122, v114
	v_min_u32_e32 v114, v122, v114
	v_max_u32_e32 v122, v123, v120
	v_min_u32_e32 v120, v123, v120
	v_max_u32_e32 v123, v115, v117
	v_min_u32_e32 v115, v115, v117
	v_max_u32_e32 v117, v116, v111
	v_min_u32_e32 v111, v116, v111
	v_max_u32_e32 v116, v0, v119
	v_min_u32_e32 v0, v0, v119
	v_max_u32_e32 v119, v2, v3
	v_min_u32_e32 v2, v2, v3
	v_max_u32_e32 v3, v1, v110
	v_min_u32_e32 v1, v1, v110
	v_max_u32_e32 v110, v121, v122
	v_min_u32_e32 v121, v121, v122
	v_max_u32_e32 v122, v118, v123
	v_min_u32_e32 v118, v118, v123
	v_max_u32_e32 v123, v112, v120
	v_min_u32_e32 v112, v112, v120
	v_max_u32_e32 v120, v114, v115
	v_min_u32_e32 v114, v114, v115
	v_max_u32_e32 v115, v117, v119
	v_min_u32_e32 v117, v117, v119
	v_max_u32_e32 v119, v116, v3
	v_min_u32_e32 v3, v116, v3
	v_max_u32_e32 v116, v111, v2
	v_min_u32_e32 v2, v111, v2
	v_max_u32_e32 v111, v0, v1
	v_min_u32_e32 v0, v0, v1
	v_max_u32_e32 v1, v110, v122
	v_min_u32_e32 v110, v110, v122
	v_max_u32_e32 v122, v121, v118
	v_min_u32_e32 v118, v121, v118
	v_max_u32_e32 v121, v123, v120
	v_min_u32_e32 v120, v123, v120
	v_max_u32_e32 v123, v112, v114
	v_min_u32_e32 v112, v112, v114
	v_max_u32_e32 v114, v115, v119
	v_min_u32_e32 v115, v115, v119
	v_max_u32_e32 v119, v117, v3
	v_min_u32_e32 v3, v117, v3
	v_max_u32_e32 v117, v116, v111
	v_min_u32_e32 v111, v116, v111
	v_max_u32_e32 v116, v2, v0
	v_min_u32_e32 v0, v2, v0
	ds_bpermute_b32 v2, v27, v1
	ds_bpermute_b32 v124, v27, v110
	ds_bpermute_b32 v125, v27, v122
	ds_bpermute_b32 v126, v27, v118
	ds_bpermute_b32 v127, v27, v121
	ds_bpermute_b32 v128, v27, v120
	ds_bpermute_b32 v129, v27, v123
	ds_bpermute_b32 v130, v27, v112
	ds_bpermute_b32 v131, v27, v114
	ds_bpermute_b32 v132, v27, v115
	ds_bpermute_b32 v133, v27, v119
	ds_bpermute_b32 v134, v27, v0
	ds_bpermute_b32 v135, v27, v116
	ds_bpermute_b32 v136, v27, v111
	ds_bpermute_b32 v137, v27, v117
	ds_bpermute_b32 v138, v27, v3
	s_waitcnt lgkmcnt(4)
; __device__ __forceinline__ void peer_tile(const Args& A, LAS unsigned char* lds, int tile) {
;     ...
;                 { const bf16_t* sp = QRY + m * 2048 + hp * 128 + 32 * g;
;                   const u32x4 s0 = *(const u32x4*)sp, s1 = *(const u32x4*)(sp + 8), s2 = *(const u32x4*)(sp + 16), s3 = *(const u32x4*)(sp + 24);
;     ...
;                 for (int msk = 16; msk <= 32; msk <<= 1) {
; #pragma unroll
;                     for (int i = 0; i < 16; ++i) k1[i] = (unsigned)__shfl_xor((int)k0[i], msk);
;                     merge16(k0, k1); }
	v_max_u32_e32 v1, v1, v134
	s_waitcnt lgkmcnt(3)
	v_max_u32_e32 v110, v110, v135
	s_waitcnt lgkmcnt(2)
	v_max_u32_e32 v122, v122, v136
	s_waitcnt lgkmcnt(1)
	v_max_u32_e32 v118, v118, v137
	s_waitcnt lgkmcnt(0)
	v_max_u32_e32 v121, v121, v138
	v_max_u32_e32 v120, v120, v133
	v_max_u32_e32 v123, v123, v132
	v_max_u32_e32 v112, v112, v131
	v_max_u32_e32 v114, v114, v130
	v_max_u32_e32 v115, v115, v129
	v_max_u32_e32 v119, v119, v128
	v_max_u32_e32 v3, v3, v127
	v_max_u32_e32 v117, v117, v126
	v_max_u32_e32 v111, v111, v125
	v_max_u32_e32 v116, v116, v124
	v_max_u32_e32 v0, v0, v2
	v_max_u32_e32 v2, v1, v114
	v_min_u32_e32 v1, v1, v114
	v_max_u32_e32 v114, v110, v115
	v_min_u32_e32 v110, v110, v115
	v_max_u32_e32 v115, v122, v119
	v_min_u32_e32 v119, v122, v119
	v_max_u32_e32 v122, v118, v3
	v_min_u32_e32 v3, v118, v3
	v_max_u32_e32 v118, v121, v117
	v_min_u32_e32 v117, v121, v117
	v_max_u32_e32 v121, v120, v111
	v_min_u32_e32 v111, v120, v111
	v_max_u32_e32 v120, v123, v116
	v_min_u32_e32 v116, v123, v116
	v_max_u32_e32 v123, v112, v0
	v_min_u32_e32 v0, v112, v0
	v_max_u32_e32 v112, v2, v118
	v_min_u32_e32 v2, v2, v118
	v_max_u32_e32 v118, v114, v121
	v_min_u32_e32 v114, v114, v121
	v_max_u32_e32 v121, v115, v120
	v_min_u32_e32 v115, v115, v120
	v_max_u32_e32 v120, v122, v123
	v_min_u32_e32 v122, v122, v123
	v_max_u32_e32 v123, v1, v117
	v_min_u32_e32 v1, v1, v117
	v_max_u32_e32 v117, v110, v111
	v_min_u32_e32 v110, v110, v111
	v_max_u32_e32 v111, v119, v116
	v_min_u32_e32 v116, v119, v116
	v_max_u32_e32 v119, v3, v0
	v_min_u32_e32 v0, v3, v0
	v_max_u32_e32 v3, v112, v121
	v_min_u32_e32 v112, v112, v121
	v_max_u32_e32 v121, v118, v120
	v_min_u32_e32 v118, v118, v120
	v_max_u32_e32 v120, v2, v115
	v_min_u32_e32 v2, v2, v115
	v_max_u32_e32 v115, v114, v122
	v_min_u32_e32 v114, v114, v122
	v_max_u32_e32 v122, v123, v111
	v_min_u32_e32 v111, v123, v111
	v_max_u32_e32 v123, v117, v119
	v_min_u32_e32 v117, v117, v119
	v_max_u32_e32 v119, v1, v116
	v_min_u32_e32 v1, v1, v116
	v_max_u32_e32 v116, v110, v0
	v_min_u32_e32 v0, v110, v0
	v_max_u32_e32 v110, v3, v121
	v_min_u32_e32 v3, v3, v121
	v_max_u32_e32 v121, v112, v118
	v_min_u32_e32 v112, v112, v118
	v_max_u32_e32 v118, v120, v115
	v_min_u32_e32 v115, v120, v115
	v_max_u32_e32 v120, v2, v114
	v_min_u32_e32 v2, v2, v114
	v_max_u32_e32 v114, v122, v123
	v_min_u32_e32 v122, v122, v123
	v_max_u32_e32 v123, v111, v117
	v_min_u32_e32 v111, v111, v117
	v_max_u32_e32 v117, v119, v116
	v_min_u32_e32 v116, v119, v116
	v_max_u32_e32 v119, v1, v0
	v_min_u32_e32 v0, v1, v0
	ds_bpermute_b32 v128, v29, v0
	ds_bpermute_b32 v1, v29, v110
	ds_bpermute_b32 v124, v29, v3
	ds_bpermute_b32 v125, v29, v121
	ds_bpermute_b32 v126, v29, v112
	s_waitcnt lgkmcnt(4)
	v_max_u32_e32 v110, v110, v128
	global_load_dwordx4 v[128:131], v[4:5], off offset:1552
	global_load_dwordx4 v[132:135], v[4:5], off offset:1536
	ds_bpermute_b32 v127, v29, v118
	ds_bpermute_b32 v136, v29, v115
	ds_bpermute_b32 v137, v29, v120
	ds_bpermute_b32 v138, v29, v2
	ds_bpermute_b32 v139, v29, v114
	ds_bpermute_b32 v140, v29, v122
	ds_bpermute_b32 v141, v29, v123
	ds_bpermute_b32 v142, v29, v111
	ds_bpermute_b32 v143, v29, v117
	ds_bpermute_b32 v144, v29, v119
	ds_bpermute_b32 v145, v29, v116
	s_waitcnt lgkmcnt(4)
	v_max_u32_e32 v115, v115, v141
	s_waitcnt lgkmcnt(3)
	v_max_u32_e32 v118, v118, v142
	s_waitcnt lgkmcnt(2)
	v_max_u32_e32 v112, v112, v143
	s_waitcnt lgkmcnt(1)
	v_max_u32_e32 v3, v3, v144
	s_waitcnt lgkmcnt(0)
	v_max_u32_e32 v121, v121, v145
	v_max_u32_e32 v120, v120, v140
	v_max_u32_e32 v2, v2, v139
	v_max_u32_e32 v114, v114, v138
	v_max_u32_e32 v122, v122, v137
	v_max_u32_e32 v123, v123, v136
	v_max_u32_e32 v111, v111, v127
	v_max_u32_e32 v117, v117, v126
	v_max_u32_e32 v116, v116, v125
	v_max_u32_e32 v119, v119, v124
	v_max_u32_e32 v0, v0, v1
	v_max_u32_e32 v1, v110, v114
	v_min_u32_e32 v110, v110, v114
	v_max_u32_e32 v114, v3, v122
	v_min_u32_e32 v3, v3, v122
	v_max_u32_e32 v122, v121, v123
	v_min_u32_e32 v121, v121, v123
	v_max_u32_e32 v123, v112, v111
	v_min_u32_e32 v111, v112, v111
	v_max_u32_e32 v112, v118, v117
	v_min_u32_e32 v117, v118, v117
	v_max_u32_e32 v118, v115, v116
	v_min_u32_e32 v115, v115, v116
	v_max_u32_e32 v116, v120, v119
	v_min_u32_e32 v119, v120, v119
	v_max_u32_e32 v120, v2, v0
	v_min_u32_e32 v0, v2, v0
	v_max_u32_e32 v2, v1, v112
	v_min_u32_e32 v1, v1, v112
	v_max_u32_e32 v112, v114, v118
	v_min_u32_e32 v114, v114, v118
	v_max_u32_e32 v118, v122, v116
	v_min_u32_e32 v116, v122, v116
	v_max_u32_e32 v122, v123, v120
	v_min_u32_e32 v120, v123, v120
	v_max_u32_e32 v123, v110, v117
	v_min_u32_e32 v110, v110, v117
	v_max_u32_e32 v117, v3, v115
	v_min_u32_e32 v3, v3, v115
	v_max_u32_e32 v115, v121, v119
	v_min_u32_e32 v119, v121, v119
	v_max_u32_e32 v121, v111, v0
	v_min_u32_e32 v0, v111, v0
	v_max_u32_e32 v111, v2, v118
	v_min_u32_e32 v2, v2, v118
	v_max_u32_e32 v118, v112, v122
	v_min_u32_e32 v112, v112, v122
	v_max_u32_e32 v127, v1, v116
	v_min_u32_e32 v1, v1, v116
	v_max_u32_e32 v116, v114, v120
	v_min_u32_e32 v114, v114, v120
	v_max_u32_e32 v136, v123, v115
	v_min_u32_e32 v115, v123, v115
	v_max_u32_e32 v137, v117, v121
	v_min_u32_e32 v138, v117, v121
	v_max_u32_e32 v139, v110, v119
	v_min_u32_e32 v110, v110, v119
	v_max_u32_e32 v140, v3, v0
	v_min_u32_e32 v0, v3, v0
	v_max_u32_e32 v126, v111, v118
	v_min_u32_e32 v125, v111, v118
	v_max_u32_e32 v124, v2, v112
	v_min_u32_e32 v123, v2, v112
	v_max_u32_e32 v122, v127, v116
	v_min_u32_e32 v121, v127, v116
	v_max_u32_e32 v120, v1, v114
	v_min_u32_e32 v119, v1, v114
	v_max_u32_e32 v118, v136, v137
	v_min_u32_e32 v117, v136, v137
	v_max_u32_e32 v116, v115, v138
	v_min_u32_e32 v115, v115, v138
	v_max_u32_e32 v114, v139, v140
	v_min_u32_e32 v112, v139, v140
	v_max_u32_e32 v111, v110, v0
	v_min_u32_e32 v110, v110, v0
	global_load_dwordx4 v[0:3], v[4:5], off offset:1584
	global_load_dwordx4 v[136:139], v[4:5], off offset:1568
	s_waitcnt vmcnt(2)
; __device__ __forceinline__ unsigned f2key(float f) { const unsigned u = __float_as_uint(f); return (u & 0x80000000u) ? ~u : (u | 0x80000000u); }
; __device__ __forceinline__ void peer_tile(const Args& A, LAS unsigned char* lds, int tile) {
;     ...
;                   for (int i = 0; i < 16; ++i) {
;                       const float lo = (float)__builtin_bit_cast(_Float16, (unsigned short)(sw[i] & 0xffffu)), hi = (float)__builtin_bit_cast(_Float16, (unsigned short)(sw[i] >> 16));
;                       const unsigned klo = (f2key(lo) & ~127u) | (unsigned)(127 - (32 * g + 2 * i)), khi = (f2key(hi) & ~127u) | (unsigned)(127 - (32 * g + 2 * i + 1));
;                       if (i < 8) { k0[2 * i] = klo; k0[2 * i + 1] = khi; } else { k1[2 * (i - 8)] = klo; k1[2 * (i - 8) + 1] = khi; } } }
	v_cvt_f32_f16_sdwa v127, v132 dst_sel:DWORD dst_unused:UNUSED_PAD src0_sel:WORD_1
	v_cvt_f32_f16_e32 v132, v132
	v_not_b32_e32 v140, v127
	v_or_b32_e32 v141, 0x80000000, v127
	v_cmp_gt_i32_e32 vcc, 0, v127
	s_nop 1
	v_cndmask_b32_e32 v127, v141, v140, vcc
	v_not_b32_e32 v140, v132
	v_or_b32_e32 v141, 0x80000000, v132
	v_cmp_gt_i32_e32 vcc, 0, v132
	v_and_b32_e32 v127, 0xffffff80, v127
	v_sub_u32_e32 v127, v127, v15
	v_cndmask_b32_e32 v132, v141, v140, vcc
	v_cvt_f32_f16_sdwa v140, v133 dst_sel:DWORD dst_unused:UNUSED_PAD src0_sel:WORD_1
	v_cvt_f32_f16_e32 v133, v133
	v_and_b32_e32 v132, 0xffffff80, v132
	v_sub_u32_e32 v132, v132, v15
	v_not_b32_e32 v141, v140
	v_or_b32_e32 v142, 0x80000000, v140
	v_cmp_gt_i32_e32 vcc, 0, v140
	v_add_u32_e32 v127, 0x7e, v127
	v_add_u32_e32 v132, 0x7f, v132
	v_cndmask_b32_e32 v140, v142, v141, vcc
	v_not_b32_e32 v141, v133
	v_or_b32_e32 v142, 0x80000000, v133
	v_cmp_gt_i32_e32 vcc, 0, v133
	v_and_b32_e32 v140, 0xffffff80, v140
	v_sub_u32_e32 v140, v140, v14
	v_cndmask_b32_e32 v133, v142, v141, vcc
	v_cvt_f32_f16_sdwa v141, v134 dst_sel:DWORD dst_unused:UNUSED_PAD src0_sel:WORD_1
	v_cvt_f32_f16_e32 v134, v134
	v_and_b32_e32 v133, 0xffffff80, v133
	v_sub_u32_e32 v133, v133, v14
	v_not_b32_e32 v142, v141
	v_or_b32_e32 v143, 0x80000000, v141
	v_cmp_gt_i32_e32 vcc, 0, v141
	v_add_u32_e32 v140, 0x7e, v140
	v_add_u32_e32 v133, 0x7f, v133
	v_cndmask_b32_e32 v141, v143, v142, vcc
	v_not_b32_e32 v142, v134
	v_or_b32_e32 v143, 0x80000000, v134
	v_cmp_gt_i32_e32 vcc, 0, v134
	v_and_b32_e32 v141, 0xffffff80, v141
	v_sub_u32_e32 v141, v141, v12
	v_cndmask_b32_e32 v134, v143, v142, vcc
	v_cvt_f32_f16_sdwa v142, v135 dst_sel:DWORD dst_unused:UNUSED_PAD src0_sel:WORD_1
	v_cvt_f32_f16_e32 v135, v135
	v_and_b32_e32 v134, 0xffffff80, v134
	v_sub_u32_e32 v134, v134, v12
	v_not_b32_e32 v143, v142
	v_or_b32_e32 v144, 0x80000000, v142
	v_cmp_gt_i32_e32 vcc, 0, v142
	v_add_u32_e32 v141, 0x7e, v141
	v_add_u32_e32 v134, 0x7f, v134
	v_cndmask_b32_e32 v142, v144, v143, vcc
	v_not_b32_e32 v143, v135
	v_or_b32_e32 v144, 0x80000000, v135
	v_cmp_gt_i32_e32 vcc, 0, v135
	v_and_b32_e32 v142, 0xffffff80, v142
	v_sub_u32_e32 v142, v142, v10
	v_cndmask_b32_e32 v135, v144, v143, vcc
	v_cvt_f32_f16_sdwa v143, v128 dst_sel:DWORD dst_unused:UNUSED_PAD src0_sel:WORD_1
	v_cvt_f32_f16_e32 v128, v128
	v_and_b32_e32 v135, 0xffffff80, v135
	v_sub_u32_e32 v135, v135, v10
	v_not_b32_e32 v144, v143
	v_or_b32_e32 v145, 0x80000000, v143
	v_cmp_gt_i32_e32 vcc, 0, v143
	v_add_u32_e32 v142, 0x7e, v142
	v_add_u32_e32 v135, 0x7f, v135
	v_cndmask_b32_e32 v143, v145, v144, vcc
	v_not_b32_e32 v144, v128
	v_or_b32_e32 v145, 0x80000000, v128
	v_cmp_gt_i32_e32 vcc, 0, v128
	v_and_b32_e32 v143, 0xffffff80, v143
	v_sub_u32_e32 v143, v143, v8
	v_cndmask_b32_e32 v128, v145, v144, vcc
	v_cvt_f32_f16_sdwa v144, v129 dst_sel:DWORD dst_unused:UNUSED_PAD src0_sel:WORD_1
	v_cvt_f32_f16_e32 v129, v129
	v_and_b32_e32 v128, 0xffffff80, v128
	v_sub_u32_e32 v128, v128, v8
	v_not_b32_e32 v145, v144
	v_or_b32_e32 v146, 0x80000000, v144
	v_cmp_gt_i32_e32 vcc, 0, v144
	v_add_u32_e32 v143, 0x7e, v143
	v_add_u32_e32 v128, 0x7f, v128
	v_cndmask_b32_e32 v144, v146, v145, vcc
	v_not_b32_e32 v145, v129
	v_or_b32_e32 v146, 0x80000000, v129
	v_cmp_gt_i32_e32 vcc, 0, v129
	v_and_b32_e32 v144, 0xffffff80, v144
	v_sub_u32_e32 v144, v144, v16
	v_cndmask_b32_e32 v129, v146, v145, vcc
	v_cvt_f32_f16_sdwa v145, v130 dst_sel:DWORD dst_unused:UNUSED_PAD src0_sel:WORD_1
	v_cvt_f32_f16_e32 v130, v130
	v_and_b32_e32 v129, 0xffffff80, v129
	v_sub_u32_e32 v129, v129, v16
	v_not_b32_e32 v146, v145
	v_or_b32_e32 v147, 0x80000000, v145
	v_cmp_gt_i32_e32 vcc, 0, v145
	v_add_u32_e32 v144, 0x7e, v144
	v_add_u32_e32 v129, 0x7f, v129
	v_cndmask_b32_e32 v145, v147, v146, vcc
	v_not_b32_e32 v146, v130
	v_or_b32_e32 v147, 0x80000000, v130
	v_cmp_gt_i32_e32 vcc, 0, v130
	v_and_b32_e32 v145, 0xffffff80, v145
	v_sub_u32_e32 v145, v145, v17
	v_cndmask_b32_e32 v130, v147, v146, vcc
	v_cvt_f32_f16_sdwa v146, v131 dst_sel:DWORD dst_unused:UNUSED_PAD src0_sel:WORD_1
	v_cvt_f32_f16_e32 v131, v131
	v_and_b32_e32 v130, 0xffffff80, v130
	v_sub_u32_e32 v130, v130, v17
	v_not_b32_e32 v147, v146
	v_or_b32_e32 v148, 0x80000000, v146
	v_cmp_gt_i32_e32 vcc, 0, v146
	v_add_u32_e32 v145, 0x7e, v145
	v_add_u32_e32 v130, 0x7f, v130
	v_cndmask_b32_e32 v146, v148, v147, vcc
	v_not_b32_e32 v147, v131
	v_or_b32_e32 v148, 0x80000000, v131
	v_cmp_gt_i32_e32 vcc, 0, v131
	v_and_b32_e32 v146, 0xffffff80, v146
	v_sub_u32_e32 v146, v146, v18
	v_cndmask_b32_e32 v131, v148, v147, vcc
	s_waitcnt vmcnt(0)
; __device__ __forceinline__ unsigned f2key(float f) { const unsigned u = __float_as_uint(f); return (u & 0x80000000u) ? ~u : (u | 0x80000000u); }
; #define CE_DESC(a, b) do { const unsigned _mx = (a) > (b) ? (a) : (b), _mn = (a) > (b) ? (b) : (a); (a) = _mx; (b) = _mn; } while (0)
; __device__ __forceinline__ void sort16_desc(unsigned (&k)[16]) {
; #pragma unroll
;     for (int size = 2; size <= 16; size <<= 1)
; #pragma unroll
;         for (int stride = size >> 1; stride > 0; stride >>= 1)
; #pragma unroll
;             for (int i = 0; i < 16; ++i) { const int j = i ^ stride;
;                 if (j > i) { if ((i & size) == 0) CE_DESC(k[i], k[j]); else CE_DESC(k[j], k[i]); } }
; }
; __device__ __forceinline__ void peer_tile(const Args& A, LAS unsigned char* lds, int tile) {
;     ...
;                   for (int i = 0; i < 16; ++i) {
;                       const float lo = (float)__builtin_bit_cast(_Float16, (unsigned short)(sw[i] & 0xffffu)), hi = (float)__builtin_bit_cast(_Float16, (unsigned short)(sw[i] >> 16));
;                       const unsigned klo = (f2key(lo) & ~127u) | (unsigned)(127 - (32 * g + 2 * i)), khi = (f2key(hi) & ~127u) | (unsigned)(127 - (32 * g + 2 * i + 1));
;                       if (i < 8) { k0[2 * i] = klo; k0[2 * i + 1] = khi; } else { k1[2 * (i - 8)] = klo; k1[2 * (i - 8) + 1] = khi; } } }
;                 sort16_desc(k0); sort16_desc(k1); merge16(k0, k1);
	v_cvt_f32_f16_sdwa v147, v136 dst_sel:DWORD dst_unused:UNUSED_PAD src0_sel:WORD_1
	v_cvt_f32_f16_e32 v136, v136
	v_and_b32_e32 v131, 0xffffff80, v131
	v_sub_u32_e32 v131, v131, v18
	v_not_b32_e32 v148, v147
	v_or_b32_e32 v149, 0x80000000, v147
	v_cmp_gt_i32_e32 vcc, 0, v147
	v_add_u32_e32 v146, 0x7e, v146
	v_add_u32_e32 v131, 0x7f, v131
	v_cndmask_b32_e32 v147, v149, v148, vcc
	v_not_b32_e32 v148, v136
	v_or_b32_e32 v149, 0x80000000, v136
	v_cmp_gt_i32_e32 vcc, 0, v136
	v_and_b32_e32 v147, 0xffffff80, v147
	v_sub_u32_e32 v147, v147, v20
	v_cndmask_b32_e32 v136, v149, v148, vcc
	v_cvt_f32_f16_sdwa v148, v137 dst_sel:DWORD dst_unused:UNUSED_PAD src0_sel:WORD_1
	v_cvt_f32_f16_e32 v137, v137
	v_and_b32_e32 v136, 0xffffff80, v136
	v_sub_u32_e32 v136, v136, v20
	v_not_b32_e32 v149, v148
	v_or_b32_e32 v150, 0x80000000, v148
	v_cmp_gt_i32_e32 vcc, 0, v148
	v_add_u32_e32 v147, 0x7e, v147
	v_add_u32_e32 v136, 0x7f, v136
	v_cndmask_b32_e32 v148, v150, v149, vcc
	v_not_b32_e32 v149, v137
	v_or_b32_e32 v150, 0x80000000, v137
	v_cmp_gt_i32_e32 vcc, 0, v137
	v_and_b32_e32 v148, 0xffffff80, v148
	v_sub_u32_e32 v148, v148, v21
	v_cndmask_b32_e32 v137, v150, v149, vcc
	v_cvt_f32_f16_sdwa v149, v138 dst_sel:DWORD dst_unused:UNUSED_PAD src0_sel:WORD_1
	v_cvt_f32_f16_e32 v138, v138
	v_and_b32_e32 v137, 0xffffff80, v137
	v_sub_u32_e32 v137, v137, v21
	v_not_b32_e32 v150, v149
	v_or_b32_e32 v151, 0x80000000, v149
	v_cmp_gt_i32_e32 vcc, 0, v149
	v_add_u32_e32 v148, 0x7e, v148
	v_add_u32_e32 v137, 0x7f, v137
	v_cndmask_b32_e32 v149, v151, v150, vcc
	v_not_b32_e32 v150, v138
	v_or_b32_e32 v151, 0x80000000, v138
	v_cmp_gt_i32_e32 vcc, 0, v138
	v_and_b32_e32 v149, 0xffffff80, v149
	v_sub_u32_e32 v149, v149, v22
	v_cndmask_b32_e32 v138, v151, v150, vcc
	v_cvt_f32_f16_sdwa v150, v139 dst_sel:DWORD dst_unused:UNUSED_PAD src0_sel:WORD_1
	v_cvt_f32_f16_e32 v139, v139
	v_and_b32_e32 v138, 0xffffff80, v138
	v_sub_u32_e32 v138, v138, v22
	v_not_b32_e32 v151, v150
	v_or_b32_e32 v152, 0x80000000, v150
	v_cmp_gt_i32_e32 vcc, 0, v150
	v_add_u32_e32 v149, 0x7e, v149
	v_add_u32_e32 v138, 0x7f, v138
	v_cndmask_b32_e32 v150, v152, v151, vcc
	v_not_b32_e32 v151, v139
	v_or_b32_e32 v152, 0x80000000, v139
	v_cmp_gt_i32_e32 vcc, 0, v139
	v_and_b32_e32 v150, 0xffffff80, v150
	v_sub_u32_e32 v150, v150, v23
	v_cndmask_b32_e32 v139, v152, v151, vcc
	v_cvt_f32_f16_sdwa v151, v0 dst_sel:DWORD dst_unused:UNUSED_PAD src0_sel:WORD_1
	v_cvt_f32_f16_e32 v0, v0
	v_and_b32_e32 v139, 0xffffff80, v139
	v_sub_u32_e32 v139, v139, v23
	v_not_b32_e32 v152, v151
	v_or_b32_e32 v153, 0x80000000, v151
	v_cmp_gt_i32_e32 vcc, 0, v151
	v_add_u32_e32 v150, 0x7e, v150
	v_add_u32_e32 v139, 0x7f, v139
	v_cndmask_b32_e32 v151, v153, v152, vcc
	v_not_b32_e32 v152, v0
	v_or_b32_e32 v153, 0x80000000, v0
	v_cmp_gt_i32_e32 vcc, 0, v0
	v_and_b32_e32 v151, 0xffffff80, v151
	v_sub_u32_e32 v151, v151, v24
	v_cndmask_b32_e32 v0, v153, v152, vcc
	v_cvt_f32_f16_sdwa v152, v1 dst_sel:DWORD dst_unused:UNUSED_PAD src0_sel:WORD_1
	v_cvt_f32_f16_e32 v1, v1
	v_and_b32_e32 v0, 0xffffff80, v0
	v_sub_u32_e32 v0, v0, v24
	v_not_b32_e32 v153, v152
	v_or_b32_e32 v154, 0x80000000, v152
	v_cmp_gt_i32_e32 vcc, 0, v152
	v_add_u32_e32 v151, 0x7e, v151
	v_add_u32_e32 v0, 0x7f, v0
	v_cndmask_b32_e32 v152, v154, v153, vcc
	v_not_b32_e32 v153, v1
	v_or_b32_e32 v154, 0x80000000, v1
	v_cmp_gt_i32_e32 vcc, 0, v1
	v_and_b32_e32 v152, 0xffffff80, v152
	v_sub_u32_e32 v152, v152, v25
	v_cndmask_b32_e32 v1, v154, v153, vcc
	v_cvt_f32_f16_sdwa v153, v2 dst_sel:DWORD dst_unused:UNUSED_PAD src0_sel:WORD_1
	v_cvt_f32_f16_e32 v2, v2
	v_and_b32_e32 v1, 0xffffff80, v1
	v_sub_u32_e32 v1, v1, v25
	v_not_b32_e32 v154, v153
	v_or_b32_e32 v155, 0x80000000, v153
	v_cmp_gt_i32_e32 vcc, 0, v153
	v_add_u32_e32 v152, 0x7e, v152
	v_add_u32_e32 v1, 0x7f, v1
	v_cndmask_b32_e32 v153, v155, v154, vcc
	v_not_b32_e32 v154, v2
	v_or_b32_e32 v155, 0x80000000, v2
	v_cmp_gt_i32_e32 vcc, 0, v2
	v_and_b32_e32 v153, 0xffffff80, v153
	v_sub_u32_e32 v153, v153, v26
	v_cndmask_b32_e32 v2, v155, v154, vcc
	v_cvt_f32_f16_sdwa v154, v3 dst_sel:DWORD dst_unused:UNUSED_PAD src0_sel:WORD_1
	v_cvt_f32_f16_e32 v3, v3
	v_and_b32_e32 v2, 0xffffff80, v2
	v_sub_u32_e32 v2, v2, v26
	v_not_b32_e32 v155, v154
	v_or_b32_e32 v156, 0x80000000, v154
	v_cmp_gt_i32_e32 vcc, 0, v154
	v_add_u32_e32 v153, 0x7e, v153
	v_add_u32_e32 v2, 0x7f, v2
	v_cndmask_b32_e32 v154, v156, v155, vcc
	v_not_b32_e32 v155, v3
	v_or_b32_e32 v156, 0x80000000, v3
	v_cmp_gt_i32_e32 vcc, 0, v3
	v_and_b32_e32 v154, 0xffffff80, v154
	v_sub_u32_e32 v154, v154, v28
	v_cndmask_b32_e32 v3, v156, v155, vcc
	v_and_b32_e32 v3, 0xffffff80, v3
	v_sub_u32_e32 v3, v3, v28
	v_add_u32_e32 v154, 0x7e, v154
	v_add_u32_e32 v3, 0x7f, v3
	v_max_u32_e32 v155, v132, v127
	v_min_u32_e32 v127, v132, v127
	v_max_u32_e32 v132, v140, v133
	v_min_u32_e32 v133, v140, v133
	v_max_u32_e32 v140, v134, v141
	v_min_u32_e32 v134, v134, v141
	v_max_u32_e32 v141, v142, v135
	v_min_u32_e32 v135, v142, v135
	v_max_u32_e32 v142, v128, v143
	v_min_u32_e32 v128, v128, v143
	v_max_u32_e32 v143, v144, v129
	v_min_u32_e32 v129, v144, v129
	v_max_u32_e32 v144, v130, v145
	v_min_u32_e32 v130, v130, v145
	v_max_u32_e32 v145, v146, v131
	v_min_u32_e32 v131, v146, v131
	v_max_u32_e32 v163, v136, v147
	v_min_u32_e32 v136, v136, v147
	v_max_u32_e32 v147, v148, v137
	v_min_u32_e32 v137, v148, v137
	v_max_u32_e32 v148, v138, v149
	v_min_u32_e32 v138, v138, v149
	v_max_u32_e32 v149, v150, v139
	v_min_u32_e32 v139, v150, v139
	v_max_u32_e32 v150, v0, v151
	v_min_u32_e32 v0, v0, v151
	v_max_u32_e32 v151, v152, v1
	v_min_u32_e32 v1, v152, v1
	v_max_u32_e32 v152, v2, v153
	v_min_u32_e32 v2, v2, v153
; #define CE_DESC(a, b) do { const unsigned _mx = (a) > (b) ? (a) : (b), _mn = (a) > (b) ? (b) : (a); (a) = _mx; (b) = _mn; } while (0)
; __device__ __forceinline__ void sort16_desc(unsigned (&k)[16]) {
; #pragma unroll
;     for (int size = 2; size <= 16; size <<= 1)
; #pragma unroll
;         for (int stride = size >> 1; stride > 0; stride >>= 1)
; #pragma unroll
;             for (int i = 0; i < 16; ++i) { const int j = i ^ stride;
;                 if (j > i) { if ((i & size) == 0) CE_DESC(k[i], k[j]); else CE_DESC(k[j], k[i]); } }
; }
	v_max_u32_e32 v153, v154, v3
	v_min_u32_e32 v3, v154, v3
	v_max_u32_e32 v146, v155, v133
	v_min_u32_e32 v133, v155, v133
	v_max_u32_e32 v155, v127, v132
	v_min_u32_e32 v127, v127, v132
	v_max_u32_e32 v132, v135, v140
	v_min_u32_e32 v135, v135, v140
	v_max_u32_e32 v140, v141, v134
	v_min_u32_e32 v134, v141, v134
	v_max_u32_e32 v141, v142, v129
	v_min_u32_e32 v129, v142, v129
	v_max_u32_e32 v142, v128, v143
	v_min_u32_e32 v128, v128, v143
	v_max_u32_e32 v143, v131, v144
	v_min_u32_e32 v131, v131, v144
	v_max_u32_e32 v144, v145, v130
	v_min_u32_e32 v130, v145, v130
	v_max_u32_e32 v154, v163, v137
	v_min_u32_e32 v137, v163, v137
	v_max_u32_e32 v163, v136, v147
	v_min_u32_e32 v136, v136, v147
	v_max_u32_e32 v147, v139, v148
	v_min_u32_e32 v139, v139, v148
	v_max_u32_e32 v148, v149, v138
	v_min_u32_e32 v138, v149, v138
	v_max_u32_e32 v149, v150, v1
	v_min_u32_e32 v1, v150, v1
	v_max_u32_e32 v150, v0, v151
	v_min_u32_e32 v0, v0, v151
	v_max_u32_e32 v151, v3, v152
	v_min_u32_e32 v3, v3, v152
	v_max_u32_e32 v152, v153, v2
	v_min_u32_e32 v2, v153, v2
	v_max_u32_e32 v145, v146, v155
	v_min_u32_e32 v146, v146, v155
	v_max_u32_e32 v155, v133, v127
	v_min_u32_e32 v127, v133, v127
	v_max_u32_e32 v133, v134, v135
	v_min_u32_e32 v134, v134, v135
	v_max_u32_e32 v135, v140, v132
	v_min_u32_e32 v132, v140, v132
	v_max_u32_e32 v140, v141, v142
	v_min_u32_e32 v141, v141, v142
	v_max_u32_e32 v142, v129, v128
	v_min_u32_e32 v128, v129, v128
	v_max_u32_e32 v129, v130, v131
	v_min_u32_e32 v130, v130, v131
	v_max_u32_e32 v131, v144, v143
	v_min_u32_e32 v143, v144, v143
	v_max_u32_e32 v153, v154, v163
	v_min_u32_e32 v154, v154, v163
	v_max_u32_e32 v163, v137, v136
	v_min_u32_e32 v136, v137, v136
	v_max_u32_e32 v137, v138, v139
	v_min_u32_e32 v138, v138, v139
	v_max_u32_e32 v139, v148, v147
	v_min_u32_e32 v147, v148, v147
	v_max_u32_e32 v148, v149, v150
	v_min_u32_e32 v149, v149, v150
	v_max_u32_e32 v150, v1, v0
	v_min_u32_e32 v0, v1, v0
	v_max_u32_e32 v1, v2, v3
	v_min_u32_e32 v2, v2, v3
	v_max_u32_e32 v3, v152, v151
	v_min_u32_e32 v151, v152, v151
	v_max_u32_e32 v144, v145, v134
	v_min_u32_e32 v134, v145, v134
	v_max_u32_e32 v145, v146, v133
	v_min_u32_e32 v133, v146, v133
	v_max_u32_e32 v146, v155, v132
	v_min_u32_e32 v132, v155, v132
	v_max_u32_e32 v155, v127, v135
	v_min_u32_e32 v127, v127, v135
	v_max_u32_e32 v135, v130, v140
	v_min_u32_e32 v130, v130, v140
	v_max_u32_e32 v140, v129, v141
	v_min_u32_e32 v129, v129, v141
	v_max_u32_e32 v141, v143, v142
	v_min_u32_e32 v142, v143, v142
	v_max_u32_e32 v143, v131, v128
	v_min_u32_e32 v128, v131, v128
	v_max_u32_e32 v152, v153, v138
	v_min_u32_e32 v138, v153, v138
	v_max_u32_e32 v153, v154, v137
	v_min_u32_e32 v137, v154, v137
	v_max_u32_e32 v154, v163, v147
	v_min_u32_e32 v147, v163, v147
	v_max_u32_e32 v163, v136, v139
	v_min_u32_e32 v136, v136, v139
	v_max_u32_e32 v139, v2, v148
	v_min_u32_e32 v2, v2, v148
	v_max_u32_e32 v148, v1, v149
	v_min_u32_e32 v1, v1, v149
	v_max_u32_e32 v149, v151, v150
	v_min_u32_e32 v150, v151, v150
	v_max_u32_e32 v151, v3, v0
	v_min_u32_e32 v0, v3, v0
	v_max_u32_e32 v131, v144, v146
	v_min_u32_e32 v144, v144, v146
	v_max_u32_e32 v146, v145, v155
	v_min_u32_e32 v145, v145, v155
	v_max_u32_e32 v155, v134, v132
	v_min_u32_e32 v132, v134, v132
	v_max_u32_e32 v134, v133, v127
	v_min_u32_e32 v127, v133, v127
	v_max_u32_e32 v133, v142, v130
	v_min_u32_e32 v130, v142, v130
	v_max_u32_e32 v142, v128, v129
	v_min_u32_e32 v128, v128, v129
	v_max_u32_e32 v129, v141, v135
	v_min_u32_e32 v135, v141, v135
	v_max_u32_e32 v141, v143, v140
	v_min_u32_e32 v140, v143, v140
	v_max_u32_e32 v3, v152, v154
	v_min_u32_e32 v152, v152, v154
	v_max_u32_e32 v154, v153, v163
	v_min_u32_e32 v153, v153, v163
	v_max_u32_e32 v163, v138, v147
	v_min_u32_e32 v138, v138, v147
	v_max_u32_e32 v147, v137, v136
	v_min_u32_e32 v136, v137, v136
	v_max_u32_e32 v137, v150, v2
	v_min_u32_e32 v2, v150, v2
	v_max_u32_e32 v150, v0, v1
	v_min_u32_e32 v0, v0, v1
	v_max_u32_e32 v1, v149, v139
	v_min_u32_e32 v139, v149, v139
	v_max_u32_e32 v149, v151, v148
	v_min_u32_e32 v148, v151, v148
	v_max_u32_e32 v143, v131, v146
	v_min_u32_e32 v131, v131, v146
	v_max_u32_e32 v146, v144, v145
	v_min_u32_e32 v144, v144, v145
	v_max_u32_e32 v145, v155, v134
	v_min_u32_e32 v134, v155, v134
	v_max_u32_e32 v155, v132, v127
	v_min_u32_e32 v127, v132, v127
	v_max_u32_e32 v132, v128, v130
	v_min_u32_e32 v128, v128, v130
	v_max_u32_e32 v130, v142, v133
	v_min_u32_e32 v133, v142, v133
	v_max_u32_e32 v142, v140, v135
	v_min_u32_e32 v135, v140, v135
	v_max_u32_e32 v140, v141, v129
	v_min_u32_e32 v129, v141, v129
	v_max_u32_e32 v151, v3, v154
	v_min_u32_e32 v3, v3, v154
	v_max_u32_e32 v154, v152, v153
	v_min_u32_e32 v152, v152, v153
	v_max_u32_e32 v153, v163, v147
	v_min_u32_e32 v147, v163, v147
	v_max_u32_e32 v163, v138, v136
	v_min_u32_e32 v136, v138, v136
	v_max_u32_e32 v138, v0, v2
	v_min_u32_e32 v0, v0, v2
	v_max_u32_e32 v2, v150, v137
	v_min_u32_e32 v137, v150, v137
	v_max_u32_e32 v150, v148, v139
	v_min_u32_e32 v139, v148, v139
	v_max_u32_e32 v148, v149, v1
	v_min_u32_e32 v1, v149, v1
	v_max_u32_e32 v141, v143, v128
	v_min_u32_e32 v128, v143, v128
	v_max_u32_e32 v143, v131, v132
	v_min_u32_e32 v131, v131, v132
	v_max_u32_e32 v132, v146, v133
	v_min_u32_e32 v133, v146, v133
	v_max_u32_e32 v146, v144, v130
	v_min_u32_e32 v130, v144, v130
	v_max_u32_e32 v144, v145, v135
	v_min_u32_e32 v135, v145, v135
	v_max_u32_e32 v145, v134, v142
	v_min_u32_e32 v134, v134, v142
	v_max_u32_e32 v142, v155, v129
	v_min_u32_e32 v129, v155, v129
	v_max_u32_e32 v155, v127, v140
	v_min_u32_e32 v127, v127, v140
	v_max_u32_e32 v149, v151, v0
	v_min_u32_e32 v0, v151, v0
; #define CE_DESC(a, b) do { const unsigned _mx = (a) > (b) ? (a) : (b), _mn = (a) > (b) ? (b) : (a); (a) = _mx; (b) = _mn; } while (0)
; __device__ __forceinline__ void merge16(unsigned (&a)[16], const unsigned (&b)[16]) {
; #pragma unroll
;     for (int i = 0; i < 16; ++i) a[i] = a[i] > b[15 - i] ? a[i] : b[15 - i];
; #pragma unroll
;     for (int stride = 8; stride > 0; stride >>= 1)
; #pragma unroll
;         for (int i = 0; i < 16; ++i) { const int j = i ^ stride; if (j > i) CE_DESC(a[i], a[j]); }
; }
; __device__ __forceinline__ void peer_tile(const Args& A, LAS unsigned char* lds, int tile) {
;     ...
;                 sort16_desc(k0); sort16_desc(k1); merge16(k0, k1);
; #pragma unroll
;                 for (int msk = 16; msk <= 32; msk <<= 1) {
; #pragma unroll
;                     for (int i = 0; i < 16; ++i) k1[i] = (unsigned)__shfl_xor((int)k0[i], msk);
;                     merge16(k0, k1); }
	v_max_u32_e32 v151, v3, v138
	v_min_u32_e32 v3, v3, v138
	v_max_u32_e32 v138, v154, v137
	v_min_u32_e32 v137, v154, v137
	v_max_u32_e32 v154, v152, v2
	v_min_u32_e32 v2, v152, v2
	v_max_u32_e32 v152, v153, v139
	v_min_u32_e32 v139, v153, v139
	v_max_u32_e32 v153, v147, v150
	v_min_u32_e32 v147, v147, v150
	v_max_u32_e32 v150, v163, v1
	v_min_u32_e32 v1, v163, v1
	v_max_u32_e32 v163, v136, v148
	v_min_u32_e32 v136, v136, v148
	v_max_u32_e32 v140, v141, v144
	v_min_u32_e32 v141, v141, v144
	v_max_u32_e32 v144, v143, v145
	v_min_u32_e32 v143, v143, v145
	v_max_u32_e32 v145, v132, v142
	v_min_u32_e32 v132, v132, v142
	v_max_u32_e32 v142, v146, v155
	v_min_u32_e32 v146, v146, v155
	v_max_u32_e32 v155, v128, v135
	v_min_u32_e32 v128, v128, v135
	v_max_u32_e32 v135, v131, v134
	v_min_u32_e32 v131, v131, v134
	v_max_u32_e32 v134, v133, v129
	v_min_u32_e32 v129, v133, v129
	v_max_u32_e32 v133, v130, v127
	v_min_u32_e32 v127, v130, v127
	v_max_u32_e32 v148, v149, v152
	v_min_u32_e32 v149, v149, v152
	v_max_u32_e32 v152, v151, v153
	v_min_u32_e32 v151, v151, v153
	v_max_u32_e32 v153, v138, v150
	v_min_u32_e32 v138, v138, v150
	v_max_u32_e32 v150, v154, v163
	v_min_u32_e32 v154, v154, v163
	v_max_u32_e32 v163, v0, v139
	v_min_u32_e32 v0, v0, v139
	v_max_u32_e32 v139, v3, v147
	v_min_u32_e32 v3, v3, v147
	v_max_u32_e32 v147, v137, v1
	v_min_u32_e32 v1, v137, v1
	v_max_u32_e32 v137, v2, v136
	v_min_u32_e32 v2, v2, v136
	v_max_u32_e32 v130, v140, v145
	v_min_u32_e32 v140, v140, v145
	v_max_u32_e32 v145, v144, v142
	v_min_u32_e32 v142, v144, v142
	v_max_u32_e32 v144, v141, v132
	v_min_u32_e32 v132, v141, v132
	v_max_u32_e32 v141, v143, v146
	v_min_u32_e32 v143, v143, v146
	v_max_u32_e32 v146, v155, v134
	v_min_u32_e32 v134, v155, v134
	v_max_u32_e32 v155, v135, v133
	v_min_u32_e32 v133, v135, v133
	v_max_u32_e32 v135, v128, v129
	v_min_u32_e32 v128, v128, v129
	v_max_u32_e32 v129, v131, v127
	v_min_u32_e32 v127, v131, v127
	v_max_u32_e32 v136, v148, v153
	v_min_u32_e32 v148, v148, v153
	v_max_u32_e32 v153, v152, v150
	v_min_u32_e32 v150, v152, v150
	v_max_u32_e32 v152, v149, v138
	v_min_u32_e32 v138, v149, v138
	v_max_u32_e32 v149, v151, v154
	v_min_u32_e32 v151, v151, v154
	v_max_u32_e32 v154, v163, v147
	v_min_u32_e32 v147, v163, v147
	v_max_u32_e32 v163, v139, v137
	v_min_u32_e32 v137, v139, v137
	v_max_u32_e32 v139, v0, v1
	v_min_u32_e32 v0, v0, v1
	v_max_u32_e32 v1, v3, v2
	v_min_u32_e32 v2, v3, v2
	v_min_u32_e32 v131, v130, v145
	v_min_u32_e32 v156, v140, v142
	v_min_u32_e32 v157, v144, v141
	v_min_u32_e32 v158, v132, v143
	v_min_u32_e32 v159, v146, v155
	v_min_u32_e32 v160, v134, v133
	v_min_u32_e32 v161, v135, v129
	v_min_u32_e32 v162, v128, v127
	v_min_u32_e32 v3, v136, v153
	v_min_u32_e32 v164, v148, v150
	v_min_u32_e32 v165, v152, v149
	v_min_u32_e32 v166, v138, v151
	v_min_u32_e32 v167, v154, v163
	v_min_u32_e32 v168, v147, v137
	v_min_u32_e32 v169, v139, v1
	v_min_u32_e32 v170, v0, v2
	v_max3_u32 v130, v130, v145, v170
	v_max3_u32 v0, v131, v0, v2
	v_max3_u32 v2, v140, v142, v169
	v_max3_u32 v1, v156, v139, v1
	v_max3_u32 v131, v144, v141, v168
	v_max3_u32 v137, v157, v147, v137
	v_max3_u32 v132, v132, v143, v167
	v_max3_u32 v139, v158, v154, v163
	v_max3_u32 v140, v146, v155, v166
	v_max3_u32 v138, v159, v138, v151
	v_max3_u32 v133, v134, v133, v165
	v_max3_u32 v134, v160, v152, v149
	v_max3_u32 v129, v135, v129, v164
	v_max3_u32 v135, v161, v148, v150
	v_max3_u32 v3, v128, v127, v3
	v_max3_u32 v127, v162, v136, v153
	v_max_u32_e32 v128, v130, v140
	v_min_u32_e32 v130, v130, v140
	v_max_u32_e32 v136, v0, v138
	v_min_u32_e32 v0, v0, v138
	v_max_u32_e32 v138, v2, v133
	v_min_u32_e32 v2, v2, v133
	v_max_u32_e32 v133, v1, v134
	v_min_u32_e32 v1, v1, v134
	v_max_u32_e32 v134, v131, v129
	v_min_u32_e32 v129, v131, v129
	v_max_u32_e32 v131, v137, v135
	v_min_u32_e32 v135, v137, v135
	v_max_u32_e32 v137, v132, v3
	v_min_u32_e32 v3, v132, v3
	v_max_u32_e32 v132, v139, v127
	v_min_u32_e32 v127, v139, v127
	v_max_u32_e32 v139, v128, v134
	v_min_u32_e32 v128, v128, v134
	v_max_u32_e32 v134, v136, v131
	v_min_u32_e32 v131, v136, v131
	v_max_u32_e32 v136, v138, v137
	v_min_u32_e32 v137, v138, v137
	v_max_u32_e32 v138, v133, v132
	v_min_u32_e32 v132, v133, v132
	v_max_u32_e32 v133, v130, v129
	v_min_u32_e32 v129, v130, v129
	v_max_u32_e32 v130, v0, v135
	v_min_u32_e32 v0, v0, v135
	v_max_u32_e32 v135, v2, v3
	v_min_u32_e32 v2, v2, v3
	v_max_u32_e32 v3, v1, v127
	v_min_u32_e32 v1, v1, v127
	v_max_u32_e32 v127, v139, v136
	v_min_u32_e32 v136, v139, v136
	v_max_u32_e32 v139, v134, v138
	v_min_u32_e32 v134, v134, v138
	v_max_u32_e32 v138, v128, v137
	v_min_u32_e32 v128, v128, v137
	v_max_u32_e32 v137, v131, v132
	v_min_u32_e32 v131, v131, v132
	v_max_u32_e32 v132, v133, v135
	v_min_u32_e32 v133, v133, v135
	v_max_u32_e32 v135, v130, v3
	v_min_u32_e32 v3, v130, v3
	v_max_u32_e32 v130, v129, v2
	v_min_u32_e32 v2, v129, v2
	v_max_u32_e32 v129, v0, v1
	v_min_u32_e32 v0, v0, v1
	v_max_u32_e32 v1, v127, v139
	v_min_u32_e32 v127, v127, v139
	v_max_u32_e32 v139, v136, v134
	v_min_u32_e32 v134, v136, v134
	v_max_u32_e32 v136, v138, v137
	v_min_u32_e32 v137, v138, v137
	v_max_u32_e32 v138, v128, v131
	v_min_u32_e32 v128, v128, v131
	v_max_u32_e32 v131, v132, v135
	v_min_u32_e32 v132, v132, v135
	v_max_u32_e32 v135, v133, v3
	v_min_u32_e32 v3, v133, v3
	v_max_u32_e32 v133, v130, v129
	v_min_u32_e32 v129, v130, v129
	v_max_u32_e32 v130, v2, v0
	v_min_u32_e32 v0, v2, v0
	ds_bpermute_b32 v2, v27, v1
	ds_bpermute_b32 v140, v27, v127
	ds_bpermute_b32 v141, v27, v139
	ds_bpermute_b32 v142, v27, v134
	ds_bpermute_b32 v143, v27, v136
	ds_bpermute_b32 v144, v27, v137
	ds_bpermute_b32 v145, v27, v138
	ds_bpermute_b32 v146, v27, v128
	ds_bpermute_b32 v147, v27, v131
	ds_bpermute_b32 v148, v27, v132
	ds_bpermute_b32 v149, v27, v135
	ds_bpermute_b32 v150, v27, v0
	ds_bpermute_b32 v151, v27, v130
	ds_bpermute_b32 v152, v27, v129
	ds_bpermute_b32 v153, v27, v133
	ds_bpermute_b32 v154, v27, v3
	s_waitcnt lgkmcnt(4)
; __device__ __forceinline__ void peer_tile(const Args& A, LAS unsigned char* lds, int tile) {
;     ...
;                 { const bf16_t* sp = QRY + m * 2048 + hp * 128 + 32 * g;
;                   const u32x4 s0 = *(const u32x4*)sp, s1 = *(const u32x4*)(sp + 8), s2 = *(const u32x4*)(sp + 16), s3 = *(const u32x4*)(sp + 24);
;     ...
;                 for (int msk = 16; msk <= 32; msk <<= 1) {
; #pragma unroll
;                     for (int i = 0; i < 16; ++i) k1[i] = (unsigned)__shfl_xor((int)k0[i], msk);
;                     merge16(k0, k1); }
	v_max_u32_e32 v1, v1, v150
	s_waitcnt lgkmcnt(3)
	v_max_u32_e32 v127, v127, v151
	s_waitcnt lgkmcnt(2)
	v_max_u32_e32 v139, v139, v152
	s_waitcnt lgkmcnt(1)
	v_max_u32_e32 v134, v134, v153
	s_waitcnt lgkmcnt(0)
	v_max_u32_e32 v136, v136, v154
	v_max_u32_e32 v137, v137, v149
	v_max_u32_e32 v138, v138, v148
	v_max_u32_e32 v128, v128, v147
	v_max_u32_e32 v131, v131, v146
	v_max_u32_e32 v132, v132, v145
	v_max_u32_e32 v135, v135, v144
	v_max_u32_e32 v3, v3, v143
	v_max_u32_e32 v133, v133, v142
	v_max_u32_e32 v129, v129, v141
	v_max_u32_e32 v130, v130, v140
	v_max_u32_e32 v0, v0, v2
	v_max_u32_e32 v2, v1, v131
	v_min_u32_e32 v1, v1, v131
	v_max_u32_e32 v131, v127, v132
	v_min_u32_e32 v127, v127, v132
	v_max_u32_e32 v132, v139, v135
	v_min_u32_e32 v135, v139, v135
	v_max_u32_e32 v139, v134, v3
	v_min_u32_e32 v3, v134, v3
	v_max_u32_e32 v134, v136, v133
	v_min_u32_e32 v133, v136, v133
	v_max_u32_e32 v136, v137, v129
	v_min_u32_e32 v129, v137, v129
	v_max_u32_e32 v137, v138, v130
	v_min_u32_e32 v130, v138, v130
	v_max_u32_e32 v138, v128, v0
	v_min_u32_e32 v0, v128, v0
	v_max_u32_e32 v128, v2, v134
	v_min_u32_e32 v2, v2, v134
	v_max_u32_e32 v134, v131, v136
	v_min_u32_e32 v131, v131, v136
	v_max_u32_e32 v136, v132, v137
	v_min_u32_e32 v132, v132, v137
	v_max_u32_e32 v137, v139, v138
	v_min_u32_e32 v138, v139, v138
	v_max_u32_e32 v139, v1, v133
	v_min_u32_e32 v1, v1, v133
	v_max_u32_e32 v133, v127, v129
	v_min_u32_e32 v127, v127, v129
	v_max_u32_e32 v129, v135, v130
	v_min_u32_e32 v130, v135, v130
	v_max_u32_e32 v135, v3, v0
	v_min_u32_e32 v0, v3, v0
	v_max_u32_e32 v3, v128, v136
	v_min_u32_e32 v128, v128, v136
	v_max_u32_e32 v136, v134, v137
	v_min_u32_e32 v134, v134, v137
	v_max_u32_e32 v137, v2, v132
	v_min_u32_e32 v2, v2, v132
	v_max_u32_e32 v132, v131, v138
	v_min_u32_e32 v131, v131, v138
	v_max_u32_e32 v138, v139, v129
	v_min_u32_e32 v129, v139, v129
	v_max_u32_e32 v139, v133, v135
	v_min_u32_e32 v133, v133, v135
	v_max_u32_e32 v135, v1, v130
	v_min_u32_e32 v1, v1, v130
	v_max_u32_e32 v130, v127, v0
	v_min_u32_e32 v0, v127, v0
	v_max_u32_e32 v127, v3, v136
	v_min_u32_e32 v3, v3, v136
	v_max_u32_e32 v136, v128, v134
	v_min_u32_e32 v128, v128, v134
	v_max_u32_e32 v134, v137, v132
	v_min_u32_e32 v132, v137, v132
	v_max_u32_e32 v137, v2, v131
	v_min_u32_e32 v2, v2, v131
	v_max_u32_e32 v131, v138, v139
	v_min_u32_e32 v138, v138, v139
	v_max_u32_e32 v139, v129, v133
	v_min_u32_e32 v129, v129, v133
	v_max_u32_e32 v133, v135, v130
	v_min_u32_e32 v130, v135, v130
	v_max_u32_e32 v135, v1, v0
	v_min_u32_e32 v0, v1, v0
	ds_bpermute_b32 v144, v29, v0
	ds_bpermute_b32 v1, v29, v127
	ds_bpermute_b32 v140, v29, v3
	ds_bpermute_b32 v141, v29, v136
	ds_bpermute_b32 v142, v29, v128
	s_waitcnt lgkmcnt(4)
	v_max_u32_e32 v127, v127, v144
	global_load_dwordx4 v[144:147], v[4:5], off offset:1808
	global_load_dwordx4 v[148:151], v[4:5], off offset:1792
	ds_bpermute_b32 v143, v29, v134
	ds_bpermute_b32 v152, v29, v132
	ds_bpermute_b32 v153, v29, v137
	ds_bpermute_b32 v154, v29, v2
	ds_bpermute_b32 v155, v29, v131
	ds_bpermute_b32 v156, v29, v138
	ds_bpermute_b32 v157, v29, v139
	ds_bpermute_b32 v158, v29, v129
	ds_bpermute_b32 v159, v29, v133
	ds_bpermute_b32 v160, v29, v135
	ds_bpermute_b32 v161, v29, v130
	s_waitcnt lgkmcnt(4)
	v_max_u32_e32 v132, v132, v157
	s_waitcnt lgkmcnt(3)
	v_max_u32_e32 v134, v134, v158
	s_waitcnt lgkmcnt(2)
	v_max_u32_e32 v128, v128, v159
	s_waitcnt lgkmcnt(1)
	v_max_u32_e32 v3, v3, v160
	s_waitcnt lgkmcnt(0)
	v_max_u32_e32 v136, v136, v161
	v_max_u32_e32 v137, v137, v156
	v_max_u32_e32 v2, v2, v155
	v_max_u32_e32 v131, v131, v154
	v_max_u32_e32 v138, v138, v153
	v_max_u32_e32 v139, v139, v152
	v_max_u32_e32 v129, v129, v143
	v_max_u32_e32 v133, v133, v142
	v_max_u32_e32 v130, v130, v141
	v_max_u32_e32 v135, v135, v140
	v_max_u32_e32 v0, v0, v1
	v_max_u32_e32 v1, v127, v131
	v_min_u32_e32 v127, v127, v131
	v_max_u32_e32 v131, v3, v138
	v_min_u32_e32 v3, v3, v138
	v_max_u32_e32 v138, v136, v139
	v_min_u32_e32 v136, v136, v139
	v_max_u32_e32 v139, v128, v129
	v_min_u32_e32 v128, v128, v129
	v_max_u32_e32 v129, v134, v133
	v_min_u32_e32 v133, v134, v133
	v_max_u32_e32 v134, v132, v130
	v_min_u32_e32 v130, v132, v130
	v_max_u32_e32 v132, v137, v135
	v_min_u32_e32 v135, v137, v135
	v_max_u32_e32 v137, v2, v0
	v_min_u32_e32 v0, v2, v0
	v_max_u32_e32 v2, v1, v129
	v_min_u32_e32 v1, v1, v129
	v_max_u32_e32 v129, v131, v134
	v_min_u32_e32 v131, v131, v134
	v_max_u32_e32 v134, v138, v132
	v_min_u32_e32 v132, v138, v132
	v_max_u32_e32 v138, v139, v137
	v_min_u32_e32 v137, v139, v137
	v_max_u32_e32 v139, v127, v133
	v_min_u32_e32 v127, v127, v133
	v_max_u32_e32 v133, v3, v130
	v_min_u32_e32 v3, v3, v130
	v_max_u32_e32 v130, v136, v135
	v_min_u32_e32 v135, v136, v135
	v_max_u32_e32 v136, v128, v0
	v_min_u32_e32 v0, v128, v0
	v_max_u32_e32 v128, v2, v134
	v_min_u32_e32 v2, v2, v134
	v_max_u32_e32 v134, v129, v138
	v_min_u32_e32 v129, v129, v138
	v_max_u32_e32 v143, v1, v132
	v_min_u32_e32 v1, v1, v132
	v_max_u32_e32 v132, v131, v137
	v_min_u32_e32 v131, v131, v137
	v_max_u32_e32 v152, v139, v130
	v_min_u32_e32 v130, v139, v130
	v_max_u32_e32 v153, v133, v136
	v_min_u32_e32 v154, v133, v136
	v_max_u32_e32 v155, v127, v135
	v_min_u32_e32 v127, v127, v135
	v_max_u32_e32 v156, v3, v0
	v_min_u32_e32 v0, v3, v0
	v_max_u32_e32 v142, v128, v134
	v_min_u32_e32 v141, v128, v134
	v_max_u32_e32 v140, v2, v129
	v_min_u32_e32 v139, v2, v129
	v_max_u32_e32 v138, v143, v132
	v_min_u32_e32 v137, v143, v132
	v_max_u32_e32 v136, v1, v131
	v_min_u32_e32 v135, v1, v131
	v_max_u32_e32 v134, v152, v153
	v_min_u32_e32 v133, v152, v153
	v_max_u32_e32 v132, v130, v154
	v_min_u32_e32 v131, v130, v154
	v_max_u32_e32 v130, v155, v156
	v_min_u32_e32 v129, v155, v156
	v_max_u32_e32 v128, v127, v0
	v_min_u32_e32 v127, v127, v0
	global_load_dwordx4 v[0:3], v[4:5], off offset:1840
	global_load_dwordx4 v[152:155], v[4:5], off offset:1824
	s_waitcnt vmcnt(2)
; __device__ __forceinline__ unsigned f2key(float f) { const unsigned u = __float_as_uint(f); return (u & 0x80000000u) ? ~u : (u | 0x80000000u); }
; __device__ __forceinline__ void peer_tile(const Args& A, LAS unsigned char* lds, int tile) {
;     ...
;                   for (int i = 0; i < 16; ++i) {
;                       const float lo = (float)__builtin_bit_cast(_Float16, (unsigned short)(sw[i] & 0xffffu)), hi = (float)__builtin_bit_cast(_Float16, (unsigned short)(sw[i] >> 16));
;                       const unsigned klo = (f2key(lo) & ~127u) | (unsigned)(127 - (32 * g + 2 * i)), khi = (f2key(hi) & ~127u) | (unsigned)(127 - (32 * g + 2 * i + 1));
;                       if (i < 8) { k0[2 * i] = klo; k0[2 * i + 1] = khi; } else { k1[2 * (i - 8)] = klo; k1[2 * (i - 8) + 1] = khi; } } }
	v_cvt_f32_f16_sdwa v143, v148 dst_sel:DWORD dst_unused:UNUSED_PAD src0_sel:WORD_1
	v_cvt_f32_f16_e32 v4, v148
	v_not_b32_e32 v5, v143
	v_or_b32_e32 v148, 0x80000000, v143
	v_cmp_gt_i32_e32 vcc, 0, v143
	v_not_b32_e32 v143, v4
	s_nop 0
	v_cndmask_b32_e32 v5, v148, v5, vcc
	v_or_b32_e32 v148, 0x80000000, v4
	v_cmp_gt_i32_e32 vcc, 0, v4
	v_and_b32_e32 v5, 0xffffff80, v5
	v_sub_u32_e32 v5, v5, v15
	v_cndmask_b32_e32 v4, v148, v143, vcc
	v_and_b32_e32 v4, 0xffffff80, v4
	v_cvt_f32_f16_sdwa v143, v149 dst_sel:DWORD dst_unused:UNUSED_PAD src0_sel:WORD_1
	v_sub_u32_e32 v4, v4, v15
	v_cvt_f32_f16_e32 v15, v149
	v_add_u32_e32 v5, 0x7e, v5
	v_not_b32_e32 v148, v143
	v_or_b32_e32 v149, 0x80000000, v143
	v_cmp_gt_i32_e32 vcc, 0, v143
	v_add_u32_e32 v4, 0x7f, v4
	s_nop 0
	v_cndmask_b32_e32 v143, v149, v148, vcc
	v_not_b32_e32 v148, v15
	v_or_b32_e32 v149, 0x80000000, v15
	v_cmp_gt_i32_e32 vcc, 0, v15
	v_and_b32_e32 v143, 0xffffff80, v143
	v_sub_u32_e32 v143, v143, v14
	v_cndmask_b32_e32 v15, v149, v148, vcc
	v_and_b32_e32 v15, 0xffffff80, v15
	v_cvt_f32_f16_sdwa v148, v150 dst_sel:DWORD dst_unused:UNUSED_PAD src0_sel:WORD_1
	v_sub_u32_e32 v14, v15, v14
	v_cvt_f32_f16_e32 v15, v150
	v_add_u32_e32 v143, 0x7e, v143
	v_not_b32_e32 v149, v148
	v_or_b32_e32 v150, 0x80000000, v148
	v_cmp_gt_i32_e32 vcc, 0, v148
	v_add_u32_e32 v14, 0x7f, v14
	s_nop 0
	v_cndmask_b32_e32 v148, v150, v149, vcc
	v_not_b32_e32 v149, v15
	v_or_b32_e32 v150, 0x80000000, v15
	v_cmp_gt_i32_e32 vcc, 0, v15
	v_and_b32_e32 v148, 0xffffff80, v148
	v_sub_u32_e32 v148, v148, v12
	v_cndmask_b32_e32 v15, v150, v149, vcc
	v_and_b32_e32 v15, 0xffffff80, v15
	v_cvt_f32_f16_sdwa v149, v151 dst_sel:DWORD dst_unused:UNUSED_PAD src0_sel:WORD_1
	v_sub_u32_e32 v12, v15, v12
	v_cvt_f32_f16_e32 v15, v151
	v_add_u32_e32 v148, 0x7e, v148
	v_not_b32_e32 v150, v149
	v_or_b32_e32 v151, 0x80000000, v149
	v_cmp_gt_i32_e32 vcc, 0, v149
	v_add_u32_e32 v12, 0x7f, v12
	s_nop 0
	v_cndmask_b32_e32 v149, v151, v150, vcc
	v_not_b32_e32 v150, v15
	v_or_b32_e32 v151, 0x80000000, v15
	v_cmp_gt_i32_e32 vcc, 0, v15
	v_and_b32_e32 v149, 0xffffff80, v149
	v_sub_u32_e32 v149, v149, v10
	v_cndmask_b32_e32 v15, v151, v150, vcc
	v_and_b32_e32 v15, 0xffffff80, v15
	v_cvt_f32_f16_sdwa v150, v144 dst_sel:DWORD dst_unused:UNUSED_PAD src0_sel:WORD_1
	v_sub_u32_e32 v10, v15, v10
	v_cvt_f32_f16_e32 v15, v144
	v_add_u32_e32 v149, 0x7e, v149
	v_not_b32_e32 v144, v150
	v_or_b32_e32 v151, 0x80000000, v150
	v_cmp_gt_i32_e32 vcc, 0, v150
	v_not_b32_e32 v150, v15
	v_add_u32_e32 v10, 0x7f, v10
	v_cndmask_b32_e32 v144, v151, v144, vcc
	v_or_b32_e32 v151, 0x80000000, v15
	v_cmp_gt_i32_e32 vcc, 0, v15
	v_and_b32_e32 v144, 0xffffff80, v144
	v_sub_u32_e32 v144, v144, v8
	v_cndmask_b32_e32 v15, v151, v150, vcc
	v_and_b32_e32 v15, 0xffffff80, v15
	v_cvt_f32_f16_sdwa v150, v145 dst_sel:DWORD dst_unused:UNUSED_PAD src0_sel:WORD_1
	v_sub_u32_e32 v8, v15, v8
	v_cvt_f32_f16_e32 v15, v145
	v_add_u32_e32 v144, 0x7e, v144
	v_not_b32_e32 v145, v150
	v_or_b32_e32 v151, 0x80000000, v150
	v_cmp_gt_i32_e32 vcc, 0, v150
	v_not_b32_e32 v150, v15
	v_add_u32_e32 v8, 0x7f, v8
	v_cndmask_b32_e32 v145, v151, v145, vcc
	v_or_b32_e32 v151, 0x80000000, v15
	v_cmp_gt_i32_e32 vcc, 0, v15
	v_and_b32_e32 v145, 0xffffff80, v145
	v_sub_u32_e32 v145, v145, v16
	v_cndmask_b32_e32 v15, v151, v150, vcc
	v_and_b32_e32 v15, 0xffffff80, v15
	v_cvt_f32_f16_sdwa v150, v146 dst_sel:DWORD dst_unused:UNUSED_PAD src0_sel:WORD_1
	v_sub_u32_e32 v15, v15, v16
	v_cvt_f32_f16_e32 v16, v146
	v_add_u32_e32 v145, 0x7e, v145
	v_not_b32_e32 v146, v150
	v_or_b32_e32 v151, 0x80000000, v150
	v_cmp_gt_i32_e32 vcc, 0, v150
	v_not_b32_e32 v150, v16
	v_add_u32_e32 v15, 0x7f, v15
	v_cndmask_b32_e32 v146, v151, v146, vcc
	v_or_b32_e32 v151, 0x80000000, v16
	v_cmp_gt_i32_e32 vcc, 0, v16
	v_and_b32_e32 v146, 0xffffff80, v146
	v_sub_u32_e32 v146, v146, v17
	v_cndmask_b32_e32 v16, v151, v150, vcc
	v_and_b32_e32 v16, 0xffffff80, v16
	v_cvt_f32_f16_sdwa v150, v147 dst_sel:DWORD dst_unused:UNUSED_PAD src0_sel:WORD_1
	v_sub_u32_e32 v16, v16, v17
	v_cvt_f32_f16_e32 v17, v147
	v_add_u32_e32 v146, 0x7e, v146
	v_not_b32_e32 v147, v150
	v_or_b32_e32 v151, 0x80000000, v150
	v_cmp_gt_i32_e32 vcc, 0, v150
	v_not_b32_e32 v150, v17
	v_add_u32_e32 v16, 0x7f, v16
	v_cndmask_b32_e32 v147, v151, v147, vcc
	v_or_b32_e32 v151, 0x80000000, v17
	v_cmp_gt_i32_e32 vcc, 0, v17
	v_and_b32_e32 v147, 0xffffff80, v147
	v_sub_u32_e32 v147, v147, v18
	v_cndmask_b32_e32 v17, v151, v150, vcc
	v_and_b32_e32 v17, 0xffffff80, v17
	s_waitcnt vmcnt(0)
; __device__ __forceinline__ unsigned f2key(float f) { const unsigned u = __float_as_uint(f); return (u & 0x80000000u) ? ~u : (u | 0x80000000u); }
; __device__ __forceinline__ void peer_tile(const Args& A, LAS unsigned char* lds, int tile) {
;     ...
;                   for (int i = 0; i < 16; ++i) {
;                       const float lo = (float)__builtin_bit_cast(_Float16, (unsigned short)(sw[i] & 0xffffu)), hi = (float)__builtin_bit_cast(_Float16, (unsigned short)(sw[i] >> 16));
;                       const unsigned klo = (f2key(lo) & ~127u) | (unsigned)(127 - (32 * g + 2 * i)), khi = (f2key(hi) & ~127u) | (unsigned)(127 - (32 * g + 2 * i + 1));
;                       if (i < 8) { k0[2 * i] = klo; k0[2 * i + 1] = khi; } else { k1[2 * (i - 8)] = klo; k1[2 * (i - 8) + 1] = khi; } } }
;                 sort16_desc(k0); sort16_desc(k1); merge16(k0, k1);
	v_cvt_f32_f16_sdwa v150, v152 dst_sel:DWORD dst_unused:UNUSED_PAD src0_sel:WORD_1
	v_sub_u32_e32 v17, v17, v18
	v_cvt_f32_f16_e32 v18, v152
	v_add_u32_e32 v147, 0x7e, v147
	v_not_b32_e32 v151, v150
	v_or_b32_e32 v152, 0x80000000, v150
	v_cmp_gt_i32_e32 vcc, 0, v150
	v_add_u32_e32 v17, 0x7f, v17
	s_nop 0
	v_cndmask_b32_e32 v150, v152, v151, vcc
	v_not_b32_e32 v151, v18
	v_or_b32_e32 v152, 0x80000000, v18
	v_cmp_gt_i32_e32 vcc, 0, v18
	v_and_b32_e32 v150, 0xffffff80, v150
	v_sub_u32_e32 v150, v150, v20
	v_cndmask_b32_e32 v18, v152, v151, vcc
	v_and_b32_e32 v18, 0xffffff80, v18
	v_cvt_f32_f16_sdwa v151, v153 dst_sel:DWORD dst_unused:UNUSED_PAD src0_sel:WORD_1
	v_sub_u32_e32 v18, v18, v20
	v_cvt_f32_f16_e32 v20, v153
	v_add_u32_e32 v150, 0x7e, v150
	v_not_b32_e32 v152, v151
	v_or_b32_e32 v153, 0x80000000, v151
	v_cmp_gt_i32_e32 vcc, 0, v151
	v_add_u32_e32 v18, 0x7f, v18
	v_max_u32_e32 v161, v18, v150
	v_cndmask_b32_e32 v151, v153, v152, vcc
	v_not_b32_e32 v152, v20
	v_or_b32_e32 v153, 0x80000000, v20
	v_cmp_gt_i32_e32 vcc, 0, v20
	v_and_b32_e32 v151, 0xffffff80, v151
	v_sub_u32_e32 v151, v151, v21
	v_cndmask_b32_e32 v20, v153, v152, vcc
	v_and_b32_e32 v20, 0xffffff80, v20
	v_cvt_f32_f16_sdwa v152, v154 dst_sel:DWORD dst_unused:UNUSED_PAD src0_sel:WORD_1
	v_sub_u32_e32 v20, v20, v21
	v_cvt_f32_f16_e32 v21, v154
	v_add_u32_e32 v151, 0x7e, v151
	v_not_b32_e32 v153, v152
	v_or_b32_e32 v154, 0x80000000, v152
	v_cmp_gt_i32_e32 vcc, 0, v152
	v_add_u32_e32 v20, 0x7f, v20
	v_min_u32_e32 v18, v18, v150
	v_cndmask_b32_e32 v152, v154, v153, vcc
	v_not_b32_e32 v153, v21
	v_or_b32_e32 v154, 0x80000000, v21
	v_cmp_gt_i32_e32 vcc, 0, v21
	v_and_b32_e32 v152, 0xffffff80, v152
	v_sub_u32_e32 v152, v152, v22
	v_cndmask_b32_e32 v21, v154, v153, vcc
	v_and_b32_e32 v21, 0xffffff80, v21
	v_cvt_f32_f16_sdwa v153, v155 dst_sel:DWORD dst_unused:UNUSED_PAD src0_sel:WORD_1
	v_sub_u32_e32 v21, v21, v22
	v_cvt_f32_f16_e32 v22, v155
	v_add_u32_e32 v152, 0x7e, v152
	v_not_b32_e32 v154, v153
	v_or_b32_e32 v155, 0x80000000, v153
	v_cmp_gt_i32_e32 vcc, 0, v153
	v_add_u32_e32 v21, 0x7f, v21
	v_max_u32_e32 v150, v151, v20
	v_cndmask_b32_e32 v153, v155, v154, vcc
	v_not_b32_e32 v154, v22
	v_or_b32_e32 v155, 0x80000000, v22
	v_cmp_gt_i32_e32 vcc, 0, v22
	v_and_b32_e32 v153, 0xffffff80, v153
	v_sub_u32_e32 v153, v153, v23
	v_cndmask_b32_e32 v22, v155, v154, vcc
	v_cvt_f32_f16_sdwa v154, v0 dst_sel:DWORD dst_unused:UNUSED_PAD src0_sel:WORD_1
	v_cvt_f32_f16_e32 v0, v0
	v_and_b32_e32 v22, 0xffffff80, v22
	v_sub_u32_e32 v22, v22, v23
	v_not_b32_e32 v23, v154
	v_or_b32_e32 v155, 0x80000000, v154
	v_cmp_gt_i32_e32 vcc, 0, v154
	v_not_b32_e32 v154, v0
	v_add_u32_e32 v153, 0x7e, v153
	v_cndmask_b32_e32 v23, v155, v23, vcc
	v_or_b32_e32 v155, 0x80000000, v0
	v_cmp_gt_i32_e32 vcc, 0, v0
	v_and_b32_e32 v23, 0xffffff80, v23
	v_sub_u32_e32 v23, v23, v24
	v_cndmask_b32_e32 v0, v155, v154, vcc
	v_cvt_f32_f16_sdwa v154, v1 dst_sel:DWORD dst_unused:UNUSED_PAD src0_sel:WORD_1
	v_cvt_f32_f16_e32 v1, v1
	v_and_b32_e32 v0, 0xffffff80, v0
	v_sub_u32_e32 v0, v0, v24
	v_not_b32_e32 v24, v154
	v_or_b32_e32 v155, 0x80000000, v154
	v_cmp_gt_i32_e32 vcc, 0, v154
	v_not_b32_e32 v154, v1
	v_add_u32_e32 v22, 0x7f, v22
	v_cndmask_b32_e32 v24, v155, v24, vcc
	v_or_b32_e32 v155, 0x80000000, v1
	v_cmp_gt_i32_e32 vcc, 0, v1
	v_and_b32_e32 v24, 0xffffff80, v24
	v_sub_u32_e32 v24, v24, v25
	v_cndmask_b32_e32 v1, v155, v154, vcc
	v_cvt_f32_f16_sdwa v154, v2 dst_sel:DWORD dst_unused:UNUSED_PAD src0_sel:WORD_1
	v_cvt_f32_f16_e32 v2, v2
	v_and_b32_e32 v1, 0xffffff80, v1
	v_sub_u32_e32 v1, v1, v25
	v_not_b32_e32 v25, v154
	v_or_b32_e32 v155, 0x80000000, v154
	v_cmp_gt_i32_e32 vcc, 0, v154
	v_not_b32_e32 v154, v2
	v_add_u32_e32 v23, 0x7e, v23
	v_cndmask_b32_e32 v25, v155, v25, vcc
	v_or_b32_e32 v155, 0x80000000, v2
	v_cmp_gt_i32_e32 vcc, 0, v2
	v_and_b32_e32 v25, 0xffffff80, v25
	v_sub_u32_e32 v25, v25, v26
	v_cndmask_b32_e32 v2, v155, v154, vcc
	v_cvt_f32_f16_sdwa v154, v3 dst_sel:DWORD dst_unused:UNUSED_PAD src0_sel:WORD_1
	v_cvt_f32_f16_e32 v3, v3
	v_and_b32_e32 v2, 0xffffff80, v2
	v_sub_u32_e32 v2, v2, v26
	v_not_b32_e32 v26, v154
	v_or_b32_e32 v155, 0x80000000, v154
	v_cmp_gt_i32_e32 vcc, 0, v154
	v_not_b32_e32 v154, v3
	v_add_u32_e32 v0, 0x7f, v0
	v_cndmask_b32_e32 v26, v155, v26, vcc
	v_or_b32_e32 v155, 0x80000000, v3
	v_cmp_gt_i32_e32 vcc, 0, v3
	v_and_b32_e32 v26, 0xffffff80, v26
	v_sub_u32_e32 v26, v26, v28
	v_cndmask_b32_e32 v3, v155, v154, vcc
	v_and_b32_e32 v3, 0xffffff80, v3
	v_sub_u32_e32 v3, v3, v28
	v_add_u32_e32 v24, 0x7e, v24
	v_add_u32_e32 v1, 0x7f, v1
	v_add_u32_e32 v25, 0x7e, v25
	v_add_u32_e32 v2, 0x7f, v2
	v_add_u32_e32 v26, 0x7e, v26
	v_add_u32_e32 v3, 0x7f, v3
	v_max_u32_e32 v28, v4, v5
	v_min_u32_e32 v4, v4, v5
	v_max_u32_e32 v5, v143, v14
	v_min_u32_e32 v14, v143, v14
	v_max_u32_e32 v143, v12, v148
	v_min_u32_e32 v12, v12, v148
	v_max_u32_e32 v148, v149, v10
	v_min_u32_e32 v10, v149, v10
	v_max_u32_e32 v149, v8, v144
	v_min_u32_e32 v8, v8, v144
	v_max_u32_e32 v144, v145, v15
	v_min_u32_e32 v15, v145, v15
	v_max_u32_e32 v145, v16, v146
	v_min_u32_e32 v16, v16, v146
	v_max_u32_e32 v146, v147, v17
	v_min_u32_e32 v17, v147, v17
	v_min_u32_e32 v20, v151, v20
	v_max_u32_e32 v151, v21, v152
	v_min_u32_e32 v21, v21, v152
	v_max_u32_e32 v152, v153, v22
	v_min_u32_e32 v22, v153, v22
	v_max_u32_e32 v153, v0, v23
	v_min_u32_e32 v0, v0, v23
	v_max_u32_e32 v23, v24, v1
	v_min_u32_e32 v1, v24, v1
	v_max_u32_e32 v24, v2, v25
	v_min_u32_e32 v2, v2, v25
	v_max_u32_e32 v25, v26, v3
	v_min_u32_e32 v3, v26, v3
	v_max_u32_e32 v147, v28, v14
	v_min_u32_e32 v14, v28, v14
	v_max_u32_e32 v28, v4, v5
	v_min_u32_e32 v4, v4, v5
; #define CE_DESC(a, b) do { const unsigned _mx = (a) > (b) ? (a) : (b), _mn = (a) > (b) ? (b) : (a); (a) = _mx; (b) = _mn; } while (0)
; __device__ __forceinline__ void sort16_desc(unsigned (&k)[16]) {
; #pragma unroll
;     for (int size = 2; size <= 16; size <<= 1)
; #pragma unroll
;         for (int stride = size >> 1; stride > 0; stride >>= 1)
; #pragma unroll
;             for (int i = 0; i < 16; ++i) { const int j = i ^ stride;
;                 if (j > i) { if ((i & size) == 0) CE_DESC(k[i], k[j]); else CE_DESC(k[j], k[i]); } }
; }
	v_max_u32_e32 v5, v10, v143
	v_min_u32_e32 v10, v10, v143
	v_max_u32_e32 v143, v148, v12
	v_min_u32_e32 v12, v148, v12
	v_max_u32_e32 v148, v149, v15
	v_min_u32_e32 v15, v149, v15
	v_max_u32_e32 v149, v8, v144
	v_min_u32_e32 v8, v8, v144
	v_max_u32_e32 v144, v17, v145
	v_min_u32_e32 v17, v17, v145
	v_max_u32_e32 v145, v146, v16
	v_min_u32_e32 v16, v146, v16
	v_max_u32_e32 v26, v161, v20
	v_min_u32_e32 v20, v161, v20
	v_max_u32_e32 v161, v18, v150
	v_min_u32_e32 v18, v18, v150
	v_max_u32_e32 v150, v22, v151
	v_min_u32_e32 v22, v22, v151
	v_max_u32_e32 v151, v152, v21
	v_min_u32_e32 v21, v152, v21
	v_max_u32_e32 v152, v153, v1
	v_min_u32_e32 v1, v153, v1
	v_max_u32_e32 v153, v0, v23
	v_min_u32_e32 v0, v0, v23
	v_max_u32_e32 v23, v3, v24
	v_min_u32_e32 v3, v3, v24
	v_max_u32_e32 v24, v25, v2
	v_min_u32_e32 v2, v25, v2
	v_max_u32_e32 v146, v147, v28
	v_min_u32_e32 v28, v147, v28
	v_max_u32_e32 v147, v14, v4
	v_min_u32_e32 v4, v14, v4
	v_max_u32_e32 v14, v12, v10
	v_min_u32_e32 v10, v12, v10
	v_max_u32_e32 v12, v143, v5
	v_min_u32_e32 v5, v143, v5
	v_max_u32_e32 v143, v148, v149
	v_min_u32_e32 v148, v148, v149
	v_max_u32_e32 v149, v15, v8
	v_min_u32_e32 v8, v15, v8
	v_max_u32_e32 v15, v16, v17
	v_min_u32_e32 v16, v16, v17
	v_max_u32_e32 v17, v145, v144
	v_min_u32_e32 v144, v145, v144
	v_max_u32_e32 v25, v26, v161
	v_min_u32_e32 v26, v26, v161
	v_max_u32_e32 v161, v20, v18
	v_min_u32_e32 v18, v20, v18
	v_max_u32_e32 v20, v21, v22
	v_min_u32_e32 v21, v21, v22
	v_max_u32_e32 v22, v151, v150
	v_min_u32_e32 v150, v151, v150
	v_max_u32_e32 v151, v152, v153
	v_min_u32_e32 v152, v152, v153
	v_max_u32_e32 v153, v1, v0
	v_min_u32_e32 v0, v1, v0
	v_max_u32_e32 v1, v2, v3
	v_min_u32_e32 v2, v2, v3
	v_max_u32_e32 v3, v24, v23
	v_min_u32_e32 v23, v24, v23
	v_max_u32_e32 v145, v146, v10
	v_min_u32_e32 v10, v146, v10
	v_max_u32_e32 v146, v28, v14
	v_min_u32_e32 v14, v28, v14
	v_max_u32_e32 v28, v147, v5
	v_min_u32_e32 v5, v147, v5
	v_max_u32_e32 v147, v4, v12
	v_min_u32_e32 v4, v4, v12
	v_max_u32_e32 v12, v16, v143
	v_min_u32_e32 v16, v16, v143
	v_max_u32_e32 v143, v15, v148
	v_min_u32_e32 v15, v15, v148
	v_max_u32_e32 v148, v144, v149
	v_min_u32_e32 v144, v144, v149
	v_max_u32_e32 v149, v17, v8
	v_min_u32_e32 v8, v17, v8
	v_max_u32_e32 v24, v25, v21
	v_min_u32_e32 v21, v25, v21
	v_max_u32_e32 v25, v26, v20
	v_min_u32_e32 v20, v26, v20
	v_max_u32_e32 v26, v161, v150
	v_min_u32_e32 v150, v161, v150
	v_max_u32_e32 v161, v18, v22
	v_min_u32_e32 v18, v18, v22
	v_max_u32_e32 v22, v2, v151
	v_min_u32_e32 v2, v2, v151
	v_max_u32_e32 v151, v1, v152
	v_min_u32_e32 v1, v1, v152
	v_max_u32_e32 v152, v23, v153
	v_min_u32_e32 v23, v23, v153
	v_max_u32_e32 v153, v3, v0
	v_min_u32_e32 v0, v3, v0
	v_max_u32_e32 v17, v145, v28
	v_min_u32_e32 v28, v145, v28
	v_max_u32_e32 v145, v146, v147
	v_min_u32_e32 v146, v146, v147
	v_max_u32_e32 v147, v10, v5
	v_min_u32_e32 v5, v10, v5
	v_max_u32_e32 v10, v14, v4
	v_min_u32_e32 v4, v14, v4
	v_max_u32_e32 v14, v144, v16
	v_min_u32_e32 v16, v144, v16
	v_max_u32_e32 v144, v8, v15
	v_min_u32_e32 v8, v8, v15
	v_max_u32_e32 v15, v148, v12
	v_min_u32_e32 v12, v148, v12
	v_max_u32_e32 v148, v149, v143
	v_min_u32_e32 v143, v149, v143
	v_max_u32_e32 v3, v24, v26
	v_min_u32_e32 v24, v24, v26
	v_max_u32_e32 v26, v25, v161
	v_min_u32_e32 v25, v25, v161
	v_max_u32_e32 v161, v21, v150
	v_min_u32_e32 v21, v21, v150
	v_max_u32_e32 v150, v20, v18
	v_min_u32_e32 v18, v20, v18
	v_max_u32_e32 v20, v23, v2
	v_min_u32_e32 v2, v23, v2
	v_max_u32_e32 v23, v0, v1
	v_min_u32_e32 v0, v0, v1
	v_max_u32_e32 v1, v152, v22
	v_min_u32_e32 v22, v152, v22
	v_max_u32_e32 v152, v153, v151
	v_min_u32_e32 v151, v153, v151
	v_max_u32_e32 v149, v17, v145
	v_min_u32_e32 v17, v17, v145
	v_max_u32_e32 v145, v28, v146
	v_min_u32_e32 v28, v28, v146
	v_max_u32_e32 v146, v147, v10
	v_min_u32_e32 v10, v147, v10
	v_max_u32_e32 v147, v5, v4
	v_min_u32_e32 v4, v5, v4
	v_max_u32_e32 v5, v8, v16
	v_min_u32_e32 v8, v8, v16
	v_max_u32_e32 v16, v144, v14
	v_min_u32_e32 v14, v144, v14
	v_max_u32_e32 v144, v143, v12
	v_min_u32_e32 v12, v143, v12
	v_max_u32_e32 v143, v148, v15
	v_min_u32_e32 v15, v148, v15
	v_max_u32_e32 v153, v3, v26
	v_min_u32_e32 v3, v3, v26
	v_max_u32_e32 v26, v24, v25
	v_min_u32_e32 v24, v24, v25
	v_max_u32_e32 v25, v161, v150
	v_min_u32_e32 v150, v161, v150
	v_max_u32_e32 v161, v21, v18
	v_min_u32_e32 v18, v21, v18
	v_max_u32_e32 v21, v0, v2
	v_min_u32_e32 v0, v0, v2
	v_max_u32_e32 v2, v23, v20
	v_min_u32_e32 v20, v23, v20
	v_max_u32_e32 v23, v151, v22
	v_min_u32_e32 v22, v151, v22
	v_max_u32_e32 v151, v152, v1
	v_min_u32_e32 v1, v152, v1
	v_max_u32_e32 v148, v149, v8
	v_min_u32_e32 v8, v149, v8
	v_max_u32_e32 v149, v17, v5
	v_min_u32_e32 v5, v17, v5
	v_max_u32_e32 v17, v145, v14
	v_min_u32_e32 v14, v145, v14
	v_max_u32_e32 v145, v28, v16
	v_min_u32_e32 v16, v28, v16
	v_max_u32_e32 v28, v146, v12
	v_min_u32_e32 v12, v146, v12
	v_max_u32_e32 v146, v10, v144
	v_min_u32_e32 v10, v10, v144
	v_max_u32_e32 v144, v147, v15
	v_min_u32_e32 v15, v147, v15
	v_max_u32_e32 v147, v4, v143
	v_min_u32_e32 v4, v4, v143
	v_max_u32_e32 v152, v153, v0
	v_min_u32_e32 v0, v153, v0
	v_max_u32_e32 v153, v3, v21
	v_min_u32_e32 v3, v3, v21
	v_max_u32_e32 v21, v26, v20
	v_min_u32_e32 v20, v26, v20
	v_max_u32_e32 v26, v24, v2
	v_min_u32_e32 v2, v24, v2
	v_max_u32_e32 v24, v25, v22
	v_min_u32_e32 v22, v25, v22
	v_max_u32_e32 v25, v150, v23
	v_min_u32_e32 v23, v150, v23
	v_max_u32_e32 v150, v161, v1
	v_min_u32_e32 v1, v161, v1
	v_max_u32_e32 v161, v18, v151
	v_min_u32_e32 v18, v18, v151
	v_max_u32_e32 v143, v148, v28
	v_min_u32_e32 v28, v148, v28
	v_max_u32_e32 v148, v149, v146
	v_min_u32_e32 v146, v149, v146
; #define CE_DESC(a, b) do { const unsigned _mx = (a) > (b) ? (a) : (b), _mn = (a) > (b) ? (b) : (a); (a) = _mx; (b) = _mn; } while (0)
; __device__ __forceinline__ void merge16(unsigned (&a)[16], const unsigned (&b)[16]) {
; #pragma unroll
;     for (int i = 0; i < 16; ++i) a[i] = a[i] > b[15 - i] ? a[i] : b[15 - i];
; #pragma unroll
;     for (int stride = 8; stride > 0; stride >>= 1)
; #pragma unroll
;         for (int i = 0; i < 16; ++i) { const int j = i ^ stride; if (j > i) CE_DESC(a[i], a[j]); }
; }
; __device__ __forceinline__ void peer_tile(const Args& A, LAS unsigned char* lds, int tile) {
;     ...
;                 sort16_desc(k0); sort16_desc(k1); merge16(k0, k1);
; #pragma unroll
;                 for (int msk = 16; msk <= 32; msk <<= 1) {
; #pragma unroll
;                     for (int i = 0; i < 16; ++i) k1[i] = (unsigned)__shfl_xor((int)k0[i], msk);
;                     merge16(k0, k1); }
	v_max_u32_e32 v149, v17, v144
	v_min_u32_e32 v17, v17, v144
	v_max_u32_e32 v144, v145, v147
	v_min_u32_e32 v145, v145, v147
	v_max_u32_e32 v147, v8, v12
	v_min_u32_e32 v8, v8, v12
	v_max_u32_e32 v12, v5, v10
	v_min_u32_e32 v5, v5, v10
	v_max_u32_e32 v10, v14, v15
	v_min_u32_e32 v14, v14, v15
	v_max_u32_e32 v15, v16, v4
	v_min_u32_e32 v4, v16, v4
	v_max_u32_e32 v151, v152, v24
	v_min_u32_e32 v24, v152, v24
	v_max_u32_e32 v152, v153, v25
	v_min_u32_e32 v25, v153, v25
	v_max_u32_e32 v153, v21, v150
	v_min_u32_e32 v21, v21, v150
	v_max_u32_e32 v150, v26, v161
	v_min_u32_e32 v26, v26, v161
	v_max_u32_e32 v161, v0, v22
	v_min_u32_e32 v0, v0, v22
	v_max_u32_e32 v22, v3, v23
	v_min_u32_e32 v3, v3, v23
	v_max_u32_e32 v23, v20, v1
	v_min_u32_e32 v1, v20, v1
	v_max_u32_e32 v20, v2, v18
	v_min_u32_e32 v2, v2, v18
	v_max_u32_e32 v16, v143, v149
	v_min_u32_e32 v143, v143, v149
	v_max_u32_e32 v149, v148, v144
	v_min_u32_e32 v144, v148, v144
	v_max_u32_e32 v148, v28, v17
	v_min_u32_e32 v17, v28, v17
	v_max_u32_e32 v28, v146, v145
	v_min_u32_e32 v145, v146, v145
	v_max_u32_e32 v146, v147, v10
	v_min_u32_e32 v10, v147, v10
	v_max_u32_e32 v147, v12, v15
	v_min_u32_e32 v12, v12, v15
	v_max_u32_e32 v15, v8, v14
	v_min_u32_e32 v8, v8, v14
	v_max_u32_e32 v14, v5, v4
	v_min_u32_e32 v4, v5, v4
	v_max_u32_e32 v18, v151, v153
	v_min_u32_e32 v151, v151, v153
	v_max_u32_e32 v153, v152, v150
	v_min_u32_e32 v150, v152, v150
	v_max_u32_e32 v152, v24, v21
	v_min_u32_e32 v21, v24, v21
	v_max_u32_e32 v24, v25, v26
	v_min_u32_e32 v25, v25, v26
	v_max_u32_e32 v26, v161, v23
	v_min_u32_e32 v23, v161, v23
	v_max_u32_e32 v161, v22, v20
	v_min_u32_e32 v20, v22, v20
	v_max_u32_e32 v22, v0, v1
	v_min_u32_e32 v0, v0, v1
	v_max_u32_e32 v1, v3, v2
	v_min_u32_e32 v2, v3, v2
	v_min_u32_e32 v5, v16, v149
	v_min_u32_e32 v154, v143, v144
	v_min_u32_e32 v155, v148, v28
	v_min_u32_e32 v156, v17, v145
	v_min_u32_e32 v157, v146, v147
	v_min_u32_e32 v158, v10, v12
	v_min_u32_e32 v159, v15, v14
	v_min_u32_e32 v160, v8, v4
	v_min_u32_e32 v3, v18, v153
	v_min_u32_e32 v162, v151, v150
	v_min_u32_e32 v163, v152, v24
	v_min_u32_e32 v164, v21, v25
	v_min_u32_e32 v165, v26, v161
	v_min_u32_e32 v166, v23, v20
	v_min_u32_e32 v167, v22, v1
	v_min_u32_e32 v168, v0, v2
	v_max3_u32 v16, v16, v149, v168
	v_max3_u32 v0, v5, v0, v2
	v_max3_u32 v2, v143, v144, v167
	v_max3_u32 v1, v154, v22, v1
	v_max3_u32 v5, v148, v28, v166
	v_max3_u32 v20, v155, v23, v20
	v_max3_u32 v17, v17, v145, v165
	v_max3_u32 v22, v156, v26, v161
	v_max3_u32 v23, v146, v147, v164
	v_max3_u32 v21, v157, v21, v25
	v_max3_u32 v10, v10, v12, v163
	v_max3_u32 v12, v158, v152, v24
	v_max3_u32 v14, v15, v14, v162
	v_max3_u32 v15, v159, v151, v150
	v_max3_u32 v3, v8, v4, v3
	v_max3_u32 v4, v160, v18, v153
	v_max_u32_e32 v8, v16, v23
	v_min_u32_e32 v16, v16, v23
	v_max_u32_e32 v18, v0, v21
	v_min_u32_e32 v0, v0, v21
	v_max_u32_e32 v21, v2, v10
	v_min_u32_e32 v2, v2, v10
	v_max_u32_e32 v10, v1, v12
	v_min_u32_e32 v1, v1, v12
	v_max_u32_e32 v12, v5, v14
	v_min_u32_e32 v5, v5, v14
	v_max_u32_e32 v14, v20, v15
	v_min_u32_e32 v15, v20, v15
	v_max_u32_e32 v20, v17, v3
	v_min_u32_e32 v3, v17, v3
	v_max_u32_e32 v17, v22, v4
	v_min_u32_e32 v4, v22, v4
	v_max_u32_e32 v22, v8, v12
	v_min_u32_e32 v8, v8, v12
	v_max_u32_e32 v12, v18, v14
	v_min_u32_e32 v14, v18, v14
	v_max_u32_e32 v18, v21, v20
	v_min_u32_e32 v20, v21, v20
	v_max_u32_e32 v21, v10, v17
	v_min_u32_e32 v10, v10, v17
	v_max_u32_e32 v17, v16, v5
	v_min_u32_e32 v5, v16, v5
	v_max_u32_e32 v16, v0, v15
	v_min_u32_e32 v0, v0, v15
	v_max_u32_e32 v15, v2, v3
	v_min_u32_e32 v2, v2, v3
	v_max_u32_e32 v3, v1, v4
	v_min_u32_e32 v1, v1, v4
	v_max_u32_e32 v4, v22, v18
	v_min_u32_e32 v18, v22, v18
	v_max_u32_e32 v22, v12, v21
	v_min_u32_e32 v12, v12, v21
	v_max_u32_e32 v21, v8, v20
	v_min_u32_e32 v8, v8, v20
	v_max_u32_e32 v20, v14, v10
	v_min_u32_e32 v10, v14, v10
	v_max_u32_e32 v14, v17, v15
	v_min_u32_e32 v15, v17, v15
	v_max_u32_e32 v17, v16, v3
	v_min_u32_e32 v3, v16, v3
	v_max_u32_e32 v16, v5, v2
	v_min_u32_e32 v2, v5, v2
	v_max_u32_e32 v5, v0, v1
	v_min_u32_e32 v0, v0, v1
	v_max_u32_e32 v1, v4, v22
	v_min_u32_e32 v4, v4, v22
	v_max_u32_e32 v22, v18, v12
	v_min_u32_e32 v12, v18, v12
	v_max_u32_e32 v18, v21, v20
	v_min_u32_e32 v20, v21, v20
	v_max_u32_e32 v21, v8, v10
	v_min_u32_e32 v8, v8, v10
	v_max_u32_e32 v10, v14, v17
	v_min_u32_e32 v14, v14, v17
	v_max_u32_e32 v17, v15, v3
	v_min_u32_e32 v3, v15, v3
	v_max_u32_e32 v15, v16, v5
	v_min_u32_e32 v5, v16, v5
	v_max_u32_e32 v16, v2, v0
	v_min_u32_e32 v0, v2, v0
	ds_bpermute_b32 v2, v27, v1
	ds_bpermute_b32 v23, v27, v4
	ds_bpermute_b32 v24, v27, v22
	ds_bpermute_b32 v25, v27, v12
	ds_bpermute_b32 v26, v27, v18
	ds_bpermute_b32 v28, v27, v20
	ds_bpermute_b32 v143, v27, v21
	ds_bpermute_b32 v144, v27, v8
	ds_bpermute_b32 v145, v27, v10
	ds_bpermute_b32 v146, v27, v14
	ds_bpermute_b32 v147, v27, v17
	ds_bpermute_b32 v148, v27, v0
	ds_bpermute_b32 v149, v27, v16
	ds_bpermute_b32 v150, v27, v5
	ds_bpermute_b32 v151, v27, v15
	ds_bpermute_b32 v27, v27, v3
	s_waitcnt lgkmcnt(4)
	v_max_u32_e32 v1, v1, v148
	s_waitcnt lgkmcnt(3)
	v_max_u32_e32 v4, v4, v149
	s_waitcnt lgkmcnt(2)
	v_max_u32_e32 v22, v22, v150
	s_waitcnt lgkmcnt(1)
	v_max_u32_e32 v12, v12, v151
	s_waitcnt lgkmcnt(0)
; __device__ __forceinline__ void peer_tile(const Args& A, LAS unsigned char* lds, int tile) {
;     ...
;                 for (int msk = 16; msk <= 32; msk <<= 1) {
; #pragma unroll
;                     for (int i = 0; i < 16; ++i) k1[i] = (unsigned)__shfl_xor((int)k0[i], msk);
;                     merge16(k0, k1); }
; #pragma unroll
;                 for (int i = 0; i < 16; ++i) LA[hh][p][i] = k0[i];
;     ...
;             const int h = 4 * hg + g;
;             unsigned L2[2][16];
; #pragma unroll
;             for (int p = 0; p < 2; ++p)
; #pragma unroll
;                 for (int i = 0; i < 16; ++i) L2[p][i] = (g & 2) ? ((g & 1) ? LA[3][p][i] : LA[2][p][i]) : ((g & 1) ? LA[1][p][i] : LA[0][p][i]);
	v_max_u32_e32 v18, v18, v27
	v_max_u32_e32 v20, v20, v147
	v_max_u32_e32 v21, v21, v146
	v_max_u32_e32 v8, v8, v145
	v_max_u32_e32 v10, v10, v144
	v_max_u32_e32 v14, v14, v143
	v_max_u32_e32 v17, v17, v28
	v_max_u32_e32 v3, v3, v26
	v_max_u32_e32 v15, v15, v25
	v_max_u32_e32 v5, v5, v24
	v_max_u32_e32 v16, v16, v23
	v_max_u32_e32 v0, v0, v2
	v_max_u32_e32 v2, v1, v10
	v_min_u32_e32 v1, v1, v10
	v_max_u32_e32 v10, v4, v14
	v_min_u32_e32 v4, v4, v14
	v_max_u32_e32 v14, v22, v17
	v_min_u32_e32 v17, v22, v17
	v_max_u32_e32 v22, v12, v3
	v_min_u32_e32 v3, v12, v3
	v_max_u32_e32 v12, v18, v15
	v_min_u32_e32 v15, v18, v15
	v_max_u32_e32 v18, v20, v5
	v_min_u32_e32 v5, v20, v5
	v_max_u32_e32 v20, v21, v16
	v_min_u32_e32 v16, v21, v16
	v_max_u32_e32 v21, v8, v0
	v_min_u32_e32 v0, v8, v0
	v_max_u32_e32 v8, v2, v12
	v_min_u32_e32 v2, v2, v12
	v_max_u32_e32 v12, v10, v18
	v_min_u32_e32 v10, v10, v18
	v_max_u32_e32 v18, v14, v20
	v_min_u32_e32 v14, v14, v20
	v_max_u32_e32 v20, v22, v21
	v_min_u32_e32 v21, v22, v21
	v_max_u32_e32 v22, v1, v15
	v_min_u32_e32 v1, v1, v15
	v_max_u32_e32 v15, v4, v5
	v_min_u32_e32 v4, v4, v5
	v_max_u32_e32 v5, v17, v16
	v_min_u32_e32 v16, v17, v16
	v_max_u32_e32 v17, v3, v0
	v_min_u32_e32 v0, v3, v0
	v_max_u32_e32 v3, v8, v18
	v_min_u32_e32 v8, v8, v18
	v_max_u32_e32 v18, v12, v20
	v_min_u32_e32 v12, v12, v20
	v_max_u32_e32 v20, v2, v14
	v_min_u32_e32 v2, v2, v14
	v_max_u32_e32 v14, v10, v21
	v_min_u32_e32 v10, v10, v21
	v_max_u32_e32 v21, v22, v5
	v_min_u32_e32 v5, v22, v5
	v_max_u32_e32 v22, v15, v17
	v_min_u32_e32 v15, v15, v17
	v_max_u32_e32 v17, v1, v16
	v_min_u32_e32 v1, v1, v16
	v_max_u32_e32 v16, v4, v0
	v_min_u32_e32 v0, v4, v0
	v_max_u32_e32 v4, v3, v18
	v_min_u32_e32 v3, v3, v18
	v_max_u32_e32 v18, v8, v12
	v_min_u32_e32 v8, v8, v12
	v_max_u32_e32 v12, v20, v14
	v_min_u32_e32 v14, v20, v14
	v_max_u32_e32 v20, v2, v10
	v_min_u32_e32 v2, v2, v10
	v_max_u32_e32 v10, v21, v22
	v_min_u32_e32 v21, v21, v22
	v_max_u32_e32 v22, v5, v15
	v_min_u32_e32 v5, v5, v15
	v_max_u32_e32 v15, v17, v16
	v_min_u32_e32 v16, v17, v16
	v_max_u32_e32 v17, v1, v0
	v_min_u32_e32 v0, v1, v0
	ds_bpermute_b32 v1, v29, v4
	ds_bpermute_b32 v23, v29, v3
	ds_bpermute_b32 v24, v29, v18
	ds_bpermute_b32 v25, v29, v8
	ds_bpermute_b32 v26, v29, v12
	ds_bpermute_b32 v27, v29, v14
	ds_bpermute_b32 v28, v29, v20
	ds_bpermute_b32 v143, v29, v2
	ds_bpermute_b32 v144, v29, v10
	ds_bpermute_b32 v145, v29, v21
	ds_bpermute_b32 v146, v29, v22
	ds_bpermute_b32 v147, v29, v0
	ds_bpermute_b32 v148, v29, v17
	ds_bpermute_b32 v149, v29, v16
	ds_bpermute_b32 v150, v29, v15
	ds_bpermute_b32 v29, v29, v5
	s_waitcnt lgkmcnt(4)
	v_max_u32_e32 v4, v4, v147
	s_waitcnt lgkmcnt(3)
	v_max_u32_e32 v3, v3, v148
	s_waitcnt lgkmcnt(2)
	v_max_u32_e32 v18, v18, v149
	s_waitcnt lgkmcnt(1)
	v_max_u32_e32 v8, v8, v150
	s_waitcnt lgkmcnt(0)
	v_max_u32_e32 v12, v12, v29
	v_max_u32_e32 v14, v14, v146
	v_max_u32_e32 v20, v20, v145
	v_max_u32_e32 v2, v2, v144
	v_max_u32_e32 v10, v10, v143
	v_max_u32_e32 v21, v21, v28
	v_max_u32_e32 v22, v22, v27
	v_max_u32_e32 v5, v5, v26
	v_max_u32_e32 v15, v15, v25
	v_max_u32_e32 v16, v16, v24
	v_max_u32_e32 v17, v17, v23
	v_max_u32_e32 v0, v0, v1
	v_max_u32_e32 v1, v4, v10
	v_min_u32_e32 v4, v4, v10
	v_max_u32_e32 v10, v3, v21
	v_min_u32_e32 v3, v3, v21
	v_max_u32_e32 v21, v18, v22
	v_min_u32_e32 v18, v18, v22
	v_max_u32_e32 v22, v8, v5
	v_min_u32_e32 v5, v8, v5
	v_max_u32_e32 v8, v12, v15
	v_min_u32_e32 v12, v12, v15
	v_max_u32_e32 v15, v14, v16
	v_min_u32_e32 v14, v14, v16
	v_max_u32_e32 v16, v20, v17
	v_min_u32_e32 v17, v20, v17
	v_max_u32_e32 v20, v2, v0
	v_min_u32_e32 v0, v2, v0
	v_max_u32_e32 v2, v1, v8
	v_min_u32_e32 v1, v1, v8
	v_max_u32_e32 v8, v10, v15
	v_min_u32_e32 v10, v10, v15
	v_max_u32_e32 v15, v21, v16
	v_min_u32_e32 v16, v21, v16
	v_max_u32_e32 v21, v22, v20
	v_min_u32_e32 v20, v22, v20
	v_max_u32_e32 v22, v4, v12
	v_min_u32_e32 v4, v4, v12
	v_max_u32_e32 v12, v3, v14
	v_min_u32_e32 v3, v3, v14
	v_max_u32_e32 v14, v18, v17
	v_min_u32_e32 v17, v18, v17
	v_max_u32_e32 v18, v5, v0
	v_min_u32_e32 v0, v5, v0
	v_max_u32_e32 v5, v2, v15
	v_min_u32_e32 v2, v2, v15
	v_max_u32_e32 v15, v8, v21
	v_min_u32_e32 v8, v8, v21
	v_max_u32_e32 v21, v1, v16
	v_min_u32_e32 v1, v1, v16
	v_max_u32_e32 v16, v10, v20
	v_min_u32_e32 v10, v10, v20
	v_max_u32_e32 v20, v22, v14
	v_min_u32_e32 v14, v22, v14
	v_max_u32_e32 v22, v12, v18
	v_min_u32_e32 v12, v12, v18
	v_max_u32_e32 v18, v4, v17
	v_min_u32_e32 v4, v4, v17
	v_max_u32_e32 v17, v3, v0
	v_min_u32_e32 v0, v3, v0
	v_max_u32_e32 v3, v5, v15
	v_min_u32_e32 v5, v5, v15
	v_max_u32_e32 v15, v2, v8
	v_min_u32_e32 v2, v2, v8
	v_max_u32_e32 v8, v21, v16
	v_min_u32_e32 v16, v21, v16
	v_max_u32_e32 v21, v1, v10
	v_min_u32_e32 v1, v1, v10
	v_max_u32_e32 v10, v20, v22
	v_min_u32_e32 v20, v20, v22
	v_max_u32_e32 v22, v14, v12
	v_min_u32_e32 v12, v14, v12
	v_max_u32_e32 v14, v18, v17
	v_min_u32_e32 v17, v18, v17
	v_max_u32_e32 v18, v4, v0
	v_min_u32_e32 v0, v4, v0
	v_and_b32_e32 v4, 16, v19
	v_cmp_eq_u32_e32 vcc, 0, v4
	v_cndmask_b32_e64 v23, v77, v45, s[0:1]
	v_cndmask_b32_e64 v24, v76, v44, s[0:1]
	v_cndmask_b32_e32 v4, v142, v109, vcc
	v_cndmask_b32_e64 v4, v4, v23, s[4:5]
	v_cndmask_b32_e32 v23, v141, v108, vcc
	v_cndmask_b32_e64 v23, v23, v24, s[4:5]
	v_cndmask_b32_e32 v24, v140, v107, vcc
	v_cndmask_b32_e64 v25, v75, v43, s[0:1]
	v_cndmask_b32_e64 v24, v24, v25, s[4:5]
	v_cndmask_b32_e32 v25, v139, v106, vcc
	v_cndmask_b32_e64 v26, v74, v42, s[0:1]
	v_cndmask_b32_e64 v25, v25, v26, s[4:5]
	v_cndmask_b32_e32 v26, v138, v105, vcc
	v_cndmask_b32_e64 v27, v73, v41, s[0:1]
	v_cndmask_b32_e64 v26, v26, v27, s[4:5]
; __device__ __forceinline__ float key2f(unsigned k) { const unsigned u = (k & 0x80000000u) ? (k & 0x7fffffffu) : ~k; return __uint_as_float(u); }
; #define CK(i, j) ((f2key(va[i] + vb[j]) & ~255u) | (unsigned)(255 - (16 * (i) + (j))))
; __device__ __forceinline__ void peer_tile(const Args& A, LAS unsigned char* lds, int tile) {
;     ...
;                 for (int i = 0; i < 16; ++i) L2[p][i] = (g & 2) ? ((g & 1) ? LA[3][p][i] : LA[2][p][i]) : ((g & 1) ? LA[1][p][i] : LA[0][p][i]);
;             float va[16], vb[16];
; #pragma unroll
;             for (int i = 0; i < 16; ++i) { va[i] = key2f(L2[0][i] & ~127u); vb[i] = key2f(L2[1][i] & ~127u); idx[i] = 127u - (L2[0][i] & 127u); idx[16 + i] = 127u - (L2[1][i] & 127u); }
;     ...
;             unsigned Lf[16], Bt[16];
; #pragma unroll
;             for (int j = 0; j < 16; ++j) Lf[j] = CK(0, j);
	v_cndmask_b32_e32 v27, v137, v104, vcc
	v_cndmask_b32_e64 v28, v72, v40, s[0:1]
	v_cndmask_b32_e64 v27, v27, v28, s[4:5]
	v_cndmask_b32_e32 v28, v136, v103, vcc
	v_cndmask_b32_e64 v29, v71, v39, s[0:1]
	v_cndmask_b32_e64 v28, v28, v29, s[4:5]
	v_cndmask_b32_e32 v29, v135, v102, vcc
	v_cndmask_b32_e64 v29, v29, v38, s[4:5]
	v_cndmask_b32_e32 v38, v134, v101, vcc
	v_cndmask_b32_e64 v37, v38, v37, s[4:5]
	v_cndmask_b32_e32 v38, v133, v100, vcc
	v_cndmask_b32_e64 v36, v38, v36, s[4:5]
	v_cndmask_b32_e32 v38, v132, v99, vcc
	v_cndmask_b32_e64 v38, v38, v35, s[4:5]
	v_cndmask_b32_e32 v35, v131, v98, vcc
	v_cndmask_b32_e64 v39, v35, v34, s[4:5]
	v_cndmask_b32_e32 v34, v130, v97, vcc
	v_cndmask_b32_e64 v33, v34, v33, s[4:5]
	v_cndmask_b32_e32 v34, v129, v96, vcc
	v_cndmask_b32_e64 v40, v34, v32, s[4:5]
	v_cndmask_b32_e32 v32, v128, v95, vcc
	v_cndmask_b32_e64 v42, v32, v31, s[4:5]
	v_cndmask_b32_e32 v31, v127, v94, vcc
	v_cndmask_b32_e64 v43, v31, v30, s[4:5]
	v_cndmask_b32_e32 v3, v3, v126, vcc
	v_cndmask_b32_e64 v30, v93, v61, s[0:1]
	v_cndmask_b32_e64 v3, v3, v30, s[4:5]
	v_cndmask_b32_e32 v5, v5, v125, vcc
	v_cndmask_b32_e64 v30, v92, v60, s[0:1]
	v_cndmask_b32_e64 v30, v5, v30, s[4:5]
	v_cndmask_b32_e32 v5, v15, v124, vcc
	v_cndmask_b32_e64 v15, v91, v59, s[0:1]
	v_cndmask_b32_e64 v15, v5, v15, s[4:5]
	v_cndmask_b32_e32 v2, v2, v123, vcc
	v_cndmask_b32_e64 v5, v90, v58, s[0:1]
	v_cndmask_b32_e64 v31, v2, v5, s[4:5]
	v_cndmask_b32_e32 v2, v8, v122, vcc
	v_cndmask_b32_e64 v5, v89, v57, s[0:1]
	v_cndmask_b32_e64 v8, v2, v5, s[4:5]
	v_cndmask_b32_e32 v2, v16, v121, vcc
	v_cndmask_b32_e64 v5, v88, v56, s[0:1]
	v_cndmask_b32_e64 v32, v2, v5, s[4:5]
	v_cndmask_b32_e32 v2, v21, v120, vcc
	v_cndmask_b32_e64 v5, v87, v55, s[0:1]
	v_cndmask_b32_e64 v21, v2, v5, s[4:5]
	v_cndmask_b32_e32 v1, v1, v119, vcc
	v_cndmask_b32_e64 v2, v86, v54, s[0:1]
	v_cndmask_b32_e64 v34, v1, v2, s[4:5]
	v_cndmask_b32_e32 v1, v10, v118, vcc
	v_cndmask_b32_e64 v2, v85, v53, s[0:1]
	v_cndmask_b32_e64 v41, v1, v2, s[4:5]
	v_cndmask_b32_e32 v1, v20, v117, vcc
	v_cndmask_b32_e64 v2, v84, v52, s[0:1]
	v_cndmask_b32_e64 v44, v1, v2, s[4:5]
	v_cndmask_b32_e32 v1, v22, v116, vcc
	v_cndmask_b32_e64 v2, v83, v51, s[0:1]
	v_cndmask_b32_e64 v45, v1, v2, s[4:5]
	v_cndmask_b32_e32 v1, v12, v115, vcc
	v_cndmask_b32_e64 v2, v82, v50, s[0:1]
	v_cndmask_b32_e64 v50, v1, v2, s[4:5]
	v_cndmask_b32_e32 v1, v14, v114, vcc
	v_cndmask_b32_e64 v2, v81, v49, s[0:1]
	v_cndmask_b32_e64 v49, v1, v2, s[4:5]
	v_cndmask_b32_e32 v1, v17, v112, vcc
	v_cndmask_b32_e64 v2, v80, v48, s[0:1]
	v_cndmask_b32_e64 v48, v1, v2, s[4:5]
	v_cndmask_b32_e32 v1, v18, v111, vcc
	v_cndmask_b32_e64 v2, v79, v47, s[0:1]
	v_cndmask_b32_e64 v47, v1, v2, s[4:5]
	v_cndmask_b32_e32 v0, v0, v110, vcc
	v_cndmask_b32_e64 v1, v78, v46, s[0:1]
	v_cndmask_b32_e64 v46, v0, v1, s[4:5]
	v_and_b32_e32 v0, 0x7fffff80, v4
	v_bitop3_b32 v1, v4, s19, v4 bitop3:0xcf
	v_cmp_gt_i32_e32 vcc, 0, v4
	v_bitop3_b32 v2, v4, s19, v4 bitop3:0xc
	v_bitop3_b32 v4, v23, s19, v23 bitop3:0xcf
	v_cndmask_b32_e32 v20, v1, v0, vcc
	v_and_b32_e32 v0, 0x7fffff80, v3
	v_bitop3_b32 v1, v3, s19, v3 bitop3:0xcf
	v_cmp_gt_i32_e32 vcc, 0, v3
	v_add_u32_e32 v5, 0, v6
	v_bitop3_b32 v3, v3, s19, v3 bitop3:0xc
	v_cndmask_b32_e32 v1, v1, v0, vcc
	v_and_b32_e32 v0, 0x7fffff80, v23
	v_cmp_gt_i32_e32 vcc, 0, v23
	v_bitop3_b32 v14, v31, s19, v31 bitop3:0xcf
	v_bitop3_b32 v6, v24, s19, v24 bitop3:0xc
	v_cndmask_b32_e32 v18, v4, v0, vcc
	v_and_b32_e32 v0, 0x7fffff80, v30
	v_bitop3_b32 v4, v30, s19, v30 bitop3:0xcf
	v_cmp_gt_i32_e32 vcc, 0, v30
	v_bitop3_b32 v10, v15, s19, v15 bitop3:0xc
	v_bitop3_b32 v16, v32, s19, v32 bitop3:0xcf
	v_cndmask_b32_e32 v0, v4, v0, vcc
	v_bitop3_b32 v4, v23, s19, v23 bitop3:0xc
	ds_write2_b32 v5, v2, v4 offset1:1
	v_bitop3_b32 v2, v30, s19, v30 bitop3:0xc
	ds_write2_b32 v5, v3, v2 offset0:16 offset1:17
	v_and_b32_e32 v2, 0x7fffff80, v24
	v_bitop3_b32 v3, v24, s19, v24 bitop3:0xcf
	v_cmp_gt_i32_e32 vcc, 0, v24
	v_bitop3_b32 v4, v25, s19, v25 bitop3:0xcf
	v_bitop3_b32 v22, v29, s19, v29 bitop3:0xcf
	v_cndmask_b32_e32 v12, v3, v2, vcc
	v_and_b32_e32 v2, 0x7fffff80, v15
	v_bitop3_b32 v3, v15, s19, v15 bitop3:0xcf
	v_cmp_gt_i32_e32 vcc, 0, v15
	v_bitop3_b32 v15, v27, s19, v27 bitop3:0xcf
	v_bitop3_b32 v24, v34, s19, v34 bitop3:0xcf
	v_cndmask_b32_e32 v3, v3, v2, vcc
	v_and_b32_e32 v2, 0x7fffff80, v25
	v_cmp_gt_i32_e32 vcc, 0, v25
	s_nop 1
	v_cndmask_b32_e32 v4, v4, v2, vcc
	v_and_b32_e32 v2, 0x7fffff80, v31
	v_cmp_gt_i32_e32 vcc, 0, v31
	s_nop 1
	v_cndmask_b32_e32 v2, v14, v2, vcc
	v_bitop3_b32 v14, v25, s19, v25 bitop3:0xc
	ds_write2_b32 v5, v6, v14 offset0:2 offset1:3
	v_bitop3_b32 v6, v31, s19, v31 bitop3:0xc
	ds_write2_b32 v5, v10, v6 offset0:18 offset1:19
	v_and_b32_e32 v6, 0x7fffff80, v26
	v_bitop3_b32 v10, v26, s19, v26 bitop3:0xcf
	v_cmp_gt_i32_e32 vcc, 0, v26
	v_bitop3_b32 v25, v36, s19, v36 bitop3:0xcf
	s_nop 0
	v_cndmask_b32_e32 v14, v10, v6, vcc
	v_and_b32_e32 v6, 0x7fffff80, v8
	v_bitop3_b32 v10, v8, s19, v8 bitop3:0xcf
	v_cmp_gt_i32_e32 vcc, 0, v8
	v_bitop3_b32 v8, v8, s19, v8 bitop3:0xc
	s_nop 0
	v_cndmask_b32_e32 v17, v10, v6, vcc
	v_and_b32_e32 v10, 0x7fffff80, v27
	v_cmp_gt_i32_e32 vcc, 0, v27
	v_bitop3_b32 v6, v26, s19, v26 bitop3:0xc
	v_bitop3_b32 v26, v43, s19, v43 bitop3:0xcf
	v_cndmask_b32_e32 v10, v15, v10, vcc
	v_and_b32_e32 v15, 0x7fffff80, v32
	v_cmp_gt_i32_e32 vcc, 0, v32
	s_nop 1
	v_cndmask_b32_e32 v16, v16, v15, vcc
	v_bitop3_b32 v15, v27, s19, v27 bitop3:0xc
	ds_write2_b32 v5, v6, v15 offset0:4 offset1:5
	v_bitop3_b32 v6, v32, s19, v32 bitop3:0xc
	ds_write2_b32 v5, v8, v6 offset0:20 offset1:21
	v_and_b32_e32 v6, 0x7fffff80, v28
; __device__ __forceinline__ float key2f(unsigned k) { const unsigned u = (k & 0x80000000u) ? (k & 0x7fffffffu) : ~k; return __uint_as_float(u); }
; #define CK(i, j) ((f2key(va[i] + vb[j]) & ~255u) | (unsigned)(255 - (16 * (i) + (j))))
; __device__ __forceinline__ void peer_tile(const Args& A, LAS unsigned char* lds, int tile) {
;     ...
;             for (int i = 0; i < 16; ++i) { va[i] = key2f(L2[0][i] & ~127u); vb[i] = key2f(L2[1][i] & ~127u); idx[i] = 127u - (L2[0][i] & 127u); idx[16 + i] = 127u - (L2[1][i] & 127u); }
;     ...
;             unsigned Lf[16], Bt[16];
; #pragma unroll
;             for (int j = 0; j < 16; ++j) Lf[j] = CK(0, j);
	v_bitop3_b32 v8, v28, s19, v28 bitop3:0xcf
	v_cmp_gt_i32_e32 vcc, 0, v28
	v_bitop3_b32 v15, v21, s19, v21 bitop3:0xcf
	s_nop 0
	v_cndmask_b32_e32 v8, v8, v6, vcc
	v_and_b32_e32 v6, 0x7fffff80, v21
	v_cmp_gt_i32_e32 vcc, 0, v21
	v_bitop3_b32 v21, v21, s19, v21 bitop3:0xc
	s_nop 0
	v_cndmask_b32_e32 v23, v15, v6, vcc
	v_and_b32_e32 v6, 0x7fffff80, v29
	v_cmp_gt_i32_e32 vcc, 0, v29
	v_bitop3_b32 v15, v28, s19, v28 bitop3:0xc
	s_nop 0
	v_cndmask_b32_e32 v6, v22, v6, vcc
	v_and_b32_e32 v22, 0x7fffff80, v34
	v_cmp_gt_i32_e32 vcc, 0, v34
	s_nop 1
	v_cndmask_b32_e32 v22, v24, v22, vcc
	v_bitop3_b32 v24, v29, s19, v29 bitop3:0xc
	ds_write2_b32 v5, v15, v24 offset0:6 offset1:7
	v_bitop3_b32 v15, v34, s19, v34 bitop3:0xc
	ds_write2_b32 v5, v21, v15 offset0:22 offset1:23
	v_and_b32_e32 v15, 0x7fffff80, v37
	v_bitop3_b32 v21, v37, s19, v37 bitop3:0xcf
	v_cmp_gt_i32_e32 vcc, 0, v37
	v_and_b32_e32 v24, 0x7fffff80, v36
	s_nop 0
	v_cndmask_b32_e32 v27, v21, v15, vcc
	v_and_b32_e32 v15, 0x7fffff80, v41
	v_bitop3_b32 v21, v41, s19, v41 bitop3:0xcf
	v_cmp_gt_i32_e32 vcc, 0, v41
	s_nop 1
	v_cndmask_b32_e32 v35, v21, v15, vcc
	v_cmp_gt_i32_e32 vcc, 0, v36
	v_bitop3_b32 v15, v37, s19, v37 bitop3:0xc
	v_bitop3_b32 v21, v41, s19, v41 bitop3:0xc
	v_cndmask_b32_e32 v28, v25, v24, vcc
	v_and_b32_e32 v24, 0x7fffff80, v44
	v_bitop3_b32 v25, v44, s19, v44 bitop3:0xcf
	v_cmp_gt_i32_e32 vcc, 0, v44
	s_nop 1
	v_cndmask_b32_e32 v34, v25, v24, vcc
	v_bitop3_b32 v24, v36, s19, v36 bitop3:0xc
	ds_write2_b32 v5, v15, v24 offset0:8 offset1:9
	v_bitop3_b32 v15, v44, s19, v44 bitop3:0xc
	ds_write2_b32 v5, v21, v15 offset0:24 offset1:25
	v_and_b32_e32 v15, 0x7fffff80, v38
	v_bitop3_b32 v21, v38, s19, v38 bitop3:0xcf
	v_cmp_gt_i32_e32 vcc, 0, v38
	v_and_b32_e32 v24, 0x7fffff80, v39
	v_bitop3_b32 v25, v39, s19, v39 bitop3:0xcf
	v_cndmask_b32_e32 v29, v21, v15, vcc
	v_and_b32_e32 v15, 0x7fffff80, v45
	v_bitop3_b32 v21, v45, s19, v45 bitop3:0xcf
	v_cmp_gt_i32_e32 vcc, 0, v45
	s_nop 1
	v_cndmask_b32_e32 v37, v21, v15, vcc
	v_cmp_gt_i32_e32 vcc, 0, v39
	v_bitop3_b32 v15, v38, s19, v38 bitop3:0xc
	v_bitop3_b32 v21, v45, s19, v45 bitop3:0xc
	v_cndmask_b32_e32 v30, v25, v24, vcc
	v_and_b32_e32 v24, 0x7fffff80, v50
	v_bitop3_b32 v25, v50, s19, v50 bitop3:0xcf
	v_cmp_gt_i32_e32 vcc, 0, v50
	s_nop 1
	v_cndmask_b32_e32 v36, v25, v24, vcc
	v_bitop3_b32 v24, v39, s19, v39 bitop3:0xc
	ds_write2_b32 v5, v15, v24 offset0:10 offset1:11
	v_bitop3_b32 v15, v50, s19, v50 bitop3:0xc
	ds_write2_b32 v5, v21, v15 offset0:26 offset1:27
	v_and_b32_e32 v15, 0x7fffff80, v33
	v_bitop3_b32 v21, v33, s19, v33 bitop3:0xcf
	v_cmp_gt_i32_e32 vcc, 0, v33
	v_and_b32_e32 v24, 0x7fffff80, v40
	v_bitop3_b32 v25, v40, s19, v40 bitop3:0xcf
	v_cndmask_b32_e32 v31, v21, v15, vcc
	v_and_b32_e32 v15, 0x7fffff80, v49
	v_bitop3_b32 v21, v49, s19, v49 bitop3:0xcf
	v_cmp_gt_i32_e32 vcc, 0, v49
	s_nop 1
	v_cndmask_b32_e32 v39, v21, v15, vcc
	v_cmp_gt_i32_e32 vcc, 0, v40
	v_bitop3_b32 v15, v33, s19, v33 bitop3:0xc
	v_bitop3_b32 v21, v49, s19, v49 bitop3:0xc
	v_cndmask_b32_e32 v32, v25, v24, vcc
	v_and_b32_e32 v24, 0x7fffff80, v48
	v_bitop3_b32 v25, v48, s19, v48 bitop3:0xcf
	v_cmp_gt_i32_e32 vcc, 0, v48
	v_bitop3_b32 v33, v46, s19, v46 bitop3:0xcf
	s_nop 0
	v_cndmask_b32_e32 v38, v25, v24, vcc
	v_bitop3_b32 v24, v40, s19, v40 bitop3:0xc
	ds_write2_b32 v5, v15, v24 offset0:12 offset1:13
	v_bitop3_b32 v15, v48, s19, v48 bitop3:0xc
	ds_write2_b32 v5, v21, v15 offset0:28 offset1:29
	v_and_b32_e32 v15, 0x7fffff80, v42
	v_bitop3_b32 v21, v42, s19, v42 bitop3:0xcf
	v_cmp_gt_i32_e32 vcc, 0, v42
	v_and_b32_e32 v24, 0x7fffff80, v43
	s_nop 0
	v_cndmask_b32_e32 v25, v21, v15, vcc
	v_and_b32_e32 v15, 0x7fffff80, v47
	v_bitop3_b32 v21, v47, s19, v47 bitop3:0xcf
	v_cmp_gt_i32_e32 vcc, 0, v47
	s_nop 1
	v_cndmask_b32_e32 v41, v21, v15, vcc
	v_cmp_gt_i32_e32 vcc, 0, v43
	v_bitop3_b32 v21, v47, s19, v47 bitop3:0xc
	v_bitop3_b32 v15, v42, s19, v42 bitop3:0xc
	v_cndmask_b32_e32 v26, v26, v24, vcc
	v_and_b32_e32 v24, 0x7fffff80, v46
	v_cmp_gt_i32_e32 vcc, 0, v46
	v_pk_add_f32 v[34:35], v[20:21], v[34:35] op_sel_hi:[0,1]
	s_nop 0
	v_cndmask_b32_e32 v40, v33, v24, vcc
	v_bitop3_b32 v24, v43, s19, v43 bitop3:0xc
	v_pk_add_f32 v[42:43], v[20:21], v[0:1] op_sel_hi:[0,1]
	ds_write2_b32 v5, v15, v24 offset0:14 offset1:15
	v_not_b32_e32 v15, v43
	v_or_b32_e32 v33, 0x80000000, v43
	v_cmp_gt_i32_e32 vcc, 0, v43
	v_or_b32_e32 v43, 0x80000000, v42
	v_bitop3_b32 v24, v46, s19, v46 bitop3:0xc
	v_cndmask_b32_e32 v15, v33, v15, vcc
	v_or_b32_e32 v33, 0xff, v15
	v_not_b32_e32 v15, v42
	v_cmp_gt_i32_e32 vcc, 0, v42
	ds_write2_b32 v5, v21, v24 offset0:30 offset1:31
	s_waitcnt lgkmcnt(0)
; #define CK(i, j) ((f2key(va[i] + vb[j]) & ~255u) | (unsigned)(255 - (16 * (i) + (j))))
; __device__ __forceinline__ void peer_tile(const Args& A, LAS unsigned char* lds, int tile) {
;     ...
;             unsigned Lf[16], Bt[16];
; #pragma unroll
;             for (int j = 0; j < 16; ++j) Lf[j] = CK(0, j);
; #pragma unroll
;             for (int j = 0; j < 8; ++j) Bt[j] = CK(1, j);
; #pragma unroll
;             for (int j = 0; j < 5; ++j) Bt[8 + j] = CK(2, j);
	s_nop 0
	v_cndmask_b32_e32 v15, v43, v15, vcc
	v_and_b32_e32 v15, 0xffffff00, v15
	v_pk_add_f32 v[42:43], v[20:21], v[2:3] op_sel_hi:[0,1]
	v_or_b32_e32 v44, 0xfe, v15
	v_not_b32_e32 v15, v43
	v_or_b32_e32 v45, 0x80000000, v43
	v_cmp_gt_i32_e32 vcc, 0, v43
	v_or_b32_e32 v43, 0x80000000, v42
	s_nop 0
	v_cndmask_b32_e32 v15, v45, v15, vcc
	v_and_b32_e32 v15, 0xffffff00, v15
	v_or_b32_e32 v45, 0xfd, v15
	v_not_b32_e32 v15, v42
	v_cmp_gt_i32_e32 vcc, 0, v42
	s_nop 1
	v_cndmask_b32_e32 v15, v43, v15, vcc
	v_and_b32_e32 v15, 0xffffff00, v15
	v_pk_add_f32 v[42:43], v[20:21], v[16:17] op_sel_hi:[0,1]
	v_or_b32_e32 v46, 0xfc, v15
	v_not_b32_e32 v15, v43
	v_or_b32_e32 v47, 0x80000000, v43
	v_cmp_gt_i32_e32 vcc, 0, v43
	v_or_b32_e32 v43, 0x80000000, v42
	s_nop 0
	v_cndmask_b32_e32 v15, v47, v15, vcc
	v_and_b32_e32 v15, 0xffffff00, v15
	v_or_b32_e32 v47, 0xfb, v15
	v_not_b32_e32 v15, v42
	v_cmp_gt_i32_e32 vcc, 0, v42
	s_nop 1
	v_cndmask_b32_e32 v15, v43, v15, vcc
	v_and_b32_e32 v15, 0xffffff00, v15
	v_pk_add_f32 v[42:43], v[20:21], v[22:23] op_sel_hi:[0,1]
	v_or_b32_e32 v48, 0xfa, v15
	v_not_b32_e32 v15, v43
	v_or_b32_e32 v49, 0x80000000, v43
	v_cmp_gt_i32_e32 vcc, 0, v43
	v_pk_add_f32 v[22:23], v[18:19], v[22:23] op_sel_hi:[0,1]
	s_nop 0
	v_cndmask_b32_e32 v15, v49, v15, vcc
	v_and_b32_e32 v15, 0xffffff00, v15
	v_or_b32_e32 v43, 0xf9, v15
	v_not_b32_e32 v15, v42
	v_or_b32_e32 v49, 0x80000000, v42
	v_cmp_gt_i32_e32 vcc, 0, v42
	s_nop 1
	v_cndmask_b32_e32 v15, v49, v15, vcc
	v_and_b32_e32 v15, 0xffffff00, v15
	v_or_b32_e32 v42, 0xf8, v15
	v_not_b32_e32 v15, v35
	v_or_b32_e32 v49, 0x80000000, v35
	v_cmp_gt_i32_e32 vcc, 0, v35
	v_or_b32_e32 v35, 0x80000000, v34
	s_nop 0
	v_cndmask_b32_e32 v15, v49, v15, vcc
	v_and_b32_e32 v15, 0xffffff00, v15
	v_or_b32_e32 v49, 0xf7, v15
	v_not_b32_e32 v15, v34
	v_cmp_gt_i32_e32 vcc, 0, v34
	s_nop 1
	v_cndmask_b32_e32 v15, v35, v15, vcc
	v_and_b32_e32 v15, 0xffffff00, v15
	v_pk_add_f32 v[34:35], v[20:21], v[36:37] op_sel_hi:[0,1]
	v_or_b32_e32 v50, 0xf6, v15
	v_not_b32_e32 v15, v35
	v_or_b32_e32 v36, 0x80000000, v35
	v_cmp_gt_i32_e32 vcc, 0, v35
	v_or_b32_e32 v35, 0x80000000, v34
	s_nop 0
	v_cndmask_b32_e32 v15, v36, v15, vcc
	v_and_b32_e32 v15, 0xffffff00, v15
	v_or_b32_e32 v36, 0xf5, v15
	v_not_b32_e32 v15, v34
	v_cmp_gt_i32_e32 vcc, 0, v34
	s_nop 1
	v_cndmask_b32_e32 v15, v35, v15, vcc
	v_and_b32_e32 v15, 0xffffff00, v15
	v_pk_add_f32 v[34:35], v[20:21], v[38:39] op_sel_hi:[0,1]
	v_or_b32_e32 v37, 0xf4, v15
	v_not_b32_e32 v15, v35
	v_or_b32_e32 v38, 0x80000000, v35
	v_cmp_gt_i32_e32 vcc, 0, v35
	v_or_b32_e32 v35, 0x80000000, v34
	s_nop 0
	v_cndmask_b32_e32 v15, v38, v15, vcc
	v_and_b32_e32 v15, 0xffffff00, v15
	v_or_b32_e32 v38, 0xf3, v15
	v_not_b32_e32 v15, v34
	v_cmp_gt_i32_e32 vcc, 0, v34
	s_nop 1
	v_cndmask_b32_e32 v15, v35, v15, vcc
	v_and_b32_e32 v15, 0xffffff00, v15
	v_pk_add_f32 v[34:35], v[20:21], v[40:41] op_sel_hi:[0,1]
	v_or_b32_e32 v39, 0xf2, v15
	v_not_b32_e32 v15, v35
	v_or_b32_e32 v20, 0x80000000, v35
	v_cmp_gt_i32_e32 vcc, 0, v35
	v_or_b32_e32 v35, 0x80000000, v34
	s_nop 0
	v_cndmask_b32_e32 v15, v20, v15, vcc
	v_and_b32_e32 v15, 0xffffff00, v15
	v_or_b32_e32 v20, 0xf1, v15
	v_not_b32_e32 v15, v34
	v_cmp_gt_i32_e32 vcc, 0, v34
	s_nop 1
	v_cndmask_b32_e32 v15, v35, v15, vcc
	v_and_b32_e32 v15, 0xffffff00, v15
	v_pk_add_f32 v[34:35], v[18:19], v[0:1] op_sel_hi:[0,1]
	v_or_b32_e32 v40, 0xf0, v15
	v_not_b32_e32 v15, v35
	v_or_b32_e32 v41, 0x80000000, v35
	v_cmp_gt_i32_e32 vcc, 0, v35
	v_or_b32_e32 v35, 0x80000000, v34
	s_nop 0
	v_cndmask_b32_e32 v15, v41, v15, vcc
	v_and_b32_e32 v15, 0xffffff00, v15
	v_or_b32_e32 v41, 0xef, v15
	v_not_b32_e32 v15, v34
	v_cmp_gt_i32_e32 vcc, 0, v34
	s_nop 1
	v_cndmask_b32_e32 v15, v35, v15, vcc
	v_and_b32_e32 v15, 0xffffff00, v15
	v_pk_add_f32 v[34:35], v[18:19], v[2:3] op_sel_hi:[0,1]
	v_or_b32_e32 v51, 0xee, v15
	v_not_b32_e32 v15, v35
	v_or_b32_e32 v52, 0x80000000, v35
	v_cmp_gt_i32_e32 vcc, 0, v35
	v_or_b32_e32 v35, 0x80000000, v34
	s_nop 0
	v_cndmask_b32_e32 v15, v52, v15, vcc
	v_and_b32_e32 v15, 0xffffff00, v15
	v_or_b32_e32 v52, 0xed, v15
	v_not_b32_e32 v15, v34
	v_cmp_gt_i32_e32 vcc, 0, v34
	s_nop 1
	v_cndmask_b32_e32 v15, v35, v15, vcc
	v_and_b32_e32 v15, 0xffffff00, v15
	v_pk_add_f32 v[34:35], v[18:19], v[16:17] op_sel_hi:[0,1]
	v_or_b32_e32 v53, 0xec, v15
	v_not_b32_e32 v15, v35
	v_or_b32_e32 v16, 0x80000000, v35
	v_cmp_gt_i32_e32 vcc, 0, v35
	s_nop 1
	v_cndmask_b32_e32 v15, v16, v15, vcc
	v_and_b32_e32 v15, 0xffffff00, v15
	v_or_b32_e32 v35, 0xeb, v15
	v_not_b32_e32 v15, v34
	v_or_b32_e32 v16, 0x80000000, v34
	v_cmp_gt_i32_e32 vcc, 0, v34
	s_nop 1
	v_cndmask_b32_e32 v15, v16, v15, vcc
	v_and_b32_e32 v15, 0xffffff00, v15
	v_or_b32_e32 v34, 0xea, v15
	v_not_b32_e32 v15, v23
	v_or_b32_e32 v16, 0x80000000, v23
	v_cmp_gt_i32_e32 vcc, 0, v23
	s_nop 1
	v_cndmask_b32_e32 v15, v16, v15, vcc
	v_and_b32_e32 v15, 0xffffff00, v15
	v_or_b32_e32 v18, 0xe9, v15
	v_not_b32_e32 v15, v22
	v_or_b32_e32 v16, 0x80000000, v22
	v_cmp_gt_i32_e32 vcc, 0, v22
	v_pk_add_f32 v[22:23], v[12:13], v[0:1] op_sel_hi:[0,1]
	s_nop 0
	v_cndmask_b32_e32 v15, v16, v15, vcc
	v_and_b32_e32 v15, 0xffffff00, v15
	v_or_b32_e32 v54, 0xe8, v15
	v_not_b32_e32 v15, v23
	v_or_b32_e32 v16, 0x80000000, v23
	v_cmp_gt_i32_e32 vcc, 0, v23
	s_nop 1
	v_cndmask_b32_e32 v15, v16, v15, vcc
	v_and_b32_e32 v15, 0xffffff00, v15
	v_or_b32_e32 v55, 0xdf, v15
	v_not_b32_e32 v15, v22
	v_or_b32_e32 v16, 0x80000000, v22
	v_cmp_gt_i32_e32 vcc, 0, v22
	v_pk_add_f32 v[22:23], v[12:13], v[2:3] op_sel_hi:[0,1]
	v_lshl_add_u32 v13, v13, 10, s35
	v_cndmask_b32_e32 v15, v16, v15, vcc
	v_and_b32_e32 v15, 0xffffff00, v15
; #define CK(i, j) ((f2key(va[i] + vb[j]) & ~255u) | (unsigned)(255 - (16 * (i) + (j))))
; __device__ __forceinline__ void peer_tile(const Args& A, LAS unsigned char* lds, int tile) {
;     ...
;             for (int j = 0; j < 8; ++j) Bt[j] = CK(1, j);
; #pragma unroll
;             for (int j = 0; j < 5; ++j) Bt[8 + j] = CK(2, j);
; #pragma unroll
;             for (int j = 0; j < 3; ++j) Bt[13 + j] = CK(4, j);
;             sort16_desc(Bt); merge16(Lf, Bt);
	v_or_b32_e32 v56, 0xde, v15
	v_not_b32_e32 v15, v23
	v_or_b32_e32 v16, 0x80000000, v23
	v_cmp_gt_i32_e32 vcc, 0, v23
	s_nop 1
	v_cndmask_b32_e32 v15, v16, v15, vcc
	v_and_b32_e32 v15, 0xffffff00, v15
	v_or_b32_e32 v23, 0xdd, v15
	v_not_b32_e32 v15, v22
	v_or_b32_e32 v16, 0x80000000, v22
	v_cmp_gt_i32_e32 vcc, 0, v22
	s_nop 1
	v_cndmask_b32_e32 v15, v16, v15, vcc
	v_and_b32_e32 v15, 0xffffff00, v15
	v_or_b32_e32 v22, 0xdc, v15
	v_mov_b32_e32 v15, v12
	v_mov_b32_e32 v16, v1
	v_pk_add_f32 v[16:17], v[14:15], v[16:17]
	s_nop 0
	v_not_b32_e32 v12, v17
	v_or_b32_e32 v15, 0x80000000, v17
	v_cmp_gt_i32_e32 vcc, 0, v17
	v_or_b32_e32 v17, 0x80000000, v16
	s_nop 0
	v_cndmask_b32_e32 v12, v15, v12, vcc
	v_not_b32_e32 v15, v16
	v_cmp_gt_i32_e32 vcc, 0, v16
	v_mov_b32_e32 v16, v3
	v_and_b32_e32 v12, 0xffffff00, v12
	v_cndmask_b32_e32 v15, v17, v15, vcc
	v_and_b32_e32 v15, 0xffffff00, v15
	v_mov_b32_e32 v17, v0
	v_or_b32_e32 v57, 0xbf, v15
	v_pk_add_f32 v[14:15], v[14:15], v[16:17] op_sel_hi:[0,1]
	v_not_b32_e32 v16, v15
	v_or_b32_e32 v17, 0x80000000, v15
	v_cmp_gt_i32_e32 vcc, 0, v15
	v_or_b32_e32 v12, 0xdb, v12
	v_pk_add_f32 v[2:3], v[4:5], v[2:3] op_sel_hi:[0,1]
	v_cndmask_b32_e32 v15, v17, v16, vcc
	v_not_b32_e32 v16, v14
	v_or_b32_e32 v17, 0x80000000, v14
	v_cmp_gt_i32_e32 vcc, 0, v14
	v_and_b32_e32 v15, 0xffffff00, v15
	v_or_b32_e32 v15, 0xbe, v15
	v_cndmask_b32_e32 v14, v17, v16, vcc
	v_and_b32_e32 v14, 0xffffff00, v14
	v_or_b32_e32 v14, 0xbd, v14
	v_max_u32_e32 v16, v41, v51
	v_min_u32_e32 v17, v41, v51
	v_max_u32_e32 v41, v53, v52
	v_min_u32_e32 v51, v53, v52
	v_max_u32_e32 v52, v35, v34
	v_min_u32_e32 v34, v35, v34
	v_max_u32_e32 v35, v54, v18
	v_min_u32_e32 v18, v54, v18
	v_max_u32_e32 v53, v55, v56
	v_min_u32_e32 v54, v55, v56
	v_max_u32_e32 v55, v22, v23
	v_min_u32_e32 v22, v22, v23
	v_max_u32_e32 v23, v12, v57
	v_min_u32_e32 v12, v12, v57
	v_max_u32_e32 v56, v14, v15
	v_min_u32_e32 v14, v14, v15
	v_max_u32_e32 v15, v16, v51
	v_min_u32_e32 v16, v16, v51
	v_max_u32_e32 v51, v17, v41
	v_min_u32_e32 v17, v17, v41
	v_max_u32_e32 v41, v18, v52
	v_min_u32_e32 v18, v18, v52
	v_max_u32_e32 v52, v35, v34
	v_min_u32_e32 v34, v35, v34
	v_max_u32_e32 v35, v53, v22
	v_min_u32_e32 v22, v53, v22
	v_max_u32_e32 v53, v54, v55
	v_min_u32_e32 v54, v54, v55
	v_max_u32_e32 v55, v14, v23
	v_min_u32_e32 v14, v14, v23
	v_max_u32_e32 v23, v56, v12
	v_min_u32_e32 v12, v56, v12
	v_max_u32_e32 v56, v15, v51
	v_min_u32_e32 v15, v15, v51
	v_max_u32_e32 v51, v16, v17
	v_min_u32_e32 v16, v16, v17
	v_max_u32_e32 v17, v34, v18
	v_min_u32_e32 v18, v34, v18
	v_max_u32_e32 v34, v52, v41
	v_min_u32_e32 v41, v52, v41
	v_max_u32_e32 v52, v35, v53
	v_min_u32_e32 v35, v35, v53
	v_max_u32_e32 v53, v22, v54
	v_min_u32_e32 v22, v22, v54
	v_max_u32_e32 v54, v12, v14
	v_min_u32_e32 v12, v12, v14
	v_max_u32_e32 v14, v23, v55
	v_min_u32_e32 v23, v23, v55
	v_max_u32_e32 v55, v56, v18
	v_min_u32_e32 v18, v56, v18
	v_max_u32_e32 v56, v15, v17
	v_min_u32_e32 v15, v15, v17
	v_max_u32_e32 v17, v51, v41
	v_min_u32_e32 v41, v51, v41
	v_max_u32_e32 v51, v16, v34
	v_min_u32_e32 v16, v16, v34
	v_max_u32_e32 v34, v12, v52
	v_min_u32_e32 v12, v12, v52
	v_max_u32_e32 v52, v54, v35
	v_min_u32_e32 v35, v54, v35
	v_max_u32_e32 v54, v23, v53
	v_min_u32_e32 v23, v23, v53
	v_max_u32_e32 v53, v14, v22
	v_min_u32_e32 v14, v14, v22
	v_max_u32_e32 v22, v55, v17
	v_min_u32_e32 v17, v55, v17
	v_max_u32_e32 v55, v56, v51
	v_min_u32_e32 v51, v56, v51
	v_max_u32_e32 v56, v18, v41
	v_min_u32_e32 v18, v18, v41
	v_max_u32_e32 v41, v15, v16
	v_min_u32_e32 v15, v15, v16
	v_max_u32_e32 v16, v23, v12
	v_min_u32_e32 v12, v23, v12
	v_max_u32_e32 v23, v14, v35
	v_min_u32_e32 v14, v14, v35
	v_max_u32_e32 v35, v54, v34
	v_min_u32_e32 v34, v54, v34
	v_max_u32_e32 v54, v53, v52
	v_min_u32_e32 v52, v53, v52
	v_max_u32_e32 v53, v22, v55
	v_min_u32_e32 v22, v22, v55
	v_max_u32_e32 v55, v17, v51
	v_min_u32_e32 v17, v17, v51
	v_max_u32_e32 v51, v56, v41
	v_min_u32_e32 v41, v56, v41
	v_max_u32_e32 v56, v18, v15
	v_min_u32_e32 v15, v18, v15
	v_max_u32_e32 v18, v14, v12
	v_min_u32_e32 v12, v14, v12
	v_max_u32_e32 v14, v23, v16
	v_min_u32_e32 v16, v23, v16
	v_max_u32_e32 v23, v52, v34
	v_min_u32_e32 v34, v52, v34
	v_max_u32_e32 v52, v54, v35
	v_min_u32_e32 v35, v54, v35
	v_max_u32_e32 v54, v53, v12
	v_min_u32_e32 v12, v53, v12
	v_max_u32_e32 v53, v22, v18
	v_min_u32_e32 v18, v22, v18
	v_max_u32_e32 v22, v55, v16
	v_min_u32_e32 v16, v55, v16
	v_max_u32_e32 v55, v17, v14
	v_min_u32_e32 v14, v17, v14
	v_max_u32_e32 v17, v51, v34
	v_min_u32_e32 v34, v51, v34
	v_max_u32_e32 v51, v41, v23
	v_min_u32_e32 v23, v41, v23
	v_max_u32_e32 v41, v56, v35
	v_min_u32_e32 v35, v56, v35
	v_max_u32_e32 v56, v15, v52
	v_min_u32_e32 v15, v15, v52
	v_max_u32_e32 v52, v54, v17
	v_min_u32_e32 v17, v54, v17
	v_max_u32_e32 v54, v53, v51
	v_min_u32_e32 v51, v53, v51
	v_max_u32_e32 v53, v22, v41
	v_min_u32_e32 v22, v22, v41
	v_max_u32_e32 v41, v55, v56
	v_min_u32_e32 v55, v55, v56
	v_max_u32_e32 v56, v12, v34
	v_min_u32_e32 v12, v12, v34
	v_max_u32_e32 v34, v18, v23
	v_min_u32_e32 v18, v18, v23
	v_max_u32_e32 v23, v16, v35
	v_min_u32_e32 v16, v16, v35
	v_max_u32_e32 v35, v14, v15
	v_min_u32_e32 v14, v14, v15
	v_max_u32_e32 v15, v52, v53
	v_min_u32_e32 v52, v52, v53
	v_max_u32_e32 v53, v54, v41
	v_min_u32_e32 v41, v54, v41
	v_max_u32_e32 v54, v17, v22
	v_min_u32_e32 v17, v17, v22
	v_max_u32_e32 v22, v51, v55
	v_min_u32_e32 v51, v51, v55
	v_max_u32_e32 v55, v56, v23
	v_min_u32_e32 v23, v56, v23
	v_max_u32_e32 v56, v34, v35
	v_min_u32_e32 v34, v34, v35
	v_max_u32_e32 v35, v12, v16
	v_min_u32_e32 v12, v12, v16
	v_max_u32_e32 v16, v18, v14
	v_min_u32_e32 v14, v18, v14
; #define CK(i, j) ((f2key(va[i] + vb[j]) & ~255u) | (unsigned)(255 - (16 * (i) + (j))))
; __device__ __forceinline__ void peer_tile(const Args& A, LAS unsigned char* lds, int tile) {
;     ...
;             sort16_desc(Bt); merge16(Lf, Bt);
; #pragma unroll
;             for (int j = 0; j < 4; ++j) Bt[j] = CK(3, j);
;             Bt[4] = CK(5, 0); Bt[5] = CK(5, 1); Bt[6] = CK(6, 0); Bt[7] = CK(6, 1); Bt[8] = CK(7, 0); Bt[9] = CK(7, 1);
;             Bt[10] = CK(8, 0); Bt[11] = CK(9, 0); Bt[12] = CK(10, 0); Bt[13] = CK(11, 0); Bt[14] = CK(12, 0); Bt[15] = CK(13, 0);
	v_min_u32_e32 v18, v15, v53
	v_min_u32_e32 v57, v52, v41
	v_min_u32_e32 v58, v54, v22
	v_min_u32_e32 v59, v17, v51
	v_min_u32_e32 v60, v55, v56
	v_min_u32_e32 v61, v23, v34
	v_min_u32_e32 v62, v35, v16
	v_min_u32_e32 v63, v12, v14
	v_max_u32_e32 v33, v33, v63
	v_max3_u32 v12, v44, v12, v14
	v_max_u32_e32 v14, v45, v62
	v_max3_u32 v16, v46, v35, v16
	v_max_u32_e32 v35, v47, v61
	v_max3_u32 v23, v48, v23, v34
	v_max_u32_e32 v34, v43, v60
	v_max3_u32 v42, v42, v55, v56
	v_max_u32_e32 v43, v49, v59
	v_max3_u32 v17, v50, v17, v51
	v_max_u32_e32 v36, v36, v58
	v_max3_u32 v22, v37, v54, v22
	v_max_u32_e32 v37, v38, v57
	v_max3_u32 v38, v39, v52, v41
	v_max_u32_e32 v18, v20, v18
	v_max3_u32 v15, v40, v15, v53
	v_max_u32_e32 v20, v33, v43
	v_min_u32_e32 v33, v33, v43
	v_max_u32_e32 v39, v12, v17
	v_min_u32_e32 v12, v12, v17
	v_max_u32_e32 v17, v14, v36
	v_min_u32_e32 v14, v14, v36
	v_max_u32_e32 v36, v16, v22
	v_min_u32_e32 v16, v16, v22
	v_max_u32_e32 v22, v35, v37
	v_min_u32_e32 v35, v35, v37
	v_max_u32_e32 v37, v23, v38
	v_min_u32_e32 v23, v23, v38
	v_max_u32_e32 v38, v34, v18
	v_min_u32_e32 v18, v34, v18
	v_max_u32_e32 v34, v42, v15
	v_min_u32_e32 v15, v42, v15
	v_max_u32_e32 v40, v20, v22
	v_min_u32_e32 v20, v20, v22
	v_max_u32_e32 v22, v39, v37
	v_min_u32_e32 v37, v39, v37
	v_max_u32_e32 v39, v17, v38
	v_min_u32_e32 v17, v17, v38
	v_max_u32_e32 v38, v36, v34
	v_min_u32_e32 v34, v36, v34
	v_max_u32_e32 v36, v33, v35
	v_min_u32_e32 v33, v33, v35
	v_max_u32_e32 v35, v12, v23
	v_min_u32_e32 v12, v12, v23
	v_max_u32_e32 v23, v14, v18
	v_min_u32_e32 v14, v14, v18
	v_max_u32_e32 v18, v16, v15
	v_min_u32_e32 v15, v16, v15
	v_max_u32_e32 v16, v40, v39
	v_min_u32_e32 v39, v40, v39
	v_max_u32_e32 v40, v22, v38
	v_min_u32_e32 v22, v22, v38
	v_max_u32_e32 v38, v20, v17
	v_min_u32_e32 v17, v20, v17
	v_max_u32_e32 v20, v37, v34
	v_min_u32_e32 v34, v37, v34
	v_max_u32_e32 v37, v36, v23
	v_min_u32_e32 v23, v36, v23
	v_max_u32_e32 v36, v35, v18
	v_min_u32_e32 v18, v35, v18
	v_max_u32_e32 v35, v33, v14
	v_min_u32_e32 v33, v33, v14
	v_max_u32_e32 v41, v12, v15
	v_min_u32_e32 v12, v12, v15
	v_pk_add_f32 v[14:15], v[4:5], v[0:1] op_sel_hi:[0,1]
	v_not_b32_e32 v50, v15
	v_or_b32_e32 v51, 0x80000000, v15
	v_cmp_gt_i32_e32 vcc, 0, v15
	v_not_b32_e32 v4, v3
	v_min_u32_e32 v42, v16, v40
	v_cndmask_b32_e32 v15, v51, v50, vcc
	v_not_b32_e32 v50, v14
	v_or_b32_e32 v51, 0x80000000, v14
	v_cmp_gt_i32_e32 vcc, 0, v14
	v_and_b32_e32 v15, 0xffffff00, v15
	v_or_b32_e32 v15, 0xcf, v15
	v_cndmask_b32_e32 v14, v51, v50, vcc
	v_or_b32_e32 v50, 0x80000000, v3
	v_cmp_gt_i32_e32 vcc, 0, v3
	v_and_b32_e32 v14, 0xffffff00, v14
	v_or_b32_e32 v14, 0xce, v14
	v_cndmask_b32_e32 v3, v50, v4, vcc
	v_and_b32_e32 v3, 0xffffff00, v3
	v_or_b32_e32 v4, 0xcd, v3
	v_not_b32_e32 v3, v2
	v_or_b32_e32 v50, 0x80000000, v2
	v_cmp_gt_i32_e32 vcc, 0, v2
	v_min_u32_e32 v43, v39, v22
	v_min_u32_e32 v44, v38, v20
	v_cndmask_b32_e32 v2, v50, v3, vcc
	v_and_b32_e32 v2, 0xffffff00, v2
	v_or_b32_e32 v50, 0xcc, v2
	v_pk_add_f32 v[2:3], v[10:11], v[0:1] op_sel_hi:[0,1]
	v_not_b32_e32 v10, v3
	v_or_b32_e32 v51, 0x80000000, v3
	v_cmp_gt_i32_e32 vcc, 0, v3
	v_min_u32_e32 v45, v17, v34
	v_min_u32_e32 v46, v37, v36
	v_cndmask_b32_e32 v3, v51, v10, vcc
	v_and_b32_e32 v3, 0xffffff00, v3
	v_or_b32_e32 v10, 0xaf, v3
	v_not_b32_e32 v3, v2
	v_or_b32_e32 v51, 0x80000000, v2
	v_cmp_gt_i32_e32 vcc, 0, v2
	v_min_u32_e32 v47, v23, v18
	v_min_u32_e32 v48, v35, v41
	v_cndmask_b32_e32 v2, v51, v3, vcc
	v_and_b32_e32 v2, 0xffffff00, v2
	v_or_b32_e32 v51, 0xae, v2
	v_pk_add_f32 v[2:3], v[8:9], v[0:1] op_sel_hi:[0,1]
	v_not_b32_e32 v8, v3
	v_or_b32_e32 v52, 0x80000000, v3
	v_cmp_gt_i32_e32 vcc, 0, v3
	v_min_u32_e32 v49, v33, v12
	v_lshlrev_b32_e32 v11, 9, v11
	v_cndmask_b32_e32 v3, v52, v8, vcc
	v_and_b32_e32 v3, 0xffffff00, v3
	v_or_b32_e32 v8, 0x9f, v3
	v_not_b32_e32 v3, v2
	v_or_b32_e32 v52, 0x80000000, v2
	v_cmp_gt_i32_e32 vcc, 0, v2
	s_nop 1
	v_cndmask_b32_e32 v2, v52, v3, vcc
	v_and_b32_e32 v2, 0xffffff00, v2
	v_or_b32_e32 v52, 0x9e, v2
	v_pk_add_f32 v[2:3], v[6:7], v[0:1] op_sel_hi:[0,1]
	v_not_b32_e32 v0, v3
	v_or_b32_e32 v6, 0x80000000, v3
	v_cmp_gt_i32_e32 vcc, 0, v3
	v_not_b32_e32 v3, v2
	s_nop 0
	v_cndmask_b32_e32 v0, v6, v0, vcc
	v_or_b32_e32 v6, 0x80000000, v2
	v_cmp_gt_i32_e32 vcc, 0, v2
	v_and_b32_e32 v0, 0xffffff00, v0
	v_or_b32_e32 v0, 0x8f, v0
	v_cndmask_b32_e32 v2, v6, v3, vcc
	v_add_f32_e32 v3, v27, v1
	v_not_b32_e32 v6, v3
	v_or_b32_e32 v27, 0x80000000, v3
	v_cmp_gt_i32_e32 vcc, 0, v3
	v_and_b32_e32 v2, 0xffffff00, v2
	v_or_b32_e32 v2, 0x8e, v2
	v_cndmask_b32_e32 v3, v27, v6, vcc
	v_add_f32_e32 v6, v28, v1
	v_not_b32_e32 v27, v6
	v_or_b32_e32 v28, 0x80000000, v6
	v_cmp_gt_i32_e32 vcc, 0, v6
	v_and_b32_e32 v3, 0xffffff00, v3
	v_or_b32_e32 v3, 0x7f, v3
	v_cndmask_b32_e32 v6, v28, v27, vcc
	v_add_f32_e32 v27, v29, v1
	v_not_b32_e32 v28, v27
	v_or_b32_e32 v29, 0x80000000, v27
	v_cmp_gt_i32_e32 vcc, 0, v27
	v_and_b32_e32 v6, 0xffffff00, v6
	v_or_b32_e32 v6, 0x6f, v6
	v_cndmask_b32_e32 v27, v29, v28, vcc
	v_add_f32_e32 v28, v30, v1
	v_not_b32_e32 v29, v28
	v_or_b32_e32 v30, 0x80000000, v28
	v_cmp_gt_i32_e32 vcc, 0, v28
	v_and_b32_e32 v27, 0xffffff00, v27
	v_or_b32_e32 v27, 0x5f, v27
	v_cndmask_b32_e32 v28, v30, v29, vcc
	v_add_f32_e32 v29, v31, v1
	v_not_b32_e32 v30, v29
	v_or_b32_e32 v31, 0x80000000, v29
	v_cmp_gt_i32_e32 vcc, 0, v29
	v_and_b32_e32 v28, 0xffffff00, v28
	v_or_b32_e32 v28, 0x4f, v28
	v_cndmask_b32_e32 v29, v31, v30, vcc
	v_add_f32_e32 v30, v32, v1
	v_not_b32_e32 v31, v30
	v_or_b32_e32 v32, 0x80000000, v30
	v_cmp_gt_i32_e32 vcc, 0, v30
	v_and_or_b32 v29, v29, s34, 63
	s_nop 0
	v_cndmask_b32_e32 v30, v32, v31, vcc
; __device__ __forceinline__ void peer_tile(const Args& A, LAS unsigned char* lds, int tile) {
;     ...
;             sort16_desc(Bt); merge16(Lf, Bt);
	v_and_or_b32 v30, v30, s34, 47
	v_max_u32_e32 v31, v15, v14
	v_min_u32_e32 v14, v15, v14
	v_max_u32_e32 v15, v50, v4
	v_min_u32_e32 v4, v50, v4
	v_max_u32_e32 v32, v10, v51
	v_min_u32_e32 v10, v10, v51
	v_max_u32_e32 v50, v52, v8
	v_min_u32_e32 v8, v52, v8
	v_max_u32_e32 v51, v0, v2
	v_min_u32_e32 v0, v0, v2
	v_max_u32_e32 v2, v6, v3
	v_min_u32_e32 v3, v6, v3
	v_max_u32_e32 v6, v27, v28
	v_min_u32_e32 v27, v27, v28
	v_max_u32_e32 v28, v30, v29
	v_min_u32_e32 v29, v30, v29
	v_max_u32_e32 v30, v31, v4
	v_min_u32_e32 v4, v31, v4
	v_max_u32_e32 v31, v14, v15
	v_min_u32_e32 v14, v14, v15
	v_max_u32_e32 v15, v8, v32
	v_min_u32_e32 v8, v8, v32
	v_max_u32_e32 v32, v50, v10
	v_min_u32_e32 v10, v50, v10
	v_max_u32_e32 v50, v51, v3
	v_min_u32_e32 v3, v51, v3
	v_max_u32_e32 v51, v0, v2
	v_min_u32_e32 v0, v0, v2
	v_max_u32_e32 v2, v29, v6
	v_min_u32_e32 v6, v29, v6
	v_max_u32_e32 v29, v28, v27
	v_min_u32_e32 v27, v28, v27
	v_max_u32_e32 v28, v30, v31
	v_min_u32_e32 v30, v30, v31
	v_max_u32_e32 v31, v4, v14
	v_min_u32_e32 v4, v4, v14
	v_max_u32_e32 v14, v10, v8
	v_min_u32_e32 v8, v10, v8
	v_max_u32_e32 v10, v32, v15
	v_min_u32_e32 v15, v32, v15
	v_max_u32_e32 v32, v50, v51
	v_min_u32_e32 v50, v50, v51
	v_max_u32_e32 v51, v3, v0
	v_min_u32_e32 v0, v3, v0
	v_max_u32_e32 v3, v27, v6
	v_min_u32_e32 v6, v27, v6
	v_max_u32_e32 v27, v29, v2
	v_min_u32_e32 v2, v29, v2
	v_max_u32_e32 v29, v28, v8
	v_min_u32_e32 v8, v28, v8
	v_max_u32_e32 v28, v30, v14
	v_min_u32_e32 v14, v30, v14
	v_max_u32_e32 v30, v31, v15
	v_min_u32_e32 v15, v31, v15
	v_max_u32_e32 v31, v4, v10
	v_min_u32_e32 v4, v4, v10
	v_max_u32_e32 v10, v6, v32
	v_min_u32_e32 v6, v6, v32
	v_max_u32_e32 v32, v3, v50
	v_min_u32_e32 v3, v3, v50
	v_max_u32_e32 v50, v2, v51
	v_min_u32_e32 v2, v2, v51
	v_max_u32_e32 v51, v27, v0
	v_min_u32_e32 v0, v27, v0
	v_max_u32_e32 v27, v29, v30
	v_min_u32_e32 v29, v29, v30
	v_max_u32_e32 v30, v28, v31
	v_min_u32_e32 v28, v28, v31
	v_max_u32_e32 v31, v8, v15
	v_min_u32_e32 v8, v8, v15
	v_max_u32_e32 v15, v14, v4
	v_min_u32_e32 v4, v14, v4
	v_max_u32_e32 v14, v2, v6
	v_min_u32_e32 v2, v2, v6
	v_max_u32_e32 v6, v0, v3
	v_min_u32_e32 v0, v0, v3
	v_max_u32_e32 v3, v50, v10
	v_min_u32_e32 v10, v50, v10
	v_max_u32_e32 v50, v51, v32
	v_min_u32_e32 v32, v51, v32
	v_max_u32_e32 v51, v27, v30
	v_min_u32_e32 v27, v27, v30
	v_max_u32_e32 v30, v29, v28
	v_min_u32_e32 v28, v29, v28
	v_max_u32_e32 v29, v31, v15
	v_min_u32_e32 v15, v31, v15
	v_max_u32_e32 v31, v8, v4
	v_min_u32_e32 v4, v8, v4
	v_max_u32_e32 v8, v0, v2
	v_min_u32_e32 v0, v0, v2
	v_max_u32_e32 v2, v6, v14
	v_min_u32_e32 v6, v6, v14
	v_max_u32_e32 v14, v32, v10
	v_min_u32_e32 v10, v32, v10
	v_max_u32_e32 v32, v50, v3
	v_min_u32_e32 v3, v50, v3
	v_max_u32_e32 v50, v51, v0
	v_min_u32_e32 v0, v51, v0
	v_max_u32_e32 v51, v27, v8
	v_min_u32_e32 v8, v27, v8
	v_max_u32_e32 v27, v30, v6
	v_min_u32_e32 v6, v30, v6
	v_max_u32_e32 v30, v28, v2
	v_min_u32_e32 v2, v28, v2
	v_max_u32_e32 v28, v29, v10
	v_min_u32_e32 v10, v29, v10
	v_max_u32_e32 v29, v15, v14
	v_min_u32_e32 v14, v15, v14
	v_max_u32_e32 v15, v31, v3
	v_min_u32_e32 v3, v31, v3
	v_max_u32_e32 v31, v4, v32
	v_min_u32_e32 v4, v4, v32
	v_max_u32_e32 v32, v50, v28
	v_min_u32_e32 v28, v50, v28
	v_max_u32_e32 v50, v51, v29
	v_min_u32_e32 v29, v51, v29
	v_max_u32_e32 v51, v27, v15
	v_min_u32_e32 v15, v27, v15
	v_max_u32_e32 v27, v30, v31
	v_min_u32_e32 v30, v30, v31
	v_max_u32_e32 v31, v0, v10
	v_min_u32_e32 v0, v0, v10
	v_max_u32_e32 v10, v8, v14
	v_min_u32_e32 v8, v8, v14
	v_max_u32_e32 v14, v6, v3
	v_min_u32_e32 v3, v6, v3
	v_max_u32_e32 v6, v2, v4
	v_min_u32_e32 v2, v2, v4
	v_max_u32_e32 v4, v32, v51
	v_min_u32_e32 v32, v32, v51
	v_max_u32_e32 v51, v50, v27
	v_min_u32_e32 v27, v50, v27
	v_max_u32_e32 v50, v28, v15
	v_min_u32_e32 v15, v28, v15
	v_max_u32_e32 v28, v29, v30
	v_min_u32_e32 v29, v29, v30
	v_max_u32_e32 v30, v31, v14
	v_min_u32_e32 v14, v31, v14
	v_max_u32_e32 v31, v10, v6
	v_min_u32_e32 v6, v10, v6
	v_max_u32_e32 v10, v0, v3
	v_min_u32_e32 v0, v0, v3
	v_max_u32_e32 v3, v8, v2
	v_min_u32_e32 v2, v8, v2
	v_min_u32_e32 v8, v4, v51
	v_min_u32_e32 v52, v32, v27
	v_min_u32_e32 v53, v50, v28
	v_min_u32_e32 v54, v15, v29
	v_min_u32_e32 v55, v30, v31
	v_min_u32_e32 v56, v14, v6
	v_min_u32_e32 v57, v10, v3
	v_min_u32_e32 v58, v0, v2
	v_max3_u32 v16, v16, v40, v58
	v_max3_u32 v0, v42, v0, v2
	v_max3_u32 v2, v39, v22, v57
	v_max3_u32 v3, v43, v10, v3
	v_max3_u32 v10, v38, v20, v56
	v_max3_u32 v6, v44, v14, v6
	v_max3_u32 v14, v17, v34, v55
	v_max3_u32 v17, v45, v30, v31
	v_max3_u32 v20, v37, v36, v54
	v_max3_u32 v15, v46, v15, v29
	v_max3_u32 v18, v23, v18, v53
	v_max3_u32 v22, v47, v50, v28
	v_max3_u32 v23, v35, v41, v52
	v_max3_u32 v27, v48, v32, v27
	v_max3_u32 v8, v33, v12, v8
	v_max3_u32 v4, v49, v4, v51
	v_max_u32_e32 v12, v16, v20
	v_min_u32_e32 v16, v16, v20
	v_max_u32_e32 v20, v0, v15
	v_min_u32_e32 v0, v0, v15
	v_max_u32_e32 v15, v2, v18
	v_min_u32_e32 v2, v2, v18
	v_max_u32_e32 v18, v3, v22
	v_min_u32_e32 v3, v3, v22
	v_max_u32_e32 v22, v10, v23
	v_min_u32_e32 v10, v10, v23
	v_max_u32_e32 v23, v6, v27
	v_min_u32_e32 v6, v6, v27
	v_max_u32_e32 v27, v14, v8
	v_min_u32_e32 v8, v14, v8
	v_max_u32_e32 v14, v17, v4
	v_min_u32_e32 v4, v17, v4
	v_max_u32_e32 v17, v12, v22
	v_min_u32_e32 v12, v12, v22
	v_max_u32_e32 v22, v20, v23
	v_min_u32_e32 v20, v20, v23
	v_max_u32_e32 v23, v15, v27
	v_min_u32_e32 v15, v15, v27
	v_max_u32_e32 v27, v18, v14
	v_min_u32_e32 v14, v18, v14
	v_max_u32_e32 v18, v16, v10
	v_min_u32_e32 v10, v16, v10
	v_max_u32_e32 v16, v0, v6
	v_min_u32_e32 v0, v0, v6
	v_max_u32_e32 v6, v2, v8
	v_min_u32_e32 v2, v2, v8
	v_max_u32_e32 v8, v3, v4
; __device__ __forceinline__ float key2f(unsigned k) { const unsigned u = (k & 0x80000000u) ? (k & 0x7fffffffu) : ~k; return __uint_as_float(u); }
; #define CE_DESC(a, b) do { const unsigned _mx = (a) > (b) ? (a) : (b), _mn = (a) > (b) ? (b) : (a); (a) = _mx; (b) = _mn; } while (0)
; #define CK(i, j) ((f2key(va[i] + vb[j]) & ~255u) | (unsigned)(255 - (16 * (i) + (j))))
; __device__ __forceinline__ void peer_tile(const Args& A, LAS unsigned char* lds, int tile) {
;     ...
;             { unsigned x0 = CK(14, 0), x1 = CK(15, 0);
; #pragma unroll
;               for (int i = 0; i < 16; ++i) CE_DESC(Lf[i], x0);
; #pragma unroll
;               for (int i = 0; i < 16; ++i) CE_DESC(Lf[i], x1); }
;     ...
;             float fv[16], den = 0.f; const float f0 = key2f(Lf[0] & ~255u);
; #pragma unroll
;             for (int k = 0; k < 16; ++k) { fv[k] = __expf(key2f(Lf[k] & ~255u) - f0); den += fv[k]; }
	v_min_u32_e32 v3, v3, v4
	v_max_u32_e32 v4, v17, v23
	v_min_u32_e32 v17, v17, v23
	v_max_u32_e32 v23, v22, v27
	v_min_u32_e32 v22, v22, v27
	v_max_u32_e32 v27, v12, v15
	v_min_u32_e32 v12, v12, v15
	v_max_u32_e32 v15, v20, v14
	v_min_u32_e32 v14, v20, v14
	v_max_u32_e32 v20, v18, v6
	v_min_u32_e32 v6, v18, v6
	v_max_u32_e32 v18, v16, v8
	v_min_u32_e32 v8, v16, v8
	v_max_u32_e32 v16, v10, v2
	v_min_u32_e32 v2, v10, v2
	v_max_u32_e32 v10, v0, v3
	v_min_u32_e32 v0, v0, v3
	v_max_u32_e32 v41, v2, v0
	v_min_u32_e32 v0, v2, v0
	v_add_f32_e32 v2, v25, v1
	v_not_b32_e32 v25, v2
	v_or_b32_e32 v42, 0x80000000, v2
	v_cmp_gt_i32_e32 vcc, 0, v2
	v_add_f32_e32 v1, v26, v1
	v_max_u32_e32 v3, v4, v23
	v_cndmask_b32_e32 v2, v42, v25, vcc
	v_and_or_b32 v2, v2, s34, 31
	v_not_b32_e32 v25, v1
	v_or_b32_e32 v26, 0x80000000, v1
	v_cmp_gt_i32_e32 vcc, 0, v1
	v_min_u32_e32 v28, v4, v23
	v_max_u32_e32 v29, v17, v22
	v_cndmask_b32_e32 v1, v26, v25, vcc
	v_max_u32_e32 v25, v3, v2
	v_min_u32_e32 v3, v3, v2
	v_min_u32_e32 v3, v28, v3
	v_min_u32_e32 v30, v17, v22
	v_med3_u32 v2, v4, v23, v2
	v_min_u32_e32 v23, v29, v3
	v_max_u32_e32 v31, v27, v15
	v_max_u32_e32 v4, v29, v3
	v_med3_u32 v3, v17, v22, v3
	v_min_u32_e32 v17, v30, v23
	v_min_u32_e32 v32, v27, v15
	v_min_u32_e32 v23, v31, v17
	v_max_u32_e32 v33, v12, v14
	v_max_u32_e32 v22, v31, v17
	v_med3_u32 v15, v27, v15, v17
	v_min_u32_e32 v17, v32, v23
	v_min_u32_e32 v34, v12, v14
	v_min_u32_e32 v26, v33, v17
	v_max_u32_e32 v35, v20, v18
	v_med3_u32 v12, v12, v14, v17
	v_min_u32_e32 v14, v34, v26
	v_min_u32_e32 v36, v20, v18
	v_min_u32_e32 v26, v35, v14
	v_max_u32_e32 v37, v6, v8
	v_max_u32_e32 v23, v33, v17
	v_max_u32_e32 v17, v35, v14
	v_med3_u32 v14, v20, v18, v14
	v_min_u32_e32 v18, v36, v26
	v_min_u32_e32 v38, v6, v8
	v_min_u32_e32 v26, v37, v18
	v_max_u32_e32 v39, v16, v10
	v_med3_u32 v6, v6, v8, v18
	v_min_u32_e32 v8, v38, v26
	v_min_u32_e32 v40, v16, v10
	v_min_u32_e32 v26, v39, v8
	v_and_or_b32 v1, v1, s34, 15
	v_max_u32_e32 v20, v37, v18
	v_max_u32_e32 v18, v39, v8
	v_med3_u32 v8, v16, v10, v8
	v_min_u32_e32 v10, v40, v26
	v_max_u32_e32 v26, v25, v1
	v_min_u32_e32 v1, v25, v1
	v_max_u32_e32 v25, v2, v1
	v_min_u32_e32 v1, v2, v1
	v_max_u32_e32 v2, v4, v1
	v_min_u32_e32 v1, v4, v1
	v_max_u32_e32 v4, v3, v1
	v_min_u32_e32 v1, v3, v1
	v_max_u32_e32 v3, v22, v1
	v_min_u32_e32 v1, v22, v1
	v_max_u32_e32 v22, v15, v1
	v_min_u32_e32 v1, v15, v1
	v_max_u32_e32 v15, v23, v1
	v_min_u32_e32 v1, v23, v1
	v_max_u32_e32 v23, v12, v1
	v_min_u32_e32 v1, v12, v1
	v_max_u32_e32 v12, v17, v1
	v_min_u32_e32 v1, v17, v1
	v_max_u32_e32 v17, v14, v1
	v_min_u32_e32 v1, v14, v1
	v_max_u32_e32 v14, v20, v1
	v_min_u32_e32 v1, v20, v1
	v_max_u32_e32 v20, v6, v1
	v_min_u32_e32 v1, v6, v1
	v_max_u32_e32 v6, v18, v1
	v_min_u32_e32 v1, v18, v1
	v_max_u32_e32 v16, v41, v10
	v_max_u32_e32 v18, v8, v1
	v_min_u32_e32 v1, v8, v1
	v_min_u32_e32 v10, v41, v10
	v_max_u32_e32 v8, v16, v1
	v_min_u32_e32 v1, v16, v1
	v_max3_u32 v10, v0, v10, v1
	v_and_b32_e32 v0, 0x7fffff00, v26
	v_bitop3_b32 v1, v26, s33, v26 bitop3:0xcf
	v_cmp_gt_i32_e32 vcc, 0, v26
	v_and_b32_e32 v16, 0x7fffff00, v25
	v_bitop3_b32 v27, v25, s33, v25 bitop3:0xcf
	v_cndmask_b32_e32 v0, v1, v0, vcc
	v_cmp_gt_i32_e32 vcc, 0, v25
	v_sub_f32_e32 v1, v0, v0
	v_bitop3_b32 v28, v2, s33, v2 bitop3:0xcf
	v_cndmask_b32_e32 v16, v27, v16, vcc
	v_and_b32_e32 v27, 0x7fffff00, v2
	v_cmp_gt_i32_e32 vcc, 0, v2
	v_mul_f32_e32 v1, 0x3fb8aa3b, v1
	v_sub_f32_e32 v16, v16, v0
	v_cndmask_b32_e32 v27, v28, v27, vcc
	v_and_b32_e32 v28, 0x7fffff00, v4
	v_bitop3_b32 v29, v4, s33, v4 bitop3:0xcf
	v_cmp_gt_i32_e32 vcc, 0, v4
	v_exp_f32_e32 v1, v1
	v_mul_f32_e32 v16, 0x3fb8aa3b, v16
	v_sub_f32_e32 v27, v27, v0
	v_cndmask_b32_e32 v28, v29, v28, vcc
	v_and_b32_e32 v30, 0x7fffff00, v3
	v_bitop3_b32 v31, v3, s33, v3 bitop3:0xcf
	v_cmp_gt_i32_e32 vcc, 0, v3
	v_exp_f32_e32 v16, v16
	v_mul_f32_e32 v27, 0x3fb8aa3b, v27
	v_sub_f32_e32 v28, v28, v0
	v_cndmask_b32_e32 v30, v31, v30, vcc
	v_and_b32_e32 v31, 0x7fffff00, v22
	v_bitop3_b32 v32, v22, s33, v22 bitop3:0xcf
	v_cmp_gt_i32_e32 vcc, 0, v22
	v_exp_f32_e32 v27, v27
	v_mul_f32_e32 v28, 0x3fb8aa3b, v28
	v_sub_f32_e32 v30, v30, v0
	v_cndmask_b32_e32 v31, v32, v31, vcc
	v_and_b32_e32 v32, 0x7fffff00, v15
	v_bitop3_b32 v33, v15, s33, v15 bitop3:0xcf
	v_cmp_gt_i32_e32 vcc, 0, v15
	v_exp_f32_e32 v28, v28
	v_mul_f32_e32 v30, 0x3fb8aa3b, v30
	v_sub_f32_e32 v31, v31, v0
	v_cndmask_b32_e32 v32, v33, v32, vcc
	v_and_b32_e32 v33, 0x7fffff00, v23
	v_bitop3_b32 v34, v23, s33, v23 bitop3:0xcf
	v_cmp_gt_i32_e32 vcc, 0, v23
	v_add_f32_e32 v29, 0, v1
	v_exp_f32_e32 v30, v30
	v_mul_f32_e32 v31, 0x3fb8aa3b, v31
	v_sub_f32_e32 v32, v32, v0
	v_cndmask_b32_e32 v33, v34, v33, vcc
	v_and_b32_e32 v34, 0x7fffff00, v12
	v_bitop3_b32 v35, v12, s33, v12 bitop3:0xcf
	v_cmp_gt_i32_e32 vcc, 0, v12
	v_add_f32_e32 v29, v29, v16
	v_exp_f32_e32 v31, v31
	v_mul_f32_e32 v32, 0x3fb8aa3b, v32
	v_sub_f32_e32 v33, v33, v0
	v_cndmask_b32_e32 v34, v35, v34, vcc
	v_and_b32_e32 v35, 0x7fffff00, v17
	v_bitop3_b32 v36, v17, s33, v17 bitop3:0xcf
	v_cmp_gt_i32_e32 vcc, 0, v17
	v_add_f32_e32 v29, v29, v27
	v_exp_f32_e32 v32, v32
	v_mul_f32_e32 v33, 0x3fb8aa3b, v33
	v_sub_f32_e32 v34, v34, v0
	v_cndmask_b32_e32 v35, v36, v35, vcc
	v_and_b32_e32 v36, 0x7fffff00, v14
	v_bitop3_b32 v37, v14, s33, v14 bitop3:0xcf
	v_cmp_gt_i32_e32 vcc, 0, v14
	v_add_f32_e32 v29, v29, v28
	v_exp_f32_e32 v33, v33
	v_mul_f32_e32 v34, 0x3fb8aa3b, v34
	v_sub_f32_e32 v35, v35, v0
	v_cndmask_b32_e32 v36, v37, v36, vcc
	v_and_b32_e32 v37, 0x7fffff00, v20
	v_bitop3_b32 v38, v20, s33, v20 bitop3:0xcf
	v_cmp_gt_i32_e32 vcc, 0, v20
	v_add_f32_e32 v29, v29, v30
; #define LDS_WAIT() asm volatile("s_waitcnt lgkmcnt(0)" ::: "memory")
; __device__ __forceinline__ float key2f(unsigned k) { const unsigned u = (k & 0x80000000u) ? (k & 0x7fffffffu) : ~k; return __uint_as_float(u); }
; __device__ __forceinline__ void peer_tile(const Args& A, LAS unsigned char* lds, int tile) {
;     ...
;             float fv[16], den = 0.f; const float f0 = key2f(Lf[0] & ~255u);
; #pragma unroll
;             for (int k = 0; k < 16; ++k) { fv[k] = __expf(key2f(Lf[k] & ~255u) - f0); den += fv[k]; }
;             const float rden = 1.f / den;
;             LDS_WAIT();
; #pragma unroll
;             for (int k = 0; k < 16; ++k) { const unsigned code = 255u - (Lf[k] & 255u); const unsigned e = idx[code >> 4] * 128u + idx[16 + (code & 15u)];
;                 u32x2 sv; sv.x = e; sv.y = __float_as_uint(fv[k] * rden); SEL[(tl * 8 + h) * 16 + k] = sv; }
	v_exp_f32_e32 v34, v34
	v_mul_f32_e32 v35, 0x3fb8aa3b, v35
	v_sub_f32_e32 v36, v36, v0
	v_cndmask_b32_e32 v37, v38, v37, vcc
	v_and_b32_e32 v38, 0x7fffff00, v6
	v_bitop3_b32 v39, v6, s33, v6 bitop3:0xcf
	v_cmp_gt_i32_e32 vcc, 0, v6
	v_add_f32_e32 v29, v29, v31
	v_exp_f32_e32 v35, v35
	v_mul_f32_e32 v36, 0x3fb8aa3b, v36
	v_sub_f32_e32 v37, v37, v0
	v_cndmask_b32_e32 v38, v39, v38, vcc
	v_and_b32_e32 v39, 0x7fffff00, v18
	v_bitop3_b32 v40, v18, s33, v18 bitop3:0xcf
	v_cmp_gt_i32_e32 vcc, 0, v18
	v_add_f32_e32 v29, v29, v32
	v_exp_f32_e32 v36, v36
	v_mul_f32_e32 v37, 0x3fb8aa3b, v37
	v_sub_f32_e32 v38, v38, v0
	v_cndmask_b32_e32 v39, v40, v39, vcc
	v_and_b32_e32 v40, 0x7fffff00, v8
	v_bitop3_b32 v41, v8, s33, v8 bitop3:0xcf
	v_cmp_gt_i32_e32 vcc, 0, v8
	v_add_f32_e32 v29, v29, v33
	v_exp_f32_e32 v37, v37
	v_mul_f32_e32 v38, 0x3fb8aa3b, v38
	v_sub_f32_e32 v39, v39, v0
	v_cndmask_b32_e32 v40, v41, v40, vcc
	v_and_b32_e32 v41, 0x7fffff00, v10
	v_bitop3_b32 v42, v10, s33, v10 bitop3:0xcf
	v_cmp_gt_i32_e32 vcc, 0, v10
	v_add_f32_e32 v29, v29, v34
	v_exp_f32_e32 v38, v38
	v_mul_f32_e32 v39, 0x3fb8aa3b, v39
	v_sub_f32_e32 v40, v40, v0
	v_cndmask_b32_e32 v41, v42, v41, vcc
	v_add_f32_e32 v29, v29, v35
	v_exp_f32_e32 v39, v39
	v_mul_f32_e32 v40, 0x3fb8aa3b, v40
	v_sub_f32_e32 v0, v41, v0
	v_add_f32_e32 v29, v29, v36
	v_exp_f32_e32 v40, v40
	v_mul_f32_e32 v0, 0x3fb8aa3b, v0
	v_add_f32_e32 v29, v29, v37
	v_exp_f32_e32 v41, v0
	v_add_f32_e32 v0, v29, v38
	v_add_f32_e32 v0, v0, v39
	v_add_f32_e32 v0, v0, v40
	v_add_f32_e32 v0, v0, v41
	v_div_scale_f32 v29, s[0:1], v0, v0, 1.0
	v_rcp_f32_e32 v42, v29
	v_not_b32_e32 v21, v26
	v_not_b32_e32 v24, v25
	v_fma_f32 v43, -v29, v42, 1.0
	v_fmac_f32_e32 v42, v43, v42
	v_div_scale_f32 v43, vcc, 1.0, v0, 1.0
	v_mul_f32_e32 v44, v43, v42
	v_fma_f32 v45, -v29, v44, v43
	v_fmac_f32_e32 v44, v45, v42
	v_fma_f32 v29, -v29, v44, v43
	v_div_fmas_f32 v29, v29, v42, v44
	v_div_fixup_f32 v29, v29, v0, 1.0
	v_and_b32_e32 v0, 48, v19
	v_lshrrev_b32_e32 v19, 2, v21
	v_and_b32_e32 v19, 60, v19
	v_bitop3_b32 v21, v26, 15, v26 bitop3:0xc
	v_add_u32_e32 v19, v5, v19
	v_lshl_add_u32 v21, v21, 2, v5
	ds_read_b32 v19, v19
	ds_read_b32 v21, v21 offset:64
	v_lshlrev_b32_e32 v0, 3, v0
	v_add3_u32 v11, v13, v11, v0
	v_mul_f32_e32 v1, v1, v29
	v_not_b32_e32 v13, v2
	s_waitcnt lgkmcnt(0)
	v_lshl_add_u32 v0, v19, 7, v21
	ds_write_b64 v11, v[0:1]
	v_lshrrev_b32_e32 v0, 2, v24
	v_and_b32_e32 v0, 60, v0
	v_bitop3_b32 v1, v25, 15, v25 bitop3:0xc
	v_add_u32_e32 v0, v5, v0
	v_lshl_add_u32 v1, v1, 2, v5
	ds_read_b32 v0, v0
	ds_read_b32 v1, v1 offset:64
	v_cmp_eq_u32_e32 vcc, 0, v9
	s_waitcnt lgkmcnt(0)
	v_lshl_add_u32 v0, v0, 7, v1
	v_mul_f32_e32 v1, v16, v29
	ds_write_b64 v11, v[0:1] offset:8
	v_lshrrev_b32_e32 v0, 2, v13
	v_and_b32_e32 v0, 60, v0
	v_bitop3_b32 v1, v2, 15, v2 bitop3:0xc
	v_add_u32_e32 v0, v5, v0
	v_lshl_add_u32 v1, v1, 2, v5
	ds_read_b32 v0, v0
	ds_read_b32 v1, v1 offset:64
	v_not_b32_e32 v2, v4
	s_waitcnt lgkmcnt(0)
	v_lshl_add_u32 v0, v0, 7, v1
	v_mul_f32_e32 v1, v27, v29
	ds_write_b64 v11, v[0:1] offset:16
	v_lshrrev_b32_e32 v0, 2, v2
	v_and_b32_e32 v0, 60, v0
	v_bitop3_b32 v1, v4, 15, v4 bitop3:0xc
	v_add_u32_e32 v0, v5, v0
	v_lshl_add_u32 v1, v1, 2, v5
	ds_read_b32 v0, v0
	ds_read_b32 v1, v1 offset:64
	v_not_b32_e32 v2, v3
	v_mul_lo_u32 v4, v7, s36
	s_waitcnt lgkmcnt(0)
	v_lshl_add_u32 v0, v0, 7, v1
	v_mul_f32_e32 v1, v28, v29
	ds_write_b64 v11, v[0:1] offset:24
	v_lshrrev_b32_e32 v0, 2, v2
	v_and_b32_e32 v0, 60, v0
	v_bitop3_b32 v1, v3, 15, v3 bitop3:0xc
	v_add_u32_e32 v0, v5, v0
	v_lshl_add_u32 v1, v1, 2, v5
	ds_read_b32 v0, v0
	ds_read_b32 v1, v1 offset:64
	v_not_b32_e32 v2, v22
	s_waitcnt lgkmcnt(0)
	v_lshl_add_u32 v0, v0, 7, v1
	v_mul_f32_e32 v1, v30, v29
	ds_write_b64 v11, v[0:1] offset:32
	v_lshrrev_b32_e32 v0, 2, v2
	v_and_b32_e32 v0, 60, v0
	v_bitop3_b32 v1, v22, 15, v22 bitop3:0xc
	v_add_u32_e32 v0, v5, v0
	v_lshl_add_u32 v1, v1, 2, v5
	ds_read_b32 v0, v0
	ds_read_b32 v1, v1 offset:64
	v_not_b32_e32 v2, v15
	s_waitcnt lgkmcnt(0)
	v_lshl_add_u32 v0, v0, 7, v1
	v_mul_f32_e32 v1, v31, v29
	ds_write_b64 v11, v[0:1] offset:40
	v_lshrrev_b32_e32 v0, 2, v2
	v_and_b32_e32 v0, 60, v0
	v_bitop3_b32 v1, v15, 15, v15 bitop3:0xc
	v_add_u32_e32 v0, v5, v0
	v_lshl_add_u32 v1, v1, 2, v5
	ds_read_b32 v0, v0
	ds_read_b32 v1, v1 offset:64
	v_not_b32_e32 v2, v23
	s_waitcnt lgkmcnt(0)
	v_lshl_add_u32 v0, v0, 7, v1
	v_mul_f32_e32 v1, v32, v29
	ds_write_b64 v11, v[0:1] offset:48
	v_lshrrev_b32_e32 v0, 2, v2
	v_and_b32_e32 v0, 60, v0
	v_bitop3_b32 v1, v23, 15, v23 bitop3:0xc
	v_add_u32_e32 v0, v5, v0
	v_lshl_add_u32 v1, v1, 2, v5
	ds_read_b32 v0, v0
	ds_read_b32 v1, v1 offset:64
	v_not_b32_e32 v2, v12
	s_waitcnt lgkmcnt(0)
	v_lshl_add_u32 v0, v0, 7, v1
	v_mul_f32_e32 v1, v33, v29
	ds_write_b64 v11, v[0:1] offset:56
	v_lshrrev_b32_e32 v0, 2, v2
	v_and_b32_e32 v0, 60, v0
	v_bitop3_b32 v1, v12, 15, v12 bitop3:0xc
	v_add_u32_e32 v0, v5, v0
	v_lshl_add_u32 v1, v1, 2, v5
	ds_read_b32 v0, v0
	ds_read_b32 v1, v1 offset:64
	v_not_b32_e32 v2, v17
	s_waitcnt lgkmcnt(0)
	v_lshl_add_u32 v0, v0, 7, v1
	v_mul_f32_e32 v1, v34, v29
	ds_write_b64 v11, v[0:1] offset:64
	v_lshrrev_b32_e32 v0, 2, v2
	v_and_b32_e32 v0, 60, v0
	v_bitop3_b32 v1, v17, 15, v17 bitop3:0xc
	v_add_u32_e32 v0, v5, v0
	v_lshl_add_u32 v1, v1, 2, v5
	ds_read_b32 v0, v0
	ds_read_b32 v1, v1 offset:64
	v_not_b32_e32 v2, v14
	s_waitcnt lgkmcnt(0)
	v_lshl_add_u32 v0, v0, 7, v1
	v_mul_f32_e32 v1, v35, v29
	ds_write_b64 v11, v[0:1] offset:72
	v_lshrrev_b32_e32 v0, 2, v2
	v_and_b32_e32 v0, 60, v0
	v_bitop3_b32 v1, v14, 15, v14 bitop3:0xc
	v_add_u32_e32 v0, v5, v0
	v_lshl_add_u32 v1, v1, 2, v5
	ds_read_b32 v0, v0
	ds_read_b32 v1, v1 offset:64
	v_not_b32_e32 v2, v20
	s_waitcnt lgkmcnt(0)
; __device__ __forceinline__ unsigned pk2(float lo, float hi) { const f32x2 v = {lo, hi}; const bf16x2_t b = __builtin_convertvector(v, bf16x2_t); return __builtin_bit_cast(unsigned, b); }
; __device__ __forceinline__ float bflo(unsigned u) { return __uint_as_float(u << 16); }
; __device__ __forceinline__ float bfhi(unsigned u) { return __uint_as_float(u & 0xffff0000u); }
; __device__ __forceinline__ void peer_tile(const Args& A, LAS unsigned char* lds, int tile) {
;     ...
;             for (int k = 0; k < 16; ++k) { const unsigned code = 255u - (Lf[k] & 255u); const unsigned e = idx[code >> 4] * 128u + idx[16 + (code & 15u)];
;                 u32x2 sv; sv.x = e; sv.y = __float_as_uint(fv[k] * rden); SEL[(tl * 8 + h) * 16 + k] = sv; }
;         }
;     }
;     __syncthreads();
;     ...
;     for (int pass = 0; pass < 2; ++pass) {
;         const int tb = 8 * w + 4 * pass;
;         u32x4 xpa[4], xpb[4]; f32x2 oacc[4][8];
; #pragma unroll
;         for (int tk = 0; tk < 4; ++tk) { const size_t m = (size_t)tile * 64 + tb + tk;
;             { const u32x4 ra = *(const u32x4*)(A3 + m * 1024 + 16 * lane), rb = *(const u32x4*)(A3 + m * 1024 + 16 * lane + 8);
;               float xr_; { const f32x4 p0 = *(const f32x4*)(RSq + m * 16), p1 = *(const f32x4*)(RSq + m * 16 + 4), p2 = *(const f32x4*)(RSq + m * 16 + 8), p3 = *(const f32x4*)(RSq + m * 16 + 12);
;                 const f32x4 ps = (p0 + p1) + (p2 + p3); xr_ = rsqrtf(((ps[0] + ps[1]) + (ps[2] + ps[3])) * (1.f / 1024.f) + 1e-6f); }
;               const unsigned rr[8] = {ra.x, ra.y, ra.z, ra.w, rb.x, rb.y, rb.z, rb.w}; unsigned hh[8];
;               const float* sp = MOD + (int)(m >> 11) * 6144 + 3072 + 16 * lane;
; #pragma unroll
;               for (int q = 0; q < 8; ++q) { const f32x2 sh = *(const f32x2*)(sp + 2 * q); hh[q] = pk2(bflo(rr[q]) * xr_ + sh[0], bfhi(rr[q]) * xr_ + sh[1]); }
;               xpa[tk] = (u32x4){hh[0], hh[1], hh[2], hh[3]}; xpb[tk] = (u32x4){hh[4], hh[5], hh[6], hh[7]}; }
	v_lshl_add_u32 v0, v0, 7, v1
	v_mul_f32_e32 v1, v36, v29
	ds_write_b64 v11, v[0:1] offset:80
	v_lshrrev_b32_e32 v0, 2, v2
	v_and_b32_e32 v0, 60, v0
	v_bitop3_b32 v1, v20, 15, v20 bitop3:0xc
	v_add_u32_e32 v0, v5, v0
	v_lshl_add_u32 v1, v1, 2, v5
	ds_read_b32 v0, v0
	ds_read_b32 v1, v1 offset:64
	v_not_b32_e32 v2, v6
	s_waitcnt lgkmcnt(0)
	v_lshl_add_u32 v0, v0, 7, v1
	v_mul_f32_e32 v1, v37, v29
	ds_write_b64 v11, v[0:1] offset:88
	v_lshrrev_b32_e32 v0, 2, v2
	v_and_b32_e32 v0, 60, v0
	v_bitop3_b32 v1, v6, 15, v6 bitop3:0xc
	v_add_u32_e32 v0, v5, v0
	v_lshl_add_u32 v1, v1, 2, v5
	ds_read_b32 v0, v0
	ds_read_b32 v1, v1 offset:64
	v_not_b32_e32 v2, v18
	s_waitcnt lgkmcnt(0)
	v_lshl_add_u32 v0, v0, 7, v1
	v_mul_f32_e32 v1, v38, v29
	ds_write_b64 v11, v[0:1] offset:96
	v_lshrrev_b32_e32 v0, 2, v2
	v_and_b32_e32 v0, 60, v0
	v_bitop3_b32 v1, v18, 15, v18 bitop3:0xc
	v_add_u32_e32 v0, v5, v0
	v_lshl_add_u32 v1, v1, 2, v5
	ds_read_b32 v0, v0
	ds_read_b32 v1, v1 offset:64
	v_not_b32_e32 v2, v8
	s_waitcnt lgkmcnt(0)
	v_lshl_add_u32 v0, v0, 7, v1
	v_mul_f32_e32 v1, v39, v29
	ds_write_b64 v11, v[0:1] offset:104
	v_lshrrev_b32_e32 v0, 2, v2
	v_and_b32_e32 v0, 60, v0
	v_bitop3_b32 v1, v8, 15, v8 bitop3:0xc
	v_add_u32_e32 v0, v5, v0
	v_lshl_add_u32 v1, v1, 2, v5
	ds_read_b32 v0, v0
	ds_read_b32 v1, v1 offset:64
	v_not_b32_e32 v2, v10
	s_waitcnt lgkmcnt(0)
	v_lshl_add_u32 v0, v0, 7, v1
	v_mul_f32_e32 v1, v40, v29
	ds_write_b64 v11, v[0:1] offset:112
	v_lshrrev_b32_e32 v0, 2, v2
	v_and_b32_e32 v0, 60, v0
	v_bitop3_b32 v1, v10, 15, v10 bitop3:0xc
	v_add_u32_e32 v0, v5, v0
	v_lshl_add_u32 v1, v1, 2, v5
	ds_read_b32 v0, v0
	ds_read_b32 v1, v1 offset:64
	v_lshlrev_b32_e32 v5, 13, v7
	v_lshl_or_b32 v6, v9, 3, v5
	s_waitcnt lgkmcnt(0)
	v_lshl_add_u32 v0, v0, 7, v1
	v_mul_f32_e32 v1, v41, v29
	ds_write_b64 v11, v[0:1] offset:120
	s_waitcnt lgkmcnt(0)
	s_barrier
	s_mov_b64 exec, -1
	v_and_b32_e32 v240, 63, v214
	v_lshrrev_b32_e32 v242, 6, v214
	v_lshlrev_b32_e32 v240, 4, v240
	v_readfirstlane_b32 s16, v242
	v_lshlrev_b32_e32 v245, 1, v240
	v_lshlrev_b32_e32 v246, 2, v240
	v_lshrrev_b32_e32 v247, 4, v240
	v_and_b32_e32 v247, 48, v247
	v_mov_b32_e32 v244, 0
	v_mov_b32_e32 v243, 0x358637bd
	v_mov_b32_e32 v242, 0xbf3a00e3
	s_add_u32 s4, s50, 0x1000000
	s_addc_u32 s5, s51, 0
	s_add_u32 s6, s50, 0x2000000
	s_addc_u32 s7, s51, 0
	s_add_u32 s8, s50, 0x3000000
	s_addc_u32 s9, s51, 0
	s_add_u32 s52, s50, 0x3010000
	s_addc_u32 s53, s51, 0
	s_add_u32 s12, s50, 0xb000000
	s_addc_u32 s13, s51, 0
	s_add_u32 s14, s50, 0xd000000
	s_addc_u32 s15, s51, 0
	s_lshr_b32 s0, s2, 5
	s_mul_i32 s0, s0, 0x6000
	s_add_u32 s10, s50, s0
	s_addc_u32 s11, s51, 0
	s_add_u32 s80, s10, 0x4000
	s_addc_u32 s81, s11, 0
	s_add_u32 s82, s10, 0x6000
	s_addc_u32 s83, s11, 0
	s_mul_i32 s22, s16, 9920
	s_cmp_eq_u32 s16, 7
	s_cselect_b32 s22, 0x21000, s22
	s_mov_b32 s85, 0xffffffff
	s_mov_b32 s72, 0x3e6d3388
	s_mov_b32 s56, s4
	s_and_b32 s57, s5, 0xffff
	s_or_b32 s57, s57, 0x04000000
	s_mov_b32 s58, 16384
	s_mov_b32 s59, 0x00027000
	s_mov_b32 s60, s6
	s_and_b32 s61, s7, 0xffff
	s_or_b32 s61, s61, 0x04000000
	s_mov_b32 s62, 16384
	s_mov_b32 s63, 0x00027000
	s_lshl_b32 s76, s16, 3
	s_lshl_b32 s0, s2, 6
	s_add_i32 s77, s0, s76
	global_load_dwordx4 v[192:195], v246, s[80:81] offset:0
	global_load_dwordx4 v[196:199], v246, s[80:81] offset:16
	global_load_dwordx4 v[200:203], v246, s[80:81] offset:32
	global_load_dwordx4 v[204:207], v246, s[80:81] offset:48
	s_add_i32 s0, s77, 0
	s_lshl_b32 s1, s0, 11
	s_add_u32 s78, s12, s1
	s_addc_u32 s79, s13, 0
	global_load_dwordx4 v[128:131], v245, s[78:79]
	global_load_dwordx4 v[132:135], v245, s[78:79] offset:16
	global_load_dwordx4 v[136:139], v245, s[78:79] offset:2048
	global_load_dwordx4 v[140:143], v245, s[78:79] offset:2064
	s_lshl_b32 s1, s0, 6
	s_add_u32 s78, s14, s1
	s_addc_u32 s79, s15, 0
	global_load_dwordx4 v[144:147], v244, s[78:79] offset:0
	global_load_dwordx4 v[148:151], v244, s[78:79] offset:16
	global_load_dwordx4 v[152:155], v244, s[78:79] offset:32
	global_load_dwordx4 v[156:159], v244, s[78:79] offset:48
	global_load_dwordx4 v[160:163], v244, s[78:79] offset:64
	global_load_dwordx4 v[164:167], v244, s[78:79] offset:80
	global_load_dwordx4 v[168:171], v244, s[78:79] offset:96
	global_load_dwordx4 v[172:175], v244, s[78:79] offset:112
	s_add_i32 s0, s77, 2
	s_lshl_b32 s1, s0, 11
	s_add_u32 s78, s12, s1
	s_addc_u32 s79, s13, 0
	global_load_dwordx4 v[176:179], v245, s[78:79]
	global_load_dwordx4 v[180:183], v245, s[78:79] offset:16
	global_load_dwordx4 v[184:187], v245, s[78:79] offset:2048
	global_load_dwordx4 v[188:191], v245, s[78:79] offset:2064
	s_lshl_b32 s1, s0, 6
	s_add_u32 s78, s14, s1
	s_addc_u32 s79, s15, 0
	global_load_dwordx4 v[216:219], v244, s[78:79] offset:0
	global_load_dwordx4 v[220:223], v244, s[78:79] offset:16
	global_load_dwordx4 v[224:227], v244, s[78:79] offset:32
	global_load_dwordx4 v[228:231], v244, s[78:79] offset:48
	global_load_dwordx4 v[232:235], v244, s[78:79] offset:64
	global_load_dwordx4 v[236:239], v244, s[78:79] offset:80
	global_load_dwordx4 v[248:251], v244, s[78:79] offset:96
	global_load_dwordx4 v[252:255], v244, s[78:79] offset:112
	s_waitcnt vmcnt(12)
; __device__ __forceinline__ unsigned pk2(float lo, float hi) { const f32x2 v = {lo, hi}; const bf16x2_t b = __builtin_convertvector(v, bf16x2_t); return __builtin_bit_cast(unsigned, b); }
; __device__ __forceinline__ float bflo(unsigned u) { return __uint_as_float(u << 16); }
; __device__ __forceinline__ float bfhi(unsigned u) { return __uint_as_float(u & 0xffff0000u); }
; __device__ __forceinline__ void peer_tile(const Args& A, LAS unsigned char* lds, int tile) {
;     ...
;         for (int tk = 0; tk < 4; ++tk) { const size_t m = (size_t)tile * 64 + tb + tk;
;             { const u32x4 ra = *(const u32x4*)(A3 + m * 1024 + 16 * lane), rb = *(const u32x4*)(A3 + m * 1024 + 16 * lane + 8);
;               float xr_; { const f32x4 p0 = *(const f32x4*)(RSq + m * 16), p1 = *(const f32x4*)(RSq + m * 16 + 4), p2 = *(const f32x4*)(RSq + m * 16 + 8), p3 = *(const f32x4*)(RSq + m * 16 + 12);
;                 const f32x4 ps = (p0 + p1) + (p2 + p3); xr_ = rsqrtf(((ps[0] + ps[1]) + (ps[2] + ps[3])) * (1.f / 1024.f) + 1e-6f); }
;               const unsigned rr[8] = {ra.x, ra.y, ra.z, ra.w, rb.x, rb.y, rb.z, rb.w}; unsigned hh[8];
;               const float* sp = MOD + (int)(m >> 11) * 6144 + 3072 + 16 * lane;
; #pragma unroll
;               for (int q = 0; q < 8; ++q) { const f32x2 sh = *(const f32x2*)(sp + 2 * q); hh[q] = pk2(bflo(rr[q]) * xr_ + sh[0], bfhi(rr[q]) * xr_ + sh[1]); }
;               xpa[tk] = (u32x4){hh[0], hh[1], hh[2], hh[3]}; xpb[tk] = (u32x4){hh[4], hh[5], hh[6], hh[7]}; }
; #pragma unroll
;             for (int q = 0; q < 8; ++q) oacc[tk][q] = (f32x2){0.f, 0.f}; }
;     ...
;                 { const unsigned xx[8] = {xpa[tk].x, xpa[tk].y, xpa[tk].z, xpa[tk].w, xpb[tk].x, xpb[tk].y, xpb[tk].z, xpb[tk].w};
; #pragma unroll
;                   for (int q = 0; q < 8; ++q) xf[q] = (f32x2){bflo(xx[q]), bfhi(xx[q])}; }
	v_pk_add_f32 v[144:145], v[144:145], v[148:149]
	v_pk_add_f32 v[146:147], v[146:147], v[150:151]
	v_pk_add_f32 v[152:153], v[152:153], v[156:157]
	v_pk_add_f32 v[154:155], v[154:155], v[158:159]
	v_pk_add_f32 v[144:145], v[144:145], v[152:153]
	v_pk_add_f32 v[146:147], v[146:147], v[154:155]
	v_add_f32_e32 v144, v144, v145
	v_add_f32_e32 v146, v146, v147
	v_add_f32_e32 v144, v144, v146
	v_fmamk_f32 v144, v144, 0x3a800000, v243
	v_rsq_f32_e32 v144, v144
	v_pk_add_f32 v[160:161], v[160:161], v[164:165]
	v_pk_add_f32 v[162:163], v[162:163], v[166:167]
	v_pk_add_f32 v[168:169], v[168:169], v[172:173]
	v_pk_add_f32 v[170:171], v[170:171], v[174:175]
	v_pk_add_f32 v[160:161], v[160:161], v[168:169]
	v_pk_add_f32 v[162:163], v[162:163], v[170:171]
	v_add_f32_e32 v160, v160, v161
	v_add_f32_e32 v162, v162, v163
	v_add_f32_e32 v160, v160, v162
	v_fmamk_f32 v160, v160, 0x3a800000, v243
	v_rsq_f32_e32 v160, v160
	v_lshlrev_b32_e32 v208, 16, v128
	v_and_b32_e32 v209, 0xffff0000, v128
	v_fma_f32 v208, v208, v144, v192
	v_fma_f32 v209, v209, v144, v193
	v_cvt_pk_bf16_f32 v210, v208, v209
	v_lshlrev_b32_e32 v0, 16, v210
	v_and_b32_e32 v1, 0xffff0000, v210
	v_lshlrev_b32_e32 v208, 16, v129
	v_and_b32_e32 v209, 0xffff0000, v129
	v_fma_f32 v208, v208, v144, v194
	v_fma_f32 v209, v209, v144, v195
	v_cvt_pk_bf16_f32 v210, v208, v209
	v_lshlrev_b32_e32 v2, 16, v210
	v_and_b32_e32 v3, 0xffff0000, v210
	v_lshlrev_b32_e32 v208, 16, v130
	v_and_b32_e32 v209, 0xffff0000, v130
	v_fma_f32 v208, v208, v144, v196
	v_fma_f32 v209, v209, v144, v197
	v_cvt_pk_bf16_f32 v210, v208, v209
	v_lshlrev_b32_e32 v4, 16, v210
	v_and_b32_e32 v5, 0xffff0000, v210
	v_lshlrev_b32_e32 v208, 16, v131
	v_and_b32_e32 v209, 0xffff0000, v131
	v_fma_f32 v208, v208, v144, v198
	v_fma_f32 v209, v209, v144, v199
	v_cvt_pk_bf16_f32 v210, v208, v209
	v_lshlrev_b32_e32 v6, 16, v210
	v_and_b32_e32 v7, 0xffff0000, v210
	v_lshlrev_b32_e32 v208, 16, v132
	v_and_b32_e32 v209, 0xffff0000, v132
	v_fma_f32 v208, v208, v144, v200
	v_fma_f32 v209, v209, v144, v201
	v_cvt_pk_bf16_f32 v210, v208, v209
	v_lshlrev_b32_e32 v8, 16, v210
	v_and_b32_e32 v9, 0xffff0000, v210
	v_lshlrev_b32_e32 v208, 16, v133
	v_and_b32_e32 v209, 0xffff0000, v133
	v_fma_f32 v208, v208, v144, v202
	v_fma_f32 v209, v209, v144, v203
	v_cvt_pk_bf16_f32 v210, v208, v209
	v_lshlrev_b32_e32 v10, 16, v210
	v_and_b32_e32 v11, 0xffff0000, v210
	v_lshlrev_b32_e32 v208, 16, v134
	v_and_b32_e32 v209, 0xffff0000, v134
	v_fma_f32 v208, v208, v144, v204
	v_fma_f32 v209, v209, v144, v205
	v_cvt_pk_bf16_f32 v210, v208, v209
	v_lshlrev_b32_e32 v12, 16, v210
	v_and_b32_e32 v13, 0xffff0000, v210
	v_lshlrev_b32_e32 v208, 16, v135
	v_and_b32_e32 v209, 0xffff0000, v135
	v_fma_f32 v208, v208, v144, v206
	v_fma_f32 v209, v209, v144, v207
	v_cvt_pk_bf16_f32 v210, v208, v209
	v_lshlrev_b32_e32 v14, 16, v210
	v_and_b32_e32 v15, 0xffff0000, v210
	v_lshlrev_b32_e32 v208, 16, v136
	v_and_b32_e32 v209, 0xffff0000, v136
	v_fma_f32 v208, v208, v160, v192
	v_fma_f32 v209, v209, v160, v193
	v_cvt_pk_bf16_f32 v210, v208, v209
	v_lshlrev_b32_e32 v16, 16, v210
	v_and_b32_e32 v17, 0xffff0000, v210
	v_lshlrev_b32_e32 v208, 16, v137
	v_and_b32_e32 v209, 0xffff0000, v137
	v_fma_f32 v208, v208, v160, v194
	v_fma_f32 v209, v209, v160, v195
	v_cvt_pk_bf16_f32 v210, v208, v209
	v_lshlrev_b32_e32 v18, 16, v210
	v_and_b32_e32 v19, 0xffff0000, v210
	v_lshlrev_b32_e32 v208, 16, v138
	v_and_b32_e32 v209, 0xffff0000, v138
	v_fma_f32 v208, v208, v160, v196
	v_fma_f32 v209, v209, v160, v197
	v_cvt_pk_bf16_f32 v210, v208, v209
	v_lshlrev_b32_e32 v20, 16, v210
	v_and_b32_e32 v21, 0xffff0000, v210
	v_lshlrev_b32_e32 v208, 16, v139
	v_and_b32_e32 v209, 0xffff0000, v139
	v_fma_f32 v208, v208, v160, v198
	v_fma_f32 v209, v209, v160, v199
	v_cvt_pk_bf16_f32 v210, v208, v209
	v_lshlrev_b32_e32 v22, 16, v210
	v_and_b32_e32 v23, 0xffff0000, v210
	v_lshlrev_b32_e32 v208, 16, v140
	v_and_b32_e32 v209, 0xffff0000, v140
	v_fma_f32 v208, v208, v160, v200
	v_fma_f32 v209, v209, v160, v201
	v_cvt_pk_bf16_f32 v210, v208, v209
	v_lshlrev_b32_e32 v24, 16, v210
	v_and_b32_e32 v25, 0xffff0000, v210
	v_lshlrev_b32_e32 v208, 16, v141
	v_and_b32_e32 v209, 0xffff0000, v141
	v_fma_f32 v208, v208, v160, v202
	v_fma_f32 v209, v209, v160, v203
	v_cvt_pk_bf16_f32 v210, v208, v209
	v_lshlrev_b32_e32 v26, 16, v210
	v_and_b32_e32 v27, 0xffff0000, v210
	v_lshlrev_b32_e32 v208, 16, v142
	v_and_b32_e32 v209, 0xffff0000, v142
	v_fma_f32 v208, v208, v160, v204
	v_fma_f32 v209, v209, v160, v205
	v_cvt_pk_bf16_f32 v210, v208, v209
	v_lshlrev_b32_e32 v28, 16, v210
	v_and_b32_e32 v29, 0xffff0000, v210
	v_lshlrev_b32_e32 v208, 16, v143
	v_and_b32_e32 v209, 0xffff0000, v143
	v_fma_f32 v208, v208, v160, v206
	v_fma_f32 v209, v209, v160, v207
	v_cvt_pk_bf16_f32 v210, v208, v209
	v_lshlrev_b32_e32 v30, 16, v210
	v_and_b32_e32 v31, 0xffff0000, v210
	s_nop 0
	s_add_i32 s0, s77, 4
	s_lshl_b32 s1, s0, 11
	s_add_u32 s78, s12, s1
	s_addc_u32 s79, s13, 0
	global_load_dwordx4 v[128:131], v245, s[78:79]
	global_load_dwordx4 v[132:135], v245, s[78:79] offset:16
	global_load_dwordx4 v[136:139], v245, s[78:79] offset:2048
	global_load_dwordx4 v[140:143], v245, s[78:79] offset:2064
	s_lshl_b32 s1, s0, 6
	s_add_u32 s78, s14, s1
	s_addc_u32 s79, s15, 0
	global_load_dwordx4 v[144:147], v244, s[78:79] offset:0
	global_load_dwordx4 v[148:151], v244, s[78:79] offset:16
	global_load_dwordx4 v[152:155], v244, s[78:79] offset:32
	global_load_dwordx4 v[156:159], v244, s[78:79] offset:48
	global_load_dwordx4 v[160:163], v244, s[78:79] offset:64
	global_load_dwordx4 v[164:167], v244, s[78:79] offset:80
	global_load_dwordx4 v[168:171], v244, s[78:79] offset:96
	global_load_dwordx4 v[172:175], v244, s[78:79] offset:112
	s_waitcnt vmcnt(12)
; __device__ __forceinline__ unsigned pk2(float lo, float hi) { const f32x2 v = {lo, hi}; const bf16x2_t b = __builtin_convertvector(v, bf16x2_t); return __builtin_bit_cast(unsigned, b); }
; __device__ __forceinline__ float bflo(unsigned u) { return __uint_as_float(u << 16); }
; __device__ __forceinline__ float bfhi(unsigned u) { return __uint_as_float(u & 0xffff0000u); }
; __device__ __forceinline__ void peer_tile(const Args& A, LAS unsigned char* lds, int tile) {
;     ...
;         for (int tk = 0; tk < 4; ++tk) { const size_t m = (size_t)tile * 64 + tb + tk;
;             { const u32x4 ra = *(const u32x4*)(A3 + m * 1024 + 16 * lane), rb = *(const u32x4*)(A3 + m * 1024 + 16 * lane + 8);
;               float xr_; { const f32x4 p0 = *(const f32x4*)(RSq + m * 16), p1 = *(const f32x4*)(RSq + m * 16 + 4), p2 = *(const f32x4*)(RSq + m * 16 + 8), p3 = *(const f32x4*)(RSq + m * 16 + 12);
;                 const f32x4 ps = (p0 + p1) + (p2 + p3); xr_ = rsqrtf(((ps[0] + ps[1]) + (ps[2] + ps[3])) * (1.f / 1024.f) + 1e-6f); }
;               const unsigned rr[8] = {ra.x, ra.y, ra.z, ra.w, rb.x, rb.y, rb.z, rb.w}; unsigned hh[8];
;               const float* sp = MOD + (int)(m >> 11) * 6144 + 3072 + 16 * lane;
; #pragma unroll
;               for (int q = 0; q < 8; ++q) { const f32x2 sh = *(const f32x2*)(sp + 2 * q); hh[q] = pk2(bflo(rr[q]) * xr_ + sh[0], bfhi(rr[q]) * xr_ + sh[1]); }
;               xpa[tk] = (u32x4){hh[0], hh[1], hh[2], hh[3]}; xpb[tk] = (u32x4){hh[4], hh[5], hh[6], hh[7]}; }
; #pragma unroll
;             for (int q = 0; q < 8; ++q) oacc[tk][q] = (f32x2){0.f, 0.f}; }
;     ...
;                 { const unsigned xx[8] = {xpa[tk].x, xpa[tk].y, xpa[tk].z, xpa[tk].w, xpb[tk].x, xpb[tk].y, xpb[tk].z, xpb[tk].w};
; #pragma unroll
;                   for (int q = 0; q < 8; ++q) xf[q] = (f32x2){bflo(xx[q]), bfhi(xx[q])}; }
	v_pk_add_f32 v[216:217], v[216:217], v[220:221]
	v_pk_add_f32 v[218:219], v[218:219], v[222:223]
	v_pk_add_f32 v[224:225], v[224:225], v[228:229]
	v_pk_add_f32 v[226:227], v[226:227], v[230:231]
	v_pk_add_f32 v[216:217], v[216:217], v[224:225]
	v_pk_add_f32 v[218:219], v[218:219], v[226:227]
	v_add_f32_e32 v216, v216, v217
	v_add_f32_e32 v218, v218, v219
	v_add_f32_e32 v216, v216, v218
	v_fmamk_f32 v216, v216, 0x3a800000, v243
	v_rsq_f32_e32 v216, v216
	v_pk_add_f32 v[232:233], v[232:233], v[236:237]
	v_pk_add_f32 v[234:235], v[234:235], v[238:239]
	v_pk_add_f32 v[248:249], v[248:249], v[252:253]
	v_pk_add_f32 v[250:251], v[250:251], v[254:255]
	v_pk_add_f32 v[232:233], v[232:233], v[248:249]
	v_pk_add_f32 v[234:235], v[234:235], v[250:251]
	v_add_f32_e32 v232, v232, v233
	v_add_f32_e32 v234, v234, v235
	v_add_f32_e32 v232, v232, v234
	v_fmamk_f32 v232, v232, 0x3a800000, v243
	v_rsq_f32_e32 v232, v232
	v_lshlrev_b32_e32 v208, 16, v176
	v_and_b32_e32 v209, 0xffff0000, v176
	v_fma_f32 v208, v208, v216, v192
	v_fma_f32 v209, v209, v216, v193
	v_cvt_pk_bf16_f32 v210, v208, v209
	v_lshlrev_b32_e32 v32, 16, v210
	v_and_b32_e32 v33, 0xffff0000, v210
	v_lshlrev_b32_e32 v208, 16, v177
	v_and_b32_e32 v209, 0xffff0000, v177
	v_fma_f32 v208, v208, v216, v194
	v_fma_f32 v209, v209, v216, v195
	v_cvt_pk_bf16_f32 v210, v208, v209
	v_lshlrev_b32_e32 v34, 16, v210
	v_and_b32_e32 v35, 0xffff0000, v210
	v_lshlrev_b32_e32 v208, 16, v178
	v_and_b32_e32 v209, 0xffff0000, v178
	v_fma_f32 v208, v208, v216, v196
	v_fma_f32 v209, v209, v216, v197
	v_cvt_pk_bf16_f32 v210, v208, v209
	v_lshlrev_b32_e32 v36, 16, v210
	v_and_b32_e32 v37, 0xffff0000, v210
	v_lshlrev_b32_e32 v208, 16, v179
	v_and_b32_e32 v209, 0xffff0000, v179
	v_fma_f32 v208, v208, v216, v198
	v_fma_f32 v209, v209, v216, v199
	v_cvt_pk_bf16_f32 v210, v208, v209
	v_lshlrev_b32_e32 v38, 16, v210
	v_and_b32_e32 v39, 0xffff0000, v210
	v_lshlrev_b32_e32 v208, 16, v180
	v_and_b32_e32 v209, 0xffff0000, v180
	v_fma_f32 v208, v208, v216, v200
	v_fma_f32 v209, v209, v216, v201
	v_cvt_pk_bf16_f32 v210, v208, v209
	v_lshlrev_b32_e32 v40, 16, v210
	v_and_b32_e32 v41, 0xffff0000, v210
	v_lshlrev_b32_e32 v208, 16, v181
	v_and_b32_e32 v209, 0xffff0000, v181
	v_fma_f32 v208, v208, v216, v202
	v_fma_f32 v209, v209, v216, v203
	v_cvt_pk_bf16_f32 v210, v208, v209
	v_lshlrev_b32_e32 v42, 16, v210
	v_and_b32_e32 v43, 0xffff0000, v210
	v_lshlrev_b32_e32 v208, 16, v182
	v_and_b32_e32 v209, 0xffff0000, v182
	v_fma_f32 v208, v208, v216, v204
	v_fma_f32 v209, v209, v216, v205
	v_cvt_pk_bf16_f32 v210, v208, v209
	v_lshlrev_b32_e32 v44, 16, v210
	v_and_b32_e32 v45, 0xffff0000, v210
	v_lshlrev_b32_e32 v208, 16, v183
	v_and_b32_e32 v209, 0xffff0000, v183
	v_fma_f32 v208, v208, v216, v206
	v_fma_f32 v209, v209, v216, v207
	v_cvt_pk_bf16_f32 v210, v208, v209
	v_lshlrev_b32_e32 v46, 16, v210
	v_and_b32_e32 v47, 0xffff0000, v210
	v_lshlrev_b32_e32 v208, 16, v184
	v_and_b32_e32 v209, 0xffff0000, v184
	v_fma_f32 v208, v208, v232, v192
	v_fma_f32 v209, v209, v232, v193
	v_cvt_pk_bf16_f32 v210, v208, v209
	v_lshlrev_b32_e32 v48, 16, v210
	v_and_b32_e32 v49, 0xffff0000, v210
	v_lshlrev_b32_e32 v208, 16, v185
	v_and_b32_e32 v209, 0xffff0000, v185
	v_fma_f32 v208, v208, v232, v194
	v_fma_f32 v209, v209, v232, v195
	v_cvt_pk_bf16_f32 v210, v208, v209
	v_lshlrev_b32_e32 v50, 16, v210
	v_and_b32_e32 v51, 0xffff0000, v210
	v_lshlrev_b32_e32 v208, 16, v186
	v_and_b32_e32 v209, 0xffff0000, v186
	v_fma_f32 v208, v208, v232, v196
	v_fma_f32 v209, v209, v232, v197
	v_cvt_pk_bf16_f32 v210, v208, v209
	v_lshlrev_b32_e32 v52, 16, v210
	v_and_b32_e32 v53, 0xffff0000, v210
	v_lshlrev_b32_e32 v208, 16, v187
	v_and_b32_e32 v209, 0xffff0000, v187
	v_fma_f32 v208, v208, v232, v198
	v_fma_f32 v209, v209, v232, v199
	v_cvt_pk_bf16_f32 v210, v208, v209
	v_lshlrev_b32_e32 v54, 16, v210
	v_and_b32_e32 v55, 0xffff0000, v210
	v_lshlrev_b32_e32 v208, 16, v188
	v_and_b32_e32 v209, 0xffff0000, v188
	v_fma_f32 v208, v208, v232, v200
	v_fma_f32 v209, v209, v232, v201
	v_cvt_pk_bf16_f32 v210, v208, v209
	v_lshlrev_b32_e32 v56, 16, v210
	v_and_b32_e32 v57, 0xffff0000, v210
	v_lshlrev_b32_e32 v208, 16, v189
	v_and_b32_e32 v209, 0xffff0000, v189
	v_fma_f32 v208, v208, v232, v202
	v_fma_f32 v209, v209, v232, v203
	v_cvt_pk_bf16_f32 v210, v208, v209
	v_lshlrev_b32_e32 v58, 16, v210
	v_and_b32_e32 v59, 0xffff0000, v210
	v_lshlrev_b32_e32 v208, 16, v190
	v_and_b32_e32 v209, 0xffff0000, v190
	v_fma_f32 v208, v208, v232, v204
	v_fma_f32 v209, v209, v232, v205
	v_cvt_pk_bf16_f32 v210, v208, v209
	v_lshlrev_b32_e32 v60, 16, v210
	v_and_b32_e32 v61, 0xffff0000, v210
	v_lshlrev_b32_e32 v208, 16, v191
	v_and_b32_e32 v209, 0xffff0000, v191
	v_fma_f32 v208, v208, v232, v206
	v_fma_f32 v209, v209, v232, v207
	v_cvt_pk_bf16_f32 v210, v208, v209
	v_lshlrev_b32_e32 v62, 16, v210
	v_and_b32_e32 v63, 0xffff0000, v210
	s_nop 0
	s_add_i32 s0, s77, 6
	s_lshl_b32 s1, s0, 11
	s_add_u32 s78, s12, s1
	s_addc_u32 s79, s13, 0
	global_load_dwordx4 v[176:179], v245, s[78:79]
	global_load_dwordx4 v[180:183], v245, s[78:79] offset:16
	global_load_dwordx4 v[184:187], v245, s[78:79] offset:2048
	global_load_dwordx4 v[188:191], v245, s[78:79] offset:2064
	s_lshl_b32 s1, s0, 6
	s_add_u32 s78, s14, s1
	s_addc_u32 s79, s15, 0
	global_load_dwordx4 v[216:219], v244, s[78:79] offset:0
	global_load_dwordx4 v[220:223], v244, s[78:79] offset:16
	global_load_dwordx4 v[224:227], v244, s[78:79] offset:32
	global_load_dwordx4 v[228:231], v244, s[78:79] offset:48
	global_load_dwordx4 v[232:235], v244, s[78:79] offset:64
	global_load_dwordx4 v[236:239], v244, s[78:79] offset:80
	global_load_dwordx4 v[248:251], v244, s[78:79] offset:96
	global_load_dwordx4 v[252:255], v244, s[78:79] offset:112
	s_waitcnt vmcnt(12)
; __device__ __forceinline__ unsigned pk2(float lo, float hi) { const f32x2 v = {lo, hi}; const bf16x2_t b = __builtin_convertvector(v, bf16x2_t); return __builtin_bit_cast(unsigned, b); }
; __device__ __forceinline__ float bflo(unsigned u) { return __uint_as_float(u << 16); }
; __device__ __forceinline__ float bfhi(unsigned u) { return __uint_as_float(u & 0xffff0000u); }
; __device__ __forceinline__ void peer_tile(const Args& A, LAS unsigned char* lds, int tile) {
;     ...
;         for (int tk = 0; tk < 4; ++tk) { const size_t m = (size_t)tile * 64 + tb + tk;
;             { const u32x4 ra = *(const u32x4*)(A3 + m * 1024 + 16 * lane), rb = *(const u32x4*)(A3 + m * 1024 + 16 * lane + 8);
;               float xr_; { const f32x4 p0 = *(const f32x4*)(RSq + m * 16), p1 = *(const f32x4*)(RSq + m * 16 + 4), p2 = *(const f32x4*)(RSq + m * 16 + 8), p3 = *(const f32x4*)(RSq + m * 16 + 12);
;                 const f32x4 ps = (p0 + p1) + (p2 + p3); xr_ = rsqrtf(((ps[0] + ps[1]) + (ps[2] + ps[3])) * (1.f / 1024.f) + 1e-6f); }
;               const unsigned rr[8] = {ra.x, ra.y, ra.z, ra.w, rb.x, rb.y, rb.z, rb.w}; unsigned hh[8];
;               const float* sp = MOD + (int)(m >> 11) * 6144 + 3072 + 16 * lane;
; #pragma unroll
;               for (int q = 0; q < 8; ++q) { const f32x2 sh = *(const f32x2*)(sp + 2 * q); hh[q] = pk2(bflo(rr[q]) * xr_ + sh[0], bfhi(rr[q]) * xr_ + sh[1]); }
;               xpa[tk] = (u32x4){hh[0], hh[1], hh[2], hh[3]}; xpb[tk] = (u32x4){hh[4], hh[5], hh[6], hh[7]}; }
; #pragma unroll
;             for (int q = 0; q < 8; ++q) oacc[tk][q] = (f32x2){0.f, 0.f}; }
;     ...
;                 { const unsigned xx[8] = {xpa[tk].x, xpa[tk].y, xpa[tk].z, xpa[tk].w, xpb[tk].x, xpb[tk].y, xpb[tk].z, xpb[tk].w};
; #pragma unroll
;                   for (int q = 0; q < 8; ++q) xf[q] = (f32x2){bflo(xx[q]), bfhi(xx[q])}; }
	v_pk_add_f32 v[144:145], v[144:145], v[148:149]
	v_pk_add_f32 v[146:147], v[146:147], v[150:151]
	v_pk_add_f32 v[152:153], v[152:153], v[156:157]
	v_pk_add_f32 v[154:155], v[154:155], v[158:159]
	v_pk_add_f32 v[144:145], v[144:145], v[152:153]
	v_pk_add_f32 v[146:147], v[146:147], v[154:155]
	v_add_f32_e32 v144, v144, v145
	v_add_f32_e32 v146, v146, v147
	v_add_f32_e32 v144, v144, v146
	v_fmamk_f32 v144, v144, 0x3a800000, v243
	v_rsq_f32_e32 v144, v144
	v_pk_add_f32 v[160:161], v[160:161], v[164:165]
	v_pk_add_f32 v[162:163], v[162:163], v[166:167]
	v_pk_add_f32 v[168:169], v[168:169], v[172:173]
	v_pk_add_f32 v[170:171], v[170:171], v[174:175]
	v_pk_add_f32 v[160:161], v[160:161], v[168:169]
	v_pk_add_f32 v[162:163], v[162:163], v[170:171]
	v_add_f32_e32 v160, v160, v161
	v_add_f32_e32 v162, v162, v163
	v_add_f32_e32 v160, v160, v162
	v_fmamk_f32 v160, v160, 0x3a800000, v243
	v_rsq_f32_e32 v160, v160
	v_lshlrev_b32_e32 v208, 16, v128
	v_and_b32_e32 v209, 0xffff0000, v128
	v_fma_f32 v208, v208, v144, v192
	v_fma_f32 v209, v209, v144, v193
	v_cvt_pk_bf16_f32 v210, v208, v209
	v_lshlrev_b32_e32 v64, 16, v210
	v_and_b32_e32 v65, 0xffff0000, v210
	v_lshlrev_b32_e32 v208, 16, v129
	v_and_b32_e32 v209, 0xffff0000, v129
	v_fma_f32 v208, v208, v144, v194
	v_fma_f32 v209, v209, v144, v195
	v_cvt_pk_bf16_f32 v210, v208, v209
	v_lshlrev_b32_e32 v66, 16, v210
	v_and_b32_e32 v67, 0xffff0000, v210
	v_lshlrev_b32_e32 v208, 16, v130
	v_and_b32_e32 v209, 0xffff0000, v130
	v_fma_f32 v208, v208, v144, v196
	v_fma_f32 v209, v209, v144, v197
	v_cvt_pk_bf16_f32 v210, v208, v209
	v_lshlrev_b32_e32 v68, 16, v210
	v_and_b32_e32 v69, 0xffff0000, v210
	v_lshlrev_b32_e32 v208, 16, v131
	v_and_b32_e32 v209, 0xffff0000, v131
	v_fma_f32 v208, v208, v144, v198
	v_fma_f32 v209, v209, v144, v199
	v_cvt_pk_bf16_f32 v210, v208, v209
	v_lshlrev_b32_e32 v70, 16, v210
	v_and_b32_e32 v71, 0xffff0000, v210
	v_lshlrev_b32_e32 v208, 16, v132
	v_and_b32_e32 v209, 0xffff0000, v132
	v_fma_f32 v208, v208, v144, v200
	v_fma_f32 v209, v209, v144, v201
	v_cvt_pk_bf16_f32 v210, v208, v209
	v_lshlrev_b32_e32 v72, 16, v210
	v_and_b32_e32 v73, 0xffff0000, v210
	v_lshlrev_b32_e32 v208, 16, v133
	v_and_b32_e32 v209, 0xffff0000, v133
	v_fma_f32 v208, v208, v144, v202
	v_fma_f32 v209, v209, v144, v203
	v_cvt_pk_bf16_f32 v210, v208, v209
	v_lshlrev_b32_e32 v74, 16, v210
	v_and_b32_e32 v75, 0xffff0000, v210
	v_lshlrev_b32_e32 v208, 16, v134
	v_and_b32_e32 v209, 0xffff0000, v134
	v_fma_f32 v208, v208, v144, v204
	v_fma_f32 v209, v209, v144, v205
	v_cvt_pk_bf16_f32 v210, v208, v209
	v_lshlrev_b32_e32 v76, 16, v210
	v_and_b32_e32 v77, 0xffff0000, v210
	v_lshlrev_b32_e32 v208, 16, v135
	v_and_b32_e32 v209, 0xffff0000, v135
	v_fma_f32 v208, v208, v144, v206
	v_fma_f32 v209, v209, v144, v207
	v_cvt_pk_bf16_f32 v210, v208, v209
	v_lshlrev_b32_e32 v78, 16, v210
	v_and_b32_e32 v79, 0xffff0000, v210
	v_lshlrev_b32_e32 v208, 16, v136
	v_and_b32_e32 v209, 0xffff0000, v136
	v_fma_f32 v208, v208, v160, v192
	v_fma_f32 v209, v209, v160, v193
	v_cvt_pk_bf16_f32 v210, v208, v209
	v_lshlrev_b32_e32 v80, 16, v210
	v_and_b32_e32 v81, 0xffff0000, v210
	v_lshlrev_b32_e32 v208, 16, v137
	v_and_b32_e32 v209, 0xffff0000, v137
	v_fma_f32 v208, v208, v160, v194
	v_fma_f32 v209, v209, v160, v195
	v_cvt_pk_bf16_f32 v210, v208, v209
	v_lshlrev_b32_e32 v82, 16, v210
	v_and_b32_e32 v83, 0xffff0000, v210
	v_lshlrev_b32_e32 v208, 16, v138
	v_and_b32_e32 v209, 0xffff0000, v138
	v_fma_f32 v208, v208, v160, v196
	v_fma_f32 v209, v209, v160, v197
	v_cvt_pk_bf16_f32 v210, v208, v209
	v_lshlrev_b32_e32 v84, 16, v210
	v_and_b32_e32 v85, 0xffff0000, v210
	v_lshlrev_b32_e32 v208, 16, v139
	v_and_b32_e32 v209, 0xffff0000, v139
	v_fma_f32 v208, v208, v160, v198
	v_fma_f32 v209, v209, v160, v199
	v_cvt_pk_bf16_f32 v210, v208, v209
	v_lshlrev_b32_e32 v86, 16, v210
	v_and_b32_e32 v87, 0xffff0000, v210
	v_lshlrev_b32_e32 v208, 16, v140
	v_and_b32_e32 v209, 0xffff0000, v140
	v_fma_f32 v208, v208, v160, v200
	v_fma_f32 v209, v209, v160, v201
	v_cvt_pk_bf16_f32 v210, v208, v209
	v_lshlrev_b32_e32 v88, 16, v210
	v_and_b32_e32 v89, 0xffff0000, v210
	v_lshlrev_b32_e32 v208, 16, v141
	v_and_b32_e32 v209, 0xffff0000, v141
	v_fma_f32 v208, v208, v160, v202
	v_fma_f32 v209, v209, v160, v203
	v_cvt_pk_bf16_f32 v210, v208, v209
	v_lshlrev_b32_e32 v90, 16, v210
	v_and_b32_e32 v91, 0xffff0000, v210
	v_lshlrev_b32_e32 v208, 16, v142
	v_and_b32_e32 v209, 0xffff0000, v142
	v_fma_f32 v208, v208, v160, v204
	v_fma_f32 v209, v209, v160, v205
	v_cvt_pk_bf16_f32 v210, v208, v209
	v_lshlrev_b32_e32 v92, 16, v210
	v_and_b32_e32 v93, 0xffff0000, v210
	v_lshlrev_b32_e32 v208, 16, v143
	v_and_b32_e32 v209, 0xffff0000, v143
	v_fma_f32 v208, v208, v160, v206
	v_fma_f32 v209, v209, v160, v207
	v_cvt_pk_bf16_f32 v210, v208, v209
	v_lshlrev_b32_e32 v94, 16, v210
	v_and_b32_e32 v95, 0xffff0000, v210
	s_nop 0
	s_waitcnt vmcnt(0)
; __device__ __forceinline__ unsigned pk2(float lo, float hi) { const f32x2 v = {lo, hi}; const bf16x2_t b = __builtin_convertvector(v, bf16x2_t); return __builtin_bit_cast(unsigned, b); }
; __device__ __forceinline__ float bflo(unsigned u) { return __uint_as_float(u << 16); }
; __device__ __forceinline__ float bfhi(unsigned u) { return __uint_as_float(u & 0xffff0000u); }
; __device__ __forceinline__ void peer_tile(const Args& A, LAS unsigned char* lds, int tile) {
;     ...
;     for (int ti = 0; ti < 8; ++ti) {
;         const int tl = 8 * w + ti;
;         const u32x2 e0 = SEL[tl * 128 + lane], e1 = SEL[tl * 128 + 64 + lane];
;         const int p0 = (int)(e0.x >> 10), p1 = (int)(e1.x >> 10);
;         int off = 0;
;         for (int p = 0; p < 16; ++p) {
;     ...
;         for (int tk = 0; tk < 4; ++tk) { const size_t m = (size_t)tile * 64 + tb + tk;
;             { const u32x4 ra = *(const u32x4*)(A3 + m * 1024 + 16 * lane), rb = *(const u32x4*)(A3 + m * 1024 + 16 * lane + 8);
;               float xr_; { const f32x4 p0 = *(const f32x4*)(RSq + m * 16), p1 = *(const f32x4*)(RSq + m * 16 + 4), p2 = *(const f32x4*)(RSq + m * 16 + 8), p3 = *(const f32x4*)(RSq + m * 16 + 12);
;                 const f32x4 ps = (p0 + p1) + (p2 + p3); xr_ = rsqrtf(((ps[0] + ps[1]) + (ps[2] + ps[3])) * (1.f / 1024.f) + 1e-6f); }
;               const unsigned rr[8] = {ra.x, ra.y, ra.z, ra.w, rb.x, rb.y, rb.z, rb.w}; unsigned hh[8];
;               const float* sp = MOD + (int)(m >> 11) * 6144 + 3072 + 16 * lane;
; #pragma unroll
;               for (int q = 0; q < 8; ++q) { const f32x2 sh = *(const f32x2*)(sp + 2 * q); hh[q] = pk2(bflo(rr[q]) * xr_ + sh[0], bfhi(rr[q]) * xr_ + sh[1]); }
;               xpa[tk] = (u32x4){hh[0], hh[1], hh[2], hh[3]}; xpb[tk] = (u32x4){hh[4], hh[5], hh[6], hh[7]}; }
; #pragma unroll
;             for (int q = 0; q < 8; ++q) oacc[tk][q] = (f32x2){0.f, 0.f}; }
	v_pk_add_f32 v[216:217], v[216:217], v[220:221]
	v_pk_add_f32 v[218:219], v[218:219], v[222:223]
	v_pk_add_f32 v[224:225], v[224:225], v[228:229]
	v_pk_add_f32 v[226:227], v[226:227], v[230:231]
	v_pk_add_f32 v[216:217], v[216:217], v[224:225]
	v_pk_add_f32 v[218:219], v[218:219], v[226:227]
	v_add_f32_e32 v216, v216, v217
	v_add_f32_e32 v218, v218, v219
	v_add_f32_e32 v216, v216, v218
	v_fmamk_f32 v216, v216, 0x3a800000, v243
	v_rsq_f32_e32 v216, v216
	v_pk_add_f32 v[232:233], v[232:233], v[236:237]
	v_pk_add_f32 v[234:235], v[234:235], v[238:239]
	v_pk_add_f32 v[248:249], v[248:249], v[252:253]
	v_pk_add_f32 v[250:251], v[250:251], v[254:255]
	v_pk_add_f32 v[232:233], v[232:233], v[248:249]
	v_pk_add_f32 v[234:235], v[234:235], v[250:251]
	v_add_f32_e32 v232, v232, v233
	v_add_f32_e32 v234, v234, v235
	v_add_f32_e32 v232, v232, v234
	v_fmamk_f32 v232, v232, 0x3a800000, v243
	v_rsq_f32_e32 v232, v232
	v_lshlrev_b32_e32 v208, 16, v176
	v_and_b32_e32 v209, 0xffff0000, v176
	v_fma_f32 v208, v208, v216, v192
	v_fma_f32 v209, v209, v216, v193
	v_cvt_pk_bf16_f32 v210, v208, v209
	v_lshlrev_b32_e32 v96, 16, v210
	v_and_b32_e32 v97, 0xffff0000, v210
	v_lshlrev_b32_e32 v208, 16, v177
	v_and_b32_e32 v209, 0xffff0000, v177
	v_fma_f32 v208, v208, v216, v194
	v_fma_f32 v209, v209, v216, v195
	v_cvt_pk_bf16_f32 v210, v208, v209
	v_lshlrev_b32_e32 v98, 16, v210
	v_and_b32_e32 v99, 0xffff0000, v210
	v_lshlrev_b32_e32 v208, 16, v178
	v_and_b32_e32 v209, 0xffff0000, v178
	v_fma_f32 v208, v208, v216, v196
	v_fma_f32 v209, v209, v216, v197
	v_cvt_pk_bf16_f32 v210, v208, v209
	v_lshlrev_b32_e32 v100, 16, v210
	v_and_b32_e32 v101, 0xffff0000, v210
	v_lshlrev_b32_e32 v208, 16, v179
	v_and_b32_e32 v209, 0xffff0000, v179
	v_fma_f32 v208, v208, v216, v198
	v_fma_f32 v209, v209, v216, v199
	v_cvt_pk_bf16_f32 v210, v208, v209
	v_lshlrev_b32_e32 v102, 16, v210
	v_and_b32_e32 v103, 0xffff0000, v210
	v_lshlrev_b32_e32 v208, 16, v180
	v_and_b32_e32 v209, 0xffff0000, v180
	v_fma_f32 v208, v208, v216, v200
	v_fma_f32 v209, v209, v216, v201
	v_cvt_pk_bf16_f32 v210, v208, v209
	v_lshlrev_b32_e32 v104, 16, v210
	v_and_b32_e32 v105, 0xffff0000, v210
	v_lshlrev_b32_e32 v208, 16, v181
	v_and_b32_e32 v209, 0xffff0000, v181
	v_fma_f32 v208, v208, v216, v202
	v_fma_f32 v209, v209, v216, v203
	v_cvt_pk_bf16_f32 v210, v208, v209
	v_lshlrev_b32_e32 v106, 16, v210
	v_and_b32_e32 v107, 0xffff0000, v210
	v_lshlrev_b32_e32 v208, 16, v182
	v_and_b32_e32 v209, 0xffff0000, v182
	v_fma_f32 v208, v208, v216, v204
	v_fma_f32 v209, v209, v216, v205
	v_cvt_pk_bf16_f32 v210, v208, v209
	v_lshlrev_b32_e32 v108, 16, v210
	v_and_b32_e32 v109, 0xffff0000, v210
	v_lshlrev_b32_e32 v208, 16, v183
	v_and_b32_e32 v209, 0xffff0000, v183
	v_fma_f32 v208, v208, v216, v206
	v_fma_f32 v209, v209, v216, v207
	v_cvt_pk_bf16_f32 v210, v208, v209
	v_lshlrev_b32_e32 v110, 16, v210
	v_and_b32_e32 v111, 0xffff0000, v210
	v_lshlrev_b32_e32 v208, 16, v184
	v_and_b32_e32 v209, 0xffff0000, v184
	v_fma_f32 v208, v208, v232, v192
	v_fma_f32 v209, v209, v232, v193
	v_cvt_pk_bf16_f32 v210, v208, v209
	v_lshlrev_b32_e32 v112, 16, v210
	v_and_b32_e32 v113, 0xffff0000, v210
	v_lshlrev_b32_e32 v208, 16, v185
	v_and_b32_e32 v209, 0xffff0000, v185
	v_fma_f32 v208, v208, v232, v194
	v_fma_f32 v209, v209, v232, v195
	v_cvt_pk_bf16_f32 v210, v208, v209
	v_lshlrev_b32_e32 v114, 16, v210
	v_and_b32_e32 v115, 0xffff0000, v210
	v_lshlrev_b32_e32 v208, 16, v186
	v_and_b32_e32 v209, 0xffff0000, v186
	v_fma_f32 v208, v208, v232, v196
	v_fma_f32 v209, v209, v232, v197
	v_cvt_pk_bf16_f32 v210, v208, v209
	v_lshlrev_b32_e32 v116, 16, v210
	v_and_b32_e32 v117, 0xffff0000, v210
	v_lshlrev_b32_e32 v208, 16, v187
	v_and_b32_e32 v209, 0xffff0000, v187
	v_fma_f32 v208, v208, v232, v198
	v_fma_f32 v209, v209, v232, v199
	v_cvt_pk_bf16_f32 v210, v208, v209
	v_lshlrev_b32_e32 v118, 16, v210
	v_and_b32_e32 v119, 0xffff0000, v210
	v_lshlrev_b32_e32 v208, 16, v188
	v_and_b32_e32 v209, 0xffff0000, v188
	v_fma_f32 v208, v208, v232, v200
	v_fma_f32 v209, v209, v232, v201
	v_cvt_pk_bf16_f32 v210, v208, v209
	v_lshlrev_b32_e32 v120, 16, v210
	v_and_b32_e32 v121, 0xffff0000, v210
	v_lshlrev_b32_e32 v208, 16, v189
	v_and_b32_e32 v209, 0xffff0000, v189
	v_fma_f32 v208, v208, v232, v202
	v_fma_f32 v209, v209, v232, v203
	v_cvt_pk_bf16_f32 v210, v208, v209
	v_lshlrev_b32_e32 v122, 16, v210
	v_and_b32_e32 v123, 0xffff0000, v210
	v_lshlrev_b32_e32 v208, 16, v190
	v_and_b32_e32 v209, 0xffff0000, v190
	v_fma_f32 v208, v208, v232, v204
	v_fma_f32 v209, v209, v232, v205
	v_cvt_pk_bf16_f32 v210, v208, v209
	v_lshlrev_b32_e32 v124, 16, v210
	v_and_b32_e32 v125, 0xffff0000, v210
	v_lshlrev_b32_e32 v208, 16, v191
	v_and_b32_e32 v209, 0xffff0000, v191
	v_fma_f32 v208, v208, v232, v206
	v_fma_f32 v209, v209, v232, v207
	v_cvt_pk_bf16_f32 v210, v208, v209
	v_lshlrev_b32_e32 v126, 16, v210
	v_and_b32_e32 v127, 0xffff0000, v210
	s_nop 0
	v_mov_b32_e32 v216, 0x7fffffff
	v_mov_b32_e32 v217, 0x7fffffff
	v_mov_b32_e32 v218, 0x7fffffff
	v_mov_b32_e32 v219, 0x7fffffff
	v_mov_b32_e32 v224, 0
	v_mov_b32_e32 v225, 0
	v_mov_b32_e32 v226, 0
	v_mov_b32_e32 v227, 0
	v_add_u32_e32 v220, s22, v240
	ds_write_b128 v220, v[216:219] offset:0
	ds_write_b128 v220, v[224:227] offset:4992
	ds_write_b128 v220, v[216:219] offset:1024
	ds_write_b128 v220, v[224:227] offset:6016
	ds_write_b128 v220, v[216:219] offset:2048
	ds_write_b128 v220, v[224:227] offset:7040
	ds_write_b128 v220, v[216:219] offset:3072
	ds_write_b128 v220, v[224:227] offset:8064
	s_mov_b32 exec_hi, 0x00ffffff
	ds_write_b128 v220, v[216:219] offset:4096
	s_mov_b32 exec_hi, 0x000fffff
	ds_write_b128 v220, v[224:227] offset:9088
	s_mov_b64 exec, -1
	v_lshrrev_b32_e32 v222, 1, v240
	s_lshl_b32 s0, s76, 10
	s_add_i32 s0, s0, 0x11000
	v_add_u32_e32 v221, s0, v222
	ds_read_b64 v[128:129], v221 offset:0
	ds_read_b64 v[130:131], v221 offset:512
	ds_read_b64 v[132:133], v221 offset:1024
	ds_read_b64 v[134:135], v221 offset:1536
	ds_read_b64 v[136:137], v221 offset:2048
	ds_read_b64 v[138:139], v221 offset:2560
	ds_read_b64 v[140:141], v221 offset:3072
	ds_read_b64 v[142:143], v221 offset:3584
	ds_read_b64 v[144:145], v221 offset:4096
	ds_read_b64 v[146:147], v221 offset:4608
	ds_read_b64 v[148:149], v221 offset:5120
	ds_read_b64 v[150:151], v221 offset:5632
	ds_read_b64 v[152:153], v221 offset:6144
	ds_read_b64 v[154:155], v221 offset:6656
	ds_read_b64 v[156:157], v221 offset:7168
	ds_read_b64 v[158:159], v221 offset:7680
	v_mov_b32_e32 v212, 0
	s_waitcnt lgkmcnt(0)
; __device__ __forceinline__ void peer_tile(const Args& A, LAS unsigned char* lds, int tile) {
;     ...
;     for (int ti = 0; ti < 8; ++ti) {
;         const int tl = 8 * w + ti;
;         const u32x2 e0 = SEL[tl * 128 + lane], e1 = SEL[tl * 128 + 64 + lane];
;         const int p0 = (int)(e0.x >> 10), p1 = (int)(e1.x >> 10);
;         int off = 0;
;         for (int p = 0; p < 16; ++p) {
;             const unsigned long long m0 = __ballot(p0 == p), m1 = __ballot(p1 == p);
;             const int c0 = __popcll(m0), c1 = __popcll(m1);
;             const int r0 = __builtin_amdgcn_mbcnt_hi((unsigned)(m0 >> 32), __builtin_amdgcn_mbcnt_lo((unsigned)m0, 0u));
;             const int r1 = __builtin_amdgcn_mbcnt_hi((unsigned)(m1 >> 32), __builtin_amdgcn_mbcnt_lo((unsigned)m1, 0u));
;             if (p0 == p) SORT[tl * 128 + off + r0] = e0;
;             if (p1 == p) SORT[tl * 128 + off + c0 + r1] = e1;
;             if (lane == 0) OFFS[tl * 17 + p] = off;
;             off += c0 + c1;
;         }
;         if (lane == 0) OFFS[tl * 17 + 16] = off;
;     }
	v_lshrrev_b32_e32 v160, 11, v128
	v_lshrrev_b32_e32 v161, 11, v130
	v_lshrrev_b32_e32 v162, 11, v132
	v_lshrrev_b32_e32 v163, 11, v134
	v_lshrrev_b32_e32 v164, 11, v136
	v_lshrrev_b32_e32 v165, 11, v138
	v_lshrrev_b32_e32 v166, 11, v140
	v_lshrrev_b32_e32 v167, 11, v142
	v_lshrrev_b32_e32 v168, 11, v144
	v_lshrrev_b32_e32 v169, 11, v146
	v_lshrrev_b32_e32 v170, 11, v148
	v_lshrrev_b32_e32 v171, 11, v150
	v_lshrrev_b32_e32 v172, 11, v152
	v_lshrrev_b32_e32 v173, 11, v154
	v_lshrrev_b32_e32 v174, 11, v156
	v_lshrrev_b32_e32 v175, 11, v158
	s_mov_b32 s74, 0
	s_mov_b32 s75, 0
	s_mov_b32 s37, 0
.Lbuild_c:
	v_cmp_eq_u32_e64 s[68:69], s74, v160
	v_cmp_eq_u32_e64 s[70:71], s74, v161
	s_nop 0
	s_lshl_b32 s3, s75, 4
	s_add_i32 s3, s3, s22
	s_bcnt1_i32_b64 s0, s[68:69]
	s_bcnt1_i32_b64 s1, s[70:71]
	v_mbcnt_lo_u32_b32 v222, s68, 0
	v_mbcnt_hi_u32_b32 v222, s69, v222
	v_mbcnt_lo_u32_b32 v223, s70, 0
	v_mbcnt_hi_u32_b32 v223, s71, v223
	v_add_u32_e32 v223, s0, v223
	v_lshl_add_u32 v222, v222, 2, s3
	v_lshl_add_u32 v223, v223, 2, s3
	s_mov_b64 exec, s[68:69]
	ds_write_b32 v222, v128
	ds_write_b32 v222, v129 offset:4992
	s_mov_b64 exec, s[70:71]
	ds_write_b32 v223, v130
	ds_write_b32 v223, v131 offset:4992
	s_add_i32 s0, s0, s1
	s_add_i32 s0, s0, 3
	s_lshr_b32 s0, s0, 2
	s_lshl_b64 s[38:39], 1, s37
	s_mov_b64 exec, s[38:39]
	v_mov_b32_e32 v212, s0
	s_mov_b64 exec, -1
	s_add_i32 s75, s75, s0
	s_add_i32 s37, s37, 1
	v_cmp_eq_u32_e64 s[68:69], s74, v162
	v_cmp_eq_u32_e64 s[70:71], s74, v163
	s_nop 0
	s_lshl_b32 s3, s75, 4
	s_add_i32 s3, s3, s22
	s_bcnt1_i32_b64 s0, s[68:69]
	s_bcnt1_i32_b64 s1, s[70:71]
	v_mbcnt_lo_u32_b32 v222, s68, 0
	v_mbcnt_hi_u32_b32 v222, s69, v222
	v_mbcnt_lo_u32_b32 v223, s70, 0
	v_mbcnt_hi_u32_b32 v223, s71, v223
	v_add_u32_e32 v223, s0, v223
	v_lshl_add_u32 v222, v222, 2, s3
	v_lshl_add_u32 v223, v223, 2, s3
	s_mov_b64 exec, s[68:69]
	ds_write_b32 v222, v132
	ds_write_b32 v222, v133 offset:4992
	s_mov_b64 exec, s[70:71]
	ds_write_b32 v223, v134
	ds_write_b32 v223, v135 offset:4992
	s_add_i32 s0, s0, s1
	s_add_i32 s0, s0, 3
	s_lshr_b32 s0, s0, 2
	s_lshl_b64 s[38:39], 1, s37
	s_mov_b64 exec, s[38:39]
	v_mov_b32_e32 v212, s0
	s_mov_b64 exec, -1
	s_add_i32 s75, s75, s0
	s_add_i32 s37, s37, 1
	v_cmp_eq_u32_e64 s[68:69], s74, v164
	v_cmp_eq_u32_e64 s[70:71], s74, v165
	s_nop 0
	s_lshl_b32 s3, s75, 4
	s_add_i32 s3, s3, s22
	s_bcnt1_i32_b64 s0, s[68:69]
	s_bcnt1_i32_b64 s1, s[70:71]
	v_mbcnt_lo_u32_b32 v222, s68, 0
	v_mbcnt_hi_u32_b32 v222, s69, v222
	v_mbcnt_lo_u32_b32 v223, s70, 0
	v_mbcnt_hi_u32_b32 v223, s71, v223
	v_add_u32_e32 v223, s0, v223
	v_lshl_add_u32 v222, v222, 2, s3
	v_lshl_add_u32 v223, v223, 2, s3
	s_mov_b64 exec, s[68:69]
	ds_write_b32 v222, v136
	ds_write_b32 v222, v137 offset:4992
	s_mov_b64 exec, s[70:71]
	ds_write_b32 v223, v138
	ds_write_b32 v223, v139 offset:4992
	s_add_i32 s0, s0, s1
	s_add_i32 s0, s0, 3
	s_lshr_b32 s0, s0, 2
	s_lshl_b64 s[38:39], 1, s37
	s_mov_b64 exec, s[38:39]
	v_mov_b32_e32 v212, s0
	s_mov_b64 exec, -1
	s_add_i32 s75, s75, s0
	s_add_i32 s37, s37, 1
	v_cmp_eq_u32_e64 s[68:69], s74, v166
	v_cmp_eq_u32_e64 s[70:71], s74, v167
	s_nop 0
	s_lshl_b32 s3, s75, 4
	s_add_i32 s3, s3, s22
	s_bcnt1_i32_b64 s0, s[68:69]
	s_bcnt1_i32_b64 s1, s[70:71]
	v_mbcnt_lo_u32_b32 v222, s68, 0
	v_mbcnt_hi_u32_b32 v222, s69, v222
	v_mbcnt_lo_u32_b32 v223, s70, 0
	v_mbcnt_hi_u32_b32 v223, s71, v223
	v_add_u32_e32 v223, s0, v223
	v_lshl_add_u32 v222, v222, 2, s3
	v_lshl_add_u32 v223, v223, 2, s3
	s_mov_b64 exec, s[68:69]
	ds_write_b32 v222, v140
	ds_write_b32 v222, v141 offset:4992
	s_mov_b64 exec, s[70:71]
	ds_write_b32 v223, v142
	ds_write_b32 v223, v143 offset:4992
	s_add_i32 s0, s0, s1
	s_add_i32 s0, s0, 3
	s_lshr_b32 s0, s0, 2
	s_lshl_b64 s[38:39], 1, s37
	s_mov_b64 exec, s[38:39]
	v_mov_b32_e32 v212, s0
	s_mov_b64 exec, -1
	s_add_i32 s75, s75, s0
	s_add_i32 s37, s37, 1
	v_cmp_eq_u32_e64 s[68:69], s74, v168
	v_cmp_eq_u32_e64 s[70:71], s74, v169
	s_nop 0
	s_lshl_b32 s3, s75, 4
	s_add_i32 s3, s3, s22
	s_bcnt1_i32_b64 s0, s[68:69]
	s_bcnt1_i32_b64 s1, s[70:71]
	v_mbcnt_lo_u32_b32 v222, s68, 0
	v_mbcnt_hi_u32_b32 v222, s69, v222
	v_mbcnt_lo_u32_b32 v223, s70, 0
	v_mbcnt_hi_u32_b32 v223, s71, v223
	v_add_u32_e32 v223, s0, v223
	v_lshl_add_u32 v222, v222, 2, s3
	v_lshl_add_u32 v223, v223, 2, s3
	s_mov_b64 exec, s[68:69]
	ds_write_b32 v222, v144
	ds_write_b32 v222, v145 offset:4992
	s_mov_b64 exec, s[70:71]
	ds_write_b32 v223, v146
	ds_write_b32 v223, v147 offset:4992
	s_add_i32 s0, s0, s1
	s_add_i32 s0, s0, 3
	s_lshr_b32 s0, s0, 2
	s_lshl_b64 s[38:39], 1, s37
	s_mov_b64 exec, s[38:39]
	v_mov_b32_e32 v212, s0
	s_mov_b64 exec, -1
	s_add_i32 s75, s75, s0
	s_add_i32 s37, s37, 1
	v_cmp_eq_u32_e64 s[68:69], s74, v170
	v_cmp_eq_u32_e64 s[70:71], s74, v171
	s_nop 0
	s_lshl_b32 s3, s75, 4
	s_add_i32 s3, s3, s22
	s_bcnt1_i32_b64 s0, s[68:69]
	s_bcnt1_i32_b64 s1, s[70:71]
	v_mbcnt_lo_u32_b32 v222, s68, 0
	v_mbcnt_hi_u32_b32 v222, s69, v222
	v_mbcnt_lo_u32_b32 v223, s70, 0
	v_mbcnt_hi_u32_b32 v223, s71, v223
	v_add_u32_e32 v223, s0, v223
	v_lshl_add_u32 v222, v222, 2, s3
	v_lshl_add_u32 v223, v223, 2, s3
	s_mov_b64 exec, s[68:69]
	ds_write_b32 v222, v148
	ds_write_b32 v222, v149 offset:4992
	s_mov_b64 exec, s[70:71]
	ds_write_b32 v223, v150
	ds_write_b32 v223, v151 offset:4992
	s_add_i32 s0, s0, s1
	s_add_i32 s0, s0, 3
	s_lshr_b32 s0, s0, 2
	s_lshl_b64 s[38:39], 1, s37
	s_mov_b64 exec, s[38:39]
	v_mov_b32_e32 v212, s0
	s_mov_b64 exec, -1
	s_add_i32 s75, s75, s0
	s_add_i32 s37, s37, 1
	v_cmp_eq_u32_e64 s[68:69], s74, v172
	v_cmp_eq_u32_e64 s[70:71], s74, v173
	s_nop 0
	s_lshl_b32 s3, s75, 4
	s_add_i32 s3, s3, s22
	s_bcnt1_i32_b64 s0, s[68:69]
; #define IT_ADVANCE() do { it_j += 4; while (it_j >= it_end) { if (it_done) break; ++it_tk; if (it_tk == 4) { it_tk = 0; ++it_p; if (it_p == 16) { it_done = true; it_p = 15; it_j = 0; it_end = 1; break; } } \
;             it_j = __builtin_amdgcn_readfirstlane(OFFS[(tb + it_tk) * 17 + it_p]); it_end = __builtin_amdgcn_readfirstlane(OFFS[(tb + it_tk) * 17 + it_p + 1]); } } while (0)
; __device__ __forceinline__ void peer_tile(const Args& A, LAS unsigned char* lds, int tile) {
;     ...
;         u32x4 uA[4], vA[4], uB[4], vB[4]; float cgA = 0.f, suA = 0.f, svA = 0.f, cgB = 0.f, suB = 0.f, svB = 0.f;
; #pragma unroll
;         for (int k = 0; k < 4; ++k) { uA[k] = (u32x4){0u, 0u, 0u, 0u}; vA[k] = uA[k]; uB[k] = uA[k]; vB[k] = uA[k]; }
;         IT_ADVANCE();
;         LOAD_SET(uA, vA, cgA, suA, svA);
	s_bcnt1_i32_b64 s1, s[70:71]
	v_mbcnt_lo_u32_b32 v222, s68, 0
	v_mbcnt_hi_u32_b32 v222, s69, v222
	v_mbcnt_lo_u32_b32 v223, s70, 0
	v_mbcnt_hi_u32_b32 v223, s71, v223
	v_add_u32_e32 v223, s0, v223
	v_lshl_add_u32 v222, v222, 2, s3
	v_lshl_add_u32 v223, v223, 2, s3
	s_mov_b64 exec, s[68:69]
	ds_write_b32 v222, v152
	ds_write_b32 v222, v153 offset:4992
	s_mov_b64 exec, s[70:71]
	ds_write_b32 v223, v154
	ds_write_b32 v223, v155 offset:4992
	s_add_i32 s0, s0, s1
	s_add_i32 s0, s0, 3
	s_lshr_b32 s0, s0, 2
	s_lshl_b64 s[38:39], 1, s37
	s_mov_b64 exec, s[38:39]
	v_mov_b32_e32 v212, s0
	s_mov_b64 exec, -1
	s_add_i32 s75, s75, s0
	s_add_i32 s37, s37, 1
	v_cmp_eq_u32_e64 s[68:69], s74, v174
	v_cmp_eq_u32_e64 s[70:71], s74, v175
	s_nop 0
	s_lshl_b32 s3, s75, 4
	s_add_i32 s3, s3, s22
	s_bcnt1_i32_b64 s0, s[68:69]
	s_bcnt1_i32_b64 s1, s[70:71]
	v_mbcnt_lo_u32_b32 v222, s68, 0
	v_mbcnt_hi_u32_b32 v222, s69, v222
	v_mbcnt_lo_u32_b32 v223, s70, 0
	v_mbcnt_hi_u32_b32 v223, s71, v223
	v_add_u32_e32 v223, s0, v223
	v_lshl_add_u32 v222, v222, 2, s3
	v_lshl_add_u32 v223, v223, 2, s3
	s_mov_b64 exec, s[68:69]
	ds_write_b32 v222, v156
	ds_write_b32 v222, v157 offset:4992
	s_mov_b64 exec, s[70:71]
	ds_write_b32 v223, v158
	ds_write_b32 v223, v159 offset:4992
	s_add_i32 s0, s0, s1
	s_add_i32 s0, s0, 3
	s_lshr_b32 s0, s0, 2
	s_lshl_b64 s[38:39], 1, s37
	s_mov_b64 exec, s[38:39]
	v_mov_b32_e32 v212, s0
	s_mov_b64 exec, -1
	s_add_i32 s75, s75, s0
	s_add_i32 s37, s37, 1
	s_add_i32 s74, s74, 1
	s_cmp_lt_u32 s74, 8
	s_cbranch_scc1 .Lbuild_c
	s_mov_b32 s91, s75
	s_add_i32 s20, s91, 3
	s_and_b32 s20, s20, -4
	s_mov_b32 s24, s8
	s_and_b32 s25, s9, 0xffff
	s_mov_b32 s26, 0x10000
	s_mov_b32 s27, 0x00027000
	s_mov_b32 s28, s52
	s_and_b32 s29, s53, 0xffff
	s_mov_b32 s30, 0x10000
	s_mov_b32 s31, 0x00027000
	s_waitcnt vmcnt(0) lgkmcnt(0)
	v_mov_b32_e32 v213, s22
	v_mov_b32_e32 v233, v240
	v_mov_b32_e32 v235, v240
	v_mov_b32_e32 v237, v240
	v_mov_b32_e32 v239, v240
	ds_read_b32 v232, v213 offset:0
	ds_read_b32 v234, v213 offset:4
	ds_read_b32 v236, v213 offset:8
	ds_read_b32 v238, v213 offset:12
	s_waitcnt lgkmcnt(0)
	buffer_load_dwordx4 v[128:131], v[232:233], s[56:59], 0 idxen offen
	buffer_load_dwordx4 v[132:135], v[234:235], s[56:59], 0 idxen offen
	buffer_load_dwordx4 v[136:139], v[236:237], s[56:59], 0 idxen offen
	buffer_load_dwordx4 v[140:143], v[238:239], s[56:59], 0 idxen offen
	ds_read_b32 v232, v213 offset:16
	ds_read_b32 v234, v213 offset:20
	ds_read_b32 v236, v213 offset:24
	ds_read_b32 v238, v213 offset:28
	s_waitcnt lgkmcnt(0)
	buffer_load_dwordx4 v[144:147], v[232:233], s[56:59], 0 idxen offen
	buffer_load_dwordx4 v[148:151], v[234:235], s[56:59], 0 idxen offen
	buffer_load_dwordx4 v[152:155], v[236:237], s[56:59], 0 idxen offen
	buffer_load_dwordx4 v[156:159], v[238:239], s[56:59], 0 idxen offen
	ds_read_b32 v232, v213 offset:32
	ds_read_b32 v234, v213 offset:36
	ds_read_b32 v236, v213 offset:40
	ds_read_b32 v238, v213 offset:44
	s_waitcnt lgkmcnt(0)
	buffer_load_dwordx4 v[160:163], v[232:233], s[56:59], 0 idxen offen
	buffer_load_dwordx4 v[164:167], v[234:235], s[56:59], 0 idxen offen
	buffer_load_dwordx4 v[168:171], v[236:237], s[56:59], 0 idxen offen
	buffer_load_dwordx4 v[172:175], v[238:239], s[56:59], 0 idxen offen
	ds_read_b32 v232, v213 offset:48
	ds_read_b32 v234, v213 offset:52
	ds_read_b32 v236, v213 offset:56
	ds_read_b32 v238, v213 offset:60
	s_mov_b32 s21, 0
	s_mov_b32 s89, -1
	v_lshrrev_b32_e32 v208, 6, v240
	v_and_b32_e32 v208, 3, v208
	v_lshrrev_b32_e32 v209, 1, v208
	v_lshlrev_b32_e32 v208, 1, v208
	v_and_b32_e32 v208, 2, v208
	v_or_b32_e32 v208, v208, v209
	v_lshlrev_b32_e32 v208, 2, v208
	v_add3_u32 v211, v208, v247, s22
	ds_read_b32 v248, v211
	ds_read_b32 v249, v211 offset:4992
	s_branch .LU_sw0
.LU_t0_s0:
	s_cmp_ge_u32 s21, s20
	s_cbranch_scc1 .LU_done
	s_waitcnt lgkmcnt(0)
	v_lshlrev_b32_e32 v208, 2, v248
	buffer_load_dword v252, v208, s[24:27], 0 offen
	buffer_load_dword v253, v208, s[28:31], 0 offen
	buffer_load_dwordx4 v[176:179], v[232:233], s[56:59], 0 idxen offen
	buffer_load_dwordx4 v[180:183], v[234:235], s[56:59], 0 idxen offen
	buffer_load_dwordx4 v[184:187], v[236:237], s[56:59], 0 idxen offen
	buffer_load_dwordx4 v[188:191], v[238:239], s[56:59], 0 idxen offen
	ds_read_b32 v232, v213 offset:64
	ds_read_b32 v234, v213 offset:68
	ds_read_b32 v236, v213 offset:72
	ds_read_b32 v238, v213 offset:76
	s_waitcnt vmcnt(14)
	v_cvt_pk_f32_fp8_e32 v[224:225], v128
	v_cvt_pk_f32_fp8_e32 v[226:227], v132
	v_cvt_pk_f32_fp8_e32 v[228:229], v136
	v_cvt_pk_f32_fp8_e32 v[230:231], v140
	v_pk_mul_f32 v[216:217], v[224:225], v[0:1]
	v_pk_mul_f32 v[218:219], v[226:227], v[0:1]
	v_pk_mul_f32 v[220:221], v[228:229], v[0:1]
	v_pk_mul_f32 v[222:223], v[230:231], v[0:1]
	v_cvt_pk_f32_fp8_sdwa v[224:225], v128 src0_sel:WORD_1
	v_cvt_pk_f32_fp8_sdwa v[226:227], v132 src0_sel:WORD_1
	v_cvt_pk_f32_fp8_sdwa v[228:229], v136 src0_sel:WORD_1
	v_cvt_pk_f32_fp8_sdwa v[230:231], v140 src0_sel:WORD_1
	v_pk_fma_f32 v[216:217], v[224:225], v[2:3], v[216:217]
	v_pk_fma_f32 v[218:219], v[226:227], v[2:3], v[218:219]
	v_pk_fma_f32 v[220:221], v[228:229], v[2:3], v[220:221]
	v_pk_fma_f32 v[222:223], v[230:231], v[2:3], v[222:223]
	v_cvt_pk_f32_fp8_e32 v[224:225], v129
	v_cvt_pk_f32_fp8_e32 v[226:227], v133
	v_cvt_pk_f32_fp8_e32 v[228:229], v137
	v_cvt_pk_f32_fp8_e32 v[230:231], v141
	v_pk_fma_f32 v[216:217], v[224:225], v[4:5], v[216:217]
	v_pk_fma_f32 v[218:219], v[226:227], v[4:5], v[218:219]
	v_pk_fma_f32 v[220:221], v[228:229], v[4:5], v[220:221]
	v_pk_fma_f32 v[222:223], v[230:231], v[4:5], v[222:223]
	v_cvt_pk_f32_fp8_sdwa v[224:225], v129 src0_sel:WORD_1
	v_cvt_pk_f32_fp8_sdwa v[226:227], v133 src0_sel:WORD_1
	v_cvt_pk_f32_fp8_sdwa v[228:229], v137 src0_sel:WORD_1
	v_cvt_pk_f32_fp8_sdwa v[230:231], v141 src0_sel:WORD_1
	v_pk_fma_f32 v[216:217], v[224:225], v[6:7], v[216:217]
	v_pk_fma_f32 v[218:219], v[226:227], v[6:7], v[218:219]
	v_pk_fma_f32 v[220:221], v[228:229], v[6:7], v[220:221]
	v_pk_fma_f32 v[222:223], v[230:231], v[6:7], v[222:223]
	v_cvt_pk_f32_fp8_e32 v[224:225], v130
	v_cvt_pk_f32_fp8_e32 v[226:227], v134
	v_cvt_pk_f32_fp8_e32 v[228:229], v138
	v_cvt_pk_f32_fp8_e32 v[230:231], v142
	v_pk_fma_f32 v[216:217], v[224:225], v[8:9], v[216:217]
	v_pk_fma_f32 v[218:219], v[226:227], v[8:9], v[218:219]
	v_pk_fma_f32 v[220:221], v[228:229], v[8:9], v[220:221]
	v_pk_fma_f32 v[222:223], v[230:231], v[8:9], v[222:223]
	v_cvt_pk_f32_fp8_sdwa v[224:225], v130 src0_sel:WORD_1
	v_cvt_pk_f32_fp8_sdwa v[226:227], v134 src0_sel:WORD_1
	v_cvt_pk_f32_fp8_sdwa v[228:229], v138 src0_sel:WORD_1
	v_cvt_pk_f32_fp8_sdwa v[230:231], v142 src0_sel:WORD_1
	v_pk_fma_f32 v[216:217], v[224:225], v[10:11], v[216:217]
	v_pk_fma_f32 v[218:219], v[226:227], v[10:11], v[218:219]
	v_pk_fma_f32 v[220:221], v[228:229], v[10:11], v[220:221]
	v_pk_fma_f32 v[222:223], v[230:231], v[10:11], v[222:223]
	v_cvt_pk_f32_fp8_e32 v[224:225], v131
	v_cvt_pk_f32_fp8_e32 v[226:227], v135
	v_cvt_pk_f32_fp8_e32 v[228:229], v139
	v_cvt_pk_f32_fp8_e32 v[230:231], v143
	v_pk_fma_f32 v[216:217], v[224:225], v[12:13], v[216:217]
	v_pk_fma_f32 v[218:219], v[226:227], v[12:13], v[218:219]
	v_pk_fma_f32 v[220:221], v[228:229], v[12:13], v[220:221]
	v_pk_fma_f32 v[222:223], v[230:231], v[12:13], v[222:223]
	v_cvt_pk_f32_fp8_sdwa v[224:225], v131 src0_sel:WORD_1
	v_cvt_pk_f32_fp8_sdwa v[226:227], v135 src0_sel:WORD_1
	v_cvt_pk_f32_fp8_sdwa v[228:229], v139 src0_sel:WORD_1
	v_cvt_pk_f32_fp8_sdwa v[230:231], v143 src0_sel:WORD_1
	v_pk_fma_f32 v[216:217], v[224:225], v[14:15], v[216:217]
	v_pk_fma_f32 v[218:219], v[226:227], v[14:15], v[218:219]
	v_pk_fma_f32 v[220:221], v[228:229], v[14:15], v[220:221]
	v_pk_fma_f32 v[222:223], v[230:231], v[14:15], v[222:223]
	v_add_f32_e32 v192, v216, v217
	v_add_f32_e32 v193, v218, v219
	v_add_f32_e32 v194, v220, v221
	v_add_f32_e32 v195, v222, v223
	s_sub_i32 s90, s90, 1
	s_cmp_eq_u32 s90, 0
	s_cbranch_scc1 .LU_sw1
.LU_t0_s1:
	s_waitcnt lgkmcnt(0)
	buffer_load_dwordx4 v[128:131], v[232:233], s[56:59], 0 idxen offen
	buffer_load_dwordx4 v[132:135], v[234:235], s[56:59], 0 idxen offen
	buffer_load_dwordx4 v[136:139], v[236:237], s[56:59], 0 idxen offen
	buffer_load_dwordx4 v[140:143], v[238:239], s[56:59], 0 idxen offen
	ds_read_b32 v232, v213 offset:80
	ds_read_b32 v234, v213 offset:84
	ds_read_b32 v236, v213 offset:88
	ds_read_b32 v238, v213 offset:92
	s_waitcnt vmcnt(14)
	v_cvt_pk_f32_fp8_e32 v[224:225], v144
	v_cvt_pk_f32_fp8_e32 v[226:227], v148
	v_cvt_pk_f32_fp8_e32 v[228:229], v152
	v_cvt_pk_f32_fp8_e32 v[230:231], v156
	v_pk_mul_f32 v[216:217], v[224:225], v[0:1]
	v_pk_mul_f32 v[218:219], v[226:227], v[0:1]
	v_pk_mul_f32 v[220:221], v[228:229], v[0:1]
	v_pk_mul_f32 v[222:223], v[230:231], v[0:1]
	v_cvt_pk_f32_fp8_sdwa v[224:225], v144 src0_sel:WORD_1
	v_cvt_pk_f32_fp8_sdwa v[226:227], v148 src0_sel:WORD_1
	v_cvt_pk_f32_fp8_sdwa v[228:229], v152 src0_sel:WORD_1
	v_cvt_pk_f32_fp8_sdwa v[230:231], v156 src0_sel:WORD_1
	v_pk_fma_f32 v[216:217], v[224:225], v[2:3], v[216:217]
	v_pk_fma_f32 v[218:219], v[226:227], v[2:3], v[218:219]
	v_pk_fma_f32 v[220:221], v[228:229], v[2:3], v[220:221]
	v_pk_fma_f32 v[222:223], v[230:231], v[2:3], v[222:223]
	v_cvt_pk_f32_fp8_e32 v[224:225], v145
	v_cvt_pk_f32_fp8_e32 v[226:227], v149
	v_cvt_pk_f32_fp8_e32 v[228:229], v153
	v_cvt_pk_f32_fp8_e32 v[230:231], v157
	v_pk_fma_f32 v[216:217], v[224:225], v[4:5], v[216:217]
	v_pk_fma_f32 v[218:219], v[226:227], v[4:5], v[218:219]
	v_pk_fma_f32 v[220:221], v[228:229], v[4:5], v[220:221]
	v_pk_fma_f32 v[222:223], v[230:231], v[4:5], v[222:223]
	v_cvt_pk_f32_fp8_sdwa v[224:225], v145 src0_sel:WORD_1
	v_cvt_pk_f32_fp8_sdwa v[226:227], v149 src0_sel:WORD_1
	v_cvt_pk_f32_fp8_sdwa v[228:229], v153 src0_sel:WORD_1
	v_cvt_pk_f32_fp8_sdwa v[230:231], v157 src0_sel:WORD_1
	v_pk_fma_f32 v[216:217], v[224:225], v[6:7], v[216:217]
	v_pk_fma_f32 v[218:219], v[226:227], v[6:7], v[218:219]
	v_pk_fma_f32 v[220:221], v[228:229], v[6:7], v[220:221]
	v_pk_fma_f32 v[222:223], v[230:231], v[6:7], v[222:223]
	v_cvt_pk_f32_fp8_e32 v[224:225], v146
	v_cvt_pk_f32_fp8_e32 v[226:227], v150
	v_cvt_pk_f32_fp8_e32 v[228:229], v154
	v_cvt_pk_f32_fp8_e32 v[230:231], v158
	v_pk_fma_f32 v[216:217], v[224:225], v[8:9], v[216:217]
	v_pk_fma_f32 v[218:219], v[226:227], v[8:9], v[218:219]
	v_pk_fma_f32 v[220:221], v[228:229], v[8:9], v[220:221]
	v_pk_fma_f32 v[222:223], v[230:231], v[8:9], v[222:223]
	v_cvt_pk_f32_fp8_sdwa v[224:225], v146 src0_sel:WORD_1
	v_cvt_pk_f32_fp8_sdwa v[226:227], v150 src0_sel:WORD_1
	v_cvt_pk_f32_fp8_sdwa v[228:229], v154 src0_sel:WORD_1
	v_cvt_pk_f32_fp8_sdwa v[230:231], v158 src0_sel:WORD_1
	v_pk_fma_f32 v[216:217], v[224:225], v[10:11], v[216:217]
	v_pk_fma_f32 v[218:219], v[226:227], v[10:11], v[218:219]
	v_pk_fma_f32 v[220:221], v[228:229], v[10:11], v[220:221]
	v_pk_fma_f32 v[222:223], v[230:231], v[10:11], v[222:223]
	v_cvt_pk_f32_fp8_e32 v[224:225], v147
	v_cvt_pk_f32_fp8_e32 v[226:227], v151
	v_cvt_pk_f32_fp8_e32 v[228:229], v155
	v_cvt_pk_f32_fp8_e32 v[230:231], v159
	v_pk_fma_f32 v[216:217], v[224:225], v[12:13], v[216:217]
	v_pk_fma_f32 v[218:219], v[226:227], v[12:13], v[218:219]
	v_pk_fma_f32 v[220:221], v[228:229], v[12:13], v[220:221]
	v_pk_fma_f32 v[222:223], v[230:231], v[12:13], v[222:223]
	v_cvt_pk_f32_fp8_sdwa v[224:225], v147 src0_sel:WORD_1
	v_cvt_pk_f32_fp8_sdwa v[226:227], v151 src0_sel:WORD_1
	v_cvt_pk_f32_fp8_sdwa v[228:229], v155 src0_sel:WORD_1
	v_cvt_pk_f32_fp8_sdwa v[230:231], v159 src0_sel:WORD_1
	v_pk_fma_f32 v[216:217], v[224:225], v[14:15], v[216:217]
	v_pk_fma_f32 v[218:219], v[226:227], v[14:15], v[218:219]
	v_pk_fma_f32 v[220:221], v[228:229], v[14:15], v[220:221]
	v_pk_fma_f32 v[222:223], v[230:231], v[14:15], v[222:223]
	v_add_f32_e32 v196, v216, v217
	v_add_f32_e32 v197, v218, v219
	v_add_f32_e32 v198, v220, v221
	v_add_f32_e32 v199, v222, v223
	s_sub_i32 s90, s90, 1
	s_cmp_eq_u32 s90, 0
	s_cbranch_scc1 .LU_sw2
.LU_t0_s2:
	s_waitcnt lgkmcnt(0)
	buffer_load_dwordx4 v[144:147], v[232:233], s[56:59], 0 idxen offen
	buffer_load_dwordx4 v[148:151], v[234:235], s[56:59], 0 idxen offen
	buffer_load_dwordx4 v[152:155], v[236:237], s[56:59], 0 idxen offen
	buffer_load_dwordx4 v[156:159], v[238:239], s[56:59], 0 idxen offen
	ds_read_b32 v232, v213 offset:96
	ds_read_b32 v234, v213 offset:100
	ds_read_b32 v236, v213 offset:104
	ds_read_b32 v238, v213 offset:108
	s_waitcnt vmcnt(14)
	v_cvt_pk_f32_fp8_e32 v[224:225], v160
	v_cvt_pk_f32_fp8_e32 v[226:227], v164
	v_cvt_pk_f32_fp8_e32 v[228:229], v168
	v_cvt_pk_f32_fp8_e32 v[230:231], v172
	v_pk_mul_f32 v[216:217], v[224:225], v[0:1]
	v_pk_mul_f32 v[218:219], v[226:227], v[0:1]
	v_pk_mul_f32 v[220:221], v[228:229], v[0:1]
	v_pk_mul_f32 v[222:223], v[230:231], v[0:1]
	v_cvt_pk_f32_fp8_sdwa v[224:225], v160 src0_sel:WORD_1
	v_cvt_pk_f32_fp8_sdwa v[226:227], v164 src0_sel:WORD_1
	v_cvt_pk_f32_fp8_sdwa v[228:229], v168 src0_sel:WORD_1
	v_cvt_pk_f32_fp8_sdwa v[230:231], v172 src0_sel:WORD_1
	v_pk_fma_f32 v[216:217], v[224:225], v[2:3], v[216:217]
	v_pk_fma_f32 v[218:219], v[226:227], v[2:3], v[218:219]
	v_pk_fma_f32 v[220:221], v[228:229], v[2:3], v[220:221]
	v_pk_fma_f32 v[222:223], v[230:231], v[2:3], v[222:223]
	v_cvt_pk_f32_fp8_e32 v[224:225], v161
	v_cvt_pk_f32_fp8_e32 v[226:227], v165
	v_cvt_pk_f32_fp8_e32 v[228:229], v169
	v_cvt_pk_f32_fp8_e32 v[230:231], v173
	v_pk_fma_f32 v[216:217], v[224:225], v[4:5], v[216:217]
	v_pk_fma_f32 v[218:219], v[226:227], v[4:5], v[218:219]
	v_pk_fma_f32 v[220:221], v[228:229], v[4:5], v[220:221]
	v_pk_fma_f32 v[222:223], v[230:231], v[4:5], v[222:223]
	v_cvt_pk_f32_fp8_sdwa v[224:225], v161 src0_sel:WORD_1
	v_cvt_pk_f32_fp8_sdwa v[226:227], v165 src0_sel:WORD_1
	v_cvt_pk_f32_fp8_sdwa v[228:229], v169 src0_sel:WORD_1
	v_cvt_pk_f32_fp8_sdwa v[230:231], v173 src0_sel:WORD_1
	v_pk_fma_f32 v[216:217], v[224:225], v[6:7], v[216:217]
	v_pk_fma_f32 v[218:219], v[226:227], v[6:7], v[218:219]
	v_pk_fma_f32 v[220:221], v[228:229], v[6:7], v[220:221]
	v_pk_fma_f32 v[222:223], v[230:231], v[6:7], v[222:223]
	v_cvt_pk_f32_fp8_e32 v[224:225], v162
	v_cvt_pk_f32_fp8_e32 v[226:227], v166
	v_cvt_pk_f32_fp8_e32 v[228:229], v170
	v_cvt_pk_f32_fp8_e32 v[230:231], v174
	v_pk_fma_f32 v[216:217], v[224:225], v[8:9], v[216:217]
	v_pk_fma_f32 v[218:219], v[226:227], v[8:9], v[218:219]
	v_pk_fma_f32 v[220:221], v[228:229], v[8:9], v[220:221]
	v_pk_fma_f32 v[222:223], v[230:231], v[8:9], v[222:223]
	v_cvt_pk_f32_fp8_sdwa v[224:225], v162 src0_sel:WORD_1
	v_cvt_pk_f32_fp8_sdwa v[226:227], v166 src0_sel:WORD_1
	v_cvt_pk_f32_fp8_sdwa v[228:229], v170 src0_sel:WORD_1
	v_cvt_pk_f32_fp8_sdwa v[230:231], v174 src0_sel:WORD_1
	v_pk_fma_f32 v[216:217], v[224:225], v[10:11], v[216:217]
	v_pk_fma_f32 v[218:219], v[226:227], v[10:11], v[218:219]
	v_pk_fma_f32 v[220:221], v[228:229], v[10:11], v[220:221]
	v_pk_fma_f32 v[222:223], v[230:231], v[10:11], v[222:223]
	v_cvt_pk_f32_fp8_e32 v[224:225], v163
	v_cvt_pk_f32_fp8_e32 v[226:227], v167
	v_cvt_pk_f32_fp8_e32 v[228:229], v171
	v_cvt_pk_f32_fp8_e32 v[230:231], v175
	v_pk_fma_f32 v[216:217], v[224:225], v[12:13], v[216:217]
	v_pk_fma_f32 v[218:219], v[226:227], v[12:13], v[218:219]
	v_pk_fma_f32 v[220:221], v[228:229], v[12:13], v[220:221]
	v_pk_fma_f32 v[222:223], v[230:231], v[12:13], v[222:223]
	v_cvt_pk_f32_fp8_sdwa v[224:225], v163 src0_sel:WORD_1
	v_cvt_pk_f32_fp8_sdwa v[226:227], v167 src0_sel:WORD_1
	v_cvt_pk_f32_fp8_sdwa v[228:229], v171 src0_sel:WORD_1
	v_cvt_pk_f32_fp8_sdwa v[230:231], v175 src0_sel:WORD_1
	v_pk_fma_f32 v[216:217], v[224:225], v[14:15], v[216:217]
	v_pk_fma_f32 v[218:219], v[226:227], v[14:15], v[218:219]
	v_pk_fma_f32 v[220:221], v[228:229], v[14:15], v[220:221]
	v_pk_fma_f32 v[222:223], v[230:231], v[14:15], v[222:223]
	v_add_f32_e32 v200, v216, v217
	v_add_f32_e32 v201, v218, v219
	v_add_f32_e32 v202, v220, v221
	v_add_f32_e32 v203, v222, v223
	s_sub_i32 s90, s90, 1
	s_cmp_eq_u32 s90, 0
	s_cbranch_scc1 .LU_sw3
; __device__ __forceinline__ float gelu_fast(float v) {
;     const float av = fabsf(v), tt = __builtin_amdgcn_rcpf(av * 0.2316418882f + 1.0f);
;     float q = tt * 0.5307027145f + (-0.7265760135f); q = q * tt + 0.7107068705f; q = q * tt + (-0.142248368f); q = q * tt + 0.127414796f; q = q * tt;
;     const float e = __builtin_amdgcn_exp2f((v * v) * (-0.72134752044f));
;     const float m = v * (q * e);
;     return v < 0.f ? m : v - m;
; }
.LU_t0_s3:
	s_waitcnt lgkmcnt(0)
	buffer_load_dwordx4 v[160:163], v[232:233], s[56:59], 0 idxen offen
	buffer_load_dwordx4 v[164:167], v[234:235], s[56:59], 0 idxen offen
	buffer_load_dwordx4 v[168:171], v[236:237], s[56:59], 0 idxen offen
	buffer_load_dwordx4 v[172:175], v[238:239], s[56:59], 0 idxen offen
	ds_read_b32 v232, v213 offset:112
	ds_read_b32 v234, v213 offset:116
	ds_read_b32 v236, v213 offset:120
	ds_read_b32 v238, v213 offset:124
	s_waitcnt vmcnt(12)
	v_cvt_pk_f32_fp8_e32 v[224:225], v176
	v_cvt_pk_f32_fp8_e32 v[226:227], v180
	v_cvt_pk_f32_fp8_e32 v[228:229], v184
	v_cvt_pk_f32_fp8_e32 v[230:231], v188
	v_pk_mul_f32 v[216:217], v[224:225], v[0:1]
	v_pk_mul_f32 v[218:219], v[226:227], v[0:1]
	v_pk_mul_f32 v[220:221], v[228:229], v[0:1]
	v_pk_mul_f32 v[222:223], v[230:231], v[0:1]
	v_cvt_pk_f32_fp8_sdwa v[224:225], v176 src0_sel:WORD_1
	v_cvt_pk_f32_fp8_sdwa v[226:227], v180 src0_sel:WORD_1
	v_cvt_pk_f32_fp8_sdwa v[228:229], v184 src0_sel:WORD_1
	v_cvt_pk_f32_fp8_sdwa v[230:231], v188 src0_sel:WORD_1
	v_pk_fma_f32 v[216:217], v[224:225], v[2:3], v[216:217]
	v_pk_fma_f32 v[218:219], v[226:227], v[2:3], v[218:219]
	v_pk_fma_f32 v[220:221], v[228:229], v[2:3], v[220:221]
	v_pk_fma_f32 v[222:223], v[230:231], v[2:3], v[222:223]
	v_cvt_pk_f32_fp8_e32 v[224:225], v177
	v_cvt_pk_f32_fp8_e32 v[226:227], v181
	v_cvt_pk_f32_fp8_e32 v[228:229], v185
	v_cvt_pk_f32_fp8_e32 v[230:231], v189
	v_pk_fma_f32 v[216:217], v[224:225], v[4:5], v[216:217]
	v_pk_fma_f32 v[218:219], v[226:227], v[4:5], v[218:219]
	v_pk_fma_f32 v[220:221], v[228:229], v[4:5], v[220:221]
	v_pk_fma_f32 v[222:223], v[230:231], v[4:5], v[222:223]
	v_cvt_pk_f32_fp8_sdwa v[224:225], v177 src0_sel:WORD_1
	v_cvt_pk_f32_fp8_sdwa v[226:227], v181 src0_sel:WORD_1
	v_cvt_pk_f32_fp8_sdwa v[228:229], v185 src0_sel:WORD_1
	v_cvt_pk_f32_fp8_sdwa v[230:231], v189 src0_sel:WORD_1
	v_pk_fma_f32 v[216:217], v[224:225], v[6:7], v[216:217]
	v_pk_fma_f32 v[218:219], v[226:227], v[6:7], v[218:219]
	v_pk_fma_f32 v[220:221], v[228:229], v[6:7], v[220:221]
	v_pk_fma_f32 v[222:223], v[230:231], v[6:7], v[222:223]
	v_cvt_pk_f32_fp8_e32 v[224:225], v178
	v_cvt_pk_f32_fp8_e32 v[226:227], v182
	v_cvt_pk_f32_fp8_e32 v[228:229], v186
	v_cvt_pk_f32_fp8_e32 v[230:231], v190
	v_pk_fma_f32 v[216:217], v[224:225], v[8:9], v[216:217]
	v_pk_fma_f32 v[218:219], v[226:227], v[8:9], v[218:219]
	v_pk_fma_f32 v[220:221], v[228:229], v[8:9], v[220:221]
	v_pk_fma_f32 v[222:223], v[230:231], v[8:9], v[222:223]
	v_cvt_pk_f32_fp8_sdwa v[224:225], v178 src0_sel:WORD_1
	v_cvt_pk_f32_fp8_sdwa v[226:227], v182 src0_sel:WORD_1
	v_cvt_pk_f32_fp8_sdwa v[228:229], v186 src0_sel:WORD_1
	v_cvt_pk_f32_fp8_sdwa v[230:231], v190 src0_sel:WORD_1
	v_pk_fma_f32 v[216:217], v[224:225], v[10:11], v[216:217]
	v_pk_fma_f32 v[218:219], v[226:227], v[10:11], v[218:219]
	v_pk_fma_f32 v[220:221], v[228:229], v[10:11], v[220:221]
	v_pk_fma_f32 v[222:223], v[230:231], v[10:11], v[222:223]
	v_cvt_pk_f32_fp8_e32 v[224:225], v179
	v_cvt_pk_f32_fp8_e32 v[226:227], v183
	v_cvt_pk_f32_fp8_e32 v[228:229], v187
	v_cvt_pk_f32_fp8_e32 v[230:231], v191
	v_pk_fma_f32 v[216:217], v[224:225], v[12:13], v[216:217]
	v_pk_fma_f32 v[218:219], v[226:227], v[12:13], v[218:219]
	v_pk_fma_f32 v[220:221], v[228:229], v[12:13], v[220:221]
	v_pk_fma_f32 v[222:223], v[230:231], v[12:13], v[222:223]
	v_cvt_pk_f32_fp8_sdwa v[224:225], v179 src0_sel:WORD_1
	v_cvt_pk_f32_fp8_sdwa v[226:227], v183 src0_sel:WORD_1
	v_cvt_pk_f32_fp8_sdwa v[228:229], v187 src0_sel:WORD_1
	v_cvt_pk_f32_fp8_sdwa v[230:231], v191 src0_sel:WORD_1
	v_pk_fma_f32 v[216:217], v[224:225], v[14:15], v[216:217]
	v_pk_fma_f32 v[218:219], v[226:227], v[14:15], v[218:219]
	v_pk_fma_f32 v[220:221], v[228:229], v[14:15], v[220:221]
	v_pk_fma_f32 v[222:223], v[230:231], v[14:15], v[222:223]
	v_add_f32_e32 v204, v216, v217
	v_add_f32_e32 v205, v218, v219
	v_add_f32_e32 v206, v220, v221
	v_add_f32_e32 v207, v222, v223
	s_nop 0
	v_permlane32_swap_b32_e32 v192, v200
	v_permlane32_swap_b32_e32 v193, v201
	v_permlane32_swap_b32_e32 v194, v202
	v_permlane32_swap_b32_e32 v195, v203
	v_permlane32_swap_b32_e32 v196, v204
	v_permlane32_swap_b32_e32 v197, v205
	v_permlane32_swap_b32_e32 v198, v206
	v_permlane32_swap_b32_e32 v199, v207
	v_add_f32_e32 v192, v192, v200
	v_add_f32_e32 v193, v193, v201
	v_add_f32_e32 v194, v194, v202
	v_add_f32_e32 v195, v195, v203
	v_add_f32_e32 v196, v196, v204
	v_add_f32_e32 v197, v197, v205
	v_add_f32_e32 v198, v198, v206
	v_add_f32_e32 v199, v199, v207
	v_permlane16_swap_b32_e32 v192, v196
	v_permlane16_swap_b32_e32 v193, v197
	v_permlane16_swap_b32_e32 v194, v198
	v_permlane16_swap_b32_e32 v195, v199
	v_add_f32_e32 v192, v192, v196
	v_add_f32_e32 v193, v193, v197
	v_add_f32_e32 v194, v194, v198
	v_add_f32_e32 v195, v195, v199
	v_add_f32_dpp v216, v192, v192 row_ror:8 row_mask:0xf bank_mask:0xf
	v_add_f32_dpp v218, v194, v194 row_ror:8 row_mask:0xf bank_mask:0xf
	v_add_f32_dpp v216, v193, v193 row_ror:8 row_mask:0xf bank_mask:0xc
	v_add_f32_dpp v218, v195, v195 row_ror:8 row_mask:0xf bank_mask:0xc
	s_nop 1
	v_add_f32_dpp v220, v216, v216 row_half_mirror row_mask:0xf bank_mask:0xf
	v_add_f32_dpp v220, v218, v218 row_half_mirror row_mask:0xf bank_mask:0xa
	s_nop 1
	v_add_f32_dpp v220, v220, v220 quad_perm:[1,0,3,2] row_mask:0xf bank_mask:0xf
	s_nop 1
	v_add_f32_dpp v220, v220, v220 quad_perm:[2,3,0,1] row_mask:0xf bank_mask:0xf
	v_mul_f32_e32 v216, v252, v220
	v_fma_f32 v218, |v216|, s72, 1.0
	v_mul_f32_e32 v222, v216, v216
	v_rcp_f32_e32 v218, v218
	v_mul_f32_e32 v222, 0xbf38aa3b, v222
	v_exp_f32_e32 v222, v222
	v_fmamk_f32 v224, v218, 0x3f07dc22, v242
	v_fmaak_f32 v224, v218, v224, 0x3f35f0e3
	v_fmaak_f32 v224, v218, v224, 0xbe11a98e
	v_fmaak_f32 v224, v218, v224, 0x3e027906
	v_mul_f32_e32 v224, v218, v224
	v_mul_f32_e32 v224, v222, v224
	v_mul_f32_e32 v226, v216, v224
	v_fma_f32 v224, -v216, v224, v216
	v_cmp_gt_f32_e32 vcc, 0, v216
	s_nop 1
	v_cndmask_b32_e32 v224, v224, v226, vcc
	v_mul_f32_e32 v224, v249, v224
	v_mul_f32_e32 v224, v253, v224
	ds_write_b32 v211, v224 offset:4992
	v_add_u32_e32 v211, 64, v211
	v_add_u32_e32 v213, 64, v213
	ds_read_b32 v248, v211
	ds_read_b32 v249, v211 offset:4992
	s_add_i32 s21, s21, 4
	s_sub_i32 s90, s90, 1
	s_cmp_eq_u32 s90, 0
	s_cbranch_scc1 .LU_sw0
	s_branch .LU_t0_s0
.LU_t1_s0:
	s_cmp_ge_u32 s21, s20
	s_cbranch_scc1 .LU_done
	s_waitcnt lgkmcnt(0)
	v_lshlrev_b32_e32 v208, 2, v248
	buffer_load_dword v252, v208, s[24:27], 0 offen
	buffer_load_dword v253, v208, s[28:31], 0 offen
	buffer_load_dwordx4 v[176:179], v[232:233], s[56:59], 0 idxen offen
	buffer_load_dwordx4 v[180:183], v[234:235], s[56:59], 0 idxen offen
	buffer_load_dwordx4 v[184:187], v[236:237], s[56:59], 0 idxen offen
	buffer_load_dwordx4 v[188:191], v[238:239], s[56:59], 0 idxen offen
	ds_read_b32 v232, v213 offset:64
	ds_read_b32 v234, v213 offset:68
	ds_read_b32 v236, v213 offset:72
	ds_read_b32 v238, v213 offset:76
	s_waitcnt vmcnt(14)
	v_cvt_pk_f32_fp8_e32 v[224:225], v128
	v_cvt_pk_f32_fp8_e32 v[226:227], v132
	v_cvt_pk_f32_fp8_e32 v[228:229], v136
	v_cvt_pk_f32_fp8_e32 v[230:231], v140
	v_pk_mul_f32 v[216:217], v[224:225], v[16:17]
	v_pk_mul_f32 v[218:219], v[226:227], v[16:17]
	v_pk_mul_f32 v[220:221], v[228:229], v[16:17]
	v_pk_mul_f32 v[222:223], v[230:231], v[16:17]
	v_cvt_pk_f32_fp8_sdwa v[224:225], v128 src0_sel:WORD_1
	v_cvt_pk_f32_fp8_sdwa v[226:227], v132 src0_sel:WORD_1
	v_cvt_pk_f32_fp8_sdwa v[228:229], v136 src0_sel:WORD_1
	v_cvt_pk_f32_fp8_sdwa v[230:231], v140 src0_sel:WORD_1
	v_pk_fma_f32 v[216:217], v[224:225], v[18:19], v[216:217]
	v_pk_fma_f32 v[218:219], v[226:227], v[18:19], v[218:219]
	v_pk_fma_f32 v[220:221], v[228:229], v[18:19], v[220:221]
	v_pk_fma_f32 v[222:223], v[230:231], v[18:19], v[222:223]
	v_cvt_pk_f32_fp8_e32 v[224:225], v129
	v_cvt_pk_f32_fp8_e32 v[226:227], v133
	v_cvt_pk_f32_fp8_e32 v[228:229], v137
	v_cvt_pk_f32_fp8_e32 v[230:231], v141
	v_pk_fma_f32 v[216:217], v[224:225], v[20:21], v[216:217]
	v_pk_fma_f32 v[218:219], v[226:227], v[20:21], v[218:219]
	v_pk_fma_f32 v[220:221], v[228:229], v[20:21], v[220:221]
	v_pk_fma_f32 v[222:223], v[230:231], v[20:21], v[222:223]
	v_cvt_pk_f32_fp8_sdwa v[224:225], v129 src0_sel:WORD_1
	v_cvt_pk_f32_fp8_sdwa v[226:227], v133 src0_sel:WORD_1
	v_cvt_pk_f32_fp8_sdwa v[228:229], v137 src0_sel:WORD_1
	v_cvt_pk_f32_fp8_sdwa v[230:231], v141 src0_sel:WORD_1
	v_pk_fma_f32 v[216:217], v[224:225], v[22:23], v[216:217]
	v_pk_fma_f32 v[218:219], v[226:227], v[22:23], v[218:219]
	v_pk_fma_f32 v[220:221], v[228:229], v[22:23], v[220:221]
	v_pk_fma_f32 v[222:223], v[230:231], v[22:23], v[222:223]
	v_cvt_pk_f32_fp8_e32 v[224:225], v130
	v_cvt_pk_f32_fp8_e32 v[226:227], v134
	v_cvt_pk_f32_fp8_e32 v[228:229], v138
	v_cvt_pk_f32_fp8_e32 v[230:231], v142
	v_pk_fma_f32 v[216:217], v[224:225], v[24:25], v[216:217]
	v_pk_fma_f32 v[218:219], v[226:227], v[24:25], v[218:219]
	v_pk_fma_f32 v[220:221], v[228:229], v[24:25], v[220:221]
	v_pk_fma_f32 v[222:223], v[230:231], v[24:25], v[222:223]
	v_cvt_pk_f32_fp8_sdwa v[224:225], v130 src0_sel:WORD_1
	v_cvt_pk_f32_fp8_sdwa v[226:227], v134 src0_sel:WORD_1
	v_cvt_pk_f32_fp8_sdwa v[228:229], v138 src0_sel:WORD_1
	v_cvt_pk_f32_fp8_sdwa v[230:231], v142 src0_sel:WORD_1
	v_pk_fma_f32 v[216:217], v[224:225], v[26:27], v[216:217]
	v_pk_fma_f32 v[218:219], v[226:227], v[26:27], v[218:219]
	v_pk_fma_f32 v[220:221], v[228:229], v[26:27], v[220:221]
	v_pk_fma_f32 v[222:223], v[230:231], v[26:27], v[222:223]
	v_cvt_pk_f32_fp8_e32 v[224:225], v131
	v_cvt_pk_f32_fp8_e32 v[226:227], v135
	v_cvt_pk_f32_fp8_e32 v[228:229], v139
	v_cvt_pk_f32_fp8_e32 v[230:231], v143
	v_pk_fma_f32 v[216:217], v[224:225], v[28:29], v[216:217]
	v_pk_fma_f32 v[218:219], v[226:227], v[28:29], v[218:219]
	v_pk_fma_f32 v[220:221], v[228:229], v[28:29], v[220:221]
	v_pk_fma_f32 v[222:223], v[230:231], v[28:29], v[222:223]
	v_cvt_pk_f32_fp8_sdwa v[224:225], v131 src0_sel:WORD_1
	v_cvt_pk_f32_fp8_sdwa v[226:227], v135 src0_sel:WORD_1
	v_cvt_pk_f32_fp8_sdwa v[228:229], v139 src0_sel:WORD_1
	v_cvt_pk_f32_fp8_sdwa v[230:231], v143 src0_sel:WORD_1
	v_pk_fma_f32 v[216:217], v[224:225], v[30:31], v[216:217]
	v_pk_fma_f32 v[218:219], v[226:227], v[30:31], v[218:219]
	v_pk_fma_f32 v[220:221], v[228:229], v[30:31], v[220:221]
	v_pk_fma_f32 v[222:223], v[230:231], v[30:31], v[222:223]
	v_add_f32_e32 v192, v216, v217
	v_add_f32_e32 v193, v218, v219
	v_add_f32_e32 v194, v220, v221
	v_add_f32_e32 v195, v222, v223
	s_sub_i32 s90, s90, 1
	s_cmp_eq_u32 s90, 0
	s_cbranch_scc1 .LU_sw1
.LU_t1_s1:
	s_waitcnt lgkmcnt(0)
	buffer_load_dwordx4 v[128:131], v[232:233], s[56:59], 0 idxen offen
	buffer_load_dwordx4 v[132:135], v[234:235], s[56:59], 0 idxen offen
	buffer_load_dwordx4 v[136:139], v[236:237], s[56:59], 0 idxen offen
	buffer_load_dwordx4 v[140:143], v[238:239], s[56:59], 0 idxen offen
	ds_read_b32 v232, v213 offset:80
	ds_read_b32 v234, v213 offset:84
	ds_read_b32 v236, v213 offset:88
	ds_read_b32 v238, v213 offset:92
	s_waitcnt vmcnt(14)
	v_cvt_pk_f32_fp8_e32 v[224:225], v144
	v_cvt_pk_f32_fp8_e32 v[226:227], v148
	v_cvt_pk_f32_fp8_e32 v[228:229], v152
	v_cvt_pk_f32_fp8_e32 v[230:231], v156
	v_pk_mul_f32 v[216:217], v[224:225], v[16:17]
	v_pk_mul_f32 v[218:219], v[226:227], v[16:17]
	v_pk_mul_f32 v[220:221], v[228:229], v[16:17]
	v_pk_mul_f32 v[222:223], v[230:231], v[16:17]
	v_cvt_pk_f32_fp8_sdwa v[224:225], v144 src0_sel:WORD_1
	v_cvt_pk_f32_fp8_sdwa v[226:227], v148 src0_sel:WORD_1
	v_cvt_pk_f32_fp8_sdwa v[228:229], v152 src0_sel:WORD_1
	v_cvt_pk_f32_fp8_sdwa v[230:231], v156 src0_sel:WORD_1
	v_pk_fma_f32 v[216:217], v[224:225], v[18:19], v[216:217]
	v_pk_fma_f32 v[218:219], v[226:227], v[18:19], v[218:219]
	v_pk_fma_f32 v[220:221], v[228:229], v[18:19], v[220:221]
	v_pk_fma_f32 v[222:223], v[230:231], v[18:19], v[222:223]
	v_cvt_pk_f32_fp8_e32 v[224:225], v145
	v_cvt_pk_f32_fp8_e32 v[226:227], v149
	v_cvt_pk_f32_fp8_e32 v[228:229], v153
	v_cvt_pk_f32_fp8_e32 v[230:231], v157
	v_pk_fma_f32 v[216:217], v[224:225], v[20:21], v[216:217]
	v_pk_fma_f32 v[218:219], v[226:227], v[20:21], v[218:219]
	v_pk_fma_f32 v[220:221], v[228:229], v[20:21], v[220:221]
	v_pk_fma_f32 v[222:223], v[230:231], v[20:21], v[222:223]
	v_cvt_pk_f32_fp8_sdwa v[224:225], v145 src0_sel:WORD_1
	v_cvt_pk_f32_fp8_sdwa v[226:227], v149 src0_sel:WORD_1
	v_cvt_pk_f32_fp8_sdwa v[228:229], v153 src0_sel:WORD_1
	v_cvt_pk_f32_fp8_sdwa v[230:231], v157 src0_sel:WORD_1
	v_pk_fma_f32 v[216:217], v[224:225], v[22:23], v[216:217]
	v_pk_fma_f32 v[218:219], v[226:227], v[22:23], v[218:219]
	v_pk_fma_f32 v[220:221], v[228:229], v[22:23], v[220:221]
	v_pk_fma_f32 v[222:223], v[230:231], v[22:23], v[222:223]
	v_cvt_pk_f32_fp8_e32 v[224:225], v146
	v_cvt_pk_f32_fp8_e32 v[226:227], v150
	v_cvt_pk_f32_fp8_e32 v[228:229], v154
	v_cvt_pk_f32_fp8_e32 v[230:231], v158
	v_pk_fma_f32 v[216:217], v[224:225], v[24:25], v[216:217]
	v_pk_fma_f32 v[218:219], v[226:227], v[24:25], v[218:219]
	v_pk_fma_f32 v[220:221], v[228:229], v[24:25], v[220:221]
	v_pk_fma_f32 v[222:223], v[230:231], v[24:25], v[222:223]
	v_cvt_pk_f32_fp8_sdwa v[224:225], v146 src0_sel:WORD_1
	v_cvt_pk_f32_fp8_sdwa v[226:227], v150 src0_sel:WORD_1
	v_cvt_pk_f32_fp8_sdwa v[228:229], v154 src0_sel:WORD_1
	v_cvt_pk_f32_fp8_sdwa v[230:231], v158 src0_sel:WORD_1
	v_pk_fma_f32 v[216:217], v[224:225], v[26:27], v[216:217]
	v_pk_fma_f32 v[218:219], v[226:227], v[26:27], v[218:219]
	v_pk_fma_f32 v[220:221], v[228:229], v[26:27], v[220:221]
	v_pk_fma_f32 v[222:223], v[230:231], v[26:27], v[222:223]
	v_cvt_pk_f32_fp8_e32 v[224:225], v147
	v_cvt_pk_f32_fp8_e32 v[226:227], v151
	v_cvt_pk_f32_fp8_e32 v[228:229], v155
	v_cvt_pk_f32_fp8_e32 v[230:231], v159
	v_pk_fma_f32 v[216:217], v[224:225], v[28:29], v[216:217]
	v_pk_fma_f32 v[218:219], v[226:227], v[28:29], v[218:219]
	v_pk_fma_f32 v[220:221], v[228:229], v[28:29], v[220:221]
	v_pk_fma_f32 v[222:223], v[230:231], v[28:29], v[222:223]
	v_cvt_pk_f32_fp8_sdwa v[224:225], v147 src0_sel:WORD_1
	v_cvt_pk_f32_fp8_sdwa v[226:227], v151 src0_sel:WORD_1
	v_cvt_pk_f32_fp8_sdwa v[228:229], v155 src0_sel:WORD_1
	v_cvt_pk_f32_fp8_sdwa v[230:231], v159 src0_sel:WORD_1
	v_pk_fma_f32 v[216:217], v[224:225], v[30:31], v[216:217]
	v_pk_fma_f32 v[218:219], v[226:227], v[30:31], v[218:219]
	v_pk_fma_f32 v[220:221], v[228:229], v[30:31], v[220:221]
	v_pk_fma_f32 v[222:223], v[230:231], v[30:31], v[222:223]
	v_add_f32_e32 v196, v216, v217
	v_add_f32_e32 v197, v218, v219
	v_add_f32_e32 v198, v220, v221
	v_add_f32_e32 v199, v222, v223
	s_sub_i32 s90, s90, 1
	s_cmp_eq_u32 s90, 0
	s_cbranch_scc1 .LU_sw2
.LU_t1_s2:
	s_waitcnt lgkmcnt(0)
	buffer_load_dwordx4 v[144:147], v[232:233], s[56:59], 0 idxen offen
	buffer_load_dwordx4 v[148:151], v[234:235], s[56:59], 0 idxen offen
	buffer_load_dwordx4 v[152:155], v[236:237], s[56:59], 0 idxen offen
	buffer_load_dwordx4 v[156:159], v[238:239], s[56:59], 0 idxen offen
	ds_read_b32 v232, v213 offset:96
	ds_read_b32 v234, v213 offset:100
	ds_read_b32 v236, v213 offset:104
	ds_read_b32 v238, v213 offset:108
	s_waitcnt vmcnt(14)
	v_cvt_pk_f32_fp8_e32 v[224:225], v160
	v_cvt_pk_f32_fp8_e32 v[226:227], v164
	v_cvt_pk_f32_fp8_e32 v[228:229], v168
	v_cvt_pk_f32_fp8_e32 v[230:231], v172
	v_pk_mul_f32 v[216:217], v[224:225], v[16:17]
	v_pk_mul_f32 v[218:219], v[226:227], v[16:17]
	v_pk_mul_f32 v[220:221], v[228:229], v[16:17]
	v_pk_mul_f32 v[222:223], v[230:231], v[16:17]
	v_cvt_pk_f32_fp8_sdwa v[224:225], v160 src0_sel:WORD_1
	v_cvt_pk_f32_fp8_sdwa v[226:227], v164 src0_sel:WORD_1
	v_cvt_pk_f32_fp8_sdwa v[228:229], v168 src0_sel:WORD_1
	v_cvt_pk_f32_fp8_sdwa v[230:231], v172 src0_sel:WORD_1
	v_pk_fma_f32 v[216:217], v[224:225], v[18:19], v[216:217]
	v_pk_fma_f32 v[218:219], v[226:227], v[18:19], v[218:219]
	v_pk_fma_f32 v[220:221], v[228:229], v[18:19], v[220:221]
	v_pk_fma_f32 v[222:223], v[230:231], v[18:19], v[222:223]
	v_cvt_pk_f32_fp8_e32 v[224:225], v161
	v_cvt_pk_f32_fp8_e32 v[226:227], v165
	v_cvt_pk_f32_fp8_e32 v[228:229], v169
	v_cvt_pk_f32_fp8_e32 v[230:231], v173
	v_pk_fma_f32 v[216:217], v[224:225], v[20:21], v[216:217]
	v_pk_fma_f32 v[218:219], v[226:227], v[20:21], v[218:219]
	v_pk_fma_f32 v[220:221], v[228:229], v[20:21], v[220:221]
	v_pk_fma_f32 v[222:223], v[230:231], v[20:21], v[222:223]
	v_cvt_pk_f32_fp8_sdwa v[224:225], v161 src0_sel:WORD_1
	v_cvt_pk_f32_fp8_sdwa v[226:227], v165 src0_sel:WORD_1
	v_cvt_pk_f32_fp8_sdwa v[228:229], v169 src0_sel:WORD_1
	v_cvt_pk_f32_fp8_sdwa v[230:231], v173 src0_sel:WORD_1
	v_pk_fma_f32 v[216:217], v[224:225], v[22:23], v[216:217]
	v_pk_fma_f32 v[218:219], v[226:227], v[22:23], v[218:219]
	v_pk_fma_f32 v[220:221], v[228:229], v[22:23], v[220:221]
	v_pk_fma_f32 v[222:223], v[230:231], v[22:23], v[222:223]
	v_cvt_pk_f32_fp8_e32 v[224:225], v162
	v_cvt_pk_f32_fp8_e32 v[226:227], v166
	v_cvt_pk_f32_fp8_e32 v[228:229], v170
	v_cvt_pk_f32_fp8_e32 v[230:231], v174
	v_pk_fma_f32 v[216:217], v[224:225], v[24:25], v[216:217]
	v_pk_fma_f32 v[218:219], v[226:227], v[24:25], v[218:219]
	v_pk_fma_f32 v[220:221], v[228:229], v[24:25], v[220:221]
	v_pk_fma_f32 v[222:223], v[230:231], v[24:25], v[222:223]
	v_cvt_pk_f32_fp8_sdwa v[224:225], v162 src0_sel:WORD_1
	v_cvt_pk_f32_fp8_sdwa v[226:227], v166 src0_sel:WORD_1
	v_cvt_pk_f32_fp8_sdwa v[228:229], v170 src0_sel:WORD_1
	v_cvt_pk_f32_fp8_sdwa v[230:231], v174 src0_sel:WORD_1
	v_pk_fma_f32 v[216:217], v[224:225], v[26:27], v[216:217]
	v_pk_fma_f32 v[218:219], v[226:227], v[26:27], v[218:219]
	v_pk_fma_f32 v[220:221], v[228:229], v[26:27], v[220:221]
	v_pk_fma_f32 v[222:223], v[230:231], v[26:27], v[222:223]
	v_cvt_pk_f32_fp8_e32 v[224:225], v163
	v_cvt_pk_f32_fp8_e32 v[226:227], v167
	v_cvt_pk_f32_fp8_e32 v[228:229], v171
	v_cvt_pk_f32_fp8_e32 v[230:231], v175
	v_pk_fma_f32 v[216:217], v[224:225], v[28:29], v[216:217]
	v_pk_fma_f32 v[218:219], v[226:227], v[28:29], v[218:219]
	v_pk_fma_f32 v[220:221], v[228:229], v[28:29], v[220:221]
	v_pk_fma_f32 v[222:223], v[230:231], v[28:29], v[222:223]
	v_cvt_pk_f32_fp8_sdwa v[224:225], v163 src0_sel:WORD_1
	v_cvt_pk_f32_fp8_sdwa v[226:227], v167 src0_sel:WORD_1
	v_cvt_pk_f32_fp8_sdwa v[228:229], v171 src0_sel:WORD_1
	v_cvt_pk_f32_fp8_sdwa v[230:231], v175 src0_sel:WORD_1
	v_pk_fma_f32 v[216:217], v[224:225], v[30:31], v[216:217]
	v_pk_fma_f32 v[218:219], v[226:227], v[30:31], v[218:219]
	v_pk_fma_f32 v[220:221], v[228:229], v[30:31], v[220:221]
	v_pk_fma_f32 v[222:223], v[230:231], v[30:31], v[222:223]
	v_add_f32_e32 v200, v216, v217
	v_add_f32_e32 v201, v218, v219
	v_add_f32_e32 v202, v220, v221
	v_add_f32_e32 v203, v222, v223
	s_sub_i32 s90, s90, 1
	s_cmp_eq_u32 s90, 0
	s_cbranch_scc1 .LU_sw3
.LU_t1_s3:
	s_waitcnt lgkmcnt(0)
	buffer_load_dwordx4 v[160:163], v[232:233], s[56:59], 0 idxen offen
	buffer_load_dwordx4 v[164:167], v[234:235], s[56:59], 0 idxen offen
	buffer_load_dwordx4 v[168:171], v[236:237], s[56:59], 0 idxen offen
	buffer_load_dwordx4 v[172:175], v[238:239], s[56:59], 0 idxen offen
	ds_read_b32 v232, v213 offset:112
	ds_read_b32 v234, v213 offset:116
	ds_read_b32 v236, v213 offset:120
	ds_read_b32 v238, v213 offset:124
	s_waitcnt vmcnt(12)
	v_cvt_pk_f32_fp8_e32 v[224:225], v176
	v_cvt_pk_f32_fp8_e32 v[226:227], v180
	v_cvt_pk_f32_fp8_e32 v[228:229], v184
	v_cvt_pk_f32_fp8_e32 v[230:231], v188
	v_pk_mul_f32 v[216:217], v[224:225], v[16:17]
	v_pk_mul_f32 v[218:219], v[226:227], v[16:17]
	v_pk_mul_f32 v[220:221], v[228:229], v[16:17]
	v_pk_mul_f32 v[222:223], v[230:231], v[16:17]
	v_cvt_pk_f32_fp8_sdwa v[224:225], v176 src0_sel:WORD_1
	v_cvt_pk_f32_fp8_sdwa v[226:227], v180 src0_sel:WORD_1
	v_cvt_pk_f32_fp8_sdwa v[228:229], v184 src0_sel:WORD_1
	v_cvt_pk_f32_fp8_sdwa v[230:231], v188 src0_sel:WORD_1
	v_pk_fma_f32 v[216:217], v[224:225], v[18:19], v[216:217]
	v_pk_fma_f32 v[218:219], v[226:227], v[18:19], v[218:219]
	v_pk_fma_f32 v[220:221], v[228:229], v[18:19], v[220:221]
	v_pk_fma_f32 v[222:223], v[230:231], v[18:19], v[222:223]
	v_cvt_pk_f32_fp8_e32 v[224:225], v177
	v_cvt_pk_f32_fp8_e32 v[226:227], v181
	v_cvt_pk_f32_fp8_e32 v[228:229], v185
	v_cvt_pk_f32_fp8_e32 v[230:231], v189
	v_pk_fma_f32 v[216:217], v[224:225], v[20:21], v[216:217]
	v_pk_fma_f32 v[218:219], v[226:227], v[20:21], v[218:219]
	v_pk_fma_f32 v[220:221], v[228:229], v[20:21], v[220:221]
	v_pk_fma_f32 v[222:223], v[230:231], v[20:21], v[222:223]
	v_cvt_pk_f32_fp8_sdwa v[224:225], v177 src0_sel:WORD_1
	v_cvt_pk_f32_fp8_sdwa v[226:227], v181 src0_sel:WORD_1
	v_cvt_pk_f32_fp8_sdwa v[228:229], v185 src0_sel:WORD_1
	v_cvt_pk_f32_fp8_sdwa v[230:231], v189 src0_sel:WORD_1
	v_pk_fma_f32 v[216:217], v[224:225], v[22:23], v[216:217]
	v_pk_fma_f32 v[218:219], v[226:227], v[22:23], v[218:219]
	v_pk_fma_f32 v[220:221], v[228:229], v[22:23], v[220:221]
	v_pk_fma_f32 v[222:223], v[230:231], v[22:23], v[222:223]
	v_cvt_pk_f32_fp8_e32 v[224:225], v178
	v_cvt_pk_f32_fp8_e32 v[226:227], v182
	v_cvt_pk_f32_fp8_e32 v[228:229], v186
	v_cvt_pk_f32_fp8_e32 v[230:231], v190
	v_pk_fma_f32 v[216:217], v[224:225], v[24:25], v[216:217]
	v_pk_fma_f32 v[218:219], v[226:227], v[24:25], v[218:219]
	v_pk_fma_f32 v[220:221], v[228:229], v[24:25], v[220:221]
	v_pk_fma_f32 v[222:223], v[230:231], v[24:25], v[222:223]
	v_cvt_pk_f32_fp8_sdwa v[224:225], v178 src0_sel:WORD_1
	v_cvt_pk_f32_fp8_sdwa v[226:227], v182 src0_sel:WORD_1
	v_cvt_pk_f32_fp8_sdwa v[228:229], v186 src0_sel:WORD_1
	v_cvt_pk_f32_fp8_sdwa v[230:231], v190 src0_sel:WORD_1
	v_pk_fma_f32 v[216:217], v[224:225], v[26:27], v[216:217]
	v_pk_fma_f32 v[218:219], v[226:227], v[26:27], v[218:219]
	v_pk_fma_f32 v[220:221], v[228:229], v[26:27], v[220:221]
	v_pk_fma_f32 v[222:223], v[230:231], v[26:27], v[222:223]
	v_cvt_pk_f32_fp8_e32 v[224:225], v179
	v_cvt_pk_f32_fp8_e32 v[226:227], v183
	v_cvt_pk_f32_fp8_e32 v[228:229], v187
	v_cvt_pk_f32_fp8_e32 v[230:231], v191
	v_pk_fma_f32 v[216:217], v[224:225], v[28:29], v[216:217]
	v_pk_fma_f32 v[218:219], v[226:227], v[28:29], v[218:219]
	v_pk_fma_f32 v[220:221], v[228:229], v[28:29], v[220:221]
	v_pk_fma_f32 v[222:223], v[230:231], v[28:29], v[222:223]
	v_cvt_pk_f32_fp8_sdwa v[224:225], v179 src0_sel:WORD_1
	v_cvt_pk_f32_fp8_sdwa v[226:227], v183 src0_sel:WORD_1
	v_cvt_pk_f32_fp8_sdwa v[228:229], v187 src0_sel:WORD_1
	v_cvt_pk_f32_fp8_sdwa v[230:231], v191 src0_sel:WORD_1
	v_pk_fma_f32 v[216:217], v[224:225], v[30:31], v[216:217]
	v_pk_fma_f32 v[218:219], v[226:227], v[30:31], v[218:219]
	v_pk_fma_f32 v[220:221], v[228:229], v[30:31], v[220:221]
	v_pk_fma_f32 v[222:223], v[230:231], v[30:31], v[222:223]
	v_add_f32_e32 v204, v216, v217
	v_add_f32_e32 v205, v218, v219
	v_add_f32_e32 v206, v220, v221
	v_add_f32_e32 v207, v222, v223
	s_nop 0
	v_permlane32_swap_b32_e32 v192, v200
	v_permlane32_swap_b32_e32 v193, v201
	v_permlane32_swap_b32_e32 v194, v202
	v_permlane32_swap_b32_e32 v195, v203
	v_permlane32_swap_b32_e32 v196, v204
	v_permlane32_swap_b32_e32 v197, v205
	v_permlane32_swap_b32_e32 v198, v206
	v_permlane32_swap_b32_e32 v199, v207
	v_add_f32_e32 v192, v192, v200
	v_add_f32_e32 v193, v193, v201
	v_add_f32_e32 v194, v194, v202
	v_add_f32_e32 v195, v195, v203
	v_add_f32_e32 v196, v196, v204
	v_add_f32_e32 v197, v197, v205
	v_add_f32_e32 v198, v198, v206
	v_add_f32_e32 v199, v199, v207
	v_permlane16_swap_b32_e32 v192, v196
	v_permlane16_swap_b32_e32 v193, v197
	v_permlane16_swap_b32_e32 v194, v198
	v_permlane16_swap_b32_e32 v195, v199
	v_add_f32_e32 v192, v192, v196
	v_add_f32_e32 v193, v193, v197
	v_add_f32_e32 v194, v194, v198
	v_add_f32_e32 v195, v195, v199
	v_add_f32_dpp v216, v192, v192 row_ror:8 row_mask:0xf bank_mask:0xf
	v_add_f32_dpp v218, v194, v194 row_ror:8 row_mask:0xf bank_mask:0xf
	v_add_f32_dpp v216, v193, v193 row_ror:8 row_mask:0xf bank_mask:0xc
	v_add_f32_dpp v218, v195, v195 row_ror:8 row_mask:0xf bank_mask:0xc
	s_nop 1
	v_add_f32_dpp v220, v216, v216 row_half_mirror row_mask:0xf bank_mask:0xf
	v_add_f32_dpp v220, v218, v218 row_half_mirror row_mask:0xf bank_mask:0xa
	s_nop 1
	v_add_f32_dpp v220, v220, v220 quad_perm:[1,0,3,2] row_mask:0xf bank_mask:0xf
	s_nop 1
	v_add_f32_dpp v220, v220, v220 quad_perm:[2,3,0,1] row_mask:0xf bank_mask:0xf
	v_mul_f32_e32 v216, v252, v220
	v_fma_f32 v218, |v216|, s72, 1.0
	v_mul_f32_e32 v222, v216, v216
	v_rcp_f32_e32 v218, v218
	v_mul_f32_e32 v222, 0xbf38aa3b, v222
	v_exp_f32_e32 v222, v222
	v_fmamk_f32 v224, v218, 0x3f07dc22, v242
	v_fmaak_f32 v224, v218, v224, 0x3f35f0e3
	v_fmaak_f32 v224, v218, v224, 0xbe11a98e
	v_fmaak_f32 v224, v218, v224, 0x3e027906
	v_mul_f32_e32 v224, v218, v224
	v_mul_f32_e32 v224, v222, v224
	v_mul_f32_e32 v226, v216, v224
	v_fma_f32 v224, -v216, v224, v216
	v_cmp_gt_f32_e32 vcc, 0, v216
	s_nop 1
	v_cndmask_b32_e32 v224, v224, v226, vcc
	v_mul_f32_e32 v224, v249, v224
	v_mul_f32_e32 v224, v253, v224
	ds_write_b32 v211, v224 offset:4992
	v_add_u32_e32 v211, 64, v211
	v_add_u32_e32 v213, 64, v213
	ds_read_b32 v248, v211
	ds_read_b32 v249, v211 offset:4992
	s_add_i32 s21, s21, 4
	s_sub_i32 s90, s90, 1
	s_cmp_eq_u32 s90, 0
	s_cbranch_scc1 .LU_sw0
	s_branch .LU_t1_s0
.LU_t2_s0:
	s_cmp_ge_u32 s21, s20
	s_cbranch_scc1 .LU_done
	s_waitcnt lgkmcnt(0)
	v_lshlrev_b32_e32 v208, 2, v248
	buffer_load_dword v252, v208, s[24:27], 0 offen
	buffer_load_dword v253, v208, s[28:31], 0 offen
	buffer_load_dwordx4 v[176:179], v[232:233], s[56:59], 0 idxen offen
	buffer_load_dwordx4 v[180:183], v[234:235], s[56:59], 0 idxen offen
	buffer_load_dwordx4 v[184:187], v[236:237], s[56:59], 0 idxen offen
	buffer_load_dwordx4 v[188:191], v[238:239], s[56:59], 0 idxen offen
	ds_read_b32 v232, v213 offset:64
	ds_read_b32 v234, v213 offset:68
	ds_read_b32 v236, v213 offset:72
	ds_read_b32 v238, v213 offset:76
	s_waitcnt vmcnt(14)
	v_cvt_pk_f32_fp8_e32 v[224:225], v128
	v_cvt_pk_f32_fp8_e32 v[226:227], v132
	v_cvt_pk_f32_fp8_e32 v[228:229], v136
	v_cvt_pk_f32_fp8_e32 v[230:231], v140
	v_pk_mul_f32 v[216:217], v[224:225], v[32:33]
	v_pk_mul_f32 v[218:219], v[226:227], v[32:33]
	v_pk_mul_f32 v[220:221], v[228:229], v[32:33]
	v_pk_mul_f32 v[222:223], v[230:231], v[32:33]
	v_cvt_pk_f32_fp8_sdwa v[224:225], v128 src0_sel:WORD_1
	v_cvt_pk_f32_fp8_sdwa v[226:227], v132 src0_sel:WORD_1
	v_cvt_pk_f32_fp8_sdwa v[228:229], v136 src0_sel:WORD_1
	v_cvt_pk_f32_fp8_sdwa v[230:231], v140 src0_sel:WORD_1
	v_pk_fma_f32 v[216:217], v[224:225], v[34:35], v[216:217]
	v_pk_fma_f32 v[218:219], v[226:227], v[34:35], v[218:219]
	v_pk_fma_f32 v[220:221], v[228:229], v[34:35], v[220:221]
	v_pk_fma_f32 v[222:223], v[230:231], v[34:35], v[222:223]
	v_cvt_pk_f32_fp8_e32 v[224:225], v129
	v_cvt_pk_f32_fp8_e32 v[226:227], v133
	v_cvt_pk_f32_fp8_e32 v[228:229], v137
	v_cvt_pk_f32_fp8_e32 v[230:231], v141
	v_pk_fma_f32 v[216:217], v[224:225], v[36:37], v[216:217]
	v_pk_fma_f32 v[218:219], v[226:227], v[36:37], v[218:219]
	v_pk_fma_f32 v[220:221], v[228:229], v[36:37], v[220:221]
	v_pk_fma_f32 v[222:223], v[230:231], v[36:37], v[222:223]
	v_cvt_pk_f32_fp8_sdwa v[224:225], v129 src0_sel:WORD_1
	v_cvt_pk_f32_fp8_sdwa v[226:227], v133 src0_sel:WORD_1
	v_cvt_pk_f32_fp8_sdwa v[228:229], v137 src0_sel:WORD_1
	v_cvt_pk_f32_fp8_sdwa v[230:231], v141 src0_sel:WORD_1
	v_pk_fma_f32 v[216:217], v[224:225], v[38:39], v[216:217]
	v_pk_fma_f32 v[218:219], v[226:227], v[38:39], v[218:219]
	v_pk_fma_f32 v[220:221], v[228:229], v[38:39], v[220:221]
	v_pk_fma_f32 v[222:223], v[230:231], v[38:39], v[222:223]
	v_cvt_pk_f32_fp8_e32 v[224:225], v130
	v_cvt_pk_f32_fp8_e32 v[226:227], v134
	v_cvt_pk_f32_fp8_e32 v[228:229], v138
	v_cvt_pk_f32_fp8_e32 v[230:231], v142
	v_pk_fma_f32 v[216:217], v[224:225], v[40:41], v[216:217]
	v_pk_fma_f32 v[218:219], v[226:227], v[40:41], v[218:219]
	v_pk_fma_f32 v[220:221], v[228:229], v[40:41], v[220:221]
	v_pk_fma_f32 v[222:223], v[230:231], v[40:41], v[222:223]
	v_cvt_pk_f32_fp8_sdwa v[224:225], v130 src0_sel:WORD_1
	v_cvt_pk_f32_fp8_sdwa v[226:227], v134 src0_sel:WORD_1
	v_cvt_pk_f32_fp8_sdwa v[228:229], v138 src0_sel:WORD_1
	v_cvt_pk_f32_fp8_sdwa v[230:231], v142 src0_sel:WORD_1
	v_pk_fma_f32 v[216:217], v[224:225], v[42:43], v[216:217]
	v_pk_fma_f32 v[218:219], v[226:227], v[42:43], v[218:219]
	v_pk_fma_f32 v[220:221], v[228:229], v[42:43], v[220:221]
	v_pk_fma_f32 v[222:223], v[230:231], v[42:43], v[222:223]
	v_cvt_pk_f32_fp8_e32 v[224:225], v131
	v_cvt_pk_f32_fp8_e32 v[226:227], v135
	v_cvt_pk_f32_fp8_e32 v[228:229], v139
	v_cvt_pk_f32_fp8_e32 v[230:231], v143
	v_pk_fma_f32 v[216:217], v[224:225], v[44:45], v[216:217]
	v_pk_fma_f32 v[218:219], v[226:227], v[44:45], v[218:219]
	v_pk_fma_f32 v[220:221], v[228:229], v[44:45], v[220:221]
	v_pk_fma_f32 v[222:223], v[230:231], v[44:45], v[222:223]
	v_cvt_pk_f32_fp8_sdwa v[224:225], v131 src0_sel:WORD_1
	v_cvt_pk_f32_fp8_sdwa v[226:227], v135 src0_sel:WORD_1
	v_cvt_pk_f32_fp8_sdwa v[228:229], v139 src0_sel:WORD_1
	v_cvt_pk_f32_fp8_sdwa v[230:231], v143 src0_sel:WORD_1
	v_pk_fma_f32 v[216:217], v[224:225], v[46:47], v[216:217]
	v_pk_fma_f32 v[218:219], v[226:227], v[46:47], v[218:219]
	v_pk_fma_f32 v[220:221], v[228:229], v[46:47], v[220:221]
	v_pk_fma_f32 v[222:223], v[230:231], v[46:47], v[222:223]
	v_add_f32_e32 v192, v216, v217
	v_add_f32_e32 v193, v218, v219
	v_add_f32_e32 v194, v220, v221
	v_add_f32_e32 v195, v222, v223
	s_sub_i32 s90, s90, 1
	s_cmp_eq_u32 s90, 0
	s_cbranch_scc1 .LU_sw1
.LU_t2_s1:
	s_waitcnt lgkmcnt(0)
	buffer_load_dwordx4 v[128:131], v[232:233], s[56:59], 0 idxen offen
	buffer_load_dwordx4 v[132:135], v[234:235], s[56:59], 0 idxen offen
	buffer_load_dwordx4 v[136:139], v[236:237], s[56:59], 0 idxen offen
	buffer_load_dwordx4 v[140:143], v[238:239], s[56:59], 0 idxen offen
	ds_read_b32 v232, v213 offset:80
	ds_read_b32 v234, v213 offset:84
	ds_read_b32 v236, v213 offset:88
	ds_read_b32 v238, v213 offset:92
	s_waitcnt vmcnt(14)
	v_cvt_pk_f32_fp8_e32 v[224:225], v144
	v_cvt_pk_f32_fp8_e32 v[226:227], v148
	v_cvt_pk_f32_fp8_e32 v[228:229], v152
	v_cvt_pk_f32_fp8_e32 v[230:231], v156
	v_pk_mul_f32 v[216:217], v[224:225], v[32:33]
	v_pk_mul_f32 v[218:219], v[226:227], v[32:33]
	v_pk_mul_f32 v[220:221], v[228:229], v[32:33]
	v_pk_mul_f32 v[222:223], v[230:231], v[32:33]
	v_cvt_pk_f32_fp8_sdwa v[224:225], v144 src0_sel:WORD_1
	v_cvt_pk_f32_fp8_sdwa v[226:227], v148 src0_sel:WORD_1
	v_cvt_pk_f32_fp8_sdwa v[228:229], v152 src0_sel:WORD_1
	v_cvt_pk_f32_fp8_sdwa v[230:231], v156 src0_sel:WORD_1
	v_pk_fma_f32 v[216:217], v[224:225], v[34:35], v[216:217]
	v_pk_fma_f32 v[218:219], v[226:227], v[34:35], v[218:219]
	v_pk_fma_f32 v[220:221], v[228:229], v[34:35], v[220:221]
	v_pk_fma_f32 v[222:223], v[230:231], v[34:35], v[222:223]
	v_cvt_pk_f32_fp8_e32 v[224:225], v145
	v_cvt_pk_f32_fp8_e32 v[226:227], v149
	v_cvt_pk_f32_fp8_e32 v[228:229], v153
	v_cvt_pk_f32_fp8_e32 v[230:231], v157
	v_pk_fma_f32 v[216:217], v[224:225], v[36:37], v[216:217]
	v_pk_fma_f32 v[218:219], v[226:227], v[36:37], v[218:219]
	v_pk_fma_f32 v[220:221], v[228:229], v[36:37], v[220:221]
	v_pk_fma_f32 v[222:223], v[230:231], v[36:37], v[222:223]
	v_cvt_pk_f32_fp8_sdwa v[224:225], v145 src0_sel:WORD_1
	v_cvt_pk_f32_fp8_sdwa v[226:227], v149 src0_sel:WORD_1
	v_cvt_pk_f32_fp8_sdwa v[228:229], v153 src0_sel:WORD_1
	v_cvt_pk_f32_fp8_sdwa v[230:231], v157 src0_sel:WORD_1
	v_pk_fma_f32 v[216:217], v[224:225], v[38:39], v[216:217]
	v_pk_fma_f32 v[218:219], v[226:227], v[38:39], v[218:219]
	v_pk_fma_f32 v[220:221], v[228:229], v[38:39], v[220:221]
	v_pk_fma_f32 v[222:223], v[230:231], v[38:39], v[222:223]
	v_cvt_pk_f32_fp8_e32 v[224:225], v146
	v_cvt_pk_f32_fp8_e32 v[226:227], v150
	v_cvt_pk_f32_fp8_e32 v[228:229], v154
	v_cvt_pk_f32_fp8_e32 v[230:231], v158
	v_pk_fma_f32 v[216:217], v[224:225], v[40:41], v[216:217]
	v_pk_fma_f32 v[218:219], v[226:227], v[40:41], v[218:219]
	v_pk_fma_f32 v[220:221], v[228:229], v[40:41], v[220:221]
	v_pk_fma_f32 v[222:223], v[230:231], v[40:41], v[222:223]
	v_cvt_pk_f32_fp8_sdwa v[224:225], v146 src0_sel:WORD_1
	v_cvt_pk_f32_fp8_sdwa v[226:227], v150 src0_sel:WORD_1
	v_cvt_pk_f32_fp8_sdwa v[228:229], v154 src0_sel:WORD_1
	v_cvt_pk_f32_fp8_sdwa v[230:231], v158 src0_sel:WORD_1
	v_pk_fma_f32 v[216:217], v[224:225], v[42:43], v[216:217]
	v_pk_fma_f32 v[218:219], v[226:227], v[42:43], v[218:219]
	v_pk_fma_f32 v[220:221], v[228:229], v[42:43], v[220:221]
	v_pk_fma_f32 v[222:223], v[230:231], v[42:43], v[222:223]
	v_cvt_pk_f32_fp8_e32 v[224:225], v147
	v_cvt_pk_f32_fp8_e32 v[226:227], v151
	v_cvt_pk_f32_fp8_e32 v[228:229], v155
	v_cvt_pk_f32_fp8_e32 v[230:231], v159
	v_pk_fma_f32 v[216:217], v[224:225], v[44:45], v[216:217]
	v_pk_fma_f32 v[218:219], v[226:227], v[44:45], v[218:219]
	v_pk_fma_f32 v[220:221], v[228:229], v[44:45], v[220:221]
	v_pk_fma_f32 v[222:223], v[230:231], v[44:45], v[222:223]
	v_cvt_pk_f32_fp8_sdwa v[224:225], v147 src0_sel:WORD_1
	v_cvt_pk_f32_fp8_sdwa v[226:227], v151 src0_sel:WORD_1
	v_cvt_pk_f32_fp8_sdwa v[228:229], v155 src0_sel:WORD_1
	v_cvt_pk_f32_fp8_sdwa v[230:231], v159 src0_sel:WORD_1
	v_pk_fma_f32 v[216:217], v[224:225], v[46:47], v[216:217]
	v_pk_fma_f32 v[218:219], v[226:227], v[46:47], v[218:219]
	v_pk_fma_f32 v[220:221], v[228:229], v[46:47], v[220:221]
	v_pk_fma_f32 v[222:223], v[230:231], v[46:47], v[222:223]
	v_add_f32_e32 v196, v216, v217
	v_add_f32_e32 v197, v218, v219
	v_add_f32_e32 v198, v220, v221
	v_add_f32_e32 v199, v222, v223
	s_sub_i32 s90, s90, 1
	s_cmp_eq_u32 s90, 0
	s_cbranch_scc1 .LU_sw2
.LU_t2_s2:
	s_waitcnt lgkmcnt(0)
	buffer_load_dwordx4 v[144:147], v[232:233], s[56:59], 0 idxen offen
	buffer_load_dwordx4 v[148:151], v[234:235], s[56:59], 0 idxen offen
	buffer_load_dwordx4 v[152:155], v[236:237], s[56:59], 0 idxen offen
	buffer_load_dwordx4 v[156:159], v[238:239], s[56:59], 0 idxen offen
	ds_read_b32 v232, v213 offset:96
	ds_read_b32 v234, v213 offset:100
	ds_read_b32 v236, v213 offset:104
	ds_read_b32 v238, v213 offset:108
	s_waitcnt vmcnt(14)
	v_cvt_pk_f32_fp8_e32 v[224:225], v160
	v_cvt_pk_f32_fp8_e32 v[226:227], v164
	v_cvt_pk_f32_fp8_e32 v[228:229], v168
	v_cvt_pk_f32_fp8_e32 v[230:231], v172
	v_pk_mul_f32 v[216:217], v[224:225], v[32:33]
	v_pk_mul_f32 v[218:219], v[226:227], v[32:33]
	v_pk_mul_f32 v[220:221], v[228:229], v[32:33]
	v_pk_mul_f32 v[222:223], v[230:231], v[32:33]
	v_cvt_pk_f32_fp8_sdwa v[224:225], v160 src0_sel:WORD_1
	v_cvt_pk_f32_fp8_sdwa v[226:227], v164 src0_sel:WORD_1
	v_cvt_pk_f32_fp8_sdwa v[228:229], v168 src0_sel:WORD_1
	v_cvt_pk_f32_fp8_sdwa v[230:231], v172 src0_sel:WORD_1
	v_pk_fma_f32 v[216:217], v[224:225], v[34:35], v[216:217]
	v_pk_fma_f32 v[218:219], v[226:227], v[34:35], v[218:219]
	v_pk_fma_f32 v[220:221], v[228:229], v[34:35], v[220:221]
	v_pk_fma_f32 v[222:223], v[230:231], v[34:35], v[222:223]
	v_cvt_pk_f32_fp8_e32 v[224:225], v161
	v_cvt_pk_f32_fp8_e32 v[226:227], v165
	v_cvt_pk_f32_fp8_e32 v[228:229], v169
	v_cvt_pk_f32_fp8_e32 v[230:231], v173
	v_pk_fma_f32 v[216:217], v[224:225], v[36:37], v[216:217]
	v_pk_fma_f32 v[218:219], v[226:227], v[36:37], v[218:219]
	v_pk_fma_f32 v[220:221], v[228:229], v[36:37], v[220:221]
	v_pk_fma_f32 v[222:223], v[230:231], v[36:37], v[222:223]
	v_cvt_pk_f32_fp8_sdwa v[224:225], v161 src0_sel:WORD_1
	v_cvt_pk_f32_fp8_sdwa v[226:227], v165 src0_sel:WORD_1
	v_cvt_pk_f32_fp8_sdwa v[228:229], v169 src0_sel:WORD_1
	v_cvt_pk_f32_fp8_sdwa v[230:231], v173 src0_sel:WORD_1
	v_pk_fma_f32 v[216:217], v[224:225], v[38:39], v[216:217]
	v_pk_fma_f32 v[218:219], v[226:227], v[38:39], v[218:219]
	v_pk_fma_f32 v[220:221], v[228:229], v[38:39], v[220:221]
	v_pk_fma_f32 v[222:223], v[230:231], v[38:39], v[222:223]
	v_cvt_pk_f32_fp8_e32 v[224:225], v162
	v_cvt_pk_f32_fp8_e32 v[226:227], v166
	v_cvt_pk_f32_fp8_e32 v[228:229], v170
	v_cvt_pk_f32_fp8_e32 v[230:231], v174
	v_pk_fma_f32 v[216:217], v[224:225], v[40:41], v[216:217]
	v_pk_fma_f32 v[218:219], v[226:227], v[40:41], v[218:219]
	v_pk_fma_f32 v[220:221], v[228:229], v[40:41], v[220:221]
	v_pk_fma_f32 v[222:223], v[230:231], v[40:41], v[222:223]
	v_cvt_pk_f32_fp8_sdwa v[224:225], v162 src0_sel:WORD_1
	v_cvt_pk_f32_fp8_sdwa v[226:227], v166 src0_sel:WORD_1
	v_cvt_pk_f32_fp8_sdwa v[228:229], v170 src0_sel:WORD_1
	v_cvt_pk_f32_fp8_sdwa v[230:231], v174 src0_sel:WORD_1
	v_pk_fma_f32 v[216:217], v[224:225], v[42:43], v[216:217]
	v_pk_fma_f32 v[218:219], v[226:227], v[42:43], v[218:219]
	v_pk_fma_f32 v[220:221], v[228:229], v[42:43], v[220:221]
	v_pk_fma_f32 v[222:223], v[230:231], v[42:43], v[222:223]
	v_cvt_pk_f32_fp8_e32 v[224:225], v163
	v_cvt_pk_f32_fp8_e32 v[226:227], v167
	v_cvt_pk_f32_fp8_e32 v[228:229], v171
	v_cvt_pk_f32_fp8_e32 v[230:231], v175
	v_pk_fma_f32 v[216:217], v[224:225], v[44:45], v[216:217]
	v_pk_fma_f32 v[218:219], v[226:227], v[44:45], v[218:219]
	v_pk_fma_f32 v[220:221], v[228:229], v[44:45], v[220:221]
	v_pk_fma_f32 v[222:223], v[230:231], v[44:45], v[222:223]
	v_cvt_pk_f32_fp8_sdwa v[224:225], v163 src0_sel:WORD_1
	v_cvt_pk_f32_fp8_sdwa v[226:227], v167 src0_sel:WORD_1
	v_cvt_pk_f32_fp8_sdwa v[228:229], v171 src0_sel:WORD_1
	v_cvt_pk_f32_fp8_sdwa v[230:231], v175 src0_sel:WORD_1
	v_pk_fma_f32 v[216:217], v[224:225], v[46:47], v[216:217]
	v_pk_fma_f32 v[218:219], v[226:227], v[46:47], v[218:219]
	v_pk_fma_f32 v[220:221], v[228:229], v[46:47], v[220:221]
	v_pk_fma_f32 v[222:223], v[230:231], v[46:47], v[222:223]
	v_add_f32_e32 v200, v216, v217
	v_add_f32_e32 v201, v218, v219
	v_add_f32_e32 v202, v220, v221
	v_add_f32_e32 v203, v222, v223
	s_sub_i32 s90, s90, 1
	s_cmp_eq_u32 s90, 0
	s_cbranch_scc1 .LU_sw3
.LU_t2_s3:
	s_waitcnt lgkmcnt(0)
	buffer_load_dwordx4 v[160:163], v[232:233], s[56:59], 0 idxen offen
	buffer_load_dwordx4 v[164:167], v[234:235], s[56:59], 0 idxen offen
	buffer_load_dwordx4 v[168:171], v[236:237], s[56:59], 0 idxen offen
	buffer_load_dwordx4 v[172:175], v[238:239], s[56:59], 0 idxen offen
	ds_read_b32 v232, v213 offset:112
	ds_read_b32 v234, v213 offset:116
	ds_read_b32 v236, v213 offset:120
	ds_read_b32 v238, v213 offset:124
	s_waitcnt vmcnt(12)
	v_cvt_pk_f32_fp8_e32 v[224:225], v176
	v_cvt_pk_f32_fp8_e32 v[226:227], v180
	v_cvt_pk_f32_fp8_e32 v[228:229], v184
	v_cvt_pk_f32_fp8_e32 v[230:231], v188
	v_pk_mul_f32 v[216:217], v[224:225], v[32:33]
	v_pk_mul_f32 v[218:219], v[226:227], v[32:33]
	v_pk_mul_f32 v[220:221], v[228:229], v[32:33]
	v_pk_mul_f32 v[222:223], v[230:231], v[32:33]
	v_cvt_pk_f32_fp8_sdwa v[224:225], v176 src0_sel:WORD_1
	v_cvt_pk_f32_fp8_sdwa v[226:227], v180 src0_sel:WORD_1
	v_cvt_pk_f32_fp8_sdwa v[228:229], v184 src0_sel:WORD_1
	v_cvt_pk_f32_fp8_sdwa v[230:231], v188 src0_sel:WORD_1
	v_pk_fma_f32 v[216:217], v[224:225], v[34:35], v[216:217]
	v_pk_fma_f32 v[218:219], v[226:227], v[34:35], v[218:219]
	v_pk_fma_f32 v[220:221], v[228:229], v[34:35], v[220:221]
	v_pk_fma_f32 v[222:223], v[230:231], v[34:35], v[222:223]
	v_cvt_pk_f32_fp8_e32 v[224:225], v177
	v_cvt_pk_f32_fp8_e32 v[226:227], v181
	v_cvt_pk_f32_fp8_e32 v[228:229], v185
	v_cvt_pk_f32_fp8_e32 v[230:231], v189
	v_pk_fma_f32 v[216:217], v[224:225], v[36:37], v[216:217]
	v_pk_fma_f32 v[218:219], v[226:227], v[36:37], v[218:219]
	v_pk_fma_f32 v[220:221], v[228:229], v[36:37], v[220:221]
	v_pk_fma_f32 v[222:223], v[230:231], v[36:37], v[222:223]
	v_cvt_pk_f32_fp8_sdwa v[224:225], v177 src0_sel:WORD_1
	v_cvt_pk_f32_fp8_sdwa v[226:227], v181 src0_sel:WORD_1
	v_cvt_pk_f32_fp8_sdwa v[228:229], v185 src0_sel:WORD_1
	v_cvt_pk_f32_fp8_sdwa v[230:231], v189 src0_sel:WORD_1
	v_pk_fma_f32 v[216:217], v[224:225], v[38:39], v[216:217]
	v_pk_fma_f32 v[218:219], v[226:227], v[38:39], v[218:219]
	v_pk_fma_f32 v[220:221], v[228:229], v[38:39], v[220:221]
; __device__ __forceinline__ float gelu_fast(float v) {
;     const float av = fabsf(v), tt = __builtin_amdgcn_rcpf(av * 0.2316418882f + 1.0f);
;     float q = tt * 0.5307027145f + (-0.7265760135f); q = q * tt + 0.7107068705f; q = q * tt + (-0.142248368f); q = q * tt + 0.127414796f; q = q * tt;
;     const float e = __builtin_amdgcn_exp2f((v * v) * (-0.72134752044f));
;     const float m = v * (q * e);
;     return v < 0.f ? m : v - m;
; }
	v_pk_fma_f32 v[222:223], v[230:231], v[38:39], v[222:223]
	v_cvt_pk_f32_fp8_e32 v[224:225], v178
	v_cvt_pk_f32_fp8_e32 v[226:227], v182
	v_cvt_pk_f32_fp8_e32 v[228:229], v186
	v_cvt_pk_f32_fp8_e32 v[230:231], v190
	v_pk_fma_f32 v[216:217], v[224:225], v[40:41], v[216:217]
	v_pk_fma_f32 v[218:219], v[226:227], v[40:41], v[218:219]
	v_pk_fma_f32 v[220:221], v[228:229], v[40:41], v[220:221]
	v_pk_fma_f32 v[222:223], v[230:231], v[40:41], v[222:223]
	v_cvt_pk_f32_fp8_sdwa v[224:225], v178 src0_sel:WORD_1
	v_cvt_pk_f32_fp8_sdwa v[226:227], v182 src0_sel:WORD_1
	v_cvt_pk_f32_fp8_sdwa v[228:229], v186 src0_sel:WORD_1
	v_cvt_pk_f32_fp8_sdwa v[230:231], v190 src0_sel:WORD_1
	v_pk_fma_f32 v[216:217], v[224:225], v[42:43], v[216:217]
	v_pk_fma_f32 v[218:219], v[226:227], v[42:43], v[218:219]
	v_pk_fma_f32 v[220:221], v[228:229], v[42:43], v[220:221]
	v_pk_fma_f32 v[222:223], v[230:231], v[42:43], v[222:223]
	v_cvt_pk_f32_fp8_e32 v[224:225], v179
	v_cvt_pk_f32_fp8_e32 v[226:227], v183
	v_cvt_pk_f32_fp8_e32 v[228:229], v187
	v_cvt_pk_f32_fp8_e32 v[230:231], v191
	v_pk_fma_f32 v[216:217], v[224:225], v[44:45], v[216:217]
	v_pk_fma_f32 v[218:219], v[226:227], v[44:45], v[218:219]
	v_pk_fma_f32 v[220:221], v[228:229], v[44:45], v[220:221]
	v_pk_fma_f32 v[222:223], v[230:231], v[44:45], v[222:223]
	v_cvt_pk_f32_fp8_sdwa v[224:225], v179 src0_sel:WORD_1
	v_cvt_pk_f32_fp8_sdwa v[226:227], v183 src0_sel:WORD_1
	v_cvt_pk_f32_fp8_sdwa v[228:229], v187 src0_sel:WORD_1
	v_cvt_pk_f32_fp8_sdwa v[230:231], v191 src0_sel:WORD_1
	v_pk_fma_f32 v[216:217], v[224:225], v[46:47], v[216:217]
	v_pk_fma_f32 v[218:219], v[226:227], v[46:47], v[218:219]
	v_pk_fma_f32 v[220:221], v[228:229], v[46:47], v[220:221]
	v_pk_fma_f32 v[222:223], v[230:231], v[46:47], v[222:223]
	v_add_f32_e32 v204, v216, v217
	v_add_f32_e32 v205, v218, v219
	v_add_f32_e32 v206, v220, v221
	v_add_f32_e32 v207, v222, v223
	s_nop 0
	v_permlane32_swap_b32_e32 v192, v200
	v_permlane32_swap_b32_e32 v193, v201
	v_permlane32_swap_b32_e32 v194, v202
	v_permlane32_swap_b32_e32 v195, v203
	v_permlane32_swap_b32_e32 v196, v204
	v_permlane32_swap_b32_e32 v197, v205
	v_permlane32_swap_b32_e32 v198, v206
	v_permlane32_swap_b32_e32 v199, v207
	v_add_f32_e32 v192, v192, v200
	v_add_f32_e32 v193, v193, v201
	v_add_f32_e32 v194, v194, v202
	v_add_f32_e32 v195, v195, v203
	v_add_f32_e32 v196, v196, v204
	v_add_f32_e32 v197, v197, v205
	v_add_f32_e32 v198, v198, v206
	v_add_f32_e32 v199, v199, v207
	v_permlane16_swap_b32_e32 v192, v196
	v_permlane16_swap_b32_e32 v193, v197
	v_permlane16_swap_b32_e32 v194, v198
	v_permlane16_swap_b32_e32 v195, v199
	v_add_f32_e32 v192, v192, v196
	v_add_f32_e32 v193, v193, v197
	v_add_f32_e32 v194, v194, v198
	v_add_f32_e32 v195, v195, v199
	v_add_f32_dpp v216, v192, v192 row_ror:8 row_mask:0xf bank_mask:0xf
	v_add_f32_dpp v218, v194, v194 row_ror:8 row_mask:0xf bank_mask:0xf
	v_add_f32_dpp v216, v193, v193 row_ror:8 row_mask:0xf bank_mask:0xc
	v_add_f32_dpp v218, v195, v195 row_ror:8 row_mask:0xf bank_mask:0xc
	s_nop 1
	v_add_f32_dpp v220, v216, v216 row_half_mirror row_mask:0xf bank_mask:0xf
	v_add_f32_dpp v220, v218, v218 row_half_mirror row_mask:0xf bank_mask:0xa
	s_nop 1
	v_add_f32_dpp v220, v220, v220 quad_perm:[1,0,3,2] row_mask:0xf bank_mask:0xf
	s_nop 1
	v_add_f32_dpp v220, v220, v220 quad_perm:[2,3,0,1] row_mask:0xf bank_mask:0xf
	v_mul_f32_e32 v216, v252, v220
	v_fma_f32 v218, |v216|, s72, 1.0
	v_mul_f32_e32 v222, v216, v216
	v_rcp_f32_e32 v218, v218
	v_mul_f32_e32 v222, 0xbf38aa3b, v222
	v_exp_f32_e32 v222, v222
	v_fmamk_f32 v224, v218, 0x3f07dc22, v242
	v_fmaak_f32 v224, v218, v224, 0x3f35f0e3
	v_fmaak_f32 v224, v218, v224, 0xbe11a98e
	v_fmaak_f32 v224, v218, v224, 0x3e027906
	v_mul_f32_e32 v224, v218, v224
	v_mul_f32_e32 v224, v222, v224
	v_mul_f32_e32 v226, v216, v224
	v_fma_f32 v224, -v216, v224, v216
	v_cmp_gt_f32_e32 vcc, 0, v216
	s_nop 1
	v_cndmask_b32_e32 v224, v224, v226, vcc
	v_mul_f32_e32 v224, v249, v224
	v_mul_f32_e32 v224, v253, v224
	ds_write_b32 v211, v224 offset:4992
	v_add_u32_e32 v211, 64, v211
	v_add_u32_e32 v213, 64, v213
	ds_read_b32 v248, v211
	ds_read_b32 v249, v211 offset:4992
	s_add_i32 s21, s21, 4
	s_sub_i32 s90, s90, 1
	s_cmp_eq_u32 s90, 0
	s_cbranch_scc1 .LU_sw0
	s_branch .LU_t2_s0
.LU_t3_s0:
	s_cmp_ge_u32 s21, s20
	s_cbranch_scc1 .LU_done
	s_waitcnt lgkmcnt(0)
	v_lshlrev_b32_e32 v208, 2, v248
	buffer_load_dword v252, v208, s[24:27], 0 offen
	buffer_load_dword v253, v208, s[28:31], 0 offen
	buffer_load_dwordx4 v[176:179], v[232:233], s[56:59], 0 idxen offen
	buffer_load_dwordx4 v[180:183], v[234:235], s[56:59], 0 idxen offen
	buffer_load_dwordx4 v[184:187], v[236:237], s[56:59], 0 idxen offen
	buffer_load_dwordx4 v[188:191], v[238:239], s[56:59], 0 idxen offen
	ds_read_b32 v232, v213 offset:64
	ds_read_b32 v234, v213 offset:68
	ds_read_b32 v236, v213 offset:72
	ds_read_b32 v238, v213 offset:76
	s_waitcnt vmcnt(14)
	v_cvt_pk_f32_fp8_e32 v[224:225], v128
	v_cvt_pk_f32_fp8_e32 v[226:227], v132
	v_cvt_pk_f32_fp8_e32 v[228:229], v136
	v_cvt_pk_f32_fp8_e32 v[230:231], v140
	v_pk_mul_f32 v[216:217], v[224:225], v[48:49]
	v_pk_mul_f32 v[218:219], v[226:227], v[48:49]
	v_pk_mul_f32 v[220:221], v[228:229], v[48:49]
	v_pk_mul_f32 v[222:223], v[230:231], v[48:49]
	v_cvt_pk_f32_fp8_sdwa v[224:225], v128 src0_sel:WORD_1
	v_cvt_pk_f32_fp8_sdwa v[226:227], v132 src0_sel:WORD_1
	v_cvt_pk_f32_fp8_sdwa v[228:229], v136 src0_sel:WORD_1
	v_cvt_pk_f32_fp8_sdwa v[230:231], v140 src0_sel:WORD_1
	v_pk_fma_f32 v[216:217], v[224:225], v[50:51], v[216:217]
	v_pk_fma_f32 v[218:219], v[226:227], v[50:51], v[218:219]
	v_pk_fma_f32 v[220:221], v[228:229], v[50:51], v[220:221]
	v_pk_fma_f32 v[222:223], v[230:231], v[50:51], v[222:223]
	v_cvt_pk_f32_fp8_e32 v[224:225], v129
	v_cvt_pk_f32_fp8_e32 v[226:227], v133
	v_cvt_pk_f32_fp8_e32 v[228:229], v137
	v_cvt_pk_f32_fp8_e32 v[230:231], v141
	v_pk_fma_f32 v[216:217], v[224:225], v[52:53], v[216:217]
	v_pk_fma_f32 v[218:219], v[226:227], v[52:53], v[218:219]
	v_pk_fma_f32 v[220:221], v[228:229], v[52:53], v[220:221]
	v_pk_fma_f32 v[222:223], v[230:231], v[52:53], v[222:223]
	v_cvt_pk_f32_fp8_sdwa v[224:225], v129 src0_sel:WORD_1
	v_cvt_pk_f32_fp8_sdwa v[226:227], v133 src0_sel:WORD_1
	v_cvt_pk_f32_fp8_sdwa v[228:229], v137 src0_sel:WORD_1
	v_cvt_pk_f32_fp8_sdwa v[230:231], v141 src0_sel:WORD_1
	v_pk_fma_f32 v[216:217], v[224:225], v[54:55], v[216:217]
	v_pk_fma_f32 v[218:219], v[226:227], v[54:55], v[218:219]
	v_pk_fma_f32 v[220:221], v[228:229], v[54:55], v[220:221]
	v_pk_fma_f32 v[222:223], v[230:231], v[54:55], v[222:223]
	v_cvt_pk_f32_fp8_e32 v[224:225], v130
	v_cvt_pk_f32_fp8_e32 v[226:227], v134
	v_cvt_pk_f32_fp8_e32 v[228:229], v138
	v_cvt_pk_f32_fp8_e32 v[230:231], v142
	v_pk_fma_f32 v[216:217], v[224:225], v[56:57], v[216:217]
	v_pk_fma_f32 v[218:219], v[226:227], v[56:57], v[218:219]
	v_pk_fma_f32 v[220:221], v[228:229], v[56:57], v[220:221]
	v_pk_fma_f32 v[222:223], v[230:231], v[56:57], v[222:223]
	v_cvt_pk_f32_fp8_sdwa v[224:225], v130 src0_sel:WORD_1
	v_cvt_pk_f32_fp8_sdwa v[226:227], v134 src0_sel:WORD_1
	v_cvt_pk_f32_fp8_sdwa v[228:229], v138 src0_sel:WORD_1
	v_cvt_pk_f32_fp8_sdwa v[230:231], v142 src0_sel:WORD_1
	v_pk_fma_f32 v[216:217], v[224:225], v[58:59], v[216:217]
	v_pk_fma_f32 v[218:219], v[226:227], v[58:59], v[218:219]
	v_pk_fma_f32 v[220:221], v[228:229], v[58:59], v[220:221]
	v_pk_fma_f32 v[222:223], v[230:231], v[58:59], v[222:223]
	v_cvt_pk_f32_fp8_e32 v[224:225], v131
	v_cvt_pk_f32_fp8_e32 v[226:227], v135
	v_cvt_pk_f32_fp8_e32 v[228:229], v139
	v_cvt_pk_f32_fp8_e32 v[230:231], v143
	v_pk_fma_f32 v[216:217], v[224:225], v[60:61], v[216:217]
	v_pk_fma_f32 v[218:219], v[226:227], v[60:61], v[218:219]
	v_pk_fma_f32 v[220:221], v[228:229], v[60:61], v[220:221]
	v_pk_fma_f32 v[222:223], v[230:231], v[60:61], v[222:223]
	v_cvt_pk_f32_fp8_sdwa v[224:225], v131 src0_sel:WORD_1
	v_cvt_pk_f32_fp8_sdwa v[226:227], v135 src0_sel:WORD_1
	v_cvt_pk_f32_fp8_sdwa v[228:229], v139 src0_sel:WORD_1
	v_cvt_pk_f32_fp8_sdwa v[230:231], v143 src0_sel:WORD_1
	v_pk_fma_f32 v[216:217], v[224:225], v[62:63], v[216:217]
	v_pk_fma_f32 v[218:219], v[226:227], v[62:63], v[218:219]
	v_pk_fma_f32 v[220:221], v[228:229], v[62:63], v[220:221]
	v_pk_fma_f32 v[222:223], v[230:231], v[62:63], v[222:223]
	v_add_f32_e32 v192, v216, v217
	v_add_f32_e32 v193, v218, v219
	v_add_f32_e32 v194, v220, v221
	v_add_f32_e32 v195, v222, v223
	s_sub_i32 s90, s90, 1
	s_cmp_eq_u32 s90, 0
	s_cbranch_scc1 .LU_sw1
.LU_t3_s1:
	s_waitcnt lgkmcnt(0)
	buffer_load_dwordx4 v[128:131], v[232:233], s[56:59], 0 idxen offen
	buffer_load_dwordx4 v[132:135], v[234:235], s[56:59], 0 idxen offen
	buffer_load_dwordx4 v[136:139], v[236:237], s[56:59], 0 idxen offen
	buffer_load_dwordx4 v[140:143], v[238:239], s[56:59], 0 idxen offen
	ds_read_b32 v232, v213 offset:80
	ds_read_b32 v234, v213 offset:84
	ds_read_b32 v236, v213 offset:88
	ds_read_b32 v238, v213 offset:92
	s_waitcnt vmcnt(14)
	v_cvt_pk_f32_fp8_e32 v[224:225], v144
	v_cvt_pk_f32_fp8_e32 v[226:227], v148
	v_cvt_pk_f32_fp8_e32 v[228:229], v152
	v_cvt_pk_f32_fp8_e32 v[230:231], v156
	v_pk_mul_f32 v[216:217], v[224:225], v[48:49]
	v_pk_mul_f32 v[218:219], v[226:227], v[48:49]
	v_pk_mul_f32 v[220:221], v[228:229], v[48:49]
	v_pk_mul_f32 v[222:223], v[230:231], v[48:49]
	v_cvt_pk_f32_fp8_sdwa v[224:225], v144 src0_sel:WORD_1
	v_cvt_pk_f32_fp8_sdwa v[226:227], v148 src0_sel:WORD_1
	v_cvt_pk_f32_fp8_sdwa v[228:229], v152 src0_sel:WORD_1
	v_cvt_pk_f32_fp8_sdwa v[230:231], v156 src0_sel:WORD_1
	v_pk_fma_f32 v[216:217], v[224:225], v[50:51], v[216:217]
	v_pk_fma_f32 v[218:219], v[226:227], v[50:51], v[218:219]
	v_pk_fma_f32 v[220:221], v[228:229], v[50:51], v[220:221]
	v_pk_fma_f32 v[222:223], v[230:231], v[50:51], v[222:223]
	v_cvt_pk_f32_fp8_e32 v[224:225], v145
	v_cvt_pk_f32_fp8_e32 v[226:227], v149
	v_cvt_pk_f32_fp8_e32 v[228:229], v153
	v_cvt_pk_f32_fp8_e32 v[230:231], v157
	v_pk_fma_f32 v[216:217], v[224:225], v[52:53], v[216:217]
	v_pk_fma_f32 v[218:219], v[226:227], v[52:53], v[218:219]
	v_pk_fma_f32 v[220:221], v[228:229], v[52:53], v[220:221]
	v_pk_fma_f32 v[222:223], v[230:231], v[52:53], v[222:223]
	v_cvt_pk_f32_fp8_sdwa v[224:225], v145 src0_sel:WORD_1
	v_cvt_pk_f32_fp8_sdwa v[226:227], v149 src0_sel:WORD_1
	v_cvt_pk_f32_fp8_sdwa v[228:229], v153 src0_sel:WORD_1
	v_cvt_pk_f32_fp8_sdwa v[230:231], v157 src0_sel:WORD_1
	v_pk_fma_f32 v[216:217], v[224:225], v[54:55], v[216:217]
	v_pk_fma_f32 v[218:219], v[226:227], v[54:55], v[218:219]
	v_pk_fma_f32 v[220:221], v[228:229], v[54:55], v[220:221]
	v_pk_fma_f32 v[222:223], v[230:231], v[54:55], v[222:223]
	v_cvt_pk_f32_fp8_e32 v[224:225], v146
	v_cvt_pk_f32_fp8_e32 v[226:227], v150
	v_cvt_pk_f32_fp8_e32 v[228:229], v154
	v_cvt_pk_f32_fp8_e32 v[230:231], v158
	v_pk_fma_f32 v[216:217], v[224:225], v[56:57], v[216:217]
	v_pk_fma_f32 v[218:219], v[226:227], v[56:57], v[218:219]
	v_pk_fma_f32 v[220:221], v[228:229], v[56:57], v[220:221]
	v_pk_fma_f32 v[222:223], v[230:231], v[56:57], v[222:223]
	v_cvt_pk_f32_fp8_sdwa v[224:225], v146 src0_sel:WORD_1
	v_cvt_pk_f32_fp8_sdwa v[226:227], v150 src0_sel:WORD_1
	v_cvt_pk_f32_fp8_sdwa v[228:229], v154 src0_sel:WORD_1
	v_cvt_pk_f32_fp8_sdwa v[230:231], v158 src0_sel:WORD_1
	v_pk_fma_f32 v[216:217], v[224:225], v[58:59], v[216:217]
	v_pk_fma_f32 v[218:219], v[226:227], v[58:59], v[218:219]
	v_pk_fma_f32 v[220:221], v[228:229], v[58:59], v[220:221]
	v_pk_fma_f32 v[222:223], v[230:231], v[58:59], v[222:223]
	v_cvt_pk_f32_fp8_e32 v[224:225], v147
	v_cvt_pk_f32_fp8_e32 v[226:227], v151
	v_cvt_pk_f32_fp8_e32 v[228:229], v155
	v_cvt_pk_f32_fp8_e32 v[230:231], v159
	v_pk_fma_f32 v[216:217], v[224:225], v[60:61], v[216:217]
	v_pk_fma_f32 v[218:219], v[226:227], v[60:61], v[218:219]
	v_pk_fma_f32 v[220:221], v[228:229], v[60:61], v[220:221]
	v_pk_fma_f32 v[222:223], v[230:231], v[60:61], v[222:223]
	v_cvt_pk_f32_fp8_sdwa v[224:225], v147 src0_sel:WORD_1
	v_cvt_pk_f32_fp8_sdwa v[226:227], v151 src0_sel:WORD_1
	v_cvt_pk_f32_fp8_sdwa v[228:229], v155 src0_sel:WORD_1
	v_cvt_pk_f32_fp8_sdwa v[230:231], v159 src0_sel:WORD_1
	v_pk_fma_f32 v[216:217], v[224:225], v[62:63], v[216:217]
	v_pk_fma_f32 v[218:219], v[226:227], v[62:63], v[218:219]
	v_pk_fma_f32 v[220:221], v[228:229], v[62:63], v[220:221]
	v_pk_fma_f32 v[222:223], v[230:231], v[62:63], v[222:223]
	v_add_f32_e32 v196, v216, v217
	v_add_f32_e32 v197, v218, v219
	v_add_f32_e32 v198, v220, v221
	v_add_f32_e32 v199, v222, v223
	s_sub_i32 s90, s90, 1
	s_cmp_eq_u32 s90, 0
	s_cbranch_scc1 .LU_sw2
.LU_t3_s2:
	s_waitcnt lgkmcnt(0)
	buffer_load_dwordx4 v[144:147], v[232:233], s[56:59], 0 idxen offen
	buffer_load_dwordx4 v[148:151], v[234:235], s[56:59], 0 idxen offen
	buffer_load_dwordx4 v[152:155], v[236:237], s[56:59], 0 idxen offen
	buffer_load_dwordx4 v[156:159], v[238:239], s[56:59], 0 idxen offen
	ds_read_b32 v232, v213 offset:96
	ds_read_b32 v234, v213 offset:100
	ds_read_b32 v236, v213 offset:104
	ds_read_b32 v238, v213 offset:108
	s_waitcnt vmcnt(14)
	v_cvt_pk_f32_fp8_e32 v[224:225], v160
	v_cvt_pk_f32_fp8_e32 v[226:227], v164
	v_cvt_pk_f32_fp8_e32 v[228:229], v168
	v_cvt_pk_f32_fp8_e32 v[230:231], v172
	v_pk_mul_f32 v[216:217], v[224:225], v[48:49]
	v_pk_mul_f32 v[218:219], v[226:227], v[48:49]
	v_pk_mul_f32 v[220:221], v[228:229], v[48:49]
	v_pk_mul_f32 v[222:223], v[230:231], v[48:49]
	v_cvt_pk_f32_fp8_sdwa v[224:225], v160 src0_sel:WORD_1
	v_cvt_pk_f32_fp8_sdwa v[226:227], v164 src0_sel:WORD_1
	v_cvt_pk_f32_fp8_sdwa v[228:229], v168 src0_sel:WORD_1
	v_cvt_pk_f32_fp8_sdwa v[230:231], v172 src0_sel:WORD_1
	v_pk_fma_f32 v[216:217], v[224:225], v[50:51], v[216:217]
	v_pk_fma_f32 v[218:219], v[226:227], v[50:51], v[218:219]
	v_pk_fma_f32 v[220:221], v[228:229], v[50:51], v[220:221]
	v_pk_fma_f32 v[222:223], v[230:231], v[50:51], v[222:223]
	v_cvt_pk_f32_fp8_e32 v[224:225], v161
	v_cvt_pk_f32_fp8_e32 v[226:227], v165
	v_cvt_pk_f32_fp8_e32 v[228:229], v169
	v_cvt_pk_f32_fp8_e32 v[230:231], v173
	v_pk_fma_f32 v[216:217], v[224:225], v[52:53], v[216:217]
	v_pk_fma_f32 v[218:219], v[226:227], v[52:53], v[218:219]
	v_pk_fma_f32 v[220:221], v[228:229], v[52:53], v[220:221]
	v_pk_fma_f32 v[222:223], v[230:231], v[52:53], v[222:223]
	v_cvt_pk_f32_fp8_sdwa v[224:225], v161 src0_sel:WORD_1
	v_cvt_pk_f32_fp8_sdwa v[226:227], v165 src0_sel:WORD_1
	v_cvt_pk_f32_fp8_sdwa v[228:229], v169 src0_sel:WORD_1
	v_cvt_pk_f32_fp8_sdwa v[230:231], v173 src0_sel:WORD_1
	v_pk_fma_f32 v[216:217], v[224:225], v[54:55], v[216:217]
	v_pk_fma_f32 v[218:219], v[226:227], v[54:55], v[218:219]
	v_pk_fma_f32 v[220:221], v[228:229], v[54:55], v[220:221]
	v_pk_fma_f32 v[222:223], v[230:231], v[54:55], v[222:223]
	v_cvt_pk_f32_fp8_e32 v[224:225], v162
	v_cvt_pk_f32_fp8_e32 v[226:227], v166
	v_cvt_pk_f32_fp8_e32 v[228:229], v170
	v_cvt_pk_f32_fp8_e32 v[230:231], v174
	v_pk_fma_f32 v[216:217], v[224:225], v[56:57], v[216:217]
	v_pk_fma_f32 v[218:219], v[226:227], v[56:57], v[218:219]
	v_pk_fma_f32 v[220:221], v[228:229], v[56:57], v[220:221]
	v_pk_fma_f32 v[222:223], v[230:231], v[56:57], v[222:223]
	v_cvt_pk_f32_fp8_sdwa v[224:225], v162 src0_sel:WORD_1
	v_cvt_pk_f32_fp8_sdwa v[226:227], v166 src0_sel:WORD_1
	v_cvt_pk_f32_fp8_sdwa v[228:229], v170 src0_sel:WORD_1
	v_cvt_pk_f32_fp8_sdwa v[230:231], v174 src0_sel:WORD_1
	v_pk_fma_f32 v[216:217], v[224:225], v[58:59], v[216:217]
	v_pk_fma_f32 v[218:219], v[226:227], v[58:59], v[218:219]
	v_pk_fma_f32 v[220:221], v[228:229], v[58:59], v[220:221]
	v_pk_fma_f32 v[222:223], v[230:231], v[58:59], v[222:223]
	v_cvt_pk_f32_fp8_e32 v[224:225], v163
	v_cvt_pk_f32_fp8_e32 v[226:227], v167
	v_cvt_pk_f32_fp8_e32 v[228:229], v171
	v_cvt_pk_f32_fp8_e32 v[230:231], v175
	v_pk_fma_f32 v[216:217], v[224:225], v[60:61], v[216:217]
	v_pk_fma_f32 v[218:219], v[226:227], v[60:61], v[218:219]
	v_pk_fma_f32 v[220:221], v[228:229], v[60:61], v[220:221]
	v_pk_fma_f32 v[222:223], v[230:231], v[60:61], v[222:223]
	v_cvt_pk_f32_fp8_sdwa v[224:225], v163 src0_sel:WORD_1
	v_cvt_pk_f32_fp8_sdwa v[226:227], v167 src0_sel:WORD_1
	v_cvt_pk_f32_fp8_sdwa v[228:229], v171 src0_sel:WORD_1
	v_cvt_pk_f32_fp8_sdwa v[230:231], v175 src0_sel:WORD_1
	v_pk_fma_f32 v[216:217], v[224:225], v[62:63], v[216:217]
	v_pk_fma_f32 v[218:219], v[226:227], v[62:63], v[218:219]
	v_pk_fma_f32 v[220:221], v[228:229], v[62:63], v[220:221]
	v_pk_fma_f32 v[222:223], v[230:231], v[62:63], v[222:223]
	v_add_f32_e32 v200, v216, v217
	v_add_f32_e32 v201, v218, v219
	v_add_f32_e32 v202, v220, v221
	v_add_f32_e32 v203, v222, v223
	s_sub_i32 s90, s90, 1
	s_cmp_eq_u32 s90, 0
	s_cbranch_scc1 .LU_sw3
.LU_t3_s3:
	s_waitcnt lgkmcnt(0)
	buffer_load_dwordx4 v[160:163], v[232:233], s[56:59], 0 idxen offen
	buffer_load_dwordx4 v[164:167], v[234:235], s[56:59], 0 idxen offen
	buffer_load_dwordx4 v[168:171], v[236:237], s[56:59], 0 idxen offen
	buffer_load_dwordx4 v[172:175], v[238:239], s[56:59], 0 idxen offen
	ds_read_b32 v232, v213 offset:112
	ds_read_b32 v234, v213 offset:116
	ds_read_b32 v236, v213 offset:120
	ds_read_b32 v238, v213 offset:124
	s_waitcnt vmcnt(12)
	v_cvt_pk_f32_fp8_e32 v[224:225], v176
	v_cvt_pk_f32_fp8_e32 v[226:227], v180
	v_cvt_pk_f32_fp8_e32 v[228:229], v184
	v_cvt_pk_f32_fp8_e32 v[230:231], v188
	v_pk_mul_f32 v[216:217], v[224:225], v[48:49]
	v_pk_mul_f32 v[218:219], v[226:227], v[48:49]
	v_pk_mul_f32 v[220:221], v[228:229], v[48:49]
	v_pk_mul_f32 v[222:223], v[230:231], v[48:49]
	v_cvt_pk_f32_fp8_sdwa v[224:225], v176 src0_sel:WORD_1
	v_cvt_pk_f32_fp8_sdwa v[226:227], v180 src0_sel:WORD_1
	v_cvt_pk_f32_fp8_sdwa v[228:229], v184 src0_sel:WORD_1
	v_cvt_pk_f32_fp8_sdwa v[230:231], v188 src0_sel:WORD_1
	v_pk_fma_f32 v[216:217], v[224:225], v[50:51], v[216:217]
	v_pk_fma_f32 v[218:219], v[226:227], v[50:51], v[218:219]
	v_pk_fma_f32 v[220:221], v[228:229], v[50:51], v[220:221]
	v_pk_fma_f32 v[222:223], v[230:231], v[50:51], v[222:223]
	v_cvt_pk_f32_fp8_e32 v[224:225], v177
	v_cvt_pk_f32_fp8_e32 v[226:227], v181
	v_cvt_pk_f32_fp8_e32 v[228:229], v185
	v_cvt_pk_f32_fp8_e32 v[230:231], v189
	v_pk_fma_f32 v[216:217], v[224:225], v[52:53], v[216:217]
	v_pk_fma_f32 v[218:219], v[226:227], v[52:53], v[218:219]
	v_pk_fma_f32 v[220:221], v[228:229], v[52:53], v[220:221]
	v_pk_fma_f32 v[222:223], v[230:231], v[52:53], v[222:223]
	v_cvt_pk_f32_fp8_sdwa v[224:225], v177 src0_sel:WORD_1
	v_cvt_pk_f32_fp8_sdwa v[226:227], v181 src0_sel:WORD_1
	v_cvt_pk_f32_fp8_sdwa v[228:229], v185 src0_sel:WORD_1
	v_cvt_pk_f32_fp8_sdwa v[230:231], v189 src0_sel:WORD_1
	v_pk_fma_f32 v[216:217], v[224:225], v[54:55], v[216:217]
	v_pk_fma_f32 v[218:219], v[226:227], v[54:55], v[218:219]
	v_pk_fma_f32 v[220:221], v[228:229], v[54:55], v[220:221]
	v_pk_fma_f32 v[222:223], v[230:231], v[54:55], v[222:223]
	v_cvt_pk_f32_fp8_e32 v[224:225], v178
	v_cvt_pk_f32_fp8_e32 v[226:227], v182
	v_cvt_pk_f32_fp8_e32 v[228:229], v186
	v_cvt_pk_f32_fp8_e32 v[230:231], v190
	v_pk_fma_f32 v[216:217], v[224:225], v[56:57], v[216:217]
	v_pk_fma_f32 v[218:219], v[226:227], v[56:57], v[218:219]
	v_pk_fma_f32 v[220:221], v[228:229], v[56:57], v[220:221]
	v_pk_fma_f32 v[222:223], v[230:231], v[56:57], v[222:223]
	v_cvt_pk_f32_fp8_sdwa v[224:225], v178 src0_sel:WORD_1
	v_cvt_pk_f32_fp8_sdwa v[226:227], v182 src0_sel:WORD_1
	v_cvt_pk_f32_fp8_sdwa v[228:229], v186 src0_sel:WORD_1
	v_cvt_pk_f32_fp8_sdwa v[230:231], v190 src0_sel:WORD_1
	v_pk_fma_f32 v[216:217], v[224:225], v[58:59], v[216:217]
	v_pk_fma_f32 v[218:219], v[226:227], v[58:59], v[218:219]
	v_pk_fma_f32 v[220:221], v[228:229], v[58:59], v[220:221]
	v_pk_fma_f32 v[222:223], v[230:231], v[58:59], v[222:223]
	v_cvt_pk_f32_fp8_e32 v[224:225], v179
	v_cvt_pk_f32_fp8_e32 v[226:227], v183
	v_cvt_pk_f32_fp8_e32 v[228:229], v187
	v_cvt_pk_f32_fp8_e32 v[230:231], v191
	v_pk_fma_f32 v[216:217], v[224:225], v[60:61], v[216:217]
	v_pk_fma_f32 v[218:219], v[226:227], v[60:61], v[218:219]
	v_pk_fma_f32 v[220:221], v[228:229], v[60:61], v[220:221]
	v_pk_fma_f32 v[222:223], v[230:231], v[60:61], v[222:223]
	v_cvt_pk_f32_fp8_sdwa v[224:225], v179 src0_sel:WORD_1
	v_cvt_pk_f32_fp8_sdwa v[226:227], v183 src0_sel:WORD_1
	v_cvt_pk_f32_fp8_sdwa v[228:229], v187 src0_sel:WORD_1
	v_cvt_pk_f32_fp8_sdwa v[230:231], v191 src0_sel:WORD_1
	v_pk_fma_f32 v[216:217], v[224:225], v[62:63], v[216:217]
	v_pk_fma_f32 v[218:219], v[226:227], v[62:63], v[218:219]
	v_pk_fma_f32 v[220:221], v[228:229], v[62:63], v[220:221]
	v_pk_fma_f32 v[222:223], v[230:231], v[62:63], v[222:223]
	v_add_f32_e32 v204, v216, v217
	v_add_f32_e32 v205, v218, v219
	v_add_f32_e32 v206, v220, v221
	v_add_f32_e32 v207, v222, v223
	s_nop 0
	v_permlane32_swap_b32_e32 v192, v200
	v_permlane32_swap_b32_e32 v193, v201
	v_permlane32_swap_b32_e32 v194, v202
	v_permlane32_swap_b32_e32 v195, v203
	v_permlane32_swap_b32_e32 v196, v204
	v_permlane32_swap_b32_e32 v197, v205
	v_permlane32_swap_b32_e32 v198, v206
	v_permlane32_swap_b32_e32 v199, v207
	v_add_f32_e32 v192, v192, v200
	v_add_f32_e32 v193, v193, v201
	v_add_f32_e32 v194, v194, v202
	v_add_f32_e32 v195, v195, v203
	v_add_f32_e32 v196, v196, v204
	v_add_f32_e32 v197, v197, v205
	v_add_f32_e32 v198, v198, v206
	v_add_f32_e32 v199, v199, v207
	v_permlane16_swap_b32_e32 v192, v196
	v_permlane16_swap_b32_e32 v193, v197
	v_permlane16_swap_b32_e32 v194, v198
	v_permlane16_swap_b32_e32 v195, v199
	v_add_f32_e32 v192, v192, v196
	v_add_f32_e32 v193, v193, v197
	v_add_f32_e32 v194, v194, v198
	v_add_f32_e32 v195, v195, v199
	v_add_f32_dpp v216, v192, v192 row_ror:8 row_mask:0xf bank_mask:0xf
	v_add_f32_dpp v218, v194, v194 row_ror:8 row_mask:0xf bank_mask:0xf
	v_add_f32_dpp v216, v193, v193 row_ror:8 row_mask:0xf bank_mask:0xc
	v_add_f32_dpp v218, v195, v195 row_ror:8 row_mask:0xf bank_mask:0xc
	s_nop 1
	v_add_f32_dpp v220, v216, v216 row_half_mirror row_mask:0xf bank_mask:0xf
	v_add_f32_dpp v220, v218, v218 row_half_mirror row_mask:0xf bank_mask:0xa
	s_nop 1
	v_add_f32_dpp v220, v220, v220 quad_perm:[1,0,3,2] row_mask:0xf bank_mask:0xf
	s_nop 1
	v_add_f32_dpp v220, v220, v220 quad_perm:[2,3,0,1] row_mask:0xf bank_mask:0xf
	v_mul_f32_e32 v216, v252, v220
	v_fma_f32 v218, |v216|, s72, 1.0
	v_mul_f32_e32 v222, v216, v216
	v_rcp_f32_e32 v218, v218
	v_mul_f32_e32 v222, 0xbf38aa3b, v222
	v_exp_f32_e32 v222, v222
	v_fmamk_f32 v224, v218, 0x3f07dc22, v242
	v_fmaak_f32 v224, v218, v224, 0x3f35f0e3
	v_fmaak_f32 v224, v218, v224, 0xbe11a98e
	v_fmaak_f32 v224, v218, v224, 0x3e027906
	v_mul_f32_e32 v224, v218, v224
	v_mul_f32_e32 v224, v222, v224
	v_mul_f32_e32 v226, v216, v224
	v_fma_f32 v224, -v216, v224, v216
	v_cmp_gt_f32_e32 vcc, 0, v216
	s_nop 1
	v_cndmask_b32_e32 v224, v224, v226, vcc
	v_mul_f32_e32 v224, v249, v224
	v_mul_f32_e32 v224, v253, v224
	ds_write_b32 v211, v224 offset:4992
	v_add_u32_e32 v211, 64, v211
	v_add_u32_e32 v213, 64, v213
	ds_read_b32 v248, v211
	ds_read_b32 v249, v211 offset:4992
	s_add_i32 s21, s21, 4
	s_sub_i32 s90, s90, 1
	s_cmp_eq_u32 s90, 0
	s_cbranch_scc1 .LU_sw0
	s_branch .LU_t3_s0
.LU_t4_s0:
	s_cmp_ge_u32 s21, s20
	s_cbranch_scc1 .LU_done
	s_waitcnt lgkmcnt(0)
	v_lshlrev_b32_e32 v208, 2, v248
	buffer_load_dword v252, v208, s[24:27], 0 offen
	buffer_load_dword v253, v208, s[28:31], 0 offen
	buffer_load_dwordx4 v[176:179], v[232:233], s[56:59], 0 idxen offen
	buffer_load_dwordx4 v[180:183], v[234:235], s[56:59], 0 idxen offen
	buffer_load_dwordx4 v[184:187], v[236:237], s[56:59], 0 idxen offen
	buffer_load_dwordx4 v[188:191], v[238:239], s[56:59], 0 idxen offen
	ds_read_b32 v232, v213 offset:64
	ds_read_b32 v234, v213 offset:68
	ds_read_b32 v236, v213 offset:72
	ds_read_b32 v238, v213 offset:76
	s_waitcnt vmcnt(14)
	v_cvt_pk_f32_fp8_e32 v[224:225], v128
	v_cvt_pk_f32_fp8_e32 v[226:227], v132
	v_cvt_pk_f32_fp8_e32 v[228:229], v136
	v_cvt_pk_f32_fp8_e32 v[230:231], v140
	v_pk_mul_f32 v[216:217], v[224:225], v[64:65]
	v_pk_mul_f32 v[218:219], v[226:227], v[64:65]
	v_pk_mul_f32 v[220:221], v[228:229], v[64:65]
	v_pk_mul_f32 v[222:223], v[230:231], v[64:65]
	v_cvt_pk_f32_fp8_sdwa v[224:225], v128 src0_sel:WORD_1
	v_cvt_pk_f32_fp8_sdwa v[226:227], v132 src0_sel:WORD_1
	v_cvt_pk_f32_fp8_sdwa v[228:229], v136 src0_sel:WORD_1
	v_cvt_pk_f32_fp8_sdwa v[230:231], v140 src0_sel:WORD_1
	v_pk_fma_f32 v[216:217], v[224:225], v[66:67], v[216:217]
	v_pk_fma_f32 v[218:219], v[226:227], v[66:67], v[218:219]
	v_pk_fma_f32 v[220:221], v[228:229], v[66:67], v[220:221]
	v_pk_fma_f32 v[222:223], v[230:231], v[66:67], v[222:223]
	v_cvt_pk_f32_fp8_e32 v[224:225], v129
	v_cvt_pk_f32_fp8_e32 v[226:227], v133
	v_cvt_pk_f32_fp8_e32 v[228:229], v137
	v_cvt_pk_f32_fp8_e32 v[230:231], v141
	v_pk_fma_f32 v[216:217], v[224:225], v[68:69], v[216:217]
	v_pk_fma_f32 v[218:219], v[226:227], v[68:69], v[218:219]
	v_pk_fma_f32 v[220:221], v[228:229], v[68:69], v[220:221]
	v_pk_fma_f32 v[222:223], v[230:231], v[68:69], v[222:223]
	v_cvt_pk_f32_fp8_sdwa v[224:225], v129 src0_sel:WORD_1
	v_cvt_pk_f32_fp8_sdwa v[226:227], v133 src0_sel:WORD_1
	v_cvt_pk_f32_fp8_sdwa v[228:229], v137 src0_sel:WORD_1
	v_cvt_pk_f32_fp8_sdwa v[230:231], v141 src0_sel:WORD_1
	v_pk_fma_f32 v[216:217], v[224:225], v[70:71], v[216:217]
	v_pk_fma_f32 v[218:219], v[226:227], v[70:71], v[218:219]
	v_pk_fma_f32 v[220:221], v[228:229], v[70:71], v[220:221]
	v_pk_fma_f32 v[222:223], v[230:231], v[70:71], v[222:223]
	v_cvt_pk_f32_fp8_e32 v[224:225], v130
	v_cvt_pk_f32_fp8_e32 v[226:227], v134
	v_cvt_pk_f32_fp8_e32 v[228:229], v138
	v_cvt_pk_f32_fp8_e32 v[230:231], v142
	v_pk_fma_f32 v[216:217], v[224:225], v[72:73], v[216:217]
	v_pk_fma_f32 v[218:219], v[226:227], v[72:73], v[218:219]
	v_pk_fma_f32 v[220:221], v[228:229], v[72:73], v[220:221]
	v_pk_fma_f32 v[222:223], v[230:231], v[72:73], v[222:223]
	v_cvt_pk_f32_fp8_sdwa v[224:225], v130 src0_sel:WORD_1
	v_cvt_pk_f32_fp8_sdwa v[226:227], v134 src0_sel:WORD_1
	v_cvt_pk_f32_fp8_sdwa v[228:229], v138 src0_sel:WORD_1
	v_cvt_pk_f32_fp8_sdwa v[230:231], v142 src0_sel:WORD_1
	v_pk_fma_f32 v[216:217], v[224:225], v[74:75], v[216:217]
	v_pk_fma_f32 v[218:219], v[226:227], v[74:75], v[218:219]
	v_pk_fma_f32 v[220:221], v[228:229], v[74:75], v[220:221]
	v_pk_fma_f32 v[222:223], v[230:231], v[74:75], v[222:223]
	v_cvt_pk_f32_fp8_e32 v[224:225], v131
	v_cvt_pk_f32_fp8_e32 v[226:227], v135
	v_cvt_pk_f32_fp8_e32 v[228:229], v139
	v_cvt_pk_f32_fp8_e32 v[230:231], v143
	v_pk_fma_f32 v[216:217], v[224:225], v[76:77], v[216:217]
	v_pk_fma_f32 v[218:219], v[226:227], v[76:77], v[218:219]
	v_pk_fma_f32 v[220:221], v[228:229], v[76:77], v[220:221]
	v_pk_fma_f32 v[222:223], v[230:231], v[76:77], v[222:223]
	v_cvt_pk_f32_fp8_sdwa v[224:225], v131 src0_sel:WORD_1
	v_cvt_pk_f32_fp8_sdwa v[226:227], v135 src0_sel:WORD_1
	v_cvt_pk_f32_fp8_sdwa v[228:229], v139 src0_sel:WORD_1
	v_cvt_pk_f32_fp8_sdwa v[230:231], v143 src0_sel:WORD_1
	v_pk_fma_f32 v[216:217], v[224:225], v[78:79], v[216:217]
	v_pk_fma_f32 v[218:219], v[226:227], v[78:79], v[218:219]
	v_pk_fma_f32 v[220:221], v[228:229], v[78:79], v[220:221]
	v_pk_fma_f32 v[222:223], v[230:231], v[78:79], v[222:223]
	v_add_f32_e32 v192, v216, v217
	v_add_f32_e32 v193, v218, v219
	v_add_f32_e32 v194, v220, v221
	v_add_f32_e32 v195, v222, v223
	s_sub_i32 s90, s90, 1
	s_cmp_eq_u32 s90, 0
	s_cbranch_scc1 .LU_sw1
.LU_t4_s1:
	s_waitcnt lgkmcnt(0)
	buffer_load_dwordx4 v[128:131], v[232:233], s[56:59], 0 idxen offen
	buffer_load_dwordx4 v[132:135], v[234:235], s[56:59], 0 idxen offen
	buffer_load_dwordx4 v[136:139], v[236:237], s[56:59], 0 idxen offen
	buffer_load_dwordx4 v[140:143], v[238:239], s[56:59], 0 idxen offen
	ds_read_b32 v232, v213 offset:80
	ds_read_b32 v234, v213 offset:84
	ds_read_b32 v236, v213 offset:88
	ds_read_b32 v238, v213 offset:92
	s_waitcnt vmcnt(14)
	v_cvt_pk_f32_fp8_e32 v[224:225], v144
	v_cvt_pk_f32_fp8_e32 v[226:227], v148
	v_cvt_pk_f32_fp8_e32 v[228:229], v152
	v_cvt_pk_f32_fp8_e32 v[230:231], v156
	v_pk_mul_f32 v[216:217], v[224:225], v[64:65]
	v_pk_mul_f32 v[218:219], v[226:227], v[64:65]
	v_pk_mul_f32 v[220:221], v[228:229], v[64:65]
	v_pk_mul_f32 v[222:223], v[230:231], v[64:65]
	v_cvt_pk_f32_fp8_sdwa v[224:225], v144 src0_sel:WORD_1
	v_cvt_pk_f32_fp8_sdwa v[226:227], v148 src0_sel:WORD_1
	v_cvt_pk_f32_fp8_sdwa v[228:229], v152 src0_sel:WORD_1
	v_cvt_pk_f32_fp8_sdwa v[230:231], v156 src0_sel:WORD_1
	v_pk_fma_f32 v[216:217], v[224:225], v[66:67], v[216:217]
	v_pk_fma_f32 v[218:219], v[226:227], v[66:67], v[218:219]
	v_pk_fma_f32 v[220:221], v[228:229], v[66:67], v[220:221]
	v_pk_fma_f32 v[222:223], v[230:231], v[66:67], v[222:223]
	v_cvt_pk_f32_fp8_e32 v[224:225], v145
	v_cvt_pk_f32_fp8_e32 v[226:227], v149
	v_cvt_pk_f32_fp8_e32 v[228:229], v153
	v_cvt_pk_f32_fp8_e32 v[230:231], v157
	v_pk_fma_f32 v[216:217], v[224:225], v[68:69], v[216:217]
	v_pk_fma_f32 v[218:219], v[226:227], v[68:69], v[218:219]
	v_pk_fma_f32 v[220:221], v[228:229], v[68:69], v[220:221]
	v_pk_fma_f32 v[222:223], v[230:231], v[68:69], v[222:223]
	v_cvt_pk_f32_fp8_sdwa v[224:225], v145 src0_sel:WORD_1
	v_cvt_pk_f32_fp8_sdwa v[226:227], v149 src0_sel:WORD_1
	v_cvt_pk_f32_fp8_sdwa v[228:229], v153 src0_sel:WORD_1
	v_cvt_pk_f32_fp8_sdwa v[230:231], v157 src0_sel:WORD_1
	v_pk_fma_f32 v[216:217], v[224:225], v[70:71], v[216:217]
	v_pk_fma_f32 v[218:219], v[226:227], v[70:71], v[218:219]
	v_pk_fma_f32 v[220:221], v[228:229], v[70:71], v[220:221]
	v_pk_fma_f32 v[222:223], v[230:231], v[70:71], v[222:223]
	v_cvt_pk_f32_fp8_e32 v[224:225], v146
	v_cvt_pk_f32_fp8_e32 v[226:227], v150
	v_cvt_pk_f32_fp8_e32 v[228:229], v154
	v_cvt_pk_f32_fp8_e32 v[230:231], v158
	v_pk_fma_f32 v[216:217], v[224:225], v[72:73], v[216:217]
	v_pk_fma_f32 v[218:219], v[226:227], v[72:73], v[218:219]
	v_pk_fma_f32 v[220:221], v[228:229], v[72:73], v[220:221]
	v_pk_fma_f32 v[222:223], v[230:231], v[72:73], v[222:223]
	v_cvt_pk_f32_fp8_sdwa v[224:225], v146 src0_sel:WORD_1
	v_cvt_pk_f32_fp8_sdwa v[226:227], v150 src0_sel:WORD_1
	v_cvt_pk_f32_fp8_sdwa v[228:229], v154 src0_sel:WORD_1
	v_cvt_pk_f32_fp8_sdwa v[230:231], v158 src0_sel:WORD_1
	v_pk_fma_f32 v[216:217], v[224:225], v[74:75], v[216:217]
	v_pk_fma_f32 v[218:219], v[226:227], v[74:75], v[218:219]
	v_pk_fma_f32 v[220:221], v[228:229], v[74:75], v[220:221]
	v_pk_fma_f32 v[222:223], v[230:231], v[74:75], v[222:223]
	v_cvt_pk_f32_fp8_e32 v[224:225], v147
	v_cvt_pk_f32_fp8_e32 v[226:227], v151
	v_cvt_pk_f32_fp8_e32 v[228:229], v155
	v_cvt_pk_f32_fp8_e32 v[230:231], v159
	v_pk_fma_f32 v[216:217], v[224:225], v[76:77], v[216:217]
	v_pk_fma_f32 v[218:219], v[226:227], v[76:77], v[218:219]
	v_pk_fma_f32 v[220:221], v[228:229], v[76:77], v[220:221]
	v_pk_fma_f32 v[222:223], v[230:231], v[76:77], v[222:223]
	v_cvt_pk_f32_fp8_sdwa v[224:225], v147 src0_sel:WORD_1
	v_cvt_pk_f32_fp8_sdwa v[226:227], v151 src0_sel:WORD_1
	v_cvt_pk_f32_fp8_sdwa v[228:229], v155 src0_sel:WORD_1
	v_cvt_pk_f32_fp8_sdwa v[230:231], v159 src0_sel:WORD_1
	v_pk_fma_f32 v[216:217], v[224:225], v[78:79], v[216:217]
	v_pk_fma_f32 v[218:219], v[226:227], v[78:79], v[218:219]
	v_pk_fma_f32 v[220:221], v[228:229], v[78:79], v[220:221]
	v_pk_fma_f32 v[222:223], v[230:231], v[78:79], v[222:223]
	v_add_f32_e32 v196, v216, v217
	v_add_f32_e32 v197, v218, v219
	v_add_f32_e32 v198, v220, v221
	v_add_f32_e32 v199, v222, v223
	s_sub_i32 s90, s90, 1
	s_cmp_eq_u32 s90, 0
	s_cbranch_scc1 .LU_sw2
.LU_t4_s2:
	s_waitcnt lgkmcnt(0)
	buffer_load_dwordx4 v[144:147], v[232:233], s[56:59], 0 idxen offen
	buffer_load_dwordx4 v[148:151], v[234:235], s[56:59], 0 idxen offen
	buffer_load_dwordx4 v[152:155], v[236:237], s[56:59], 0 idxen offen
	buffer_load_dwordx4 v[156:159], v[238:239], s[56:59], 0 idxen offen
	ds_read_b32 v232, v213 offset:96
	ds_read_b32 v234, v213 offset:100
	ds_read_b32 v236, v213 offset:104
	ds_read_b32 v238, v213 offset:108
	s_waitcnt vmcnt(14)
	v_cvt_pk_f32_fp8_e32 v[224:225], v160
	v_cvt_pk_f32_fp8_e32 v[226:227], v164
	v_cvt_pk_f32_fp8_e32 v[228:229], v168
	v_cvt_pk_f32_fp8_e32 v[230:231], v172
	v_pk_mul_f32 v[216:217], v[224:225], v[64:65]
	v_pk_mul_f32 v[218:219], v[226:227], v[64:65]
	v_pk_mul_f32 v[220:221], v[228:229], v[64:65]
	v_pk_mul_f32 v[222:223], v[230:231], v[64:65]
	v_cvt_pk_f32_fp8_sdwa v[224:225], v160 src0_sel:WORD_1
	v_cvt_pk_f32_fp8_sdwa v[226:227], v164 src0_sel:WORD_1
	v_cvt_pk_f32_fp8_sdwa v[228:229], v168 src0_sel:WORD_1
	v_cvt_pk_f32_fp8_sdwa v[230:231], v172 src0_sel:WORD_1
	v_pk_fma_f32 v[216:217], v[224:225], v[66:67], v[216:217]
	v_pk_fma_f32 v[218:219], v[226:227], v[66:67], v[218:219]
	v_pk_fma_f32 v[220:221], v[228:229], v[66:67], v[220:221]
	v_pk_fma_f32 v[222:223], v[230:231], v[66:67], v[222:223]
	v_cvt_pk_f32_fp8_e32 v[224:225], v161
	v_cvt_pk_f32_fp8_e32 v[226:227], v165
	v_cvt_pk_f32_fp8_e32 v[228:229], v169
	v_cvt_pk_f32_fp8_e32 v[230:231], v173
	v_pk_fma_f32 v[216:217], v[224:225], v[68:69], v[216:217]
	v_pk_fma_f32 v[218:219], v[226:227], v[68:69], v[218:219]
	v_pk_fma_f32 v[220:221], v[228:229], v[68:69], v[220:221]
	v_pk_fma_f32 v[222:223], v[230:231], v[68:69], v[222:223]
	v_cvt_pk_f32_fp8_sdwa v[224:225], v161 src0_sel:WORD_1
	v_cvt_pk_f32_fp8_sdwa v[226:227], v165 src0_sel:WORD_1
	v_cvt_pk_f32_fp8_sdwa v[228:229], v169 src0_sel:WORD_1
	v_cvt_pk_f32_fp8_sdwa v[230:231], v173 src0_sel:WORD_1
	v_pk_fma_f32 v[216:217], v[224:225], v[70:71], v[216:217]
	v_pk_fma_f32 v[218:219], v[226:227], v[70:71], v[218:219]
	v_pk_fma_f32 v[220:221], v[228:229], v[70:71], v[220:221]
	v_pk_fma_f32 v[222:223], v[230:231], v[70:71], v[222:223]
	v_cvt_pk_f32_fp8_e32 v[224:225], v162
	v_cvt_pk_f32_fp8_e32 v[226:227], v166
	v_cvt_pk_f32_fp8_e32 v[228:229], v170
	v_cvt_pk_f32_fp8_e32 v[230:231], v174
	v_pk_fma_f32 v[216:217], v[224:225], v[72:73], v[216:217]
	v_pk_fma_f32 v[218:219], v[226:227], v[72:73], v[218:219]
	v_pk_fma_f32 v[220:221], v[228:229], v[72:73], v[220:221]
	v_pk_fma_f32 v[222:223], v[230:231], v[72:73], v[222:223]
	v_cvt_pk_f32_fp8_sdwa v[224:225], v162 src0_sel:WORD_1
	v_cvt_pk_f32_fp8_sdwa v[226:227], v166 src0_sel:WORD_1
	v_cvt_pk_f32_fp8_sdwa v[228:229], v170 src0_sel:WORD_1
	v_cvt_pk_f32_fp8_sdwa v[230:231], v174 src0_sel:WORD_1
	v_pk_fma_f32 v[216:217], v[224:225], v[74:75], v[216:217]
	v_pk_fma_f32 v[218:219], v[226:227], v[74:75], v[218:219]
	v_pk_fma_f32 v[220:221], v[228:229], v[74:75], v[220:221]
	v_pk_fma_f32 v[222:223], v[230:231], v[74:75], v[222:223]
	v_cvt_pk_f32_fp8_e32 v[224:225], v163
	v_cvt_pk_f32_fp8_e32 v[226:227], v167
	v_cvt_pk_f32_fp8_e32 v[228:229], v171
	v_cvt_pk_f32_fp8_e32 v[230:231], v175
	v_pk_fma_f32 v[216:217], v[224:225], v[76:77], v[216:217]
	v_pk_fma_f32 v[218:219], v[226:227], v[76:77], v[218:219]
	v_pk_fma_f32 v[220:221], v[228:229], v[76:77], v[220:221]
	v_pk_fma_f32 v[222:223], v[230:231], v[76:77], v[222:223]
	v_cvt_pk_f32_fp8_sdwa v[224:225], v163 src0_sel:WORD_1
	v_cvt_pk_f32_fp8_sdwa v[226:227], v167 src0_sel:WORD_1
	v_cvt_pk_f32_fp8_sdwa v[228:229], v171 src0_sel:WORD_1
	v_cvt_pk_f32_fp8_sdwa v[230:231], v175 src0_sel:WORD_1
	v_pk_fma_f32 v[216:217], v[224:225], v[78:79], v[216:217]
	v_pk_fma_f32 v[218:219], v[226:227], v[78:79], v[218:219]
	v_pk_fma_f32 v[220:221], v[228:229], v[78:79], v[220:221]
	v_pk_fma_f32 v[222:223], v[230:231], v[78:79], v[222:223]
	v_add_f32_e32 v200, v216, v217
	v_add_f32_e32 v201, v218, v219
	v_add_f32_e32 v202, v220, v221
	v_add_f32_e32 v203, v222, v223
	s_sub_i32 s90, s90, 1
	s_cmp_eq_u32 s90, 0
	s_cbranch_scc1 .LU_sw3
.LU_t4_s3:
	s_waitcnt lgkmcnt(0)
	buffer_load_dwordx4 v[160:163], v[232:233], s[56:59], 0 idxen offen
	buffer_load_dwordx4 v[164:167], v[234:235], s[56:59], 0 idxen offen
	buffer_load_dwordx4 v[168:171], v[236:237], s[56:59], 0 idxen offen
	buffer_load_dwordx4 v[172:175], v[238:239], s[56:59], 0 idxen offen
	ds_read_b32 v232, v213 offset:112
	ds_read_b32 v234, v213 offset:116
	ds_read_b32 v236, v213 offset:120
	ds_read_b32 v238, v213 offset:124
	s_waitcnt vmcnt(12)
	v_cvt_pk_f32_fp8_e32 v[224:225], v176
	v_cvt_pk_f32_fp8_e32 v[226:227], v180
	v_cvt_pk_f32_fp8_e32 v[228:229], v184
	v_cvt_pk_f32_fp8_e32 v[230:231], v188
	v_pk_mul_f32 v[216:217], v[224:225], v[64:65]
	v_pk_mul_f32 v[218:219], v[226:227], v[64:65]
	v_pk_mul_f32 v[220:221], v[228:229], v[64:65]
	v_pk_mul_f32 v[222:223], v[230:231], v[64:65]
	v_cvt_pk_f32_fp8_sdwa v[224:225], v176 src0_sel:WORD_1
	v_cvt_pk_f32_fp8_sdwa v[226:227], v180 src0_sel:WORD_1
	v_cvt_pk_f32_fp8_sdwa v[228:229], v184 src0_sel:WORD_1
	v_cvt_pk_f32_fp8_sdwa v[230:231], v188 src0_sel:WORD_1
	v_pk_fma_f32 v[216:217], v[224:225], v[66:67], v[216:217]
	v_pk_fma_f32 v[218:219], v[226:227], v[66:67], v[218:219]
	v_pk_fma_f32 v[220:221], v[228:229], v[66:67], v[220:221]
	v_pk_fma_f32 v[222:223], v[230:231], v[66:67], v[222:223]
	v_cvt_pk_f32_fp8_e32 v[224:225], v177
	v_cvt_pk_f32_fp8_e32 v[226:227], v181
	v_cvt_pk_f32_fp8_e32 v[228:229], v185
	v_cvt_pk_f32_fp8_e32 v[230:231], v189
	v_pk_fma_f32 v[216:217], v[224:225], v[68:69], v[216:217]
	v_pk_fma_f32 v[218:219], v[226:227], v[68:69], v[218:219]
	v_pk_fma_f32 v[220:221], v[228:229], v[68:69], v[220:221]
	v_pk_fma_f32 v[222:223], v[230:231], v[68:69], v[222:223]
	v_cvt_pk_f32_fp8_sdwa v[224:225], v177 src0_sel:WORD_1
	v_cvt_pk_f32_fp8_sdwa v[226:227], v181 src0_sel:WORD_1
	v_cvt_pk_f32_fp8_sdwa v[228:229], v185 src0_sel:WORD_1
	v_cvt_pk_f32_fp8_sdwa v[230:231], v189 src0_sel:WORD_1
	v_pk_fma_f32 v[216:217], v[224:225], v[70:71], v[216:217]
	v_pk_fma_f32 v[218:219], v[226:227], v[70:71], v[218:219]
	v_pk_fma_f32 v[220:221], v[228:229], v[70:71], v[220:221]
	v_pk_fma_f32 v[222:223], v[230:231], v[70:71], v[222:223]
	v_cvt_pk_f32_fp8_e32 v[224:225], v178
	v_cvt_pk_f32_fp8_e32 v[226:227], v182
	v_cvt_pk_f32_fp8_e32 v[228:229], v186
	v_cvt_pk_f32_fp8_e32 v[230:231], v190
	v_pk_fma_f32 v[216:217], v[224:225], v[72:73], v[216:217]
	v_pk_fma_f32 v[218:219], v[226:227], v[72:73], v[218:219]
	v_pk_fma_f32 v[220:221], v[228:229], v[72:73], v[220:221]
	v_pk_fma_f32 v[222:223], v[230:231], v[72:73], v[222:223]
	v_cvt_pk_f32_fp8_sdwa v[224:225], v178 src0_sel:WORD_1
	v_cvt_pk_f32_fp8_sdwa v[226:227], v182 src0_sel:WORD_1
	v_cvt_pk_f32_fp8_sdwa v[228:229], v186 src0_sel:WORD_1
	v_cvt_pk_f32_fp8_sdwa v[230:231], v190 src0_sel:WORD_1
	v_pk_fma_f32 v[216:217], v[224:225], v[74:75], v[216:217]
	v_pk_fma_f32 v[218:219], v[226:227], v[74:75], v[218:219]
	v_pk_fma_f32 v[220:221], v[228:229], v[74:75], v[220:221]
	v_pk_fma_f32 v[222:223], v[230:231], v[74:75], v[222:223]
	v_cvt_pk_f32_fp8_e32 v[224:225], v179
	v_cvt_pk_f32_fp8_e32 v[226:227], v183
	v_cvt_pk_f32_fp8_e32 v[228:229], v187
	v_cvt_pk_f32_fp8_e32 v[230:231], v191
	v_pk_fma_f32 v[216:217], v[224:225], v[76:77], v[216:217]
	v_pk_fma_f32 v[218:219], v[226:227], v[76:77], v[218:219]
	v_pk_fma_f32 v[220:221], v[228:229], v[76:77], v[220:221]
	v_pk_fma_f32 v[222:223], v[230:231], v[76:77], v[222:223]
	v_cvt_pk_f32_fp8_sdwa v[224:225], v179 src0_sel:WORD_1
	v_cvt_pk_f32_fp8_sdwa v[226:227], v183 src0_sel:WORD_1
	v_cvt_pk_f32_fp8_sdwa v[228:229], v187 src0_sel:WORD_1
	v_cvt_pk_f32_fp8_sdwa v[230:231], v191 src0_sel:WORD_1
	v_pk_fma_f32 v[216:217], v[224:225], v[78:79], v[216:217]
	v_pk_fma_f32 v[218:219], v[226:227], v[78:79], v[218:219]
	v_pk_fma_f32 v[220:221], v[228:229], v[78:79], v[220:221]
	v_pk_fma_f32 v[222:223], v[230:231], v[78:79], v[222:223]
	v_add_f32_e32 v204, v216, v217
	v_add_f32_e32 v205, v218, v219
	v_add_f32_e32 v206, v220, v221
	v_add_f32_e32 v207, v222, v223
	s_nop 0
	v_permlane32_swap_b32_e32 v192, v200
	v_permlane32_swap_b32_e32 v193, v201
	v_permlane32_swap_b32_e32 v194, v202
	v_permlane32_swap_b32_e32 v195, v203
	v_permlane32_swap_b32_e32 v196, v204
	v_permlane32_swap_b32_e32 v197, v205
	v_permlane32_swap_b32_e32 v198, v206
	v_permlane32_swap_b32_e32 v199, v207
	v_add_f32_e32 v192, v192, v200
	v_add_f32_e32 v193, v193, v201
	v_add_f32_e32 v194, v194, v202
	v_add_f32_e32 v195, v195, v203
	v_add_f32_e32 v196, v196, v204
	v_add_f32_e32 v197, v197, v205
	v_add_f32_e32 v198, v198, v206
	v_add_f32_e32 v199, v199, v207
	v_permlane16_swap_b32_e32 v192, v196
	v_permlane16_swap_b32_e32 v193, v197
	v_permlane16_swap_b32_e32 v194, v198
	v_permlane16_swap_b32_e32 v195, v199
	v_add_f32_e32 v192, v192, v196
	v_add_f32_e32 v193, v193, v197
	v_add_f32_e32 v194, v194, v198
	v_add_f32_e32 v195, v195, v199
	v_add_f32_dpp v216, v192, v192 row_ror:8 row_mask:0xf bank_mask:0xf
	v_add_f32_dpp v218, v194, v194 row_ror:8 row_mask:0xf bank_mask:0xf
	v_add_f32_dpp v216, v193, v193 row_ror:8 row_mask:0xf bank_mask:0xc
	v_add_f32_dpp v218, v195, v195 row_ror:8 row_mask:0xf bank_mask:0xc
	s_nop 1
	v_add_f32_dpp v220, v216, v216 row_half_mirror row_mask:0xf bank_mask:0xf
	v_add_f32_dpp v220, v218, v218 row_half_mirror row_mask:0xf bank_mask:0xa
	s_nop 1
	v_add_f32_dpp v220, v220, v220 quad_perm:[1,0,3,2] row_mask:0xf bank_mask:0xf
	s_nop 1
	v_add_f32_dpp v220, v220, v220 quad_perm:[2,3,0,1] row_mask:0xf bank_mask:0xf
	v_mul_f32_e32 v216, v252, v220
	v_fma_f32 v218, |v216|, s72, 1.0
	v_mul_f32_e32 v222, v216, v216
	v_rcp_f32_e32 v218, v218
	v_mul_f32_e32 v222, 0xbf38aa3b, v222
	v_exp_f32_e32 v222, v222
	v_fmamk_f32 v224, v218, 0x3f07dc22, v242
	v_fmaak_f32 v224, v218, v224, 0x3f35f0e3
	v_fmaak_f32 v224, v218, v224, 0xbe11a98e
	v_fmaak_f32 v224, v218, v224, 0x3e027906
	v_mul_f32_e32 v224, v218, v224
	v_mul_f32_e32 v224, v222, v224
	v_mul_f32_e32 v226, v216, v224
	v_fma_f32 v224, -v216, v224, v216
	v_cmp_gt_f32_e32 vcc, 0, v216
	s_nop 1
	v_cndmask_b32_e32 v224, v224, v226, vcc
	v_mul_f32_e32 v224, v249, v224
	v_mul_f32_e32 v224, v253, v224
	ds_write_b32 v211, v224 offset:4992
	v_add_u32_e32 v211, 64, v211
	v_add_u32_e32 v213, 64, v213
	ds_read_b32 v248, v211
	ds_read_b32 v249, v211 offset:4992
	s_add_i32 s21, s21, 4
	s_sub_i32 s90, s90, 1
	s_cmp_eq_u32 s90, 0
	s_cbranch_scc1 .LU_sw0
	s_branch .LU_t4_s0
.LU_t5_s0:
	s_cmp_ge_u32 s21, s20
	s_cbranch_scc1 .LU_done
	s_waitcnt lgkmcnt(0)
	v_lshlrev_b32_e32 v208, 2, v248
	buffer_load_dword v252, v208, s[24:27], 0 offen
	buffer_load_dword v253, v208, s[28:31], 0 offen
	buffer_load_dwordx4 v[176:179], v[232:233], s[56:59], 0 idxen offen
	buffer_load_dwordx4 v[180:183], v[234:235], s[56:59], 0 idxen offen
	buffer_load_dwordx4 v[184:187], v[236:237], s[56:59], 0 idxen offen
	buffer_load_dwordx4 v[188:191], v[238:239], s[56:59], 0 idxen offen
	ds_read_b32 v232, v213 offset:64
	ds_read_b32 v234, v213 offset:68
	ds_read_b32 v236, v213 offset:72
	ds_read_b32 v238, v213 offset:76
	s_waitcnt vmcnt(14)
	v_cvt_pk_f32_fp8_e32 v[224:225], v128
	v_cvt_pk_f32_fp8_e32 v[226:227], v132
	v_cvt_pk_f32_fp8_e32 v[228:229], v136
	v_cvt_pk_f32_fp8_e32 v[230:231], v140
	v_pk_mul_f32 v[216:217], v[224:225], v[80:81]
	v_pk_mul_f32 v[218:219], v[226:227], v[80:81]
	v_pk_mul_f32 v[220:221], v[228:229], v[80:81]
	v_pk_mul_f32 v[222:223], v[230:231], v[80:81]
	v_cvt_pk_f32_fp8_sdwa v[224:225], v128 src0_sel:WORD_1
	v_cvt_pk_f32_fp8_sdwa v[226:227], v132 src0_sel:WORD_1
	v_cvt_pk_f32_fp8_sdwa v[228:229], v136 src0_sel:WORD_1
	v_cvt_pk_f32_fp8_sdwa v[230:231], v140 src0_sel:WORD_1
	v_pk_fma_f32 v[216:217], v[224:225], v[82:83], v[216:217]
	v_pk_fma_f32 v[218:219], v[226:227], v[82:83], v[218:219]
	v_pk_fma_f32 v[220:221], v[228:229], v[82:83], v[220:221]
	v_pk_fma_f32 v[222:223], v[230:231], v[82:83], v[222:223]
	v_cvt_pk_f32_fp8_e32 v[224:225], v129
	v_cvt_pk_f32_fp8_e32 v[226:227], v133
	v_cvt_pk_f32_fp8_e32 v[228:229], v137
	v_cvt_pk_f32_fp8_e32 v[230:231], v141
	v_pk_fma_f32 v[216:217], v[224:225], v[84:85], v[216:217]
	v_pk_fma_f32 v[218:219], v[226:227], v[84:85], v[218:219]
	v_pk_fma_f32 v[220:221], v[228:229], v[84:85], v[220:221]
	v_pk_fma_f32 v[222:223], v[230:231], v[84:85], v[222:223]
	v_cvt_pk_f32_fp8_sdwa v[224:225], v129 src0_sel:WORD_1
	v_cvt_pk_f32_fp8_sdwa v[226:227], v133 src0_sel:WORD_1
	v_cvt_pk_f32_fp8_sdwa v[228:229], v137 src0_sel:WORD_1
	v_cvt_pk_f32_fp8_sdwa v[230:231], v141 src0_sel:WORD_1
	v_pk_fma_f32 v[216:217], v[224:225], v[86:87], v[216:217]
	v_pk_fma_f32 v[218:219], v[226:227], v[86:87], v[218:219]
	v_pk_fma_f32 v[220:221], v[228:229], v[86:87], v[220:221]
	v_pk_fma_f32 v[222:223], v[230:231], v[86:87], v[222:223]
	v_cvt_pk_f32_fp8_e32 v[224:225], v130
	v_cvt_pk_f32_fp8_e32 v[226:227], v134
	v_cvt_pk_f32_fp8_e32 v[228:229], v138
	v_cvt_pk_f32_fp8_e32 v[230:231], v142
	v_pk_fma_f32 v[216:217], v[224:225], v[88:89], v[216:217]
	v_pk_fma_f32 v[218:219], v[226:227], v[88:89], v[218:219]
	v_pk_fma_f32 v[220:221], v[228:229], v[88:89], v[220:221]
	v_pk_fma_f32 v[222:223], v[230:231], v[88:89], v[222:223]
	v_cvt_pk_f32_fp8_sdwa v[224:225], v130 src0_sel:WORD_1
	v_cvt_pk_f32_fp8_sdwa v[226:227], v134 src0_sel:WORD_1
	v_cvt_pk_f32_fp8_sdwa v[228:229], v138 src0_sel:WORD_1
	v_cvt_pk_f32_fp8_sdwa v[230:231], v142 src0_sel:WORD_1
	v_pk_fma_f32 v[216:217], v[224:225], v[90:91], v[216:217]
	v_pk_fma_f32 v[218:219], v[226:227], v[90:91], v[218:219]
	v_pk_fma_f32 v[220:221], v[228:229], v[90:91], v[220:221]
	v_pk_fma_f32 v[222:223], v[230:231], v[90:91], v[222:223]
	v_cvt_pk_f32_fp8_e32 v[224:225], v131
	v_cvt_pk_f32_fp8_e32 v[226:227], v135
	v_cvt_pk_f32_fp8_e32 v[228:229], v139
	v_cvt_pk_f32_fp8_e32 v[230:231], v143
	v_pk_fma_f32 v[216:217], v[224:225], v[92:93], v[216:217]
	v_pk_fma_f32 v[218:219], v[226:227], v[92:93], v[218:219]
	v_pk_fma_f32 v[220:221], v[228:229], v[92:93], v[220:221]
	v_pk_fma_f32 v[222:223], v[230:231], v[92:93], v[222:223]
	v_cvt_pk_f32_fp8_sdwa v[224:225], v131 src0_sel:WORD_1
	v_cvt_pk_f32_fp8_sdwa v[226:227], v135 src0_sel:WORD_1
	v_cvt_pk_f32_fp8_sdwa v[228:229], v139 src0_sel:WORD_1
	v_cvt_pk_f32_fp8_sdwa v[230:231], v143 src0_sel:WORD_1
	v_pk_fma_f32 v[216:217], v[224:225], v[94:95], v[216:217]
	v_pk_fma_f32 v[218:219], v[226:227], v[94:95], v[218:219]
	v_pk_fma_f32 v[220:221], v[228:229], v[94:95], v[220:221]
	v_pk_fma_f32 v[222:223], v[230:231], v[94:95], v[222:223]
	v_add_f32_e32 v192, v216, v217
	v_add_f32_e32 v193, v218, v219
	v_add_f32_e32 v194, v220, v221
	v_add_f32_e32 v195, v222, v223
	s_sub_i32 s90, s90, 1
	s_cmp_eq_u32 s90, 0
	s_cbranch_scc1 .LU_sw1
.LU_t5_s1:
	s_waitcnt lgkmcnt(0)
	buffer_load_dwordx4 v[128:131], v[232:233], s[56:59], 0 idxen offen
	buffer_load_dwordx4 v[132:135], v[234:235], s[56:59], 0 idxen offen
	buffer_load_dwordx4 v[136:139], v[236:237], s[56:59], 0 idxen offen
	buffer_load_dwordx4 v[140:143], v[238:239], s[56:59], 0 idxen offen
	ds_read_b32 v232, v213 offset:80
	ds_read_b32 v234, v213 offset:84
	ds_read_b32 v236, v213 offset:88
	ds_read_b32 v238, v213 offset:92
	s_waitcnt vmcnt(14)
	v_cvt_pk_f32_fp8_e32 v[224:225], v144
	v_cvt_pk_f32_fp8_e32 v[226:227], v148
	v_cvt_pk_f32_fp8_e32 v[228:229], v152
	v_cvt_pk_f32_fp8_e32 v[230:231], v156
	v_pk_mul_f32 v[216:217], v[224:225], v[80:81]
	v_pk_mul_f32 v[218:219], v[226:227], v[80:81]
	v_pk_mul_f32 v[220:221], v[228:229], v[80:81]
	v_pk_mul_f32 v[222:223], v[230:231], v[80:81]
	v_cvt_pk_f32_fp8_sdwa v[224:225], v144 src0_sel:WORD_1
	v_cvt_pk_f32_fp8_sdwa v[226:227], v148 src0_sel:WORD_1
	v_cvt_pk_f32_fp8_sdwa v[228:229], v152 src0_sel:WORD_1
	v_cvt_pk_f32_fp8_sdwa v[230:231], v156 src0_sel:WORD_1
	v_pk_fma_f32 v[216:217], v[224:225], v[82:83], v[216:217]
	v_pk_fma_f32 v[218:219], v[226:227], v[82:83], v[218:219]
	v_pk_fma_f32 v[220:221], v[228:229], v[82:83], v[220:221]
	v_pk_fma_f32 v[222:223], v[230:231], v[82:83], v[222:223]
	v_cvt_pk_f32_fp8_e32 v[224:225], v145
	v_cvt_pk_f32_fp8_e32 v[226:227], v149
	v_cvt_pk_f32_fp8_e32 v[228:229], v153
	v_cvt_pk_f32_fp8_e32 v[230:231], v157
	v_pk_fma_f32 v[216:217], v[224:225], v[84:85], v[216:217]
	v_pk_fma_f32 v[218:219], v[226:227], v[84:85], v[218:219]
	v_pk_fma_f32 v[220:221], v[228:229], v[84:85], v[220:221]
	v_pk_fma_f32 v[222:223], v[230:231], v[84:85], v[222:223]
	v_cvt_pk_f32_fp8_sdwa v[224:225], v145 src0_sel:WORD_1
	v_cvt_pk_f32_fp8_sdwa v[226:227], v149 src0_sel:WORD_1
	v_cvt_pk_f32_fp8_sdwa v[228:229], v153 src0_sel:WORD_1
	v_cvt_pk_f32_fp8_sdwa v[230:231], v157 src0_sel:WORD_1
	v_pk_fma_f32 v[216:217], v[224:225], v[86:87], v[216:217]
	v_pk_fma_f32 v[218:219], v[226:227], v[86:87], v[218:219]
	v_pk_fma_f32 v[220:221], v[228:229], v[86:87], v[220:221]
	v_pk_fma_f32 v[222:223], v[230:231], v[86:87], v[222:223]
	v_cvt_pk_f32_fp8_e32 v[224:225], v146
	v_cvt_pk_f32_fp8_e32 v[226:227], v150
	v_cvt_pk_f32_fp8_e32 v[228:229], v154
	v_cvt_pk_f32_fp8_e32 v[230:231], v158
	v_pk_fma_f32 v[216:217], v[224:225], v[88:89], v[216:217]
	v_pk_fma_f32 v[218:219], v[226:227], v[88:89], v[218:219]
	v_pk_fma_f32 v[220:221], v[228:229], v[88:89], v[220:221]
	v_pk_fma_f32 v[222:223], v[230:231], v[88:89], v[222:223]
	v_cvt_pk_f32_fp8_sdwa v[224:225], v146 src0_sel:WORD_1
	v_cvt_pk_f32_fp8_sdwa v[226:227], v150 src0_sel:WORD_1
	v_cvt_pk_f32_fp8_sdwa v[228:229], v154 src0_sel:WORD_1
	v_cvt_pk_f32_fp8_sdwa v[230:231], v158 src0_sel:WORD_1
	v_pk_fma_f32 v[216:217], v[224:225], v[90:91], v[216:217]
	v_pk_fma_f32 v[218:219], v[226:227], v[90:91], v[218:219]
	v_pk_fma_f32 v[220:221], v[228:229], v[90:91], v[220:221]
	v_pk_fma_f32 v[222:223], v[230:231], v[90:91], v[222:223]
	v_cvt_pk_f32_fp8_e32 v[224:225], v147
	v_cvt_pk_f32_fp8_e32 v[226:227], v151
	v_cvt_pk_f32_fp8_e32 v[228:229], v155
	v_cvt_pk_f32_fp8_e32 v[230:231], v159
	v_pk_fma_f32 v[216:217], v[224:225], v[92:93], v[216:217]
	v_pk_fma_f32 v[218:219], v[226:227], v[92:93], v[218:219]
	v_pk_fma_f32 v[220:221], v[228:229], v[92:93], v[220:221]
	v_pk_fma_f32 v[222:223], v[230:231], v[92:93], v[222:223]
	v_cvt_pk_f32_fp8_sdwa v[224:225], v147 src0_sel:WORD_1
	v_cvt_pk_f32_fp8_sdwa v[226:227], v151 src0_sel:WORD_1
	v_cvt_pk_f32_fp8_sdwa v[228:229], v155 src0_sel:WORD_1
	v_cvt_pk_f32_fp8_sdwa v[230:231], v159 src0_sel:WORD_1
	v_pk_fma_f32 v[216:217], v[224:225], v[94:95], v[216:217]
	v_pk_fma_f32 v[218:219], v[226:227], v[94:95], v[218:219]
	v_pk_fma_f32 v[220:221], v[228:229], v[94:95], v[220:221]
	v_pk_fma_f32 v[222:223], v[230:231], v[94:95], v[222:223]
	v_add_f32_e32 v196, v216, v217
	v_add_f32_e32 v197, v218, v219
	v_add_f32_e32 v198, v220, v221
	v_add_f32_e32 v199, v222, v223
	s_sub_i32 s90, s90, 1
	s_cmp_eq_u32 s90, 0
	s_cbranch_scc1 .LU_sw2
.LU_t5_s2:
	s_waitcnt lgkmcnt(0)
	buffer_load_dwordx4 v[144:147], v[232:233], s[56:59], 0 idxen offen
	buffer_load_dwordx4 v[148:151], v[234:235], s[56:59], 0 idxen offen
	buffer_load_dwordx4 v[152:155], v[236:237], s[56:59], 0 idxen offen
	buffer_load_dwordx4 v[156:159], v[238:239], s[56:59], 0 idxen offen
	ds_read_b32 v232, v213 offset:96
	ds_read_b32 v234, v213 offset:100
	ds_read_b32 v236, v213 offset:104
	ds_read_b32 v238, v213 offset:108
	s_waitcnt vmcnt(14)
	v_cvt_pk_f32_fp8_e32 v[224:225], v160
	v_cvt_pk_f32_fp8_e32 v[226:227], v164
	v_cvt_pk_f32_fp8_e32 v[228:229], v168
	v_cvt_pk_f32_fp8_e32 v[230:231], v172
	v_pk_mul_f32 v[216:217], v[224:225], v[80:81]
	v_pk_mul_f32 v[218:219], v[226:227], v[80:81]
	v_pk_mul_f32 v[220:221], v[228:229], v[80:81]
	v_pk_mul_f32 v[222:223], v[230:231], v[80:81]
	v_cvt_pk_f32_fp8_sdwa v[224:225], v160 src0_sel:WORD_1
	v_cvt_pk_f32_fp8_sdwa v[226:227], v164 src0_sel:WORD_1
	v_cvt_pk_f32_fp8_sdwa v[228:229], v168 src0_sel:WORD_1
	v_cvt_pk_f32_fp8_sdwa v[230:231], v172 src0_sel:WORD_1
	v_pk_fma_f32 v[216:217], v[224:225], v[82:83], v[216:217]
	v_pk_fma_f32 v[218:219], v[226:227], v[82:83], v[218:219]
	v_pk_fma_f32 v[220:221], v[228:229], v[82:83], v[220:221]
	v_pk_fma_f32 v[222:223], v[230:231], v[82:83], v[222:223]
	v_cvt_pk_f32_fp8_e32 v[224:225], v161
	v_cvt_pk_f32_fp8_e32 v[226:227], v165
	v_cvt_pk_f32_fp8_e32 v[228:229], v169
	v_cvt_pk_f32_fp8_e32 v[230:231], v173
	v_pk_fma_f32 v[216:217], v[224:225], v[84:85], v[216:217]
	v_pk_fma_f32 v[218:219], v[226:227], v[84:85], v[218:219]
	v_pk_fma_f32 v[220:221], v[228:229], v[84:85], v[220:221]
	v_pk_fma_f32 v[222:223], v[230:231], v[84:85], v[222:223]
	v_cvt_pk_f32_fp8_sdwa v[224:225], v161 src0_sel:WORD_1
	v_cvt_pk_f32_fp8_sdwa v[226:227], v165 src0_sel:WORD_1
	v_cvt_pk_f32_fp8_sdwa v[228:229], v169 src0_sel:WORD_1
	v_cvt_pk_f32_fp8_sdwa v[230:231], v173 src0_sel:WORD_1
	v_pk_fma_f32 v[216:217], v[224:225], v[86:87], v[216:217]
	v_pk_fma_f32 v[218:219], v[226:227], v[86:87], v[218:219]
	v_pk_fma_f32 v[220:221], v[228:229], v[86:87], v[220:221]
	v_pk_fma_f32 v[222:223], v[230:231], v[86:87], v[222:223]
	v_cvt_pk_f32_fp8_e32 v[224:225], v162
	v_cvt_pk_f32_fp8_e32 v[226:227], v166
	v_cvt_pk_f32_fp8_e32 v[228:229], v170
	v_cvt_pk_f32_fp8_e32 v[230:231], v174
	v_pk_fma_f32 v[216:217], v[224:225], v[88:89], v[216:217]
	v_pk_fma_f32 v[218:219], v[226:227], v[88:89], v[218:219]
	v_pk_fma_f32 v[220:221], v[228:229], v[88:89], v[220:221]
	v_pk_fma_f32 v[222:223], v[230:231], v[88:89], v[222:223]
	v_cvt_pk_f32_fp8_sdwa v[224:225], v162 src0_sel:WORD_1
	v_cvt_pk_f32_fp8_sdwa v[226:227], v166 src0_sel:WORD_1
	v_cvt_pk_f32_fp8_sdwa v[228:229], v170 src0_sel:WORD_1
	v_cvt_pk_f32_fp8_sdwa v[230:231], v174 src0_sel:WORD_1
	v_pk_fma_f32 v[216:217], v[224:225], v[90:91], v[216:217]
	v_pk_fma_f32 v[218:219], v[226:227], v[90:91], v[218:219]
	v_pk_fma_f32 v[220:221], v[228:229], v[90:91], v[220:221]
	v_pk_fma_f32 v[222:223], v[230:231], v[90:91], v[222:223]
	v_cvt_pk_f32_fp8_e32 v[224:225], v163
	v_cvt_pk_f32_fp8_e32 v[226:227], v167
	v_cvt_pk_f32_fp8_e32 v[228:229], v171
	v_cvt_pk_f32_fp8_e32 v[230:231], v175
	v_pk_fma_f32 v[216:217], v[224:225], v[92:93], v[216:217]
	v_pk_fma_f32 v[218:219], v[226:227], v[92:93], v[218:219]
	v_pk_fma_f32 v[220:221], v[228:229], v[92:93], v[220:221]
	v_pk_fma_f32 v[222:223], v[230:231], v[92:93], v[222:223]
	v_cvt_pk_f32_fp8_sdwa v[224:225], v163 src0_sel:WORD_1
	v_cvt_pk_f32_fp8_sdwa v[226:227], v167 src0_sel:WORD_1
	v_cvt_pk_f32_fp8_sdwa v[228:229], v171 src0_sel:WORD_1
	v_cvt_pk_f32_fp8_sdwa v[230:231], v175 src0_sel:WORD_1
	v_pk_fma_f32 v[216:217], v[224:225], v[94:95], v[216:217]
	v_pk_fma_f32 v[218:219], v[226:227], v[94:95], v[218:219]
	v_pk_fma_f32 v[220:221], v[228:229], v[94:95], v[220:221]
	v_pk_fma_f32 v[222:223], v[230:231], v[94:95], v[222:223]
	v_add_f32_e32 v200, v216, v217
	v_add_f32_e32 v201, v218, v219
	v_add_f32_e32 v202, v220, v221
	v_add_f32_e32 v203, v222, v223
	s_sub_i32 s90, s90, 1
	s_cmp_eq_u32 s90, 0
	s_cbranch_scc1 .LU_sw3
.LU_t5_s3:
	s_waitcnt lgkmcnt(0)
	buffer_load_dwordx4 v[160:163], v[232:233], s[56:59], 0 idxen offen
	buffer_load_dwordx4 v[164:167], v[234:235], s[56:59], 0 idxen offen
	buffer_load_dwordx4 v[168:171], v[236:237], s[56:59], 0 idxen offen
	buffer_load_dwordx4 v[172:175], v[238:239], s[56:59], 0 idxen offen
	ds_read_b32 v232, v213 offset:112
	ds_read_b32 v234, v213 offset:116
	ds_read_b32 v236, v213 offset:120
	ds_read_b32 v238, v213 offset:124
	s_waitcnt vmcnt(12)
	v_cvt_pk_f32_fp8_e32 v[224:225], v176
	v_cvt_pk_f32_fp8_e32 v[226:227], v180
	v_cvt_pk_f32_fp8_e32 v[228:229], v184
	v_cvt_pk_f32_fp8_e32 v[230:231], v188
	v_pk_mul_f32 v[216:217], v[224:225], v[80:81]
	v_pk_mul_f32 v[218:219], v[226:227], v[80:81]
	v_pk_mul_f32 v[220:221], v[228:229], v[80:81]
	v_pk_mul_f32 v[222:223], v[230:231], v[80:81]
	v_cvt_pk_f32_fp8_sdwa v[224:225], v176 src0_sel:WORD_1
	v_cvt_pk_f32_fp8_sdwa v[226:227], v180 src0_sel:WORD_1
	v_cvt_pk_f32_fp8_sdwa v[228:229], v184 src0_sel:WORD_1
	v_cvt_pk_f32_fp8_sdwa v[230:231], v188 src0_sel:WORD_1
	v_pk_fma_f32 v[216:217], v[224:225], v[82:83], v[216:217]
	v_pk_fma_f32 v[218:219], v[226:227], v[82:83], v[218:219]
	v_pk_fma_f32 v[220:221], v[228:229], v[82:83], v[220:221]
	v_pk_fma_f32 v[222:223], v[230:231], v[82:83], v[222:223]
	v_cvt_pk_f32_fp8_e32 v[224:225], v177
	v_cvt_pk_f32_fp8_e32 v[226:227], v181
	v_cvt_pk_f32_fp8_e32 v[228:229], v185
	v_cvt_pk_f32_fp8_e32 v[230:231], v189
	v_pk_fma_f32 v[216:217], v[224:225], v[84:85], v[216:217]
	v_pk_fma_f32 v[218:219], v[226:227], v[84:85], v[218:219]
	v_pk_fma_f32 v[220:221], v[228:229], v[84:85], v[220:221]
	v_pk_fma_f32 v[222:223], v[230:231], v[84:85], v[222:223]
	v_cvt_pk_f32_fp8_sdwa v[224:225], v177 src0_sel:WORD_1
	v_cvt_pk_f32_fp8_sdwa v[226:227], v181 src0_sel:WORD_1
	v_cvt_pk_f32_fp8_sdwa v[228:229], v185 src0_sel:WORD_1
	v_cvt_pk_f32_fp8_sdwa v[230:231], v189 src0_sel:WORD_1
	v_pk_fma_f32 v[216:217], v[224:225], v[86:87], v[216:217]
	v_pk_fma_f32 v[218:219], v[226:227], v[86:87], v[218:219]
	v_pk_fma_f32 v[220:221], v[228:229], v[86:87], v[220:221]
	v_pk_fma_f32 v[222:223], v[230:231], v[86:87], v[222:223]
	v_cvt_pk_f32_fp8_e32 v[224:225], v178
	v_cvt_pk_f32_fp8_e32 v[226:227], v182
	v_cvt_pk_f32_fp8_e32 v[228:229], v186
	v_cvt_pk_f32_fp8_e32 v[230:231], v190
	v_pk_fma_f32 v[216:217], v[224:225], v[88:89], v[216:217]
	v_pk_fma_f32 v[218:219], v[226:227], v[88:89], v[218:219]
	v_pk_fma_f32 v[220:221], v[228:229], v[88:89], v[220:221]
	v_pk_fma_f32 v[222:223], v[230:231], v[88:89], v[222:223]
	v_cvt_pk_f32_fp8_sdwa v[224:225], v178 src0_sel:WORD_1
	v_cvt_pk_f32_fp8_sdwa v[226:227], v182 src0_sel:WORD_1
	v_cvt_pk_f32_fp8_sdwa v[228:229], v186 src0_sel:WORD_1
	v_cvt_pk_f32_fp8_sdwa v[230:231], v190 src0_sel:WORD_1
	v_pk_fma_f32 v[216:217], v[224:225], v[90:91], v[216:217]
	v_pk_fma_f32 v[218:219], v[226:227], v[90:91], v[218:219]
	v_pk_fma_f32 v[220:221], v[228:229], v[90:91], v[220:221]
	v_pk_fma_f32 v[222:223], v[230:231], v[90:91], v[222:223]
	v_cvt_pk_f32_fp8_e32 v[224:225], v179
	v_cvt_pk_f32_fp8_e32 v[226:227], v183
	v_cvt_pk_f32_fp8_e32 v[228:229], v187
	v_cvt_pk_f32_fp8_e32 v[230:231], v191
	v_pk_fma_f32 v[216:217], v[224:225], v[92:93], v[216:217]
	v_pk_fma_f32 v[218:219], v[226:227], v[92:93], v[218:219]
	v_pk_fma_f32 v[220:221], v[228:229], v[92:93], v[220:221]
	v_pk_fma_f32 v[222:223], v[230:231], v[92:93], v[222:223]
	v_cvt_pk_f32_fp8_sdwa v[224:225], v179 src0_sel:WORD_1
	v_cvt_pk_f32_fp8_sdwa v[226:227], v183 src0_sel:WORD_1
	v_cvt_pk_f32_fp8_sdwa v[228:229], v187 src0_sel:WORD_1
	v_cvt_pk_f32_fp8_sdwa v[230:231], v191 src0_sel:WORD_1
	v_pk_fma_f32 v[216:217], v[224:225], v[94:95], v[216:217]
	v_pk_fma_f32 v[218:219], v[226:227], v[94:95], v[218:219]
	v_pk_fma_f32 v[220:221], v[228:229], v[94:95], v[220:221]
	v_pk_fma_f32 v[222:223], v[230:231], v[94:95], v[222:223]
	v_add_f32_e32 v204, v216, v217
	v_add_f32_e32 v205, v218, v219
	v_add_f32_e32 v206, v220, v221
	v_add_f32_e32 v207, v222, v223
	s_nop 0
	v_permlane32_swap_b32_e32 v192, v200
	v_permlane32_swap_b32_e32 v193, v201
	v_permlane32_swap_b32_e32 v194, v202
	v_permlane32_swap_b32_e32 v195, v203
	v_permlane32_swap_b32_e32 v196, v204
	v_permlane32_swap_b32_e32 v197, v205
	v_permlane32_swap_b32_e32 v198, v206
	v_permlane32_swap_b32_e32 v199, v207
	v_add_f32_e32 v192, v192, v200
	v_add_f32_e32 v193, v193, v201
	v_add_f32_e32 v194, v194, v202
	v_add_f32_e32 v195, v195, v203
	v_add_f32_e32 v196, v196, v204
	v_add_f32_e32 v197, v197, v205
	v_add_f32_e32 v198, v198, v206
	v_add_f32_e32 v199, v199, v207
	v_permlane16_swap_b32_e32 v192, v196
	v_permlane16_swap_b32_e32 v193, v197
	v_permlane16_swap_b32_e32 v194, v198
	v_permlane16_swap_b32_e32 v195, v199
	v_add_f32_e32 v192, v192, v196
	v_add_f32_e32 v193, v193, v197
	v_add_f32_e32 v194, v194, v198
	v_add_f32_e32 v195, v195, v199
	v_add_f32_dpp v216, v192, v192 row_ror:8 row_mask:0xf bank_mask:0xf
	v_add_f32_dpp v218, v194, v194 row_ror:8 row_mask:0xf bank_mask:0xf
	v_add_f32_dpp v216, v193, v193 row_ror:8 row_mask:0xf bank_mask:0xc
	v_add_f32_dpp v218, v195, v195 row_ror:8 row_mask:0xf bank_mask:0xc
	s_nop 1
	v_add_f32_dpp v220, v216, v216 row_half_mirror row_mask:0xf bank_mask:0xf
	v_add_f32_dpp v220, v218, v218 row_half_mirror row_mask:0xf bank_mask:0xa
	s_nop 1
	v_add_f32_dpp v220, v220, v220 quad_perm:[1,0,3,2] row_mask:0xf bank_mask:0xf
	s_nop 1
	v_add_f32_dpp v220, v220, v220 quad_perm:[2,3,0,1] row_mask:0xf bank_mask:0xf
	v_mul_f32_e32 v216, v252, v220
	v_fma_f32 v218, |v216|, s72, 1.0
	v_mul_f32_e32 v222, v216, v216
	v_rcp_f32_e32 v218, v218
	v_mul_f32_e32 v222, 0xbf38aa3b, v222
	v_exp_f32_e32 v222, v222
	v_fmamk_f32 v224, v218, 0x3f07dc22, v242
	v_fmaak_f32 v224, v218, v224, 0x3f35f0e3
	v_fmaak_f32 v224, v218, v224, 0xbe11a98e
	v_fmaak_f32 v224, v218, v224, 0x3e027906
	v_mul_f32_e32 v224, v218, v224
	v_mul_f32_e32 v224, v222, v224
	v_mul_f32_e32 v226, v216, v224
	v_fma_f32 v224, -v216, v224, v216
	v_cmp_gt_f32_e32 vcc, 0, v216
	s_nop 1
	v_cndmask_b32_e32 v224, v224, v226, vcc
	v_mul_f32_e32 v224, v249, v224
	v_mul_f32_e32 v224, v253, v224
	ds_write_b32 v211, v224 offset:4992
	v_add_u32_e32 v211, 64, v211
	v_add_u32_e32 v213, 64, v213
	ds_read_b32 v248, v211
	ds_read_b32 v249, v211 offset:4992
	s_add_i32 s21, s21, 4
	s_sub_i32 s90, s90, 1
	s_cmp_eq_u32 s90, 0
	s_cbranch_scc1 .LU_sw0
	s_branch .LU_t5_s0
.LU_t6_s0:
	s_cmp_ge_u32 s21, s20
	s_cbranch_scc1 .LU_done
	s_waitcnt lgkmcnt(0)
	v_lshlrev_b32_e32 v208, 2, v248
	buffer_load_dword v252, v208, s[24:27], 0 offen
	buffer_load_dword v253, v208, s[28:31], 0 offen
	buffer_load_dwordx4 v[176:179], v[232:233], s[56:59], 0 idxen offen
	buffer_load_dwordx4 v[180:183], v[234:235], s[56:59], 0 idxen offen
	buffer_load_dwordx4 v[184:187], v[236:237], s[56:59], 0 idxen offen
	buffer_load_dwordx4 v[188:191], v[238:239], s[56:59], 0 idxen offen
	ds_read_b32 v232, v213 offset:64
	ds_read_b32 v234, v213 offset:68
	ds_read_b32 v236, v213 offset:72
	ds_read_b32 v238, v213 offset:76
	s_waitcnt vmcnt(14)
	v_cvt_pk_f32_fp8_e32 v[224:225], v128
	v_cvt_pk_f32_fp8_e32 v[226:227], v132
	v_cvt_pk_f32_fp8_e32 v[228:229], v136
	v_cvt_pk_f32_fp8_e32 v[230:231], v140
	v_pk_mul_f32 v[216:217], v[224:225], v[96:97]
	v_pk_mul_f32 v[218:219], v[226:227], v[96:97]
	v_pk_mul_f32 v[220:221], v[228:229], v[96:97]
	v_pk_mul_f32 v[222:223], v[230:231], v[96:97]
	v_cvt_pk_f32_fp8_sdwa v[224:225], v128 src0_sel:WORD_1
	v_cvt_pk_f32_fp8_sdwa v[226:227], v132 src0_sel:WORD_1
	v_cvt_pk_f32_fp8_sdwa v[228:229], v136 src0_sel:WORD_1
	v_cvt_pk_f32_fp8_sdwa v[230:231], v140 src0_sel:WORD_1
	v_pk_fma_f32 v[216:217], v[224:225], v[98:99], v[216:217]
	v_pk_fma_f32 v[218:219], v[226:227], v[98:99], v[218:219]
	v_pk_fma_f32 v[220:221], v[228:229], v[98:99], v[220:221]
	v_pk_fma_f32 v[222:223], v[230:231], v[98:99], v[222:223]
	v_cvt_pk_f32_fp8_e32 v[224:225], v129
	v_cvt_pk_f32_fp8_e32 v[226:227], v133
	v_cvt_pk_f32_fp8_e32 v[228:229], v137
	v_cvt_pk_f32_fp8_e32 v[230:231], v141
	v_pk_fma_f32 v[216:217], v[224:225], v[100:101], v[216:217]
	v_pk_fma_f32 v[218:219], v[226:227], v[100:101], v[218:219]
	v_pk_fma_f32 v[220:221], v[228:229], v[100:101], v[220:221]
	v_pk_fma_f32 v[222:223], v[230:231], v[100:101], v[222:223]
	v_cvt_pk_f32_fp8_sdwa v[224:225], v129 src0_sel:WORD_1
	v_cvt_pk_f32_fp8_sdwa v[226:227], v133 src0_sel:WORD_1
	v_cvt_pk_f32_fp8_sdwa v[228:229], v137 src0_sel:WORD_1
	v_cvt_pk_f32_fp8_sdwa v[230:231], v141 src0_sel:WORD_1
	v_pk_fma_f32 v[216:217], v[224:225], v[102:103], v[216:217]
	v_pk_fma_f32 v[218:219], v[226:227], v[102:103], v[218:219]
	v_pk_fma_f32 v[220:221], v[228:229], v[102:103], v[220:221]
	v_pk_fma_f32 v[222:223], v[230:231], v[102:103], v[222:223]
	v_cvt_pk_f32_fp8_e32 v[224:225], v130
	v_cvt_pk_f32_fp8_e32 v[226:227], v134
	v_cvt_pk_f32_fp8_e32 v[228:229], v138
	v_cvt_pk_f32_fp8_e32 v[230:231], v142
	v_pk_fma_f32 v[216:217], v[224:225], v[104:105], v[216:217]
	v_pk_fma_f32 v[218:219], v[226:227], v[104:105], v[218:219]
	v_pk_fma_f32 v[220:221], v[228:229], v[104:105], v[220:221]
	v_pk_fma_f32 v[222:223], v[230:231], v[104:105], v[222:223]
	v_cvt_pk_f32_fp8_sdwa v[224:225], v130 src0_sel:WORD_1
	v_cvt_pk_f32_fp8_sdwa v[226:227], v134 src0_sel:WORD_1
	v_cvt_pk_f32_fp8_sdwa v[228:229], v138 src0_sel:WORD_1
	v_cvt_pk_f32_fp8_sdwa v[230:231], v142 src0_sel:WORD_1
	v_pk_fma_f32 v[216:217], v[224:225], v[106:107], v[216:217]
	v_pk_fma_f32 v[218:219], v[226:227], v[106:107], v[218:219]
	v_pk_fma_f32 v[220:221], v[228:229], v[106:107], v[220:221]
	v_pk_fma_f32 v[222:223], v[230:231], v[106:107], v[222:223]
	v_cvt_pk_f32_fp8_e32 v[224:225], v131
	v_cvt_pk_f32_fp8_e32 v[226:227], v135
	v_cvt_pk_f32_fp8_e32 v[228:229], v139
	v_cvt_pk_f32_fp8_e32 v[230:231], v143
	v_pk_fma_f32 v[216:217], v[224:225], v[108:109], v[216:217]
	v_pk_fma_f32 v[218:219], v[226:227], v[108:109], v[218:219]
	v_pk_fma_f32 v[220:221], v[228:229], v[108:109], v[220:221]
	v_pk_fma_f32 v[222:223], v[230:231], v[108:109], v[222:223]
	v_cvt_pk_f32_fp8_sdwa v[224:225], v131 src0_sel:WORD_1
	v_cvt_pk_f32_fp8_sdwa v[226:227], v135 src0_sel:WORD_1
	v_cvt_pk_f32_fp8_sdwa v[228:229], v139 src0_sel:WORD_1
	v_cvt_pk_f32_fp8_sdwa v[230:231], v143 src0_sel:WORD_1
	v_pk_fma_f32 v[216:217], v[224:225], v[110:111], v[216:217]
	v_pk_fma_f32 v[218:219], v[226:227], v[110:111], v[218:219]
	v_pk_fma_f32 v[220:221], v[228:229], v[110:111], v[220:221]
	v_pk_fma_f32 v[222:223], v[230:231], v[110:111], v[222:223]
	v_add_f32_e32 v192, v216, v217
	v_add_f32_e32 v193, v218, v219
	v_add_f32_e32 v194, v220, v221
	v_add_f32_e32 v195, v222, v223
	s_sub_i32 s90, s90, 1
	s_cmp_eq_u32 s90, 0
	s_cbranch_scc1 .LU_sw1
.LU_t6_s1:
	s_waitcnt lgkmcnt(0)
	buffer_load_dwordx4 v[128:131], v[232:233], s[56:59], 0 idxen offen
	buffer_load_dwordx4 v[132:135], v[234:235], s[56:59], 0 idxen offen
	buffer_load_dwordx4 v[136:139], v[236:237], s[56:59], 0 idxen offen
	buffer_load_dwordx4 v[140:143], v[238:239], s[56:59], 0 idxen offen
	ds_read_b32 v232, v213 offset:80
	ds_read_b32 v234, v213 offset:84
	ds_read_b32 v236, v213 offset:88
	ds_read_b32 v238, v213 offset:92
	s_waitcnt vmcnt(14)
	v_cvt_pk_f32_fp8_e32 v[224:225], v144
	v_cvt_pk_f32_fp8_e32 v[226:227], v148
	v_cvt_pk_f32_fp8_e32 v[228:229], v152
	v_cvt_pk_f32_fp8_e32 v[230:231], v156
	v_pk_mul_f32 v[216:217], v[224:225], v[96:97]
	v_pk_mul_f32 v[218:219], v[226:227], v[96:97]
	v_pk_mul_f32 v[220:221], v[228:229], v[96:97]
	v_pk_mul_f32 v[222:223], v[230:231], v[96:97]
	v_cvt_pk_f32_fp8_sdwa v[224:225], v144 src0_sel:WORD_1
	v_cvt_pk_f32_fp8_sdwa v[226:227], v148 src0_sel:WORD_1
	v_cvt_pk_f32_fp8_sdwa v[228:229], v152 src0_sel:WORD_1
	v_cvt_pk_f32_fp8_sdwa v[230:231], v156 src0_sel:WORD_1
	v_pk_fma_f32 v[216:217], v[224:225], v[98:99], v[216:217]
	v_pk_fma_f32 v[218:219], v[226:227], v[98:99], v[218:219]
	v_pk_fma_f32 v[220:221], v[228:229], v[98:99], v[220:221]
	v_pk_fma_f32 v[222:223], v[230:231], v[98:99], v[222:223]
	v_cvt_pk_f32_fp8_e32 v[224:225], v145
	v_cvt_pk_f32_fp8_e32 v[226:227], v149
	v_cvt_pk_f32_fp8_e32 v[228:229], v153
	v_cvt_pk_f32_fp8_e32 v[230:231], v157
	v_pk_fma_f32 v[216:217], v[224:225], v[100:101], v[216:217]
	v_pk_fma_f32 v[218:219], v[226:227], v[100:101], v[218:219]
	v_pk_fma_f32 v[220:221], v[228:229], v[100:101], v[220:221]
	v_pk_fma_f32 v[222:223], v[230:231], v[100:101], v[222:223]
	v_cvt_pk_f32_fp8_sdwa v[224:225], v145 src0_sel:WORD_1
	v_cvt_pk_f32_fp8_sdwa v[226:227], v149 src0_sel:WORD_1
	v_cvt_pk_f32_fp8_sdwa v[228:229], v153 src0_sel:WORD_1
	v_cvt_pk_f32_fp8_sdwa v[230:231], v157 src0_sel:WORD_1
	v_pk_fma_f32 v[216:217], v[224:225], v[102:103], v[216:217]
	v_pk_fma_f32 v[218:219], v[226:227], v[102:103], v[218:219]
	v_pk_fma_f32 v[220:221], v[228:229], v[102:103], v[220:221]
	v_pk_fma_f32 v[222:223], v[230:231], v[102:103], v[222:223]
	v_cvt_pk_f32_fp8_e32 v[224:225], v146
	v_cvt_pk_f32_fp8_e32 v[226:227], v150
	v_cvt_pk_f32_fp8_e32 v[228:229], v154
	v_cvt_pk_f32_fp8_e32 v[230:231], v158
	v_pk_fma_f32 v[216:217], v[224:225], v[104:105], v[216:217]
	v_pk_fma_f32 v[218:219], v[226:227], v[104:105], v[218:219]
	v_pk_fma_f32 v[220:221], v[228:229], v[104:105], v[220:221]
	v_pk_fma_f32 v[222:223], v[230:231], v[104:105], v[222:223]
	v_cvt_pk_f32_fp8_sdwa v[224:225], v146 src0_sel:WORD_1
	v_cvt_pk_f32_fp8_sdwa v[226:227], v150 src0_sel:WORD_1
	v_cvt_pk_f32_fp8_sdwa v[228:229], v154 src0_sel:WORD_1
	v_cvt_pk_f32_fp8_sdwa v[230:231], v158 src0_sel:WORD_1
	v_pk_fma_f32 v[216:217], v[224:225], v[106:107], v[216:217]
	v_pk_fma_f32 v[218:219], v[226:227], v[106:107], v[218:219]
	v_pk_fma_f32 v[220:221], v[228:229], v[106:107], v[220:221]
	v_pk_fma_f32 v[222:223], v[230:231], v[106:107], v[222:223]
	v_cvt_pk_f32_fp8_e32 v[224:225], v147
	v_cvt_pk_f32_fp8_e32 v[226:227], v151
	v_cvt_pk_f32_fp8_e32 v[228:229], v155
	v_cvt_pk_f32_fp8_e32 v[230:231], v159
	v_pk_fma_f32 v[216:217], v[224:225], v[108:109], v[216:217]
	v_pk_fma_f32 v[218:219], v[226:227], v[108:109], v[218:219]
	v_pk_fma_f32 v[220:221], v[228:229], v[108:109], v[220:221]
	v_pk_fma_f32 v[222:223], v[230:231], v[108:109], v[222:223]
	v_cvt_pk_f32_fp8_sdwa v[224:225], v147 src0_sel:WORD_1
	v_cvt_pk_f32_fp8_sdwa v[226:227], v151 src0_sel:WORD_1
	v_cvt_pk_f32_fp8_sdwa v[228:229], v155 src0_sel:WORD_1
	v_cvt_pk_f32_fp8_sdwa v[230:231], v159 src0_sel:WORD_1
	v_pk_fma_f32 v[216:217], v[224:225], v[110:111], v[216:217]
	v_pk_fma_f32 v[218:219], v[226:227], v[110:111], v[218:219]
	v_pk_fma_f32 v[220:221], v[228:229], v[110:111], v[220:221]
	v_pk_fma_f32 v[222:223], v[230:231], v[110:111], v[222:223]
	v_add_f32_e32 v196, v216, v217
	v_add_f32_e32 v197, v218, v219
	v_add_f32_e32 v198, v220, v221
	v_add_f32_e32 v199, v222, v223
	s_sub_i32 s90, s90, 1
	s_cmp_eq_u32 s90, 0
	s_cbranch_scc1 .LU_sw2
.LU_t6_s2:
	s_waitcnt lgkmcnt(0)
	buffer_load_dwordx4 v[144:147], v[232:233], s[56:59], 0 idxen offen
	buffer_load_dwordx4 v[148:151], v[234:235], s[56:59], 0 idxen offen
	buffer_load_dwordx4 v[152:155], v[236:237], s[56:59], 0 idxen offen
	buffer_load_dwordx4 v[156:159], v[238:239], s[56:59], 0 idxen offen
	ds_read_b32 v232, v213 offset:96
	ds_read_b32 v234, v213 offset:100
	ds_read_b32 v236, v213 offset:104
	ds_read_b32 v238, v213 offset:108
	s_waitcnt vmcnt(14)
	v_cvt_pk_f32_fp8_e32 v[224:225], v160
	v_cvt_pk_f32_fp8_e32 v[226:227], v164
	v_cvt_pk_f32_fp8_e32 v[228:229], v168
	v_cvt_pk_f32_fp8_e32 v[230:231], v172
	v_pk_mul_f32 v[216:217], v[224:225], v[96:97]
	v_pk_mul_f32 v[218:219], v[226:227], v[96:97]
	v_pk_mul_f32 v[220:221], v[228:229], v[96:97]
	v_pk_mul_f32 v[222:223], v[230:231], v[96:97]
	v_cvt_pk_f32_fp8_sdwa v[224:225], v160 src0_sel:WORD_1
	v_cvt_pk_f32_fp8_sdwa v[226:227], v164 src0_sel:WORD_1
	v_cvt_pk_f32_fp8_sdwa v[228:229], v168 src0_sel:WORD_1
	v_cvt_pk_f32_fp8_sdwa v[230:231], v172 src0_sel:WORD_1
	v_pk_fma_f32 v[216:217], v[224:225], v[98:99], v[216:217]
	v_pk_fma_f32 v[218:219], v[226:227], v[98:99], v[218:219]
	v_pk_fma_f32 v[220:221], v[228:229], v[98:99], v[220:221]
	v_pk_fma_f32 v[222:223], v[230:231], v[98:99], v[222:223]
	v_cvt_pk_f32_fp8_e32 v[224:225], v161
	v_cvt_pk_f32_fp8_e32 v[226:227], v165
	v_cvt_pk_f32_fp8_e32 v[228:229], v169
	v_cvt_pk_f32_fp8_e32 v[230:231], v173
	v_pk_fma_f32 v[216:217], v[224:225], v[100:101], v[216:217]
	v_pk_fma_f32 v[218:219], v[226:227], v[100:101], v[218:219]
	v_pk_fma_f32 v[220:221], v[228:229], v[100:101], v[220:221]
	v_pk_fma_f32 v[222:223], v[230:231], v[100:101], v[222:223]
	v_cvt_pk_f32_fp8_sdwa v[224:225], v161 src0_sel:WORD_1
	v_cvt_pk_f32_fp8_sdwa v[226:227], v165 src0_sel:WORD_1
	v_cvt_pk_f32_fp8_sdwa v[228:229], v169 src0_sel:WORD_1
	v_cvt_pk_f32_fp8_sdwa v[230:231], v173 src0_sel:WORD_1
	v_pk_fma_f32 v[216:217], v[224:225], v[102:103], v[216:217]
	v_pk_fma_f32 v[218:219], v[226:227], v[102:103], v[218:219]
	v_pk_fma_f32 v[220:221], v[228:229], v[102:103], v[220:221]
	v_pk_fma_f32 v[222:223], v[230:231], v[102:103], v[222:223]
	v_cvt_pk_f32_fp8_e32 v[224:225], v162
	v_cvt_pk_f32_fp8_e32 v[226:227], v166
	v_cvt_pk_f32_fp8_e32 v[228:229], v170
	v_cvt_pk_f32_fp8_e32 v[230:231], v174
	v_pk_fma_f32 v[216:217], v[224:225], v[104:105], v[216:217]
	v_pk_fma_f32 v[218:219], v[226:227], v[104:105], v[218:219]
	v_pk_fma_f32 v[220:221], v[228:229], v[104:105], v[220:221]
	v_pk_fma_f32 v[222:223], v[230:231], v[104:105], v[222:223]
	v_cvt_pk_f32_fp8_sdwa v[224:225], v162 src0_sel:WORD_1
	v_cvt_pk_f32_fp8_sdwa v[226:227], v166 src0_sel:WORD_1
	v_cvt_pk_f32_fp8_sdwa v[228:229], v170 src0_sel:WORD_1
	v_cvt_pk_f32_fp8_sdwa v[230:231], v174 src0_sel:WORD_1
	v_pk_fma_f32 v[216:217], v[224:225], v[106:107], v[216:217]
	v_pk_fma_f32 v[218:219], v[226:227], v[106:107], v[218:219]
	v_pk_fma_f32 v[220:221], v[228:229], v[106:107], v[220:221]
	v_pk_fma_f32 v[222:223], v[230:231], v[106:107], v[222:223]
	v_cvt_pk_f32_fp8_e32 v[224:225], v163
	v_cvt_pk_f32_fp8_e32 v[226:227], v167
	v_cvt_pk_f32_fp8_e32 v[228:229], v171
	v_cvt_pk_f32_fp8_e32 v[230:231], v175
	v_pk_fma_f32 v[216:217], v[224:225], v[108:109], v[216:217]
	v_pk_fma_f32 v[218:219], v[226:227], v[108:109], v[218:219]
	v_pk_fma_f32 v[220:221], v[228:229], v[108:109], v[220:221]
	v_pk_fma_f32 v[222:223], v[230:231], v[108:109], v[222:223]
	v_cvt_pk_f32_fp8_sdwa v[224:225], v163 src0_sel:WORD_1
	v_cvt_pk_f32_fp8_sdwa v[226:227], v167 src0_sel:WORD_1
	v_cvt_pk_f32_fp8_sdwa v[228:229], v171 src0_sel:WORD_1
	v_cvt_pk_f32_fp8_sdwa v[230:231], v175 src0_sel:WORD_1
	v_pk_fma_f32 v[216:217], v[224:225], v[110:111], v[216:217]
	v_pk_fma_f32 v[218:219], v[226:227], v[110:111], v[218:219]
	v_pk_fma_f32 v[220:221], v[228:229], v[110:111], v[220:221]
	v_pk_fma_f32 v[222:223], v[230:231], v[110:111], v[222:223]
	v_add_f32_e32 v200, v216, v217
	v_add_f32_e32 v201, v218, v219
	v_add_f32_e32 v202, v220, v221
	v_add_f32_e32 v203, v222, v223
	s_sub_i32 s90, s90, 1
	s_cmp_eq_u32 s90, 0
	s_cbranch_scc1 .LU_sw3
.LU_t6_s3:
	s_waitcnt lgkmcnt(0)
	buffer_load_dwordx4 v[160:163], v[232:233], s[56:59], 0 idxen offen
	buffer_load_dwordx4 v[164:167], v[234:235], s[56:59], 0 idxen offen
	buffer_load_dwordx4 v[168:171], v[236:237], s[56:59], 0 idxen offen
	buffer_load_dwordx4 v[172:175], v[238:239], s[56:59], 0 idxen offen
	ds_read_b32 v232, v213 offset:112
	ds_read_b32 v234, v213 offset:116
	ds_read_b32 v236, v213 offset:120
	ds_read_b32 v238, v213 offset:124
	s_waitcnt vmcnt(12)
	v_cvt_pk_f32_fp8_e32 v[224:225], v176
	v_cvt_pk_f32_fp8_e32 v[226:227], v180
	v_cvt_pk_f32_fp8_e32 v[228:229], v184
	v_cvt_pk_f32_fp8_e32 v[230:231], v188
	v_pk_mul_f32 v[216:217], v[224:225], v[96:97]
	v_pk_mul_f32 v[218:219], v[226:227], v[96:97]
	v_pk_mul_f32 v[220:221], v[228:229], v[96:97]
	v_pk_mul_f32 v[222:223], v[230:231], v[96:97]
	v_cvt_pk_f32_fp8_sdwa v[224:225], v176 src0_sel:WORD_1
	v_cvt_pk_f32_fp8_sdwa v[226:227], v180 src0_sel:WORD_1
	v_cvt_pk_f32_fp8_sdwa v[228:229], v184 src0_sel:WORD_1
	v_cvt_pk_f32_fp8_sdwa v[230:231], v188 src0_sel:WORD_1
	v_pk_fma_f32 v[216:217], v[224:225], v[98:99], v[216:217]
	v_pk_fma_f32 v[218:219], v[226:227], v[98:99], v[218:219]
	v_pk_fma_f32 v[220:221], v[228:229], v[98:99], v[220:221]
	v_pk_fma_f32 v[222:223], v[230:231], v[98:99], v[222:223]
	v_cvt_pk_f32_fp8_e32 v[224:225], v177
	v_cvt_pk_f32_fp8_e32 v[226:227], v181
	v_cvt_pk_f32_fp8_e32 v[228:229], v185
	v_cvt_pk_f32_fp8_e32 v[230:231], v189
	v_pk_fma_f32 v[216:217], v[224:225], v[100:101], v[216:217]
	v_pk_fma_f32 v[218:219], v[226:227], v[100:101], v[218:219]
	v_pk_fma_f32 v[220:221], v[228:229], v[100:101], v[220:221]
	v_pk_fma_f32 v[222:223], v[230:231], v[100:101], v[222:223]
	v_cvt_pk_f32_fp8_sdwa v[224:225], v177 src0_sel:WORD_1
	v_cvt_pk_f32_fp8_sdwa v[226:227], v181 src0_sel:WORD_1
	v_cvt_pk_f32_fp8_sdwa v[228:229], v185 src0_sel:WORD_1
	v_cvt_pk_f32_fp8_sdwa v[230:231], v189 src0_sel:WORD_1
	v_pk_fma_f32 v[216:217], v[224:225], v[102:103], v[216:217]
	v_pk_fma_f32 v[218:219], v[226:227], v[102:103], v[218:219]
	v_pk_fma_f32 v[220:221], v[228:229], v[102:103], v[220:221]
	v_pk_fma_f32 v[222:223], v[230:231], v[102:103], v[222:223]
	v_cvt_pk_f32_fp8_e32 v[224:225], v178
	v_cvt_pk_f32_fp8_e32 v[226:227], v182
	v_cvt_pk_f32_fp8_e32 v[228:229], v186
	v_cvt_pk_f32_fp8_e32 v[230:231], v190
	v_pk_fma_f32 v[216:217], v[224:225], v[104:105], v[216:217]
	v_pk_fma_f32 v[218:219], v[226:227], v[104:105], v[218:219]
	v_pk_fma_f32 v[220:221], v[228:229], v[104:105], v[220:221]
	v_pk_fma_f32 v[222:223], v[230:231], v[104:105], v[222:223]
	v_cvt_pk_f32_fp8_sdwa v[224:225], v178 src0_sel:WORD_1
	v_cvt_pk_f32_fp8_sdwa v[226:227], v182 src0_sel:WORD_1
	v_cvt_pk_f32_fp8_sdwa v[228:229], v186 src0_sel:WORD_1
	v_cvt_pk_f32_fp8_sdwa v[230:231], v190 src0_sel:WORD_1
	v_pk_fma_f32 v[216:217], v[224:225], v[106:107], v[216:217]
	v_pk_fma_f32 v[218:219], v[226:227], v[106:107], v[218:219]
	v_pk_fma_f32 v[220:221], v[228:229], v[106:107], v[220:221]
	v_pk_fma_f32 v[222:223], v[230:231], v[106:107], v[222:223]
	v_cvt_pk_f32_fp8_e32 v[224:225], v179
	v_cvt_pk_f32_fp8_e32 v[226:227], v183
	v_cvt_pk_f32_fp8_e32 v[228:229], v187
	v_cvt_pk_f32_fp8_e32 v[230:231], v191
	v_pk_fma_f32 v[216:217], v[224:225], v[108:109], v[216:217]
	v_pk_fma_f32 v[218:219], v[226:227], v[108:109], v[218:219]
	v_pk_fma_f32 v[220:221], v[228:229], v[108:109], v[220:221]
	v_pk_fma_f32 v[222:223], v[230:231], v[108:109], v[222:223]
	v_cvt_pk_f32_fp8_sdwa v[224:225], v179 src0_sel:WORD_1
	v_cvt_pk_f32_fp8_sdwa v[226:227], v183 src0_sel:WORD_1
	v_cvt_pk_f32_fp8_sdwa v[228:229], v187 src0_sel:WORD_1
	v_cvt_pk_f32_fp8_sdwa v[230:231], v191 src0_sel:WORD_1
	v_pk_fma_f32 v[216:217], v[224:225], v[110:111], v[216:217]
	v_pk_fma_f32 v[218:219], v[226:227], v[110:111], v[218:219]
	v_pk_fma_f32 v[220:221], v[228:229], v[110:111], v[220:221]
	v_pk_fma_f32 v[222:223], v[230:231], v[110:111], v[222:223]
	v_add_f32_e32 v204, v216, v217
	v_add_f32_e32 v205, v218, v219
	v_add_f32_e32 v206, v220, v221
	v_add_f32_e32 v207, v222, v223
	s_nop 0
	v_permlane32_swap_b32_e32 v192, v200
	v_permlane32_swap_b32_e32 v193, v201
	v_permlane32_swap_b32_e32 v194, v202
	v_permlane32_swap_b32_e32 v195, v203
	v_permlane32_swap_b32_e32 v196, v204
	v_permlane32_swap_b32_e32 v197, v205
	v_permlane32_swap_b32_e32 v198, v206
	v_permlane32_swap_b32_e32 v199, v207
	v_add_f32_e32 v192, v192, v200
	v_add_f32_e32 v193, v193, v201
	v_add_f32_e32 v194, v194, v202
	v_add_f32_e32 v195, v195, v203
	v_add_f32_e32 v196, v196, v204
	v_add_f32_e32 v197, v197, v205
	v_add_f32_e32 v198, v198, v206
	v_add_f32_e32 v199, v199, v207
	v_permlane16_swap_b32_e32 v192, v196
	v_permlane16_swap_b32_e32 v193, v197
	v_permlane16_swap_b32_e32 v194, v198
	v_permlane16_swap_b32_e32 v195, v199
	v_add_f32_e32 v192, v192, v196
	v_add_f32_e32 v193, v193, v197
	v_add_f32_e32 v194, v194, v198
	v_add_f32_e32 v195, v195, v199
	v_add_f32_dpp v216, v192, v192 row_ror:8 row_mask:0xf bank_mask:0xf
	v_add_f32_dpp v218, v194, v194 row_ror:8 row_mask:0xf bank_mask:0xf
	v_add_f32_dpp v216, v193, v193 row_ror:8 row_mask:0xf bank_mask:0xc
	v_add_f32_dpp v218, v195, v195 row_ror:8 row_mask:0xf bank_mask:0xc
	s_nop 1
	v_add_f32_dpp v220, v216, v216 row_half_mirror row_mask:0xf bank_mask:0xf
	v_add_f32_dpp v220, v218, v218 row_half_mirror row_mask:0xf bank_mask:0xa
	s_nop 1
	v_add_f32_dpp v220, v220, v220 quad_perm:[1,0,3,2] row_mask:0xf bank_mask:0xf
	s_nop 1
	v_add_f32_dpp v220, v220, v220 quad_perm:[2,3,0,1] row_mask:0xf bank_mask:0xf
	v_mul_f32_e32 v216, v252, v220
	v_fma_f32 v218, |v216|, s72, 1.0
	v_mul_f32_e32 v222, v216, v216
	v_rcp_f32_e32 v218, v218
	v_mul_f32_e32 v222, 0xbf38aa3b, v222
	v_exp_f32_e32 v222, v222
	v_fmamk_f32 v224, v218, 0x3f07dc22, v242
	v_fmaak_f32 v224, v218, v224, 0x3f35f0e3
	v_fmaak_f32 v224, v218, v224, 0xbe11a98e
	v_fmaak_f32 v224, v218, v224, 0x3e027906
	v_mul_f32_e32 v224, v218, v224
	v_mul_f32_e32 v224, v222, v224
	v_mul_f32_e32 v226, v216, v224
	v_fma_f32 v224, -v216, v224, v216
	v_cmp_gt_f32_e32 vcc, 0, v216
	s_nop 1
	v_cndmask_b32_e32 v224, v224, v226, vcc
	v_mul_f32_e32 v224, v249, v224
	v_mul_f32_e32 v224, v253, v224
	ds_write_b32 v211, v224 offset:4992
	v_add_u32_e32 v211, 64, v211
	v_add_u32_e32 v213, 64, v213
	ds_read_b32 v248, v211
	ds_read_b32 v249, v211 offset:4992
	s_add_i32 s21, s21, 4
	s_sub_i32 s90, s90, 1
	s_cmp_eq_u32 s90, 0
	s_cbranch_scc1 .LU_sw0
	s_branch .LU_t6_s0
.LU_t7_s0:
	s_cmp_ge_u32 s21, s20
	s_cbranch_scc1 .LU_done
	s_waitcnt lgkmcnt(0)
	v_lshlrev_b32_e32 v208, 2, v248
	buffer_load_dword v252, v208, s[24:27], 0 offen
	buffer_load_dword v253, v208, s[28:31], 0 offen
	buffer_load_dwordx4 v[176:179], v[232:233], s[56:59], 0 idxen offen
	buffer_load_dwordx4 v[180:183], v[234:235], s[56:59], 0 idxen offen
	buffer_load_dwordx4 v[184:187], v[236:237], s[56:59], 0 idxen offen
	buffer_load_dwordx4 v[188:191], v[238:239], s[56:59], 0 idxen offen
	ds_read_b32 v232, v213 offset:64
	ds_read_b32 v234, v213 offset:68
	ds_read_b32 v236, v213 offset:72
	ds_read_b32 v238, v213 offset:76
	s_waitcnt vmcnt(14)
	v_cvt_pk_f32_fp8_e32 v[224:225], v128
	v_cvt_pk_f32_fp8_e32 v[226:227], v132
	v_cvt_pk_f32_fp8_e32 v[228:229], v136
	v_cvt_pk_f32_fp8_e32 v[230:231], v140
	v_pk_mul_f32 v[216:217], v[224:225], v[112:113]
	v_pk_mul_f32 v[218:219], v[226:227], v[112:113]
	v_pk_mul_f32 v[220:221], v[228:229], v[112:113]
	v_pk_mul_f32 v[222:223], v[230:231], v[112:113]
	v_cvt_pk_f32_fp8_sdwa v[224:225], v128 src0_sel:WORD_1
	v_cvt_pk_f32_fp8_sdwa v[226:227], v132 src0_sel:WORD_1
	v_cvt_pk_f32_fp8_sdwa v[228:229], v136 src0_sel:WORD_1
	v_cvt_pk_f32_fp8_sdwa v[230:231], v140 src0_sel:WORD_1
	v_pk_fma_f32 v[216:217], v[224:225], v[114:115], v[216:217]
	v_pk_fma_f32 v[218:219], v[226:227], v[114:115], v[218:219]
	v_pk_fma_f32 v[220:221], v[228:229], v[114:115], v[220:221]
	v_pk_fma_f32 v[222:223], v[230:231], v[114:115], v[222:223]
	v_cvt_pk_f32_fp8_e32 v[224:225], v129
	v_cvt_pk_f32_fp8_e32 v[226:227], v133
	v_cvt_pk_f32_fp8_e32 v[228:229], v137
	v_cvt_pk_f32_fp8_e32 v[230:231], v141
	v_pk_fma_f32 v[216:217], v[224:225], v[116:117], v[216:217]
	v_pk_fma_f32 v[218:219], v[226:227], v[116:117], v[218:219]
	v_pk_fma_f32 v[220:221], v[228:229], v[116:117], v[220:221]
	v_pk_fma_f32 v[222:223], v[230:231], v[116:117], v[222:223]
	v_cvt_pk_f32_fp8_sdwa v[224:225], v129 src0_sel:WORD_1
	v_cvt_pk_f32_fp8_sdwa v[226:227], v133 src0_sel:WORD_1
	v_cvt_pk_f32_fp8_sdwa v[228:229], v137 src0_sel:WORD_1
	v_cvt_pk_f32_fp8_sdwa v[230:231], v141 src0_sel:WORD_1
	v_pk_fma_f32 v[216:217], v[224:225], v[118:119], v[216:217]
	v_pk_fma_f32 v[218:219], v[226:227], v[118:119], v[218:219]
	v_pk_fma_f32 v[220:221], v[228:229], v[118:119], v[220:221]
	v_pk_fma_f32 v[222:223], v[230:231], v[118:119], v[222:223]
	v_cvt_pk_f32_fp8_e32 v[224:225], v130
	v_cvt_pk_f32_fp8_e32 v[226:227], v134
	v_cvt_pk_f32_fp8_e32 v[228:229], v138
	v_cvt_pk_f32_fp8_e32 v[230:231], v142
	v_pk_fma_f32 v[216:217], v[224:225], v[120:121], v[216:217]
	v_pk_fma_f32 v[218:219], v[226:227], v[120:121], v[218:219]
	v_pk_fma_f32 v[220:221], v[228:229], v[120:121], v[220:221]
	v_pk_fma_f32 v[222:223], v[230:231], v[120:121], v[222:223]
	v_cvt_pk_f32_fp8_sdwa v[224:225], v130 src0_sel:WORD_1
	v_cvt_pk_f32_fp8_sdwa v[226:227], v134 src0_sel:WORD_1
	v_cvt_pk_f32_fp8_sdwa v[228:229], v138 src0_sel:WORD_1
	v_cvt_pk_f32_fp8_sdwa v[230:231], v142 src0_sel:WORD_1
	v_pk_fma_f32 v[216:217], v[224:225], v[122:123], v[216:217]
	v_pk_fma_f32 v[218:219], v[226:227], v[122:123], v[218:219]
	v_pk_fma_f32 v[220:221], v[228:229], v[122:123], v[220:221]
	v_pk_fma_f32 v[222:223], v[230:231], v[122:123], v[222:223]
	v_cvt_pk_f32_fp8_e32 v[224:225], v131
	v_cvt_pk_f32_fp8_e32 v[226:227], v135
	v_cvt_pk_f32_fp8_e32 v[228:229], v139
	v_cvt_pk_f32_fp8_e32 v[230:231], v143
	v_pk_fma_f32 v[216:217], v[224:225], v[124:125], v[216:217]
	v_pk_fma_f32 v[218:219], v[226:227], v[124:125], v[218:219]
	v_pk_fma_f32 v[220:221], v[228:229], v[124:125], v[220:221]
	v_pk_fma_f32 v[222:223], v[230:231], v[124:125], v[222:223]
	v_cvt_pk_f32_fp8_sdwa v[224:225], v131 src0_sel:WORD_1
	v_cvt_pk_f32_fp8_sdwa v[226:227], v135 src0_sel:WORD_1
	v_cvt_pk_f32_fp8_sdwa v[228:229], v139 src0_sel:WORD_1
	v_cvt_pk_f32_fp8_sdwa v[230:231], v143 src0_sel:WORD_1
	v_pk_fma_f32 v[216:217], v[224:225], v[126:127], v[216:217]
	v_pk_fma_f32 v[218:219], v[226:227], v[126:127], v[218:219]
	v_pk_fma_f32 v[220:221], v[228:229], v[126:127], v[220:221]
	v_pk_fma_f32 v[222:223], v[230:231], v[126:127], v[222:223]
	v_add_f32_e32 v192, v216, v217
	v_add_f32_e32 v193, v218, v219
	v_add_f32_e32 v194, v220, v221
	v_add_f32_e32 v195, v222, v223
	s_sub_i32 s90, s90, 1
	s_cmp_eq_u32 s90, 0
	s_cbranch_scc1 .LU_sw1
.LU_t7_s1:
	s_waitcnt lgkmcnt(0)
	buffer_load_dwordx4 v[128:131], v[232:233], s[56:59], 0 idxen offen
	buffer_load_dwordx4 v[132:135], v[234:235], s[56:59], 0 idxen offen
	buffer_load_dwordx4 v[136:139], v[236:237], s[56:59], 0 idxen offen
	buffer_load_dwordx4 v[140:143], v[238:239], s[56:59], 0 idxen offen
	ds_read_b32 v232, v213 offset:80
	ds_read_b32 v234, v213 offset:84
	ds_read_b32 v236, v213 offset:88
	ds_read_b32 v238, v213 offset:92
	s_waitcnt vmcnt(14)
	v_cvt_pk_f32_fp8_e32 v[224:225], v144
	v_cvt_pk_f32_fp8_e32 v[226:227], v148
	v_cvt_pk_f32_fp8_e32 v[228:229], v152
	v_cvt_pk_f32_fp8_e32 v[230:231], v156
	v_pk_mul_f32 v[216:217], v[224:225], v[112:113]
	v_pk_mul_f32 v[218:219], v[226:227], v[112:113]
	v_pk_mul_f32 v[220:221], v[228:229], v[112:113]
	v_pk_mul_f32 v[222:223], v[230:231], v[112:113]
	v_cvt_pk_f32_fp8_sdwa v[224:225], v144 src0_sel:WORD_1
	v_cvt_pk_f32_fp8_sdwa v[226:227], v148 src0_sel:WORD_1
	v_cvt_pk_f32_fp8_sdwa v[228:229], v152 src0_sel:WORD_1
	v_cvt_pk_f32_fp8_sdwa v[230:231], v156 src0_sel:WORD_1
	v_pk_fma_f32 v[216:217], v[224:225], v[114:115], v[216:217]
	v_pk_fma_f32 v[218:219], v[226:227], v[114:115], v[218:219]
	v_pk_fma_f32 v[220:221], v[228:229], v[114:115], v[220:221]
	v_pk_fma_f32 v[222:223], v[230:231], v[114:115], v[222:223]
	v_cvt_pk_f32_fp8_e32 v[224:225], v145
	v_cvt_pk_f32_fp8_e32 v[226:227], v149
	v_cvt_pk_f32_fp8_e32 v[228:229], v153
	v_cvt_pk_f32_fp8_e32 v[230:231], v157
	v_pk_fma_f32 v[216:217], v[224:225], v[116:117], v[216:217]
	v_pk_fma_f32 v[218:219], v[226:227], v[116:117], v[218:219]
	v_pk_fma_f32 v[220:221], v[228:229], v[116:117], v[220:221]
	v_pk_fma_f32 v[222:223], v[230:231], v[116:117], v[222:223]
	v_cvt_pk_f32_fp8_sdwa v[224:225], v145 src0_sel:WORD_1
	v_cvt_pk_f32_fp8_sdwa v[226:227], v149 src0_sel:WORD_1
	v_cvt_pk_f32_fp8_sdwa v[228:229], v153 src0_sel:WORD_1
	v_cvt_pk_f32_fp8_sdwa v[230:231], v157 src0_sel:WORD_1
	v_pk_fma_f32 v[216:217], v[224:225], v[118:119], v[216:217]
	v_pk_fma_f32 v[218:219], v[226:227], v[118:119], v[218:219]
	v_pk_fma_f32 v[220:221], v[228:229], v[118:119], v[220:221]
	v_pk_fma_f32 v[222:223], v[230:231], v[118:119], v[222:223]
	v_cvt_pk_f32_fp8_e32 v[224:225], v146
	v_cvt_pk_f32_fp8_e32 v[226:227], v150
	v_cvt_pk_f32_fp8_e32 v[228:229], v154
	v_cvt_pk_f32_fp8_e32 v[230:231], v158
	v_pk_fma_f32 v[216:217], v[224:225], v[120:121], v[216:217]
	v_pk_fma_f32 v[218:219], v[226:227], v[120:121], v[218:219]
	v_pk_fma_f32 v[220:221], v[228:229], v[120:121], v[220:221]
	v_pk_fma_f32 v[222:223], v[230:231], v[120:121], v[222:223]
	v_cvt_pk_f32_fp8_sdwa v[224:225], v146 src0_sel:WORD_1
	v_cvt_pk_f32_fp8_sdwa v[226:227], v150 src0_sel:WORD_1
	v_cvt_pk_f32_fp8_sdwa v[228:229], v154 src0_sel:WORD_1
	v_cvt_pk_f32_fp8_sdwa v[230:231], v158 src0_sel:WORD_1
	v_pk_fma_f32 v[216:217], v[224:225], v[122:123], v[216:217]
	v_pk_fma_f32 v[218:219], v[226:227], v[122:123], v[218:219]
	v_pk_fma_f32 v[220:221], v[228:229], v[122:123], v[220:221]
	v_pk_fma_f32 v[222:223], v[230:231], v[122:123], v[222:223]
	v_cvt_pk_f32_fp8_e32 v[224:225], v147
	v_cvt_pk_f32_fp8_e32 v[226:227], v151
	v_cvt_pk_f32_fp8_e32 v[228:229], v155
	v_cvt_pk_f32_fp8_e32 v[230:231], v159
	v_pk_fma_f32 v[216:217], v[224:225], v[124:125], v[216:217]
	v_pk_fma_f32 v[218:219], v[226:227], v[124:125], v[218:219]
	v_pk_fma_f32 v[220:221], v[228:229], v[124:125], v[220:221]
	v_pk_fma_f32 v[222:223], v[230:231], v[124:125], v[222:223]
	v_cvt_pk_f32_fp8_sdwa v[224:225], v147 src0_sel:WORD_1
	v_cvt_pk_f32_fp8_sdwa v[226:227], v151 src0_sel:WORD_1
	v_cvt_pk_f32_fp8_sdwa v[228:229], v155 src0_sel:WORD_1
	v_cvt_pk_f32_fp8_sdwa v[230:231], v159 src0_sel:WORD_1
	v_pk_fma_f32 v[216:217], v[224:225], v[126:127], v[216:217]
	v_pk_fma_f32 v[218:219], v[226:227], v[126:127], v[218:219]
	v_pk_fma_f32 v[220:221], v[228:229], v[126:127], v[220:221]
	v_pk_fma_f32 v[222:223], v[230:231], v[126:127], v[222:223]
	v_add_f32_e32 v196, v216, v217
	v_add_f32_e32 v197, v218, v219
	v_add_f32_e32 v198, v220, v221
	v_add_f32_e32 v199, v222, v223
	s_sub_i32 s90, s90, 1
	s_cmp_eq_u32 s90, 0
	s_cbranch_scc1 .LU_sw2
.LU_t7_s2:
	s_waitcnt lgkmcnt(0)
	buffer_load_dwordx4 v[144:147], v[232:233], s[56:59], 0 idxen offen
	buffer_load_dwordx4 v[148:151], v[234:235], s[56:59], 0 idxen offen
	buffer_load_dwordx4 v[152:155], v[236:237], s[56:59], 0 idxen offen
	buffer_load_dwordx4 v[156:159], v[238:239], s[56:59], 0 idxen offen
	ds_read_b32 v232, v213 offset:96
	ds_read_b32 v234, v213 offset:100
	ds_read_b32 v236, v213 offset:104
	ds_read_b32 v238, v213 offset:108
	s_waitcnt vmcnt(14)
	v_cvt_pk_f32_fp8_e32 v[224:225], v160
	v_cvt_pk_f32_fp8_e32 v[226:227], v164
	v_cvt_pk_f32_fp8_e32 v[228:229], v168
	v_cvt_pk_f32_fp8_e32 v[230:231], v172
	v_pk_mul_f32 v[216:217], v[224:225], v[112:113]
	v_pk_mul_f32 v[218:219], v[226:227], v[112:113]
	v_pk_mul_f32 v[220:221], v[228:229], v[112:113]
	v_pk_mul_f32 v[222:223], v[230:231], v[112:113]
	v_cvt_pk_f32_fp8_sdwa v[224:225], v160 src0_sel:WORD_1
	v_cvt_pk_f32_fp8_sdwa v[226:227], v164 src0_sel:WORD_1
	v_cvt_pk_f32_fp8_sdwa v[228:229], v168 src0_sel:WORD_1
	v_cvt_pk_f32_fp8_sdwa v[230:231], v172 src0_sel:WORD_1
	v_pk_fma_f32 v[216:217], v[224:225], v[114:115], v[216:217]
	v_pk_fma_f32 v[218:219], v[226:227], v[114:115], v[218:219]
	v_pk_fma_f32 v[220:221], v[228:229], v[114:115], v[220:221]
	v_pk_fma_f32 v[222:223], v[230:231], v[114:115], v[222:223]
	v_cvt_pk_f32_fp8_e32 v[224:225], v161
	v_cvt_pk_f32_fp8_e32 v[226:227], v165
	v_cvt_pk_f32_fp8_e32 v[228:229], v169
	v_cvt_pk_f32_fp8_e32 v[230:231], v173
	v_pk_fma_f32 v[216:217], v[224:225], v[116:117], v[216:217]
	v_pk_fma_f32 v[218:219], v[226:227], v[116:117], v[218:219]
	v_pk_fma_f32 v[220:221], v[228:229], v[116:117], v[220:221]
	v_pk_fma_f32 v[222:223], v[230:231], v[116:117], v[222:223]
	v_cvt_pk_f32_fp8_sdwa v[224:225], v161 src0_sel:WORD_1
	v_cvt_pk_f32_fp8_sdwa v[226:227], v165 src0_sel:WORD_1
	v_cvt_pk_f32_fp8_sdwa v[228:229], v169 src0_sel:WORD_1
	v_cvt_pk_f32_fp8_sdwa v[230:231], v173 src0_sel:WORD_1
	v_pk_fma_f32 v[216:217], v[224:225], v[118:119], v[216:217]
	v_pk_fma_f32 v[218:219], v[226:227], v[118:119], v[218:219]
	v_pk_fma_f32 v[220:221], v[228:229], v[118:119], v[220:221]
	v_pk_fma_f32 v[222:223], v[230:231], v[118:119], v[222:223]
	v_cvt_pk_f32_fp8_e32 v[224:225], v162
	v_cvt_pk_f32_fp8_e32 v[226:227], v166
	v_cvt_pk_f32_fp8_e32 v[228:229], v170
	v_cvt_pk_f32_fp8_e32 v[230:231], v174
	v_pk_fma_f32 v[216:217], v[224:225], v[120:121], v[216:217]
	v_pk_fma_f32 v[218:219], v[226:227], v[120:121], v[218:219]
	v_pk_fma_f32 v[220:221], v[228:229], v[120:121], v[220:221]
	v_pk_fma_f32 v[222:223], v[230:231], v[120:121], v[222:223]
	v_cvt_pk_f32_fp8_sdwa v[224:225], v162 src0_sel:WORD_1
	v_cvt_pk_f32_fp8_sdwa v[226:227], v166 src0_sel:WORD_1
	v_cvt_pk_f32_fp8_sdwa v[228:229], v170 src0_sel:WORD_1
	v_cvt_pk_f32_fp8_sdwa v[230:231], v174 src0_sel:WORD_1
	v_pk_fma_f32 v[216:217], v[224:225], v[122:123], v[216:217]
	v_pk_fma_f32 v[218:219], v[226:227], v[122:123], v[218:219]
	v_pk_fma_f32 v[220:221], v[228:229], v[122:123], v[220:221]
	v_pk_fma_f32 v[222:223], v[230:231], v[122:123], v[222:223]
	v_cvt_pk_f32_fp8_e32 v[224:225], v163
	v_cvt_pk_f32_fp8_e32 v[226:227], v167
	v_cvt_pk_f32_fp8_e32 v[228:229], v171
	v_cvt_pk_f32_fp8_e32 v[230:231], v175
	v_pk_fma_f32 v[216:217], v[224:225], v[124:125], v[216:217]
	v_pk_fma_f32 v[218:219], v[226:227], v[124:125], v[218:219]
	v_pk_fma_f32 v[220:221], v[228:229], v[124:125], v[220:221]
	v_pk_fma_f32 v[222:223], v[230:231], v[124:125], v[222:223]
	v_cvt_pk_f32_fp8_sdwa v[224:225], v163 src0_sel:WORD_1
	v_cvt_pk_f32_fp8_sdwa v[226:227], v167 src0_sel:WORD_1
	v_cvt_pk_f32_fp8_sdwa v[228:229], v171 src0_sel:WORD_1
	v_cvt_pk_f32_fp8_sdwa v[230:231], v175 src0_sel:WORD_1
	v_pk_fma_f32 v[216:217], v[224:225], v[126:127], v[216:217]
	v_pk_fma_f32 v[218:219], v[226:227], v[126:127], v[218:219]
	v_pk_fma_f32 v[220:221], v[228:229], v[126:127], v[220:221]
	v_pk_fma_f32 v[222:223], v[230:231], v[126:127], v[222:223]
	v_add_f32_e32 v200, v216, v217
	v_add_f32_e32 v201, v218, v219
	v_add_f32_e32 v202, v220, v221
	v_add_f32_e32 v203, v222, v223
	s_sub_i32 s90, s90, 1
	s_cmp_eq_u32 s90, 0
	s_cbranch_scc1 .LU_sw3
.LU_t7_s3:
	s_waitcnt lgkmcnt(0)
	buffer_load_dwordx4 v[160:163], v[232:233], s[56:59], 0 idxen offen
	buffer_load_dwordx4 v[164:167], v[234:235], s[56:59], 0 idxen offen
	buffer_load_dwordx4 v[168:171], v[236:237], s[56:59], 0 idxen offen
	buffer_load_dwordx4 v[172:175], v[238:239], s[56:59], 0 idxen offen
	ds_read_b32 v232, v213 offset:112
	ds_read_b32 v234, v213 offset:116
	ds_read_b32 v236, v213 offset:120
	ds_read_b32 v238, v213 offset:124
	s_waitcnt vmcnt(12)
	v_cvt_pk_f32_fp8_e32 v[224:225], v176
	v_cvt_pk_f32_fp8_e32 v[226:227], v180
	v_cvt_pk_f32_fp8_e32 v[228:229], v184
	v_cvt_pk_f32_fp8_e32 v[230:231], v188
	v_pk_mul_f32 v[216:217], v[224:225], v[112:113]
	v_pk_mul_f32 v[218:219], v[226:227], v[112:113]
	v_pk_mul_f32 v[220:221], v[228:229], v[112:113]
	v_pk_mul_f32 v[222:223], v[230:231], v[112:113]
	v_cvt_pk_f32_fp8_sdwa v[224:225], v176 src0_sel:WORD_1
	v_cvt_pk_f32_fp8_sdwa v[226:227], v180 src0_sel:WORD_1
	v_cvt_pk_f32_fp8_sdwa v[228:229], v184 src0_sel:WORD_1
	v_cvt_pk_f32_fp8_sdwa v[230:231], v188 src0_sel:WORD_1
	v_pk_fma_f32 v[216:217], v[224:225], v[114:115], v[216:217]
	v_pk_fma_f32 v[218:219], v[226:227], v[114:115], v[218:219]
	v_pk_fma_f32 v[220:221], v[228:229], v[114:115], v[220:221]
	v_pk_fma_f32 v[222:223], v[230:231], v[114:115], v[222:223]
	v_cvt_pk_f32_fp8_e32 v[224:225], v177
	v_cvt_pk_f32_fp8_e32 v[226:227], v181
	v_cvt_pk_f32_fp8_e32 v[228:229], v185
	v_cvt_pk_f32_fp8_e32 v[230:231], v189
	v_pk_fma_f32 v[216:217], v[224:225], v[116:117], v[216:217]
	v_pk_fma_f32 v[218:219], v[226:227], v[116:117], v[218:219]
	v_pk_fma_f32 v[220:221], v[228:229], v[116:117], v[220:221]
	v_pk_fma_f32 v[222:223], v[230:231], v[116:117], v[222:223]
	v_cvt_pk_f32_fp8_sdwa v[224:225], v177 src0_sel:WORD_1
	v_cvt_pk_f32_fp8_sdwa v[226:227], v181 src0_sel:WORD_1
	v_cvt_pk_f32_fp8_sdwa v[228:229], v185 src0_sel:WORD_1
	v_cvt_pk_f32_fp8_sdwa v[230:231], v189 src0_sel:WORD_1
	v_pk_fma_f32 v[216:217], v[224:225], v[118:119], v[216:217]
	v_pk_fma_f32 v[218:219], v[226:227], v[118:119], v[218:219]
	v_pk_fma_f32 v[220:221], v[228:229], v[118:119], v[220:221]
	v_pk_fma_f32 v[222:223], v[230:231], v[118:119], v[222:223]
	v_cvt_pk_f32_fp8_e32 v[224:225], v178
	v_cvt_pk_f32_fp8_e32 v[226:227], v182
	v_cvt_pk_f32_fp8_e32 v[228:229], v186
	v_cvt_pk_f32_fp8_e32 v[230:231], v190
	v_pk_fma_f32 v[216:217], v[224:225], v[120:121], v[216:217]
	v_pk_fma_f32 v[218:219], v[226:227], v[120:121], v[218:219]
	v_pk_fma_f32 v[220:221], v[228:229], v[120:121], v[220:221]
	v_pk_fma_f32 v[222:223], v[230:231], v[120:121], v[222:223]
	v_cvt_pk_f32_fp8_sdwa v[224:225], v178 src0_sel:WORD_1
	v_cvt_pk_f32_fp8_sdwa v[226:227], v182 src0_sel:WORD_1
	v_cvt_pk_f32_fp8_sdwa v[228:229], v186 src0_sel:WORD_1
	v_cvt_pk_f32_fp8_sdwa v[230:231], v190 src0_sel:WORD_1
	v_pk_fma_f32 v[216:217], v[224:225], v[122:123], v[216:217]
	v_pk_fma_f32 v[218:219], v[226:227], v[122:123], v[218:219]
	v_pk_fma_f32 v[220:221], v[228:229], v[122:123], v[220:221]
	v_pk_fma_f32 v[222:223], v[230:231], v[122:123], v[222:223]
	v_cvt_pk_f32_fp8_e32 v[224:225], v179
	v_cvt_pk_f32_fp8_e32 v[226:227], v183
	v_cvt_pk_f32_fp8_e32 v[228:229], v187
	v_cvt_pk_f32_fp8_e32 v[230:231], v191
	v_pk_fma_f32 v[216:217], v[224:225], v[124:125], v[216:217]
	v_pk_fma_f32 v[218:219], v[226:227], v[124:125], v[218:219]
	v_pk_fma_f32 v[220:221], v[228:229], v[124:125], v[220:221]
	v_pk_fma_f32 v[222:223], v[230:231], v[124:125], v[222:223]
	v_cvt_pk_f32_fp8_sdwa v[224:225], v179 src0_sel:WORD_1
	v_cvt_pk_f32_fp8_sdwa v[226:227], v183 src0_sel:WORD_1
	v_cvt_pk_f32_fp8_sdwa v[228:229], v187 src0_sel:WORD_1
	v_cvt_pk_f32_fp8_sdwa v[230:231], v191 src0_sel:WORD_1
	v_pk_fma_f32 v[216:217], v[224:225], v[126:127], v[216:217]
	v_pk_fma_f32 v[218:219], v[226:227], v[126:127], v[218:219]
	v_pk_fma_f32 v[220:221], v[228:229], v[126:127], v[220:221]
	v_pk_fma_f32 v[222:223], v[230:231], v[126:127], v[222:223]
	v_add_f32_e32 v204, v216, v217
	v_add_f32_e32 v205, v218, v219
	v_add_f32_e32 v206, v220, v221
	v_add_f32_e32 v207, v222, v223
	s_nop 0
	v_permlane32_swap_b32_e32 v192, v200
	v_permlane32_swap_b32_e32 v193, v201
	v_permlane32_swap_b32_e32 v194, v202
	v_permlane32_swap_b32_e32 v195, v203
	v_permlane32_swap_b32_e32 v196, v204
	v_permlane32_swap_b32_e32 v197, v205
	v_permlane32_swap_b32_e32 v198, v206
	v_permlane32_swap_b32_e32 v199, v207
	v_add_f32_e32 v192, v192, v200
	v_add_f32_e32 v193, v193, v201
	v_add_f32_e32 v194, v194, v202
	v_add_f32_e32 v195, v195, v203
	v_add_f32_e32 v196, v196, v204
	v_add_f32_e32 v197, v197, v205
	v_add_f32_e32 v198, v198, v206
	v_add_f32_e32 v199, v199, v207
	v_permlane16_swap_b32_e32 v192, v196
	v_permlane16_swap_b32_e32 v193, v197
	v_permlane16_swap_b32_e32 v194, v198
	v_permlane16_swap_b32_e32 v195, v199
	v_add_f32_e32 v192, v192, v196
	v_add_f32_e32 v193, v193, v197
	v_add_f32_e32 v194, v194, v198
	v_add_f32_e32 v195, v195, v199
	v_add_f32_dpp v216, v192, v192 row_ror:8 row_mask:0xf bank_mask:0xf
	v_add_f32_dpp v218, v194, v194 row_ror:8 row_mask:0xf bank_mask:0xf
	v_add_f32_dpp v216, v193, v193 row_ror:8 row_mask:0xf bank_mask:0xc
	v_add_f32_dpp v218, v195, v195 row_ror:8 row_mask:0xf bank_mask:0xc
	s_nop 1
	v_add_f32_dpp v220, v216, v216 row_half_mirror row_mask:0xf bank_mask:0xf
	v_add_f32_dpp v220, v218, v218 row_half_mirror row_mask:0xf bank_mask:0xa
	s_nop 1
	v_add_f32_dpp v220, v220, v220 quad_perm:[1,0,3,2] row_mask:0xf bank_mask:0xf
	s_nop 1
	v_add_f32_dpp v220, v220, v220 quad_perm:[2,3,0,1] row_mask:0xf bank_mask:0xf
	v_mul_f32_e32 v216, v252, v220
	v_fma_f32 v218, |v216|, s72, 1.0
	v_mul_f32_e32 v222, v216, v216
	v_rcp_f32_e32 v218, v218
	v_mul_f32_e32 v222, 0xbf38aa3b, v222
	v_exp_f32_e32 v222, v222
	v_fmamk_f32 v224, v218, 0x3f07dc22, v242
	v_fmaak_f32 v224, v218, v224, 0x3f35f0e3
	v_fmaak_f32 v224, v218, v224, 0xbe11a98e
	v_fmaak_f32 v224, v218, v224, 0x3e027906
	v_mul_f32_e32 v224, v218, v224
	v_mul_f32_e32 v224, v222, v224
	v_mul_f32_e32 v226, v216, v224
	v_fma_f32 v224, -v216, v224, v216
	v_cmp_gt_f32_e32 vcc, 0, v216
	s_nop 1
	v_cndmask_b32_e32 v224, v224, v226, vcc
	v_mul_f32_e32 v224, v249, v224
	v_mul_f32_e32 v224, v253, v224
	ds_write_b32 v211, v224 offset:4992
	v_add_u32_e32 v211, 64, v211
	v_add_u32_e32 v213, 64, v213
	ds_read_b32 v248, v211
	ds_read_b32 v249, v211 offset:4992
	s_add_i32 s21, s21, 4
	s_sub_i32 s90, s90, 1
	s_cmp_eq_u32 s90, 0
	s_cbranch_scc1 .LU_sw0
	s_branch .LU_t7_s0

; #define IT_ADVANCE() do { it_j += 4; while (it_j >= it_end) { if (it_done) break; ++it_tk; if (it_tk == 4) { it_tk = 0; ++it_p; if (it_p == 16) { it_done = true; it_p = 15; it_j = 0; it_end = 1; break; } } \
;             it_j = __builtin_amdgcn_readfirstlane(OFFS[(tb + it_tk) * 17 + it_p]); it_end = __builtin_amdgcn_readfirstlane(OFFS[(tb + it_tk) * 17 + it_p + 1]); } } while (0)
; __device__ __forceinline__ void peer_tile(const Args& A, LAS unsigned char* lds, int tile) {
;     ...
;             for (int q = 0; q < 8; ++q) oacc[tk][q] = (f32x2){0.f, 0.f}; }
;         int it_p = 0, it_tk = -1, it_j = 0, it_end = 0; bool it_done = false;
;     ...
;         u32x4 uA[4], vA[4], uB[4], vB[4]; float cgA = 0.f, suA = 0.f, svA = 0.f, cgB = 0.f, suB = 0.f, svB = 0.f;
; #pragma unroll
;         for (int k = 0; k < 4; ++k) { uA[k] = (u32x4){0u, 0u, 0u, 0u}; vA[k] = uA[k]; uB[k] = uA[k]; vB[k] = uA[k]; }
;         IT_ADVANCE();
;         LOAD_SET(uA, vA, cgA, suA, svA);
.LU_done:
	s_waitcnt vmcnt(0) lgkmcnt(0)
	v_mov_b64_e32 v[0:1], 0
	v_mov_b64_e32 v[2:3], 0
	v_mov_b64_e32 v[4:5], 0
	v_mov_b64_e32 v[6:7], 0
	v_mov_b64_e32 v[8:9], 0
	v_mov_b64_e32 v[10:11], 0
	v_mov_b64_e32 v[12:13], 0
	v_mov_b64_e32 v[14:15], 0
	v_mov_b64_e32 v[16:17], 0
	v_mov_b64_e32 v[18:19], 0
	v_mov_b64_e32 v[20:21], 0
	v_mov_b64_e32 v[22:23], 0
	v_mov_b64_e32 v[24:25], 0
	v_mov_b64_e32 v[26:27], 0
	v_mov_b64_e32 v[28:29], 0
	v_mov_b64_e32 v[30:31], 0
	v_mov_b64_e32 v[32:33], 0
	v_mov_b64_e32 v[34:35], 0
	v_mov_b64_e32 v[36:37], 0
	v_mov_b64_e32 v[38:39], 0
	v_mov_b64_e32 v[40:41], 0
	v_mov_b64_e32 v[42:43], 0
	v_mov_b64_e32 v[44:45], 0
	v_mov_b64_e32 v[46:47], 0
	v_mov_b64_e32 v[48:49], 0
	v_mov_b64_e32 v[50:51], 0
	v_mov_b64_e32 v[52:53], 0
	v_mov_b64_e32 v[54:55], 0
	v_mov_b64_e32 v[56:57], 0
	v_mov_b64_e32 v[58:59], 0
	v_mov_b64_e32 v[60:61], 0
	v_mov_b64_e32 v[62:63], 0
	v_mov_b64_e32 v[64:65], 0
	v_mov_b64_e32 v[66:67], 0
	v_mov_b64_e32 v[68:69], 0
	v_mov_b64_e32 v[70:71], 0
	v_mov_b64_e32 v[72:73], 0
	v_mov_b64_e32 v[74:75], 0
	v_mov_b64_e32 v[76:77], 0
	v_mov_b64_e32 v[78:79], 0
	v_mov_b64_e32 v[80:81], 0
	v_mov_b64_e32 v[82:83], 0
	v_mov_b64_e32 v[84:85], 0
	v_mov_b64_e32 v[86:87], 0
	v_mov_b64_e32 v[88:89], 0
	v_mov_b64_e32 v[90:91], 0
	v_mov_b64_e32 v[92:93], 0
	v_mov_b64_e32 v[94:95], 0
	v_mov_b64_e32 v[96:97], 0
	v_mov_b64_e32 v[98:99], 0
	v_mov_b64_e32 v[100:101], 0
	v_mov_b64_e32 v[102:103], 0
	v_mov_b64_e32 v[104:105], 0
	v_mov_b64_e32 v[106:107], 0
	v_mov_b64_e32 v[108:109], 0
	v_mov_b64_e32 v[110:111], 0
	v_mov_b64_e32 v[112:113], 0
	v_mov_b64_e32 v[114:115], 0
	v_mov_b64_e32 v[116:117], 0
	v_mov_b64_e32 v[118:119], 0
	v_mov_b64_e32 v[120:121], 0
	v_mov_b64_e32 v[122:123], 0
	v_mov_b64_e32 v[124:125], 0
	v_mov_b64_e32 v[126:127], 0
	s_add_i32 s20, s91, 3
	s_and_b32 s20, s20, -4
	s_waitcnt vmcnt(0) lgkmcnt(0)
	v_mov_b32_e32 v213, s22
	v_mov_b32_e32 v233, v240
	v_mov_b32_e32 v235, v240
	v_mov_b32_e32 v237, v240
	v_mov_b32_e32 v239, v240
	ds_read_b32 v232, v213 offset:0
	ds_read_b32 v234, v213 offset:4
	ds_read_b32 v236, v213 offset:8
	ds_read_b32 v238, v213 offset:12
	s_waitcnt lgkmcnt(0)
	buffer_load_dwordx4 v[128:131], v[232:233], s[60:63], 0 idxen offen
	buffer_load_dwordx4 v[132:135], v[234:235], s[60:63], 0 idxen offen
	buffer_load_dwordx4 v[136:139], v[236:237], s[60:63], 0 idxen offen
	buffer_load_dwordx4 v[140:143], v[238:239], s[60:63], 0 idxen offen
	ds_read_b32 v232, v213 offset:16
	ds_read_b32 v234, v213 offset:20
	ds_read_b32 v236, v213 offset:24
	ds_read_b32 v238, v213 offset:28
	s_waitcnt lgkmcnt(0)
	buffer_load_dwordx4 v[144:147], v[232:233], s[60:63], 0 idxen offen
	buffer_load_dwordx4 v[148:151], v[234:235], s[60:63], 0 idxen offen
	buffer_load_dwordx4 v[152:155], v[236:237], s[60:63], 0 idxen offen
	buffer_load_dwordx4 v[156:159], v[238:239], s[60:63], 0 idxen offen
	ds_read_b32 v232, v213 offset:32
	ds_read_b32 v234, v213 offset:36
	ds_read_b32 v236, v213 offset:40
	ds_read_b32 v238, v213 offset:44
	s_waitcnt lgkmcnt(0)
	buffer_load_dwordx4 v[160:163], v[232:233], s[60:63], 0 idxen offen
	buffer_load_dwordx4 v[164:167], v[234:235], s[60:63], 0 idxen offen
	buffer_load_dwordx4 v[168:171], v[236:237], s[60:63], 0 idxen offen
	buffer_load_dwordx4 v[172:175], v[238:239], s[60:63], 0 idxen offen
	ds_read_b128 v[248:251], v213 offset:4992
	ds_read_b32 v232, v213 offset:48
	ds_read_b32 v234, v213 offset:52
	ds_read_b32 v236, v213 offset:56
	ds_read_b32 v238, v213 offset:60
	s_mov_b32 s21, 0
	s_mov_b32 s89, -1
	s_branch .LV_sw0
.LV_t0_s0:
	s_cmp_ge_u32 s21, s20
	s_cbranch_scc1 .LV_done
	s_waitcnt lgkmcnt(0)
	buffer_load_dwordx4 v[176:179], v[232:233], s[60:63], 0 idxen offen
	buffer_load_dwordx4 v[180:183], v[234:235], s[60:63], 0 idxen offen
	buffer_load_dwordx4 v[184:187], v[236:237], s[60:63], 0 idxen offen
	buffer_load_dwordx4 v[188:191], v[238:239], s[60:63], 0 idxen offen
	ds_read_b32 v232, v213 offset:64
	ds_read_b32 v234, v213 offset:68
	ds_read_b32 v236, v213 offset:72
	ds_read_b32 v238, v213 offset:76
	ds_read_b128 v[252:255], v213 offset:5008
	s_waitcnt vmcnt(12)
	v_cvt_pk_f32_fp8_e32 v[224:225], v128
	v_cvt_pk_f32_fp8_sdwa v[226:227], v128 src0_sel:WORD_1
	v_cvt_pk_f32_fp8_e32 v[228:229], v129
	v_cvt_pk_f32_fp8_sdwa v[230:231], v129 src0_sel:WORD_1
	v_pk_fma_f32 v[0:1], v[224:225], v[248:249], v[0:1] op_sel_hi:[1,0,1]
	v_pk_fma_f32 v[2:3], v[226:227], v[248:249], v[2:3] op_sel_hi:[1,0,1]
	v_pk_fma_f32 v[4:5], v[228:229], v[248:249], v[4:5] op_sel_hi:[1,0,1]
	v_pk_fma_f32 v[6:7], v[230:231], v[248:249], v[6:7] op_sel_hi:[1,0,1]
	v_cvt_pk_f32_fp8_e32 v[224:225], v130
	v_cvt_pk_f32_fp8_sdwa v[226:227], v130 src0_sel:WORD_1
	v_cvt_pk_f32_fp8_e32 v[228:229], v131
	v_cvt_pk_f32_fp8_sdwa v[230:231], v131 src0_sel:WORD_1
	v_pk_fma_f32 v[8:9], v[224:225], v[248:249], v[8:9] op_sel_hi:[1,0,1]
	v_pk_fma_f32 v[10:11], v[226:227], v[248:249], v[10:11] op_sel_hi:[1,0,1]
	v_pk_fma_f32 v[12:13], v[228:229], v[248:249], v[12:13] op_sel_hi:[1,0,1]
	v_pk_fma_f32 v[14:15], v[230:231], v[248:249], v[14:15] op_sel_hi:[1,0,1]
	v_cvt_pk_f32_fp8_e32 v[224:225], v132
	v_cvt_pk_f32_fp8_sdwa v[226:227], v132 src0_sel:WORD_1
	v_cvt_pk_f32_fp8_e32 v[228:229], v133
	v_cvt_pk_f32_fp8_sdwa v[230:231], v133 src0_sel:WORD_1
	v_pk_fma_f32 v[0:1], v[224:225], v[248:249], v[0:1] op_sel:[0,1,0] op_sel_hi:[1,1,1]
	v_pk_fma_f32 v[2:3], v[226:227], v[248:249], v[2:3] op_sel:[0,1,0] op_sel_hi:[1,1,1]
	v_pk_fma_f32 v[4:5], v[228:229], v[248:249], v[4:5] op_sel:[0,1,0] op_sel_hi:[1,1,1]
	v_pk_fma_f32 v[6:7], v[230:231], v[248:249], v[6:7] op_sel:[0,1,0] op_sel_hi:[1,1,1]
	v_cvt_pk_f32_fp8_e32 v[224:225], v134
	v_cvt_pk_f32_fp8_sdwa v[226:227], v134 src0_sel:WORD_1
	v_cvt_pk_f32_fp8_e32 v[228:229], v135
	v_cvt_pk_f32_fp8_sdwa v[230:231], v135 src0_sel:WORD_1
	v_pk_fma_f32 v[8:9], v[224:225], v[248:249], v[8:9] op_sel:[0,1,0] op_sel_hi:[1,1,1]
	v_pk_fma_f32 v[10:11], v[226:227], v[248:249], v[10:11] op_sel:[0,1,0] op_sel_hi:[1,1,1]
	v_pk_fma_f32 v[12:13], v[228:229], v[248:249], v[12:13] op_sel:[0,1,0] op_sel_hi:[1,1,1]
	v_pk_fma_f32 v[14:15], v[230:231], v[248:249], v[14:15] op_sel:[0,1,0] op_sel_hi:[1,1,1]
	v_cvt_pk_f32_fp8_e32 v[224:225], v136
	v_cvt_pk_f32_fp8_sdwa v[226:227], v136 src0_sel:WORD_1
	v_cvt_pk_f32_fp8_e32 v[228:229], v137
	v_cvt_pk_f32_fp8_sdwa v[230:231], v137 src0_sel:WORD_1
	v_pk_fma_f32 v[0:1], v[224:225], v[250:251], v[0:1] op_sel_hi:[1,0,1]
	v_pk_fma_f32 v[2:3], v[226:227], v[250:251], v[2:3] op_sel_hi:[1,0,1]
	v_pk_fma_f32 v[4:5], v[228:229], v[250:251], v[4:5] op_sel_hi:[1,0,1]
	v_pk_fma_f32 v[6:7], v[230:231], v[250:251], v[6:7] op_sel_hi:[1,0,1]
	v_cvt_pk_f32_fp8_e32 v[224:225], v138
	v_cvt_pk_f32_fp8_sdwa v[226:227], v138 src0_sel:WORD_1
	v_cvt_pk_f32_fp8_e32 v[228:229], v139
	v_cvt_pk_f32_fp8_sdwa v[230:231], v139 src0_sel:WORD_1
	v_pk_fma_f32 v[8:9], v[224:225], v[250:251], v[8:9] op_sel_hi:[1,0,1]
	v_pk_fma_f32 v[10:11], v[226:227], v[250:251], v[10:11] op_sel_hi:[1,0,1]
	v_pk_fma_f32 v[12:13], v[228:229], v[250:251], v[12:13] op_sel_hi:[1,0,1]
	v_pk_fma_f32 v[14:15], v[230:231], v[250:251], v[14:15] op_sel_hi:[1,0,1]
	v_cvt_pk_f32_fp8_e32 v[224:225], v140
	v_cvt_pk_f32_fp8_sdwa v[226:227], v140 src0_sel:WORD_1
	v_cvt_pk_f32_fp8_e32 v[228:229], v141
	v_cvt_pk_f32_fp8_sdwa v[230:231], v141 src0_sel:WORD_1
	v_pk_fma_f32 v[0:1], v[224:225], v[250:251], v[0:1] op_sel:[0,1,0] op_sel_hi:[1,1,1]
	v_pk_fma_f32 v[2:3], v[226:227], v[250:251], v[2:3] op_sel:[0,1,0] op_sel_hi:[1,1,1]
	v_pk_fma_f32 v[4:5], v[228:229], v[250:251], v[4:5] op_sel:[0,1,0] op_sel_hi:[1,1,1]
	v_pk_fma_f32 v[6:7], v[230:231], v[250:251], v[6:7] op_sel:[0,1,0] op_sel_hi:[1,1,1]
	v_cvt_pk_f32_fp8_e32 v[224:225], v142
	v_cvt_pk_f32_fp8_sdwa v[226:227], v142 src0_sel:WORD_1
	v_cvt_pk_f32_fp8_e32 v[228:229], v143
	v_cvt_pk_f32_fp8_sdwa v[230:231], v143 src0_sel:WORD_1
	v_pk_fma_f32 v[8:9], v[224:225], v[250:251], v[8:9] op_sel:[0,1,0] op_sel_hi:[1,1,1]
	v_pk_fma_f32 v[10:11], v[226:227], v[250:251], v[10:11] op_sel:[0,1,0] op_sel_hi:[1,1,1]
	v_pk_fma_f32 v[12:13], v[228:229], v[250:251], v[12:13] op_sel:[0,1,0] op_sel_hi:[1,1,1]
	v_pk_fma_f32 v[14:15], v[230:231], v[250:251], v[14:15] op_sel:[0,1,0] op_sel_hi:[1,1,1]
	s_sub_i32 s90, s90, 1
	s_cmp_eq_u32 s90, 0
	s_cbranch_scc1 .LV_sw1
.LV_t0_s1:
	s_waitcnt lgkmcnt(0)
	buffer_load_dwordx4 v[128:131], v[232:233], s[60:63], 0 idxen offen
	buffer_load_dwordx4 v[132:135], v[234:235], s[60:63], 0 idxen offen
	buffer_load_dwordx4 v[136:139], v[236:237], s[60:63], 0 idxen offen
	buffer_load_dwordx4 v[140:143], v[238:239], s[60:63], 0 idxen offen
	ds_read_b32 v232, v213 offset:80
	ds_read_b32 v234, v213 offset:84
	ds_read_b32 v236, v213 offset:88
	ds_read_b32 v238, v213 offset:92
	ds_read_b128 v[248:251], v213 offset:5024
	s_waitcnt vmcnt(12)
	v_cvt_pk_f32_fp8_e32 v[224:225], v144
	v_cvt_pk_f32_fp8_sdwa v[226:227], v144 src0_sel:WORD_1
	v_cvt_pk_f32_fp8_e32 v[228:229], v145
	v_cvt_pk_f32_fp8_sdwa v[230:231], v145 src0_sel:WORD_1
	v_pk_fma_f32 v[0:1], v[224:225], v[252:253], v[0:1] op_sel_hi:[1,0,1]
	v_pk_fma_f32 v[2:3], v[226:227], v[252:253], v[2:3] op_sel_hi:[1,0,1]
	v_pk_fma_f32 v[4:5], v[228:229], v[252:253], v[4:5] op_sel_hi:[1,0,1]
	v_pk_fma_f32 v[6:7], v[230:231], v[252:253], v[6:7] op_sel_hi:[1,0,1]
	v_cvt_pk_f32_fp8_e32 v[224:225], v146
	v_cvt_pk_f32_fp8_sdwa v[226:227], v146 src0_sel:WORD_1
	v_cvt_pk_f32_fp8_e32 v[228:229], v147
	v_cvt_pk_f32_fp8_sdwa v[230:231], v147 src0_sel:WORD_1
	v_pk_fma_f32 v[8:9], v[224:225], v[252:253], v[8:9] op_sel_hi:[1,0,1]
	v_pk_fma_f32 v[10:11], v[226:227], v[252:253], v[10:11] op_sel_hi:[1,0,1]
	v_pk_fma_f32 v[12:13], v[228:229], v[252:253], v[12:13] op_sel_hi:[1,0,1]
	v_pk_fma_f32 v[14:15], v[230:231], v[252:253], v[14:15] op_sel_hi:[1,0,1]
	v_cvt_pk_f32_fp8_e32 v[224:225], v148
	v_cvt_pk_f32_fp8_sdwa v[226:227], v148 src0_sel:WORD_1
	v_cvt_pk_f32_fp8_e32 v[228:229], v149
	v_cvt_pk_f32_fp8_sdwa v[230:231], v149 src0_sel:WORD_1
	v_pk_fma_f32 v[0:1], v[224:225], v[252:253], v[0:1] op_sel:[0,1,0] op_sel_hi:[1,1,1]
	v_pk_fma_f32 v[2:3], v[226:227], v[252:253], v[2:3] op_sel:[0,1,0] op_sel_hi:[1,1,1]
	v_pk_fma_f32 v[4:5], v[228:229], v[252:253], v[4:5] op_sel:[0,1,0] op_sel_hi:[1,1,1]
	v_pk_fma_f32 v[6:7], v[230:231], v[252:253], v[6:7] op_sel:[0,1,0] op_sel_hi:[1,1,1]
	v_cvt_pk_f32_fp8_e32 v[224:225], v150
	v_cvt_pk_f32_fp8_sdwa v[226:227], v150 src0_sel:WORD_1
	v_cvt_pk_f32_fp8_e32 v[228:229], v151
	v_cvt_pk_f32_fp8_sdwa v[230:231], v151 src0_sel:WORD_1
	v_pk_fma_f32 v[8:9], v[224:225], v[252:253], v[8:9] op_sel:[0,1,0] op_sel_hi:[1,1,1]
	v_pk_fma_f32 v[10:11], v[226:227], v[252:253], v[10:11] op_sel:[0,1,0] op_sel_hi:[1,1,1]
	v_pk_fma_f32 v[12:13], v[228:229], v[252:253], v[12:13] op_sel:[0,1,0] op_sel_hi:[1,1,1]
	v_pk_fma_f32 v[14:15], v[230:231], v[252:253], v[14:15] op_sel:[0,1,0] op_sel_hi:[1,1,1]
	v_cvt_pk_f32_fp8_e32 v[224:225], v152
	v_cvt_pk_f32_fp8_sdwa v[226:227], v152 src0_sel:WORD_1
	v_cvt_pk_f32_fp8_e32 v[228:229], v153
	v_cvt_pk_f32_fp8_sdwa v[230:231], v153 src0_sel:WORD_1
	v_pk_fma_f32 v[0:1], v[224:225], v[254:255], v[0:1] op_sel_hi:[1,0,1]
	v_pk_fma_f32 v[2:3], v[226:227], v[254:255], v[2:3] op_sel_hi:[1,0,1]
	v_pk_fma_f32 v[4:5], v[228:229], v[254:255], v[4:5] op_sel_hi:[1,0,1]
	v_pk_fma_f32 v[6:7], v[230:231], v[254:255], v[6:7] op_sel_hi:[1,0,1]
	v_cvt_pk_f32_fp8_e32 v[224:225], v154
	v_cvt_pk_f32_fp8_sdwa v[226:227], v154 src0_sel:WORD_1
	v_cvt_pk_f32_fp8_e32 v[228:229], v155
	v_cvt_pk_f32_fp8_sdwa v[230:231], v155 src0_sel:WORD_1
	v_pk_fma_f32 v[8:9], v[224:225], v[254:255], v[8:9] op_sel_hi:[1,0,1]
	v_pk_fma_f32 v[10:11], v[226:227], v[254:255], v[10:11] op_sel_hi:[1,0,1]
	v_pk_fma_f32 v[12:13], v[228:229], v[254:255], v[12:13] op_sel_hi:[1,0,1]
	v_pk_fma_f32 v[14:15], v[230:231], v[254:255], v[14:15] op_sel_hi:[1,0,1]
	v_cvt_pk_f32_fp8_e32 v[224:225], v156
	v_cvt_pk_f32_fp8_sdwa v[226:227], v156 src0_sel:WORD_1
	v_cvt_pk_f32_fp8_e32 v[228:229], v157
	v_cvt_pk_f32_fp8_sdwa v[230:231], v157 src0_sel:WORD_1
	v_pk_fma_f32 v[0:1], v[224:225], v[254:255], v[0:1] op_sel:[0,1,0] op_sel_hi:[1,1,1]
	v_pk_fma_f32 v[2:3], v[226:227], v[254:255], v[2:3] op_sel:[0,1,0] op_sel_hi:[1,1,1]
	v_pk_fma_f32 v[4:5], v[228:229], v[254:255], v[4:5] op_sel:[0,1,0] op_sel_hi:[1,1,1]
	v_pk_fma_f32 v[6:7], v[230:231], v[254:255], v[6:7] op_sel:[0,1,0] op_sel_hi:[1,1,1]
	v_cvt_pk_f32_fp8_e32 v[224:225], v158
	v_cvt_pk_f32_fp8_sdwa v[226:227], v158 src0_sel:WORD_1
	v_cvt_pk_f32_fp8_e32 v[228:229], v159
	v_cvt_pk_f32_fp8_sdwa v[230:231], v159 src0_sel:WORD_1
	v_pk_fma_f32 v[8:9], v[224:225], v[254:255], v[8:9] op_sel:[0,1,0] op_sel_hi:[1,1,1]
	v_pk_fma_f32 v[10:11], v[226:227], v[254:255], v[10:11] op_sel:[0,1,0] op_sel_hi:[1,1,1]
	v_pk_fma_f32 v[12:13], v[228:229], v[254:255], v[12:13] op_sel:[0,1,0] op_sel_hi:[1,1,1]
	v_pk_fma_f32 v[14:15], v[230:231], v[254:255], v[14:15] op_sel:[0,1,0] op_sel_hi:[1,1,1]
	s_sub_i32 s90, s90, 1
	s_cmp_eq_u32 s90, 0
	s_cbranch_scc1 .LV_sw2
.LV_t0_s2:
	s_waitcnt lgkmcnt(0)
	buffer_load_dwordx4 v[144:147], v[232:233], s[60:63], 0 idxen offen
	buffer_load_dwordx4 v[148:151], v[234:235], s[60:63], 0 idxen offen
	buffer_load_dwordx4 v[152:155], v[236:237], s[60:63], 0 idxen offen
	buffer_load_dwordx4 v[156:159], v[238:239], s[60:63], 0 idxen offen
	ds_read_b32 v232, v213 offset:96
	ds_read_b32 v234, v213 offset:100
	ds_read_b32 v236, v213 offset:104
	ds_read_b32 v238, v213 offset:108
	ds_read_b128 v[252:255], v213 offset:5040
	s_waitcnt vmcnt(12)
	v_cvt_pk_f32_fp8_e32 v[224:225], v160
	v_cvt_pk_f32_fp8_sdwa v[226:227], v160 src0_sel:WORD_1
	v_cvt_pk_f32_fp8_e32 v[228:229], v161
	v_cvt_pk_f32_fp8_sdwa v[230:231], v161 src0_sel:WORD_1
	v_pk_fma_f32 v[0:1], v[224:225], v[248:249], v[0:1] op_sel_hi:[1,0,1]
	v_pk_fma_f32 v[2:3], v[226:227], v[248:249], v[2:3] op_sel_hi:[1,0,1]
	v_pk_fma_f32 v[4:5], v[228:229], v[248:249], v[4:5] op_sel_hi:[1,0,1]
	v_pk_fma_f32 v[6:7], v[230:231], v[248:249], v[6:7] op_sel_hi:[1,0,1]
	v_cvt_pk_f32_fp8_e32 v[224:225], v162
	v_cvt_pk_f32_fp8_sdwa v[226:227], v162 src0_sel:WORD_1
	v_cvt_pk_f32_fp8_e32 v[228:229], v163
	v_cvt_pk_f32_fp8_sdwa v[230:231], v163 src0_sel:WORD_1
	v_pk_fma_f32 v[8:9], v[224:225], v[248:249], v[8:9] op_sel_hi:[1,0,1]
	v_pk_fma_f32 v[10:11], v[226:227], v[248:249], v[10:11] op_sel_hi:[1,0,1]
	v_pk_fma_f32 v[12:13], v[228:229], v[248:249], v[12:13] op_sel_hi:[1,0,1]
	v_pk_fma_f32 v[14:15], v[230:231], v[248:249], v[14:15] op_sel_hi:[1,0,1]
	v_cvt_pk_f32_fp8_e32 v[224:225], v164
	v_cvt_pk_f32_fp8_sdwa v[226:227], v164 src0_sel:WORD_1
	v_cvt_pk_f32_fp8_e32 v[228:229], v165
	v_cvt_pk_f32_fp8_sdwa v[230:231], v165 src0_sel:WORD_1
	v_pk_fma_f32 v[0:1], v[224:225], v[248:249], v[0:1] op_sel:[0,1,0] op_sel_hi:[1,1,1]
	v_pk_fma_f32 v[2:3], v[226:227], v[248:249], v[2:3] op_sel:[0,1,0] op_sel_hi:[1,1,1]
	v_pk_fma_f32 v[4:5], v[228:229], v[248:249], v[4:5] op_sel:[0,1,0] op_sel_hi:[1,1,1]
	v_pk_fma_f32 v[6:7], v[230:231], v[248:249], v[6:7] op_sel:[0,1,0] op_sel_hi:[1,1,1]
	v_cvt_pk_f32_fp8_e32 v[224:225], v166
	v_cvt_pk_f32_fp8_sdwa v[226:227], v166 src0_sel:WORD_1
	v_cvt_pk_f32_fp8_e32 v[228:229], v167
	v_cvt_pk_f32_fp8_sdwa v[230:231], v167 src0_sel:WORD_1
	v_pk_fma_f32 v[8:9], v[224:225], v[248:249], v[8:9] op_sel:[0,1,0] op_sel_hi:[1,1,1]
	v_pk_fma_f32 v[10:11], v[226:227], v[248:249], v[10:11] op_sel:[0,1,0] op_sel_hi:[1,1,1]
	v_pk_fma_f32 v[12:13], v[228:229], v[248:249], v[12:13] op_sel:[0,1,0] op_sel_hi:[1,1,1]
	v_pk_fma_f32 v[14:15], v[230:231], v[248:249], v[14:15] op_sel:[0,1,0] op_sel_hi:[1,1,1]
	v_cvt_pk_f32_fp8_e32 v[224:225], v168
	v_cvt_pk_f32_fp8_sdwa v[226:227], v168 src0_sel:WORD_1
	v_cvt_pk_f32_fp8_e32 v[228:229], v169
	v_cvt_pk_f32_fp8_sdwa v[230:231], v169 src0_sel:WORD_1
	v_pk_fma_f32 v[0:1], v[224:225], v[250:251], v[0:1] op_sel_hi:[1,0,1]
	v_pk_fma_f32 v[2:3], v[226:227], v[250:251], v[2:3] op_sel_hi:[1,0,1]
	v_pk_fma_f32 v[4:5], v[228:229], v[250:251], v[4:5] op_sel_hi:[1,0,1]
	v_pk_fma_f32 v[6:7], v[230:231], v[250:251], v[6:7] op_sel_hi:[1,0,1]
	v_cvt_pk_f32_fp8_e32 v[224:225], v170
	v_cvt_pk_f32_fp8_sdwa v[226:227], v170 src0_sel:WORD_1
	v_cvt_pk_f32_fp8_e32 v[228:229], v171
	v_cvt_pk_f32_fp8_sdwa v[230:231], v171 src0_sel:WORD_1
	v_pk_fma_f32 v[8:9], v[224:225], v[250:251], v[8:9] op_sel_hi:[1,0,1]
	v_pk_fma_f32 v[10:11], v[226:227], v[250:251], v[10:11] op_sel_hi:[1,0,1]
	v_pk_fma_f32 v[12:13], v[228:229], v[250:251], v[12:13] op_sel_hi:[1,0,1]
	v_pk_fma_f32 v[14:15], v[230:231], v[250:251], v[14:15] op_sel_hi:[1,0,1]
	v_cvt_pk_f32_fp8_e32 v[224:225], v172
	v_cvt_pk_f32_fp8_sdwa v[226:227], v172 src0_sel:WORD_1
	v_cvt_pk_f32_fp8_e32 v[228:229], v173
	v_cvt_pk_f32_fp8_sdwa v[230:231], v173 src0_sel:WORD_1
	v_pk_fma_f32 v[0:1], v[224:225], v[250:251], v[0:1] op_sel:[0,1,0] op_sel_hi:[1,1,1]
	v_pk_fma_f32 v[2:3], v[226:227], v[250:251], v[2:3] op_sel:[0,1,0] op_sel_hi:[1,1,1]
	v_pk_fma_f32 v[4:5], v[228:229], v[250:251], v[4:5] op_sel:[0,1,0] op_sel_hi:[1,1,1]
	v_pk_fma_f32 v[6:7], v[230:231], v[250:251], v[6:7] op_sel:[0,1,0] op_sel_hi:[1,1,1]
	v_cvt_pk_f32_fp8_e32 v[224:225], v174
	v_cvt_pk_f32_fp8_sdwa v[226:227], v174 src0_sel:WORD_1
	v_cvt_pk_f32_fp8_e32 v[228:229], v175
	v_cvt_pk_f32_fp8_sdwa v[230:231], v175 src0_sel:WORD_1
	v_pk_fma_f32 v[8:9], v[224:225], v[250:251], v[8:9] op_sel:[0,1,0] op_sel_hi:[1,1,1]
	v_pk_fma_f32 v[10:11], v[226:227], v[250:251], v[10:11] op_sel:[0,1,0] op_sel_hi:[1,1,1]
	v_pk_fma_f32 v[12:13], v[228:229], v[250:251], v[12:13] op_sel:[0,1,0] op_sel_hi:[1,1,1]
	v_pk_fma_f32 v[14:15], v[230:231], v[250:251], v[14:15] op_sel:[0,1,0] op_sel_hi:[1,1,1]
	s_sub_i32 s90, s90, 1
	s_cmp_eq_u32 s90, 0
	s_cbranch_scc1 .LV_sw3
.LV_t0_s3:
	s_waitcnt lgkmcnt(0)
	buffer_load_dwordx4 v[160:163], v[232:233], s[60:63], 0 idxen offen
	buffer_load_dwordx4 v[164:167], v[234:235], s[60:63], 0 idxen offen
	buffer_load_dwordx4 v[168:171], v[236:237], s[60:63], 0 idxen offen
	buffer_load_dwordx4 v[172:175], v[238:239], s[60:63], 0 idxen offen
	ds_read_b32 v232, v213 offset:112
	ds_read_b32 v234, v213 offset:116
	ds_read_b32 v236, v213 offset:120
	ds_read_b32 v238, v213 offset:124
	ds_read_b128 v[248:251], v213 offset:5056
	s_waitcnt vmcnt(12)
	v_cvt_pk_f32_fp8_e32 v[224:225], v176
	v_cvt_pk_f32_fp8_sdwa v[226:227], v176 src0_sel:WORD_1
	v_cvt_pk_f32_fp8_e32 v[228:229], v177
	v_cvt_pk_f32_fp8_sdwa v[230:231], v177 src0_sel:WORD_1
	v_pk_fma_f32 v[0:1], v[224:225], v[252:253], v[0:1] op_sel_hi:[1,0,1]
	v_pk_fma_f32 v[2:3], v[226:227], v[252:253], v[2:3] op_sel_hi:[1,0,1]
	v_pk_fma_f32 v[4:5], v[228:229], v[252:253], v[4:5] op_sel_hi:[1,0,1]
	v_pk_fma_f32 v[6:7], v[230:231], v[252:253], v[6:7] op_sel_hi:[1,0,1]
	v_cvt_pk_f32_fp8_e32 v[224:225], v178
	v_cvt_pk_f32_fp8_sdwa v[226:227], v178 src0_sel:WORD_1
	v_cvt_pk_f32_fp8_e32 v[228:229], v179
	v_cvt_pk_f32_fp8_sdwa v[230:231], v179 src0_sel:WORD_1
	v_pk_fma_f32 v[8:9], v[224:225], v[252:253], v[8:9] op_sel_hi:[1,0,1]
	v_pk_fma_f32 v[10:11], v[226:227], v[252:253], v[10:11] op_sel_hi:[1,0,1]
	v_pk_fma_f32 v[12:13], v[228:229], v[252:253], v[12:13] op_sel_hi:[1,0,1]
	v_pk_fma_f32 v[14:15], v[230:231], v[252:253], v[14:15] op_sel_hi:[1,0,1]
	v_cvt_pk_f32_fp8_e32 v[224:225], v180
	v_cvt_pk_f32_fp8_sdwa v[226:227], v180 src0_sel:WORD_1
	v_cvt_pk_f32_fp8_e32 v[228:229], v181
	v_cvt_pk_f32_fp8_sdwa v[230:231], v181 src0_sel:WORD_1
	v_pk_fma_f32 v[0:1], v[224:225], v[252:253], v[0:1] op_sel:[0,1,0] op_sel_hi:[1,1,1]
	v_pk_fma_f32 v[2:3], v[226:227], v[252:253], v[2:3] op_sel:[0,1,0] op_sel_hi:[1,1,1]
	v_pk_fma_f32 v[4:5], v[228:229], v[252:253], v[4:5] op_sel:[0,1,0] op_sel_hi:[1,1,1]
	v_pk_fma_f32 v[6:7], v[230:231], v[252:253], v[6:7] op_sel:[0,1,0] op_sel_hi:[1,1,1]
	v_cvt_pk_f32_fp8_e32 v[224:225], v182
	v_cvt_pk_f32_fp8_sdwa v[226:227], v182 src0_sel:WORD_1
	v_cvt_pk_f32_fp8_e32 v[228:229], v183
	v_cvt_pk_f32_fp8_sdwa v[230:231], v183 src0_sel:WORD_1
	v_pk_fma_f32 v[8:9], v[224:225], v[252:253], v[8:9] op_sel:[0,1,0] op_sel_hi:[1,1,1]
	v_pk_fma_f32 v[10:11], v[226:227], v[252:253], v[10:11] op_sel:[0,1,0] op_sel_hi:[1,1,1]
	v_pk_fma_f32 v[12:13], v[228:229], v[252:253], v[12:13] op_sel:[0,1,0] op_sel_hi:[1,1,1]
	v_pk_fma_f32 v[14:15], v[230:231], v[252:253], v[14:15] op_sel:[0,1,0] op_sel_hi:[1,1,1]
	v_cvt_pk_f32_fp8_e32 v[224:225], v184
	v_cvt_pk_f32_fp8_sdwa v[226:227], v184 src0_sel:WORD_1
	v_cvt_pk_f32_fp8_e32 v[228:229], v185
	v_cvt_pk_f32_fp8_sdwa v[230:231], v185 src0_sel:WORD_1
	v_pk_fma_f32 v[0:1], v[224:225], v[254:255], v[0:1] op_sel_hi:[1,0,1]
	v_pk_fma_f32 v[2:3], v[226:227], v[254:255], v[2:3] op_sel_hi:[1,0,1]
	v_pk_fma_f32 v[4:5], v[228:229], v[254:255], v[4:5] op_sel_hi:[1,0,1]
	v_pk_fma_f32 v[6:7], v[230:231], v[254:255], v[6:7] op_sel_hi:[1,0,1]
	v_cvt_pk_f32_fp8_e32 v[224:225], v186
	v_cvt_pk_f32_fp8_sdwa v[226:227], v186 src0_sel:WORD_1
	v_cvt_pk_f32_fp8_e32 v[228:229], v187
	v_cvt_pk_f32_fp8_sdwa v[230:231], v187 src0_sel:WORD_1
	v_pk_fma_f32 v[8:9], v[224:225], v[254:255], v[8:9] op_sel_hi:[1,0,1]
	v_pk_fma_f32 v[10:11], v[226:227], v[254:255], v[10:11] op_sel_hi:[1,0,1]
	v_pk_fma_f32 v[12:13], v[228:229], v[254:255], v[12:13] op_sel_hi:[1,0,1]
	v_pk_fma_f32 v[14:15], v[230:231], v[254:255], v[14:15] op_sel_hi:[1,0,1]
	v_cvt_pk_f32_fp8_e32 v[224:225], v188
	v_cvt_pk_f32_fp8_sdwa v[226:227], v188 src0_sel:WORD_1
	v_cvt_pk_f32_fp8_e32 v[228:229], v189
	v_cvt_pk_f32_fp8_sdwa v[230:231], v189 src0_sel:WORD_1
	v_pk_fma_f32 v[0:1], v[224:225], v[254:255], v[0:1] op_sel:[0,1,0] op_sel_hi:[1,1,1]
	v_pk_fma_f32 v[2:3], v[226:227], v[254:255], v[2:3] op_sel:[0,1,0] op_sel_hi:[1,1,1]
	v_pk_fma_f32 v[4:5], v[228:229], v[254:255], v[4:5] op_sel:[0,1,0] op_sel_hi:[1,1,1]
	v_pk_fma_f32 v[6:7], v[230:231], v[254:255], v[6:7] op_sel:[0,1,0] op_sel_hi:[1,1,1]
	v_cvt_pk_f32_fp8_e32 v[224:225], v190
	v_cvt_pk_f32_fp8_sdwa v[226:227], v190 src0_sel:WORD_1
	v_cvt_pk_f32_fp8_e32 v[228:229], v191
	v_cvt_pk_f32_fp8_sdwa v[230:231], v191 src0_sel:WORD_1
	v_pk_fma_f32 v[8:9], v[224:225], v[254:255], v[8:9] op_sel:[0,1,0] op_sel_hi:[1,1,1]
	v_pk_fma_f32 v[10:11], v[226:227], v[254:255], v[10:11] op_sel:[0,1,0] op_sel_hi:[1,1,1]
	v_pk_fma_f32 v[12:13], v[228:229], v[254:255], v[12:13] op_sel:[0,1,0] op_sel_hi:[1,1,1]
	v_pk_fma_f32 v[14:15], v[230:231], v[254:255], v[14:15] op_sel:[0,1,0] op_sel_hi:[1,1,1]
	v_add_u32_e32 v213, 64, v213
	s_add_i32 s21, s21, 4
	s_sub_i32 s90, s90, 1
	s_cmp_eq_u32 s90, 0
	s_cbranch_scc1 .LV_sw0
	s_branch .LV_t0_s0
.LV_t1_s0:
	s_cmp_ge_u32 s21, s20
	s_cbranch_scc1 .LV_done
	s_waitcnt lgkmcnt(0)
	buffer_load_dwordx4 v[176:179], v[232:233], s[60:63], 0 idxen offen
	buffer_load_dwordx4 v[180:183], v[234:235], s[60:63], 0 idxen offen
	buffer_load_dwordx4 v[184:187], v[236:237], s[60:63], 0 idxen offen
	buffer_load_dwordx4 v[188:191], v[238:239], s[60:63], 0 idxen offen
	ds_read_b32 v232, v213 offset:64
	ds_read_b32 v234, v213 offset:68
	ds_read_b32 v236, v213 offset:72
	ds_read_b32 v238, v213 offset:76
	ds_read_b128 v[252:255], v213 offset:5008
	s_waitcnt vmcnt(12)
	v_cvt_pk_f32_fp8_e32 v[224:225], v128
	v_cvt_pk_f32_fp8_sdwa v[226:227], v128 src0_sel:WORD_1
	v_cvt_pk_f32_fp8_e32 v[228:229], v129
	v_cvt_pk_f32_fp8_sdwa v[230:231], v129 src0_sel:WORD_1
	v_pk_fma_f32 v[16:17], v[224:225], v[248:249], v[16:17] op_sel_hi:[1,0,1]
	v_pk_fma_f32 v[18:19], v[226:227], v[248:249], v[18:19] op_sel_hi:[1,0,1]
	v_pk_fma_f32 v[20:21], v[228:229], v[248:249], v[20:21] op_sel_hi:[1,0,1]
	v_pk_fma_f32 v[22:23], v[230:231], v[248:249], v[22:23] op_sel_hi:[1,0,1]
	v_cvt_pk_f32_fp8_e32 v[224:225], v130
	v_cvt_pk_f32_fp8_sdwa v[226:227], v130 src0_sel:WORD_1
	v_cvt_pk_f32_fp8_e32 v[228:229], v131
	v_cvt_pk_f32_fp8_sdwa v[230:231], v131 src0_sel:WORD_1
	v_pk_fma_f32 v[24:25], v[224:225], v[248:249], v[24:25] op_sel_hi:[1,0,1]
	v_pk_fma_f32 v[26:27], v[226:227], v[248:249], v[26:27] op_sel_hi:[1,0,1]
	v_pk_fma_f32 v[28:29], v[228:229], v[248:249], v[28:29] op_sel_hi:[1,0,1]
	v_pk_fma_f32 v[30:31], v[230:231], v[248:249], v[30:31] op_sel_hi:[1,0,1]
	v_cvt_pk_f32_fp8_e32 v[224:225], v132
	v_cvt_pk_f32_fp8_sdwa v[226:227], v132 src0_sel:WORD_1
	v_cvt_pk_f32_fp8_e32 v[228:229], v133
	v_cvt_pk_f32_fp8_sdwa v[230:231], v133 src0_sel:WORD_1
	v_pk_fma_f32 v[16:17], v[224:225], v[248:249], v[16:17] op_sel:[0,1,0] op_sel_hi:[1,1,1]
	v_pk_fma_f32 v[18:19], v[226:227], v[248:249], v[18:19] op_sel:[0,1,0] op_sel_hi:[1,1,1]
	v_pk_fma_f32 v[20:21], v[228:229], v[248:249], v[20:21] op_sel:[0,1,0] op_sel_hi:[1,1,1]
	v_pk_fma_f32 v[22:23], v[230:231], v[248:249], v[22:23] op_sel:[0,1,0] op_sel_hi:[1,1,1]
	v_cvt_pk_f32_fp8_e32 v[224:225], v134
	v_cvt_pk_f32_fp8_sdwa v[226:227], v134 src0_sel:WORD_1
	v_cvt_pk_f32_fp8_e32 v[228:229], v135
	v_cvt_pk_f32_fp8_sdwa v[230:231], v135 src0_sel:WORD_1
	v_pk_fma_f32 v[24:25], v[224:225], v[248:249], v[24:25] op_sel:[0,1,0] op_sel_hi:[1,1,1]
	v_pk_fma_f32 v[26:27], v[226:227], v[248:249], v[26:27] op_sel:[0,1,0] op_sel_hi:[1,1,1]
	v_pk_fma_f32 v[28:29], v[228:229], v[248:249], v[28:29] op_sel:[0,1,0] op_sel_hi:[1,1,1]
	v_pk_fma_f32 v[30:31], v[230:231], v[248:249], v[30:31] op_sel:[0,1,0] op_sel_hi:[1,1,1]
	v_cvt_pk_f32_fp8_e32 v[224:225], v136
	v_cvt_pk_f32_fp8_sdwa v[226:227], v136 src0_sel:WORD_1
	v_cvt_pk_f32_fp8_e32 v[228:229], v137
	v_cvt_pk_f32_fp8_sdwa v[230:231], v137 src0_sel:WORD_1
	v_pk_fma_f32 v[16:17], v[224:225], v[250:251], v[16:17] op_sel_hi:[1,0,1]
	v_pk_fma_f32 v[18:19], v[226:227], v[250:251], v[18:19] op_sel_hi:[1,0,1]
	v_pk_fma_f32 v[20:21], v[228:229], v[250:251], v[20:21] op_sel_hi:[1,0,1]
	v_pk_fma_f32 v[22:23], v[230:231], v[250:251], v[22:23] op_sel_hi:[1,0,1]
	v_cvt_pk_f32_fp8_e32 v[224:225], v138
	v_cvt_pk_f32_fp8_sdwa v[226:227], v138 src0_sel:WORD_1
	v_cvt_pk_f32_fp8_e32 v[228:229], v139
	v_cvt_pk_f32_fp8_sdwa v[230:231], v139 src0_sel:WORD_1
	v_pk_fma_f32 v[24:25], v[224:225], v[250:251], v[24:25] op_sel_hi:[1,0,1]
	v_pk_fma_f32 v[26:27], v[226:227], v[250:251], v[26:27] op_sel_hi:[1,0,1]
	v_pk_fma_f32 v[28:29], v[228:229], v[250:251], v[28:29] op_sel_hi:[1,0,1]
	v_pk_fma_f32 v[30:31], v[230:231], v[250:251], v[30:31] op_sel_hi:[1,0,1]
	v_cvt_pk_f32_fp8_e32 v[224:225], v140
	v_cvt_pk_f32_fp8_sdwa v[226:227], v140 src0_sel:WORD_1
	v_cvt_pk_f32_fp8_e32 v[228:229], v141
	v_cvt_pk_f32_fp8_sdwa v[230:231], v141 src0_sel:WORD_1
	v_pk_fma_f32 v[16:17], v[224:225], v[250:251], v[16:17] op_sel:[0,1,0] op_sel_hi:[1,1,1]
	v_pk_fma_f32 v[18:19], v[226:227], v[250:251], v[18:19] op_sel:[0,1,0] op_sel_hi:[1,1,1]
	v_pk_fma_f32 v[20:21], v[228:229], v[250:251], v[20:21] op_sel:[0,1,0] op_sel_hi:[1,1,1]
	v_pk_fma_f32 v[22:23], v[230:231], v[250:251], v[22:23] op_sel:[0,1,0] op_sel_hi:[1,1,1]
	v_cvt_pk_f32_fp8_e32 v[224:225], v142
	v_cvt_pk_f32_fp8_sdwa v[226:227], v142 src0_sel:WORD_1
	v_cvt_pk_f32_fp8_e32 v[228:229], v143
	v_cvt_pk_f32_fp8_sdwa v[230:231], v143 src0_sel:WORD_1
	v_pk_fma_f32 v[24:25], v[224:225], v[250:251], v[24:25] op_sel:[0,1,0] op_sel_hi:[1,1,1]
	v_pk_fma_f32 v[26:27], v[226:227], v[250:251], v[26:27] op_sel:[0,1,0] op_sel_hi:[1,1,1]
	v_pk_fma_f32 v[28:29], v[228:229], v[250:251], v[28:29] op_sel:[0,1,0] op_sel_hi:[1,1,1]
	v_pk_fma_f32 v[30:31], v[230:231], v[250:251], v[30:31] op_sel:[0,1,0] op_sel_hi:[1,1,1]
	s_sub_i32 s90, s90, 1
	s_cmp_eq_u32 s90, 0
	s_cbranch_scc1 .LV_sw1
.LV_t1_s1:
	s_waitcnt lgkmcnt(0)
	buffer_load_dwordx4 v[128:131], v[232:233], s[60:63], 0 idxen offen
	buffer_load_dwordx4 v[132:135], v[234:235], s[60:63], 0 idxen offen
	buffer_load_dwordx4 v[136:139], v[236:237], s[60:63], 0 idxen offen
	buffer_load_dwordx4 v[140:143], v[238:239], s[60:63], 0 idxen offen
	ds_read_b32 v232, v213 offset:80
	ds_read_b32 v234, v213 offset:84
	ds_read_b32 v236, v213 offset:88
	ds_read_b32 v238, v213 offset:92
	ds_read_b128 v[248:251], v213 offset:5024
	s_waitcnt vmcnt(12)
	v_cvt_pk_f32_fp8_e32 v[224:225], v144
	v_cvt_pk_f32_fp8_sdwa v[226:227], v144 src0_sel:WORD_1
	v_cvt_pk_f32_fp8_e32 v[228:229], v145
	v_cvt_pk_f32_fp8_sdwa v[230:231], v145 src0_sel:WORD_1
	v_pk_fma_f32 v[16:17], v[224:225], v[252:253], v[16:17] op_sel_hi:[1,0,1]
	v_pk_fma_f32 v[18:19], v[226:227], v[252:253], v[18:19] op_sel_hi:[1,0,1]
	v_pk_fma_f32 v[20:21], v[228:229], v[252:253], v[20:21] op_sel_hi:[1,0,1]
	v_pk_fma_f32 v[22:23], v[230:231], v[252:253], v[22:23] op_sel_hi:[1,0,1]
	v_cvt_pk_f32_fp8_e32 v[224:225], v146
	v_cvt_pk_f32_fp8_sdwa v[226:227], v146 src0_sel:WORD_1
	v_cvt_pk_f32_fp8_e32 v[228:229], v147
	v_cvt_pk_f32_fp8_sdwa v[230:231], v147 src0_sel:WORD_1
	v_pk_fma_f32 v[24:25], v[224:225], v[252:253], v[24:25] op_sel_hi:[1,0,1]
	v_pk_fma_f32 v[26:27], v[226:227], v[252:253], v[26:27] op_sel_hi:[1,0,1]
	v_pk_fma_f32 v[28:29], v[228:229], v[252:253], v[28:29] op_sel_hi:[1,0,1]
	v_pk_fma_f32 v[30:31], v[230:231], v[252:253], v[30:31] op_sel_hi:[1,0,1]
	v_cvt_pk_f32_fp8_e32 v[224:225], v148
	v_cvt_pk_f32_fp8_sdwa v[226:227], v148 src0_sel:WORD_1
	v_cvt_pk_f32_fp8_e32 v[228:229], v149
	v_cvt_pk_f32_fp8_sdwa v[230:231], v149 src0_sel:WORD_1
	v_pk_fma_f32 v[16:17], v[224:225], v[252:253], v[16:17] op_sel:[0,1,0] op_sel_hi:[1,1,1]
	v_pk_fma_f32 v[18:19], v[226:227], v[252:253], v[18:19] op_sel:[0,1,0] op_sel_hi:[1,1,1]
	v_pk_fma_f32 v[20:21], v[228:229], v[252:253], v[20:21] op_sel:[0,1,0] op_sel_hi:[1,1,1]
	v_pk_fma_f32 v[22:23], v[230:231], v[252:253], v[22:23] op_sel:[0,1,0] op_sel_hi:[1,1,1]
	v_cvt_pk_f32_fp8_e32 v[224:225], v150
	v_cvt_pk_f32_fp8_sdwa v[226:227], v150 src0_sel:WORD_1
	v_cvt_pk_f32_fp8_e32 v[228:229], v151
	v_cvt_pk_f32_fp8_sdwa v[230:231], v151 src0_sel:WORD_1
	v_pk_fma_f32 v[24:25], v[224:225], v[252:253], v[24:25] op_sel:[0,1,0] op_sel_hi:[1,1,1]
	v_pk_fma_f32 v[26:27], v[226:227], v[252:253], v[26:27] op_sel:[0,1,0] op_sel_hi:[1,1,1]
	v_pk_fma_f32 v[28:29], v[228:229], v[252:253], v[28:29] op_sel:[0,1,0] op_sel_hi:[1,1,1]
	v_pk_fma_f32 v[30:31], v[230:231], v[252:253], v[30:31] op_sel:[0,1,0] op_sel_hi:[1,1,1]
	v_cvt_pk_f32_fp8_e32 v[224:225], v152
	v_cvt_pk_f32_fp8_sdwa v[226:227], v152 src0_sel:WORD_1
	v_cvt_pk_f32_fp8_e32 v[228:229], v153
	v_cvt_pk_f32_fp8_sdwa v[230:231], v153 src0_sel:WORD_1
	v_pk_fma_f32 v[16:17], v[224:225], v[254:255], v[16:17] op_sel_hi:[1,0,1]
	v_pk_fma_f32 v[18:19], v[226:227], v[254:255], v[18:19] op_sel_hi:[1,0,1]
	v_pk_fma_f32 v[20:21], v[228:229], v[254:255], v[20:21] op_sel_hi:[1,0,1]
	v_pk_fma_f32 v[22:23], v[230:231], v[254:255], v[22:23] op_sel_hi:[1,0,1]
	v_cvt_pk_f32_fp8_e32 v[224:225], v154
	v_cvt_pk_f32_fp8_sdwa v[226:227], v154 src0_sel:WORD_1
	v_cvt_pk_f32_fp8_e32 v[228:229], v155
	v_cvt_pk_f32_fp8_sdwa v[230:231], v155 src0_sel:WORD_1
	v_pk_fma_f32 v[24:25], v[224:225], v[254:255], v[24:25] op_sel_hi:[1,0,1]
	v_pk_fma_f32 v[26:27], v[226:227], v[254:255], v[26:27] op_sel_hi:[1,0,1]
	v_pk_fma_f32 v[28:29], v[228:229], v[254:255], v[28:29] op_sel_hi:[1,0,1]
	v_pk_fma_f32 v[30:31], v[230:231], v[254:255], v[30:31] op_sel_hi:[1,0,1]
	v_cvt_pk_f32_fp8_e32 v[224:225], v156
	v_cvt_pk_f32_fp8_sdwa v[226:227], v156 src0_sel:WORD_1
	v_cvt_pk_f32_fp8_e32 v[228:229], v157
	v_cvt_pk_f32_fp8_sdwa v[230:231], v157 src0_sel:WORD_1
	v_pk_fma_f32 v[16:17], v[224:225], v[254:255], v[16:17] op_sel:[0,1,0] op_sel_hi:[1,1,1]
	v_pk_fma_f32 v[18:19], v[226:227], v[254:255], v[18:19] op_sel:[0,1,0] op_sel_hi:[1,1,1]
	v_pk_fma_f32 v[20:21], v[228:229], v[254:255], v[20:21] op_sel:[0,1,0] op_sel_hi:[1,1,1]
	v_pk_fma_f32 v[22:23], v[230:231], v[254:255], v[22:23] op_sel:[0,1,0] op_sel_hi:[1,1,1]
	v_cvt_pk_f32_fp8_e32 v[224:225], v158
	v_cvt_pk_f32_fp8_sdwa v[226:227], v158 src0_sel:WORD_1
	v_cvt_pk_f32_fp8_e32 v[228:229], v159
	v_cvt_pk_f32_fp8_sdwa v[230:231], v159 src0_sel:WORD_1
	v_pk_fma_f32 v[24:25], v[224:225], v[254:255], v[24:25] op_sel:[0,1,0] op_sel_hi:[1,1,1]
	v_pk_fma_f32 v[26:27], v[226:227], v[254:255], v[26:27] op_sel:[0,1,0] op_sel_hi:[1,1,1]
	v_pk_fma_f32 v[28:29], v[228:229], v[254:255], v[28:29] op_sel:[0,1,0] op_sel_hi:[1,1,1]
	v_pk_fma_f32 v[30:31], v[230:231], v[254:255], v[30:31] op_sel:[0,1,0] op_sel_hi:[1,1,1]
	s_sub_i32 s90, s90, 1
	s_cmp_eq_u32 s90, 0
	s_cbranch_scc1 .LV_sw2
.LV_t1_s2:
	s_waitcnt lgkmcnt(0)
	buffer_load_dwordx4 v[144:147], v[232:233], s[60:63], 0 idxen offen
	buffer_load_dwordx4 v[148:151], v[234:235], s[60:63], 0 idxen offen
	buffer_load_dwordx4 v[152:155], v[236:237], s[60:63], 0 idxen offen
	buffer_load_dwordx4 v[156:159], v[238:239], s[60:63], 0 idxen offen
	ds_read_b32 v232, v213 offset:96
	ds_read_b32 v234, v213 offset:100
	ds_read_b32 v236, v213 offset:104
	ds_read_b32 v238, v213 offset:108
	ds_read_b128 v[252:255], v213 offset:5040
	s_waitcnt vmcnt(12)
	v_cvt_pk_f32_fp8_e32 v[224:225], v160
	v_cvt_pk_f32_fp8_sdwa v[226:227], v160 src0_sel:WORD_1
	v_cvt_pk_f32_fp8_e32 v[228:229], v161
	v_cvt_pk_f32_fp8_sdwa v[230:231], v161 src0_sel:WORD_1
	v_pk_fma_f32 v[16:17], v[224:225], v[248:249], v[16:17] op_sel_hi:[1,0,1]
	v_pk_fma_f32 v[18:19], v[226:227], v[248:249], v[18:19] op_sel_hi:[1,0,1]
	v_pk_fma_f32 v[20:21], v[228:229], v[248:249], v[20:21] op_sel_hi:[1,0,1]
	v_pk_fma_f32 v[22:23], v[230:231], v[248:249], v[22:23] op_sel_hi:[1,0,1]
	v_cvt_pk_f32_fp8_e32 v[224:225], v162
	v_cvt_pk_f32_fp8_sdwa v[226:227], v162 src0_sel:WORD_1
	v_cvt_pk_f32_fp8_e32 v[228:229], v163
	v_cvt_pk_f32_fp8_sdwa v[230:231], v163 src0_sel:WORD_1
	v_pk_fma_f32 v[24:25], v[224:225], v[248:249], v[24:25] op_sel_hi:[1,0,1]
	v_pk_fma_f32 v[26:27], v[226:227], v[248:249], v[26:27] op_sel_hi:[1,0,1]
	v_pk_fma_f32 v[28:29], v[228:229], v[248:249], v[28:29] op_sel_hi:[1,0,1]
	v_pk_fma_f32 v[30:31], v[230:231], v[248:249], v[30:31] op_sel_hi:[1,0,1]
	v_cvt_pk_f32_fp8_e32 v[224:225], v164
	v_cvt_pk_f32_fp8_sdwa v[226:227], v164 src0_sel:WORD_1
	v_cvt_pk_f32_fp8_e32 v[228:229], v165
	v_cvt_pk_f32_fp8_sdwa v[230:231], v165 src0_sel:WORD_1
	v_pk_fma_f32 v[16:17], v[224:225], v[248:249], v[16:17] op_sel:[0,1,0] op_sel_hi:[1,1,1]
	v_pk_fma_f32 v[18:19], v[226:227], v[248:249], v[18:19] op_sel:[0,1,0] op_sel_hi:[1,1,1]
	v_pk_fma_f32 v[20:21], v[228:229], v[248:249], v[20:21] op_sel:[0,1,0] op_sel_hi:[1,1,1]
	v_pk_fma_f32 v[22:23], v[230:231], v[248:249], v[22:23] op_sel:[0,1,0] op_sel_hi:[1,1,1]
	v_cvt_pk_f32_fp8_e32 v[224:225], v166
	v_cvt_pk_f32_fp8_sdwa v[226:227], v166 src0_sel:WORD_1
	v_cvt_pk_f32_fp8_e32 v[228:229], v167
	v_cvt_pk_f32_fp8_sdwa v[230:231], v167 src0_sel:WORD_1
	v_pk_fma_f32 v[24:25], v[224:225], v[248:249], v[24:25] op_sel:[0,1,0] op_sel_hi:[1,1,1]
	v_pk_fma_f32 v[26:27], v[226:227], v[248:249], v[26:27] op_sel:[0,1,0] op_sel_hi:[1,1,1]
	v_pk_fma_f32 v[28:29], v[228:229], v[248:249], v[28:29] op_sel:[0,1,0] op_sel_hi:[1,1,1]
	v_pk_fma_f32 v[30:31], v[230:231], v[248:249], v[30:31] op_sel:[0,1,0] op_sel_hi:[1,1,1]
	v_cvt_pk_f32_fp8_e32 v[224:225], v168
	v_cvt_pk_f32_fp8_sdwa v[226:227], v168 src0_sel:WORD_1
	v_cvt_pk_f32_fp8_e32 v[228:229], v169
	v_cvt_pk_f32_fp8_sdwa v[230:231], v169 src0_sel:WORD_1
	v_pk_fma_f32 v[16:17], v[224:225], v[250:251], v[16:17] op_sel_hi:[1,0,1]
	v_pk_fma_f32 v[18:19], v[226:227], v[250:251], v[18:19] op_sel_hi:[1,0,1]
	v_pk_fma_f32 v[20:21], v[228:229], v[250:251], v[20:21] op_sel_hi:[1,0,1]
	v_pk_fma_f32 v[22:23], v[230:231], v[250:251], v[22:23] op_sel_hi:[1,0,1]
	v_cvt_pk_f32_fp8_e32 v[224:225], v170
	v_cvt_pk_f32_fp8_sdwa v[226:227], v170 src0_sel:WORD_1
	v_cvt_pk_f32_fp8_e32 v[228:229], v171
	v_cvt_pk_f32_fp8_sdwa v[230:231], v171 src0_sel:WORD_1
	v_pk_fma_f32 v[24:25], v[224:225], v[250:251], v[24:25] op_sel_hi:[1,0,1]
	v_pk_fma_f32 v[26:27], v[226:227], v[250:251], v[26:27] op_sel_hi:[1,0,1]
	v_pk_fma_f32 v[28:29], v[228:229], v[250:251], v[28:29] op_sel_hi:[1,0,1]
	v_pk_fma_f32 v[30:31], v[230:231], v[250:251], v[30:31] op_sel_hi:[1,0,1]
	v_cvt_pk_f32_fp8_e32 v[224:225], v172
	v_cvt_pk_f32_fp8_sdwa v[226:227], v172 src0_sel:WORD_1
	v_cvt_pk_f32_fp8_e32 v[228:229], v173
	v_cvt_pk_f32_fp8_sdwa v[230:231], v173 src0_sel:WORD_1
	v_pk_fma_f32 v[16:17], v[224:225], v[250:251], v[16:17] op_sel:[0,1,0] op_sel_hi:[1,1,1]
	v_pk_fma_f32 v[18:19], v[226:227], v[250:251], v[18:19] op_sel:[0,1,0] op_sel_hi:[1,1,1]
	v_pk_fma_f32 v[20:21], v[228:229], v[250:251], v[20:21] op_sel:[0,1,0] op_sel_hi:[1,1,1]
	v_pk_fma_f32 v[22:23], v[230:231], v[250:251], v[22:23] op_sel:[0,1,0] op_sel_hi:[1,1,1]
	v_cvt_pk_f32_fp8_e32 v[224:225], v174
	v_cvt_pk_f32_fp8_sdwa v[226:227], v174 src0_sel:WORD_1
	v_cvt_pk_f32_fp8_e32 v[228:229], v175
	v_cvt_pk_f32_fp8_sdwa v[230:231], v175 src0_sel:WORD_1
	v_pk_fma_f32 v[24:25], v[224:225], v[250:251], v[24:25] op_sel:[0,1,0] op_sel_hi:[1,1,1]
	v_pk_fma_f32 v[26:27], v[226:227], v[250:251], v[26:27] op_sel:[0,1,0] op_sel_hi:[1,1,1]
	v_pk_fma_f32 v[28:29], v[228:229], v[250:251], v[28:29] op_sel:[0,1,0] op_sel_hi:[1,1,1]
	v_pk_fma_f32 v[30:31], v[230:231], v[250:251], v[30:31] op_sel:[0,1,0] op_sel_hi:[1,1,1]
	s_sub_i32 s90, s90, 1
	s_cmp_eq_u32 s90, 0
	s_cbranch_scc1 .LV_sw3
.LV_t1_s3:
	s_waitcnt lgkmcnt(0)
	buffer_load_dwordx4 v[160:163], v[232:233], s[60:63], 0 idxen offen
	buffer_load_dwordx4 v[164:167], v[234:235], s[60:63], 0 idxen offen
	buffer_load_dwordx4 v[168:171], v[236:237], s[60:63], 0 idxen offen
	buffer_load_dwordx4 v[172:175], v[238:239], s[60:63], 0 idxen offen
	ds_read_b32 v232, v213 offset:112
	ds_read_b32 v234, v213 offset:116
	ds_read_b32 v236, v213 offset:120
	ds_read_b32 v238, v213 offset:124
	ds_read_b128 v[248:251], v213 offset:5056
	s_waitcnt vmcnt(12)
	v_cvt_pk_f32_fp8_e32 v[224:225], v176
	v_cvt_pk_f32_fp8_sdwa v[226:227], v176 src0_sel:WORD_1
	v_cvt_pk_f32_fp8_e32 v[228:229], v177
	v_cvt_pk_f32_fp8_sdwa v[230:231], v177 src0_sel:WORD_1
	v_pk_fma_f32 v[16:17], v[224:225], v[252:253], v[16:17] op_sel_hi:[1,0,1]
	v_pk_fma_f32 v[18:19], v[226:227], v[252:253], v[18:19] op_sel_hi:[1,0,1]
	v_pk_fma_f32 v[20:21], v[228:229], v[252:253], v[20:21] op_sel_hi:[1,0,1]
	v_pk_fma_f32 v[22:23], v[230:231], v[252:253], v[22:23] op_sel_hi:[1,0,1]
	v_cvt_pk_f32_fp8_e32 v[224:225], v178
	v_cvt_pk_f32_fp8_sdwa v[226:227], v178 src0_sel:WORD_1
	v_cvt_pk_f32_fp8_e32 v[228:229], v179
	v_cvt_pk_f32_fp8_sdwa v[230:231], v179 src0_sel:WORD_1
	v_pk_fma_f32 v[24:25], v[224:225], v[252:253], v[24:25] op_sel_hi:[1,0,1]
	v_pk_fma_f32 v[26:27], v[226:227], v[252:253], v[26:27] op_sel_hi:[1,0,1]
	v_pk_fma_f32 v[28:29], v[228:229], v[252:253], v[28:29] op_sel_hi:[1,0,1]
	v_pk_fma_f32 v[30:31], v[230:231], v[252:253], v[30:31] op_sel_hi:[1,0,1]
	v_cvt_pk_f32_fp8_e32 v[224:225], v180
	v_cvt_pk_f32_fp8_sdwa v[226:227], v180 src0_sel:WORD_1
	v_cvt_pk_f32_fp8_e32 v[228:229], v181
	v_cvt_pk_f32_fp8_sdwa v[230:231], v181 src0_sel:WORD_1
	v_pk_fma_f32 v[16:17], v[224:225], v[252:253], v[16:17] op_sel:[0,1,0] op_sel_hi:[1,1,1]
	v_pk_fma_f32 v[18:19], v[226:227], v[252:253], v[18:19] op_sel:[0,1,0] op_sel_hi:[1,1,1]
	v_pk_fma_f32 v[20:21], v[228:229], v[252:253], v[20:21] op_sel:[0,1,0] op_sel_hi:[1,1,1]
	v_pk_fma_f32 v[22:23], v[230:231], v[252:253], v[22:23] op_sel:[0,1,0] op_sel_hi:[1,1,1]
	v_cvt_pk_f32_fp8_e32 v[224:225], v182
	v_cvt_pk_f32_fp8_sdwa v[226:227], v182 src0_sel:WORD_1
	v_cvt_pk_f32_fp8_e32 v[228:229], v183
	v_cvt_pk_f32_fp8_sdwa v[230:231], v183 src0_sel:WORD_1
	v_pk_fma_f32 v[24:25], v[224:225], v[252:253], v[24:25] op_sel:[0,1,0] op_sel_hi:[1,1,1]
	v_pk_fma_f32 v[26:27], v[226:227], v[252:253], v[26:27] op_sel:[0,1,0] op_sel_hi:[1,1,1]
	v_pk_fma_f32 v[28:29], v[228:229], v[252:253], v[28:29] op_sel:[0,1,0] op_sel_hi:[1,1,1]
	v_pk_fma_f32 v[30:31], v[230:231], v[252:253], v[30:31] op_sel:[0,1,0] op_sel_hi:[1,1,1]
	v_cvt_pk_f32_fp8_e32 v[224:225], v184
	v_cvt_pk_f32_fp8_sdwa v[226:227], v184 src0_sel:WORD_1
	v_cvt_pk_f32_fp8_e32 v[228:229], v185
	v_cvt_pk_f32_fp8_sdwa v[230:231], v185 src0_sel:WORD_1
	v_pk_fma_f32 v[16:17], v[224:225], v[254:255], v[16:17] op_sel_hi:[1,0,1]
	v_pk_fma_f32 v[18:19], v[226:227], v[254:255], v[18:19] op_sel_hi:[1,0,1]
	v_pk_fma_f32 v[20:21], v[228:229], v[254:255], v[20:21] op_sel_hi:[1,0,1]
	v_pk_fma_f32 v[22:23], v[230:231], v[254:255], v[22:23] op_sel_hi:[1,0,1]
	v_cvt_pk_f32_fp8_e32 v[224:225], v186
	v_cvt_pk_f32_fp8_sdwa v[226:227], v186 src0_sel:WORD_1
	v_cvt_pk_f32_fp8_e32 v[228:229], v187
	v_cvt_pk_f32_fp8_sdwa v[230:231], v187 src0_sel:WORD_1
	v_pk_fma_f32 v[24:25], v[224:225], v[254:255], v[24:25] op_sel_hi:[1,0,1]
	v_pk_fma_f32 v[26:27], v[226:227], v[254:255], v[26:27] op_sel_hi:[1,0,1]
	v_pk_fma_f32 v[28:29], v[228:229], v[254:255], v[28:29] op_sel_hi:[1,0,1]
	v_pk_fma_f32 v[30:31], v[230:231], v[254:255], v[30:31] op_sel_hi:[1,0,1]
	v_cvt_pk_f32_fp8_e32 v[224:225], v188
	v_cvt_pk_f32_fp8_sdwa v[226:227], v188 src0_sel:WORD_1
	v_cvt_pk_f32_fp8_e32 v[228:229], v189
	v_cvt_pk_f32_fp8_sdwa v[230:231], v189 src0_sel:WORD_1
	v_pk_fma_f32 v[16:17], v[224:225], v[254:255], v[16:17] op_sel:[0,1,0] op_sel_hi:[1,1,1]
	v_pk_fma_f32 v[18:19], v[226:227], v[254:255], v[18:19] op_sel:[0,1,0] op_sel_hi:[1,1,1]
	v_pk_fma_f32 v[20:21], v[228:229], v[254:255], v[20:21] op_sel:[0,1,0] op_sel_hi:[1,1,1]
	v_pk_fma_f32 v[22:23], v[230:231], v[254:255], v[22:23] op_sel:[0,1,0] op_sel_hi:[1,1,1]
	v_cvt_pk_f32_fp8_e32 v[224:225], v190
	v_cvt_pk_f32_fp8_sdwa v[226:227], v190 src0_sel:WORD_1
	v_cvt_pk_f32_fp8_e32 v[228:229], v191
	v_cvt_pk_f32_fp8_sdwa v[230:231], v191 src0_sel:WORD_1
	v_pk_fma_f32 v[24:25], v[224:225], v[254:255], v[24:25] op_sel:[0,1,0] op_sel_hi:[1,1,1]
	v_pk_fma_f32 v[26:27], v[226:227], v[254:255], v[26:27] op_sel:[0,1,0] op_sel_hi:[1,1,1]
	v_pk_fma_f32 v[28:29], v[228:229], v[254:255], v[28:29] op_sel:[0,1,0] op_sel_hi:[1,1,1]
	v_pk_fma_f32 v[30:31], v[230:231], v[254:255], v[30:31] op_sel:[0,1,0] op_sel_hi:[1,1,1]
	v_add_u32_e32 v213, 64, v213
	s_add_i32 s21, s21, 4
	s_sub_i32 s90, s90, 1
	s_cmp_eq_u32 s90, 0
	s_cbranch_scc1 .LV_sw0
	s_branch .LV_t1_s0
.LV_t2_s0:
	s_cmp_ge_u32 s21, s20
	s_cbranch_scc1 .LV_done
	s_waitcnt lgkmcnt(0)
	buffer_load_dwordx4 v[176:179], v[232:233], s[60:63], 0 idxen offen
	buffer_load_dwordx4 v[180:183], v[234:235], s[60:63], 0 idxen offen
	buffer_load_dwordx4 v[184:187], v[236:237], s[60:63], 0 idxen offen
	buffer_load_dwordx4 v[188:191], v[238:239], s[60:63], 0 idxen offen
	ds_read_b32 v232, v213 offset:64
	ds_read_b32 v234, v213 offset:68
	ds_read_b32 v236, v213 offset:72
	ds_read_b32 v238, v213 offset:76
	ds_read_b128 v[252:255], v213 offset:5008
	s_waitcnt vmcnt(12)
	v_cvt_pk_f32_fp8_e32 v[224:225], v128
	v_cvt_pk_f32_fp8_sdwa v[226:227], v128 src0_sel:WORD_1
	v_cvt_pk_f32_fp8_e32 v[228:229], v129
	v_cvt_pk_f32_fp8_sdwa v[230:231], v129 src0_sel:WORD_1
	v_pk_fma_f32 v[32:33], v[224:225], v[248:249], v[32:33] op_sel_hi:[1,0,1]
	v_pk_fma_f32 v[34:35], v[226:227], v[248:249], v[34:35] op_sel_hi:[1,0,1]
	v_pk_fma_f32 v[36:37], v[228:229], v[248:249], v[36:37] op_sel_hi:[1,0,1]
	v_pk_fma_f32 v[38:39], v[230:231], v[248:249], v[38:39] op_sel_hi:[1,0,1]
	v_cvt_pk_f32_fp8_e32 v[224:225], v130
	v_cvt_pk_f32_fp8_sdwa v[226:227], v130 src0_sel:WORD_1
	v_cvt_pk_f32_fp8_e32 v[228:229], v131
	v_cvt_pk_f32_fp8_sdwa v[230:231], v131 src0_sel:WORD_1
	v_pk_fma_f32 v[40:41], v[224:225], v[248:249], v[40:41] op_sel_hi:[1,0,1]
	v_pk_fma_f32 v[42:43], v[226:227], v[248:249], v[42:43] op_sel_hi:[1,0,1]
	v_pk_fma_f32 v[44:45], v[228:229], v[248:249], v[44:45] op_sel_hi:[1,0,1]
	v_pk_fma_f32 v[46:47], v[230:231], v[248:249], v[46:47] op_sel_hi:[1,0,1]
	v_cvt_pk_f32_fp8_e32 v[224:225], v132
	v_cvt_pk_f32_fp8_sdwa v[226:227], v132 src0_sel:WORD_1
	v_cvt_pk_f32_fp8_e32 v[228:229], v133
	v_cvt_pk_f32_fp8_sdwa v[230:231], v133 src0_sel:WORD_1
	v_pk_fma_f32 v[32:33], v[224:225], v[248:249], v[32:33] op_sel:[0,1,0] op_sel_hi:[1,1,1]
	v_pk_fma_f32 v[34:35], v[226:227], v[248:249], v[34:35] op_sel:[0,1,0] op_sel_hi:[1,1,1]
	v_pk_fma_f32 v[36:37], v[228:229], v[248:249], v[36:37] op_sel:[0,1,0] op_sel_hi:[1,1,1]
	v_pk_fma_f32 v[38:39], v[230:231], v[248:249], v[38:39] op_sel:[0,1,0] op_sel_hi:[1,1,1]
	v_cvt_pk_f32_fp8_e32 v[224:225], v134
	v_cvt_pk_f32_fp8_sdwa v[226:227], v134 src0_sel:WORD_1
	v_cvt_pk_f32_fp8_e32 v[228:229], v135
	v_cvt_pk_f32_fp8_sdwa v[230:231], v135 src0_sel:WORD_1
	v_pk_fma_f32 v[40:41], v[224:225], v[248:249], v[40:41] op_sel:[0,1,0] op_sel_hi:[1,1,1]
	v_pk_fma_f32 v[42:43], v[226:227], v[248:249], v[42:43] op_sel:[0,1,0] op_sel_hi:[1,1,1]
	v_pk_fma_f32 v[44:45], v[228:229], v[248:249], v[44:45] op_sel:[0,1,0] op_sel_hi:[1,1,1]
	v_pk_fma_f32 v[46:47], v[230:231], v[248:249], v[46:47] op_sel:[0,1,0] op_sel_hi:[1,1,1]
	v_cvt_pk_f32_fp8_e32 v[224:225], v136
	v_cvt_pk_f32_fp8_sdwa v[226:227], v136 src0_sel:WORD_1
	v_cvt_pk_f32_fp8_e32 v[228:229], v137
	v_cvt_pk_f32_fp8_sdwa v[230:231], v137 src0_sel:WORD_1
	v_pk_fma_f32 v[32:33], v[224:225], v[250:251], v[32:33] op_sel_hi:[1,0,1]
	v_pk_fma_f32 v[34:35], v[226:227], v[250:251], v[34:35] op_sel_hi:[1,0,1]
	v_pk_fma_f32 v[36:37], v[228:229], v[250:251], v[36:37] op_sel_hi:[1,0,1]
	v_pk_fma_f32 v[38:39], v[230:231], v[250:251], v[38:39] op_sel_hi:[1,0,1]
	v_cvt_pk_f32_fp8_e32 v[224:225], v138
	v_cvt_pk_f32_fp8_sdwa v[226:227], v138 src0_sel:WORD_1
	v_cvt_pk_f32_fp8_e32 v[228:229], v139
	v_cvt_pk_f32_fp8_sdwa v[230:231], v139 src0_sel:WORD_1
	v_pk_fma_f32 v[40:41], v[224:225], v[250:251], v[40:41] op_sel_hi:[1,0,1]
	v_pk_fma_f32 v[42:43], v[226:227], v[250:251], v[42:43] op_sel_hi:[1,0,1]
	v_pk_fma_f32 v[44:45], v[228:229], v[250:251], v[44:45] op_sel_hi:[1,0,1]
	v_pk_fma_f32 v[46:47], v[230:231], v[250:251], v[46:47] op_sel_hi:[1,0,1]
	v_cvt_pk_f32_fp8_e32 v[224:225], v140
	v_cvt_pk_f32_fp8_sdwa v[226:227], v140 src0_sel:WORD_1
	v_cvt_pk_f32_fp8_e32 v[228:229], v141
	v_cvt_pk_f32_fp8_sdwa v[230:231], v141 src0_sel:WORD_1
	v_pk_fma_f32 v[32:33], v[224:225], v[250:251], v[32:33] op_sel:[0,1,0] op_sel_hi:[1,1,1]
	v_pk_fma_f32 v[34:35], v[226:227], v[250:251], v[34:35] op_sel:[0,1,0] op_sel_hi:[1,1,1]
	v_pk_fma_f32 v[36:37], v[228:229], v[250:251], v[36:37] op_sel:[0,1,0] op_sel_hi:[1,1,1]
	v_pk_fma_f32 v[38:39], v[230:231], v[250:251], v[38:39] op_sel:[0,1,0] op_sel_hi:[1,1,1]
	v_cvt_pk_f32_fp8_e32 v[224:225], v142
	v_cvt_pk_f32_fp8_sdwa v[226:227], v142 src0_sel:WORD_1
	v_cvt_pk_f32_fp8_e32 v[228:229], v143
	v_cvt_pk_f32_fp8_sdwa v[230:231], v143 src0_sel:WORD_1
	v_pk_fma_f32 v[40:41], v[224:225], v[250:251], v[40:41] op_sel:[0,1,0] op_sel_hi:[1,1,1]
	v_pk_fma_f32 v[42:43], v[226:227], v[250:251], v[42:43] op_sel:[0,1,0] op_sel_hi:[1,1,1]
	v_pk_fma_f32 v[44:45], v[228:229], v[250:251], v[44:45] op_sel:[0,1,0] op_sel_hi:[1,1,1]
	v_pk_fma_f32 v[46:47], v[230:231], v[250:251], v[46:47] op_sel:[0,1,0] op_sel_hi:[1,1,1]
	s_sub_i32 s90, s90, 1
	s_cmp_eq_u32 s90, 0
	s_cbranch_scc1 .LV_sw1
.LV_t2_s1:
	s_waitcnt lgkmcnt(0)
	buffer_load_dwordx4 v[128:131], v[232:233], s[60:63], 0 idxen offen
	buffer_load_dwordx4 v[132:135], v[234:235], s[60:63], 0 idxen offen
	buffer_load_dwordx4 v[136:139], v[236:237], s[60:63], 0 idxen offen
	buffer_load_dwordx4 v[140:143], v[238:239], s[60:63], 0 idxen offen
	ds_read_b32 v232, v213 offset:80
	ds_read_b32 v234, v213 offset:84
	ds_read_b32 v236, v213 offset:88
	ds_read_b32 v238, v213 offset:92
	ds_read_b128 v[248:251], v213 offset:5024
	s_waitcnt vmcnt(12)
	v_cvt_pk_f32_fp8_e32 v[224:225], v144
	v_cvt_pk_f32_fp8_sdwa v[226:227], v144 src0_sel:WORD_1
	v_cvt_pk_f32_fp8_e32 v[228:229], v145
	v_cvt_pk_f32_fp8_sdwa v[230:231], v145 src0_sel:WORD_1
	v_pk_fma_f32 v[32:33], v[224:225], v[252:253], v[32:33] op_sel_hi:[1,0,1]
	v_pk_fma_f32 v[34:35], v[226:227], v[252:253], v[34:35] op_sel_hi:[1,0,1]
	v_pk_fma_f32 v[36:37], v[228:229], v[252:253], v[36:37] op_sel_hi:[1,0,1]
	v_pk_fma_f32 v[38:39], v[230:231], v[252:253], v[38:39] op_sel_hi:[1,0,1]
	v_cvt_pk_f32_fp8_e32 v[224:225], v146
	v_cvt_pk_f32_fp8_sdwa v[226:227], v146 src0_sel:WORD_1
	v_cvt_pk_f32_fp8_e32 v[228:229], v147
	v_cvt_pk_f32_fp8_sdwa v[230:231], v147 src0_sel:WORD_1
	v_pk_fma_f32 v[40:41], v[224:225], v[252:253], v[40:41] op_sel_hi:[1,0,1]
	v_pk_fma_f32 v[42:43], v[226:227], v[252:253], v[42:43] op_sel_hi:[1,0,1]
	v_pk_fma_f32 v[44:45], v[228:229], v[252:253], v[44:45] op_sel_hi:[1,0,1]
	v_pk_fma_f32 v[46:47], v[230:231], v[252:253], v[46:47] op_sel_hi:[1,0,1]
	v_cvt_pk_f32_fp8_e32 v[224:225], v148
	v_cvt_pk_f32_fp8_sdwa v[226:227], v148 src0_sel:WORD_1
	v_cvt_pk_f32_fp8_e32 v[228:229], v149
	v_cvt_pk_f32_fp8_sdwa v[230:231], v149 src0_sel:WORD_1
	v_pk_fma_f32 v[32:33], v[224:225], v[252:253], v[32:33] op_sel:[0,1,0] op_sel_hi:[1,1,1]
	v_pk_fma_f32 v[34:35], v[226:227], v[252:253], v[34:35] op_sel:[0,1,0] op_sel_hi:[1,1,1]
	v_pk_fma_f32 v[36:37], v[228:229], v[252:253], v[36:37] op_sel:[0,1,0] op_sel_hi:[1,1,1]
	v_pk_fma_f32 v[38:39], v[230:231], v[252:253], v[38:39] op_sel:[0,1,0] op_sel_hi:[1,1,1]
	v_cvt_pk_f32_fp8_e32 v[224:225], v150
	v_cvt_pk_f32_fp8_sdwa v[226:227], v150 src0_sel:WORD_1
	v_cvt_pk_f32_fp8_e32 v[228:229], v151
	v_cvt_pk_f32_fp8_sdwa v[230:231], v151 src0_sel:WORD_1
	v_pk_fma_f32 v[40:41], v[224:225], v[252:253], v[40:41] op_sel:[0,1,0] op_sel_hi:[1,1,1]
	v_pk_fma_f32 v[42:43], v[226:227], v[252:253], v[42:43] op_sel:[0,1,0] op_sel_hi:[1,1,1]
	v_pk_fma_f32 v[44:45], v[228:229], v[252:253], v[44:45] op_sel:[0,1,0] op_sel_hi:[1,1,1]
	v_pk_fma_f32 v[46:47], v[230:231], v[252:253], v[46:47] op_sel:[0,1,0] op_sel_hi:[1,1,1]
	v_cvt_pk_f32_fp8_e32 v[224:225], v152
	v_cvt_pk_f32_fp8_sdwa v[226:227], v152 src0_sel:WORD_1
	v_cvt_pk_f32_fp8_e32 v[228:229], v153
	v_cvt_pk_f32_fp8_sdwa v[230:231], v153 src0_sel:WORD_1
	v_pk_fma_f32 v[32:33], v[224:225], v[254:255], v[32:33] op_sel_hi:[1,0,1]
	v_pk_fma_f32 v[34:35], v[226:227], v[254:255], v[34:35] op_sel_hi:[1,0,1]
	v_pk_fma_f32 v[36:37], v[228:229], v[254:255], v[36:37] op_sel_hi:[1,0,1]
	v_pk_fma_f32 v[38:39], v[230:231], v[254:255], v[38:39] op_sel_hi:[1,0,1]
	v_cvt_pk_f32_fp8_e32 v[224:225], v154
	v_cvt_pk_f32_fp8_sdwa v[226:227], v154 src0_sel:WORD_1
	v_cvt_pk_f32_fp8_e32 v[228:229], v155
	v_cvt_pk_f32_fp8_sdwa v[230:231], v155 src0_sel:WORD_1
	v_pk_fma_f32 v[40:41], v[224:225], v[254:255], v[40:41] op_sel_hi:[1,0,1]
	v_pk_fma_f32 v[42:43], v[226:227], v[254:255], v[42:43] op_sel_hi:[1,0,1]
	v_pk_fma_f32 v[44:45], v[228:229], v[254:255], v[44:45] op_sel_hi:[1,0,1]
	v_pk_fma_f32 v[46:47], v[230:231], v[254:255], v[46:47] op_sel_hi:[1,0,1]
	v_cvt_pk_f32_fp8_e32 v[224:225], v156
	v_cvt_pk_f32_fp8_sdwa v[226:227], v156 src0_sel:WORD_1
	v_cvt_pk_f32_fp8_e32 v[228:229], v157
	v_cvt_pk_f32_fp8_sdwa v[230:231], v157 src0_sel:WORD_1
	v_pk_fma_f32 v[32:33], v[224:225], v[254:255], v[32:33] op_sel:[0,1,0] op_sel_hi:[1,1,1]
	v_pk_fma_f32 v[34:35], v[226:227], v[254:255], v[34:35] op_sel:[0,1,0] op_sel_hi:[1,1,1]
	v_pk_fma_f32 v[36:37], v[228:229], v[254:255], v[36:37] op_sel:[0,1,0] op_sel_hi:[1,1,1]
	v_pk_fma_f32 v[38:39], v[230:231], v[254:255], v[38:39] op_sel:[0,1,0] op_sel_hi:[1,1,1]
	v_cvt_pk_f32_fp8_e32 v[224:225], v158
	v_cvt_pk_f32_fp8_sdwa v[226:227], v158 src0_sel:WORD_1
	v_cvt_pk_f32_fp8_e32 v[228:229], v159
	v_cvt_pk_f32_fp8_sdwa v[230:231], v159 src0_sel:WORD_1
	v_pk_fma_f32 v[40:41], v[224:225], v[254:255], v[40:41] op_sel:[0,1,0] op_sel_hi:[1,1,1]
	v_pk_fma_f32 v[42:43], v[226:227], v[254:255], v[42:43] op_sel:[0,1,0] op_sel_hi:[1,1,1]
	v_pk_fma_f32 v[44:45], v[228:229], v[254:255], v[44:45] op_sel:[0,1,0] op_sel_hi:[1,1,1]
	v_pk_fma_f32 v[46:47], v[230:231], v[254:255], v[46:47] op_sel:[0,1,0] op_sel_hi:[1,1,1]
	s_sub_i32 s90, s90, 1
	s_cmp_eq_u32 s90, 0
	s_cbranch_scc1 .LV_sw2
.LV_t2_s2:
	s_waitcnt lgkmcnt(0)
	buffer_load_dwordx4 v[144:147], v[232:233], s[60:63], 0 idxen offen
	buffer_load_dwordx4 v[148:151], v[234:235], s[60:63], 0 idxen offen
	buffer_load_dwordx4 v[152:155], v[236:237], s[60:63], 0 idxen offen
	buffer_load_dwordx4 v[156:159], v[238:239], s[60:63], 0 idxen offen
	ds_read_b32 v232, v213 offset:96
	ds_read_b32 v234, v213 offset:100
	ds_read_b32 v236, v213 offset:104
	ds_read_b32 v238, v213 offset:108
	ds_read_b128 v[252:255], v213 offset:5040
	s_waitcnt vmcnt(12)
	v_cvt_pk_f32_fp8_e32 v[224:225], v160
	v_cvt_pk_f32_fp8_sdwa v[226:227], v160 src0_sel:WORD_1
	v_cvt_pk_f32_fp8_e32 v[228:229], v161
	v_cvt_pk_f32_fp8_sdwa v[230:231], v161 src0_sel:WORD_1
	v_pk_fma_f32 v[32:33], v[224:225], v[248:249], v[32:33] op_sel_hi:[1,0,1]
	v_pk_fma_f32 v[34:35], v[226:227], v[248:249], v[34:35] op_sel_hi:[1,0,1]
	v_pk_fma_f32 v[36:37], v[228:229], v[248:249], v[36:37] op_sel_hi:[1,0,1]
	v_pk_fma_f32 v[38:39], v[230:231], v[248:249], v[38:39] op_sel_hi:[1,0,1]
	v_cvt_pk_f32_fp8_e32 v[224:225], v162
	v_cvt_pk_f32_fp8_sdwa v[226:227], v162 src0_sel:WORD_1
	v_cvt_pk_f32_fp8_e32 v[228:229], v163
	v_cvt_pk_f32_fp8_sdwa v[230:231], v163 src0_sel:WORD_1
	v_pk_fma_f32 v[40:41], v[224:225], v[248:249], v[40:41] op_sel_hi:[1,0,1]
	v_pk_fma_f32 v[42:43], v[226:227], v[248:249], v[42:43] op_sel_hi:[1,0,1]
	v_pk_fma_f32 v[44:45], v[228:229], v[248:249], v[44:45] op_sel_hi:[1,0,1]
	v_pk_fma_f32 v[46:47], v[230:231], v[248:249], v[46:47] op_sel_hi:[1,0,1]
	v_cvt_pk_f32_fp8_e32 v[224:225], v164
	v_cvt_pk_f32_fp8_sdwa v[226:227], v164 src0_sel:WORD_1
	v_cvt_pk_f32_fp8_e32 v[228:229], v165
	v_cvt_pk_f32_fp8_sdwa v[230:231], v165 src0_sel:WORD_1
	v_pk_fma_f32 v[32:33], v[224:225], v[248:249], v[32:33] op_sel:[0,1,0] op_sel_hi:[1,1,1]
	v_pk_fma_f32 v[34:35], v[226:227], v[248:249], v[34:35] op_sel:[0,1,0] op_sel_hi:[1,1,1]
	v_pk_fma_f32 v[36:37], v[228:229], v[248:249], v[36:37] op_sel:[0,1,0] op_sel_hi:[1,1,1]
	v_pk_fma_f32 v[38:39], v[230:231], v[248:249], v[38:39] op_sel:[0,1,0] op_sel_hi:[1,1,1]
	v_cvt_pk_f32_fp8_e32 v[224:225], v166
	v_cvt_pk_f32_fp8_sdwa v[226:227], v166 src0_sel:WORD_1
	v_cvt_pk_f32_fp8_e32 v[228:229], v167
	v_cvt_pk_f32_fp8_sdwa v[230:231], v167 src0_sel:WORD_1
	v_pk_fma_f32 v[40:41], v[224:225], v[248:249], v[40:41] op_sel:[0,1,0] op_sel_hi:[1,1,1]
	v_pk_fma_f32 v[42:43], v[226:227], v[248:249], v[42:43] op_sel:[0,1,0] op_sel_hi:[1,1,1]
	v_pk_fma_f32 v[44:45], v[228:229], v[248:249], v[44:45] op_sel:[0,1,0] op_sel_hi:[1,1,1]
	v_pk_fma_f32 v[46:47], v[230:231], v[248:249], v[46:47] op_sel:[0,1,0] op_sel_hi:[1,1,1]
	v_cvt_pk_f32_fp8_e32 v[224:225], v168
	v_cvt_pk_f32_fp8_sdwa v[226:227], v168 src0_sel:WORD_1
	v_cvt_pk_f32_fp8_e32 v[228:229], v169
	v_cvt_pk_f32_fp8_sdwa v[230:231], v169 src0_sel:WORD_1
	v_pk_fma_f32 v[32:33], v[224:225], v[250:251], v[32:33] op_sel_hi:[1,0,1]
	v_pk_fma_f32 v[34:35], v[226:227], v[250:251], v[34:35] op_sel_hi:[1,0,1]
	v_pk_fma_f32 v[36:37], v[228:229], v[250:251], v[36:37] op_sel_hi:[1,0,1]
	v_pk_fma_f32 v[38:39], v[230:231], v[250:251], v[38:39] op_sel_hi:[1,0,1]
	v_cvt_pk_f32_fp8_e32 v[224:225], v170
	v_cvt_pk_f32_fp8_sdwa v[226:227], v170 src0_sel:WORD_1
	v_cvt_pk_f32_fp8_e32 v[228:229], v171
	v_cvt_pk_f32_fp8_sdwa v[230:231], v171 src0_sel:WORD_1
	v_pk_fma_f32 v[40:41], v[224:225], v[250:251], v[40:41] op_sel_hi:[1,0,1]
	v_pk_fma_f32 v[42:43], v[226:227], v[250:251], v[42:43] op_sel_hi:[1,0,1]
	v_pk_fma_f32 v[44:45], v[228:229], v[250:251], v[44:45] op_sel_hi:[1,0,1]
	v_pk_fma_f32 v[46:47], v[230:231], v[250:251], v[46:47] op_sel_hi:[1,0,1]
	v_cvt_pk_f32_fp8_e32 v[224:225], v172
	v_cvt_pk_f32_fp8_sdwa v[226:227], v172 src0_sel:WORD_1
	v_cvt_pk_f32_fp8_e32 v[228:229], v173
	v_cvt_pk_f32_fp8_sdwa v[230:231], v173 src0_sel:WORD_1
	v_pk_fma_f32 v[32:33], v[224:225], v[250:251], v[32:33] op_sel:[0,1,0] op_sel_hi:[1,1,1]
	v_pk_fma_f32 v[34:35], v[226:227], v[250:251], v[34:35] op_sel:[0,1,0] op_sel_hi:[1,1,1]
	v_pk_fma_f32 v[36:37], v[228:229], v[250:251], v[36:37] op_sel:[0,1,0] op_sel_hi:[1,1,1]
	v_pk_fma_f32 v[38:39], v[230:231], v[250:251], v[38:39] op_sel:[0,1,0] op_sel_hi:[1,1,1]
	v_cvt_pk_f32_fp8_e32 v[224:225], v174
	v_cvt_pk_f32_fp8_sdwa v[226:227], v174 src0_sel:WORD_1
	v_cvt_pk_f32_fp8_e32 v[228:229], v175
	v_cvt_pk_f32_fp8_sdwa v[230:231], v175 src0_sel:WORD_1
	v_pk_fma_f32 v[40:41], v[224:225], v[250:251], v[40:41] op_sel:[0,1,0] op_sel_hi:[1,1,1]
	v_pk_fma_f32 v[42:43], v[226:227], v[250:251], v[42:43] op_sel:[0,1,0] op_sel_hi:[1,1,1]
	v_pk_fma_f32 v[44:45], v[228:229], v[250:251], v[44:45] op_sel:[0,1,0] op_sel_hi:[1,1,1]
	v_pk_fma_f32 v[46:47], v[230:231], v[250:251], v[46:47] op_sel:[0,1,0] op_sel_hi:[1,1,1]
	s_sub_i32 s90, s90, 1
	s_cmp_eq_u32 s90, 0
	s_cbranch_scc1 .LV_sw3
.LV_t2_s3:
	s_waitcnt lgkmcnt(0)
	buffer_load_dwordx4 v[160:163], v[232:233], s[60:63], 0 idxen offen
	buffer_load_dwordx4 v[164:167], v[234:235], s[60:63], 0 idxen offen
	buffer_load_dwordx4 v[168:171], v[236:237], s[60:63], 0 idxen offen
	buffer_load_dwordx4 v[172:175], v[238:239], s[60:63], 0 idxen offen
	ds_read_b32 v232, v213 offset:112
	ds_read_b32 v234, v213 offset:116
	ds_read_b32 v236, v213 offset:120
	ds_read_b32 v238, v213 offset:124
	ds_read_b128 v[248:251], v213 offset:5056
	s_waitcnt vmcnt(12)
	v_cvt_pk_f32_fp8_e32 v[224:225], v176
	v_cvt_pk_f32_fp8_sdwa v[226:227], v176 src0_sel:WORD_1
	v_cvt_pk_f32_fp8_e32 v[228:229], v177
	v_cvt_pk_f32_fp8_sdwa v[230:231], v177 src0_sel:WORD_1
	v_pk_fma_f32 v[32:33], v[224:225], v[252:253], v[32:33] op_sel_hi:[1,0,1]
	v_pk_fma_f32 v[34:35], v[226:227], v[252:253], v[34:35] op_sel_hi:[1,0,1]
	v_pk_fma_f32 v[36:37], v[228:229], v[252:253], v[36:37] op_sel_hi:[1,0,1]
	v_pk_fma_f32 v[38:39], v[230:231], v[252:253], v[38:39] op_sel_hi:[1,0,1]
	v_cvt_pk_f32_fp8_e32 v[224:225], v178
	v_cvt_pk_f32_fp8_sdwa v[226:227], v178 src0_sel:WORD_1
	v_cvt_pk_f32_fp8_e32 v[228:229], v179
	v_cvt_pk_f32_fp8_sdwa v[230:231], v179 src0_sel:WORD_1
	v_pk_fma_f32 v[40:41], v[224:225], v[252:253], v[40:41] op_sel_hi:[1,0,1]
	v_pk_fma_f32 v[42:43], v[226:227], v[252:253], v[42:43] op_sel_hi:[1,0,1]
	v_pk_fma_f32 v[44:45], v[228:229], v[252:253], v[44:45] op_sel_hi:[1,0,1]
	v_pk_fma_f32 v[46:47], v[230:231], v[252:253], v[46:47] op_sel_hi:[1,0,1]
	v_cvt_pk_f32_fp8_e32 v[224:225], v180
	v_cvt_pk_f32_fp8_sdwa v[226:227], v180 src0_sel:WORD_1
	v_cvt_pk_f32_fp8_e32 v[228:229], v181
	v_cvt_pk_f32_fp8_sdwa v[230:231], v181 src0_sel:WORD_1
	v_pk_fma_f32 v[32:33], v[224:225], v[252:253], v[32:33] op_sel:[0,1,0] op_sel_hi:[1,1,1]
	v_pk_fma_f32 v[34:35], v[226:227], v[252:253], v[34:35] op_sel:[0,1,0] op_sel_hi:[1,1,1]
	v_pk_fma_f32 v[36:37], v[228:229], v[252:253], v[36:37] op_sel:[0,1,0] op_sel_hi:[1,1,1]
	v_pk_fma_f32 v[38:39], v[230:231], v[252:253], v[38:39] op_sel:[0,1,0] op_sel_hi:[1,1,1]
	v_cvt_pk_f32_fp8_e32 v[224:225], v182
	v_cvt_pk_f32_fp8_sdwa v[226:227], v182 src0_sel:WORD_1
	v_cvt_pk_f32_fp8_e32 v[228:229], v183
	v_cvt_pk_f32_fp8_sdwa v[230:231], v183 src0_sel:WORD_1
	v_pk_fma_f32 v[40:41], v[224:225], v[252:253], v[40:41] op_sel:[0,1,0] op_sel_hi:[1,1,1]
	v_pk_fma_f32 v[42:43], v[226:227], v[252:253], v[42:43] op_sel:[0,1,0] op_sel_hi:[1,1,1]
	v_pk_fma_f32 v[44:45], v[228:229], v[252:253], v[44:45] op_sel:[0,1,0] op_sel_hi:[1,1,1]
	v_pk_fma_f32 v[46:47], v[230:231], v[252:253], v[46:47] op_sel:[0,1,0] op_sel_hi:[1,1,1]
	v_cvt_pk_f32_fp8_e32 v[224:225], v184
	v_cvt_pk_f32_fp8_sdwa v[226:227], v184 src0_sel:WORD_1
	v_cvt_pk_f32_fp8_e32 v[228:229], v185
	v_cvt_pk_f32_fp8_sdwa v[230:231], v185 src0_sel:WORD_1
	v_pk_fma_f32 v[32:33], v[224:225], v[254:255], v[32:33] op_sel_hi:[1,0,1]
	v_pk_fma_f32 v[34:35], v[226:227], v[254:255], v[34:35] op_sel_hi:[1,0,1]
	v_pk_fma_f32 v[36:37], v[228:229], v[254:255], v[36:37] op_sel_hi:[1,0,1]
	v_pk_fma_f32 v[38:39], v[230:231], v[254:255], v[38:39] op_sel_hi:[1,0,1]
	v_cvt_pk_f32_fp8_e32 v[224:225], v186
	v_cvt_pk_f32_fp8_sdwa v[226:227], v186 src0_sel:WORD_1
	v_cvt_pk_f32_fp8_e32 v[228:229], v187
	v_cvt_pk_f32_fp8_sdwa v[230:231], v187 src0_sel:WORD_1
	v_pk_fma_f32 v[40:41], v[224:225], v[254:255], v[40:41] op_sel_hi:[1,0,1]
	v_pk_fma_f32 v[42:43], v[226:227], v[254:255], v[42:43] op_sel_hi:[1,0,1]
	v_pk_fma_f32 v[44:45], v[228:229], v[254:255], v[44:45] op_sel_hi:[1,0,1]
	v_pk_fma_f32 v[46:47], v[230:231], v[254:255], v[46:47] op_sel_hi:[1,0,1]
	v_cvt_pk_f32_fp8_e32 v[224:225], v188
	v_cvt_pk_f32_fp8_sdwa v[226:227], v188 src0_sel:WORD_1
	v_cvt_pk_f32_fp8_e32 v[228:229], v189
	v_cvt_pk_f32_fp8_sdwa v[230:231], v189 src0_sel:WORD_1
	v_pk_fma_f32 v[32:33], v[224:225], v[254:255], v[32:33] op_sel:[0,1,0] op_sel_hi:[1,1,1]
	v_pk_fma_f32 v[34:35], v[226:227], v[254:255], v[34:35] op_sel:[0,1,0] op_sel_hi:[1,1,1]
	v_pk_fma_f32 v[36:37], v[228:229], v[254:255], v[36:37] op_sel:[0,1,0] op_sel_hi:[1,1,1]
	v_pk_fma_f32 v[38:39], v[230:231], v[254:255], v[38:39] op_sel:[0,1,0] op_sel_hi:[1,1,1]
	v_cvt_pk_f32_fp8_e32 v[224:225], v190
	v_cvt_pk_f32_fp8_sdwa v[226:227], v190 src0_sel:WORD_1
	v_cvt_pk_f32_fp8_e32 v[228:229], v191
	v_cvt_pk_f32_fp8_sdwa v[230:231], v191 src0_sel:WORD_1
	v_pk_fma_f32 v[40:41], v[224:225], v[254:255], v[40:41] op_sel:[0,1,0] op_sel_hi:[1,1,1]
	v_pk_fma_f32 v[42:43], v[226:227], v[254:255], v[42:43] op_sel:[0,1,0] op_sel_hi:[1,1,1]
	v_pk_fma_f32 v[44:45], v[228:229], v[254:255], v[44:45] op_sel:[0,1,0] op_sel_hi:[1,1,1]
	v_pk_fma_f32 v[46:47], v[230:231], v[254:255], v[46:47] op_sel:[0,1,0] op_sel_hi:[1,1,1]
	v_add_u32_e32 v213, 64, v213
	s_add_i32 s21, s21, 4
	s_sub_i32 s90, s90, 1
	s_cmp_eq_u32 s90, 0
	s_cbranch_scc1 .LV_sw0
	s_branch .LV_t2_s0
.LV_t3_s0:
	s_cmp_ge_u32 s21, s20
	s_cbranch_scc1 .LV_done
	s_waitcnt lgkmcnt(0)
	buffer_load_dwordx4 v[176:179], v[232:233], s[60:63], 0 idxen offen
	buffer_load_dwordx4 v[180:183], v[234:235], s[60:63], 0 idxen offen
	buffer_load_dwordx4 v[184:187], v[236:237], s[60:63], 0 idxen offen
	buffer_load_dwordx4 v[188:191], v[238:239], s[60:63], 0 idxen offen
	ds_read_b32 v232, v213 offset:64
	ds_read_b32 v234, v213 offset:68
	ds_read_b32 v236, v213 offset:72
	ds_read_b32 v238, v213 offset:76
	ds_read_b128 v[252:255], v213 offset:5008
	s_waitcnt vmcnt(12)
	v_cvt_pk_f32_fp8_e32 v[224:225], v128
	v_cvt_pk_f32_fp8_sdwa v[226:227], v128 src0_sel:WORD_1
	v_cvt_pk_f32_fp8_e32 v[228:229], v129
	v_cvt_pk_f32_fp8_sdwa v[230:231], v129 src0_sel:WORD_1
	v_pk_fma_f32 v[48:49], v[224:225], v[248:249], v[48:49] op_sel_hi:[1,0,1]
	v_pk_fma_f32 v[50:51], v[226:227], v[248:249], v[50:51] op_sel_hi:[1,0,1]
	v_pk_fma_f32 v[52:53], v[228:229], v[248:249], v[52:53] op_sel_hi:[1,0,1]
	v_pk_fma_f32 v[54:55], v[230:231], v[248:249], v[54:55] op_sel_hi:[1,0,1]
	v_cvt_pk_f32_fp8_e32 v[224:225], v130
	v_cvt_pk_f32_fp8_sdwa v[226:227], v130 src0_sel:WORD_1
	v_cvt_pk_f32_fp8_e32 v[228:229], v131
	v_cvt_pk_f32_fp8_sdwa v[230:231], v131 src0_sel:WORD_1
	v_pk_fma_f32 v[56:57], v[224:225], v[248:249], v[56:57] op_sel_hi:[1,0,1]
	v_pk_fma_f32 v[58:59], v[226:227], v[248:249], v[58:59] op_sel_hi:[1,0,1]
	v_pk_fma_f32 v[60:61], v[228:229], v[248:249], v[60:61] op_sel_hi:[1,0,1]
	v_pk_fma_f32 v[62:63], v[230:231], v[248:249], v[62:63] op_sel_hi:[1,0,1]
	v_cvt_pk_f32_fp8_e32 v[224:225], v132
	v_cvt_pk_f32_fp8_sdwa v[226:227], v132 src0_sel:WORD_1
	v_cvt_pk_f32_fp8_e32 v[228:229], v133
	v_cvt_pk_f32_fp8_sdwa v[230:231], v133 src0_sel:WORD_1
	v_pk_fma_f32 v[48:49], v[224:225], v[248:249], v[48:49] op_sel:[0,1,0] op_sel_hi:[1,1,1]
	v_pk_fma_f32 v[50:51], v[226:227], v[248:249], v[50:51] op_sel:[0,1,0] op_sel_hi:[1,1,1]
	v_pk_fma_f32 v[52:53], v[228:229], v[248:249], v[52:53] op_sel:[0,1,0] op_sel_hi:[1,1,1]
	v_pk_fma_f32 v[54:55], v[230:231], v[248:249], v[54:55] op_sel:[0,1,0] op_sel_hi:[1,1,1]
	v_cvt_pk_f32_fp8_e32 v[224:225], v134
	v_cvt_pk_f32_fp8_sdwa v[226:227], v134 src0_sel:WORD_1
	v_cvt_pk_f32_fp8_e32 v[228:229], v135
	v_cvt_pk_f32_fp8_sdwa v[230:231], v135 src0_sel:WORD_1
	v_pk_fma_f32 v[56:57], v[224:225], v[248:249], v[56:57] op_sel:[0,1,0] op_sel_hi:[1,1,1]
	v_pk_fma_f32 v[58:59], v[226:227], v[248:249], v[58:59] op_sel:[0,1,0] op_sel_hi:[1,1,1]
	v_pk_fma_f32 v[60:61], v[228:229], v[248:249], v[60:61] op_sel:[0,1,0] op_sel_hi:[1,1,1]
	v_pk_fma_f32 v[62:63], v[230:231], v[248:249], v[62:63] op_sel:[0,1,0] op_sel_hi:[1,1,1]
	v_cvt_pk_f32_fp8_e32 v[224:225], v136
	v_cvt_pk_f32_fp8_sdwa v[226:227], v136 src0_sel:WORD_1
	v_cvt_pk_f32_fp8_e32 v[228:229], v137
	v_cvt_pk_f32_fp8_sdwa v[230:231], v137 src0_sel:WORD_1
	v_pk_fma_f32 v[48:49], v[224:225], v[250:251], v[48:49] op_sel_hi:[1,0,1]
	v_pk_fma_f32 v[50:51], v[226:227], v[250:251], v[50:51] op_sel_hi:[1,0,1]
	v_pk_fma_f32 v[52:53], v[228:229], v[250:251], v[52:53] op_sel_hi:[1,0,1]
	v_pk_fma_f32 v[54:55], v[230:231], v[250:251], v[54:55] op_sel_hi:[1,0,1]
	v_cvt_pk_f32_fp8_e32 v[224:225], v138
	v_cvt_pk_f32_fp8_sdwa v[226:227], v138 src0_sel:WORD_1
	v_cvt_pk_f32_fp8_e32 v[228:229], v139
	v_cvt_pk_f32_fp8_sdwa v[230:231], v139 src0_sel:WORD_1
	v_pk_fma_f32 v[56:57], v[224:225], v[250:251], v[56:57] op_sel_hi:[1,0,1]
	v_pk_fma_f32 v[58:59], v[226:227], v[250:251], v[58:59] op_sel_hi:[1,0,1]
	v_pk_fma_f32 v[60:61], v[228:229], v[250:251], v[60:61] op_sel_hi:[1,0,1]
	v_pk_fma_f32 v[62:63], v[230:231], v[250:251], v[62:63] op_sel_hi:[1,0,1]
	v_cvt_pk_f32_fp8_e32 v[224:225], v140
	v_cvt_pk_f32_fp8_sdwa v[226:227], v140 src0_sel:WORD_1
	v_cvt_pk_f32_fp8_e32 v[228:229], v141
	v_cvt_pk_f32_fp8_sdwa v[230:231], v141 src0_sel:WORD_1
	v_pk_fma_f32 v[48:49], v[224:225], v[250:251], v[48:49] op_sel:[0,1,0] op_sel_hi:[1,1,1]
	v_pk_fma_f32 v[50:51], v[226:227], v[250:251], v[50:51] op_sel:[0,1,0] op_sel_hi:[1,1,1]
	v_pk_fma_f32 v[52:53], v[228:229], v[250:251], v[52:53] op_sel:[0,1,0] op_sel_hi:[1,1,1]
	v_pk_fma_f32 v[54:55], v[230:231], v[250:251], v[54:55] op_sel:[0,1,0] op_sel_hi:[1,1,1]
	v_cvt_pk_f32_fp8_e32 v[224:225], v142
	v_cvt_pk_f32_fp8_sdwa v[226:227], v142 src0_sel:WORD_1
	v_cvt_pk_f32_fp8_e32 v[228:229], v143
	v_cvt_pk_f32_fp8_sdwa v[230:231], v143 src0_sel:WORD_1
	v_pk_fma_f32 v[56:57], v[224:225], v[250:251], v[56:57] op_sel:[0,1,0] op_sel_hi:[1,1,1]
	v_pk_fma_f32 v[58:59], v[226:227], v[250:251], v[58:59] op_sel:[0,1,0] op_sel_hi:[1,1,1]
	v_pk_fma_f32 v[60:61], v[228:229], v[250:251], v[60:61] op_sel:[0,1,0] op_sel_hi:[1,1,1]
	v_pk_fma_f32 v[62:63], v[230:231], v[250:251], v[62:63] op_sel:[0,1,0] op_sel_hi:[1,1,1]
	s_sub_i32 s90, s90, 1
	s_cmp_eq_u32 s90, 0
	s_cbranch_scc1 .LV_sw1
.LV_t3_s1:
	s_waitcnt lgkmcnt(0)
	buffer_load_dwordx4 v[128:131], v[232:233], s[60:63], 0 idxen offen
	buffer_load_dwordx4 v[132:135], v[234:235], s[60:63], 0 idxen offen
	buffer_load_dwordx4 v[136:139], v[236:237], s[60:63], 0 idxen offen
	buffer_load_dwordx4 v[140:143], v[238:239], s[60:63], 0 idxen offen
	ds_read_b32 v232, v213 offset:80
	ds_read_b32 v234, v213 offset:84
	ds_read_b32 v236, v213 offset:88
	ds_read_b32 v238, v213 offset:92
	ds_read_b128 v[248:251], v213 offset:5024
	s_waitcnt vmcnt(12)
	v_cvt_pk_f32_fp8_e32 v[224:225], v144
	v_cvt_pk_f32_fp8_sdwa v[226:227], v144 src0_sel:WORD_1
	v_cvt_pk_f32_fp8_e32 v[228:229], v145
	v_cvt_pk_f32_fp8_sdwa v[230:231], v145 src0_sel:WORD_1
	v_pk_fma_f32 v[48:49], v[224:225], v[252:253], v[48:49] op_sel_hi:[1,0,1]
	v_pk_fma_f32 v[50:51], v[226:227], v[252:253], v[50:51] op_sel_hi:[1,0,1]
	v_pk_fma_f32 v[52:53], v[228:229], v[252:253], v[52:53] op_sel_hi:[1,0,1]
	v_pk_fma_f32 v[54:55], v[230:231], v[252:253], v[54:55] op_sel_hi:[1,0,1]
	v_cvt_pk_f32_fp8_e32 v[224:225], v146
	v_cvt_pk_f32_fp8_sdwa v[226:227], v146 src0_sel:WORD_1
	v_cvt_pk_f32_fp8_e32 v[228:229], v147
	v_cvt_pk_f32_fp8_sdwa v[230:231], v147 src0_sel:WORD_1
	v_pk_fma_f32 v[56:57], v[224:225], v[252:253], v[56:57] op_sel_hi:[1,0,1]
	v_pk_fma_f32 v[58:59], v[226:227], v[252:253], v[58:59] op_sel_hi:[1,0,1]
	v_pk_fma_f32 v[60:61], v[228:229], v[252:253], v[60:61] op_sel_hi:[1,0,1]
	v_pk_fma_f32 v[62:63], v[230:231], v[252:253], v[62:63] op_sel_hi:[1,0,1]
	v_cvt_pk_f32_fp8_e32 v[224:225], v148
	v_cvt_pk_f32_fp8_sdwa v[226:227], v148 src0_sel:WORD_1
	v_cvt_pk_f32_fp8_e32 v[228:229], v149
	v_cvt_pk_f32_fp8_sdwa v[230:231], v149 src0_sel:WORD_1
	v_pk_fma_f32 v[48:49], v[224:225], v[252:253], v[48:49] op_sel:[0,1,0] op_sel_hi:[1,1,1]
	v_pk_fma_f32 v[50:51], v[226:227], v[252:253], v[50:51] op_sel:[0,1,0] op_sel_hi:[1,1,1]
	v_pk_fma_f32 v[52:53], v[228:229], v[252:253], v[52:53] op_sel:[0,1,0] op_sel_hi:[1,1,1]
	v_pk_fma_f32 v[54:55], v[230:231], v[252:253], v[54:55] op_sel:[0,1,0] op_sel_hi:[1,1,1]
	v_cvt_pk_f32_fp8_e32 v[224:225], v150
	v_cvt_pk_f32_fp8_sdwa v[226:227], v150 src0_sel:WORD_1
	v_cvt_pk_f32_fp8_e32 v[228:229], v151
	v_cvt_pk_f32_fp8_sdwa v[230:231], v151 src0_sel:WORD_1
	v_pk_fma_f32 v[56:57], v[224:225], v[252:253], v[56:57] op_sel:[0,1,0] op_sel_hi:[1,1,1]
	v_pk_fma_f32 v[58:59], v[226:227], v[252:253], v[58:59] op_sel:[0,1,0] op_sel_hi:[1,1,1]
	v_pk_fma_f32 v[60:61], v[228:229], v[252:253], v[60:61] op_sel:[0,1,0] op_sel_hi:[1,1,1]
	v_pk_fma_f32 v[62:63], v[230:231], v[252:253], v[62:63] op_sel:[0,1,0] op_sel_hi:[1,1,1]
	v_cvt_pk_f32_fp8_e32 v[224:225], v152
	v_cvt_pk_f32_fp8_sdwa v[226:227], v152 src0_sel:WORD_1
	v_cvt_pk_f32_fp8_e32 v[228:229], v153
	v_cvt_pk_f32_fp8_sdwa v[230:231], v153 src0_sel:WORD_1
	v_pk_fma_f32 v[48:49], v[224:225], v[254:255], v[48:49] op_sel_hi:[1,0,1]
	v_pk_fma_f32 v[50:51], v[226:227], v[254:255], v[50:51] op_sel_hi:[1,0,1]
	v_pk_fma_f32 v[52:53], v[228:229], v[254:255], v[52:53] op_sel_hi:[1,0,1]
	v_pk_fma_f32 v[54:55], v[230:231], v[254:255], v[54:55] op_sel_hi:[1,0,1]
	v_cvt_pk_f32_fp8_e32 v[224:225], v154
	v_cvt_pk_f32_fp8_sdwa v[226:227], v154 src0_sel:WORD_1
	v_cvt_pk_f32_fp8_e32 v[228:229], v155
	v_cvt_pk_f32_fp8_sdwa v[230:231], v155 src0_sel:WORD_1
	v_pk_fma_f32 v[56:57], v[224:225], v[254:255], v[56:57] op_sel_hi:[1,0,1]
	v_pk_fma_f32 v[58:59], v[226:227], v[254:255], v[58:59] op_sel_hi:[1,0,1]
	v_pk_fma_f32 v[60:61], v[228:229], v[254:255], v[60:61] op_sel_hi:[1,0,1]
	v_pk_fma_f32 v[62:63], v[230:231], v[254:255], v[62:63] op_sel_hi:[1,0,1]
	v_cvt_pk_f32_fp8_e32 v[224:225], v156
	v_cvt_pk_f32_fp8_sdwa v[226:227], v156 src0_sel:WORD_1
	v_cvt_pk_f32_fp8_e32 v[228:229], v157
	v_cvt_pk_f32_fp8_sdwa v[230:231], v157 src0_sel:WORD_1
	v_pk_fma_f32 v[48:49], v[224:225], v[254:255], v[48:49] op_sel:[0,1,0] op_sel_hi:[1,1,1]
	v_pk_fma_f32 v[50:51], v[226:227], v[254:255], v[50:51] op_sel:[0,1,0] op_sel_hi:[1,1,1]
	v_pk_fma_f32 v[52:53], v[228:229], v[254:255], v[52:53] op_sel:[0,1,0] op_sel_hi:[1,1,1]
	v_pk_fma_f32 v[54:55], v[230:231], v[254:255], v[54:55] op_sel:[0,1,0] op_sel_hi:[1,1,1]
	v_cvt_pk_f32_fp8_e32 v[224:225], v158
	v_cvt_pk_f32_fp8_sdwa v[226:227], v158 src0_sel:WORD_1
	v_cvt_pk_f32_fp8_e32 v[228:229], v159
	v_cvt_pk_f32_fp8_sdwa v[230:231], v159 src0_sel:WORD_1
	v_pk_fma_f32 v[56:57], v[224:225], v[254:255], v[56:57] op_sel:[0,1,0] op_sel_hi:[1,1,1]
	v_pk_fma_f32 v[58:59], v[226:227], v[254:255], v[58:59] op_sel:[0,1,0] op_sel_hi:[1,1,1]
	v_pk_fma_f32 v[60:61], v[228:229], v[254:255], v[60:61] op_sel:[0,1,0] op_sel_hi:[1,1,1]
	v_pk_fma_f32 v[62:63], v[230:231], v[254:255], v[62:63] op_sel:[0,1,0] op_sel_hi:[1,1,1]
	s_sub_i32 s90, s90, 1
	s_cmp_eq_u32 s90, 0
	s_cbranch_scc1 .LV_sw2
.LV_t3_s2:
	s_waitcnt lgkmcnt(0)
	buffer_load_dwordx4 v[144:147], v[232:233], s[60:63], 0 idxen offen
	buffer_load_dwordx4 v[148:151], v[234:235], s[60:63], 0 idxen offen
	buffer_load_dwordx4 v[152:155], v[236:237], s[60:63], 0 idxen offen
	buffer_load_dwordx4 v[156:159], v[238:239], s[60:63], 0 idxen offen
	ds_read_b32 v232, v213 offset:96
	ds_read_b32 v234, v213 offset:100
	ds_read_b32 v236, v213 offset:104
	ds_read_b32 v238, v213 offset:108
	ds_read_b128 v[252:255], v213 offset:5040
	s_waitcnt vmcnt(12)
	v_cvt_pk_f32_fp8_e32 v[224:225], v160
	v_cvt_pk_f32_fp8_sdwa v[226:227], v160 src0_sel:WORD_1
	v_cvt_pk_f32_fp8_e32 v[228:229], v161
	v_cvt_pk_f32_fp8_sdwa v[230:231], v161 src0_sel:WORD_1
	v_pk_fma_f32 v[48:49], v[224:225], v[248:249], v[48:49] op_sel_hi:[1,0,1]
	v_pk_fma_f32 v[50:51], v[226:227], v[248:249], v[50:51] op_sel_hi:[1,0,1]
	v_pk_fma_f32 v[52:53], v[228:229], v[248:249], v[52:53] op_sel_hi:[1,0,1]
	v_pk_fma_f32 v[54:55], v[230:231], v[248:249], v[54:55] op_sel_hi:[1,0,1]
	v_cvt_pk_f32_fp8_e32 v[224:225], v162
	v_cvt_pk_f32_fp8_sdwa v[226:227], v162 src0_sel:WORD_1
	v_cvt_pk_f32_fp8_e32 v[228:229], v163
	v_cvt_pk_f32_fp8_sdwa v[230:231], v163 src0_sel:WORD_1
	v_pk_fma_f32 v[56:57], v[224:225], v[248:249], v[56:57] op_sel_hi:[1,0,1]
	v_pk_fma_f32 v[58:59], v[226:227], v[248:249], v[58:59] op_sel_hi:[1,0,1]
	v_pk_fma_f32 v[60:61], v[228:229], v[248:249], v[60:61] op_sel_hi:[1,0,1]
	v_pk_fma_f32 v[62:63], v[230:231], v[248:249], v[62:63] op_sel_hi:[1,0,1]
	v_cvt_pk_f32_fp8_e32 v[224:225], v164
	v_cvt_pk_f32_fp8_sdwa v[226:227], v164 src0_sel:WORD_1
	v_cvt_pk_f32_fp8_e32 v[228:229], v165
	v_cvt_pk_f32_fp8_sdwa v[230:231], v165 src0_sel:WORD_1
	v_pk_fma_f32 v[48:49], v[224:225], v[248:249], v[48:49] op_sel:[0,1,0] op_sel_hi:[1,1,1]
	v_pk_fma_f32 v[50:51], v[226:227], v[248:249], v[50:51] op_sel:[0,1,0] op_sel_hi:[1,1,1]
	v_pk_fma_f32 v[52:53], v[228:229], v[248:249], v[52:53] op_sel:[0,1,0] op_sel_hi:[1,1,1]
	v_pk_fma_f32 v[54:55], v[230:231], v[248:249], v[54:55] op_sel:[0,1,0] op_sel_hi:[1,1,1]
	v_cvt_pk_f32_fp8_e32 v[224:225], v166
	v_cvt_pk_f32_fp8_sdwa v[226:227], v166 src0_sel:WORD_1
	v_cvt_pk_f32_fp8_e32 v[228:229], v167
	v_cvt_pk_f32_fp8_sdwa v[230:231], v167 src0_sel:WORD_1
	v_pk_fma_f32 v[56:57], v[224:225], v[248:249], v[56:57] op_sel:[0,1,0] op_sel_hi:[1,1,1]
	v_pk_fma_f32 v[58:59], v[226:227], v[248:249], v[58:59] op_sel:[0,1,0] op_sel_hi:[1,1,1]
	v_pk_fma_f32 v[60:61], v[228:229], v[248:249], v[60:61] op_sel:[0,1,0] op_sel_hi:[1,1,1]
	v_pk_fma_f32 v[62:63], v[230:231], v[248:249], v[62:63] op_sel:[0,1,0] op_sel_hi:[1,1,1]
	v_cvt_pk_f32_fp8_e32 v[224:225], v168
	v_cvt_pk_f32_fp8_sdwa v[226:227], v168 src0_sel:WORD_1
	v_cvt_pk_f32_fp8_e32 v[228:229], v169
	v_cvt_pk_f32_fp8_sdwa v[230:231], v169 src0_sel:WORD_1
	v_pk_fma_f32 v[48:49], v[224:225], v[250:251], v[48:49] op_sel_hi:[1,0,1]
	v_pk_fma_f32 v[50:51], v[226:227], v[250:251], v[50:51] op_sel_hi:[1,0,1]
	v_pk_fma_f32 v[52:53], v[228:229], v[250:251], v[52:53] op_sel_hi:[1,0,1]
	v_pk_fma_f32 v[54:55], v[230:231], v[250:251], v[54:55] op_sel_hi:[1,0,1]
	v_cvt_pk_f32_fp8_e32 v[224:225], v170
	v_cvt_pk_f32_fp8_sdwa v[226:227], v170 src0_sel:WORD_1
	v_cvt_pk_f32_fp8_e32 v[228:229], v171
	v_cvt_pk_f32_fp8_sdwa v[230:231], v171 src0_sel:WORD_1
	v_pk_fma_f32 v[56:57], v[224:225], v[250:251], v[56:57] op_sel_hi:[1,0,1]
	v_pk_fma_f32 v[58:59], v[226:227], v[250:251], v[58:59] op_sel_hi:[1,0,1]
	v_pk_fma_f32 v[60:61], v[228:229], v[250:251], v[60:61] op_sel_hi:[1,0,1]
	v_pk_fma_f32 v[62:63], v[230:231], v[250:251], v[62:63] op_sel_hi:[1,0,1]
	v_cvt_pk_f32_fp8_e32 v[224:225], v172
	v_cvt_pk_f32_fp8_sdwa v[226:227], v172 src0_sel:WORD_1
	v_cvt_pk_f32_fp8_e32 v[228:229], v173
	v_cvt_pk_f32_fp8_sdwa v[230:231], v173 src0_sel:WORD_1
	v_pk_fma_f32 v[48:49], v[224:225], v[250:251], v[48:49] op_sel:[0,1,0] op_sel_hi:[1,1,1]
	v_pk_fma_f32 v[50:51], v[226:227], v[250:251], v[50:51] op_sel:[0,1,0] op_sel_hi:[1,1,1]
	v_pk_fma_f32 v[52:53], v[228:229], v[250:251], v[52:53] op_sel:[0,1,0] op_sel_hi:[1,1,1]
	v_pk_fma_f32 v[54:55], v[230:231], v[250:251], v[54:55] op_sel:[0,1,0] op_sel_hi:[1,1,1]
	v_cvt_pk_f32_fp8_e32 v[224:225], v174
	v_cvt_pk_f32_fp8_sdwa v[226:227], v174 src0_sel:WORD_1
	v_cvt_pk_f32_fp8_e32 v[228:229], v175
	v_cvt_pk_f32_fp8_sdwa v[230:231], v175 src0_sel:WORD_1
	v_pk_fma_f32 v[56:57], v[224:225], v[250:251], v[56:57] op_sel:[0,1,0] op_sel_hi:[1,1,1]
	v_pk_fma_f32 v[58:59], v[226:227], v[250:251], v[58:59] op_sel:[0,1,0] op_sel_hi:[1,1,1]
	v_pk_fma_f32 v[60:61], v[228:229], v[250:251], v[60:61] op_sel:[0,1,0] op_sel_hi:[1,1,1]
	v_pk_fma_f32 v[62:63], v[230:231], v[250:251], v[62:63] op_sel:[0,1,0] op_sel_hi:[1,1,1]
	s_sub_i32 s90, s90, 1
	s_cmp_eq_u32 s90, 0
	s_cbranch_scc1 .LV_sw3
.LV_t3_s3:
	s_waitcnt lgkmcnt(0)
	buffer_load_dwordx4 v[160:163], v[232:233], s[60:63], 0 idxen offen
	buffer_load_dwordx4 v[164:167], v[234:235], s[60:63], 0 idxen offen
	buffer_load_dwordx4 v[168:171], v[236:237], s[60:63], 0 idxen offen
	buffer_load_dwordx4 v[172:175], v[238:239], s[60:63], 0 idxen offen
	ds_read_b32 v232, v213 offset:112
	ds_read_b32 v234, v213 offset:116
	ds_read_b32 v236, v213 offset:120
	ds_read_b32 v238, v213 offset:124
	ds_read_b128 v[248:251], v213 offset:5056
	s_waitcnt vmcnt(12)
	v_cvt_pk_f32_fp8_e32 v[224:225], v176
	v_cvt_pk_f32_fp8_sdwa v[226:227], v176 src0_sel:WORD_1
	v_cvt_pk_f32_fp8_e32 v[228:229], v177
	v_cvt_pk_f32_fp8_sdwa v[230:231], v177 src0_sel:WORD_1
	v_pk_fma_f32 v[48:49], v[224:225], v[252:253], v[48:49] op_sel_hi:[1,0,1]
	v_pk_fma_f32 v[50:51], v[226:227], v[252:253], v[50:51] op_sel_hi:[1,0,1]
	v_pk_fma_f32 v[52:53], v[228:229], v[252:253], v[52:53] op_sel_hi:[1,0,1]
	v_pk_fma_f32 v[54:55], v[230:231], v[252:253], v[54:55] op_sel_hi:[1,0,1]
	v_cvt_pk_f32_fp8_e32 v[224:225], v178
	v_cvt_pk_f32_fp8_sdwa v[226:227], v178 src0_sel:WORD_1
	v_cvt_pk_f32_fp8_e32 v[228:229], v179
	v_cvt_pk_f32_fp8_sdwa v[230:231], v179 src0_sel:WORD_1
	v_pk_fma_f32 v[56:57], v[224:225], v[252:253], v[56:57] op_sel_hi:[1,0,1]
	v_pk_fma_f32 v[58:59], v[226:227], v[252:253], v[58:59] op_sel_hi:[1,0,1]
	v_pk_fma_f32 v[60:61], v[228:229], v[252:253], v[60:61] op_sel_hi:[1,0,1]
	v_pk_fma_f32 v[62:63], v[230:231], v[252:253], v[62:63] op_sel_hi:[1,0,1]
	v_cvt_pk_f32_fp8_e32 v[224:225], v180
	v_cvt_pk_f32_fp8_sdwa v[226:227], v180 src0_sel:WORD_1
	v_cvt_pk_f32_fp8_e32 v[228:229], v181
	v_cvt_pk_f32_fp8_sdwa v[230:231], v181 src0_sel:WORD_1
	v_pk_fma_f32 v[48:49], v[224:225], v[252:253], v[48:49] op_sel:[0,1,0] op_sel_hi:[1,1,1]
	v_pk_fma_f32 v[50:51], v[226:227], v[252:253], v[50:51] op_sel:[0,1,0] op_sel_hi:[1,1,1]
	v_pk_fma_f32 v[52:53], v[228:229], v[252:253], v[52:53] op_sel:[0,1,0] op_sel_hi:[1,1,1]
	v_pk_fma_f32 v[54:55], v[230:231], v[252:253], v[54:55] op_sel:[0,1,0] op_sel_hi:[1,1,1]
	v_cvt_pk_f32_fp8_e32 v[224:225], v182
	v_cvt_pk_f32_fp8_sdwa v[226:227], v182 src0_sel:WORD_1
	v_cvt_pk_f32_fp8_e32 v[228:229], v183
	v_cvt_pk_f32_fp8_sdwa v[230:231], v183 src0_sel:WORD_1
	v_pk_fma_f32 v[56:57], v[224:225], v[252:253], v[56:57] op_sel:[0,1,0] op_sel_hi:[1,1,1]
	v_pk_fma_f32 v[58:59], v[226:227], v[252:253], v[58:59] op_sel:[0,1,0] op_sel_hi:[1,1,1]
	v_pk_fma_f32 v[60:61], v[228:229], v[252:253], v[60:61] op_sel:[0,1,0] op_sel_hi:[1,1,1]
	v_pk_fma_f32 v[62:63], v[230:231], v[252:253], v[62:63] op_sel:[0,1,0] op_sel_hi:[1,1,1]
	v_cvt_pk_f32_fp8_e32 v[224:225], v184
	v_cvt_pk_f32_fp8_sdwa v[226:227], v184 src0_sel:WORD_1
	v_cvt_pk_f32_fp8_e32 v[228:229], v185
	v_cvt_pk_f32_fp8_sdwa v[230:231], v185 src0_sel:WORD_1
	v_pk_fma_f32 v[48:49], v[224:225], v[254:255], v[48:49] op_sel_hi:[1,0,1]
	v_pk_fma_f32 v[50:51], v[226:227], v[254:255], v[50:51] op_sel_hi:[1,0,1]
	v_pk_fma_f32 v[52:53], v[228:229], v[254:255], v[52:53] op_sel_hi:[1,0,1]
	v_pk_fma_f32 v[54:55], v[230:231], v[254:255], v[54:55] op_sel_hi:[1,0,1]
	v_cvt_pk_f32_fp8_e32 v[224:225], v186
	v_cvt_pk_f32_fp8_sdwa v[226:227], v186 src0_sel:WORD_1
	v_cvt_pk_f32_fp8_e32 v[228:229], v187
	v_cvt_pk_f32_fp8_sdwa v[230:231], v187 src0_sel:WORD_1
	v_pk_fma_f32 v[56:57], v[224:225], v[254:255], v[56:57] op_sel_hi:[1,0,1]
	v_pk_fma_f32 v[58:59], v[226:227], v[254:255], v[58:59] op_sel_hi:[1,0,1]
	v_pk_fma_f32 v[60:61], v[228:229], v[254:255], v[60:61] op_sel_hi:[1,0,1]
	v_pk_fma_f32 v[62:63], v[230:231], v[254:255], v[62:63] op_sel_hi:[1,0,1]
	v_cvt_pk_f32_fp8_e32 v[224:225], v188
	v_cvt_pk_f32_fp8_sdwa v[226:227], v188 src0_sel:WORD_1
	v_cvt_pk_f32_fp8_e32 v[228:229], v189
	v_cvt_pk_f32_fp8_sdwa v[230:231], v189 src0_sel:WORD_1
	v_pk_fma_f32 v[48:49], v[224:225], v[254:255], v[48:49] op_sel:[0,1,0] op_sel_hi:[1,1,1]
	v_pk_fma_f32 v[50:51], v[226:227], v[254:255], v[50:51] op_sel:[0,1,0] op_sel_hi:[1,1,1]
	v_pk_fma_f32 v[52:53], v[228:229], v[254:255], v[52:53] op_sel:[0,1,0] op_sel_hi:[1,1,1]
	v_pk_fma_f32 v[54:55], v[230:231], v[254:255], v[54:55] op_sel:[0,1,0] op_sel_hi:[1,1,1]
	v_cvt_pk_f32_fp8_e32 v[224:225], v190
	v_cvt_pk_f32_fp8_sdwa v[226:227], v190 src0_sel:WORD_1
	v_cvt_pk_f32_fp8_e32 v[228:229], v191
	v_cvt_pk_f32_fp8_sdwa v[230:231], v191 src0_sel:WORD_1
	v_pk_fma_f32 v[56:57], v[224:225], v[254:255], v[56:57] op_sel:[0,1,0] op_sel_hi:[1,1,1]
	v_pk_fma_f32 v[58:59], v[226:227], v[254:255], v[58:59] op_sel:[0,1,0] op_sel_hi:[1,1,1]
	v_pk_fma_f32 v[60:61], v[228:229], v[254:255], v[60:61] op_sel:[0,1,0] op_sel_hi:[1,1,1]
	v_pk_fma_f32 v[62:63], v[230:231], v[254:255], v[62:63] op_sel:[0,1,0] op_sel_hi:[1,1,1]
	v_add_u32_e32 v213, 64, v213
	s_add_i32 s21, s21, 4
	s_sub_i32 s90, s90, 1
	s_cmp_eq_u32 s90, 0
	s_cbranch_scc1 .LV_sw0
	s_branch .LV_t3_s0
.LV_t4_s0:
	s_cmp_ge_u32 s21, s20
	s_cbranch_scc1 .LV_done
	s_waitcnt lgkmcnt(0)
	buffer_load_dwordx4 v[176:179], v[232:233], s[60:63], 0 idxen offen
	buffer_load_dwordx4 v[180:183], v[234:235], s[60:63], 0 idxen offen
	buffer_load_dwordx4 v[184:187], v[236:237], s[60:63], 0 idxen offen
	buffer_load_dwordx4 v[188:191], v[238:239], s[60:63], 0 idxen offen
	ds_read_b32 v232, v213 offset:64
	ds_read_b32 v234, v213 offset:68
	ds_read_b32 v236, v213 offset:72
	ds_read_b32 v238, v213 offset:76
	ds_read_b128 v[252:255], v213 offset:5008
	s_waitcnt vmcnt(12)
	v_cvt_pk_f32_fp8_e32 v[224:225], v128
	v_cvt_pk_f32_fp8_sdwa v[226:227], v128 src0_sel:WORD_1
	v_cvt_pk_f32_fp8_e32 v[228:229], v129
	v_cvt_pk_f32_fp8_sdwa v[230:231], v129 src0_sel:WORD_1
	v_pk_fma_f32 v[64:65], v[224:225], v[248:249], v[64:65] op_sel_hi:[1,0,1]
	v_pk_fma_f32 v[66:67], v[226:227], v[248:249], v[66:67] op_sel_hi:[1,0,1]
	v_pk_fma_f32 v[68:69], v[228:229], v[248:249], v[68:69] op_sel_hi:[1,0,1]
	v_pk_fma_f32 v[70:71], v[230:231], v[248:249], v[70:71] op_sel_hi:[1,0,1]
	v_cvt_pk_f32_fp8_e32 v[224:225], v130
	v_cvt_pk_f32_fp8_sdwa v[226:227], v130 src0_sel:WORD_1
	v_cvt_pk_f32_fp8_e32 v[228:229], v131
	v_cvt_pk_f32_fp8_sdwa v[230:231], v131 src0_sel:WORD_1
	v_pk_fma_f32 v[72:73], v[224:225], v[248:249], v[72:73] op_sel_hi:[1,0,1]
	v_pk_fma_f32 v[74:75], v[226:227], v[248:249], v[74:75] op_sel_hi:[1,0,1]
	v_pk_fma_f32 v[76:77], v[228:229], v[248:249], v[76:77] op_sel_hi:[1,0,1]
	v_pk_fma_f32 v[78:79], v[230:231], v[248:249], v[78:79] op_sel_hi:[1,0,1]
	v_cvt_pk_f32_fp8_e32 v[224:225], v132
	v_cvt_pk_f32_fp8_sdwa v[226:227], v132 src0_sel:WORD_1
	v_cvt_pk_f32_fp8_e32 v[228:229], v133
	v_cvt_pk_f32_fp8_sdwa v[230:231], v133 src0_sel:WORD_1
	v_pk_fma_f32 v[64:65], v[224:225], v[248:249], v[64:65] op_sel:[0,1,0] op_sel_hi:[1,1,1]
	v_pk_fma_f32 v[66:67], v[226:227], v[248:249], v[66:67] op_sel:[0,1,0] op_sel_hi:[1,1,1]
	v_pk_fma_f32 v[68:69], v[228:229], v[248:249], v[68:69] op_sel:[0,1,0] op_sel_hi:[1,1,1]
	v_pk_fma_f32 v[70:71], v[230:231], v[248:249], v[70:71] op_sel:[0,1,0] op_sel_hi:[1,1,1]
	v_cvt_pk_f32_fp8_e32 v[224:225], v134
	v_cvt_pk_f32_fp8_sdwa v[226:227], v134 src0_sel:WORD_1
	v_cvt_pk_f32_fp8_e32 v[228:229], v135
	v_cvt_pk_f32_fp8_sdwa v[230:231], v135 src0_sel:WORD_1
	v_pk_fma_f32 v[72:73], v[224:225], v[248:249], v[72:73] op_sel:[0,1,0] op_sel_hi:[1,1,1]
	v_pk_fma_f32 v[74:75], v[226:227], v[248:249], v[74:75] op_sel:[0,1,0] op_sel_hi:[1,1,1]
	v_pk_fma_f32 v[76:77], v[228:229], v[248:249], v[76:77] op_sel:[0,1,0] op_sel_hi:[1,1,1]
	v_pk_fma_f32 v[78:79], v[230:231], v[248:249], v[78:79] op_sel:[0,1,0] op_sel_hi:[1,1,1]
	v_cvt_pk_f32_fp8_e32 v[224:225], v136
	v_cvt_pk_f32_fp8_sdwa v[226:227], v136 src0_sel:WORD_1
	v_cvt_pk_f32_fp8_e32 v[228:229], v137
	v_cvt_pk_f32_fp8_sdwa v[230:231], v137 src0_sel:WORD_1
	v_pk_fma_f32 v[64:65], v[224:225], v[250:251], v[64:65] op_sel_hi:[1,0,1]
	v_pk_fma_f32 v[66:67], v[226:227], v[250:251], v[66:67] op_sel_hi:[1,0,1]
	v_pk_fma_f32 v[68:69], v[228:229], v[250:251], v[68:69] op_sel_hi:[1,0,1]
	v_pk_fma_f32 v[70:71], v[230:231], v[250:251], v[70:71] op_sel_hi:[1,0,1]
	v_cvt_pk_f32_fp8_e32 v[224:225], v138
	v_cvt_pk_f32_fp8_sdwa v[226:227], v138 src0_sel:WORD_1
	v_cvt_pk_f32_fp8_e32 v[228:229], v139
	v_cvt_pk_f32_fp8_sdwa v[230:231], v139 src0_sel:WORD_1
	v_pk_fma_f32 v[72:73], v[224:225], v[250:251], v[72:73] op_sel_hi:[1,0,1]
	v_pk_fma_f32 v[74:75], v[226:227], v[250:251], v[74:75] op_sel_hi:[1,0,1]
	v_pk_fma_f32 v[76:77], v[228:229], v[250:251], v[76:77] op_sel_hi:[1,0,1]
	v_pk_fma_f32 v[78:79], v[230:231], v[250:251], v[78:79] op_sel_hi:[1,0,1]
	v_cvt_pk_f32_fp8_e32 v[224:225], v140
	v_cvt_pk_f32_fp8_sdwa v[226:227], v140 src0_sel:WORD_1
	v_cvt_pk_f32_fp8_e32 v[228:229], v141
	v_cvt_pk_f32_fp8_sdwa v[230:231], v141 src0_sel:WORD_1
	v_pk_fma_f32 v[64:65], v[224:225], v[250:251], v[64:65] op_sel:[0,1,0] op_sel_hi:[1,1,1]
	v_pk_fma_f32 v[66:67], v[226:227], v[250:251], v[66:67] op_sel:[0,1,0] op_sel_hi:[1,1,1]
	v_pk_fma_f32 v[68:69], v[228:229], v[250:251], v[68:69] op_sel:[0,1,0] op_sel_hi:[1,1,1]
	v_pk_fma_f32 v[70:71], v[230:231], v[250:251], v[70:71] op_sel:[0,1,0] op_sel_hi:[1,1,1]
	v_cvt_pk_f32_fp8_e32 v[224:225], v142
	v_cvt_pk_f32_fp8_sdwa v[226:227], v142 src0_sel:WORD_1
	v_cvt_pk_f32_fp8_e32 v[228:229], v143
	v_cvt_pk_f32_fp8_sdwa v[230:231], v143 src0_sel:WORD_1
	v_pk_fma_f32 v[72:73], v[224:225], v[250:251], v[72:73] op_sel:[0,1,0] op_sel_hi:[1,1,1]
	v_pk_fma_f32 v[74:75], v[226:227], v[250:251], v[74:75] op_sel:[0,1,0] op_sel_hi:[1,1,1]
	v_pk_fma_f32 v[76:77], v[228:229], v[250:251], v[76:77] op_sel:[0,1,0] op_sel_hi:[1,1,1]
	v_pk_fma_f32 v[78:79], v[230:231], v[250:251], v[78:79] op_sel:[0,1,0] op_sel_hi:[1,1,1]
	s_sub_i32 s90, s90, 1
	s_cmp_eq_u32 s90, 0
	s_cbranch_scc1 .LV_sw1
.LV_t4_s1:
	s_waitcnt lgkmcnt(0)
	buffer_load_dwordx4 v[128:131], v[232:233], s[60:63], 0 idxen offen
	buffer_load_dwordx4 v[132:135], v[234:235], s[60:63], 0 idxen offen
	buffer_load_dwordx4 v[136:139], v[236:237], s[60:63], 0 idxen offen
	buffer_load_dwordx4 v[140:143], v[238:239], s[60:63], 0 idxen offen
	ds_read_b32 v232, v213 offset:80
	ds_read_b32 v234, v213 offset:84
	ds_read_b32 v236, v213 offset:88
	ds_read_b32 v238, v213 offset:92
	ds_read_b128 v[248:251], v213 offset:5024
	s_waitcnt vmcnt(12)
	v_cvt_pk_f32_fp8_e32 v[224:225], v144
	v_cvt_pk_f32_fp8_sdwa v[226:227], v144 src0_sel:WORD_1
	v_cvt_pk_f32_fp8_e32 v[228:229], v145
	v_cvt_pk_f32_fp8_sdwa v[230:231], v145 src0_sel:WORD_1
	v_pk_fma_f32 v[64:65], v[224:225], v[252:253], v[64:65] op_sel_hi:[1,0,1]
	v_pk_fma_f32 v[66:67], v[226:227], v[252:253], v[66:67] op_sel_hi:[1,0,1]
	v_pk_fma_f32 v[68:69], v[228:229], v[252:253], v[68:69] op_sel_hi:[1,0,1]
	v_pk_fma_f32 v[70:71], v[230:231], v[252:253], v[70:71] op_sel_hi:[1,0,1]
	v_cvt_pk_f32_fp8_e32 v[224:225], v146
	v_cvt_pk_f32_fp8_sdwa v[226:227], v146 src0_sel:WORD_1
	v_cvt_pk_f32_fp8_e32 v[228:229], v147
	v_cvt_pk_f32_fp8_sdwa v[230:231], v147 src0_sel:WORD_1
	v_pk_fma_f32 v[72:73], v[224:225], v[252:253], v[72:73] op_sel_hi:[1,0,1]
	v_pk_fma_f32 v[74:75], v[226:227], v[252:253], v[74:75] op_sel_hi:[1,0,1]
	v_pk_fma_f32 v[76:77], v[228:229], v[252:253], v[76:77] op_sel_hi:[1,0,1]
	v_pk_fma_f32 v[78:79], v[230:231], v[252:253], v[78:79] op_sel_hi:[1,0,1]
	v_cvt_pk_f32_fp8_e32 v[224:225], v148
	v_cvt_pk_f32_fp8_sdwa v[226:227], v148 src0_sel:WORD_1
	v_cvt_pk_f32_fp8_e32 v[228:229], v149
	v_cvt_pk_f32_fp8_sdwa v[230:231], v149 src0_sel:WORD_1
	v_pk_fma_f32 v[64:65], v[224:225], v[252:253], v[64:65] op_sel:[0,1,0] op_sel_hi:[1,1,1]
	v_pk_fma_f32 v[66:67], v[226:227], v[252:253], v[66:67] op_sel:[0,1,0] op_sel_hi:[1,1,1]
	v_pk_fma_f32 v[68:69], v[228:229], v[252:253], v[68:69] op_sel:[0,1,0] op_sel_hi:[1,1,1]
	v_pk_fma_f32 v[70:71], v[230:231], v[252:253], v[70:71] op_sel:[0,1,0] op_sel_hi:[1,1,1]
	v_cvt_pk_f32_fp8_e32 v[224:225], v150
	v_cvt_pk_f32_fp8_sdwa v[226:227], v150 src0_sel:WORD_1
	v_cvt_pk_f32_fp8_e32 v[228:229], v151
	v_cvt_pk_f32_fp8_sdwa v[230:231], v151 src0_sel:WORD_1
	v_pk_fma_f32 v[72:73], v[224:225], v[252:253], v[72:73] op_sel:[0,1,0] op_sel_hi:[1,1,1]
	v_pk_fma_f32 v[74:75], v[226:227], v[252:253], v[74:75] op_sel:[0,1,0] op_sel_hi:[1,1,1]
	v_pk_fma_f32 v[76:77], v[228:229], v[252:253], v[76:77] op_sel:[0,1,0] op_sel_hi:[1,1,1]
	v_pk_fma_f32 v[78:79], v[230:231], v[252:253], v[78:79] op_sel:[0,1,0] op_sel_hi:[1,1,1]
	v_cvt_pk_f32_fp8_e32 v[224:225], v152
	v_cvt_pk_f32_fp8_sdwa v[226:227], v152 src0_sel:WORD_1
	v_cvt_pk_f32_fp8_e32 v[228:229], v153
	v_cvt_pk_f32_fp8_sdwa v[230:231], v153 src0_sel:WORD_1
	v_pk_fma_f32 v[64:65], v[224:225], v[254:255], v[64:65] op_sel_hi:[1,0,1]
	v_pk_fma_f32 v[66:67], v[226:227], v[254:255], v[66:67] op_sel_hi:[1,0,1]
	v_pk_fma_f32 v[68:69], v[228:229], v[254:255], v[68:69] op_sel_hi:[1,0,1]
	v_pk_fma_f32 v[70:71], v[230:231], v[254:255], v[70:71] op_sel_hi:[1,0,1]
	v_cvt_pk_f32_fp8_e32 v[224:225], v154
	v_cvt_pk_f32_fp8_sdwa v[226:227], v154 src0_sel:WORD_1
	v_cvt_pk_f32_fp8_e32 v[228:229], v155
	v_cvt_pk_f32_fp8_sdwa v[230:231], v155 src0_sel:WORD_1
	v_pk_fma_f32 v[72:73], v[224:225], v[254:255], v[72:73] op_sel_hi:[1,0,1]
	v_pk_fma_f32 v[74:75], v[226:227], v[254:255], v[74:75] op_sel_hi:[1,0,1]
	v_pk_fma_f32 v[76:77], v[228:229], v[254:255], v[76:77] op_sel_hi:[1,0,1]
	v_pk_fma_f32 v[78:79], v[230:231], v[254:255], v[78:79] op_sel_hi:[1,0,1]
	v_cvt_pk_f32_fp8_e32 v[224:225], v156
	v_cvt_pk_f32_fp8_sdwa v[226:227], v156 src0_sel:WORD_1
	v_cvt_pk_f32_fp8_e32 v[228:229], v157
	v_cvt_pk_f32_fp8_sdwa v[230:231], v157 src0_sel:WORD_1
	v_pk_fma_f32 v[64:65], v[224:225], v[254:255], v[64:65] op_sel:[0,1,0] op_sel_hi:[1,1,1]
	v_pk_fma_f32 v[66:67], v[226:227], v[254:255], v[66:67] op_sel:[0,1,0] op_sel_hi:[1,1,1]
	v_pk_fma_f32 v[68:69], v[228:229], v[254:255], v[68:69] op_sel:[0,1,0] op_sel_hi:[1,1,1]
	v_pk_fma_f32 v[70:71], v[230:231], v[254:255], v[70:71] op_sel:[0,1,0] op_sel_hi:[1,1,1]
	v_cvt_pk_f32_fp8_e32 v[224:225], v158
	v_cvt_pk_f32_fp8_sdwa v[226:227], v158 src0_sel:WORD_1
	v_cvt_pk_f32_fp8_e32 v[228:229], v159
	v_cvt_pk_f32_fp8_sdwa v[230:231], v159 src0_sel:WORD_1
	v_pk_fma_f32 v[72:73], v[224:225], v[254:255], v[72:73] op_sel:[0,1,0] op_sel_hi:[1,1,1]
	v_pk_fma_f32 v[74:75], v[226:227], v[254:255], v[74:75] op_sel:[0,1,0] op_sel_hi:[1,1,1]
	v_pk_fma_f32 v[76:77], v[228:229], v[254:255], v[76:77] op_sel:[0,1,0] op_sel_hi:[1,1,1]
	v_pk_fma_f32 v[78:79], v[230:231], v[254:255], v[78:79] op_sel:[0,1,0] op_sel_hi:[1,1,1]
	s_sub_i32 s90, s90, 1
	s_cmp_eq_u32 s90, 0
	s_cbranch_scc1 .LV_sw2
.LV_t4_s2:
	s_waitcnt lgkmcnt(0)
	buffer_load_dwordx4 v[144:147], v[232:233], s[60:63], 0 idxen offen
	buffer_load_dwordx4 v[148:151], v[234:235], s[60:63], 0 idxen offen
	buffer_load_dwordx4 v[152:155], v[236:237], s[60:63], 0 idxen offen
	buffer_load_dwordx4 v[156:159], v[238:239], s[60:63], 0 idxen offen
	ds_read_b32 v232, v213 offset:96
	ds_read_b32 v234, v213 offset:100
	ds_read_b32 v236, v213 offset:104
	ds_read_b32 v238, v213 offset:108
	ds_read_b128 v[252:255], v213 offset:5040
	s_waitcnt vmcnt(12)
	v_cvt_pk_f32_fp8_e32 v[224:225], v160
	v_cvt_pk_f32_fp8_sdwa v[226:227], v160 src0_sel:WORD_1
	v_cvt_pk_f32_fp8_e32 v[228:229], v161
	v_cvt_pk_f32_fp8_sdwa v[230:231], v161 src0_sel:WORD_1
	v_pk_fma_f32 v[64:65], v[224:225], v[248:249], v[64:65] op_sel_hi:[1,0,1]
	v_pk_fma_f32 v[66:67], v[226:227], v[248:249], v[66:67] op_sel_hi:[1,0,1]
	v_pk_fma_f32 v[68:69], v[228:229], v[248:249], v[68:69] op_sel_hi:[1,0,1]
	v_pk_fma_f32 v[70:71], v[230:231], v[248:249], v[70:71] op_sel_hi:[1,0,1]
	v_cvt_pk_f32_fp8_e32 v[224:225], v162
	v_cvt_pk_f32_fp8_sdwa v[226:227], v162 src0_sel:WORD_1
	v_cvt_pk_f32_fp8_e32 v[228:229], v163
	v_cvt_pk_f32_fp8_sdwa v[230:231], v163 src0_sel:WORD_1
	v_pk_fma_f32 v[72:73], v[224:225], v[248:249], v[72:73] op_sel_hi:[1,0,1]
	v_pk_fma_f32 v[74:75], v[226:227], v[248:249], v[74:75] op_sel_hi:[1,0,1]
	v_pk_fma_f32 v[76:77], v[228:229], v[248:249], v[76:77] op_sel_hi:[1,0,1]
	v_pk_fma_f32 v[78:79], v[230:231], v[248:249], v[78:79] op_sel_hi:[1,0,1]
	v_cvt_pk_f32_fp8_e32 v[224:225], v164
	v_cvt_pk_f32_fp8_sdwa v[226:227], v164 src0_sel:WORD_1
	v_cvt_pk_f32_fp8_e32 v[228:229], v165
	v_cvt_pk_f32_fp8_sdwa v[230:231], v165 src0_sel:WORD_1
	v_pk_fma_f32 v[64:65], v[224:225], v[248:249], v[64:65] op_sel:[0,1,0] op_sel_hi:[1,1,1]
	v_pk_fma_f32 v[66:67], v[226:227], v[248:249], v[66:67] op_sel:[0,1,0] op_sel_hi:[1,1,1]
	v_pk_fma_f32 v[68:69], v[228:229], v[248:249], v[68:69] op_sel:[0,1,0] op_sel_hi:[1,1,1]
	v_pk_fma_f32 v[70:71], v[230:231], v[248:249], v[70:71] op_sel:[0,1,0] op_sel_hi:[1,1,1]
	v_cvt_pk_f32_fp8_e32 v[224:225], v166
	v_cvt_pk_f32_fp8_sdwa v[226:227], v166 src0_sel:WORD_1
	v_cvt_pk_f32_fp8_e32 v[228:229], v167
	v_cvt_pk_f32_fp8_sdwa v[230:231], v167 src0_sel:WORD_1
	v_pk_fma_f32 v[72:73], v[224:225], v[248:249], v[72:73] op_sel:[0,1,0] op_sel_hi:[1,1,1]
	v_pk_fma_f32 v[74:75], v[226:227], v[248:249], v[74:75] op_sel:[0,1,0] op_sel_hi:[1,1,1]
	v_pk_fma_f32 v[76:77], v[228:229], v[248:249], v[76:77] op_sel:[0,1,0] op_sel_hi:[1,1,1]
	v_pk_fma_f32 v[78:79], v[230:231], v[248:249], v[78:79] op_sel:[0,1,0] op_sel_hi:[1,1,1]
	v_cvt_pk_f32_fp8_e32 v[224:225], v168
	v_cvt_pk_f32_fp8_sdwa v[226:227], v168 src0_sel:WORD_1
	v_cvt_pk_f32_fp8_e32 v[228:229], v169
	v_cvt_pk_f32_fp8_sdwa v[230:231], v169 src0_sel:WORD_1
	v_pk_fma_f32 v[64:65], v[224:225], v[250:251], v[64:65] op_sel_hi:[1,0,1]
	v_pk_fma_f32 v[66:67], v[226:227], v[250:251], v[66:67] op_sel_hi:[1,0,1]
	v_pk_fma_f32 v[68:69], v[228:229], v[250:251], v[68:69] op_sel_hi:[1,0,1]
	v_pk_fma_f32 v[70:71], v[230:231], v[250:251], v[70:71] op_sel_hi:[1,0,1]
	v_cvt_pk_f32_fp8_e32 v[224:225], v170
	v_cvt_pk_f32_fp8_sdwa v[226:227], v170 src0_sel:WORD_1
	v_cvt_pk_f32_fp8_e32 v[228:229], v171
	v_cvt_pk_f32_fp8_sdwa v[230:231], v171 src0_sel:WORD_1
	v_pk_fma_f32 v[72:73], v[224:225], v[250:251], v[72:73] op_sel_hi:[1,0,1]
	v_pk_fma_f32 v[74:75], v[226:227], v[250:251], v[74:75] op_sel_hi:[1,0,1]
	v_pk_fma_f32 v[76:77], v[228:229], v[250:251], v[76:77] op_sel_hi:[1,0,1]
	v_pk_fma_f32 v[78:79], v[230:231], v[250:251], v[78:79] op_sel_hi:[1,0,1]
	v_cvt_pk_f32_fp8_e32 v[224:225], v172
	v_cvt_pk_f32_fp8_sdwa v[226:227], v172 src0_sel:WORD_1
	v_cvt_pk_f32_fp8_e32 v[228:229], v173
	v_cvt_pk_f32_fp8_sdwa v[230:231], v173 src0_sel:WORD_1
	v_pk_fma_f32 v[64:65], v[224:225], v[250:251], v[64:65] op_sel:[0,1,0] op_sel_hi:[1,1,1]
	v_pk_fma_f32 v[66:67], v[226:227], v[250:251], v[66:67] op_sel:[0,1,0] op_sel_hi:[1,1,1]
	v_pk_fma_f32 v[68:69], v[228:229], v[250:251], v[68:69] op_sel:[0,1,0] op_sel_hi:[1,1,1]
	v_pk_fma_f32 v[70:71], v[230:231], v[250:251], v[70:71] op_sel:[0,1,0] op_sel_hi:[1,1,1]
	v_cvt_pk_f32_fp8_e32 v[224:225], v174
	v_cvt_pk_f32_fp8_sdwa v[226:227], v174 src0_sel:WORD_1
	v_cvt_pk_f32_fp8_e32 v[228:229], v175
	v_cvt_pk_f32_fp8_sdwa v[230:231], v175 src0_sel:WORD_1
	v_pk_fma_f32 v[72:73], v[224:225], v[250:251], v[72:73] op_sel:[0,1,0] op_sel_hi:[1,1,1]
	v_pk_fma_f32 v[74:75], v[226:227], v[250:251], v[74:75] op_sel:[0,1,0] op_sel_hi:[1,1,1]
	v_pk_fma_f32 v[76:77], v[228:229], v[250:251], v[76:77] op_sel:[0,1,0] op_sel_hi:[1,1,1]
	v_pk_fma_f32 v[78:79], v[230:231], v[250:251], v[78:79] op_sel:[0,1,0] op_sel_hi:[1,1,1]
	s_sub_i32 s90, s90, 1
	s_cmp_eq_u32 s90, 0
	s_cbranch_scc1 .LV_sw3
.LV_t4_s3:
	s_waitcnt lgkmcnt(0)
	buffer_load_dwordx4 v[160:163], v[232:233], s[60:63], 0 idxen offen
	buffer_load_dwordx4 v[164:167], v[234:235], s[60:63], 0 idxen offen
	buffer_load_dwordx4 v[168:171], v[236:237], s[60:63], 0 idxen offen
	buffer_load_dwordx4 v[172:175], v[238:239], s[60:63], 0 idxen offen
	ds_read_b32 v232, v213 offset:112
	ds_read_b32 v234, v213 offset:116
	ds_read_b32 v236, v213 offset:120
	ds_read_b32 v238, v213 offset:124
	ds_read_b128 v[248:251], v213 offset:5056
	s_waitcnt vmcnt(12)
	v_cvt_pk_f32_fp8_e32 v[224:225], v176
	v_cvt_pk_f32_fp8_sdwa v[226:227], v176 src0_sel:WORD_1
	v_cvt_pk_f32_fp8_e32 v[228:229], v177
	v_cvt_pk_f32_fp8_sdwa v[230:231], v177 src0_sel:WORD_1
	v_pk_fma_f32 v[64:65], v[224:225], v[252:253], v[64:65] op_sel_hi:[1,0,1]
	v_pk_fma_f32 v[66:67], v[226:227], v[252:253], v[66:67] op_sel_hi:[1,0,1]
	v_pk_fma_f32 v[68:69], v[228:229], v[252:253], v[68:69] op_sel_hi:[1,0,1]
	v_pk_fma_f32 v[70:71], v[230:231], v[252:253], v[70:71] op_sel_hi:[1,0,1]
	v_cvt_pk_f32_fp8_e32 v[224:225], v178
	v_cvt_pk_f32_fp8_sdwa v[226:227], v178 src0_sel:WORD_1
	v_cvt_pk_f32_fp8_e32 v[228:229], v179
	v_cvt_pk_f32_fp8_sdwa v[230:231], v179 src0_sel:WORD_1
	v_pk_fma_f32 v[72:73], v[224:225], v[252:253], v[72:73] op_sel_hi:[1,0,1]
	v_pk_fma_f32 v[74:75], v[226:227], v[252:253], v[74:75] op_sel_hi:[1,0,1]
	v_pk_fma_f32 v[76:77], v[228:229], v[252:253], v[76:77] op_sel_hi:[1,0,1]
	v_pk_fma_f32 v[78:79], v[230:231], v[252:253], v[78:79] op_sel_hi:[1,0,1]
	v_cvt_pk_f32_fp8_e32 v[224:225], v180
	v_cvt_pk_f32_fp8_sdwa v[226:227], v180 src0_sel:WORD_1
	v_cvt_pk_f32_fp8_e32 v[228:229], v181
	v_cvt_pk_f32_fp8_sdwa v[230:231], v181 src0_sel:WORD_1
	v_pk_fma_f32 v[64:65], v[224:225], v[252:253], v[64:65] op_sel:[0,1,0] op_sel_hi:[1,1,1]
	v_pk_fma_f32 v[66:67], v[226:227], v[252:253], v[66:67] op_sel:[0,1,0] op_sel_hi:[1,1,1]
	v_pk_fma_f32 v[68:69], v[228:229], v[252:253], v[68:69] op_sel:[0,1,0] op_sel_hi:[1,1,1]
	v_pk_fma_f32 v[70:71], v[230:231], v[252:253], v[70:71] op_sel:[0,1,0] op_sel_hi:[1,1,1]
	v_cvt_pk_f32_fp8_e32 v[224:225], v182
	v_cvt_pk_f32_fp8_sdwa v[226:227], v182 src0_sel:WORD_1
	v_cvt_pk_f32_fp8_e32 v[228:229], v183
	v_cvt_pk_f32_fp8_sdwa v[230:231], v183 src0_sel:WORD_1
	v_pk_fma_f32 v[72:73], v[224:225], v[252:253], v[72:73] op_sel:[0,1,0] op_sel_hi:[1,1,1]
	v_pk_fma_f32 v[74:75], v[226:227], v[252:253], v[74:75] op_sel:[0,1,0] op_sel_hi:[1,1,1]
	v_pk_fma_f32 v[76:77], v[228:229], v[252:253], v[76:77] op_sel:[0,1,0] op_sel_hi:[1,1,1]
	v_pk_fma_f32 v[78:79], v[230:231], v[252:253], v[78:79] op_sel:[0,1,0] op_sel_hi:[1,1,1]
	v_cvt_pk_f32_fp8_e32 v[224:225], v184
	v_cvt_pk_f32_fp8_sdwa v[226:227], v184 src0_sel:WORD_1
	v_cvt_pk_f32_fp8_e32 v[228:229], v185
	v_cvt_pk_f32_fp8_sdwa v[230:231], v185 src0_sel:WORD_1
	v_pk_fma_f32 v[64:65], v[224:225], v[254:255], v[64:65] op_sel_hi:[1,0,1]
	v_pk_fma_f32 v[66:67], v[226:227], v[254:255], v[66:67] op_sel_hi:[1,0,1]
	v_pk_fma_f32 v[68:69], v[228:229], v[254:255], v[68:69] op_sel_hi:[1,0,1]
	v_pk_fma_f32 v[70:71], v[230:231], v[254:255], v[70:71] op_sel_hi:[1,0,1]
	v_cvt_pk_f32_fp8_e32 v[224:225], v186
	v_cvt_pk_f32_fp8_sdwa v[226:227], v186 src0_sel:WORD_1
	v_cvt_pk_f32_fp8_e32 v[228:229], v187
	v_cvt_pk_f32_fp8_sdwa v[230:231], v187 src0_sel:WORD_1
	v_pk_fma_f32 v[72:73], v[224:225], v[254:255], v[72:73] op_sel_hi:[1,0,1]
	v_pk_fma_f32 v[74:75], v[226:227], v[254:255], v[74:75] op_sel_hi:[1,0,1]
	v_pk_fma_f32 v[76:77], v[228:229], v[254:255], v[76:77] op_sel_hi:[1,0,1]
	v_pk_fma_f32 v[78:79], v[230:231], v[254:255], v[78:79] op_sel_hi:[1,0,1]
	v_cvt_pk_f32_fp8_e32 v[224:225], v188
	v_cvt_pk_f32_fp8_sdwa v[226:227], v188 src0_sel:WORD_1
	v_cvt_pk_f32_fp8_e32 v[228:229], v189
	v_cvt_pk_f32_fp8_sdwa v[230:231], v189 src0_sel:WORD_1
	v_pk_fma_f32 v[64:65], v[224:225], v[254:255], v[64:65] op_sel:[0,1,0] op_sel_hi:[1,1,1]
	v_pk_fma_f32 v[66:67], v[226:227], v[254:255], v[66:67] op_sel:[0,1,0] op_sel_hi:[1,1,1]
	v_pk_fma_f32 v[68:69], v[228:229], v[254:255], v[68:69] op_sel:[0,1,0] op_sel_hi:[1,1,1]
	v_pk_fma_f32 v[70:71], v[230:231], v[254:255], v[70:71] op_sel:[0,1,0] op_sel_hi:[1,1,1]
	v_cvt_pk_f32_fp8_e32 v[224:225], v190
	v_cvt_pk_f32_fp8_sdwa v[226:227], v190 src0_sel:WORD_1
	v_cvt_pk_f32_fp8_e32 v[228:229], v191
	v_cvt_pk_f32_fp8_sdwa v[230:231], v191 src0_sel:WORD_1
	v_pk_fma_f32 v[72:73], v[224:225], v[254:255], v[72:73] op_sel:[0,1,0] op_sel_hi:[1,1,1]
	v_pk_fma_f32 v[74:75], v[226:227], v[254:255], v[74:75] op_sel:[0,1,0] op_sel_hi:[1,1,1]
	v_pk_fma_f32 v[76:77], v[228:229], v[254:255], v[76:77] op_sel:[0,1,0] op_sel_hi:[1,1,1]
	v_pk_fma_f32 v[78:79], v[230:231], v[254:255], v[78:79] op_sel:[0,1,0] op_sel_hi:[1,1,1]
	v_add_u32_e32 v213, 64, v213
	s_add_i32 s21, s21, 4
	s_sub_i32 s90, s90, 1
	s_cmp_eq_u32 s90, 0
	s_cbranch_scc1 .LV_sw0
	s_branch .LV_t4_s0
.LV_t5_s0:
	s_cmp_ge_u32 s21, s20
	s_cbranch_scc1 .LV_done
	s_waitcnt lgkmcnt(0)
	buffer_load_dwordx4 v[176:179], v[232:233], s[60:63], 0 idxen offen
	buffer_load_dwordx4 v[180:183], v[234:235], s[60:63], 0 idxen offen
	buffer_load_dwordx4 v[184:187], v[236:237], s[60:63], 0 idxen offen
	buffer_load_dwordx4 v[188:191], v[238:239], s[60:63], 0 idxen offen
	ds_read_b32 v232, v213 offset:64
	ds_read_b32 v234, v213 offset:68
	ds_read_b32 v236, v213 offset:72
	ds_read_b32 v238, v213 offset:76
	ds_read_b128 v[252:255], v213 offset:5008
	s_waitcnt vmcnt(12)
	v_cvt_pk_f32_fp8_e32 v[224:225], v128
	v_cvt_pk_f32_fp8_sdwa v[226:227], v128 src0_sel:WORD_1
	v_cvt_pk_f32_fp8_e32 v[228:229], v129
	v_cvt_pk_f32_fp8_sdwa v[230:231], v129 src0_sel:WORD_1
	v_pk_fma_f32 v[80:81], v[224:225], v[248:249], v[80:81] op_sel_hi:[1,0,1]
	v_pk_fma_f32 v[82:83], v[226:227], v[248:249], v[82:83] op_sel_hi:[1,0,1]
	v_pk_fma_f32 v[84:85], v[228:229], v[248:249], v[84:85] op_sel_hi:[1,0,1]
	v_pk_fma_f32 v[86:87], v[230:231], v[248:249], v[86:87] op_sel_hi:[1,0,1]
	v_cvt_pk_f32_fp8_e32 v[224:225], v130
	v_cvt_pk_f32_fp8_sdwa v[226:227], v130 src0_sel:WORD_1
	v_cvt_pk_f32_fp8_e32 v[228:229], v131
	v_cvt_pk_f32_fp8_sdwa v[230:231], v131 src0_sel:WORD_1
	v_pk_fma_f32 v[88:89], v[224:225], v[248:249], v[88:89] op_sel_hi:[1,0,1]
	v_pk_fma_f32 v[90:91], v[226:227], v[248:249], v[90:91] op_sel_hi:[1,0,1]
	v_pk_fma_f32 v[92:93], v[228:229], v[248:249], v[92:93] op_sel_hi:[1,0,1]
	v_pk_fma_f32 v[94:95], v[230:231], v[248:249], v[94:95] op_sel_hi:[1,0,1]
	v_cvt_pk_f32_fp8_e32 v[224:225], v132
	v_cvt_pk_f32_fp8_sdwa v[226:227], v132 src0_sel:WORD_1
	v_cvt_pk_f32_fp8_e32 v[228:229], v133
	v_cvt_pk_f32_fp8_sdwa v[230:231], v133 src0_sel:WORD_1
	v_pk_fma_f32 v[80:81], v[224:225], v[248:249], v[80:81] op_sel:[0,1,0] op_sel_hi:[1,1,1]
	v_pk_fma_f32 v[82:83], v[226:227], v[248:249], v[82:83] op_sel:[0,1,0] op_sel_hi:[1,1,1]
	v_pk_fma_f32 v[84:85], v[228:229], v[248:249], v[84:85] op_sel:[0,1,0] op_sel_hi:[1,1,1]
	v_pk_fma_f32 v[86:87], v[230:231], v[248:249], v[86:87] op_sel:[0,1,0] op_sel_hi:[1,1,1]
	v_cvt_pk_f32_fp8_e32 v[224:225], v134
	v_cvt_pk_f32_fp8_sdwa v[226:227], v134 src0_sel:WORD_1
	v_cvt_pk_f32_fp8_e32 v[228:229], v135
	v_cvt_pk_f32_fp8_sdwa v[230:231], v135 src0_sel:WORD_1
	v_pk_fma_f32 v[88:89], v[224:225], v[248:249], v[88:89] op_sel:[0,1,0] op_sel_hi:[1,1,1]
	v_pk_fma_f32 v[90:91], v[226:227], v[248:249], v[90:91] op_sel:[0,1,0] op_sel_hi:[1,1,1]
	v_pk_fma_f32 v[92:93], v[228:229], v[248:249], v[92:93] op_sel:[0,1,0] op_sel_hi:[1,1,1]
	v_pk_fma_f32 v[94:95], v[230:231], v[248:249], v[94:95] op_sel:[0,1,0] op_sel_hi:[1,1,1]
	v_cvt_pk_f32_fp8_e32 v[224:225], v136
	v_cvt_pk_f32_fp8_sdwa v[226:227], v136 src0_sel:WORD_1
	v_cvt_pk_f32_fp8_e32 v[228:229], v137
	v_cvt_pk_f32_fp8_sdwa v[230:231], v137 src0_sel:WORD_1
	v_pk_fma_f32 v[80:81], v[224:225], v[250:251], v[80:81] op_sel_hi:[1,0,1]
	v_pk_fma_f32 v[82:83], v[226:227], v[250:251], v[82:83] op_sel_hi:[1,0,1]
	v_pk_fma_f32 v[84:85], v[228:229], v[250:251], v[84:85] op_sel_hi:[1,0,1]
	v_pk_fma_f32 v[86:87], v[230:231], v[250:251], v[86:87] op_sel_hi:[1,0,1]
	v_cvt_pk_f32_fp8_e32 v[224:225], v138
	v_cvt_pk_f32_fp8_sdwa v[226:227], v138 src0_sel:WORD_1
	v_cvt_pk_f32_fp8_e32 v[228:229], v139
	v_cvt_pk_f32_fp8_sdwa v[230:231], v139 src0_sel:WORD_1
	v_pk_fma_f32 v[88:89], v[224:225], v[250:251], v[88:89] op_sel_hi:[1,0,1]
	v_pk_fma_f32 v[90:91], v[226:227], v[250:251], v[90:91] op_sel_hi:[1,0,1]
	v_pk_fma_f32 v[92:93], v[228:229], v[250:251], v[92:93] op_sel_hi:[1,0,1]
	v_pk_fma_f32 v[94:95], v[230:231], v[250:251], v[94:95] op_sel_hi:[1,0,1]
	v_cvt_pk_f32_fp8_e32 v[224:225], v140
	v_cvt_pk_f32_fp8_sdwa v[226:227], v140 src0_sel:WORD_1
	v_cvt_pk_f32_fp8_e32 v[228:229], v141
	v_cvt_pk_f32_fp8_sdwa v[230:231], v141 src0_sel:WORD_1
	v_pk_fma_f32 v[80:81], v[224:225], v[250:251], v[80:81] op_sel:[0,1,0] op_sel_hi:[1,1,1]
	v_pk_fma_f32 v[82:83], v[226:227], v[250:251], v[82:83] op_sel:[0,1,0] op_sel_hi:[1,1,1]
	v_pk_fma_f32 v[84:85], v[228:229], v[250:251], v[84:85] op_sel:[0,1,0] op_sel_hi:[1,1,1]
	v_pk_fma_f32 v[86:87], v[230:231], v[250:251], v[86:87] op_sel:[0,1,0] op_sel_hi:[1,1,1]
	v_cvt_pk_f32_fp8_e32 v[224:225], v142
	v_cvt_pk_f32_fp8_sdwa v[226:227], v142 src0_sel:WORD_1
	v_cvt_pk_f32_fp8_e32 v[228:229], v143
	v_cvt_pk_f32_fp8_sdwa v[230:231], v143 src0_sel:WORD_1
	v_pk_fma_f32 v[88:89], v[224:225], v[250:251], v[88:89] op_sel:[0,1,0] op_sel_hi:[1,1,1]
	v_pk_fma_f32 v[90:91], v[226:227], v[250:251], v[90:91] op_sel:[0,1,0] op_sel_hi:[1,1,1]
	v_pk_fma_f32 v[92:93], v[228:229], v[250:251], v[92:93] op_sel:[0,1,0] op_sel_hi:[1,1,1]
	v_pk_fma_f32 v[94:95], v[230:231], v[250:251], v[94:95] op_sel:[0,1,0] op_sel_hi:[1,1,1]
	s_sub_i32 s90, s90, 1
	s_cmp_eq_u32 s90, 0
	s_cbranch_scc1 .LV_sw1
.LV_t5_s1:
	s_waitcnt lgkmcnt(0)
	buffer_load_dwordx4 v[128:131], v[232:233], s[60:63], 0 idxen offen
	buffer_load_dwordx4 v[132:135], v[234:235], s[60:63], 0 idxen offen
	buffer_load_dwordx4 v[136:139], v[236:237], s[60:63], 0 idxen offen
	buffer_load_dwordx4 v[140:143], v[238:239], s[60:63], 0 idxen offen
	ds_read_b32 v232, v213 offset:80
	ds_read_b32 v234, v213 offset:84
	ds_read_b32 v236, v213 offset:88
	ds_read_b32 v238, v213 offset:92
	ds_read_b128 v[248:251], v213 offset:5024
	s_waitcnt vmcnt(12)
	v_cvt_pk_f32_fp8_e32 v[224:225], v144
	v_cvt_pk_f32_fp8_sdwa v[226:227], v144 src0_sel:WORD_1
	v_cvt_pk_f32_fp8_e32 v[228:229], v145
	v_cvt_pk_f32_fp8_sdwa v[230:231], v145 src0_sel:WORD_1
	v_pk_fma_f32 v[80:81], v[224:225], v[252:253], v[80:81] op_sel_hi:[1,0,1]
	v_pk_fma_f32 v[82:83], v[226:227], v[252:253], v[82:83] op_sel_hi:[1,0,1]
	v_pk_fma_f32 v[84:85], v[228:229], v[252:253], v[84:85] op_sel_hi:[1,0,1]
	v_pk_fma_f32 v[86:87], v[230:231], v[252:253], v[86:87] op_sel_hi:[1,0,1]
	v_cvt_pk_f32_fp8_e32 v[224:225], v146
	v_cvt_pk_f32_fp8_sdwa v[226:227], v146 src0_sel:WORD_1
	v_cvt_pk_f32_fp8_e32 v[228:229], v147
	v_cvt_pk_f32_fp8_sdwa v[230:231], v147 src0_sel:WORD_1
	v_pk_fma_f32 v[88:89], v[224:225], v[252:253], v[88:89] op_sel_hi:[1,0,1]
	v_pk_fma_f32 v[90:91], v[226:227], v[252:253], v[90:91] op_sel_hi:[1,0,1]
	v_pk_fma_f32 v[92:93], v[228:229], v[252:253], v[92:93] op_sel_hi:[1,0,1]
	v_pk_fma_f32 v[94:95], v[230:231], v[252:253], v[94:95] op_sel_hi:[1,0,1]
	v_cvt_pk_f32_fp8_e32 v[224:225], v148
	v_cvt_pk_f32_fp8_sdwa v[226:227], v148 src0_sel:WORD_1
	v_cvt_pk_f32_fp8_e32 v[228:229], v149
	v_cvt_pk_f32_fp8_sdwa v[230:231], v149 src0_sel:WORD_1
	v_pk_fma_f32 v[80:81], v[224:225], v[252:253], v[80:81] op_sel:[0,1,0] op_sel_hi:[1,1,1]
	v_pk_fma_f32 v[82:83], v[226:227], v[252:253], v[82:83] op_sel:[0,1,0] op_sel_hi:[1,1,1]
	v_pk_fma_f32 v[84:85], v[228:229], v[252:253], v[84:85] op_sel:[0,1,0] op_sel_hi:[1,1,1]
	v_pk_fma_f32 v[86:87], v[230:231], v[252:253], v[86:87] op_sel:[0,1,0] op_sel_hi:[1,1,1]
	v_cvt_pk_f32_fp8_e32 v[224:225], v150
	v_cvt_pk_f32_fp8_sdwa v[226:227], v150 src0_sel:WORD_1
	v_cvt_pk_f32_fp8_e32 v[228:229], v151
	v_cvt_pk_f32_fp8_sdwa v[230:231], v151 src0_sel:WORD_1
	v_pk_fma_f32 v[88:89], v[224:225], v[252:253], v[88:89] op_sel:[0,1,0] op_sel_hi:[1,1,1]
	v_pk_fma_f32 v[90:91], v[226:227], v[252:253], v[90:91] op_sel:[0,1,0] op_sel_hi:[1,1,1]
	v_pk_fma_f32 v[92:93], v[228:229], v[252:253], v[92:93] op_sel:[0,1,0] op_sel_hi:[1,1,1]
	v_pk_fma_f32 v[94:95], v[230:231], v[252:253], v[94:95] op_sel:[0,1,0] op_sel_hi:[1,1,1]
	v_cvt_pk_f32_fp8_e32 v[224:225], v152
	v_cvt_pk_f32_fp8_sdwa v[226:227], v152 src0_sel:WORD_1
	v_cvt_pk_f32_fp8_e32 v[228:229], v153
	v_cvt_pk_f32_fp8_sdwa v[230:231], v153 src0_sel:WORD_1
	v_pk_fma_f32 v[80:81], v[224:225], v[254:255], v[80:81] op_sel_hi:[1,0,1]
	v_pk_fma_f32 v[82:83], v[226:227], v[254:255], v[82:83] op_sel_hi:[1,0,1]
	v_pk_fma_f32 v[84:85], v[228:229], v[254:255], v[84:85] op_sel_hi:[1,0,1]
	v_pk_fma_f32 v[86:87], v[230:231], v[254:255], v[86:87] op_sel_hi:[1,0,1]
	v_cvt_pk_f32_fp8_e32 v[224:225], v154
	v_cvt_pk_f32_fp8_sdwa v[226:227], v154 src0_sel:WORD_1
	v_cvt_pk_f32_fp8_e32 v[228:229], v155
	v_cvt_pk_f32_fp8_sdwa v[230:231], v155 src0_sel:WORD_1
	v_pk_fma_f32 v[88:89], v[224:225], v[254:255], v[88:89] op_sel_hi:[1,0,1]
	v_pk_fma_f32 v[90:91], v[226:227], v[254:255], v[90:91] op_sel_hi:[1,0,1]
	v_pk_fma_f32 v[92:93], v[228:229], v[254:255], v[92:93] op_sel_hi:[1,0,1]
	v_pk_fma_f32 v[94:95], v[230:231], v[254:255], v[94:95] op_sel_hi:[1,0,1]
	v_cvt_pk_f32_fp8_e32 v[224:225], v156
	v_cvt_pk_f32_fp8_sdwa v[226:227], v156 src0_sel:WORD_1
	v_cvt_pk_f32_fp8_e32 v[228:229], v157
	v_cvt_pk_f32_fp8_sdwa v[230:231], v157 src0_sel:WORD_1
	v_pk_fma_f32 v[80:81], v[224:225], v[254:255], v[80:81] op_sel:[0,1,0] op_sel_hi:[1,1,1]
	v_pk_fma_f32 v[82:83], v[226:227], v[254:255], v[82:83] op_sel:[0,1,0] op_sel_hi:[1,1,1]
	v_pk_fma_f32 v[84:85], v[228:229], v[254:255], v[84:85] op_sel:[0,1,0] op_sel_hi:[1,1,1]
	v_pk_fma_f32 v[86:87], v[230:231], v[254:255], v[86:87] op_sel:[0,1,0] op_sel_hi:[1,1,1]
	v_cvt_pk_f32_fp8_e32 v[224:225], v158
	v_cvt_pk_f32_fp8_sdwa v[226:227], v158 src0_sel:WORD_1
	v_cvt_pk_f32_fp8_e32 v[228:229], v159
	v_cvt_pk_f32_fp8_sdwa v[230:231], v159 src0_sel:WORD_1
	v_pk_fma_f32 v[88:89], v[224:225], v[254:255], v[88:89] op_sel:[0,1,0] op_sel_hi:[1,1,1]
	v_pk_fma_f32 v[90:91], v[226:227], v[254:255], v[90:91] op_sel:[0,1,0] op_sel_hi:[1,1,1]
	v_pk_fma_f32 v[92:93], v[228:229], v[254:255], v[92:93] op_sel:[0,1,0] op_sel_hi:[1,1,1]
	v_pk_fma_f32 v[94:95], v[230:231], v[254:255], v[94:95] op_sel:[0,1,0] op_sel_hi:[1,1,1]
	s_sub_i32 s90, s90, 1
	s_cmp_eq_u32 s90, 0
	s_cbranch_scc1 .LV_sw2
.LV_t5_s2:
	s_waitcnt lgkmcnt(0)
	buffer_load_dwordx4 v[144:147], v[232:233], s[60:63], 0 idxen offen
	buffer_load_dwordx4 v[148:151], v[234:235], s[60:63], 0 idxen offen
	buffer_load_dwordx4 v[152:155], v[236:237], s[60:63], 0 idxen offen
	buffer_load_dwordx4 v[156:159], v[238:239], s[60:63], 0 idxen offen
	ds_read_b32 v232, v213 offset:96
	ds_read_b32 v234, v213 offset:100
	ds_read_b32 v236, v213 offset:104
	ds_read_b32 v238, v213 offset:108
	ds_read_b128 v[252:255], v213 offset:5040
	s_waitcnt vmcnt(12)
	v_cvt_pk_f32_fp8_e32 v[224:225], v160
	v_cvt_pk_f32_fp8_sdwa v[226:227], v160 src0_sel:WORD_1
	v_cvt_pk_f32_fp8_e32 v[228:229], v161
	v_cvt_pk_f32_fp8_sdwa v[230:231], v161 src0_sel:WORD_1
	v_pk_fma_f32 v[80:81], v[224:225], v[248:249], v[80:81] op_sel_hi:[1,0,1]
	v_pk_fma_f32 v[82:83], v[226:227], v[248:249], v[82:83] op_sel_hi:[1,0,1]
	v_pk_fma_f32 v[84:85], v[228:229], v[248:249], v[84:85] op_sel_hi:[1,0,1]
	v_pk_fma_f32 v[86:87], v[230:231], v[248:249], v[86:87] op_sel_hi:[1,0,1]
	v_cvt_pk_f32_fp8_e32 v[224:225], v162
	v_cvt_pk_f32_fp8_sdwa v[226:227], v162 src0_sel:WORD_1
	v_cvt_pk_f32_fp8_e32 v[228:229], v163
	v_cvt_pk_f32_fp8_sdwa v[230:231], v163 src0_sel:WORD_1
	v_pk_fma_f32 v[88:89], v[224:225], v[248:249], v[88:89] op_sel_hi:[1,0,1]
	v_pk_fma_f32 v[90:91], v[226:227], v[248:249], v[90:91] op_sel_hi:[1,0,1]
	v_pk_fma_f32 v[92:93], v[228:229], v[248:249], v[92:93] op_sel_hi:[1,0,1]
	v_pk_fma_f32 v[94:95], v[230:231], v[248:249], v[94:95] op_sel_hi:[1,0,1]
	v_cvt_pk_f32_fp8_e32 v[224:225], v164
	v_cvt_pk_f32_fp8_sdwa v[226:227], v164 src0_sel:WORD_1
	v_cvt_pk_f32_fp8_e32 v[228:229], v165
	v_cvt_pk_f32_fp8_sdwa v[230:231], v165 src0_sel:WORD_1
	v_pk_fma_f32 v[80:81], v[224:225], v[248:249], v[80:81] op_sel:[0,1,0] op_sel_hi:[1,1,1]
	v_pk_fma_f32 v[82:83], v[226:227], v[248:249], v[82:83] op_sel:[0,1,0] op_sel_hi:[1,1,1]
	v_pk_fma_f32 v[84:85], v[228:229], v[248:249], v[84:85] op_sel:[0,1,0] op_sel_hi:[1,1,1]
	v_pk_fma_f32 v[86:87], v[230:231], v[248:249], v[86:87] op_sel:[0,1,0] op_sel_hi:[1,1,1]
	v_cvt_pk_f32_fp8_e32 v[224:225], v166
	v_cvt_pk_f32_fp8_sdwa v[226:227], v166 src0_sel:WORD_1
	v_cvt_pk_f32_fp8_e32 v[228:229], v167
	v_cvt_pk_f32_fp8_sdwa v[230:231], v167 src0_sel:WORD_1
	v_pk_fma_f32 v[88:89], v[224:225], v[248:249], v[88:89] op_sel:[0,1,0] op_sel_hi:[1,1,1]
	v_pk_fma_f32 v[90:91], v[226:227], v[248:249], v[90:91] op_sel:[0,1,0] op_sel_hi:[1,1,1]
	v_pk_fma_f32 v[92:93], v[228:229], v[248:249], v[92:93] op_sel:[0,1,0] op_sel_hi:[1,1,1]
	v_pk_fma_f32 v[94:95], v[230:231], v[248:249], v[94:95] op_sel:[0,1,0] op_sel_hi:[1,1,1]
	v_cvt_pk_f32_fp8_e32 v[224:225], v168
	v_cvt_pk_f32_fp8_sdwa v[226:227], v168 src0_sel:WORD_1
	v_cvt_pk_f32_fp8_e32 v[228:229], v169
	v_cvt_pk_f32_fp8_sdwa v[230:231], v169 src0_sel:WORD_1
	v_pk_fma_f32 v[80:81], v[224:225], v[250:251], v[80:81] op_sel_hi:[1,0,1]
	v_pk_fma_f32 v[82:83], v[226:227], v[250:251], v[82:83] op_sel_hi:[1,0,1]
	v_pk_fma_f32 v[84:85], v[228:229], v[250:251], v[84:85] op_sel_hi:[1,0,1]
	v_pk_fma_f32 v[86:87], v[230:231], v[250:251], v[86:87] op_sel_hi:[1,0,1]
	v_cvt_pk_f32_fp8_e32 v[224:225], v170
	v_cvt_pk_f32_fp8_sdwa v[226:227], v170 src0_sel:WORD_1
	v_cvt_pk_f32_fp8_e32 v[228:229], v171
	v_cvt_pk_f32_fp8_sdwa v[230:231], v171 src0_sel:WORD_1
	v_pk_fma_f32 v[88:89], v[224:225], v[250:251], v[88:89] op_sel_hi:[1,0,1]
	v_pk_fma_f32 v[90:91], v[226:227], v[250:251], v[90:91] op_sel_hi:[1,0,1]
	v_pk_fma_f32 v[92:93], v[228:229], v[250:251], v[92:93] op_sel_hi:[1,0,1]
	v_pk_fma_f32 v[94:95], v[230:231], v[250:251], v[94:95] op_sel_hi:[1,0,1]
	v_cvt_pk_f32_fp8_e32 v[224:225], v172
	v_cvt_pk_f32_fp8_sdwa v[226:227], v172 src0_sel:WORD_1
	v_cvt_pk_f32_fp8_e32 v[228:229], v173
	v_cvt_pk_f32_fp8_sdwa v[230:231], v173 src0_sel:WORD_1
	v_pk_fma_f32 v[80:81], v[224:225], v[250:251], v[80:81] op_sel:[0,1,0] op_sel_hi:[1,1,1]
	v_pk_fma_f32 v[82:83], v[226:227], v[250:251], v[82:83] op_sel:[0,1,0] op_sel_hi:[1,1,1]
	v_pk_fma_f32 v[84:85], v[228:229], v[250:251], v[84:85] op_sel:[0,1,0] op_sel_hi:[1,1,1]
	v_pk_fma_f32 v[86:87], v[230:231], v[250:251], v[86:87] op_sel:[0,1,0] op_sel_hi:[1,1,1]
	v_cvt_pk_f32_fp8_e32 v[224:225], v174
	v_cvt_pk_f32_fp8_sdwa v[226:227], v174 src0_sel:WORD_1
	v_cvt_pk_f32_fp8_e32 v[228:229], v175
	v_cvt_pk_f32_fp8_sdwa v[230:231], v175 src0_sel:WORD_1
	v_pk_fma_f32 v[88:89], v[224:225], v[250:251], v[88:89] op_sel:[0,1,0] op_sel_hi:[1,1,1]
	v_pk_fma_f32 v[90:91], v[226:227], v[250:251], v[90:91] op_sel:[0,1,0] op_sel_hi:[1,1,1]
	v_pk_fma_f32 v[92:93], v[228:229], v[250:251], v[92:93] op_sel:[0,1,0] op_sel_hi:[1,1,1]
	v_pk_fma_f32 v[94:95], v[230:231], v[250:251], v[94:95] op_sel:[0,1,0] op_sel_hi:[1,1,1]
	s_sub_i32 s90, s90, 1
	s_cmp_eq_u32 s90, 0
	s_cbranch_scc1 .LV_sw3
.LV_t5_s3:
	s_waitcnt lgkmcnt(0)
	buffer_load_dwordx4 v[160:163], v[232:233], s[60:63], 0 idxen offen
	buffer_load_dwordx4 v[164:167], v[234:235], s[60:63], 0 idxen offen
	buffer_load_dwordx4 v[168:171], v[236:237], s[60:63], 0 idxen offen
	buffer_load_dwordx4 v[172:175], v[238:239], s[60:63], 0 idxen offen
	ds_read_b32 v232, v213 offset:112
	ds_read_b32 v234, v213 offset:116
	ds_read_b32 v236, v213 offset:120
	ds_read_b32 v238, v213 offset:124
	ds_read_b128 v[248:251], v213 offset:5056
	s_waitcnt vmcnt(12)
	v_cvt_pk_f32_fp8_e32 v[224:225], v176
	v_cvt_pk_f32_fp8_sdwa v[226:227], v176 src0_sel:WORD_1
	v_cvt_pk_f32_fp8_e32 v[228:229], v177
	v_cvt_pk_f32_fp8_sdwa v[230:231], v177 src0_sel:WORD_1
	v_pk_fma_f32 v[80:81], v[224:225], v[252:253], v[80:81] op_sel_hi:[1,0,1]
	v_pk_fma_f32 v[82:83], v[226:227], v[252:253], v[82:83] op_sel_hi:[1,0,1]
	v_pk_fma_f32 v[84:85], v[228:229], v[252:253], v[84:85] op_sel_hi:[1,0,1]
	v_pk_fma_f32 v[86:87], v[230:231], v[252:253], v[86:87] op_sel_hi:[1,0,1]
	v_cvt_pk_f32_fp8_e32 v[224:225], v178
	v_cvt_pk_f32_fp8_sdwa v[226:227], v178 src0_sel:WORD_1
	v_cvt_pk_f32_fp8_e32 v[228:229], v179
	v_cvt_pk_f32_fp8_sdwa v[230:231], v179 src0_sel:WORD_1
	v_pk_fma_f32 v[88:89], v[224:225], v[252:253], v[88:89] op_sel_hi:[1,0,1]
	v_pk_fma_f32 v[90:91], v[226:227], v[252:253], v[90:91] op_sel_hi:[1,0,1]
	v_pk_fma_f32 v[92:93], v[228:229], v[252:253], v[92:93] op_sel_hi:[1,0,1]
	v_pk_fma_f32 v[94:95], v[230:231], v[252:253], v[94:95] op_sel_hi:[1,0,1]
	v_cvt_pk_f32_fp8_e32 v[224:225], v180
	v_cvt_pk_f32_fp8_sdwa v[226:227], v180 src0_sel:WORD_1
	v_cvt_pk_f32_fp8_e32 v[228:229], v181
	v_cvt_pk_f32_fp8_sdwa v[230:231], v181 src0_sel:WORD_1
	v_pk_fma_f32 v[80:81], v[224:225], v[252:253], v[80:81] op_sel:[0,1,0] op_sel_hi:[1,1,1]
	v_pk_fma_f32 v[82:83], v[226:227], v[252:253], v[82:83] op_sel:[0,1,0] op_sel_hi:[1,1,1]
	v_pk_fma_f32 v[84:85], v[228:229], v[252:253], v[84:85] op_sel:[0,1,0] op_sel_hi:[1,1,1]
	v_pk_fma_f32 v[86:87], v[230:231], v[252:253], v[86:87] op_sel:[0,1,0] op_sel_hi:[1,1,1]
	v_cvt_pk_f32_fp8_e32 v[224:225], v182
	v_cvt_pk_f32_fp8_sdwa v[226:227], v182 src0_sel:WORD_1
	v_cvt_pk_f32_fp8_e32 v[228:229], v183
	v_cvt_pk_f32_fp8_sdwa v[230:231], v183 src0_sel:WORD_1
	v_pk_fma_f32 v[88:89], v[224:225], v[252:253], v[88:89] op_sel:[0,1,0] op_sel_hi:[1,1,1]
	v_pk_fma_f32 v[90:91], v[226:227], v[252:253], v[90:91] op_sel:[0,1,0] op_sel_hi:[1,1,1]
	v_pk_fma_f32 v[92:93], v[228:229], v[252:253], v[92:93] op_sel:[0,1,0] op_sel_hi:[1,1,1]
	v_pk_fma_f32 v[94:95], v[230:231], v[252:253], v[94:95] op_sel:[0,1,0] op_sel_hi:[1,1,1]
	v_cvt_pk_f32_fp8_e32 v[224:225], v184
	v_cvt_pk_f32_fp8_sdwa v[226:227], v184 src0_sel:WORD_1
	v_cvt_pk_f32_fp8_e32 v[228:229], v185
	v_cvt_pk_f32_fp8_sdwa v[230:231], v185 src0_sel:WORD_1
	v_pk_fma_f32 v[80:81], v[224:225], v[254:255], v[80:81] op_sel_hi:[1,0,1]
	v_pk_fma_f32 v[82:83], v[226:227], v[254:255], v[82:83] op_sel_hi:[1,0,1]
	v_pk_fma_f32 v[84:85], v[228:229], v[254:255], v[84:85] op_sel_hi:[1,0,1]
	v_pk_fma_f32 v[86:87], v[230:231], v[254:255], v[86:87] op_sel_hi:[1,0,1]
	v_cvt_pk_f32_fp8_e32 v[224:225], v186
	v_cvt_pk_f32_fp8_sdwa v[226:227], v186 src0_sel:WORD_1
	v_cvt_pk_f32_fp8_e32 v[228:229], v187
	v_cvt_pk_f32_fp8_sdwa v[230:231], v187 src0_sel:WORD_1
	v_pk_fma_f32 v[88:89], v[224:225], v[254:255], v[88:89] op_sel_hi:[1,0,1]
	v_pk_fma_f32 v[90:91], v[226:227], v[254:255], v[90:91] op_sel_hi:[1,0,1]
	v_pk_fma_f32 v[92:93], v[228:229], v[254:255], v[92:93] op_sel_hi:[1,0,1]
	v_pk_fma_f32 v[94:95], v[230:231], v[254:255], v[94:95] op_sel_hi:[1,0,1]
	v_cvt_pk_f32_fp8_e32 v[224:225], v188
	v_cvt_pk_f32_fp8_sdwa v[226:227], v188 src0_sel:WORD_1
	v_cvt_pk_f32_fp8_e32 v[228:229], v189
	v_cvt_pk_f32_fp8_sdwa v[230:231], v189 src0_sel:WORD_1
	v_pk_fma_f32 v[80:81], v[224:225], v[254:255], v[80:81] op_sel:[0,1,0] op_sel_hi:[1,1,1]
	v_pk_fma_f32 v[82:83], v[226:227], v[254:255], v[82:83] op_sel:[0,1,0] op_sel_hi:[1,1,1]
	v_pk_fma_f32 v[84:85], v[228:229], v[254:255], v[84:85] op_sel:[0,1,0] op_sel_hi:[1,1,1]
	v_pk_fma_f32 v[86:87], v[230:231], v[254:255], v[86:87] op_sel:[0,1,0] op_sel_hi:[1,1,1]
	v_cvt_pk_f32_fp8_e32 v[224:225], v190
	v_cvt_pk_f32_fp8_sdwa v[226:227], v190 src0_sel:WORD_1
	v_cvt_pk_f32_fp8_e32 v[228:229], v191
	v_cvt_pk_f32_fp8_sdwa v[230:231], v191 src0_sel:WORD_1
	v_pk_fma_f32 v[88:89], v[224:225], v[254:255], v[88:89] op_sel:[0,1,0] op_sel_hi:[1,1,1]
	v_pk_fma_f32 v[90:91], v[226:227], v[254:255], v[90:91] op_sel:[0,1,0] op_sel_hi:[1,1,1]
	v_pk_fma_f32 v[92:93], v[228:229], v[254:255], v[92:93] op_sel:[0,1,0] op_sel_hi:[1,1,1]
	v_pk_fma_f32 v[94:95], v[230:231], v[254:255], v[94:95] op_sel:[0,1,0] op_sel_hi:[1,1,1]
	v_add_u32_e32 v213, 64, v213
	s_add_i32 s21, s21, 4
	s_sub_i32 s90, s90, 1
	s_cmp_eq_u32 s90, 0
	s_cbranch_scc1 .LV_sw0
	s_branch .LV_t5_s0
.LV_t6_s0:
	s_cmp_ge_u32 s21, s20
	s_cbranch_scc1 .LV_done
	s_waitcnt lgkmcnt(0)
	buffer_load_dwordx4 v[176:179], v[232:233], s[60:63], 0 idxen offen
	buffer_load_dwordx4 v[180:183], v[234:235], s[60:63], 0 idxen offen
	buffer_load_dwordx4 v[184:187], v[236:237], s[60:63], 0 idxen offen
	buffer_load_dwordx4 v[188:191], v[238:239], s[60:63], 0 idxen offen
	ds_read_b32 v232, v213 offset:64
	ds_read_b32 v234, v213 offset:68
	ds_read_b32 v236, v213 offset:72
	ds_read_b32 v238, v213 offset:76
	ds_read_b128 v[252:255], v213 offset:5008
	s_waitcnt vmcnt(12)
	v_cvt_pk_f32_fp8_e32 v[224:225], v128
	v_cvt_pk_f32_fp8_sdwa v[226:227], v128 src0_sel:WORD_1
	v_cvt_pk_f32_fp8_e32 v[228:229], v129
	v_cvt_pk_f32_fp8_sdwa v[230:231], v129 src0_sel:WORD_1
	v_pk_fma_f32 v[96:97], v[224:225], v[248:249], v[96:97] op_sel_hi:[1,0,1]
	v_pk_fma_f32 v[98:99], v[226:227], v[248:249], v[98:99] op_sel_hi:[1,0,1]
	v_pk_fma_f32 v[100:101], v[228:229], v[248:249], v[100:101] op_sel_hi:[1,0,1]
	v_pk_fma_f32 v[102:103], v[230:231], v[248:249], v[102:103] op_sel_hi:[1,0,1]
	v_cvt_pk_f32_fp8_e32 v[224:225], v130
	v_cvt_pk_f32_fp8_sdwa v[226:227], v130 src0_sel:WORD_1
	v_cvt_pk_f32_fp8_e32 v[228:229], v131
	v_cvt_pk_f32_fp8_sdwa v[230:231], v131 src0_sel:WORD_1
	v_pk_fma_f32 v[104:105], v[224:225], v[248:249], v[104:105] op_sel_hi:[1,0,1]
	v_pk_fma_f32 v[106:107], v[226:227], v[248:249], v[106:107] op_sel_hi:[1,0,1]
	v_pk_fma_f32 v[108:109], v[228:229], v[248:249], v[108:109] op_sel_hi:[1,0,1]
	v_pk_fma_f32 v[110:111], v[230:231], v[248:249], v[110:111] op_sel_hi:[1,0,1]
	v_cvt_pk_f32_fp8_e32 v[224:225], v132
	v_cvt_pk_f32_fp8_sdwa v[226:227], v132 src0_sel:WORD_1
	v_cvt_pk_f32_fp8_e32 v[228:229], v133
	v_cvt_pk_f32_fp8_sdwa v[230:231], v133 src0_sel:WORD_1
	v_pk_fma_f32 v[96:97], v[224:225], v[248:249], v[96:97] op_sel:[0,1,0] op_sel_hi:[1,1,1]
	v_pk_fma_f32 v[98:99], v[226:227], v[248:249], v[98:99] op_sel:[0,1,0] op_sel_hi:[1,1,1]
	v_pk_fma_f32 v[100:101], v[228:229], v[248:249], v[100:101] op_sel:[0,1,0] op_sel_hi:[1,1,1]
	v_pk_fma_f32 v[102:103], v[230:231], v[248:249], v[102:103] op_sel:[0,1,0] op_sel_hi:[1,1,1]
	v_cvt_pk_f32_fp8_e32 v[224:225], v134
	v_cvt_pk_f32_fp8_sdwa v[226:227], v134 src0_sel:WORD_1
	v_cvt_pk_f32_fp8_e32 v[228:229], v135
	v_cvt_pk_f32_fp8_sdwa v[230:231], v135 src0_sel:WORD_1
	v_pk_fma_f32 v[104:105], v[224:225], v[248:249], v[104:105] op_sel:[0,1,0] op_sel_hi:[1,1,1]
	v_pk_fma_f32 v[106:107], v[226:227], v[248:249], v[106:107] op_sel:[0,1,0] op_sel_hi:[1,1,1]
	v_pk_fma_f32 v[108:109], v[228:229], v[248:249], v[108:109] op_sel:[0,1,0] op_sel_hi:[1,1,1]
	v_pk_fma_f32 v[110:111], v[230:231], v[248:249], v[110:111] op_sel:[0,1,0] op_sel_hi:[1,1,1]
	v_cvt_pk_f32_fp8_e32 v[224:225], v136
	v_cvt_pk_f32_fp8_sdwa v[226:227], v136 src0_sel:WORD_1
	v_cvt_pk_f32_fp8_e32 v[228:229], v137
	v_cvt_pk_f32_fp8_sdwa v[230:231], v137 src0_sel:WORD_1
	v_pk_fma_f32 v[96:97], v[224:225], v[250:251], v[96:97] op_sel_hi:[1,0,1]
	v_pk_fma_f32 v[98:99], v[226:227], v[250:251], v[98:99] op_sel_hi:[1,0,1]
	v_pk_fma_f32 v[100:101], v[228:229], v[250:251], v[100:101] op_sel_hi:[1,0,1]
	v_pk_fma_f32 v[102:103], v[230:231], v[250:251], v[102:103] op_sel_hi:[1,0,1]
	v_cvt_pk_f32_fp8_e32 v[224:225], v138
	v_cvt_pk_f32_fp8_sdwa v[226:227], v138 src0_sel:WORD_1
	v_cvt_pk_f32_fp8_e32 v[228:229], v139
	v_cvt_pk_f32_fp8_sdwa v[230:231], v139 src0_sel:WORD_1
	v_pk_fma_f32 v[104:105], v[224:225], v[250:251], v[104:105] op_sel_hi:[1,0,1]
	v_pk_fma_f32 v[106:107], v[226:227], v[250:251], v[106:107] op_sel_hi:[1,0,1]
	v_pk_fma_f32 v[108:109], v[228:229], v[250:251], v[108:109] op_sel_hi:[1,0,1]
	v_pk_fma_f32 v[110:111], v[230:231], v[250:251], v[110:111] op_sel_hi:[1,0,1]
	v_cvt_pk_f32_fp8_e32 v[224:225], v140
	v_cvt_pk_f32_fp8_sdwa v[226:227], v140 src0_sel:WORD_1
	v_cvt_pk_f32_fp8_e32 v[228:229], v141
	v_cvt_pk_f32_fp8_sdwa v[230:231], v141 src0_sel:WORD_1
	v_pk_fma_f32 v[96:97], v[224:225], v[250:251], v[96:97] op_sel:[0,1,0] op_sel_hi:[1,1,1]
	v_pk_fma_f32 v[98:99], v[226:227], v[250:251], v[98:99] op_sel:[0,1,0] op_sel_hi:[1,1,1]
	v_pk_fma_f32 v[100:101], v[228:229], v[250:251], v[100:101] op_sel:[0,1,0] op_sel_hi:[1,1,1]
	v_pk_fma_f32 v[102:103], v[230:231], v[250:251], v[102:103] op_sel:[0,1,0] op_sel_hi:[1,1,1]
	v_cvt_pk_f32_fp8_e32 v[224:225], v142
	v_cvt_pk_f32_fp8_sdwa v[226:227], v142 src0_sel:WORD_1
	v_cvt_pk_f32_fp8_e32 v[228:229], v143
	v_cvt_pk_f32_fp8_sdwa v[230:231], v143 src0_sel:WORD_1
	v_pk_fma_f32 v[104:105], v[224:225], v[250:251], v[104:105] op_sel:[0,1,0] op_sel_hi:[1,1,1]
	v_pk_fma_f32 v[106:107], v[226:227], v[250:251], v[106:107] op_sel:[0,1,0] op_sel_hi:[1,1,1]
	v_pk_fma_f32 v[108:109], v[228:229], v[250:251], v[108:109] op_sel:[0,1,0] op_sel_hi:[1,1,1]
	v_pk_fma_f32 v[110:111], v[230:231], v[250:251], v[110:111] op_sel:[0,1,0] op_sel_hi:[1,1,1]
	s_sub_i32 s90, s90, 1
	s_cmp_eq_u32 s90, 0
	s_cbranch_scc1 .LV_sw1
.LV_t6_s1:
	s_waitcnt lgkmcnt(0)
	buffer_load_dwordx4 v[128:131], v[232:233], s[60:63], 0 idxen offen
	buffer_load_dwordx4 v[132:135], v[234:235], s[60:63], 0 idxen offen
	buffer_load_dwordx4 v[136:139], v[236:237], s[60:63], 0 idxen offen
	buffer_load_dwordx4 v[140:143], v[238:239], s[60:63], 0 idxen offen
	ds_read_b32 v232, v213 offset:80
	ds_read_b32 v234, v213 offset:84
	ds_read_b32 v236, v213 offset:88
	ds_read_b32 v238, v213 offset:92
	ds_read_b128 v[248:251], v213 offset:5024
	s_waitcnt vmcnt(12)
	v_cvt_pk_f32_fp8_e32 v[224:225], v144
	v_cvt_pk_f32_fp8_sdwa v[226:227], v144 src0_sel:WORD_1
	v_cvt_pk_f32_fp8_e32 v[228:229], v145
	v_cvt_pk_f32_fp8_sdwa v[230:231], v145 src0_sel:WORD_1
	v_pk_fma_f32 v[96:97], v[224:225], v[252:253], v[96:97] op_sel_hi:[1,0,1]
	v_pk_fma_f32 v[98:99], v[226:227], v[252:253], v[98:99] op_sel_hi:[1,0,1]
	v_pk_fma_f32 v[100:101], v[228:229], v[252:253], v[100:101] op_sel_hi:[1,0,1]
	v_pk_fma_f32 v[102:103], v[230:231], v[252:253], v[102:103] op_sel_hi:[1,0,1]
	v_cvt_pk_f32_fp8_e32 v[224:225], v146
	v_cvt_pk_f32_fp8_sdwa v[226:227], v146 src0_sel:WORD_1
	v_cvt_pk_f32_fp8_e32 v[228:229], v147
	v_cvt_pk_f32_fp8_sdwa v[230:231], v147 src0_sel:WORD_1
	v_pk_fma_f32 v[104:105], v[224:225], v[252:253], v[104:105] op_sel_hi:[1,0,1]
	v_pk_fma_f32 v[106:107], v[226:227], v[252:253], v[106:107] op_sel_hi:[1,0,1]
	v_pk_fma_f32 v[108:109], v[228:229], v[252:253], v[108:109] op_sel_hi:[1,0,1]
	v_pk_fma_f32 v[110:111], v[230:231], v[252:253], v[110:111] op_sel_hi:[1,0,1]
	v_cvt_pk_f32_fp8_e32 v[224:225], v148
	v_cvt_pk_f32_fp8_sdwa v[226:227], v148 src0_sel:WORD_1
	v_cvt_pk_f32_fp8_e32 v[228:229], v149
	v_cvt_pk_f32_fp8_sdwa v[230:231], v149 src0_sel:WORD_1
	v_pk_fma_f32 v[96:97], v[224:225], v[252:253], v[96:97] op_sel:[0,1,0] op_sel_hi:[1,1,1]
	v_pk_fma_f32 v[98:99], v[226:227], v[252:253], v[98:99] op_sel:[0,1,0] op_sel_hi:[1,1,1]
	v_pk_fma_f32 v[100:101], v[228:229], v[252:253], v[100:101] op_sel:[0,1,0] op_sel_hi:[1,1,1]
	v_pk_fma_f32 v[102:103], v[230:231], v[252:253], v[102:103] op_sel:[0,1,0] op_sel_hi:[1,1,1]
	v_cvt_pk_f32_fp8_e32 v[224:225], v150
	v_cvt_pk_f32_fp8_sdwa v[226:227], v150 src0_sel:WORD_1
	v_cvt_pk_f32_fp8_e32 v[228:229], v151
	v_cvt_pk_f32_fp8_sdwa v[230:231], v151 src0_sel:WORD_1
	v_pk_fma_f32 v[104:105], v[224:225], v[252:253], v[104:105] op_sel:[0,1,0] op_sel_hi:[1,1,1]
	v_pk_fma_f32 v[106:107], v[226:227], v[252:253], v[106:107] op_sel:[0,1,0] op_sel_hi:[1,1,1]
	v_pk_fma_f32 v[108:109], v[228:229], v[252:253], v[108:109] op_sel:[0,1,0] op_sel_hi:[1,1,1]
	v_pk_fma_f32 v[110:111], v[230:231], v[252:253], v[110:111] op_sel:[0,1,0] op_sel_hi:[1,1,1]
	v_cvt_pk_f32_fp8_e32 v[224:225], v152
	v_cvt_pk_f32_fp8_sdwa v[226:227], v152 src0_sel:WORD_1
	v_cvt_pk_f32_fp8_e32 v[228:229], v153
	v_cvt_pk_f32_fp8_sdwa v[230:231], v153 src0_sel:WORD_1
	v_pk_fma_f32 v[96:97], v[224:225], v[254:255], v[96:97] op_sel_hi:[1,0,1]
	v_pk_fma_f32 v[98:99], v[226:227], v[254:255], v[98:99] op_sel_hi:[1,0,1]
	v_pk_fma_f32 v[100:101], v[228:229], v[254:255], v[100:101] op_sel_hi:[1,0,1]
	v_pk_fma_f32 v[102:103], v[230:231], v[254:255], v[102:103] op_sel_hi:[1,0,1]
	v_cvt_pk_f32_fp8_e32 v[224:225], v154
	v_cvt_pk_f32_fp8_sdwa v[226:227], v154 src0_sel:WORD_1
	v_cvt_pk_f32_fp8_e32 v[228:229], v155
	v_cvt_pk_f32_fp8_sdwa v[230:231], v155 src0_sel:WORD_1
	v_pk_fma_f32 v[104:105], v[224:225], v[254:255], v[104:105] op_sel_hi:[1,0,1]
	v_pk_fma_f32 v[106:107], v[226:227], v[254:255], v[106:107] op_sel_hi:[1,0,1]
	v_pk_fma_f32 v[108:109], v[228:229], v[254:255], v[108:109] op_sel_hi:[1,0,1]
	v_pk_fma_f32 v[110:111], v[230:231], v[254:255], v[110:111] op_sel_hi:[1,0,1]
	v_cvt_pk_f32_fp8_e32 v[224:225], v156
	v_cvt_pk_f32_fp8_sdwa v[226:227], v156 src0_sel:WORD_1
	v_cvt_pk_f32_fp8_e32 v[228:229], v157
	v_cvt_pk_f32_fp8_sdwa v[230:231], v157 src0_sel:WORD_1
	v_pk_fma_f32 v[96:97], v[224:225], v[254:255], v[96:97] op_sel:[0,1,0] op_sel_hi:[1,1,1]
	v_pk_fma_f32 v[98:99], v[226:227], v[254:255], v[98:99] op_sel:[0,1,0] op_sel_hi:[1,1,1]
	v_pk_fma_f32 v[100:101], v[228:229], v[254:255], v[100:101] op_sel:[0,1,0] op_sel_hi:[1,1,1]
	v_pk_fma_f32 v[102:103], v[230:231], v[254:255], v[102:103] op_sel:[0,1,0] op_sel_hi:[1,1,1]
	v_cvt_pk_f32_fp8_e32 v[224:225], v158
	v_cvt_pk_f32_fp8_sdwa v[226:227], v158 src0_sel:WORD_1
	v_cvt_pk_f32_fp8_e32 v[228:229], v159
	v_cvt_pk_f32_fp8_sdwa v[230:231], v159 src0_sel:WORD_1
	v_pk_fma_f32 v[104:105], v[224:225], v[254:255], v[104:105] op_sel:[0,1,0] op_sel_hi:[1,1,1]
	v_pk_fma_f32 v[106:107], v[226:227], v[254:255], v[106:107] op_sel:[0,1,0] op_sel_hi:[1,1,1]
	v_pk_fma_f32 v[108:109], v[228:229], v[254:255], v[108:109] op_sel:[0,1,0] op_sel_hi:[1,1,1]
	v_pk_fma_f32 v[110:111], v[230:231], v[254:255], v[110:111] op_sel:[0,1,0] op_sel_hi:[1,1,1]
	s_sub_i32 s90, s90, 1
	s_cmp_eq_u32 s90, 0
	s_cbranch_scc1 .LV_sw2
.LV_t6_s2:
	s_waitcnt lgkmcnt(0)
	buffer_load_dwordx4 v[144:147], v[232:233], s[60:63], 0 idxen offen
	buffer_load_dwordx4 v[148:151], v[234:235], s[60:63], 0 idxen offen
	buffer_load_dwordx4 v[152:155], v[236:237], s[60:63], 0 idxen offen
	buffer_load_dwordx4 v[156:159], v[238:239], s[60:63], 0 idxen offen
	ds_read_b32 v232, v213 offset:96
	ds_read_b32 v234, v213 offset:100
	ds_read_b32 v236, v213 offset:104
	ds_read_b32 v238, v213 offset:108
	ds_read_b128 v[252:255], v213 offset:5040
	s_waitcnt vmcnt(12)
	v_cvt_pk_f32_fp8_e32 v[224:225], v160
	v_cvt_pk_f32_fp8_sdwa v[226:227], v160 src0_sel:WORD_1
	v_cvt_pk_f32_fp8_e32 v[228:229], v161
	v_cvt_pk_f32_fp8_sdwa v[230:231], v161 src0_sel:WORD_1
	v_pk_fma_f32 v[96:97], v[224:225], v[248:249], v[96:97] op_sel_hi:[1,0,1]
	v_pk_fma_f32 v[98:99], v[226:227], v[248:249], v[98:99] op_sel_hi:[1,0,1]
	v_pk_fma_f32 v[100:101], v[228:229], v[248:249], v[100:101] op_sel_hi:[1,0,1]
	v_pk_fma_f32 v[102:103], v[230:231], v[248:249], v[102:103] op_sel_hi:[1,0,1]
	v_cvt_pk_f32_fp8_e32 v[224:225], v162
	v_cvt_pk_f32_fp8_sdwa v[226:227], v162 src0_sel:WORD_1
	v_cvt_pk_f32_fp8_e32 v[228:229], v163
	v_cvt_pk_f32_fp8_sdwa v[230:231], v163 src0_sel:WORD_1
	v_pk_fma_f32 v[104:105], v[224:225], v[248:249], v[104:105] op_sel_hi:[1,0,1]
	v_pk_fma_f32 v[106:107], v[226:227], v[248:249], v[106:107] op_sel_hi:[1,0,1]
	v_pk_fma_f32 v[108:109], v[228:229], v[248:249], v[108:109] op_sel_hi:[1,0,1]
	v_pk_fma_f32 v[110:111], v[230:231], v[248:249], v[110:111] op_sel_hi:[1,0,1]
	v_cvt_pk_f32_fp8_e32 v[224:225], v164
	v_cvt_pk_f32_fp8_sdwa v[226:227], v164 src0_sel:WORD_1
	v_cvt_pk_f32_fp8_e32 v[228:229], v165
	v_cvt_pk_f32_fp8_sdwa v[230:231], v165 src0_sel:WORD_1
	v_pk_fma_f32 v[96:97], v[224:225], v[248:249], v[96:97] op_sel:[0,1,0] op_sel_hi:[1,1,1]
	v_pk_fma_f32 v[98:99], v[226:227], v[248:249], v[98:99] op_sel:[0,1,0] op_sel_hi:[1,1,1]
	v_pk_fma_f32 v[100:101], v[228:229], v[248:249], v[100:101] op_sel:[0,1,0] op_sel_hi:[1,1,1]
	v_pk_fma_f32 v[102:103], v[230:231], v[248:249], v[102:103] op_sel:[0,1,0] op_sel_hi:[1,1,1]
	v_cvt_pk_f32_fp8_e32 v[224:225], v166
	v_cvt_pk_f32_fp8_sdwa v[226:227], v166 src0_sel:WORD_1
	v_cvt_pk_f32_fp8_e32 v[228:229], v167
	v_cvt_pk_f32_fp8_sdwa v[230:231], v167 src0_sel:WORD_1
	v_pk_fma_f32 v[104:105], v[224:225], v[248:249], v[104:105] op_sel:[0,1,0] op_sel_hi:[1,1,1]
	v_pk_fma_f32 v[106:107], v[226:227], v[248:249], v[106:107] op_sel:[0,1,0] op_sel_hi:[1,1,1]
	v_pk_fma_f32 v[108:109], v[228:229], v[248:249], v[108:109] op_sel:[0,1,0] op_sel_hi:[1,1,1]
	v_pk_fma_f32 v[110:111], v[230:231], v[248:249], v[110:111] op_sel:[0,1,0] op_sel_hi:[1,1,1]
	v_cvt_pk_f32_fp8_e32 v[224:225], v168
	v_cvt_pk_f32_fp8_sdwa v[226:227], v168 src0_sel:WORD_1
	v_cvt_pk_f32_fp8_e32 v[228:229], v169
	v_cvt_pk_f32_fp8_sdwa v[230:231], v169 src0_sel:WORD_1
	v_pk_fma_f32 v[96:97], v[224:225], v[250:251], v[96:97] op_sel_hi:[1,0,1]
	v_pk_fma_f32 v[98:99], v[226:227], v[250:251], v[98:99] op_sel_hi:[1,0,1]
	v_pk_fma_f32 v[100:101], v[228:229], v[250:251], v[100:101] op_sel_hi:[1,0,1]
	v_pk_fma_f32 v[102:103], v[230:231], v[250:251], v[102:103] op_sel_hi:[1,0,1]
	v_cvt_pk_f32_fp8_e32 v[224:225], v170
	v_cvt_pk_f32_fp8_sdwa v[226:227], v170 src0_sel:WORD_1
	v_cvt_pk_f32_fp8_e32 v[228:229], v171
	v_cvt_pk_f32_fp8_sdwa v[230:231], v171 src0_sel:WORD_1
	v_pk_fma_f32 v[104:105], v[224:225], v[250:251], v[104:105] op_sel_hi:[1,0,1]
	v_pk_fma_f32 v[106:107], v[226:227], v[250:251], v[106:107] op_sel_hi:[1,0,1]
	v_pk_fma_f32 v[108:109], v[228:229], v[250:251], v[108:109] op_sel_hi:[1,0,1]
	v_pk_fma_f32 v[110:111], v[230:231], v[250:251], v[110:111] op_sel_hi:[1,0,1]
	v_cvt_pk_f32_fp8_e32 v[224:225], v172
	v_cvt_pk_f32_fp8_sdwa v[226:227], v172 src0_sel:WORD_1
	v_cvt_pk_f32_fp8_e32 v[228:229], v173
	v_cvt_pk_f32_fp8_sdwa v[230:231], v173 src0_sel:WORD_1
	v_pk_fma_f32 v[96:97], v[224:225], v[250:251], v[96:97] op_sel:[0,1,0] op_sel_hi:[1,1,1]
	v_pk_fma_f32 v[98:99], v[226:227], v[250:251], v[98:99] op_sel:[0,1,0] op_sel_hi:[1,1,1]
	v_pk_fma_f32 v[100:101], v[228:229], v[250:251], v[100:101] op_sel:[0,1,0] op_sel_hi:[1,1,1]
	v_pk_fma_f32 v[102:103], v[230:231], v[250:251], v[102:103] op_sel:[0,1,0] op_sel_hi:[1,1,1]
	v_cvt_pk_f32_fp8_e32 v[224:225], v174
	v_cvt_pk_f32_fp8_sdwa v[226:227], v174 src0_sel:WORD_1
	v_cvt_pk_f32_fp8_e32 v[228:229], v175
	v_cvt_pk_f32_fp8_sdwa v[230:231], v175 src0_sel:WORD_1
	v_pk_fma_f32 v[104:105], v[224:225], v[250:251], v[104:105] op_sel:[0,1,0] op_sel_hi:[1,1,1]
	v_pk_fma_f32 v[106:107], v[226:227], v[250:251], v[106:107] op_sel:[0,1,0] op_sel_hi:[1,1,1]
	v_pk_fma_f32 v[108:109], v[228:229], v[250:251], v[108:109] op_sel:[0,1,0] op_sel_hi:[1,1,1]
	v_pk_fma_f32 v[110:111], v[230:231], v[250:251], v[110:111] op_sel:[0,1,0] op_sel_hi:[1,1,1]
	s_sub_i32 s90, s90, 1
	s_cmp_eq_u32 s90, 0
	s_cbranch_scc1 .LV_sw3
.LV_t6_s3:
	s_waitcnt lgkmcnt(0)
	buffer_load_dwordx4 v[160:163], v[232:233], s[60:63], 0 idxen offen
	buffer_load_dwordx4 v[164:167], v[234:235], s[60:63], 0 idxen offen
	buffer_load_dwordx4 v[168:171], v[236:237], s[60:63], 0 idxen offen
	buffer_load_dwordx4 v[172:175], v[238:239], s[60:63], 0 idxen offen
	ds_read_b32 v232, v213 offset:112
	ds_read_b32 v234, v213 offset:116
	ds_read_b32 v236, v213 offset:120
	ds_read_b32 v238, v213 offset:124
	ds_read_b128 v[248:251], v213 offset:5056
	s_waitcnt vmcnt(12)
	v_cvt_pk_f32_fp8_e32 v[224:225], v176
	v_cvt_pk_f32_fp8_sdwa v[226:227], v176 src0_sel:WORD_1
	v_cvt_pk_f32_fp8_e32 v[228:229], v177
	v_cvt_pk_f32_fp8_sdwa v[230:231], v177 src0_sel:WORD_1
	v_pk_fma_f32 v[96:97], v[224:225], v[252:253], v[96:97] op_sel_hi:[1,0,1]
	v_pk_fma_f32 v[98:99], v[226:227], v[252:253], v[98:99] op_sel_hi:[1,0,1]
	v_pk_fma_f32 v[100:101], v[228:229], v[252:253], v[100:101] op_sel_hi:[1,0,1]
	v_pk_fma_f32 v[102:103], v[230:231], v[252:253], v[102:103] op_sel_hi:[1,0,1]
	v_cvt_pk_f32_fp8_e32 v[224:225], v178
	v_cvt_pk_f32_fp8_sdwa v[226:227], v178 src0_sel:WORD_1
	v_cvt_pk_f32_fp8_e32 v[228:229], v179
	v_cvt_pk_f32_fp8_sdwa v[230:231], v179 src0_sel:WORD_1
	v_pk_fma_f32 v[104:105], v[224:225], v[252:253], v[104:105] op_sel_hi:[1,0,1]
	v_pk_fma_f32 v[106:107], v[226:227], v[252:253], v[106:107] op_sel_hi:[1,0,1]
	v_pk_fma_f32 v[108:109], v[228:229], v[252:253], v[108:109] op_sel_hi:[1,0,1]
	v_pk_fma_f32 v[110:111], v[230:231], v[252:253], v[110:111] op_sel_hi:[1,0,1]
	v_cvt_pk_f32_fp8_e32 v[224:225], v180
	v_cvt_pk_f32_fp8_sdwa v[226:227], v180 src0_sel:WORD_1
	v_cvt_pk_f32_fp8_e32 v[228:229], v181
	v_cvt_pk_f32_fp8_sdwa v[230:231], v181 src0_sel:WORD_1
	v_pk_fma_f32 v[96:97], v[224:225], v[252:253], v[96:97] op_sel:[0,1,0] op_sel_hi:[1,1,1]
	v_pk_fma_f32 v[98:99], v[226:227], v[252:253], v[98:99] op_sel:[0,1,0] op_sel_hi:[1,1,1]
	v_pk_fma_f32 v[100:101], v[228:229], v[252:253], v[100:101] op_sel:[0,1,0] op_sel_hi:[1,1,1]
	v_pk_fma_f32 v[102:103], v[230:231], v[252:253], v[102:103] op_sel:[0,1,0] op_sel_hi:[1,1,1]
	v_cvt_pk_f32_fp8_e32 v[224:225], v182
	v_cvt_pk_f32_fp8_sdwa v[226:227], v182 src0_sel:WORD_1
	v_cvt_pk_f32_fp8_e32 v[228:229], v183
	v_cvt_pk_f32_fp8_sdwa v[230:231], v183 src0_sel:WORD_1
	v_pk_fma_f32 v[104:105], v[224:225], v[252:253], v[104:105] op_sel:[0,1,0] op_sel_hi:[1,1,1]
	v_pk_fma_f32 v[106:107], v[226:227], v[252:253], v[106:107] op_sel:[0,1,0] op_sel_hi:[1,1,1]
	v_pk_fma_f32 v[108:109], v[228:229], v[252:253], v[108:109] op_sel:[0,1,0] op_sel_hi:[1,1,1]
	v_pk_fma_f32 v[110:111], v[230:231], v[252:253], v[110:111] op_sel:[0,1,0] op_sel_hi:[1,1,1]
	v_cvt_pk_f32_fp8_e32 v[224:225], v184
	v_cvt_pk_f32_fp8_sdwa v[226:227], v184 src0_sel:WORD_1
	v_cvt_pk_f32_fp8_e32 v[228:229], v185
	v_cvt_pk_f32_fp8_sdwa v[230:231], v185 src0_sel:WORD_1
	v_pk_fma_f32 v[96:97], v[224:225], v[254:255], v[96:97] op_sel_hi:[1,0,1]
	v_pk_fma_f32 v[98:99], v[226:227], v[254:255], v[98:99] op_sel_hi:[1,0,1]
	v_pk_fma_f32 v[100:101], v[228:229], v[254:255], v[100:101] op_sel_hi:[1,0,1]
	v_pk_fma_f32 v[102:103], v[230:231], v[254:255], v[102:103] op_sel_hi:[1,0,1]
	v_cvt_pk_f32_fp8_e32 v[224:225], v186
	v_cvt_pk_f32_fp8_sdwa v[226:227], v186 src0_sel:WORD_1
	v_cvt_pk_f32_fp8_e32 v[228:229], v187
	v_cvt_pk_f32_fp8_sdwa v[230:231], v187 src0_sel:WORD_1
	v_pk_fma_f32 v[104:105], v[224:225], v[254:255], v[104:105] op_sel_hi:[1,0,1]
	v_pk_fma_f32 v[106:107], v[226:227], v[254:255], v[106:107] op_sel_hi:[1,0,1]
	v_pk_fma_f32 v[108:109], v[228:229], v[254:255], v[108:109] op_sel_hi:[1,0,1]
	v_pk_fma_f32 v[110:111], v[230:231], v[254:255], v[110:111] op_sel_hi:[1,0,1]
	v_cvt_pk_f32_fp8_e32 v[224:225], v188
	v_cvt_pk_f32_fp8_sdwa v[226:227], v188 src0_sel:WORD_1
	v_cvt_pk_f32_fp8_e32 v[228:229], v189
	v_cvt_pk_f32_fp8_sdwa v[230:231], v189 src0_sel:WORD_1
	v_pk_fma_f32 v[96:97], v[224:225], v[254:255], v[96:97] op_sel:[0,1,0] op_sel_hi:[1,1,1]
	v_pk_fma_f32 v[98:99], v[226:227], v[254:255], v[98:99] op_sel:[0,1,0] op_sel_hi:[1,1,1]
	v_pk_fma_f32 v[100:101], v[228:229], v[254:255], v[100:101] op_sel:[0,1,0] op_sel_hi:[1,1,1]
	v_pk_fma_f32 v[102:103], v[230:231], v[254:255], v[102:103] op_sel:[0,1,0] op_sel_hi:[1,1,1]
	v_cvt_pk_f32_fp8_e32 v[224:225], v190
	v_cvt_pk_f32_fp8_sdwa v[226:227], v190 src0_sel:WORD_1
	v_cvt_pk_f32_fp8_e32 v[228:229], v191
	v_cvt_pk_f32_fp8_sdwa v[230:231], v191 src0_sel:WORD_1
	v_pk_fma_f32 v[104:105], v[224:225], v[254:255], v[104:105] op_sel:[0,1,0] op_sel_hi:[1,1,1]
	v_pk_fma_f32 v[106:107], v[226:227], v[254:255], v[106:107] op_sel:[0,1,0] op_sel_hi:[1,1,1]
	v_pk_fma_f32 v[108:109], v[228:229], v[254:255], v[108:109] op_sel:[0,1,0] op_sel_hi:[1,1,1]
	v_pk_fma_f32 v[110:111], v[230:231], v[254:255], v[110:111] op_sel:[0,1,0] op_sel_hi:[1,1,1]
	v_add_u32_e32 v213, 64, v213
	s_add_i32 s21, s21, 4
	s_sub_i32 s90, s90, 1
	s_cmp_eq_u32 s90, 0
	s_cbranch_scc1 .LV_sw0
	s_branch .LV_t6_s0
.LV_t7_s0:
	s_cmp_ge_u32 s21, s20
	s_cbranch_scc1 .LV_done
	s_waitcnt lgkmcnt(0)
	buffer_load_dwordx4 v[176:179], v[232:233], s[60:63], 0 idxen offen
	buffer_load_dwordx4 v[180:183], v[234:235], s[60:63], 0 idxen offen
	buffer_load_dwordx4 v[184:187], v[236:237], s[60:63], 0 idxen offen
	buffer_load_dwordx4 v[188:191], v[238:239], s[60:63], 0 idxen offen
	ds_read_b32 v232, v213 offset:64
	ds_read_b32 v234, v213 offset:68
	ds_read_b32 v236, v213 offset:72
	ds_read_b32 v238, v213 offset:76
	ds_read_b128 v[252:255], v213 offset:5008
	s_waitcnt vmcnt(12)
	v_cvt_pk_f32_fp8_e32 v[224:225], v128
	v_cvt_pk_f32_fp8_sdwa v[226:227], v128 src0_sel:WORD_1
	v_cvt_pk_f32_fp8_e32 v[228:229], v129
	v_cvt_pk_f32_fp8_sdwa v[230:231], v129 src0_sel:WORD_1
	v_pk_fma_f32 v[112:113], v[224:225], v[248:249], v[112:113] op_sel_hi:[1,0,1]
	v_pk_fma_f32 v[114:115], v[226:227], v[248:249], v[114:115] op_sel_hi:[1,0,1]
	v_pk_fma_f32 v[116:117], v[228:229], v[248:249], v[116:117] op_sel_hi:[1,0,1]
	v_pk_fma_f32 v[118:119], v[230:231], v[248:249], v[118:119] op_sel_hi:[1,0,1]
	v_cvt_pk_f32_fp8_e32 v[224:225], v130
	v_cvt_pk_f32_fp8_sdwa v[226:227], v130 src0_sel:WORD_1
	v_cvt_pk_f32_fp8_e32 v[228:229], v131
	v_cvt_pk_f32_fp8_sdwa v[230:231], v131 src0_sel:WORD_1
	v_pk_fma_f32 v[120:121], v[224:225], v[248:249], v[120:121] op_sel_hi:[1,0,1]
	v_pk_fma_f32 v[122:123], v[226:227], v[248:249], v[122:123] op_sel_hi:[1,0,1]
	v_pk_fma_f32 v[124:125], v[228:229], v[248:249], v[124:125] op_sel_hi:[1,0,1]
	v_pk_fma_f32 v[126:127], v[230:231], v[248:249], v[126:127] op_sel_hi:[1,0,1]
	v_cvt_pk_f32_fp8_e32 v[224:225], v132
	v_cvt_pk_f32_fp8_sdwa v[226:227], v132 src0_sel:WORD_1
	v_cvt_pk_f32_fp8_e32 v[228:229], v133
	v_cvt_pk_f32_fp8_sdwa v[230:231], v133 src0_sel:WORD_1
	v_pk_fma_f32 v[112:113], v[224:225], v[248:249], v[112:113] op_sel:[0,1,0] op_sel_hi:[1,1,1]
	v_pk_fma_f32 v[114:115], v[226:227], v[248:249], v[114:115] op_sel:[0,1,0] op_sel_hi:[1,1,1]
	v_pk_fma_f32 v[116:117], v[228:229], v[248:249], v[116:117] op_sel:[0,1,0] op_sel_hi:[1,1,1]
	v_pk_fma_f32 v[118:119], v[230:231], v[248:249], v[118:119] op_sel:[0,1,0] op_sel_hi:[1,1,1]
	v_cvt_pk_f32_fp8_e32 v[224:225], v134
	v_cvt_pk_f32_fp8_sdwa v[226:227], v134 src0_sel:WORD_1
	v_cvt_pk_f32_fp8_e32 v[228:229], v135
	v_cvt_pk_f32_fp8_sdwa v[230:231], v135 src0_sel:WORD_1
	v_pk_fma_f32 v[120:121], v[224:225], v[248:249], v[120:121] op_sel:[0,1,0] op_sel_hi:[1,1,1]
	v_pk_fma_f32 v[122:123], v[226:227], v[248:249], v[122:123] op_sel:[0,1,0] op_sel_hi:[1,1,1]
	v_pk_fma_f32 v[124:125], v[228:229], v[248:249], v[124:125] op_sel:[0,1,0] op_sel_hi:[1,1,1]
	v_pk_fma_f32 v[126:127], v[230:231], v[248:249], v[126:127] op_sel:[0,1,0] op_sel_hi:[1,1,1]
	v_cvt_pk_f32_fp8_e32 v[224:225], v136
	v_cvt_pk_f32_fp8_sdwa v[226:227], v136 src0_sel:WORD_1
	v_cvt_pk_f32_fp8_e32 v[228:229], v137
	v_cvt_pk_f32_fp8_sdwa v[230:231], v137 src0_sel:WORD_1
	v_pk_fma_f32 v[112:113], v[224:225], v[250:251], v[112:113] op_sel_hi:[1,0,1]
	v_pk_fma_f32 v[114:115], v[226:227], v[250:251], v[114:115] op_sel_hi:[1,0,1]
	v_pk_fma_f32 v[116:117], v[228:229], v[250:251], v[116:117] op_sel_hi:[1,0,1]
	v_pk_fma_f32 v[118:119], v[230:231], v[250:251], v[118:119] op_sel_hi:[1,0,1]
	v_cvt_pk_f32_fp8_e32 v[224:225], v138
	v_cvt_pk_f32_fp8_sdwa v[226:227], v138 src0_sel:WORD_1
	v_cvt_pk_f32_fp8_e32 v[228:229], v139
	v_cvt_pk_f32_fp8_sdwa v[230:231], v139 src0_sel:WORD_1
	v_pk_fma_f32 v[120:121], v[224:225], v[250:251], v[120:121] op_sel_hi:[1,0,1]
	v_pk_fma_f32 v[122:123], v[226:227], v[250:251], v[122:123] op_sel_hi:[1,0,1]
	v_pk_fma_f32 v[124:125], v[228:229], v[250:251], v[124:125] op_sel_hi:[1,0,1]
	v_pk_fma_f32 v[126:127], v[230:231], v[250:251], v[126:127] op_sel_hi:[1,0,1]
	v_cvt_pk_f32_fp8_e32 v[224:225], v140
	v_cvt_pk_f32_fp8_sdwa v[226:227], v140 src0_sel:WORD_1
	v_cvt_pk_f32_fp8_e32 v[228:229], v141
	v_cvt_pk_f32_fp8_sdwa v[230:231], v141 src0_sel:WORD_1
	v_pk_fma_f32 v[112:113], v[224:225], v[250:251], v[112:113] op_sel:[0,1,0] op_sel_hi:[1,1,1]
	v_pk_fma_f32 v[114:115], v[226:227], v[250:251], v[114:115] op_sel:[0,1,0] op_sel_hi:[1,1,1]
	v_pk_fma_f32 v[116:117], v[228:229], v[250:251], v[116:117] op_sel:[0,1,0] op_sel_hi:[1,1,1]
	v_pk_fma_f32 v[118:119], v[230:231], v[250:251], v[118:119] op_sel:[0,1,0] op_sel_hi:[1,1,1]
	v_cvt_pk_f32_fp8_e32 v[224:225], v142
	v_cvt_pk_f32_fp8_sdwa v[226:227], v142 src0_sel:WORD_1
	v_cvt_pk_f32_fp8_e32 v[228:229], v143
	v_cvt_pk_f32_fp8_sdwa v[230:231], v143 src0_sel:WORD_1
	v_pk_fma_f32 v[120:121], v[224:225], v[250:251], v[120:121] op_sel:[0,1,0] op_sel_hi:[1,1,1]
	v_pk_fma_f32 v[122:123], v[226:227], v[250:251], v[122:123] op_sel:[0,1,0] op_sel_hi:[1,1,1]
	v_pk_fma_f32 v[124:125], v[228:229], v[250:251], v[124:125] op_sel:[0,1,0] op_sel_hi:[1,1,1]
	v_pk_fma_f32 v[126:127], v[230:231], v[250:251], v[126:127] op_sel:[0,1,0] op_sel_hi:[1,1,1]
	s_sub_i32 s90, s90, 1
	s_cmp_eq_u32 s90, 0
	s_cbranch_scc1 .LV_sw1
.LV_t7_s1:
	s_waitcnt lgkmcnt(0)
	buffer_load_dwordx4 v[128:131], v[232:233], s[60:63], 0 idxen offen
	buffer_load_dwordx4 v[132:135], v[234:235], s[60:63], 0 idxen offen
	buffer_load_dwordx4 v[136:139], v[236:237], s[60:63], 0 idxen offen
	buffer_load_dwordx4 v[140:143], v[238:239], s[60:63], 0 idxen offen
	ds_read_b32 v232, v213 offset:80
	ds_read_b32 v234, v213 offset:84
	ds_read_b32 v236, v213 offset:88
	ds_read_b32 v238, v213 offset:92
	ds_read_b128 v[248:251], v213 offset:5024
	s_waitcnt vmcnt(12)
	v_cvt_pk_f32_fp8_e32 v[224:225], v144
	v_cvt_pk_f32_fp8_sdwa v[226:227], v144 src0_sel:WORD_1
	v_cvt_pk_f32_fp8_e32 v[228:229], v145
	v_cvt_pk_f32_fp8_sdwa v[230:231], v145 src0_sel:WORD_1
	v_pk_fma_f32 v[112:113], v[224:225], v[252:253], v[112:113] op_sel_hi:[1,0,1]
	v_pk_fma_f32 v[114:115], v[226:227], v[252:253], v[114:115] op_sel_hi:[1,0,1]
	v_pk_fma_f32 v[116:117], v[228:229], v[252:253], v[116:117] op_sel_hi:[1,0,1]
	v_pk_fma_f32 v[118:119], v[230:231], v[252:253], v[118:119] op_sel_hi:[1,0,1]
	v_cvt_pk_f32_fp8_e32 v[224:225], v146
	v_cvt_pk_f32_fp8_sdwa v[226:227], v146 src0_sel:WORD_1
	v_cvt_pk_f32_fp8_e32 v[228:229], v147
	v_cvt_pk_f32_fp8_sdwa v[230:231], v147 src0_sel:WORD_1
	v_pk_fma_f32 v[120:121], v[224:225], v[252:253], v[120:121] op_sel_hi:[1,0,1]
	v_pk_fma_f32 v[122:123], v[226:227], v[252:253], v[122:123] op_sel_hi:[1,0,1]
	v_pk_fma_f32 v[124:125], v[228:229], v[252:253], v[124:125] op_sel_hi:[1,0,1]
	v_pk_fma_f32 v[126:127], v[230:231], v[252:253], v[126:127] op_sel_hi:[1,0,1]
	v_cvt_pk_f32_fp8_e32 v[224:225], v148
	v_cvt_pk_f32_fp8_sdwa v[226:227], v148 src0_sel:WORD_1
	v_cvt_pk_f32_fp8_e32 v[228:229], v149
	v_cvt_pk_f32_fp8_sdwa v[230:231], v149 src0_sel:WORD_1
	v_pk_fma_f32 v[112:113], v[224:225], v[252:253], v[112:113] op_sel:[0,1,0] op_sel_hi:[1,1,1]
	v_pk_fma_f32 v[114:115], v[226:227], v[252:253], v[114:115] op_sel:[0,1,0] op_sel_hi:[1,1,1]
	v_pk_fma_f32 v[116:117], v[228:229], v[252:253], v[116:117] op_sel:[0,1,0] op_sel_hi:[1,1,1]
	v_pk_fma_f32 v[118:119], v[230:231], v[252:253], v[118:119] op_sel:[0,1,0] op_sel_hi:[1,1,1]
	v_cvt_pk_f32_fp8_e32 v[224:225], v150
	v_cvt_pk_f32_fp8_sdwa v[226:227], v150 src0_sel:WORD_1
	v_cvt_pk_f32_fp8_e32 v[228:229], v151
	v_cvt_pk_f32_fp8_sdwa v[230:231], v151 src0_sel:WORD_1
	v_pk_fma_f32 v[120:121], v[224:225], v[252:253], v[120:121] op_sel:[0,1,0] op_sel_hi:[1,1,1]
	v_pk_fma_f32 v[122:123], v[226:227], v[252:253], v[122:123] op_sel:[0,1,0] op_sel_hi:[1,1,1]
	v_pk_fma_f32 v[124:125], v[228:229], v[252:253], v[124:125] op_sel:[0,1,0] op_sel_hi:[1,1,1]
	v_pk_fma_f32 v[126:127], v[230:231], v[252:253], v[126:127] op_sel:[0,1,0] op_sel_hi:[1,1,1]
	v_cvt_pk_f32_fp8_e32 v[224:225], v152
	v_cvt_pk_f32_fp8_sdwa v[226:227], v152 src0_sel:WORD_1
	v_cvt_pk_f32_fp8_e32 v[228:229], v153
	v_cvt_pk_f32_fp8_sdwa v[230:231], v153 src0_sel:WORD_1
	v_pk_fma_f32 v[112:113], v[224:225], v[254:255], v[112:113] op_sel_hi:[1,0,1]
	v_pk_fma_f32 v[114:115], v[226:227], v[254:255], v[114:115] op_sel_hi:[1,0,1]
	v_pk_fma_f32 v[116:117], v[228:229], v[254:255], v[116:117] op_sel_hi:[1,0,1]
	v_pk_fma_f32 v[118:119], v[230:231], v[254:255], v[118:119] op_sel_hi:[1,0,1]
	v_cvt_pk_f32_fp8_e32 v[224:225], v154
	v_cvt_pk_f32_fp8_sdwa v[226:227], v154 src0_sel:WORD_1
	v_cvt_pk_f32_fp8_e32 v[228:229], v155
	v_cvt_pk_f32_fp8_sdwa v[230:231], v155 src0_sel:WORD_1
	v_pk_fma_f32 v[120:121], v[224:225], v[254:255], v[120:121] op_sel_hi:[1,0,1]
	v_pk_fma_f32 v[122:123], v[226:227], v[254:255], v[122:123] op_sel_hi:[1,0,1]
	v_pk_fma_f32 v[124:125], v[228:229], v[254:255], v[124:125] op_sel_hi:[1,0,1]
	v_pk_fma_f32 v[126:127], v[230:231], v[254:255], v[126:127] op_sel_hi:[1,0,1]
	v_cvt_pk_f32_fp8_e32 v[224:225], v156
	v_cvt_pk_f32_fp8_sdwa v[226:227], v156 src0_sel:WORD_1
	v_cvt_pk_f32_fp8_e32 v[228:229], v157
	v_cvt_pk_f32_fp8_sdwa v[230:231], v157 src0_sel:WORD_1
	v_pk_fma_f32 v[112:113], v[224:225], v[254:255], v[112:113] op_sel:[0,1,0] op_sel_hi:[1,1,1]
	v_pk_fma_f32 v[114:115], v[226:227], v[254:255], v[114:115] op_sel:[0,1,0] op_sel_hi:[1,1,1]
	v_pk_fma_f32 v[116:117], v[228:229], v[254:255], v[116:117] op_sel:[0,1,0] op_sel_hi:[1,1,1]
	v_pk_fma_f32 v[118:119], v[230:231], v[254:255], v[118:119] op_sel:[0,1,0] op_sel_hi:[1,1,1]
	v_cvt_pk_f32_fp8_e32 v[224:225], v158
	v_cvt_pk_f32_fp8_sdwa v[226:227], v158 src0_sel:WORD_1
	v_cvt_pk_f32_fp8_e32 v[228:229], v159
	v_cvt_pk_f32_fp8_sdwa v[230:231], v159 src0_sel:WORD_1
	v_pk_fma_f32 v[120:121], v[224:225], v[254:255], v[120:121] op_sel:[0,1,0] op_sel_hi:[1,1,1]
	v_pk_fma_f32 v[122:123], v[226:227], v[254:255], v[122:123] op_sel:[0,1,0] op_sel_hi:[1,1,1]
	v_pk_fma_f32 v[124:125], v[228:229], v[254:255], v[124:125] op_sel:[0,1,0] op_sel_hi:[1,1,1]
	v_pk_fma_f32 v[126:127], v[230:231], v[254:255], v[126:127] op_sel:[0,1,0] op_sel_hi:[1,1,1]
	s_sub_i32 s90, s90, 1
	s_cmp_eq_u32 s90, 0
	s_cbranch_scc1 .LV_sw2
.LV_t7_s2:
	s_waitcnt lgkmcnt(0)
	buffer_load_dwordx4 v[144:147], v[232:233], s[60:63], 0 idxen offen
	buffer_load_dwordx4 v[148:151], v[234:235], s[60:63], 0 idxen offen
	buffer_load_dwordx4 v[152:155], v[236:237], s[60:63], 0 idxen offen
	buffer_load_dwordx4 v[156:159], v[238:239], s[60:63], 0 idxen offen
	ds_read_b32 v232, v213 offset:96
	ds_read_b32 v234, v213 offset:100
	ds_read_b32 v236, v213 offset:104
	ds_read_b32 v238, v213 offset:108
	ds_read_b128 v[252:255], v213 offset:5040
	s_waitcnt vmcnt(12)
	v_cvt_pk_f32_fp8_e32 v[224:225], v160
	v_cvt_pk_f32_fp8_sdwa v[226:227], v160 src0_sel:WORD_1
	v_cvt_pk_f32_fp8_e32 v[228:229], v161
	v_cvt_pk_f32_fp8_sdwa v[230:231], v161 src0_sel:WORD_1
	v_pk_fma_f32 v[112:113], v[224:225], v[248:249], v[112:113] op_sel_hi:[1,0,1]
	v_pk_fma_f32 v[114:115], v[226:227], v[248:249], v[114:115] op_sel_hi:[1,0,1]
	v_pk_fma_f32 v[116:117], v[228:229], v[248:249], v[116:117] op_sel_hi:[1,0,1]
	v_pk_fma_f32 v[118:119], v[230:231], v[248:249], v[118:119] op_sel_hi:[1,0,1]
	v_cvt_pk_f32_fp8_e32 v[224:225], v162
	v_cvt_pk_f32_fp8_sdwa v[226:227], v162 src0_sel:WORD_1
	v_cvt_pk_f32_fp8_e32 v[228:229], v163
	v_cvt_pk_f32_fp8_sdwa v[230:231], v163 src0_sel:WORD_1
	v_pk_fma_f32 v[120:121], v[224:225], v[248:249], v[120:121] op_sel_hi:[1,0,1]
	v_pk_fma_f32 v[122:123], v[226:227], v[248:249], v[122:123] op_sel_hi:[1,0,1]
	v_pk_fma_f32 v[124:125], v[228:229], v[248:249], v[124:125] op_sel_hi:[1,0,1]
	v_pk_fma_f32 v[126:127], v[230:231], v[248:249], v[126:127] op_sel_hi:[1,0,1]
	v_cvt_pk_f32_fp8_e32 v[224:225], v164
	v_cvt_pk_f32_fp8_sdwa v[226:227], v164 src0_sel:WORD_1
	v_cvt_pk_f32_fp8_e32 v[228:229], v165
	v_cvt_pk_f32_fp8_sdwa v[230:231], v165 src0_sel:WORD_1
	v_pk_fma_f32 v[112:113], v[224:225], v[248:249], v[112:113] op_sel:[0,1,0] op_sel_hi:[1,1,1]
	v_pk_fma_f32 v[114:115], v[226:227], v[248:249], v[114:115] op_sel:[0,1,0] op_sel_hi:[1,1,1]
	v_pk_fma_f32 v[116:117], v[228:229], v[248:249], v[116:117] op_sel:[0,1,0] op_sel_hi:[1,1,1]
	v_pk_fma_f32 v[118:119], v[230:231], v[248:249], v[118:119] op_sel:[0,1,0] op_sel_hi:[1,1,1]
	v_cvt_pk_f32_fp8_e32 v[224:225], v166
	v_cvt_pk_f32_fp8_sdwa v[226:227], v166 src0_sel:WORD_1
	v_cvt_pk_f32_fp8_e32 v[228:229], v167
	v_cvt_pk_f32_fp8_sdwa v[230:231], v167 src0_sel:WORD_1
	v_pk_fma_f32 v[120:121], v[224:225], v[248:249], v[120:121] op_sel:[0,1,0] op_sel_hi:[1,1,1]
	v_pk_fma_f32 v[122:123], v[226:227], v[248:249], v[122:123] op_sel:[0,1,0] op_sel_hi:[1,1,1]
	v_pk_fma_f32 v[124:125], v[228:229], v[248:249], v[124:125] op_sel:[0,1,0] op_sel_hi:[1,1,1]
	v_pk_fma_f32 v[126:127], v[230:231], v[248:249], v[126:127] op_sel:[0,1,0] op_sel_hi:[1,1,1]
	v_cvt_pk_f32_fp8_e32 v[224:225], v168
	v_cvt_pk_f32_fp8_sdwa v[226:227], v168 src0_sel:WORD_1
	v_cvt_pk_f32_fp8_e32 v[228:229], v169
	v_cvt_pk_f32_fp8_sdwa v[230:231], v169 src0_sel:WORD_1
	v_pk_fma_f32 v[112:113], v[224:225], v[250:251], v[112:113] op_sel_hi:[1,0,1]
	v_pk_fma_f32 v[114:115], v[226:227], v[250:251], v[114:115] op_sel_hi:[1,0,1]
	v_pk_fma_f32 v[116:117], v[228:229], v[250:251], v[116:117] op_sel_hi:[1,0,1]
	v_pk_fma_f32 v[118:119], v[230:231], v[250:251], v[118:119] op_sel_hi:[1,0,1]
	v_cvt_pk_f32_fp8_e32 v[224:225], v170
	v_cvt_pk_f32_fp8_sdwa v[226:227], v170 src0_sel:WORD_1
	v_cvt_pk_f32_fp8_e32 v[228:229], v171
	v_cvt_pk_f32_fp8_sdwa v[230:231], v171 src0_sel:WORD_1
	v_pk_fma_f32 v[120:121], v[224:225], v[250:251], v[120:121] op_sel_hi:[1,0,1]
	v_pk_fma_f32 v[122:123], v[226:227], v[250:251], v[122:123] op_sel_hi:[1,0,1]
	v_pk_fma_f32 v[124:125], v[228:229], v[250:251], v[124:125] op_sel_hi:[1,0,1]
	v_pk_fma_f32 v[126:127], v[230:231], v[250:251], v[126:127] op_sel_hi:[1,0,1]
	v_cvt_pk_f32_fp8_e32 v[224:225], v172
	v_cvt_pk_f32_fp8_sdwa v[226:227], v172 src0_sel:WORD_1
	v_cvt_pk_f32_fp8_e32 v[228:229], v173
	v_cvt_pk_f32_fp8_sdwa v[230:231], v173 src0_sel:WORD_1
	v_pk_fma_f32 v[112:113], v[224:225], v[250:251], v[112:113] op_sel:[0,1,0] op_sel_hi:[1,1,1]
	v_pk_fma_f32 v[114:115], v[226:227], v[250:251], v[114:115] op_sel:[0,1,0] op_sel_hi:[1,1,1]
	v_pk_fma_f32 v[116:117], v[228:229], v[250:251], v[116:117] op_sel:[0,1,0] op_sel_hi:[1,1,1]
	v_pk_fma_f32 v[118:119], v[230:231], v[250:251], v[118:119] op_sel:[0,1,0] op_sel_hi:[1,1,1]
	v_cvt_pk_f32_fp8_e32 v[224:225], v174
	v_cvt_pk_f32_fp8_sdwa v[226:227], v174 src0_sel:WORD_1
	v_cvt_pk_f32_fp8_e32 v[228:229], v175
	v_cvt_pk_f32_fp8_sdwa v[230:231], v175 src0_sel:WORD_1
	v_pk_fma_f32 v[120:121], v[224:225], v[250:251], v[120:121] op_sel:[0,1,0] op_sel_hi:[1,1,1]
	v_pk_fma_f32 v[122:123], v[226:227], v[250:251], v[122:123] op_sel:[0,1,0] op_sel_hi:[1,1,1]
	v_pk_fma_f32 v[124:125], v[228:229], v[250:251], v[124:125] op_sel:[0,1,0] op_sel_hi:[1,1,1]
	v_pk_fma_f32 v[126:127], v[230:231], v[250:251], v[126:127] op_sel:[0,1,0] op_sel_hi:[1,1,1]
	s_sub_i32 s90, s90, 1
	s_cmp_eq_u32 s90, 0
	s_cbranch_scc1 .LV_sw3
.LV_t7_s3:
	s_waitcnt lgkmcnt(0)
	buffer_load_dwordx4 v[160:163], v[232:233], s[60:63], 0 idxen offen
	buffer_load_dwordx4 v[164:167], v[234:235], s[60:63], 0 idxen offen
	buffer_load_dwordx4 v[168:171], v[236:237], s[60:63], 0 idxen offen
	buffer_load_dwordx4 v[172:175], v[238:239], s[60:63], 0 idxen offen
	ds_read_b32 v232, v213 offset:112
	ds_read_b32 v234, v213 offset:116
	ds_read_b32 v236, v213 offset:120
	ds_read_b32 v238, v213 offset:124
	ds_read_b128 v[248:251], v213 offset:5056
	s_waitcnt vmcnt(12)
	v_cvt_pk_f32_fp8_e32 v[224:225], v176
	v_cvt_pk_f32_fp8_sdwa v[226:227], v176 src0_sel:WORD_1
	v_cvt_pk_f32_fp8_e32 v[228:229], v177
	v_cvt_pk_f32_fp8_sdwa v[230:231], v177 src0_sel:WORD_1
	v_pk_fma_f32 v[112:113], v[224:225], v[252:253], v[112:113] op_sel_hi:[1,0,1]
	v_pk_fma_f32 v[114:115], v[226:227], v[252:253], v[114:115] op_sel_hi:[1,0,1]
	v_pk_fma_f32 v[116:117], v[228:229], v[252:253], v[116:117] op_sel_hi:[1,0,1]
	v_pk_fma_f32 v[118:119], v[230:231], v[252:253], v[118:119] op_sel_hi:[1,0,1]
	v_cvt_pk_f32_fp8_e32 v[224:225], v178
	v_cvt_pk_f32_fp8_sdwa v[226:227], v178 src0_sel:WORD_1
	v_cvt_pk_f32_fp8_e32 v[228:229], v179
	v_cvt_pk_f32_fp8_sdwa v[230:231], v179 src0_sel:WORD_1
	v_pk_fma_f32 v[120:121], v[224:225], v[252:253], v[120:121] op_sel_hi:[1,0,1]
	v_pk_fma_f32 v[122:123], v[226:227], v[252:253], v[122:123] op_sel_hi:[1,0,1]
	v_pk_fma_f32 v[124:125], v[228:229], v[252:253], v[124:125] op_sel_hi:[1,0,1]
	v_pk_fma_f32 v[126:127], v[230:231], v[252:253], v[126:127] op_sel_hi:[1,0,1]
	v_cvt_pk_f32_fp8_e32 v[224:225], v180
	v_cvt_pk_f32_fp8_sdwa v[226:227], v180 src0_sel:WORD_1
	v_cvt_pk_f32_fp8_e32 v[228:229], v181
	v_cvt_pk_f32_fp8_sdwa v[230:231], v181 src0_sel:WORD_1
	v_pk_fma_f32 v[112:113], v[224:225], v[252:253], v[112:113] op_sel:[0,1,0] op_sel_hi:[1,1,1]
	v_pk_fma_f32 v[114:115], v[226:227], v[252:253], v[114:115] op_sel:[0,1,0] op_sel_hi:[1,1,1]
	v_pk_fma_f32 v[116:117], v[228:229], v[252:253], v[116:117] op_sel:[0,1,0] op_sel_hi:[1,1,1]
	v_pk_fma_f32 v[118:119], v[230:231], v[252:253], v[118:119] op_sel:[0,1,0] op_sel_hi:[1,1,1]
	v_cvt_pk_f32_fp8_e32 v[224:225], v182
	v_cvt_pk_f32_fp8_sdwa v[226:227], v182 src0_sel:WORD_1
	v_cvt_pk_f32_fp8_e32 v[228:229], v183
	v_cvt_pk_f32_fp8_sdwa v[230:231], v183 src0_sel:WORD_1
	v_pk_fma_f32 v[120:121], v[224:225], v[252:253], v[120:121] op_sel:[0,1,0] op_sel_hi:[1,1,1]
	v_pk_fma_f32 v[122:123], v[226:227], v[252:253], v[122:123] op_sel:[0,1,0] op_sel_hi:[1,1,1]
	v_pk_fma_f32 v[124:125], v[228:229], v[252:253], v[124:125] op_sel:[0,1,0] op_sel_hi:[1,1,1]
	v_pk_fma_f32 v[126:127], v[230:231], v[252:253], v[126:127] op_sel:[0,1,0] op_sel_hi:[1,1,1]
	v_cvt_pk_f32_fp8_e32 v[224:225], v184
	v_cvt_pk_f32_fp8_sdwa v[226:227], v184 src0_sel:WORD_1
	v_cvt_pk_f32_fp8_e32 v[228:229], v185
	v_cvt_pk_f32_fp8_sdwa v[230:231], v185 src0_sel:WORD_1
	v_pk_fma_f32 v[112:113], v[224:225], v[254:255], v[112:113] op_sel_hi:[1,0,1]
	v_pk_fma_f32 v[114:115], v[226:227], v[254:255], v[114:115] op_sel_hi:[1,0,1]
	v_pk_fma_f32 v[116:117], v[228:229], v[254:255], v[116:117] op_sel_hi:[1,0,1]
	v_pk_fma_f32 v[118:119], v[230:231], v[254:255], v[118:119] op_sel_hi:[1,0,1]
	v_cvt_pk_f32_fp8_e32 v[224:225], v186
	v_cvt_pk_f32_fp8_sdwa v[226:227], v186 src0_sel:WORD_1
	v_cvt_pk_f32_fp8_e32 v[228:229], v187
	v_cvt_pk_f32_fp8_sdwa v[230:231], v187 src0_sel:WORD_1
	v_pk_fma_f32 v[120:121], v[224:225], v[254:255], v[120:121] op_sel_hi:[1,0,1]
	v_pk_fma_f32 v[122:123], v[226:227], v[254:255], v[122:123] op_sel_hi:[1,0,1]
	v_pk_fma_f32 v[124:125], v[228:229], v[254:255], v[124:125] op_sel_hi:[1,0,1]
	v_pk_fma_f32 v[126:127], v[230:231], v[254:255], v[126:127] op_sel_hi:[1,0,1]
	v_cvt_pk_f32_fp8_e32 v[224:225], v188
	v_cvt_pk_f32_fp8_sdwa v[226:227], v188 src0_sel:WORD_1
	v_cvt_pk_f32_fp8_e32 v[228:229], v189
	v_cvt_pk_f32_fp8_sdwa v[230:231], v189 src0_sel:WORD_1
	v_pk_fma_f32 v[112:113], v[224:225], v[254:255], v[112:113] op_sel:[0,1,0] op_sel_hi:[1,1,1]
	v_pk_fma_f32 v[114:115], v[226:227], v[254:255], v[114:115] op_sel:[0,1,0] op_sel_hi:[1,1,1]
	v_pk_fma_f32 v[116:117], v[228:229], v[254:255], v[116:117] op_sel:[0,1,0] op_sel_hi:[1,1,1]
	v_pk_fma_f32 v[118:119], v[230:231], v[254:255], v[118:119] op_sel:[0,1,0] op_sel_hi:[1,1,1]
	v_cvt_pk_f32_fp8_e32 v[224:225], v190
	v_cvt_pk_f32_fp8_sdwa v[226:227], v190 src0_sel:WORD_1
	v_cvt_pk_f32_fp8_e32 v[228:229], v191
	v_cvt_pk_f32_fp8_sdwa v[230:231], v191 src0_sel:WORD_1
	v_pk_fma_f32 v[120:121], v[224:225], v[254:255], v[120:121] op_sel:[0,1,0] op_sel_hi:[1,1,1]
	v_pk_fma_f32 v[122:123], v[226:227], v[254:255], v[122:123] op_sel:[0,1,0] op_sel_hi:[1,1,1]
	v_pk_fma_f32 v[124:125], v[228:229], v[254:255], v[124:125] op_sel:[0,1,0] op_sel_hi:[1,1,1]
	v_pk_fma_f32 v[126:127], v[230:231], v[254:255], v[126:127] op_sel:[0,1,0] op_sel_hi:[1,1,1]
	v_add_u32_e32 v213, 64, v213
	s_add_i32 s21, s21, 4
	s_sub_i32 s90, s90, 1
	s_cmp_eq_u32 s90, 0
	s_cbranch_scc1 .LV_sw0
	s_branch .LV_t7_s0
